# speedup vs baseline: 1.0010x; 1.0010x over previous
; __device__ void gate_scan(const Ctx& p) {
;     ...
; #pragma unroll
;     for (int e = 0; e < 16; ++e) {
;       int t = tid * 16 + e;
;       float A = fmaxf(offm, am[e]);
;       ga[bh * SEQ + t] = ip[e];
;       gA[bh * SEQ + t] = A;
;       gE[bh * SEQ + t] = __expf(-(lf[e] + A));
;     }
.LBB0_33:
	s_or_b64 exec, exec, s[0:1]
	v_cndmask_b32_e64 v58, v58, 0, s[4:5]
	v_max3_f32 v64, v59, v58, 0
	v_add_u32_e32 v58, -15, v4
	v_max_f32_e32 v59, v62, v62
	v_max_f32_e32 v65, v64, v59
	v_ashrrev_i32_e32 v59, 31, v58
	v_lshlrev_b64 v[58:59], 2, v[58:59]
	v_add_f32_e32 v60, v60, v65
	v_lshl_add_u64 v[62:63], s[84:85], 0, v[58:59]
	v_mul_f32_e32 v60, 0xbfb8aa3b, v60
	global_store_dword v[62:63], v61, off
	v_exp_f32_e32 v62, v60
	v_lshl_add_u64 v[60:61], s[68:69], 0, v[58:59]
	v_lshl_add_u64 v[58:59], s[54:55], 0, v[58:59]
	v_max_f32_e32 v57, v57, v57
	global_store_dword v[58:59], v62, off
	v_max_f32_e32 v62, v64, v57
	v_add_u32_e32 v58, -14, v4
	v_add_f32_e32 v55, v55, v62
	v_ashrrev_i32_e32 v59, 31, v58
	v_mul_f32_e32 v55, 0xbfb8aa3b, v55
	v_lshlrev_b64 v[58:59], 2, v[58:59]
	v_exp_f32_e32 v55, v55
	global_store_dword v[60:61], v65, off
	v_lshl_add_u64 v[60:61], s[84:85], 0, v[58:59]
	global_store_dword v[60:61], v56, off
	v_lshl_add_u64 v[56:57], s[68:69], 0, v[58:59]
	v_max_f32_e32 v54, v54, v54
	global_store_dword v[56:57], v62, off
	v_lshl_add_u64 v[56:57], s[54:55], 0, v[58:59]
	v_max_f32_e32 v58, v64, v54
	v_add_u32_e32 v54, -13, v4
	global_store_dword v[56:57], v55, off
	v_ashrrev_i32_e32 v55, 31, v54
	v_lshlrev_b64 v[54:55], 2, v[54:55]
	v_add_f32_e32 v52, v52, v58
	v_lshl_add_u64 v[56:57], s[84:85], 0, v[54:55]
	v_mul_f32_e32 v52, 0xbfb8aa3b, v52
	global_store_dword v[56:57], v53, off
	v_exp_f32_e32 v56, v52
	v_lshl_add_u64 v[52:53], s[68:69], 0, v[54:55]
	global_store_dword v[52:53], v58, off
	v_lshl_add_u64 v[52:53], s[54:55], 0, v[54:55]
	v_max_f32_e32 v51, v51, v51
	global_store_dword v[52:53], v56, off
	v_max_f32_e32 v56, v64, v51
	v_add_u32_e32 v52, -12, v4
	v_add_f32_e32 v49, v49, v56
	v_ashrrev_i32_e32 v53, 31, v52
	v_mul_f32_e32 v49, 0xbfb8aa3b, v49
	v_lshlrev_b64 v[52:53], 2, v[52:53]
	v_exp_f32_e32 v49, v49
	v_lshl_add_u64 v[54:55], s[84:85], 0, v[52:53]
	global_store_dword v[54:55], v50, off
	v_lshl_add_u64 v[50:51], s[68:69], 0, v[52:53]
	v_max_f32_e32 v48, v48, v48
	global_store_dword v[50:51], v56, off
	v_lshl_add_u64 v[50:51], s[54:55], 0, v[52:53]
	v_max_f32_e32 v52, v64, v48
	v_add_u32_e32 v48, -11, v4
	global_store_dword v[50:51], v49, off
	v_ashrrev_i32_e32 v49, 31, v48
	v_lshlrev_b64 v[48:49], 2, v[48:49]
	v_add_f32_e32 v46, v46, v52
	v_lshl_add_u64 v[50:51], s[84:85], 0, v[48:49]
	v_mul_f32_e32 v46, 0xbfb8aa3b, v46
	global_store_dword v[50:51], v47, off
	v_exp_f32_e32 v50, v46
	v_lshl_add_u64 v[46:47], s[68:69], 0, v[48:49]
	global_store_dword v[46:47], v52, off
	v_lshl_add_u64 v[46:47], s[54:55], 0, v[48:49]
	v_max_f32_e32 v45, v45, v45
	global_store_dword v[46:47], v50, off
	v_max_f32_e32 v50, v64, v45
	v_add_u32_e32 v46, -10, v4
	v_add_f32_e32 v43, v43, v50
	v_ashrrev_i32_e32 v47, 31, v46
	v_mul_f32_e32 v43, 0xbfb8aa3b, v43
	v_lshlrev_b64 v[46:47], 2, v[46:47]
	v_exp_f32_e32 v43, v43
	v_lshl_add_u64 v[48:49], s[84:85], 0, v[46:47]
	global_store_dword v[48:49], v44, off
	v_lshl_add_u64 v[44:45], s[68:69], 0, v[46:47]
	v_max_f32_e32 v42, v42, v42
	global_store_dword v[44:45], v50, off
	v_lshl_add_u64 v[44:45], s[54:55], 0, v[46:47]
	v_max_f32_e32 v46, v64, v42
	v_add_u32_e32 v42, -9, v4
	global_store_dword v[44:45], v43, off
	v_ashrrev_i32_e32 v43, 31, v42
	v_lshlrev_b64 v[42:43], 2, v[42:43]
	v_add_f32_e32 v40, v40, v46
	v_lshl_add_u64 v[44:45], s[84:85], 0, v[42:43]
	v_mul_f32_e32 v40, 0xbfb8aa3b, v40
	global_store_dword v[44:45], v41, off
	v_exp_f32_e32 v44, v40
	v_lshl_add_u64 v[40:41], s[68:69], 0, v[42:43]
	global_store_dword v[40:41], v46, off
	v_lshl_add_u64 v[40:41], s[54:55], 0, v[42:43]
	v_max_f32_e32 v39, v39, v39
	global_store_dword v[40:41], v44, off
	v_max_f32_e32 v44, v64, v39
	v_add_u32_e32 v40, -8, v4
	v_add_f32_e32 v37, v37, v44
	v_ashrrev_i32_e32 v41, 31, v40
	v_mul_f32_e32 v37, 0xbfb8aa3b, v37
	v_lshlrev_b64 v[40:41], 2, v[40:41]
	v_exp_f32_e32 v37, v37
	v_lshl_add_u64 v[42:43], s[84:85], 0, v[40:41]
	global_store_dword v[42:43], v38, off
	v_lshl_add_u64 v[38:39], s[68:69], 0, v[40:41]
	v_max_f32_e32 v36, v36, v36
	global_store_dword v[38:39], v44, off
	v_lshl_add_u64 v[38:39], s[54:55], 0, v[40:41]
	v_max_f32_e32 v40, v64, v36
	v_add_u32_e32 v36, -7, v4
	global_store_dword v[38:39], v37, off
	v_ashrrev_i32_e32 v37, 31, v36
	v_lshlrev_b64 v[36:37], 2, v[36:37]
	v_add_f32_e32 v34, v34, v40
	v_lshl_add_u64 v[38:39], s[84:85], 0, v[36:37]
	v_mul_f32_e32 v34, 0xbfb8aa3b, v34
	global_store_dword v[38:39], v35, off
	v_exp_f32_e32 v38, v34
	v_lshl_add_u64 v[34:35], s[68:69], 0, v[36:37]
	global_store_dword v[34:35], v40, off
	v_lshl_add_u64 v[34:35], s[54:55], 0, v[36:37]
	v_max_f32_e32 v33, v33, v33
	global_store_dword v[34:35], v38, off
	v_max_f32_e32 v38, v64, v33
	v_add_u32_e32 v34, -6, v4
	v_add_f32_e32 v31, v31, v38
	v_ashrrev_i32_e32 v35, 31, v34
	v_mul_f32_e32 v31, 0xbfb8aa3b, v31
	v_lshlrev_b64 v[34:35], 2, v[34:35]
	v_exp_f32_e32 v31, v31
	v_lshl_add_u64 v[36:37], s[84:85], 0, v[34:35]
	global_store_dword v[36:37], v32, off
	v_lshl_add_u64 v[32:33], s[68:69], 0, v[34:35]
	v_max_f32_e32 v30, v30, v30
	global_store_dword v[32:33], v38, off
	v_lshl_add_u64 v[32:33], s[54:55], 0, v[34:35]
	v_max_f32_e32 v34, v64, v30
	v_add_u32_e32 v30, -5, v4
	global_store_dword v[32:33], v31, off
	v_ashrrev_i32_e32 v31, 31, v30
	v_lshlrev_b64 v[30:31], 2, v[30:31]
	v_add_f32_e32 v22, v22, v34
	v_lshl_add_u64 v[32:33], s[84:85], 0, v[30:31]
	v_mul_f32_e32 v22, 0xbfb8aa3b, v22
	global_store_dword v[32:33], v23, off
	v_exp_f32_e32 v32, v22
	v_lshl_add_u64 v[22:23], s[68:69], 0, v[30:31]
	global_store_dword v[22:23], v34, off
	v_lshl_add_u64 v[22:23], s[54:55], 0, v[30:31]
	v_max_f32_e32 v21, v21, v21
; __device__ __forceinline__ float logsig(float x) { return fminf(x, 0.f) - __logf(1.f + __expf(-fabsf(x))); }
; __device__ void gate_scan(const Ctx& p) {
;     ...
; #pragma unroll
;     for (int e = 0; e < 16; ++e) {
;       long tok = (long)b * SEQ + tid * 16 + e;
;       float si = bi, sf = bf;
; #pragma unroll
;       for (int cgp = 0; cgp < 8; ++cgp) {
;         si += gpart[((long)cgp * NTOK + tok) * 8 + h];
;         sf += gpart[((long)cgp * NTOK + tok) * 8 + 4 + h];
;       }
;       ip[e] = si;
;       run += logsig(sf);
;       lf[e] = run;
;     }
;     ...
; #pragma unroll
;     for (int e = 0; e < 16; ++e) {
;       int t = tid * 16 + e;
;       float A = fmaxf(offm, am[e]);
;       ga[bh * SEQ + t] = ip[e];
;       gA[bh * SEQ + t] = A;
;       gE[bh * SEQ + t] = __expf(-(lf[e] + A));
;     }
;     __syncthreads();
	global_store_dword v[22:23], v32, off
	v_max_f32_e32 v32, v64, v21
	v_add_u32_e32 v22, -4, v4
	v_add_f32_e32 v19, v19, v32
	v_ashrrev_i32_e32 v23, 31, v22
	v_mul_f32_e32 v19, 0xbfb8aa3b, v19
	v_lshlrev_b64 v[22:23], 2, v[22:23]
	v_exp_f32_e32 v19, v19
	v_lshl_add_u64 v[30:31], s[84:85], 0, v[22:23]
	global_store_dword v[30:31], v20, off
	v_lshl_add_u64 v[20:21], s[68:69], 0, v[22:23]
	v_max_f32_e32 v18, v18, v18
	global_store_dword v[20:21], v32, off
	v_lshl_add_u64 v[20:21], s[54:55], 0, v[22:23]
	v_max_f32_e32 v22, v64, v18
	v_add_u32_e32 v18, -3, v4
	global_store_dword v[20:21], v19, off
	v_ashrrev_i32_e32 v19, 31, v18
	v_lshlrev_b64 v[18:19], 2, v[18:19]
	v_add_f32_e32 v16, v16, v22
	v_lshl_add_u64 v[20:21], s[84:85], 0, v[18:19]
	v_mul_f32_e32 v16, 0xbfb8aa3b, v16
	global_store_dword v[20:21], v17, off
	v_exp_f32_e32 v20, v16
	v_lshl_add_u64 v[16:17], s[68:69], 0, v[18:19]
	global_store_dword v[16:17], v22, off
	v_lshl_add_u64 v[16:17], s[54:55], 0, v[18:19]
	v_max_f32_e32 v15, v15, v15
	global_store_dword v[16:17], v20, off
	v_max_f32_e32 v20, v64, v15
	v_add_u32_e32 v16, -2, v4
	v_add_f32_e32 v13, v13, v20
	v_ashrrev_i32_e32 v17, 31, v16
	v_mul_f32_e32 v13, 0xbfb8aa3b, v13
	v_lshlrev_b64 v[16:17], 2, v[16:17]
	v_exp_f32_e32 v13, v13
	v_lshl_add_u64 v[18:19], s[84:85], 0, v[16:17]
	global_store_dword v[18:19], v14, off
	v_lshl_add_u64 v[14:15], s[68:69], 0, v[16:17]
	v_max_f32_e32 v12, v12, v12
	global_store_dword v[14:15], v20, off
	v_lshl_add_u64 v[14:15], s[54:55], 0, v[16:17]
	v_max_f32_e32 v16, v64, v12
	v_add_u32_e32 v12, -1, v4
	global_store_dword v[14:15], v13, off
	v_ashrrev_i32_e32 v13, 31, v12
	v_lshlrev_b64 v[12:13], 2, v[12:13]
	v_add_f32_e32 v10, v10, v16
	v_lshl_add_u64 v[14:15], s[84:85], 0, v[12:13]
	v_mul_f32_e32 v10, 0xbfb8aa3b, v10
	global_store_dword v[14:15], v11, off
	v_exp_f32_e32 v14, v10
	v_lshl_add_u64 v[10:11], s[68:69], 0, v[12:13]
	global_store_dword v[10:11], v16, off
	v_lshl_add_u64 v[10:11], s[54:55], 0, v[12:13]
	v_max_f32_e32 v5, v5, v5
	global_store_dword v[10:11], v14, off
	v_max_f32_e32 v14, v64, v5
	v_ashrrev_i32_e32 v5, 31, v4
	v_lshlrev_b64 v[10:11], 2, v[4:5]
	v_add_f32_e32 v5, v8, v14
	v_mul_f32_e32 v5, 0xbfb8aa3b, v5
	v_exp_f32_e32 v5, v5
	v_lshl_add_u64 v[12:13], s[84:85], 0, v[10:11]
	global_store_dword v[12:13], v9, off
	v_lshl_add_u64 v[8:9], s[68:69], 0, v[10:11]
	s_add_i32 s61, s61, s96
	v_readlane_b32 s0, v252, 12
	global_store_dword v[8:9], v14, off
	v_lshl_add_u64 v[8:9], s[54:55], 0, v[10:11]
	s_cmp_lt_i32 s61, 8
	v_add_u32_e32 v4, s0, v4
	global_store_dword v[8:9], v5, off
	s_waitcnt lgkmcnt(0)
	s_barrier
	s_cbranch_scc0 .LBB0_73
.LBB0_34:
	global_load_dwordx2 v[8:9], v[6:7], off
	s_ashr_i32 s0, s61, 2
	s_and_b32 s1, s61, 3
	s_lshl_b32 s52, s1, 2
	s_ashr_i32 s1, s0, 31
	s_add_u32 s38, s46, s52
	s_addc_u32 s39, s47, 0
	s_lshl_b64 s[0:1], s[0:1], 18
	s_add_u32 s0, s38, s0
	s_addc_u32 s1, s39, s1
	s_waitcnt vmcnt(0) lgkmcnt(0)
	v_lshl_add_u64 v[8:9], v[8:9], 0, s[52:53]
	global_load_dword v5, v[8:9], off
	global_load_dword v58, v[8:9], off offset:16
	v_lshl_add_u64 v[8:9], s[0:1], 0, v[2:3]
	s_mov_b32 s0, 0x80000
	v_add_co_u32_e64 v20, s[0:1], s0, v8
	global_load_dword v30, v[8:9], off
	global_load_dword v10, v[8:9], off offset:16
	v_addc_co_u32_e64 v21, s[0:1], 0, v9, s[0:1]
	global_load_dword v31, v[20:21], off
	global_load_dword v11, v[20:21], off offset:16
	s_waitcnt vmcnt(0) lgkmcnt(0)
	v_add_f32_e32 v10, v58, v10
	v_add_f32_e32 v12, v10, v11
	v_add_co_u32_e64 v10, s[0:1], s40, v8
	s_nop 1
	v_addc_co_u32_e64 v11, s[0:1], 0, v9, s[0:1]
	global_load_dword v32, v[10:11], off
	global_load_dword v13, v[10:11], off offset:16
	s_mov_b32 s0, 0x180000
	s_waitcnt vmcnt(0) lgkmcnt(0)
	v_add_f32_e32 v14, v12, v13
	v_add_co_u32_e64 v12, s[0:1], s0, v8
	s_nop 1
	v_addc_co_u32_e64 v13, s[0:1], 0, v9, s[0:1]
	global_load_dword v33, v[12:13], off
	global_load_dword v15, v[12:13], off offset:16
	s_mov_b32 s0, 0x200000
	s_waitcnt vmcnt(0) lgkmcnt(0)
	v_add_f32_e32 v16, v14, v15
	v_add_co_u32_e64 v14, s[0:1], s0, v8
	s_nop 1
	v_addc_co_u32_e64 v15, s[0:1], 0, v9, s[0:1]
	global_load_dword v35, v[14:15], off
	global_load_dword v17, v[14:15], off offset:16
	s_mov_b32 s0, 0x280000
	s_waitcnt vmcnt(0) lgkmcnt(0)
	v_add_f32_e32 v18, v16, v17
	v_add_co_u32_e64 v16, s[0:1], s0, v8
	s_nop 1
	v_addc_co_u32_e64 v17, s[0:1], 0, v9, s[0:1]
	global_load_dword v36, v[16:17], off
	global_load_dword v19, v[16:17], off offset:16
	s_mov_b32 s0, 0x300000
	s_waitcnt vmcnt(0) lgkmcnt(0)
	v_add_f32_e32 v22, v18, v19
	v_add_co_u32_e64 v18, s[0:1], s0, v8
	s_nop 1
	v_addc_co_u32_e64 v19, s[0:1], 0, v9, s[0:1]
	global_load_dword v37, v[18:19], off
	global_load_dword v23, v[18:19], off offset:16
	s_mov_b32 s0, 0x380000
	s_waitcnt vmcnt(0) lgkmcnt(0)
	v_add_f32_e32 v34, v22, v23
	v_add_co_u32_e64 v22, s[0:1], s0, v8
	s_nop 1
	v_addc_co_u32_e64 v23, s[0:1], 0, v9, s[0:1]
	global_load_dword v38, v[22:23], off
	global_load_dword v39, v[22:23], off offset:16
	s_waitcnt vmcnt(0) lgkmcnt(0)
	v_add_f32_e32 v34, v34, v39
	v_min_f32_e32 v39, 0, v34
	v_mul_f32_e64 v34, |v34|, s94
	v_exp_f32_e32 v34, v34
	s_nop 0
	v_add_f32_e32 v34, 1.0, v34
	v_cmp_gt_f32_e64 s[0:1], s48, v34
	s_nop 1
	v_cndmask_b32_e64 v40, 0, 32, s[0:1]
	v_ldexp_f32 v34, v34, v40
	v_log_f32_e32 v34, v34
	s_nop 0
	v_mul_f32_e32 v40, 0x3f317217, v34
	v_fma_f32 v40, v34, s49, -v40
	v_fmac_f32_e32 v40, 0x3377d1cf, v34
	v_fmac_f32_e32 v40, 0x3f317217, v34
	v_cmp_lt_f32_e64 s[38:39], |v34|, s36
	s_nop 1
	v_cndmask_b32_e64 v34, v34, v40, s[38:39]
	v_cndmask_b32_e64 v40, 0, v192, s[0:1]
	v_sub_f32_e32 v34, v34, v40
	v_sub_f32_e32 v34, v39, v34
	global_load_dword v39, v[8:9], off offset:32
	global_load_dword v40, v[8:9], off offset:48
	global_load_dword v41, v[20:21], off offset:32
	global_load_dword v42, v[20:21], off offset:48
	v_add_f32_e32 v34, 0, v34
	s_waitcnt vmcnt(0) lgkmcnt(0)
; __device__ __forceinline__ float logsig(float x) { return fminf(x, 0.f) - __logf(1.f + __expf(-fabsf(x))); }
; __device__ void gate_scan(const Ctx& p) {
;     ...
;     for (int e = 0; e < 16; ++e) {
;       long tok = (long)b * SEQ + tid * 16 + e;
;       float si = bi, sf = bf;
; #pragma unroll
;       for (int cgp = 0; cgp < 8; ++cgp) {
;         si += gpart[((long)cgp * NTOK + tok) * 8 + h];
;         sf += gpart[((long)cgp * NTOK + tok) * 8 + 4 + h];
;       }
;       ip[e] = si;
;       run += logsig(sf);
;       lf[e] = run;
;     }
	v_add_f32_e32 v40, v58, v40
	v_add_f32_e32 v40, v40, v42
	global_load_dword v42, v[10:11], off offset:32
	global_load_dword v43, v[10:11], off offset:48
	s_waitcnt vmcnt(0) lgkmcnt(0)
	v_add_f32_e32 v40, v40, v43
	global_load_dword v43, v[12:13], off offset:32
	global_load_dword v44, v[12:13], off offset:48
	s_waitcnt vmcnt(0) lgkmcnt(0)
	v_add_f32_e32 v40, v40, v44
	global_load_dword v44, v[14:15], off offset:32
	global_load_dword v45, v[14:15], off offset:48
	s_waitcnt vmcnt(0) lgkmcnt(0)
	v_add_f32_e32 v40, v40, v45
	global_load_dword v45, v[16:17], off offset:32
	global_load_dword v46, v[16:17], off offset:48
	s_waitcnt vmcnt(0) lgkmcnt(0)
	v_add_f32_e32 v40, v40, v46
	global_load_dword v46, v[18:19], off offset:32
	global_load_dword v47, v[18:19], off offset:48
	s_waitcnt vmcnt(0) lgkmcnt(0)
	v_add_f32_e32 v40, v40, v47
	global_load_dword v47, v[22:23], off offset:32
	global_load_dword v48, v[22:23], off offset:48
	s_waitcnt vmcnt(0) lgkmcnt(0)
	v_add_f32_e32 v40, v40, v48
	v_min_f32_e32 v48, 0, v40
	v_mul_f32_e64 v40, |v40|, s94
	v_exp_f32_e32 v40, v40
	s_nop 0
	v_add_f32_e32 v40, 1.0, v40
	v_cmp_gt_f32_e64 s[0:1], s48, v40
	s_nop 1
	v_cndmask_b32_e64 v49, 0, 32, s[0:1]
	v_ldexp_f32 v40, v40, v49
	v_log_f32_e32 v40, v40
	s_nop 0
	v_mul_f32_e32 v49, 0x3f317217, v40
	v_fma_f32 v49, v40, s49, -v49
	v_fmac_f32_e32 v49, 0x3377d1cf, v40
	v_fmac_f32_e32 v49, 0x3f317217, v40
	v_cmp_lt_f32_e64 s[38:39], |v40|, s36
	s_nop 1
	v_cndmask_b32_e64 v40, v40, v49, s[38:39]
	v_cndmask_b32_e64 v49, 0, v192, s[0:1]
	v_sub_f32_e32 v40, v40, v49
	v_sub_f32_e32 v40, v48, v40
	global_load_dword v48, v[8:9], off offset:64
	global_load_dword v49, v[8:9], off offset:80
	global_load_dword v50, v[20:21], off offset:64
	global_load_dword v51, v[20:21], off offset:80
	v_add_f32_e32 v40, v34, v40
	s_waitcnt vmcnt(0) lgkmcnt(0)
	v_add_f32_e32 v49, v58, v49
	v_add_f32_e32 v49, v49, v51
	global_load_dword v51, v[10:11], off offset:64
	global_load_dword v52, v[10:11], off offset:80
	s_waitcnt vmcnt(0) lgkmcnt(0)
	v_add_f32_e32 v49, v49, v52
	global_load_dword v52, v[12:13], off offset:64
	global_load_dword v53, v[12:13], off offset:80
	s_waitcnt vmcnt(0) lgkmcnt(0)
	v_add_f32_e32 v49, v49, v53
	global_load_dword v53, v[14:15], off offset:64
	global_load_dword v54, v[14:15], off offset:80
	s_waitcnt vmcnt(0) lgkmcnt(0)
	v_add_f32_e32 v49, v49, v54
	global_load_dword v54, v[16:17], off offset:64
	global_load_dword v55, v[16:17], off offset:80
	s_waitcnt vmcnt(0) lgkmcnt(0)
	v_add_f32_e32 v49, v49, v55
	global_load_dword v55, v[18:19], off offset:64
	global_load_dword v56, v[18:19], off offset:80
	s_waitcnt vmcnt(0) lgkmcnt(0)
	v_add_f32_e32 v49, v49, v56
	global_load_dword v56, v[22:23], off offset:64
	global_load_dword v57, v[22:23], off offset:80
	s_waitcnt vmcnt(0) lgkmcnt(0)
	v_add_f32_e32 v49, v49, v57
	v_min_f32_e32 v57, 0, v49
	v_mul_f32_e64 v49, |v49|, s94
	v_exp_f32_e32 v49, v49
	s_nop 0
	v_add_f32_e32 v49, 1.0, v49
	v_cmp_gt_f32_e64 s[0:1], s48, v49
	s_nop 1
	v_cndmask_b32_e64 v59, 0, 32, s[0:1]
	v_ldexp_f32 v49, v49, v59
	v_log_f32_e32 v49, v49
	s_nop 0
	v_mul_f32_e32 v59, 0x3f317217, v49
	v_fma_f32 v59, v49, s49, -v59
	v_fmac_f32_e32 v59, 0x3377d1cf, v49
	v_fmac_f32_e32 v59, 0x3f317217, v49
	v_cmp_lt_f32_e64 s[38:39], |v49|, s36
	s_nop 1
	v_cndmask_b32_e64 v49, v49, v59, s[38:39]
	v_cndmask_b32_e64 v59, 0, v192, s[0:1]
	v_sub_f32_e32 v49, v49, v59
	v_sub_f32_e32 v49, v57, v49
	global_load_dword v57, v[8:9], off offset:96
	global_load_dword v59, v[8:9], off offset:112
	global_load_dword v60, v[20:21], off offset:96
	global_load_dword v61, v[20:21], off offset:112
	v_add_f32_e32 v49, v40, v49
	s_waitcnt vmcnt(0) lgkmcnt(0)
	v_add_f32_e32 v59, v58, v59
	v_add_f32_e32 v59, v59, v61
	global_load_dword v61, v[10:11], off offset:96
	global_load_dword v62, v[10:11], off offset:112
	s_waitcnt vmcnt(0) lgkmcnt(0)
	v_add_f32_e32 v59, v59, v62
	global_load_dword v62, v[12:13], off offset:96
	global_load_dword v63, v[12:13], off offset:112
	s_waitcnt vmcnt(0) lgkmcnt(0)
	v_add_f32_e32 v59, v59, v63
	global_load_dword v63, v[14:15], off offset:96
	global_load_dword v64, v[14:15], off offset:112
	s_waitcnt vmcnt(0) lgkmcnt(0)
	v_add_f32_e32 v59, v59, v64
	global_load_dword v64, v[16:17], off offset:96
	global_load_dword v65, v[16:17], off offset:112
	s_waitcnt vmcnt(0) lgkmcnt(0)
	v_add_f32_e32 v59, v59, v65
	global_load_dword v65, v[18:19], off offset:96
	global_load_dword v66, v[18:19], off offset:112
	s_waitcnt vmcnt(0) lgkmcnt(0)
	v_add_f32_e32 v59, v59, v66
	global_load_dword v66, v[22:23], off offset:96
	global_load_dword v67, v[22:23], off offset:112
	s_waitcnt vmcnt(0) lgkmcnt(0)
	v_add_f32_e32 v59, v59, v67
	v_min_f32_e32 v67, 0, v59
	v_mul_f32_e64 v59, |v59|, s94
	v_exp_f32_e32 v59, v59
	s_nop 0
	v_add_f32_e32 v59, 1.0, v59
	v_cmp_gt_f32_e64 s[0:1], s48, v59
	s_nop 1
	v_cndmask_b32_e64 v68, 0, 32, s[0:1]
	v_ldexp_f32 v59, v59, v68
	v_log_f32_e32 v59, v59
	s_nop 0
	v_mul_f32_e32 v68, 0x3f317217, v59
	v_fma_f32 v68, v59, s49, -v68
	v_fmac_f32_e32 v68, 0x3377d1cf, v59
	v_fmac_f32_e32 v68, 0x3f317217, v59
	v_cmp_lt_f32_e64 s[38:39], |v59|, s36
	s_nop 1
	v_cndmask_b32_e64 v59, v59, v68, s[38:39]
	v_cndmask_b32_e64 v68, 0, v192, s[0:1]
	v_sub_f32_e32 v59, v59, v68
	v_sub_f32_e32 v59, v67, v59
	global_load_dword v67, v[8:9], off offset:128
	global_load_dword v68, v[8:9], off offset:144
	v_add_f32_e32 v59, v49, v59
	s_waitcnt vmcnt(0) lgkmcnt(0)
	v_add_f32_e32 v69, v58, v68
	global_load_dword v68, v[20:21], off offset:128
	global_load_dword v70, v[20:21], off offset:144
	s_waitcnt vmcnt(0) lgkmcnt(0)
; __device__ __forceinline__ float logsig(float x) { return fminf(x, 0.f) - __logf(1.f + __expf(-fabsf(x))); }
; __device__ void gate_scan(const Ctx& p) {
;     ...
;     for (int e = 0; e < 16; ++e) {
;       long tok = (long)b * SEQ + tid * 16 + e;
;       float si = bi, sf = bf;
; #pragma unroll
;       for (int cgp = 0; cgp < 8; ++cgp) {
;         si += gpart[((long)cgp * NTOK + tok) * 8 + h];
;         sf += gpart[((long)cgp * NTOK + tok) * 8 + 4 + h];
;       }
;       ip[e] = si;
;       run += logsig(sf);
;       lf[e] = run;
;     }
	v_add_f32_e32 v70, v69, v70
	global_load_dword v69, v[10:11], off offset:128
	global_load_dword v71, v[10:11], off offset:144
	s_waitcnt vmcnt(0) lgkmcnt(0)
	v_add_f32_e32 v71, v70, v71
	global_load_dword v70, v[12:13], off offset:128
	global_load_dword v72, v[12:13], off offset:144
	s_waitcnt vmcnt(0) lgkmcnt(0)
	v_add_f32_e32 v72, v71, v72
	global_load_dword v71, v[14:15], off offset:128
	global_load_dword v73, v[14:15], off offset:144
	s_waitcnt vmcnt(0) lgkmcnt(0)
	v_add_f32_e32 v73, v72, v73
	global_load_dword v72, v[16:17], off offset:128
	global_load_dword v74, v[16:17], off offset:144
	s_waitcnt vmcnt(0) lgkmcnt(0)
	v_add_f32_e32 v74, v73, v74
	global_load_dword v73, v[18:19], off offset:128
	global_load_dword v75, v[18:19], off offset:144
	s_waitcnt vmcnt(0) lgkmcnt(0)
	v_add_f32_e32 v75, v74, v75
	global_load_dword v74, v[22:23], off offset:128
	global_load_dword v76, v[22:23], off offset:144
	s_waitcnt vmcnt(0) lgkmcnt(0)
	v_add_f32_e32 v75, v75, v76
	v_min_f32_e32 v76, 0, v75
	v_mul_f32_e64 v75, |v75|, s94
	v_exp_f32_e32 v75, v75
	s_nop 0
	v_add_f32_e32 v75, 1.0, v75
	v_cmp_gt_f32_e64 s[0:1], s48, v75
	s_nop 1
	v_cndmask_b32_e64 v77, 0, 32, s[0:1]
	v_ldexp_f32 v75, v75, v77
	v_log_f32_e32 v75, v75
	s_nop 0
	v_mul_f32_e32 v77, 0x3f317217, v75
	v_fma_f32 v77, v75, s49, -v77
	v_fmac_f32_e32 v77, 0x3377d1cf, v75
	v_fmac_f32_e32 v77, 0x3f317217, v75
	v_cmp_lt_f32_e64 s[38:39], |v75|, s36
	s_nop 1
	v_cndmask_b32_e64 v75, v75, v77, s[38:39]
	v_cndmask_b32_e64 v77, 0, v192, s[0:1]
	v_sub_f32_e32 v75, v75, v77
	v_sub_f32_e32 v75, v76, v75
	global_load_dword v76, v[8:9], off offset:160
	global_load_dword v77, v[8:9], off offset:176
	v_add_f32_e32 v75, v59, v75
	s_waitcnt vmcnt(0) lgkmcnt(0)
	v_add_f32_e32 v78, v58, v77
	global_load_dword v77, v[20:21], off offset:160
	global_load_dword v79, v[20:21], off offset:176
	s_waitcnt vmcnt(0) lgkmcnt(0)
	v_add_f32_e32 v79, v78, v79
	global_load_dword v78, v[10:11], off offset:160
	global_load_dword v80, v[10:11], off offset:176
	s_waitcnt vmcnt(0) lgkmcnt(0)
	v_add_f32_e32 v79, v79, v80
	global_load_dword v80, v[12:13], off offset:160
	global_load_dword v81, v[12:13], off offset:176
	s_waitcnt vmcnt(0) lgkmcnt(0)
	v_add_f32_e32 v79, v79, v81
	global_load_dword v81, v[14:15], off offset:160
	global_load_dword v82, v[14:15], off offset:176
	s_waitcnt vmcnt(0) lgkmcnt(0)
	v_add_f32_e32 v79, v79, v82
	global_load_dword v82, v[16:17], off offset:160
	global_load_dword v83, v[16:17], off offset:176
	s_waitcnt vmcnt(0) lgkmcnt(0)
	v_add_f32_e32 v79, v79, v83
	global_load_dword v83, v[18:19], off offset:160
	global_load_dword v84, v[18:19], off offset:176
	s_waitcnt vmcnt(0) lgkmcnt(0)
	v_add_f32_e32 v79, v79, v84
	global_load_dword v84, v[22:23], off offset:160
	global_load_dword v85, v[22:23], off offset:176
	s_waitcnt vmcnt(0) lgkmcnt(0)
	v_add_f32_e32 v79, v79, v85
	v_min_f32_e32 v85, 0, v79
	v_mul_f32_e64 v79, |v79|, s94
	v_exp_f32_e32 v79, v79
	s_nop 0
	v_add_f32_e32 v79, 1.0, v79
	v_cmp_gt_f32_e64 s[0:1], s48, v79
	s_nop 1
	v_cndmask_b32_e64 v86, 0, 32, s[0:1]
	v_ldexp_f32 v79, v79, v86
	v_log_f32_e32 v79, v79
	s_nop 0
	v_mul_f32_e32 v86, 0x3f317217, v79
	v_fma_f32 v86, v79, s49, -v86
	v_fmac_f32_e32 v86, 0x3377d1cf, v79
	v_fmac_f32_e32 v86, 0x3f317217, v79
	v_cmp_lt_f32_e64 s[38:39], |v79|, s36
	s_nop 1
	v_cndmask_b32_e64 v79, v79, v86, s[38:39]
	v_cndmask_b32_e64 v86, 0, v192, s[0:1]
	v_sub_f32_e32 v79, v79, v86
	v_sub_f32_e32 v79, v85, v79
	global_load_dword v85, v[8:9], off offset:192
	global_load_dword v86, v[8:9], off offset:208
	global_load_dword v87, v[20:21], off offset:192
	global_load_dword v88, v[20:21], off offset:208
	v_add_f32_e32 v79, v75, v79
	s_waitcnt vmcnt(0) lgkmcnt(0)
	v_add_f32_e32 v86, v58, v86
	v_add_f32_e32 v86, v86, v88
	global_load_dword v88, v[10:11], off offset:192
	global_load_dword v89, v[10:11], off offset:208
	s_waitcnt vmcnt(0) lgkmcnt(0)
	v_add_f32_e32 v86, v86, v89
	global_load_dword v89, v[12:13], off offset:192
	global_load_dword v90, v[12:13], off offset:208
	s_waitcnt vmcnt(0) lgkmcnt(0)
	v_add_f32_e32 v86, v86, v90
	global_load_dword v90, v[14:15], off offset:192
	global_load_dword v91, v[14:15], off offset:208
	s_waitcnt vmcnt(0) lgkmcnt(0)
	v_add_f32_e32 v86, v86, v91
	global_load_dword v91, v[16:17], off offset:192
	global_load_dword v92, v[16:17], off offset:208
	s_waitcnt vmcnt(0) lgkmcnt(0)
	v_add_f32_e32 v86, v86, v92
	global_load_dword v92, v[18:19], off offset:192
	global_load_dword v93, v[18:19], off offset:208
	s_waitcnt vmcnt(0) lgkmcnt(0)
	v_add_f32_e32 v86, v86, v93
	global_load_dword v93, v[22:23], off offset:192
	global_load_dword v94, v[22:23], off offset:208
	s_waitcnt vmcnt(0) lgkmcnt(0)
	v_add_f32_e32 v86, v86, v94
	v_min_f32_e32 v94, 0, v86
	v_mul_f32_e64 v86, |v86|, s94
	v_exp_f32_e32 v86, v86
	s_nop 0
	v_add_f32_e32 v86, 1.0, v86
	v_cmp_gt_f32_e64 s[0:1], s48, v86
	s_nop 1
	v_cndmask_b32_e64 v95, 0, 32, s[0:1]
	v_ldexp_f32 v86, v86, v95
	v_log_f32_e32 v86, v86
	s_nop 0
	v_mul_f32_e32 v95, 0x3f317217, v86
	v_fma_f32 v95, v86, s49, -v95
	v_fmac_f32_e32 v95, 0x3377d1cf, v86
	v_fmac_f32_e32 v95, 0x3f317217, v86
	v_cmp_lt_f32_e64 s[38:39], |v86|, s36
	s_nop 1
	v_cndmask_b32_e64 v86, v86, v95, s[38:39]
	v_cndmask_b32_e64 v95, 0, v192, s[0:1]
	v_sub_f32_e32 v86, v86, v95
	v_sub_f32_e32 v86, v94, v86
	global_load_dword v94, v[8:9], off offset:224
	global_load_dword v95, v[8:9], off offset:240
	v_add_f32_e32 v86, v79, v86
	s_waitcnt vmcnt(0) lgkmcnt(0)
	v_add_f32_e32 v96, v58, v95
	global_load_dword v95, v[20:21], off offset:224
	global_load_dword v97, v[20:21], off offset:240
	s_waitcnt vmcnt(0) lgkmcnt(0)
; __device__ __forceinline__ float logsig(float x) { return fminf(x, 0.f) - __logf(1.f + __expf(-fabsf(x))); }
; __device__ void gate_scan(const Ctx& p) {
;     ...
;     for (int e = 0; e < 16; ++e) {
;       long tok = (long)b * SEQ + tid * 16 + e;
;       float si = bi, sf = bf;
; #pragma unroll
;       for (int cgp = 0; cgp < 8; ++cgp) {
;         si += gpart[((long)cgp * NTOK + tok) * 8 + h];
;         sf += gpart[((long)cgp * NTOK + tok) * 8 + 4 + h];
;       }
;       ip[e] = si;
;       run += logsig(sf);
;       lf[e] = run;
;     }
	v_add_f32_e32 v97, v96, v97
	global_load_dword v96, v[10:11], off offset:224
	global_load_dword v98, v[10:11], off offset:240
	s_waitcnt vmcnt(0) lgkmcnt(0)
	v_add_f32_e32 v98, v97, v98
	global_load_dword v97, v[12:13], off offset:224
	global_load_dword v99, v[12:13], off offset:240
	s_waitcnt vmcnt(0) lgkmcnt(0)
	v_add_f32_e32 v99, v98, v99
	global_load_dword v98, v[14:15], off offset:224
	global_load_dword v100, v[14:15], off offset:240
	s_waitcnt vmcnt(0) lgkmcnt(0)
	v_add_f32_e32 v99, v99, v100
	global_load_dword v100, v[16:17], off offset:224
	global_load_dword v101, v[16:17], off offset:240
	s_waitcnt vmcnt(0) lgkmcnt(0)
	v_add_f32_e32 v99, v99, v101
	global_load_dword v101, v[18:19], off offset:224
	global_load_dword v102, v[18:19], off offset:240
	s_waitcnt vmcnt(0) lgkmcnt(0)
	v_add_f32_e32 v99, v99, v102
	global_load_dword v102, v[22:23], off offset:224
	global_load_dword v103, v[22:23], off offset:240
	s_waitcnt vmcnt(0) lgkmcnt(0)
	v_add_f32_e32 v99, v99, v103
	v_min_f32_e32 v103, 0, v99
	v_mul_f32_e64 v99, |v99|, s94
	v_exp_f32_e32 v99, v99
	s_nop 0
	v_add_f32_e32 v99, 1.0, v99
	v_cmp_gt_f32_e64 s[0:1], s48, v99
	s_nop 1
	v_cndmask_b32_e64 v104, 0, 32, s[0:1]
	v_ldexp_f32 v99, v99, v104
	v_log_f32_e32 v99, v99
	s_nop 0
	v_mul_f32_e32 v104, 0x3f317217, v99
	v_fma_f32 v104, v99, s49, -v104
	v_fmac_f32_e32 v104, 0x3377d1cf, v99
	v_fmac_f32_e32 v104, 0x3f317217, v99
	v_cmp_lt_f32_e64 s[38:39], |v99|, s36
	s_nop 1
	v_cndmask_b32_e64 v99, v99, v104, s[38:39]
	v_cndmask_b32_e64 v104, 0, v192, s[0:1]
	v_sub_f32_e32 v99, v99, v104
	v_sub_f32_e32 v99, v103, v99
	global_load_dword v103, v[8:9], off offset:256
	global_load_dword v104, v[8:9], off offset:272
	v_add_f32_e32 v99, v86, v99
	s_waitcnt vmcnt(0) lgkmcnt(0)
	v_add_f32_e32 v105, v58, v104
	global_load_dword v104, v[20:21], off offset:256
	global_load_dword v106, v[20:21], off offset:272
	s_waitcnt vmcnt(0) lgkmcnt(0)
	v_add_f32_e32 v106, v105, v106
	global_load_dword v105, v[10:11], off offset:256
	global_load_dword v107, v[10:11], off offset:272
	s_waitcnt vmcnt(0) lgkmcnt(0)
	v_add_f32_e32 v107, v106, v107
	global_load_dword v106, v[12:13], off offset:256
	global_load_dword v108, v[12:13], off offset:272
	s_waitcnt vmcnt(0) lgkmcnt(0)
	v_add_f32_e32 v108, v107, v108
	global_load_dword v107, v[14:15], off offset:256
	global_load_dword v109, v[14:15], off offset:272
	s_waitcnt vmcnt(0) lgkmcnt(0)
	v_add_f32_e32 v109, v108, v109
	global_load_dword v108, v[16:17], off offset:256
	global_load_dword v110, v[16:17], off offset:272
	s_waitcnt vmcnt(0) lgkmcnt(0)
	v_add_f32_e32 v109, v109, v110
	global_load_dword v110, v[18:19], off offset:256
	global_load_dword v111, v[18:19], off offset:272
	s_waitcnt vmcnt(0) lgkmcnt(0)
	v_add_f32_e32 v109, v109, v111
	global_load_dword v111, v[22:23], off offset:256
	global_load_dword v112, v[22:23], off offset:272
	s_waitcnt vmcnt(0) lgkmcnt(0)
	v_add_f32_e32 v109, v109, v112
	v_min_f32_e32 v112, 0, v109
	v_mul_f32_e64 v109, |v109|, s94
	v_exp_f32_e32 v109, v109
	s_nop 0
	v_add_f32_e32 v109, 1.0, v109
	v_cmp_gt_f32_e64 s[0:1], s48, v109
	s_nop 1
	v_cndmask_b32_e64 v113, 0, 32, s[0:1]
	v_ldexp_f32 v109, v109, v113
	v_log_f32_e32 v109, v109
	s_nop 0
	v_mul_f32_e32 v113, 0x3f317217, v109
	v_fma_f32 v113, v109, s49, -v113
	v_fmac_f32_e32 v113, 0x3377d1cf, v109
	v_fmac_f32_e32 v113, 0x3f317217, v109
	v_cmp_lt_f32_e64 s[38:39], |v109|, s36
	s_nop 1
	v_cndmask_b32_e64 v109, v109, v113, s[38:39]
	v_cndmask_b32_e64 v113, 0, v192, s[0:1]
	v_sub_f32_e32 v109, v109, v113
	v_sub_f32_e32 v109, v112, v109
	global_load_dword v112, v[8:9], off offset:288
	global_load_dword v113, v[8:9], off offset:304
	v_add_f32_e32 v109, v99, v109
	s_waitcnt vmcnt(0) lgkmcnt(0)
	v_add_f32_e32 v114, v58, v113
	global_load_dword v113, v[20:21], off offset:288
	global_load_dword v115, v[20:21], off offset:304
	s_waitcnt vmcnt(0) lgkmcnt(0)
	v_add_f32_e32 v115, v114, v115
	global_load_dword v114, v[10:11], off offset:288
	global_load_dword v116, v[10:11], off offset:304
	s_waitcnt vmcnt(0) lgkmcnt(0)
	v_add_f32_e32 v115, v115, v116
	global_load_dword v116, v[12:13], off offset:288
	global_load_dword v117, v[12:13], off offset:304
	s_waitcnt vmcnt(0) lgkmcnt(0)
	v_add_f32_e32 v115, v115, v117
	global_load_dword v117, v[14:15], off offset:288
	global_load_dword v118, v[14:15], off offset:304
	s_waitcnt vmcnt(0) lgkmcnt(0)
	v_add_f32_e32 v115, v115, v118
	global_load_dword v118, v[16:17], off offset:288
	global_load_dword v119, v[16:17], off offset:304
	s_waitcnt vmcnt(0) lgkmcnt(0)
	v_add_f32_e32 v115, v115, v119
	global_load_dword v119, v[18:19], off offset:288
	global_load_dword v120, v[18:19], off offset:304
	s_waitcnt vmcnt(0) lgkmcnt(0)
	v_add_f32_e32 v115, v115, v120
	global_load_dword v120, v[22:23], off offset:288
	global_load_dword v121, v[22:23], off offset:304
	s_waitcnt vmcnt(0) lgkmcnt(0)
	v_add_f32_e32 v115, v115, v121
	v_min_f32_e32 v121, 0, v115
	v_mul_f32_e64 v115, |v115|, s94
	v_exp_f32_e32 v115, v115
	s_nop 0
	v_add_f32_e32 v115, 1.0, v115
	v_cmp_gt_f32_e64 s[0:1], s48, v115
	s_nop 1
	v_cndmask_b32_e64 v122, 0, 32, s[0:1]
	v_ldexp_f32 v115, v115, v122
	v_log_f32_e32 v115, v115
	s_nop 0
	v_mul_f32_e32 v122, 0x3f317217, v115
	v_fma_f32 v122, v115, s49, -v122
	v_fmac_f32_e32 v122, 0x3377d1cf, v115
	v_fmac_f32_e32 v122, 0x3f317217, v115
	v_cmp_lt_f32_e64 s[38:39], |v115|, s36
	s_nop 1
	v_cndmask_b32_e64 v115, v115, v122, s[38:39]
	v_cndmask_b32_e64 v122, 0, v192, s[0:1]
	v_sub_f32_e32 v115, v115, v122
	v_sub_f32_e32 v115, v121, v115
	global_load_dword v121, v[8:9], off offset:320
	global_load_dword v122, v[8:9], off offset:336
	global_load_dword v123, v[20:21], off offset:320
	global_load_dword v124, v[20:21], off offset:336
	v_add_f32_e32 v115, v109, v115
	s_waitcnt vmcnt(0) lgkmcnt(0)
; __device__ __forceinline__ float logsig(float x) { return fminf(x, 0.f) - __logf(1.f + __expf(-fabsf(x))); }
; __device__ void gate_scan(const Ctx& p) {
;     ...
;     for (int e = 0; e < 16; ++e) {
;       long tok = (long)b * SEQ + tid * 16 + e;
;       float si = bi, sf = bf;
; #pragma unroll
;       for (int cgp = 0; cgp < 8; ++cgp) {
;         si += gpart[((long)cgp * NTOK + tok) * 8 + h];
;         sf += gpart[((long)cgp * NTOK + tok) * 8 + 4 + h];
;       }
;       ip[e] = si;
;       run += logsig(sf);
;       lf[e] = run;
;     }
	v_add_f32_e32 v122, v58, v122
	v_add_f32_e32 v122, v122, v124
	global_load_dword v124, v[10:11], off offset:320
	global_load_dword v125, v[10:11], off offset:336
	s_waitcnt vmcnt(0) lgkmcnt(0)
	v_add_f32_e32 v122, v122, v125
	global_load_dword v125, v[12:13], off offset:320
	global_load_dword v126, v[12:13], off offset:336
	s_waitcnt vmcnt(0) lgkmcnt(0)
	v_add_f32_e32 v122, v122, v126
	global_load_dword v126, v[14:15], off offset:320
	global_load_dword v127, v[14:15], off offset:336
	s_waitcnt vmcnt(0) lgkmcnt(0)
	v_add_f32_e32 v122, v122, v127
	global_load_dword v127, v[16:17], off offset:320
	global_load_dword v128, v[16:17], off offset:336
	s_waitcnt vmcnt(0) lgkmcnt(0)
	v_add_f32_e32 v122, v122, v128
	global_load_dword v128, v[18:19], off offset:320
	global_load_dword v129, v[18:19], off offset:336
	s_waitcnt vmcnt(0) lgkmcnt(0)
	v_add_f32_e32 v122, v122, v129
	global_load_dword v129, v[22:23], off offset:320
	global_load_dword v130, v[22:23], off offset:336
	s_waitcnt vmcnt(0) lgkmcnt(0)
	v_add_f32_e32 v122, v122, v130
	v_min_f32_e32 v130, 0, v122
	v_mul_f32_e64 v122, |v122|, s94
	v_exp_f32_e32 v122, v122
	s_nop 0
	v_add_f32_e32 v122, 1.0, v122
	v_cmp_gt_f32_e64 s[0:1], s48, v122
	s_nop 1
	v_cndmask_b32_e64 v131, 0, 32, s[0:1]
	v_ldexp_f32 v122, v122, v131
	v_log_f32_e32 v122, v122
	s_nop 0
	v_mul_f32_e32 v131, 0x3f317217, v122
	v_fma_f32 v131, v122, s49, -v131
	v_fmac_f32_e32 v131, 0x3377d1cf, v122
	v_fmac_f32_e32 v131, 0x3f317217, v122
	v_cmp_lt_f32_e64 s[38:39], |v122|, s36
	s_nop 1
	v_cndmask_b32_e64 v122, v122, v131, s[38:39]
	v_cndmask_b32_e64 v131, 0, v192, s[0:1]
	v_sub_f32_e32 v122, v122, v131
	v_sub_f32_e32 v122, v130, v122
	global_load_dword v130, v[8:9], off offset:352
	global_load_dword v131, v[8:9], off offset:368
	v_add_f32_e32 v122, v115, v122
	s_waitcnt vmcnt(0) lgkmcnt(0)
	v_add_f32_e32 v132, v58, v131
	global_load_dword v131, v[20:21], off offset:352
	global_load_dword v133, v[20:21], off offset:368
	s_waitcnt vmcnt(0) lgkmcnt(0)
	v_add_f32_e32 v133, v132, v133
	global_load_dword v132, v[10:11], off offset:352
	global_load_dword v134, v[10:11], off offset:368
	s_waitcnt vmcnt(0) lgkmcnt(0)
	v_add_f32_e32 v134, v133, v134
	global_load_dword v133, v[12:13], off offset:352
	global_load_dword v135, v[12:13], off offset:368
	s_waitcnt vmcnt(0) lgkmcnt(0)
	v_add_f32_e32 v135, v134, v135
	global_load_dword v134, v[14:15], off offset:352
	global_load_dword v136, v[14:15], off offset:368
	s_waitcnt vmcnt(0) lgkmcnt(0)
	v_add_f32_e32 v135, v135, v136
	global_load_dword v136, v[16:17], off offset:352
	global_load_dword v141, v[16:17], off offset:368
	s_waitcnt vmcnt(0) lgkmcnt(0)
	v_add_f32_e32 v135, v135, v141
	global_load_dword v141, v[18:19], off offset:352
	global_load_dword v142, v[18:19], off offset:368
	s_waitcnt vmcnt(0) lgkmcnt(0)
	v_add_f32_e32 v135, v135, v142
	global_load_dword v142, v[22:23], off offset:352
	global_load_dword v143, v[22:23], off offset:368
	s_waitcnt vmcnt(0) lgkmcnt(0)
	v_add_f32_e32 v135, v135, v143
	v_min_f32_e32 v143, 0, v135
	v_mul_f32_e64 v135, |v135|, s94
	v_exp_f32_e32 v135, v135
	s_nop 0
	v_add_f32_e32 v135, 1.0, v135
	v_cmp_gt_f32_e64 s[0:1], s48, v135
	s_nop 1
	v_cndmask_b32_e64 v144, 0, 32, s[0:1]
	v_ldexp_f32 v135, v135, v144
	v_log_f32_e32 v135, v135
	s_nop 0
	v_mul_f32_e32 v144, 0x3f317217, v135
	v_fma_f32 v144, v135, s49, -v144
	v_fmac_f32_e32 v144, 0x3377d1cf, v135
	v_fmac_f32_e32 v144, 0x3f317217, v135
	v_cmp_lt_f32_e64 s[38:39], |v135|, s36
	s_nop 1
	v_cndmask_b32_e64 v135, v135, v144, s[38:39]
	v_cndmask_b32_e64 v144, 0, v192, s[0:1]
	v_sub_f32_e32 v135, v135, v144
	v_sub_f32_e32 v135, v143, v135
	global_load_dword v143, v[8:9], off offset:384
	global_load_dword v144, v[8:9], off offset:400
	v_add_f32_e32 v135, v122, v135
	s_waitcnt vmcnt(0) lgkmcnt(0)
	v_add_f32_e32 v145, v58, v144
	global_load_dword v144, v[20:21], off offset:384
	global_load_dword v146, v[20:21], off offset:400
	s_waitcnt vmcnt(0) lgkmcnt(0)
	v_add_f32_e32 v146, v145, v146
	global_load_dword v145, v[10:11], off offset:384
	global_load_dword v147, v[10:11], off offset:400
	s_waitcnt vmcnt(0) lgkmcnt(0)
	v_add_f32_e32 v147, v146, v147
	global_load_dword v146, v[12:13], off offset:384
	global_load_dword v148, v[12:13], off offset:400
	s_waitcnt vmcnt(0) lgkmcnt(0)
	v_add_f32_e32 v148, v147, v148
	global_load_dword v147, v[14:15], off offset:384
	global_load_dword v149, v[14:15], off offset:400
	s_waitcnt vmcnt(0) lgkmcnt(0)
	v_add_f32_e32 v149, v148, v149
	global_load_dword v148, v[16:17], off offset:384
	global_load_dword v150, v[16:17], off offset:400
	s_waitcnt vmcnt(0) lgkmcnt(0)
	v_add_f32_e32 v150, v149, v150
	global_load_dword v149, v[18:19], off offset:384
	global_load_dword v151, v[18:19], off offset:400
	s_waitcnt vmcnt(0) lgkmcnt(0)
	v_add_f32_e32 v150, v150, v151
	global_load_dword v151, v[22:23], off offset:384
	global_load_dword v152, v[22:23], off offset:400
	s_waitcnt vmcnt(0) lgkmcnt(0)
	v_add_f32_e32 v150, v150, v152
	v_min_f32_e32 v152, 0, v150
	v_mul_f32_e64 v150, |v150|, s94
	v_exp_f32_e32 v150, v150
	s_nop 0
	v_add_f32_e32 v150, 1.0, v150
	v_cmp_gt_f32_e64 s[0:1], s48, v150
	s_nop 1
	v_cndmask_b32_e64 v153, 0, 32, s[0:1]
	v_ldexp_f32 v150, v150, v153
	v_log_f32_e32 v150, v150
	s_nop 0
	v_mul_f32_e32 v153, 0x3f317217, v150
	v_fma_f32 v153, v150, s49, -v153
	v_fmac_f32_e32 v153, 0x3377d1cf, v150
	v_fmac_f32_e32 v153, 0x3f317217, v150
	v_cmp_lt_f32_e64 s[38:39], |v150|, s36
	s_nop 1
	v_cndmask_b32_e64 v150, v150, v153, s[38:39]
	v_cndmask_b32_e64 v153, 0, v192, s[0:1]
	v_sub_f32_e32 v150, v150, v153
	v_sub_f32_e32 v150, v152, v150
	global_load_dword v152, v[8:9], off offset:416
	global_load_dword v153, v[8:9], off offset:432
	v_add_f32_e32 v150, v135, v150
	s_waitcnt vmcnt(0) lgkmcnt(0)
; __device__ __forceinline__ float logsig(float x) { return fminf(x, 0.f) - __logf(1.f + __expf(-fabsf(x))); }
; __device__ void gate_scan(const Ctx& p) {
;     ...
;     for (int e = 0; e < 16; ++e) {
;       long tok = (long)b * SEQ + tid * 16 + e;
;       float si = bi, sf = bf;
; #pragma unroll
;       for (int cgp = 0; cgp < 8; ++cgp) {
;         si += gpart[((long)cgp * NTOK + tok) * 8 + h];
;         sf += gpart[((long)cgp * NTOK + tok) * 8 + 4 + h];
;       }
;       ip[e] = si;
;       run += logsig(sf);
;       lf[e] = run;
;     }
;     const int lane = tid & 63, w = tid >> 6;
;     float sc = run;
; #pragma unroll
;     for (int o = 1; o < 64; o <<= 1) { const float t = __shfl_up(sc, o, 64); if (lane >= o) sc += t; }
;     __syncthreads();
;     if (lane == 63) red[w] = sc;
;     __syncthreads();
;     float woff = 0.f;
; #pragma unroll
;     for (int i = 0; i < 8; ++i) { const float v = red[i]; if (i < w) woff += v; }
	v_add_f32_e32 v154, v58, v153
	global_load_dword v153, v[20:21], off offset:416
	global_load_dword v155, v[20:21], off offset:432
	s_waitcnt vmcnt(0) lgkmcnt(0)
	v_add_f32_e32 v155, v154, v155
	global_load_dword v154, v[10:11], off offset:416
	global_load_dword v156, v[10:11], off offset:432
	s_waitcnt vmcnt(0) lgkmcnt(0)
	v_add_f32_e32 v156, v155, v156
	global_load_dword v155, v[12:13], off offset:416
	global_load_dword v157, v[12:13], off offset:432
	s_waitcnt vmcnt(0) lgkmcnt(0)
	v_add_f32_e32 v156, v156, v157
	global_load_dword v157, v[14:15], off offset:416
	global_load_dword v158, v[14:15], off offset:432
	s_waitcnt vmcnt(0) lgkmcnt(0)
	v_add_f32_e32 v156, v156, v158
	global_load_dword v158, v[16:17], off offset:416
	global_load_dword v159, v[16:17], off offset:432
	s_waitcnt vmcnt(0) lgkmcnt(0)
	v_add_f32_e32 v156, v156, v159
	global_load_dword v159, v[18:19], off offset:416
	global_load_dword v160, v[18:19], off offset:432
	s_waitcnt vmcnt(0) lgkmcnt(0)
	v_add_f32_e32 v156, v156, v160
	global_load_dword v160, v[22:23], off offset:416
	global_load_dword v161, v[22:23], off offset:432
	s_waitcnt vmcnt(0) lgkmcnt(0)
	v_add_f32_e32 v156, v156, v161
	v_min_f32_e32 v161, 0, v156
	v_mul_f32_e64 v156, |v156|, s94
	v_exp_f32_e32 v156, v156
	s_nop 0
	v_add_f32_e32 v156, 1.0, v156
	v_cmp_gt_f32_e64 s[0:1], s48, v156
	s_nop 1
	v_cndmask_b32_e64 v162, 0, 32, s[0:1]
	v_ldexp_f32 v156, v156, v162
	v_log_f32_e32 v156, v156
	s_nop 0
	v_mul_f32_e32 v162, 0x3f317217, v156
	v_fma_f32 v162, v156, s49, -v162
	v_fmac_f32_e32 v162, 0x3377d1cf, v156
	v_fmac_f32_e32 v162, 0x3f317217, v156
	v_cmp_lt_f32_e64 s[38:39], |v156|, s36
	s_nop 1
	v_cndmask_b32_e64 v156, v156, v162, s[38:39]
	v_cndmask_b32_e64 v162, 0, v192, s[0:1]
	v_sub_f32_e32 v156, v156, v162
	v_sub_f32_e32 v156, v161, v156
	global_load_dword v161, v[8:9], off offset:448
	global_load_dword v162, v[8:9], off offset:464
	global_load_dword v163, v[20:21], off offset:448
	global_load_dword v164, v[20:21], off offset:464
	v_add_f32_e32 v156, v150, v156
	s_waitcnt vmcnt(0) lgkmcnt(0)
	v_add_f32_e32 v162, v58, v162
	v_add_f32_e32 v162, v162, v164
	global_load_dword v164, v[10:11], off offset:448
	global_load_dword v165, v[10:11], off offset:464
	s_waitcnt vmcnt(0) lgkmcnt(0)
	v_add_f32_e32 v162, v162, v165
	global_load_dword v165, v[12:13], off offset:448
	global_load_dword v166, v[12:13], off offset:464
	s_waitcnt vmcnt(0) lgkmcnt(0)
	v_add_f32_e32 v162, v162, v166
	global_load_dword v166, v[14:15], off offset:448
	global_load_dword v167, v[14:15], off offset:464
	s_waitcnt vmcnt(0) lgkmcnt(0)
	v_add_f32_e32 v162, v162, v167
	global_load_dword v167, v[16:17], off offset:448
	global_load_dword v168, v[16:17], off offset:464
	s_waitcnt vmcnt(0) lgkmcnt(0)
	v_add_f32_e32 v162, v162, v168
	global_load_dword v168, v[18:19], off offset:448
	global_load_dword v169, v[18:19], off offset:464
	s_waitcnt vmcnt(0) lgkmcnt(0)
	v_add_f32_e32 v162, v162, v169
	global_load_dword v169, v[22:23], off offset:448
	global_load_dword v170, v[22:23], off offset:464
	s_waitcnt vmcnt(0) lgkmcnt(0)
	v_add_f32_e32 v162, v162, v170
	v_min_f32_e32 v170, 0, v162
	v_mul_f32_e64 v162, |v162|, s94
	v_exp_f32_e32 v162, v162
	s_nop 0
	v_add_f32_e32 v162, 1.0, v162
	v_cmp_gt_f32_e64 s[0:1], s48, v162
	s_nop 1
	v_cndmask_b32_e64 v171, 0, 32, s[0:1]
	v_ldexp_f32 v162, v162, v171
	v_log_f32_e32 v162, v162
	s_nop 0
	v_mul_f32_e32 v171, 0x3f317217, v162
	v_fma_f32 v171, v162, s49, -v171
	v_fmac_f32_e32 v171, 0x3377d1cf, v162
	v_fmac_f32_e32 v171, 0x3f317217, v162
	v_cmp_lt_f32_e64 s[38:39], |v162|, s36
	s_nop 1
	v_cndmask_b32_e64 v162, v162, v171, s[38:39]
	v_cndmask_b32_e64 v171, 0, v192, s[0:1]
	v_sub_f32_e32 v162, v162, v171
	v_sub_f32_e32 v162, v170, v162
	global_load_dword v170, v[8:9], off offset:480
	s_nop 0
	global_load_dword v8, v[8:9], off offset:496
	v_add_f32_e32 v162, v156, v162
	s_waitcnt vmcnt(0) lgkmcnt(0)
	v_add_f32_e32 v9, v58, v8
	global_load_dword v8, v[20:21], off offset:480
	s_nop 0
	global_load_dword v20, v[20:21], off offset:496
	s_waitcnt vmcnt(0) lgkmcnt(0)
	v_add_f32_e32 v20, v9, v20
	global_load_dword v9, v[10:11], off offset:480
	s_nop 0
	global_load_dword v10, v[10:11], off offset:496
	s_waitcnt vmcnt(0) lgkmcnt(0)
	v_add_f32_e32 v11, v20, v10
	global_load_dword v10, v[12:13], off offset:480
	s_nop 0
	global_load_dword v12, v[12:13], off offset:496
	s_waitcnt vmcnt(0) lgkmcnt(0)
	v_add_f32_e32 v12, v11, v12
	global_load_dword v11, v[14:15], off offset:480
	global_load_dword v13, v[14:15], off offset:496
	s_waitcnt vmcnt(0) lgkmcnt(0)
	v_add_f32_e32 v13, v12, v13
	global_load_dword v12, v[16:17], off offset:480
	global_load_dword v14, v[16:17], off offset:496
	s_waitcnt vmcnt(0) lgkmcnt(0)
	v_add_f32_e32 v14, v13, v14
	global_load_dword v13, v[18:19], off offset:480
	global_load_dword v15, v[18:19], off offset:496
	s_waitcnt vmcnt(0) lgkmcnt(0)
	v_add_f32_e32 v15, v14, v15
	global_load_dword v14, v[22:23], off offset:480
	global_load_dword v16, v[22:23], off offset:496
	s_waitcnt lgkmcnt(0)
	s_barrier
	s_waitcnt vmcnt(0)
	v_add_f32_e32 v15, v15, v16
	v_min_f32_e32 v16, 0, v15
	v_mul_f32_e64 v15, |v15|, s94
	v_exp_f32_e32 v15, v15
	s_nop 0
	v_add_f32_e32 v15, 1.0, v15
	v_cmp_gt_f32_e64 s[0:1], s48, v15
	s_nop 1
	v_cndmask_b32_e64 v17, 0, 32, s[0:1]
	v_ldexp_f32 v15, v15, v17
	v_log_f32_e32 v15, v15
	s_nop 0
	v_mul_f32_e32 v17, 0x3f317217, v15
	v_fma_f32 v17, v15, s49, -v17
	v_fmac_f32_e32 v17, 0x3377d1cf, v15
	v_fmac_f32_e32 v17, 0x3f317217, v15
	v_cmp_lt_f32_e64 s[38:39], |v15|, s36
	s_nop 1
	v_cndmask_b32_e64 v15, v15, v17, s[38:39]
	v_cndmask_b32_e64 v17, 0, v192, s[0:1]
	v_sub_f32_e32 v15, v15, v17
	v_sub_f32_e32 v15, v16, v15
	v_add_f32_e32 v58, v162, v15
	ds_bpermute_b32 v15, v24, v58
	s_waitcnt lgkmcnt(0)
	v_add_f32_e32 v15, v58, v15
	v_cndmask_b32_e64 v15, v15, v58, s[4:5]
	ds_bpermute_b32 v16, v25, v15
	s_waitcnt lgkmcnt(0)
	v_add_f32_e32 v16, v15, v16
	v_cndmask_b32_e64 v15, v16, v15, s[6:7]
	ds_bpermute_b32 v16, v26, v15
	s_waitcnt lgkmcnt(0)
	v_add_f32_e32 v16, v15, v16
	v_cndmask_b32_e64 v15, v16, v15, s[8:9]
	ds_bpermute_b32 v16, v27, v15
	s_waitcnt lgkmcnt(0)
	v_add_f32_e32 v16, v15, v16
	v_cndmask_b32_e64 v15, v16, v15, s[10:11]
	ds_bpermute_b32 v16, v28, v15
	s_waitcnt lgkmcnt(0)
	v_add_f32_e32 v16, v15, v16
	v_cndmask_b32_e64 v15, v16, v15, s[12:13]
	ds_bpermute_b32 v16, v29, v15
	s_waitcnt lgkmcnt(0)
	v_add_f32_e32 v16, v15, v16
	s_and_saveexec_b64 s[0:1], vcc
	ds_write_b32 v0, v16
	s_or_b64 exec, exec, s[0:1]
	v_mov_b32_e32 v17, 0
	s_waitcnt lgkmcnt(0)
	s_barrier
	s_and_saveexec_b64 s[0:1], s[16:17]
	s_cbranch_execz .LBB0_44
	ds_read_b32 v17, v203
	s_waitcnt lgkmcnt(0)
	v_add_f32_e32 v17, 0, v17
	s_or_b64 exec, exec, s[0:1]
	s_and_saveexec_b64 s[0:1], s[18:19]
	s_cbranch_execnz .LBB0_45

;   __device__ __forceinline__ const float* in(int i) const { return ((const float* const*)(ws + OFF_TBL))[i]; }
; __device__ __forceinline__ int ltid() { int t = threadIdx.x; asm volatile("" : "+v"(t)); return t; }
;   const int tid = ltid();
;   const int kg = tid & 7, ng = tid >> 3;
;   const int tn = Nd / 256, tk = R / 64;
;   if (nblk == 0) nblk = gridDim.x;
;   if ((int)blockIdx.x < blk0 || (int)blockIdx.x >= blk0 + nblk) return;
;   for (int t = (int)blockIdx.x - blk0; t < tn * tk; t += nblk) {
;     const int n0 = (t / tk) * 256 + ng * 4, k0 = (t % tk) * 64 + kg * 8;
;     int c = n0;
;     if (mode == 1) c = (n0 < 6144) ? n0 : (n0 < 15360 ? n0 + 16 : (n0 < 15376 ? 6144 + (n0 - 15360) : -1));
;     float4 v[8];
; #pragma unroll
;     for (int r = 0; r < 8; ++r) v[r] = (c >= 0) ? *(const float4*)(src + (long)(k0 + r) * C + c) : make_float4(0.f, 0.f, 0.f, 0.f);
;     uint4 o;
;     o.x = pack2(v[0].x, v[1].x); o.y = pack2(v[2].x, v[3].x); o.z = pack2(v[4].x, v[5].x); o.w = pack2(v[6].x, v[7].x);
;     *(uint4*)(dst + (long)(n0 + 0) * R + k0) = o;
;     o.x = pack2(v[0].y, v[1].y); o.y = pack2(v[2].y, v[3].y); o.z = pack2(v[4].y, v[5].y); o.w = pack2(v[6].y, v[7].y);
;     *(uint4*)(dst + (long)(n0 + 1) * R + k0) = o;
;     o.x = pack2(v[0].z, v[1].z); o.y = pack2(v[2].z, v[3].z); o.z = pack2(v[4].z, v[5].z); o.w = pack2(v[6].z, v[7].z);
;     *(uint4*)(dst + (long)(n0 + 2) * R + k0) = o;
;     o.x = pack2(v[0].w, v[1].w); o.y = pack2(v[2].w, v[3].w); o.z = pack2(v[4].w, v[5].w); o.w = pack2(v[6].w, v[7].w);
;     *(uint4*)(dst + (long)(n0 + 3) * R + k0) = o;
;   }
; __device__ __forceinline__ void run_phase(char* ws_in, int ph, int dry) {
;     ...
;     if (gridDim.x > 16) transpose_cvt(p.in(25), 8704, DM, (u16*)(ws + OFF_WO1T), DM, 0, 8, (int)gridDim.x - 8);
.LBB0_73:
	v_mov_b32_e32 v0, s66
	s_waitcnt vmcnt(0) lgkmcnt(0)
	v_add_co_u32_e32 v2, vcc, 0x4375c000, v0
	v_mov_b32_e32 v0, s67
	s_nop 0
	v_addc_co_u32_e32 v3, vcc, 0, v0, vcc
	global_load_dwordx2 v[34:35], v[2:3], off offset:200
	v_readlane_b32 s4, v253, 0
	v_readlane_b32 s5, v253, 1
	s_load_dword s0, s[4:5], 0x10
	s_nop 0
	s_load_dword s4, s[4:5], 0x0
	s_mov_b32 s69, 0x100000
	s_waitcnt lgkmcnt(0)
	s_lshr_b32 s0, s0, 16
	s_cmp_lg_u32 s0, 0
	s_cselect_b64 s[0:1], -1, 0
	s_cmp_lg_u64 s[0:1], 0
	s_addc_u32 s8, s4, 0
	s_add_u32 s4, s66, 0x36800000
	s_addc_u32 s5, s67, 0
	s_cmp_lt_u32 s8, 17
	s_mov_b64 s[0:1], -1
	s_cbranch_scc0 .LBB0_94
	s_cmp_lt_u32 s63, s8
	v_readlane_b32 s6, v253, 36
	s_cselect_b64 s[0:1], -1, 0
	v_readlane_b32 s7, v253, 37
	s_and_b64 s[0:1], s[6:7], s[0:1]
	v_mov_b32_e32 v0, v139
	s_andn2_b64 vcc, exec, s[0:1]
	s_cbranch_vccnz .LBB0_93
	v_ashrrev_i32_e32 v2, 1, v0
	v_and_b32_e32 v40, -4, v2
	v_lshlrev_b32_e32 v2, 3, v0
	v_and_b32_e32 v0, 7, v0
	v_readlane_b32 s0, v252, 13
	v_and_b32_e32 v2, 56, v2
	s_lshl_b32 s9, s8, 18
	v_lshl_add_u32 v41, v0, 15, s0
	v_readlane_b32 s0, v252, 14
	s_lshl_b32 s10, s8, 6
	s_mov_b32 s11, s63
	v_add_u32_e32 v42, s0, v2
	s_branch .LBB0_77
.LBB0_76:
	s_or_b64 exec, exec, s[6:7]
	s_mulk_i32 s12, 0x2200
	v_subrev_u32_e32 v44, s12, v42
	v_mov_b64_e32 v[46:47], s[4:5]
	v_mov_b32_e32 v45, v1
	v_mad_i64_i32 v[48:49], s[0:1], v0, s45, v[46:47]
	v_lshlrev_b64 v[44:45], 1, v[44:45]
	s_waitcnt vmcnt(0) lgkmcnt(0)
	v_cvt_pk_bf16_f32 v36, v2, v6
	v_cvt_pk_bf16_f32 v37, v14, v10
	v_cvt_pk_bf16_f32 v38, v22, v18
	v_cvt_pk_bf16_f32 v39, v30, v26
	v_lshl_add_u64 v[48:49], v[48:49], 0, v[44:45]
	v_or_b32_e32 v2, 1, v0
	global_store_dwordx4 v[48:49], v[36:39], off
	s_add_i32 s11, s11, s8
	v_add_u32_e32 v41, s9, v41
	v_cvt_pk_bf16_f32 v36, v3, v7
	v_mad_i64_i32 v[2:3], s[0:1], v2, s45, v[46:47]
	v_cvt_pk_bf16_f32 v37, v15, v11
	v_cvt_pk_bf16_f32 v38, v23, v19
	v_cvt_pk_bf16_f32 v39, v31, v27
	v_lshl_add_u64 v[2:3], v[2:3], 0, v[44:45]
	global_store_dwordx4 v[2:3], v[36:39], off
	v_or_b32_e32 v2, 2, v0
	v_mad_i64_i32 v[2:3], s[0:1], v2, s45, v[46:47]
	v_or_b32_e32 v0, 3, v0
	v_cvt_pk_bf16_f32 v36, v4, v8
	v_cvt_pk_bf16_f32 v37, v16, v12
	v_cvt_pk_bf16_f32 v38, v24, v20
	v_cvt_pk_bf16_f32 v39, v32, v28
	v_lshl_add_u64 v[2:3], v[2:3], 0, v[44:45]
	v_mad_i64_i32 v[6:7], s[0:1], v0, s45, v[46:47]
	global_store_dwordx4 v[2:3], v[36:39], off
	v_cvt_pk_bf16_f32 v2, v5, v9
	v_cvt_pk_bf16_f32 v3, v17, v13
	v_cvt_pk_bf16_f32 v4, v25, v21
	v_cvt_pk_bf16_f32 v5, v33, v29
	v_lshl_add_u64 v[6:7], v[6:7], 0, v[44:45]
	s_cmpk_gt_i32 s11, 0x87f
	v_add_u32_e32 v42, s10, v42
	global_store_dwordx4 v[6:7], v[2:5], off
	s_cbranch_scc1 .LBB0_93
.LBB0_77:
	s_mul_hi_u32 s0, s11, 0xf0f0f0f1
	s_lshr_b32 s12, s0, 7
	s_mul_i32 s0, s12, 0x2200000
	v_lshl_add_u32 v0, s12, 8, v40
	v_subrev_u32_e32 v36, s0, v41
	v_cmp_lt_i32_e64 s[0:1], -1, v0
	s_waitcnt vmcnt(0)
	v_lshl_add_u64 v[38:39], v[0:1], 2, v[34:35]
	v_mov_b32_e32 v8, 0
	v_mov_b32_e32 v4, 0
	v_mov_b32_e32 v5, 0
	v_mov_b32_e32 v2, 0
	v_mov_b32_e32 v3, 0
	s_and_saveexec_b64 s[6:7], s[0:1]
	s_cbranch_execz .LBB0_79
	v_mov_b32_e32 v37, v1
	v_lshl_add_u64 v[2:3], v[36:37], 2, v[38:39]
	global_load_dwordx4 v[2:5], v[2:3], off
.LBB0_79:
	s_or_b64 exec, exec, s[6:7]
	v_mov_b32_e32 v9, 0
	v_mov_b32_e32 v6, 0
	v_mov_b32_e32 v7, 0
	s_and_saveexec_b64 s[6:7], s[0:1]
	s_cbranch_execz .LBB0_81
	v_mov_b32_e32 v37, v1
	v_lshl_add_u64 v[6:7], v[36:37], 2, v[38:39]
	v_add_co_u32_e32 v6, vcc, 0x4000, v6
	s_nop 1
	v_addc_co_u32_e32 v7, vcc, 0, v7, vcc
	global_load_dwordx4 v[6:9], v[6:7], off
.LBB0_81:
	s_or_b64 exec, exec, s[6:7]
	v_mov_b32_e32 v12, 0
	v_mov_b32_e32 v16, 0
	v_mov_b32_e32 v17, 0
	v_mov_b32_e32 v14, 0
	v_mov_b32_e32 v15, 0
	s_and_saveexec_b64 s[6:7], s[0:1]
	s_cbranch_execz .LBB0_83
	v_mov_b32_e32 v37, v1
	v_lshl_add_u64 v[10:11], v[36:37], 2, v[38:39]
	v_add_co_u32_e32 v10, vcc, 0x8000, v10
	s_nop 1
	v_addc_co_u32_e32 v11, vcc, 0, v11, vcc
	global_load_dwordx4 v[14:17], v[10:11], off
.LBB0_83:
	s_or_b64 exec, exec, s[6:7]
	v_mov_b32_e32 v13, 0
	v_mov_b32_e32 v10, 0
	v_mov_b32_e32 v11, 0
	s_and_saveexec_b64 s[6:7], s[0:1]
	s_cbranch_execz .LBB0_85
	v_mov_b32_e32 v37, v1
	v_lshl_add_u64 v[10:11], v[36:37], 2, v[38:39]
	v_add_co_u32_e32 v10, vcc, 0xc000, v10
	s_nop 1
	v_addc_co_u32_e32 v11, vcc, 0, v11, vcc
	global_load_dwordx4 v[10:13], v[10:11], off
.LBB0_85:
	s_or_b64 exec, exec, s[6:7]
	v_mov_b32_e32 v20, 0
	v_mov_b32_e32 v24, 0
	v_mov_b32_e32 v25, 0
	v_mov_b32_e32 v22, 0
	v_mov_b32_e32 v23, 0
	s_and_saveexec_b64 s[6:7], s[0:1]
	s_cbranch_execz .LBB0_87
	v_mov_b32_e32 v37, v1
	v_lshl_add_u64 v[18:19], v[36:37], 2, v[38:39]
	v_add_co_u32_e32 v18, vcc, 0x10000, v18
	s_nop 1
	v_addc_co_u32_e32 v19, vcc, 0, v19, vcc
	global_load_dwordx4 v[22:25], v[18:19], off
.LBB0_87:
	s_or_b64 exec, exec, s[6:7]
	v_mov_b32_e32 v21, 0
	v_mov_b32_e32 v18, 0
	v_mov_b32_e32 v19, 0
	s_and_saveexec_b64 s[6:7], s[0:1]
	s_cbranch_execz .LBB0_89
	v_mov_b32_e32 v37, v1
	v_lshl_add_u64 v[18:19], v[36:37], 2, v[38:39]
	v_add_co_u32_e32 v18, vcc, 0x14000, v18
	s_nop 1
	v_addc_co_u32_e32 v19, vcc, 0, v19, vcc
	global_load_dwordx4 v[18:21], v[18:19], off
.LBB0_89:
	s_or_b64 exec, exec, s[6:7]
	v_mov_b32_e32 v28, 0
	v_mov_b32_e32 v32, 0
	v_mov_b32_e32 v33, 0
	v_mov_b32_e32 v30, 0
	v_mov_b32_e32 v31, 0
	s_and_saveexec_b64 s[6:7], s[0:1]
	s_cbranch_execz .LBB0_91
	v_mov_b32_e32 v37, v1
	v_lshl_add_u64 v[26:27], v[36:37], 2, v[38:39]
	v_add_co_u32_e32 v26, vcc, 0x18000, v26
	s_nop 1
	v_addc_co_u32_e32 v27, vcc, 0, v27, vcc
	global_load_dwordx4 v[30:33], v[26:27], off
.LBB0_91:
	s_or_b64 exec, exec, s[6:7]
	v_mov_b32_e32 v29, 0
	v_mov_b32_e32 v26, 0
	v_mov_b32_e32 v27, 0
	s_and_saveexec_b64 s[6:7], s[0:1]
	s_cbranch_execz .LBB0_76
	v_mov_b32_e32 v37, v1
	v_lshl_add_u64 v[26:27], v[36:37], 2, v[38:39]
	v_add_co_u32_e32 v26, vcc, 0x1c000, v26
	s_nop 1
	v_addc_co_u32_e32 v27, vcc, 0, v27, vcc
	global_load_dwordx4 v[26:29], v[26:27], off
	s_branch .LBB0_76

;   __device__ __forceinline__ const float* in(int i) const { return ((const float* const*)(ws + OFF_TBL))[i]; }
; __device__ __forceinline__ int ltid() { int t = threadIdx.x; asm volatile("" : "+v"(t)); return t; }
;   const int tid = ltid();
;   const int kg = tid & 7, ng = tid >> 3;
;   const int tn = Nd / 256, tk = R / 64;
;   if (nblk == 0) nblk = gridDim.x;
;   if ((int)blockIdx.x < blk0 || (int)blockIdx.x >= blk0 + nblk) return;
;   for (int t = (int)blockIdx.x - blk0; t < tn * tk; t += nblk) {
;     const int n0 = (t / tk) * 256 + ng * 4, k0 = (t % tk) * 64 + kg * 8;
;     int c = n0;
;     if (mode == 1) c = (n0 < 6144) ? n0 : (n0 < 15360 ? n0 + 16 : (n0 < 15376 ? 6144 + (n0 - 15360) : -1));
;     float4 v[8];
; #pragma unroll
;     for (int r = 0; r < 8; ++r) v[r] = (c >= 0) ? *(const float4*)(src + (long)(k0 + r) * C + c) : make_float4(0.f, 0.f, 0.f, 0.f);
;     uint4 o;
;     o.x = pack2(v[0].x, v[1].x); o.y = pack2(v[2].x, v[3].x); o.z = pack2(v[4].x, v[5].x); o.w = pack2(v[6].x, v[7].x);
;     *(uint4*)(dst + (long)(n0 + 0) * R + k0) = o;
;     o.x = pack2(v[0].y, v[1].y); o.y = pack2(v[2].y, v[3].y); o.z = pack2(v[4].y, v[5].y); o.w = pack2(v[6].y, v[7].y);
;     *(uint4*)(dst + (long)(n0 + 1) * R + k0) = o;
;     o.x = pack2(v[0].z, v[1].z); o.y = pack2(v[2].z, v[3].z); o.z = pack2(v[4].z, v[5].z); o.w = pack2(v[6].z, v[7].z);
;     *(uint4*)(dst + (long)(n0 + 2) * R + k0) = o;
;     o.x = pack2(v[0].w, v[1].w); o.y = pack2(v[2].w, v[3].w); o.z = pack2(v[4].w, v[5].w); o.w = pack2(v[6].w, v[7].w);
;     *(uint4*)(dst + (long)(n0 + 3) * R + k0) = o;
;   }
; __device__ __forceinline__ void run_phase(char* ws_in, int ph, int dry) {
;     ...
;     else transpose_cvt(p.in(25), 8704, DM, (u16*)(ws + OFF_WO1T), DM, 0);
.LBB0_97:
	s_or_b64 exec, exec, s[0:1]
	v_mov_b64_e32 v[46:47], s[4:5]
	v_mad_i64_i32 v[38:39], s[0:1], v0, s45, v[46:47]
	v_lshlrev_b64 v[48:49], 1, v[36:37]
	s_waitcnt vmcnt(0) lgkmcnt(0)
	v_cvt_pk_bf16_f32 v42, v2, v6
	v_cvt_pk_bf16_f32 v43, v14, v10
	v_cvt_pk_bf16_f32 v44, v22, v18
	v_cvt_pk_bf16_f32 v45, v30, v26
	v_lshl_add_u64 v[36:37], v[38:39], 0, v[48:49]
	v_or_b32_e32 v2, 1, v0
	global_store_dwordx4 v[36:37], v[42:45], off
	v_cvt_pk_bf16_f32 v36, v3, v7
	v_mad_i64_i32 v[2:3], s[0:1], v2, s45, v[46:47]
	v_cvt_pk_bf16_f32 v37, v15, v11
	v_cvt_pk_bf16_f32 v38, v23, v19
	v_cvt_pk_bf16_f32 v39, v31, v27
	v_lshl_add_u64 v[2:3], v[2:3], 0, v[48:49]
	global_store_dwordx4 v[2:3], v[36:39], off
	v_or_b32_e32 v2, 2, v0
	v_mad_i64_i32 v[2:3], s[0:1], v2, s45, v[46:47]
	v_or_b32_e32 v0, 3, v0
	v_cvt_pk_bf16_f32 v36, v4, v8
	v_cvt_pk_bf16_f32 v37, v16, v12
	v_cvt_pk_bf16_f32 v38, v24, v20
	v_cvt_pk_bf16_f32 v39, v32, v28
	v_lshl_add_u64 v[2:3], v[2:3], 0, v[48:49]
	v_mad_i64_i32 v[6:7], s[0:1], v0, s45, v[46:47]
	s_add_i32 s7, s7, s8
	global_store_dwordx4 v[2:3], v[36:39], off
	v_cvt_pk_bf16_f32 v2, v5, v9
	v_cvt_pk_bf16_f32 v3, v17, v13
	v_cvt_pk_bf16_f32 v4, v25, v21
	v_cvt_pk_bf16_f32 v5, v33, v29
	v_lshl_add_u64 v[6:7], v[6:7], 0, v[48:49]
	s_cmpk_gt_i32 s7, 0x87f
	v_add_u32_e32 v41, s6, v41
	global_store_dwordx4 v[6:7], v[2:5], off
	s_cbranch_scc1 .LBB0_114
.LBB0_98:
	s_mul_hi_i32 s0, s7, 0x78787879
	s_lshr_b32 s1, s0, 31
	s_ashr_i32 s0, s0, 6
	s_add_i32 s0, s0, s1
	v_lshl_add_u32 v0, s0, 8, v40
	s_mulk_i32 s0, 0xde00
	v_add_u32_e32 v36, s0, v41
	v_cmp_lt_i32_e32 vcc, -1, v0
	s_waitcnt vmcnt(0)
	v_lshl_add_u64 v[38:39], v[0:1], 2, v[34:35]
	v_mov_b32_e32 v8, 0
	v_ashrrev_i32_e32 v37, 31, v36
	v_mov_b32_e32 v4, 0
	v_mov_b32_e32 v5, 0
	v_mov_b32_e32 v2, 0
	v_mov_b32_e32 v3, 0
	s_and_saveexec_b64 s[0:1], vcc
	s_cbranch_execz .LBB0_100
	v_lshlrev_b64 v[2:3], 14, v[36:37]
	v_lshl_add_u64 v[2:3], v[38:39], 0, v[2:3]
	global_load_dwordx4 v[2:5], v[2:3], off
.LBB0_100:
	s_or_b64 exec, exec, s[0:1]
	v_mov_b32_e32 v9, 0
	v_mov_b32_e32 v6, 0
	v_mov_b32_e32 v7, 0
	s_and_saveexec_b64 s[0:1], vcc
	s_cbranch_execz .LBB0_102
	v_add_u32_e32 v6, 1, v36
	v_ashrrev_i32_e32 v7, 31, v6
	v_lshlrev_b64 v[6:7], 14, v[6:7]
	v_lshl_add_u64 v[6:7], v[38:39], 0, v[6:7]
	global_load_dwordx4 v[6:9], v[6:7], off
.LBB0_102:
	s_or_b64 exec, exec, s[0:1]
	v_mov_b32_e32 v12, 0
	v_mov_b32_e32 v16, 0
	v_mov_b32_e32 v17, 0
	v_mov_b32_e32 v14, 0
	v_mov_b32_e32 v15, 0
	s_and_saveexec_b64 s[0:1], vcc
	s_cbranch_execz .LBB0_104
	v_add_u32_e32 v10, 2, v36
	v_ashrrev_i32_e32 v11, 31, v10
	v_lshlrev_b64 v[10:11], 14, v[10:11]
	v_lshl_add_u64 v[10:11], v[38:39], 0, v[10:11]
	global_load_dwordx4 v[14:17], v[10:11], off
.LBB0_104:
	s_or_b64 exec, exec, s[0:1]
	v_mov_b32_e32 v13, 0
	v_mov_b32_e32 v10, 0
	v_mov_b32_e32 v11, 0
	s_and_saveexec_b64 s[0:1], vcc
	s_cbranch_execz .LBB0_106
	v_add_u32_e32 v10, 3, v36
	v_ashrrev_i32_e32 v11, 31, v10
	v_lshlrev_b64 v[10:11], 14, v[10:11]
	v_lshl_add_u64 v[10:11], v[38:39], 0, v[10:11]
	global_load_dwordx4 v[10:13], v[10:11], off
.LBB0_106:
	s_or_b64 exec, exec, s[0:1]
	v_mov_b32_e32 v20, 0
	v_mov_b32_e32 v24, 0
	v_mov_b32_e32 v25, 0
	v_mov_b32_e32 v22, 0
	v_mov_b32_e32 v23, 0
	s_and_saveexec_b64 s[0:1], vcc
	s_cbranch_execz .LBB0_108
	v_add_u32_e32 v18, 4, v36
	v_ashrrev_i32_e32 v19, 31, v18
	v_lshlrev_b64 v[18:19], 14, v[18:19]
	v_lshl_add_u64 v[18:19], v[38:39], 0, v[18:19]
	global_load_dwordx4 v[22:25], v[18:19], off
.LBB0_108:
	s_or_b64 exec, exec, s[0:1]
	v_mov_b32_e32 v21, 0
	v_mov_b32_e32 v18, 0
	v_mov_b32_e32 v19, 0
	s_and_saveexec_b64 s[0:1], vcc
	s_cbranch_execz .LBB0_110
	v_add_u32_e32 v18, 5, v36
	v_ashrrev_i32_e32 v19, 31, v18
	v_lshlrev_b64 v[18:19], 14, v[18:19]
	v_lshl_add_u64 v[18:19], v[38:39], 0, v[18:19]
	global_load_dwordx4 v[18:21], v[18:19], off
.LBB0_110:
	s_or_b64 exec, exec, s[0:1]
	v_mov_b32_e32 v28, 0
	v_mov_b32_e32 v32, 0
	v_mov_b32_e32 v33, 0
	v_mov_b32_e32 v30, 0
	v_mov_b32_e32 v31, 0
	s_and_saveexec_b64 s[0:1], vcc
	s_cbranch_execz .LBB0_112
	v_add_u32_e32 v26, 6, v36
	v_ashrrev_i32_e32 v27, 31, v26
	v_lshlrev_b64 v[26:27], 14, v[26:27]
	v_lshl_add_u64 v[26:27], v[38:39], 0, v[26:27]
	global_load_dwordx4 v[30:33], v[26:27], off
.LBB0_112:
	s_or_b64 exec, exec, s[0:1]
	v_mov_b32_e32 v29, 0
	v_mov_b32_e32 v26, 0
	v_mov_b32_e32 v27, 0
	s_and_saveexec_b64 s[0:1], vcc
	s_cbranch_execz .LBB0_97
	v_add_u32_e32 v26, 7, v36
	v_ashrrev_i32_e32 v27, 31, v26
	v_lshlrev_b64 v[26:27], 14, v[26:27]
	v_lshl_add_u64 v[26:27], v[38:39], 0, v[26:27]
	global_load_dwordx4 v[26:29], v[26:27], off
	s_branch .LBB0_97

;   __device__ __forceinline__ const float* in(int i) const { return ((const float* const*)(ws + OFF_TBL))[i]; }
; __device__ __forceinline__ int ltid() { int t = threadIdx.x; asm volatile("" : "+v"(t)); return t; }
; __device__ void gates_partial(const Ctx& p) {
;   char* ws = p.ws;
;   const u16* xmt = (const u16*)(ws + OFF_XMT);
;   const float* Wqk = (const float*)(ws + OFF_WEFF); const float* Wv = Wqk + 8192 * 8;
;   float* gpart = (float*)(ws + OFF_GPART);
;   float* Wl = (float*)g_smem;
;   float* Cl = Wl + 1024 * 16;
;   float* red = Cl + 1024 * 8;
;   const int tid = ltid(), tl = tid & 255, sub = tid >> 8;
;   const float* cw = p.in(14); const float* cb = p.in(15);
;   for (int item = blockIdx.x; item < 2 * 16 * 8; item += gridDim.x) {
;     const int b = item >> 7, tt = (item >> 3) & 15, cg_ = item & 7;
.LBB0_116:
	v_readlane_b32 s0, v253, 9
	v_readlane_b32 s1, v253, 10
	v_mov_b32_e32 v37, v139
	s_andn2_b64 vcc, exec, s[0:1]
	s_cbranch_vccnz .LBB0_131
	v_mov_b32_e32 v0, s66
	s_waitcnt vmcnt(0) lgkmcnt(0)
	v_add_co_u32_e32 v2, vcc, 0x4375c000, v0
	v_mov_b32_e32 v0, s67
	s_nop 0
	v_addc_co_u32_e32 v3, vcc, 0, v0, vcc
	global_load_dwordx4 v[2:5], v[2:3], off offset:112
	s_movk_i32 s0, 0x800
	v_mov_b32_e32 v0, 5
	v_and_b32_e32 v7, 1, v37
	s_add_u32 s14, s66, 0x3ac00000
	v_ashrrev_i32_e32 v6, 8, v37
	v_cmp_gt_i32_e64 s[4:5], s0, v37
	s_movk_i32 s0, 0x400
	v_lshlrev_b32_sdwa v43, v0, v37 dst_sel:DWORD dst_unused:UNUSED_PAD src0_sel:DWORD src1_sel:BYTE_0
	v_cmp_eq_u32_e32 vcc, 0, v7
	v_mov_b32_e32 v0, 0x43640000
	v_mov_b32_e32 v8, 0x43600000
	s_addc_u32 s15, s67, 0
	v_cmp_gt_i32_e64 s[6:7], s0, v37
	v_lshlrev_b32_e32 v14, 9, v6
	v_lshlrev_b32_e32 v47, 5, v37
	v_cndmask_b32_e32 v0, v0, v8, vcc
	s_add_i32 s0, 16, 0x10000
	v_lshlrev_b32_sdwa v41, v194, v37 dst_sel:DWORD dst_unused:UNUSED_PAD src0_sel:DWORD src1_sel:BYTE_0
	v_cmp_eq_u32_e64 s[8:9], 1, v6
	v_cmp_gt_u32_e64 s[10:11], s97, v37
	v_lshl_add_u64 v[16:17], s[66:67], 0, v[0:1]
	v_lshl_add_u32 v49, v7, 5, 16
	v_or_b32_e32 v53, 0x1f8, v14
	v_add_u32_e32 v55, 0xfffffe00, v37
	v_add_u32_e32 v59, s0, v47
	v_add_u32_e32 v61, -8, v14
	v_lshlrev_b32_e32 v65, 15, v6
	v_lshlrev_b32_e32 v67, 14, v6
	v_ashrrev_i32_e32 v15, 31, v14
	v_readlane_b32 s20, v252, 14
	s_mov_b32 s21, s63
	s_mov_b32 s22, s63
	s_branch .LBB0_119

; __device__ void gates_partial(const Ctx& p) {
;     ...
;     for (int e = tid; e < 1024 * 2; e += 512) {
;       const int c = e >> 1, hh = e & 1;
;       const float* s = (hh ? Wv : Wqk) + (long)(cg_ * 1024 + c) * 8;
;       *(float4*)(Wl + c * 16 + hh * 8) = *(const float4*)s;
;       *(float4*)(Wl + c * 16 + hh * 8 + 4) = *(const float4*)(s + 4);
;     }
.LBB0_121:
	v_ashrrev_i32_e32 v8, 1, v0
	v_add_u32_e32 v6, s16, v8
	v_ashrrev_i32_e32 v7, 31, v6
	v_lshlrev_b64 v[6:7], 5, v[6:7]
	v_lshl_add_u64 v[10:11], v[16:17], 0, v[6:7]
	v_lshl_add_u32 v12, v8, 6, v49
	global_load_dwordx4 v[6:9], v[10:11], off
	s_movk_i32 s17, 0x5ff
	v_cmp_lt_i32_e32 vcc, s17, v0
	s_or_b64 s[12:13], vcc, s[12:13]
	s_waitcnt vmcnt(0) lgkmcnt(0)
	ds_write_b128 v12, v[6:9]
	global_load_dwordx4 v[6:9], v[10:11], off offset:16
	s_waitcnt vmcnt(0) lgkmcnt(0)
	ds_write_b128 v12, v[6:9] offset:16
	v_add_u32_e32 v6, 0x200, v0
	v_mov_b32_e32 v0, v6
	s_andn2_b64 exec, exec, s[12:13]
	s_cbranch_execnz .LBB0_121

; __device__ void gates_partial(const Ctx& p) {
;     ...
;     for (int c = tid; c < 1024; c += 512) {
;       const int cgl = cg_ * 1024 + c;
;       *(float4*)(Cl + c * 8) = make_float4(cw[cgl], cw[8192 + cgl], cw[16384 + cgl], cw[24576 + cgl]);
;       Cl[c * 8 + 4] = cb[cgl];
;     }
.LBB0_124:
	v_lshl_add_u64 v[24:25], v[8:9], 0, v[6:7]
	v_add_co_u32_e32 v22, vcc, 0x8000, v24
	global_load_dword v20, v[24:25], off
	s_nop 0
	v_addc_co_u32_e32 v23, vcc, 0, v25, vcc
	global_load_dword v21, v[22:23], off
	v_add_co_u32_e32 v22, vcc, 0x10000, v24
	v_add_u32_e32 v19, 0x200, v19
	s_nop 0
	v_addc_co_u32_e32 v23, vcc, 0, v25, vcc
	v_add_co_u32_e32 v24, vcc, 0x18000, v24
	global_load_dword v22, v[22:23], off
	s_nop 0
	v_addc_co_u32_e32 v25, vcc, 0, v25, vcc
	global_load_dword v23, v[24:25], off
	v_cmp_lt_i32_e32 vcc, s60, v19
	v_lshl_add_u64 v[8:9], v[8:9], 0, s[16:17]
	s_or_b64 s[12:13], vcc, s[12:13]
	s_waitcnt vmcnt(0) lgkmcnt(0)
	ds_write_b128 v18, v[20:23]
	v_lshl_add_u64 v[20:21], v[10:11], 0, v[6:7]
	global_load_dword v20, v[20:21], off
	v_lshl_add_u64 v[10:11], v[10:11], 0, s[16:17]
	s_waitcnt vmcnt(0) lgkmcnt(0)
	ds_write_b32 v18, v20 offset:16
	v_add_u32_e32 v18, 0x4000, v18
	s_andn2_b64 exec, exec, s[12:13]
	s_cbranch_execnz .LBB0_124

; __device__ __forceinline__ float bf2f(u16 h) { return __uint_as_float(((unsigned)h) << 16); }
; __device__ __forceinline__ float siluf(float x) { return x * __builtin_amdgcn_rcpf(1.f + __expf(-x)); }
; __device__ void gates_partial(const Ctx& p) {
;     ...
;     for (int cb0 = sub * 512; cb0 < sub * 512 + 512; cb0 += 8) {
;       unsigned rA[8], rB[8]; u16 rC[8];
; #pragma unroll
;       for (int x = 0; x < 8; ++x) {
;         const u16* xr = xmt + ((long)b * 8192 + cg_ * 1024 + cb0 + x) * SEQ;
;         rA[x] = *(const unsigned*)(xr + ta);
;         rB[x] = *(const unsigned*)(xr + ib_);
;         rC[x] = xr[ic_];
;       }
; #pragma unroll
;       for (int x = 0; x < 8; ++x) {
;         const int c = cb0 + x;
;         const float4 w4 = *(const float4*)(Cl + c * 8);
;         const float bb = Cl[c * 8 + 4];
;         const float4 q0 = *(const float4*)(Wl + c * 16), q1 = *(const float4*)(Wl + c * 16 + 4);
;         const float4 v0 = *(const float4*)(Wl + c * 16 + 8), v1 = *(const float4*)(Wl + c * 16 + 12);
;         const float xa0 = __uint_as_float(rA[x] << 16), xa1 = __uint_as_float(rA[x] & 0xffff0000u);
;         const float xm2 = (ta >= 2) ? __uint_as_float(rB[x] << 16) : 0.f;
;         const float xm1 = (ta >= 2) ? __uint_as_float(rB[x] & 0xffff0000u) : 0.f;
;         const float xm3 = (ta >= 3) ? bf2f(rC[x]) : 0.f;
;         {
;           const float xc = siluf(bb + w4.x * xm3 + w4.y * xm2 + w4.z * xm1 + w4.w * xa0);
;           g0[0] += xc * q0.x + xa0 * v0.x; g0[1] += xc * q0.y + xa0 * v0.y; g0[2] += xc * q0.z + xa0 * v0.z; g0[3] += xc * q0.w + xa0 * v0.w;
;           g0[4] += xc * q1.x + xa0 * v1.x; g0[5] += xc * q1.y + xa0 * v1.y; g0[6] += xc * q1.z + xa0 * v1.z; g0[7] += xc * q1.w + xa0 * v1.w;
;         }
;         {
;           const float xc = siluf(bb + w4.x * xm2 + w4.y * xm1 + w4.z * xa0 + w4.w * xa1);
.LBB0_126:
	s_waitcnt vmcnt(0)
	v_lshl_add_u64 v[34:35], v[30:31], 0, v[28:29]
	s_mov_b32 s0, 0x10800000
	v_add_co_u32_e64 v32, s[0:1], s0, v34
	v_lshl_add_u64 v[38:39], v[30:31], 0, v[26:27]
	s_nop 0
	v_addc_co_u32_e64 v33, s[0:1], 0, v35, s[0:1]
	global_load_dword v36, v[32:33], off
	v_add_co_u32_e64 v32, s[0:1], s64, v38
	v_add_u32_e32 v86, 16, v73
	s_nop 0
	v_addc_co_u32_e64 v33, s[0:1], 0, v39, s[0:1]
	s_mov_b32 s0, 0x10804000
	s_nop 0
	v_add_co_u32_e64 v44, s[0:1], s0, v34
	global_load_dword v40, v[32:33], off offset:4092
	s_nop 0
	v_addc_co_u32_e64 v45, s[0:1], 0, v35, s[0:1]
	global_load_dword v42, v[44:45], off
	v_add_co_u32_e64 v44, s[0:1], s73, v38
	v_add_u32_e32 v135, 16, v76
	s_nop 0
	v_addc_co_u32_e64 v45, s[0:1], 0, v39, s[0:1]
	s_mov_b32 s0, 0x10808000
	global_load_dword v46, v[44:45], off offset:4092
	v_add_co_u32_e64 v44, s[0:1], s0, v34
	v_add_u32_e32 v77, 8, v77
	s_nop 0
	v_addc_co_u32_e64 v45, s[0:1], 0, v35, s[0:1]
	global_load_dword v48, v[44:45], off
	v_add_co_u32_e64 v44, s[0:1], s72, v38
	v_add_u32_e32 v76, 0x200, v76
	s_nop 0
	v_addc_co_u32_e64 v45, s[0:1], 0, v39, s[0:1]
	s_mov_b32 s0, 0x1080c000
	global_load_dword v52, v[44:45], off offset:4092
	v_add_co_u32_e64 v44, s[0:1], s0, v34
	s_nop 1
	v_addc_co_u32_e64 v45, s[0:1], 0, v35, s[0:1]
	global_load_dword v54, v[44:45], off
	v_add_co_u32_e64 v44, s[0:1], s3, v38
	s_nop 1
	v_addc_co_u32_e64 v45, s[0:1], 0, v39, s[0:1]
	s_mov_b32 s0, 0x10810000
	global_load_dword v58, v[44:45], off offset:4092
	v_add_co_u32_e64 v44, s[0:1], s0, v34
	s_nop 1
	v_addc_co_u32_e64 v45, s[0:1], 0, v35, s[0:1]
	global_load_dword v60, v[44:45], off
	v_add_co_u32_e64 v44, s[0:1], s92, v38
	s_nop 1
	v_addc_co_u32_e64 v45, s[0:1], 0, v39, s[0:1]
	s_mov_b32 s0, 0x10814000
	global_load_dword v64, v[44:45], off offset:4092
	v_add_co_u32_e64 v44, s[0:1], s0, v34
	s_nop 1
	v_addc_co_u32_e64 v45, s[0:1], 0, v35, s[0:1]
	global_load_dword v66, v[44:45], off
	v_add_co_u32_e64 v44, s[0:1], s93, v38
	s_nop 1
	v_addc_co_u32_e64 v45, s[0:1], 0, v39, s[0:1]
	s_mov_b32 s0, 0x10818000
	global_load_dword v70, v[44:45], off offset:4092
	v_add_co_u32_e64 v44, s[0:1], s0, v34
	s_nop 1
	v_addc_co_u32_e64 v45, s[0:1], 0, v35, s[0:1]
	global_load_dword v72, v[44:45], off
	v_add_co_u32_e64 v44, s[0:1], s37, v38
	s_nop 1
	v_addc_co_u32_e64 v45, s[0:1], 0, v39, s[0:1]
	s_mov_b32 s0, 0x1081c000
	s_nop 0
	v_add_co_u32_e64 v34, s[0:1], s0, v34
	global_load_dword v82, v[44:45], off offset:4092
	s_nop 0
	v_addc_co_u32_e64 v35, s[0:1], 0, v35, s[0:1]
	global_load_dword v84, v[34:35], off
	v_add_co_u32_e64 v34, s[0:1], s50, v38
	v_lshl_add_u64 v[32:33], v[30:31], 0, v[0:1]
	s_nop 0
	v_addc_co_u32_e64 v35, s[0:1], 0, v39, s[0:1]
	v_add_co_u32_e64 v44, s[0:1], s64, v32
	global_load_dword v85, v[34:35], off offset:4092
	s_nop 0
	v_addc_co_u32_e64 v45, s[0:1], 0, v33, s[0:1]
	global_load_ushort v39, v[44:45], off offset:4090
	v_add_u32_e32 v34, 0x10000, v86
	ds_read_b128 v[78:81], v34
	v_add_u32_e32 v34, 0x10010, v86
	ds_read_b32 v50, v34
	s_waitcnt vmcnt(0) lgkmcnt(0)
	v_lshlrev_b32_e32 v34, 16, v36
	v_and_b32_e32 v35, 0xffff0000, v36
	v_lshlrev_b32_e32 v36, 16, v40
	v_cndmask_b32_e64 v36, v36, 0, vcc
	v_and_b32_e32 v38, 0xffff0000, v40
	v_cndmask_b32_e64 v38, v38, 0, vcc
	v_and_b32_e32 v44, 0xffff0000, v46
	v_cndmask_b32_e64 v44, v44, 0, vcc
	v_mov_b32_e32 v158, v35
	v_lshl_add_u64 v[30:31], v[30:31], 0, s[88:89]
	v_lshlrev_b32_e32 v39, 16, v39
	v_cndmask_b32_e64 v39, 0, v39, s[12:13]
	v_fma_f32 v40, v39, v78, v50
	v_fmac_f32_e32 v50, v36, v78
	v_mov_b32_e32 v39, v34
	v_fmac_f32_e32 v40, v36, v79
	v_fmac_f32_e32 v50, v38, v79
	v_pk_mul_f32 v[38:39], v[80:81], v[38:39]
	s_nop 0
	v_add_f32_e32 v36, v38, v40
	v_add_f32_e32 v36, v39, v36
	v_mul_f32_e32 v38, 0xbfb8aa3b, v36
	v_exp_f32_e32 v38, v38
	s_nop 0
	v_add_f32_e32 v38, 1.0, v38
	v_rcp_f32_e32 v38, v38
	s_nop 0
	v_mul_f32_e32 v36, v36, v38
	v_pk_mul_f32 v[38:39], v[80:81], v[34:35]
	s_nop 0
	v_add_f32_e32 v38, v38, v50
	v_add_co_u32_e64 v50, s[0:1], s73, v32
	v_add_f32_e32 v38, v39, v38
	s_nop 0
	v_addc_co_u32_e64 v51, s[0:1], 0, v33, s[0:1]
	global_load_ushort v45, v[50:51], off offset:4090
	v_mul_f32_e32 v39, 0xbfb8aa3b, v38
	v_exp_f32_e32 v39, v39
	v_and_b32_e32 v50, 0xffff0000, v52
	v_cndmask_b32_e64 v50, v50, 0, vcc
	v_add_f32_e32 v39, 1.0, v39
	v_rcp_f32_e32 v39, v39
	s_waitcnt vmcnt(0) lgkmcnt(0)
	v_lshlrev_b32_e32 v45, 16, v45
	v_mul_f32_e32 v40, v38, v39
	v_add_u32_e32 v38, 0x10020, v86
	ds_read_b128 v[78:81], v38
	v_add_u32_e32 v38, 0x10030, v86
	ds_read_b32 v56, v38
	v_lshlrev_b32_e32 v38, 16, v42
	v_and_b32_e32 v39, 0xffff0000, v42
	v_lshlrev_b32_e32 v42, 16, v46
	v_cndmask_b32_e64 v42, v42, 0, vcc
	v_cndmask_b32_e64 v45, 0, v45, s[12:13]
	s_waitcnt lgkmcnt(0)
	v_fma_f32 v46, v45, v78, v56
	v_fmac_f32_e32 v56, v42, v78
	v_mov_b32_e32 v45, v38
	v_fmac_f32_e32 v46, v42, v79
	v_fmac_f32_e32 v56, v44, v79
	v_pk_mul_f32 v[44:45], v[80:81], v[44:45]
	v_mov_b32_e32 v160, v39
	v_add_f32_e32 v42, v44, v46
	v_add_f32_e32 v42, v45, v42
	v_mul_f32_e32 v44, 0xbfb8aa3b, v42
	v_exp_f32_e32 v44, v44
	s_nop 0
	v_add_f32_e32 v44, 1.0, v44
	v_rcp_f32_e32 v44, v44
	s_nop 0
	v_mul_f32_e32 v42, v42, v44
	v_pk_mul_f32 v[44:45], v[80:81], v[38:39]
	s_nop 0
	v_add_f32_e32 v44, v44, v56
	v_add_co_u32_e64 v56, s[0:1], s72, v32
	v_add_f32_e32 v44, v45, v44
	s_nop 0
	v_addc_co_u32_e64 v57, s[0:1], 0, v33, s[0:1]
	global_load_ushort v51, v[56:57], off offset:4090
	v_mul_f32_e32 v45, 0xbfb8aa3b, v44
	v_exp_f32_e32 v45, v45
	v_and_b32_e32 v56, 0xffff0000, v58
	v_cndmask_b32_e64 v56, v56, 0, vcc
	v_add_f32_e32 v45, 1.0, v45
	v_rcp_f32_e32 v45, v45
	s_waitcnt vmcnt(0) lgkmcnt(0)
; __device__ __forceinline__ float bf2f(u16 h) { return __uint_as_float(((unsigned)h) << 16); }
; __device__ __forceinline__ float siluf(float x) { return x * __builtin_amdgcn_rcpf(1.f + __expf(-x)); }
; __device__ void gates_partial(const Ctx& p) {
;     ...
;       for (int x = 0; x < 8; ++x) {
;         const int c = cb0 + x;
;         const float4 w4 = *(const float4*)(Cl + c * 8);
;         const float bb = Cl[c * 8 + 4];
;         const float4 q0 = *(const float4*)(Wl + c * 16), q1 = *(const float4*)(Wl + c * 16 + 4);
;         const float4 v0 = *(const float4*)(Wl + c * 16 + 8), v1 = *(const float4*)(Wl + c * 16 + 12);
;         const float xa0 = __uint_as_float(rA[x] << 16), xa1 = __uint_as_float(rA[x] & 0xffff0000u);
;         const float xm2 = (ta >= 2) ? __uint_as_float(rB[x] << 16) : 0.f;
;         const float xm1 = (ta >= 2) ? __uint_as_float(rB[x] & 0xffff0000u) : 0.f;
;         const float xm3 = (ta >= 3) ? bf2f(rC[x]) : 0.f;
;         {
;           const float xc = siluf(bb + w4.x * xm3 + w4.y * xm2 + w4.z * xm1 + w4.w * xa0);
;           g0[0] += xc * q0.x + xa0 * v0.x; g0[1] += xc * q0.y + xa0 * v0.y; g0[2] += xc * q0.z + xa0 * v0.z; g0[3] += xc * q0.w + xa0 * v0.w;
;           g0[4] += xc * q1.x + xa0 * v1.x; g0[5] += xc * q1.y + xa0 * v1.y; g0[6] += xc * q1.z + xa0 * v1.z; g0[7] += xc * q1.w + xa0 * v1.w;
;         }
;         {
;           const float xc = siluf(bb + w4.x * xm2 + w4.y * xm1 + w4.z * xa0 + w4.w * xa1);
	v_lshlrev_b32_e32 v51, 16, v51
	v_mul_f32_e32 v46, v44, v45
	v_add_u32_e32 v44, 0x10040, v86
	ds_read_b128 v[78:81], v44
	v_add_u32_e32 v44, 0x10050, v86
	ds_read_b32 v62, v44
	v_lshlrev_b32_e32 v44, 16, v48
	v_and_b32_e32 v45, 0xffff0000, v48
	v_lshlrev_b32_e32 v48, 16, v52
	v_cndmask_b32_e64 v48, v48, 0, vcc
	v_cndmask_b32_e64 v51, 0, v51, s[12:13]
	s_waitcnt lgkmcnt(0)
	v_fma_f32 v52, v51, v78, v62
	v_fmac_f32_e32 v62, v48, v78
	v_mov_b32_e32 v51, v44
	v_fmac_f32_e32 v52, v48, v79
	v_fmac_f32_e32 v62, v50, v79
	v_pk_mul_f32 v[50:51], v[80:81], v[50:51]
	v_mov_b32_e32 v162, v45
	v_add_f32_e32 v48, v50, v52
	v_add_f32_e32 v48, v51, v48
	v_mul_f32_e32 v50, 0xbfb8aa3b, v48
	v_exp_f32_e32 v50, v50
	s_nop 0
	v_add_f32_e32 v50, 1.0, v50
	v_rcp_f32_e32 v50, v50
	s_nop 0
	v_mul_f32_e32 v48, v48, v50
	v_pk_mul_f32 v[50:51], v[80:81], v[44:45]
	s_nop 0
	v_add_f32_e32 v50, v50, v62
	v_add_co_u32_e64 v62, s[0:1], s3, v32
	v_add_f32_e32 v50, v51, v50
	s_nop 0
	v_addc_co_u32_e64 v63, s[0:1], 0, v33, s[0:1]
	global_load_ushort v57, v[62:63], off offset:4090
	v_mul_f32_e32 v51, 0xbfb8aa3b, v50
	v_exp_f32_e32 v51, v51
	v_and_b32_e32 v62, 0xffff0000, v64
	v_cndmask_b32_e64 v62, v62, 0, vcc
	v_add_f32_e32 v51, 1.0, v51
	v_rcp_f32_e32 v51, v51
	s_waitcnt vmcnt(0) lgkmcnt(0)
	v_lshlrev_b32_e32 v57, 16, v57
	v_mul_f32_e32 v52, v50, v51
	v_add_u32_e32 v50, 0x10060, v86
	ds_read_b128 v[78:81], v50
	v_add_u32_e32 v50, 0x10070, v86
	ds_read_b32 v68, v50
	v_lshlrev_b32_e32 v50, 16, v54
	v_and_b32_e32 v51, 0xffff0000, v54
	v_lshlrev_b32_e32 v54, 16, v58
	v_cndmask_b32_e64 v54, v54, 0, vcc
	v_cndmask_b32_e64 v57, 0, v57, s[12:13]
	s_waitcnt lgkmcnt(0)
	v_fma_f32 v58, v57, v78, v68
	v_fmac_f32_e32 v68, v54, v78
	v_mov_b32_e32 v57, v50
	v_fmac_f32_e32 v58, v54, v79
	v_fmac_f32_e32 v68, v56, v79
	v_pk_mul_f32 v[56:57], v[80:81], v[56:57]
	v_mov_b32_e32 v164, v51
	v_add_f32_e32 v54, v56, v58
	v_add_f32_e32 v54, v57, v54
	v_mul_f32_e32 v56, 0xbfb8aa3b, v54
	v_exp_f32_e32 v56, v56
	s_nop 0
	v_add_f32_e32 v56, 1.0, v56
	v_rcp_f32_e32 v56, v56
	s_nop 0
	v_mul_f32_e32 v54, v54, v56
	v_pk_mul_f32 v[56:57], v[80:81], v[50:51]
	s_nop 0
	v_add_f32_e32 v56, v56, v68
	v_add_co_u32_e64 v68, s[0:1], s92, v32
	v_add_f32_e32 v56, v57, v56
	s_nop 0
	v_addc_co_u32_e64 v69, s[0:1], 0, v33, s[0:1]
	global_load_ushort v63, v[68:69], off offset:4090
	v_mul_f32_e32 v57, 0xbfb8aa3b, v56
	v_exp_f32_e32 v57, v57
	v_and_b32_e32 v68, 0xffff0000, v70
	v_cndmask_b32_e64 v68, v68, 0, vcc
	v_add_f32_e32 v57, 1.0, v57
	v_rcp_f32_e32 v57, v57
	s_waitcnt vmcnt(0) lgkmcnt(0)
	v_lshlrev_b32_e32 v63, 16, v63
	v_mul_f32_e32 v58, v56, v57
	v_add_u32_e32 v56, 0x10080, v86
	ds_read_b128 v[78:81], v56
	v_add_u32_e32 v56, 0x10090, v86
	ds_read_b32 v74, v56
	v_lshlrev_b32_e32 v56, 16, v60
	v_and_b32_e32 v57, 0xffff0000, v60
	v_lshlrev_b32_e32 v60, 16, v64
	v_cndmask_b32_e64 v60, v60, 0, vcc
	v_cndmask_b32_e64 v63, 0, v63, s[12:13]
	s_waitcnt lgkmcnt(0)
	v_fma_f32 v64, v63, v78, v74
	v_fmac_f32_e32 v74, v60, v78
	v_mov_b32_e32 v63, v56
	v_fmac_f32_e32 v64, v60, v79
	v_fmac_f32_e32 v74, v62, v79
	v_pk_mul_f32 v[62:63], v[80:81], v[62:63]
	v_mov_b32_e32 v166, v57
	v_add_f32_e32 v60, v62, v64
	v_add_f32_e32 v60, v63, v60
	v_mul_f32_e32 v62, 0xbfb8aa3b, v60
	v_exp_f32_e32 v62, v62
	s_nop 0
	v_add_f32_e32 v62, 1.0, v62
	v_rcp_f32_e32 v62, v62
	s_nop 0
	v_mul_f32_e32 v60, v60, v62
	v_pk_mul_f32 v[62:63], v[80:81], v[56:57]
	s_nop 0
	v_add_f32_e32 v62, v62, v74
	v_add_co_u32_e64 v74, s[0:1], s93, v32
	v_add_f32_e32 v62, v63, v62
	s_nop 0
	v_addc_co_u32_e64 v75, s[0:1], 0, v33, s[0:1]
	global_load_ushort v69, v[74:75], off offset:4090
	v_mul_f32_e32 v63, 0xbfb8aa3b, v62
	v_exp_f32_e32 v63, v63
	v_and_b32_e32 v74, 0xffff0000, v82
	v_cndmask_b32_e64 v74, v74, 0, vcc
	v_add_f32_e32 v63, 1.0, v63
	v_rcp_f32_e32 v63, v63
	s_waitcnt vmcnt(0) lgkmcnt(0)
	v_lshlrev_b32_e32 v69, 16, v69
	v_mul_f32_e32 v64, v62, v63
	v_add_u32_e32 v62, 0x100a0, v86
	ds_read_b128 v[78:81], v62
	v_add_u32_e32 v62, 0x100b0, v86
	ds_read_b32 v83, v62
	v_lshlrev_b32_e32 v62, 16, v66
	v_and_b32_e32 v63, 0xffff0000, v66
	v_lshlrev_b32_e32 v66, 16, v70
	v_cndmask_b32_e64 v66, v66, 0, vcc
	v_cndmask_b32_e64 v69, 0, v69, s[12:13]
	s_waitcnt lgkmcnt(0)
	v_fma_f32 v70, v69, v78, v83
	v_fmac_f32_e32 v83, v66, v78
	v_mov_b32_e32 v69, v62
	v_fmac_f32_e32 v70, v66, v79
	v_fmac_f32_e32 v83, v68, v79
	v_pk_mul_f32 v[68:69], v[80:81], v[68:69]
	v_mov_b32_e32 v168, v63
	v_add_f32_e32 v66, v68, v70
	v_add_f32_e32 v66, v69, v66
	v_mul_f32_e32 v68, 0xbfb8aa3b, v66
	v_exp_f32_e32 v68, v68
	s_nop 0
	v_add_f32_e32 v68, 1.0, v68
	v_rcp_f32_e32 v68, v68
	s_nop 0
	v_mul_f32_e32 v66, v66, v68
	v_pk_mul_f32 v[68:69], v[80:81], v[62:63]
	s_nop 0
	v_add_f32_e32 v68, v68, v83
	v_add_f32_e32 v68, v69, v68
	v_mul_f32_e32 v69, 0xbfb8aa3b, v68
	v_exp_f32_e32 v69, v69
	s_nop 0
	v_add_f32_e32 v69, 1.0, v69
	v_rcp_f32_e32 v69, v69
	s_nop 0
	v_mul_f32_e32 v70, v68, v69
	v_add_u32_e32 v68, 0x100c0, v86
	ds_read_b128 v[78:81], v68
	v_add_u32_e32 v68, 0x100d0, v86
	ds_read_b32 v87, v68
	v_lshlrev_b32_e32 v68, 16, v72
	v_and_b32_e32 v69, 0xffff0000, v72
	v_lshlrev_b32_e32 v72, 16, v82
	v_add_co_u32_e64 v82, s[0:1], s37, v32
	v_cndmask_b32_e64 v72, v72, 0, vcc
	s_nop 0
	v_addc_co_u32_e64 v83, s[0:1], 0, v33, s[0:1]
	global_load_ushort v75, v[82:83], off offset:4090
	v_add_co_u32_e64 v32, s[0:1], s50, v32
	v_mov_b32_e32 v170, v69
	s_nop 0
	v_addc_co_u32_e64 v33, s[0:1], 0, v33, s[0:1]
	global_load_ushort v32, v[32:33], off offset:4090
	v_cmp_ge_i32_e64 s[0:1], v77, v53
	s_or_b64 s[18:19], s[0:1], s[18:19]
	s_waitcnt vmcnt(0) lgkmcnt(0)
; __device__ __forceinline__ float bf2f(u16 h) { return __uint_as_float(((unsigned)h) << 16); }
; __device__ __forceinline__ float siluf(float x) { return x * __builtin_amdgcn_rcpf(1.f + __expf(-x)); }
; __device__ void gates_partial(const Ctx& p) {
;     ...
;       for (int x = 0; x < 8; ++x) {
;         const int c = cb0 + x;
;         const float4 w4 = *(const float4*)(Cl + c * 8);
;         const float bb = Cl[c * 8 + 4];
;         const float4 q0 = *(const float4*)(Wl + c * 16), q1 = *(const float4*)(Wl + c * 16 + 4);
;         const float4 v0 = *(const float4*)(Wl + c * 16 + 8), v1 = *(const float4*)(Wl + c * 16 + 12);
;         const float xa0 = __uint_as_float(rA[x] << 16), xa1 = __uint_as_float(rA[x] & 0xffff0000u);
;         const float xm2 = (ta >= 2) ? __uint_as_float(rB[x] << 16) : 0.f;
;         const float xm1 = (ta >= 2) ? __uint_as_float(rB[x] & 0xffff0000u) : 0.f;
;         const float xm3 = (ta >= 3) ? bf2f(rC[x]) : 0.f;
;         {
;           const float xc = siluf(bb + w4.x * xm3 + w4.y * xm2 + w4.z * xm1 + w4.w * xa0);
;           g0[0] += xc * q0.x + xa0 * v0.x; g0[1] += xc * q0.y + xa0 * v0.y; g0[2] += xc * q0.z + xa0 * v0.z; g0[3] += xc * q0.w + xa0 * v0.w;
;           g0[4] += xc * q1.x + xa0 * v1.x; g0[5] += xc * q1.y + xa0 * v1.y; g0[6] += xc * q1.z + xa0 * v1.z; g0[7] += xc * q1.w + xa0 * v1.w;
;         }
;         {
;           const float xc = siluf(bb + w4.x * xm2 + w4.y * xm1 + w4.z * xa0 + w4.w * xa1);
;           g1[0] += xc * q0.x + xa1 * v0.x; g1[1] += xc * q0.y + xa1 * v0.y; g1[2] += xc * q0.z + xa1 * v0.z; g1[3] += xc * q0.w + xa1 * v0.w;
;           g1[4] += xc * q1.x + xa1 * v1.x; g1[5] += xc * q1.y + xa1 * v1.y; g1[6] += xc * q1.z + xa1 * v1.z; g1[7] += xc * q1.w + xa1 * v1.w;
;         }
	v_lshlrev_b32_e32 v75, 16, v75
	v_cndmask_b32_e64 v75, 0, v75, s[12:13]
	v_fma_f32 v82, v75, v78, v87
	v_fmac_f32_e32 v87, v72, v78
	v_mov_b32_e32 v75, v68
	v_fmac_f32_e32 v82, v72, v79
	v_fmac_f32_e32 v87, v74, v79
	v_pk_mul_f32 v[74:75], v[80:81], v[74:75]
	v_lshlrev_b32_e32 v32, 16, v32
	v_add_f32_e32 v72, v74, v82
	v_add_f32_e32 v72, v75, v72
	v_mul_f32_e32 v74, 0xbfb8aa3b, v72
	v_exp_f32_e32 v74, v74
	v_lshlrev_b32_e32 v82, 16, v85
	v_cndmask_b32_e64 v32, 0, v32, s[12:13]
	v_cndmask_b32_e64 v83, v82, 0, vcc
	v_add_f32_e32 v74, 1.0, v74
	v_rcp_f32_e32 v74, v74
	v_and_b32_e32 v82, 0xffff0000, v85
	v_cndmask_b32_e64 v82, v82, 0, vcc
	v_mul_f32_e32 v72, v72, v74
	v_pk_mul_f32 v[74:75], v[80:81], v[68:69]
	s_nop 0
	v_add_f32_e32 v74, v74, v87
	v_add_f32_e32 v74, v75, v74
	v_mul_f32_e32 v75, 0xbfb8aa3b, v74
	v_exp_f32_e32 v75, v75
	s_nop 0
	v_add_f32_e32 v75, 1.0, v75
	v_rcp_f32_e32 v75, v75
	s_nop 0
	v_mul_f32_e32 v134, v74, v75
	v_add_u32_e32 v74, 0x100e0, v86
	ds_read_b128 v[78:81], v74
	v_add_u32_e32 v74, 0x100f0, v86
	ds_read_b32 v86, v74
	v_lshlrev_b32_e32 v74, 16, v84
	v_and_b32_e32 v75, 0xffff0000, v84
	v_mov_b32_e32 v172, v75
	s_waitcnt lgkmcnt(0)
	v_fma_f32 v84, v32, v78, v86
	v_fmac_f32_e32 v84, v83, v79
	v_fmac_f32_e32 v86, v83, v78
	v_mov_b32_e32 v83, v74
	v_pk_mul_f32 v[32:33], v[82:83], v[80:81]
	v_fmac_f32_e32 v86, v82, v79
	v_add_f32_e32 v32, v32, v84
	v_add_f32_e32 v32, v33, v32
	v_mul_f32_e32 v33, 0xbfb8aa3b, v32
	v_exp_f32_e32 v33, v33
	v_pk_mul_f32 v[78:79], v[80:81], v[74:75]
	v_add_f32_e32 v33, 1.0, v33
	v_rcp_f32_e32 v33, v33
	s_nop 0
	v_mul_f32_e32 v32, v32, v33
	v_add_f32_e32 v33, v78, v86
	v_add_f32_e32 v33, v79, v33
	v_mul_f32_e32 v78, 0xbfb8aa3b, v33
	v_exp_f32_e32 v78, v78
	s_nop 0
	v_add_f32_e32 v78, 1.0, v78
	v_rcp_f32_e32 v78, v78
	s_nop 0
	v_mul_f32_e32 v136, v33, v78
	ds_read_b128 v[78:81], v135
	ds_read_b128 v[82:85], v135 offset:16
	ds_read_b128 v[86:89], v135 offset:32
	ds_read_b128 v[90:93], v135 offset:48
	s_waitcnt lgkmcnt(1)
	v_pk_mul_f32 v[94:95], v[86:87], v[158:159] op_sel_hi:[1,0]
	s_nop 0
	v_pk_fma_f32 v[94:95], v[78:79], v[40:41], v[94:95] op_sel_hi:[1,0,1]
	v_pk_mul_f32 v[86:87], v[86:87], v[34:35] op_sel_hi:[1,0]
	v_pk_add_f32 v[10:11], v[10:11], v[94:95]
	ds_read_b128 v[94:97], v135 offset:64
	ds_read_b128 v[98:101], v135 offset:96
	v_pk_fma_f32 v[78:79], v[78:79], v[36:37], v[86:87] op_sel_hi:[1,0,1]
	s_waitcnt lgkmcnt(0)
	v_pk_mul_f32 v[102:103], v[98:99], v[160:161] op_sel_hi:[1,0]
	s_nop 0
	v_pk_fma_f32 v[102:103], v[94:95], v[46:47], v[102:103] op_sel_hi:[1,0,1]
	v_pk_add_f32 v[24:25], v[24:25], v[78:79]
	v_pk_add_f32 v[10:11], v[10:11], v[102:103]
	ds_read_b128 v[102:105], v135 offset:128
	ds_read_b128 v[106:109], v135 offset:160
	v_pk_mul_f32 v[78:79], v[98:99], v[38:39] op_sel_hi:[1,0]
	s_waitcnt lgkmcnt(0)
	v_pk_mul_f32 v[110:111], v[106:107], v[162:163] op_sel_hi:[1,0]
	s_nop 0
	v_pk_fma_f32 v[110:111], v[102:103], v[52:53], v[110:111] op_sel_hi:[1,0,1]
	v_pk_fma_f32 v[78:79], v[94:95], v[42:43], v[78:79] op_sel_hi:[1,0,1]
	v_pk_add_f32 v[10:11], v[10:11], v[110:111]
	ds_read_b128 v[110:113], v135 offset:192
	ds_read_b128 v[114:117], v135 offset:224
	v_pk_add_f32 v[24:25], v[24:25], v[78:79]
	v_pk_mul_f32 v[78:79], v[106:107], v[44:45] op_sel_hi:[1,0]
	s_waitcnt lgkmcnt(0)
	v_pk_mul_f32 v[118:119], v[114:115], v[164:165] op_sel_hi:[1,0]
	s_nop 0
	v_pk_fma_f32 v[118:119], v[110:111], v[58:59], v[118:119] op_sel_hi:[1,0,1]
	v_pk_fma_f32 v[78:79], v[102:103], v[48:49], v[78:79] op_sel_hi:[1,0,1]
	v_pk_add_f32 v[10:11], v[10:11], v[118:119]
	ds_read_b128 v[118:121], v135 offset:256
	ds_read_b128 v[122:125], v135 offset:288
	v_pk_add_f32 v[24:25], v[24:25], v[78:79]
	v_pk_mul_f32 v[78:79], v[114:115], v[50:51] op_sel_hi:[1,0]
	s_waitcnt lgkmcnt(0)
	v_pk_mul_f32 v[126:127], v[122:123], v[166:167] op_sel_hi:[1,0]
	s_nop 0
	v_pk_fma_f32 v[126:127], v[118:119], v[64:65], v[126:127] op_sel_hi:[1,0,1]
	v_pk_fma_f32 v[78:79], v[110:111], v[54:55], v[78:79] op_sel_hi:[1,0,1]
	v_pk_add_f32 v[10:11], v[10:11], v[126:127]
	ds_read_b128 v[126:129], v135 offset:320
	ds_read_b128 v[130:133], v135 offset:352
	v_pk_add_f32 v[24:25], v[24:25], v[78:79]
	v_pk_mul_f32 v[78:79], v[122:123], v[56:57] op_sel_hi:[1,0]
	s_waitcnt lgkmcnt(0)
	v_pk_mul_f32 v[142:143], v[130:131], v[168:169] op_sel_hi:[1,0]
	s_nop 0
	v_pk_fma_f32 v[142:143], v[126:127], v[70:71], v[142:143] op_sel_hi:[1,0,1]
	v_pk_fma_f32 v[78:79], v[118:119], v[60:61], v[78:79] op_sel_hi:[1,0,1]
	v_pk_add_f32 v[10:11], v[10:11], v[142:143]
	ds_read_b128 v[142:145], v135 offset:384
	ds_read_b128 v[146:149], v135 offset:416
	v_pk_add_f32 v[24:25], v[24:25], v[78:79]
	v_pk_mul_f32 v[78:79], v[130:131], v[62:63] op_sel_hi:[1,0]
	s_waitcnt lgkmcnt(0)
	v_pk_mul_f32 v[150:151], v[146:147], v[170:171] op_sel_hi:[1,0]
	s_nop 0
	v_pk_fma_f32 v[150:151], v[142:143], v[134:135], v[150:151] op_sel_hi:[1,0,1]
	v_pk_fma_f32 v[78:79], v[126:127], v[66:67], v[78:79] op_sel_hi:[1,0,1]
	v_pk_add_f32 v[10:11], v[10:11], v[150:151]
	ds_read_b128 v[150:153], v135 offset:448
	ds_read_b128 v[154:157], v135 offset:480
	v_pk_add_f32 v[24:25], v[24:25], v[78:79]
	v_pk_mul_f32 v[78:79], v[146:147], v[68:69] op_sel_hi:[1,0]
	s_nop 0
	v_pk_fma_f32 v[78:79], v[142:143], v[72:73], v[78:79] op_sel_hi:[1,0,1]
	s_nop 0
	v_pk_add_f32 v[24:25], v[24:25], v[78:79]
	s_waitcnt lgkmcnt(0)
; __device__ __forceinline__ float siluf(float x) { return x * __builtin_amdgcn_rcpf(1.f + __expf(-x)); }
; __device__ void gates_partial(const Ctx& p) {
;     ...
;         {
;           const float xc = siluf(bb + w4.x * xm3 + w4.y * xm2 + w4.z * xm1 + w4.w * xa0);
;           g0[0] += xc * q0.x + xa0 * v0.x; g0[1] += xc * q0.y + xa0 * v0.y; g0[2] += xc * q0.z + xa0 * v0.z; g0[3] += xc * q0.w + xa0 * v0.w;
;           g0[4] += xc * q1.x + xa0 * v1.x; g0[5] += xc * q1.y + xa0 * v1.y; g0[6] += xc * q1.z + xa0 * v1.z; g0[7] += xc * q1.w + xa0 * v1.w;
;         }
;         {
;           const float xc = siluf(bb + w4.x * xm2 + w4.y * xm1 + w4.z * xa0 + w4.w * xa1);
;           g1[0] += xc * q0.x + xa1 * v0.x; g1[1] += xc * q0.y + xa1 * v0.y; g1[2] += xc * q0.z + xa1 * v0.z; g1[3] += xc * q0.w + xa1 * v0.w;
;           g1[4] += xc * q1.x + xa1 * v1.x; g1[5] += xc * q1.y + xa1 * v1.y; g1[6] += xc * q1.z + xa1 * v1.z; g1[7] += xc * q1.w + xa1 * v1.w;
;         }
	v_pk_mul_f32 v[78:79], v[154:155], v[74:75] op_sel_hi:[1,0]
	s_nop 0
	v_pk_fma_f32 v[78:79], v[150:151], v[32:33], v[78:79] op_sel_hi:[1,0,1]
	s_nop 0
	v_pk_add_f32 v[24:25], v[24:25], v[78:79]
	v_pk_mul_f32 v[78:79], v[154:155], v[172:173] op_sel_hi:[1,0]
	s_nop 0
	v_pk_fma_f32 v[78:79], v[150:151], v[136:137], v[78:79] op_sel_hi:[1,0,1]
	s_nop 0
	v_pk_add_f32 v[10:11], v[10:11], v[78:79]
	v_pk_mul_f32 v[78:79], v[88:89], v[158:159] op_sel_hi:[1,0]
	s_nop 0
	v_pk_fma_f32 v[78:79], v[80:81], v[40:41], v[78:79] op_sel_hi:[1,0,1]
	s_nop 0
	v_pk_add_f32 v[12:13], v[12:13], v[78:79]
	v_pk_mul_f32 v[78:79], v[100:101], v[160:161] op_sel_hi:[1,0]
	s_nop 0
	v_pk_fma_f32 v[78:79], v[96:97], v[46:47], v[78:79] op_sel_hi:[1,0,1]
	s_nop 0
	v_pk_add_f32 v[12:13], v[12:13], v[78:79]
	v_pk_mul_f32 v[78:79], v[108:109], v[162:163] op_sel_hi:[1,0]
	s_nop 0
	v_pk_fma_f32 v[78:79], v[104:105], v[52:53], v[78:79] op_sel_hi:[1,0,1]
	s_nop 0
	v_pk_add_f32 v[12:13], v[12:13], v[78:79]
	v_pk_mul_f32 v[78:79], v[116:117], v[164:165] op_sel_hi:[1,0]
	s_nop 0
	v_pk_fma_f32 v[78:79], v[112:113], v[58:59], v[78:79] op_sel_hi:[1,0,1]
	s_nop 0
	v_pk_add_f32 v[12:13], v[12:13], v[78:79]
	v_pk_mul_f32 v[78:79], v[124:125], v[166:167] op_sel_hi:[1,0]
	s_nop 0
	v_pk_fma_f32 v[78:79], v[120:121], v[64:65], v[78:79] op_sel_hi:[1,0,1]
	s_nop 0
	v_pk_add_f32 v[12:13], v[12:13], v[78:79]
	v_pk_mul_f32 v[78:79], v[132:133], v[168:169] op_sel_hi:[1,0]
	s_nop 0
	v_pk_fma_f32 v[78:79], v[128:129], v[70:71], v[78:79] op_sel_hi:[1,0,1]
	s_nop 0
	v_pk_add_f32 v[12:13], v[12:13], v[78:79]
	v_pk_mul_f32 v[78:79], v[148:149], v[170:171] op_sel_hi:[1,0]
	s_nop 0
	v_pk_fma_f32 v[78:79], v[144:145], v[134:135], v[78:79] op_sel_hi:[1,0,1]
	s_nop 0
	v_pk_add_f32 v[12:13], v[12:13], v[78:79]
	v_pk_mul_f32 v[78:79], v[88:89], v[34:35] op_sel_hi:[1,0]
	s_nop 0
	v_pk_fma_f32 v[78:79], v[80:81], v[36:37], v[78:79] op_sel_hi:[1,0,1]
	s_nop 0
	v_pk_add_f32 v[22:23], v[22:23], v[78:79]
	v_pk_mul_f32 v[78:79], v[100:101], v[38:39] op_sel_hi:[1,0]
	s_nop 0
	v_pk_fma_f32 v[78:79], v[96:97], v[42:43], v[78:79] op_sel_hi:[1,0,1]
	s_nop 0
	v_pk_add_f32 v[22:23], v[22:23], v[78:79]
	v_pk_mul_f32 v[78:79], v[108:109], v[44:45] op_sel_hi:[1,0]
	s_nop 0
	v_pk_fma_f32 v[78:79], v[104:105], v[48:49], v[78:79] op_sel_hi:[1,0,1]
	s_nop 0
	v_pk_add_f32 v[22:23], v[22:23], v[78:79]
	v_pk_mul_f32 v[78:79], v[116:117], v[50:51] op_sel_hi:[1,0]
	s_nop 0
	v_pk_fma_f32 v[78:79], v[112:113], v[54:55], v[78:79] op_sel_hi:[1,0,1]
	s_nop 0
	v_pk_add_f32 v[22:23], v[22:23], v[78:79]
	v_pk_mul_f32 v[78:79], v[124:125], v[56:57] op_sel_hi:[1,0]
	s_nop 0
	v_pk_fma_f32 v[78:79], v[120:121], v[60:61], v[78:79] op_sel_hi:[1,0,1]
	s_nop 0
	v_pk_add_f32 v[22:23], v[22:23], v[78:79]
	v_pk_mul_f32 v[78:79], v[132:133], v[62:63] op_sel_hi:[1,0]
	s_nop 0
	v_pk_fma_f32 v[78:79], v[128:129], v[66:67], v[78:79] op_sel_hi:[1,0,1]
	s_nop 0
	v_pk_add_f32 v[22:23], v[22:23], v[78:79]
	v_pk_mul_f32 v[78:79], v[148:149], v[68:69] op_sel_hi:[1,0]
	s_nop 0
	v_pk_fma_f32 v[78:79], v[144:145], v[72:73], v[78:79] op_sel_hi:[1,0,1]
	s_nop 0
	v_pk_add_f32 v[22:23], v[22:23], v[78:79]
	v_pk_mul_f32 v[78:79], v[156:157], v[74:75] op_sel_hi:[1,0]
	s_nop 0
	v_pk_fma_f32 v[78:79], v[152:153], v[32:33], v[78:79] op_sel_hi:[1,0,1]
	s_nop 0
	v_pk_add_f32 v[22:23], v[22:23], v[78:79]
	v_pk_mul_f32 v[78:79], v[156:157], v[172:173] op_sel_hi:[1,0]
	s_nop 0
	v_pk_fma_f32 v[78:79], v[152:153], v[136:137], v[78:79] op_sel_hi:[1,0,1]
	s_nop 0
	v_pk_add_f32 v[12:13], v[12:13], v[78:79]
	v_pk_mul_f32 v[78:79], v[90:91], v[158:159] op_sel_hi:[1,0]
	v_pk_mul_f32 v[90:91], v[90:91], v[34:35] op_sel_hi:[1,0]
	v_pk_fma_f32 v[78:79], v[82:83], v[40:41], v[78:79] op_sel_hi:[1,0,1]
	v_pk_fma_f32 v[82:83], v[82:83], v[36:37], v[90:91] op_sel_hi:[1,0,1]
	v_pk_add_f32 v[6:7], v[6:7], v[78:79]
	ds_read_b128 v[78:81], v135 offset:80
	ds_read_b128 v[86:89], v135 offset:112
	v_pk_add_f32 v[20:21], v[20:21], v[82:83]
	v_pk_mul_f32 v[34:35], v[92:93], v[34:35] op_sel_hi:[1,0]
	s_waitcnt lgkmcnt(0)
	v_pk_mul_f32 v[94:95], v[86:87], v[160:161] op_sel_hi:[1,0]
	s_nop 0
	v_pk_fma_f32 v[94:95], v[78:79], v[46:47], v[94:95] op_sel_hi:[1,0,1]
	v_pk_mul_f32 v[82:83], v[86:87], v[38:39] op_sel_hi:[1,0]
	v_pk_add_f32 v[6:7], v[6:7], v[94:95]
	ds_read_b128 v[94:97], v135 offset:144
	ds_read_b128 v[98:101], v135 offset:176
	v_pk_fma_f32 v[78:79], v[78:79], v[42:43], v[82:83] op_sel_hi:[1,0,1]
	v_pk_fma_f32 v[34:35], v[84:85], v[36:37], v[34:35] op_sel_hi:[1,0,1]
	v_pk_add_f32 v[20:21], v[20:21], v[78:79]
	v_pk_add_f32 v[18:19], v[18:19], v[34:35]
	s_waitcnt lgkmcnt(0)
	v_pk_mul_f32 v[102:103], v[98:99], v[162:163] op_sel_hi:[1,0]
	v_pk_mul_f32 v[78:79], v[98:99], v[44:45] op_sel_hi:[1,0]
	v_pk_fma_f32 v[102:103], v[94:95], v[52:53], v[102:103] op_sel_hi:[1,0,1]
	v_pk_fma_f32 v[78:79], v[94:95], v[48:49], v[78:79] op_sel_hi:[1,0,1]
	v_pk_add_f32 v[6:7], v[6:7], v[102:103]
	ds_read_b128 v[102:105], v135 offset:208
	ds_read_b128 v[106:109], v135 offset:240
	v_pk_add_f32 v[20:21], v[20:21], v[78:79]
	v_pk_mul_f32 v[34:35], v[88:89], v[38:39] op_sel_hi:[1,0]
	s_waitcnt lgkmcnt(0)
	v_pk_mul_f32 v[110:111], v[106:107], v[164:165] op_sel_hi:[1,0]
	s_nop 0
	v_pk_fma_f32 v[110:111], v[102:103], v[58:59], v[110:111] op_sel_hi:[1,0,1]
	v_pk_mul_f32 v[78:79], v[106:107], v[50:51] op_sel_hi:[1,0]
	v_pk_add_f32 v[6:7], v[6:7], v[110:111]
	ds_read_b128 v[110:113], v135 offset:272
	ds_read_b128 v[114:117], v135 offset:304
	v_pk_fma_f32 v[78:79], v[102:103], v[54:55], v[78:79] op_sel_hi:[1,0,1]
	v_pk_fma_f32 v[34:35], v[80:81], v[42:43], v[34:35] op_sel_hi:[1,0,1]
	v_pk_add_f32 v[20:21], v[20:21], v[78:79]
	v_pk_add_f32 v[18:19], v[18:19], v[34:35]
	s_waitcnt lgkmcnt(0)
; __device__ __forceinline__ float siluf(float x) { return x * __builtin_amdgcn_rcpf(1.f + __expf(-x)); }
; __device__ void gates_partial(const Ctx& p) {
;     ...
;         {
;           const float xc = siluf(bb + w4.x * xm3 + w4.y * xm2 + w4.z * xm1 + w4.w * xa0);
;           g0[0] += xc * q0.x + xa0 * v0.x; g0[1] += xc * q0.y + xa0 * v0.y; g0[2] += xc * q0.z + xa0 * v0.z; g0[3] += xc * q0.w + xa0 * v0.w;
;           g0[4] += xc * q1.x + xa0 * v1.x; g0[5] += xc * q1.y + xa0 * v1.y; g0[6] += xc * q1.z + xa0 * v1.z; g0[7] += xc * q1.w + xa0 * v1.w;
;         }
;         {
;           const float xc = siluf(bb + w4.x * xm2 + w4.y * xm1 + w4.z * xa0 + w4.w * xa1);
;           g1[0] += xc * q0.x + xa1 * v0.x; g1[1] += xc * q0.y + xa1 * v0.y; g1[2] += xc * q0.z + xa1 * v0.z; g1[3] += xc * q0.w + xa1 * v0.w;
;           g1[4] += xc * q1.x + xa1 * v1.x; g1[5] += xc * q1.y + xa1 * v1.y; g1[6] += xc * q1.z + xa1 * v1.z; g1[7] += xc * q1.w + xa1 * v1.w;
;         }
;       }
;     }
;     if (sub == 1) {
; #pragma unroll
;       for (int k = 0; k < 8; ++k) { red[tl * 8 + k] = g0[k]; red[(256 + tl) * 8 + k] = g1[k]; }
;     }
	v_pk_mul_f32 v[118:119], v[114:115], v[166:167] op_sel_hi:[1,0]
	v_pk_mul_f32 v[78:79], v[114:115], v[56:57] op_sel_hi:[1,0]
	v_pk_fma_f32 v[118:119], v[110:111], v[64:65], v[118:119] op_sel_hi:[1,0,1]
	v_pk_fma_f32 v[78:79], v[110:111], v[60:61], v[78:79] op_sel_hi:[1,0,1]
	v_pk_add_f32 v[6:7], v[6:7], v[118:119]
	ds_read_b128 v[118:121], v135 offset:336
	ds_read_b128 v[122:125], v135 offset:368
	v_pk_add_f32 v[20:21], v[20:21], v[78:79]
	v_pk_mul_f32 v[34:35], v[100:101], v[44:45] op_sel_hi:[1,0]
	s_waitcnt lgkmcnt(0)
	v_pk_mul_f32 v[126:127], v[122:123], v[168:169] op_sel_hi:[1,0]
	s_nop 0
	v_pk_fma_f32 v[126:127], v[118:119], v[70:71], v[126:127] op_sel_hi:[1,0,1]
	v_pk_mul_f32 v[78:79], v[122:123], v[62:63] op_sel_hi:[1,0]
	v_pk_add_f32 v[6:7], v[6:7], v[126:127]
	ds_read_b128 v[126:129], v135 offset:400
	ds_read_b128 v[130:133], v135 offset:432
	v_pk_fma_f32 v[78:79], v[118:119], v[66:67], v[78:79] op_sel_hi:[1,0,1]
	v_pk_fma_f32 v[34:35], v[96:97], v[48:49], v[34:35] op_sel_hi:[1,0,1]
	v_pk_add_f32 v[20:21], v[20:21], v[78:79]
	v_pk_add_f32 v[18:19], v[18:19], v[34:35]
	s_waitcnt lgkmcnt(0)
	v_pk_mul_f32 v[142:143], v[130:131], v[170:171] op_sel_hi:[1,0]
	v_pk_mul_f32 v[78:79], v[130:131], v[68:69] op_sel_hi:[1,0]
	v_pk_fma_f32 v[142:143], v[126:127], v[134:135], v[142:143] op_sel_hi:[1,0,1]
	v_pk_fma_f32 v[78:79], v[126:127], v[72:73], v[78:79] op_sel_hi:[1,0,1]
	v_pk_add_f32 v[6:7], v[6:7], v[142:143]
	ds_read_b128 v[142:145], v135 offset:464
	ds_read_b128 v[146:149], v135 offset:496
	v_pk_add_f32 v[20:21], v[20:21], v[78:79]
	v_pk_mul_f32 v[34:35], v[108:109], v[50:51] op_sel_hi:[1,0]
	s_waitcnt lgkmcnt(0)
	v_pk_mul_f32 v[78:79], v[146:147], v[74:75] op_sel_hi:[1,0]
	s_nop 0
	v_pk_fma_f32 v[78:79], v[142:143], v[32:33], v[78:79] op_sel_hi:[1,0,1]
	v_pk_fma_f32 v[34:35], v[104:105], v[54:55], v[34:35] op_sel_hi:[1,0,1]
	v_pk_add_f32 v[20:21], v[20:21], v[78:79]
	v_pk_mul_f32 v[78:79], v[146:147], v[172:173] op_sel_hi:[1,0]
	v_pk_add_f32 v[18:19], v[18:19], v[34:35]
	v_pk_fma_f32 v[78:79], v[142:143], v[136:137], v[78:79] op_sel_hi:[1,0,1]
	v_pk_mul_f32 v[34:35], v[116:117], v[56:57] op_sel_hi:[1,0]
	v_pk_add_f32 v[6:7], v[6:7], v[78:79]
	v_pk_mul_f32 v[78:79], v[92:93], v[158:159] op_sel_hi:[1,0]
	v_pk_fma_f32 v[34:35], v[112:113], v[60:61], v[34:35] op_sel_hi:[1,0,1]
	v_pk_fma_f32 v[78:79], v[84:85], v[40:41], v[78:79] op_sel_hi:[1,0,1]
	v_pk_add_f32 v[18:19], v[18:19], v[34:35]
	v_pk_add_f32 v[8:9], v[8:9], v[78:79]
	v_pk_mul_f32 v[78:79], v[88:89], v[160:161] op_sel_hi:[1,0]
	v_pk_mul_f32 v[34:35], v[124:125], v[62:63] op_sel_hi:[1,0]
	v_pk_fma_f32 v[78:79], v[80:81], v[46:47], v[78:79] op_sel_hi:[1,0,1]
	v_pk_fma_f32 v[34:35], v[120:121], v[66:67], v[34:35] op_sel_hi:[1,0,1]
	v_pk_add_f32 v[8:9], v[8:9], v[78:79]
	v_pk_mul_f32 v[78:79], v[100:101], v[162:163] op_sel_hi:[1,0]
	v_pk_add_f32 v[18:19], v[18:19], v[34:35]
	v_pk_fma_f32 v[78:79], v[96:97], v[52:53], v[78:79] op_sel_hi:[1,0,1]
	v_pk_mul_f32 v[34:35], v[132:133], v[68:69] op_sel_hi:[1,0]
	v_pk_add_f32 v[8:9], v[8:9], v[78:79]
	v_pk_mul_f32 v[78:79], v[108:109], v[164:165] op_sel_hi:[1,0]
	v_pk_fma_f32 v[34:35], v[128:129], v[72:73], v[34:35] op_sel_hi:[1,0,1]
	v_pk_fma_f32 v[78:79], v[104:105], v[58:59], v[78:79] op_sel_hi:[1,0,1]
	v_pk_add_f32 v[18:19], v[18:19], v[34:35]
	v_pk_add_f32 v[8:9], v[8:9], v[78:79]
	v_pk_mul_f32 v[78:79], v[116:117], v[166:167] op_sel_hi:[1,0]
	v_pk_mul_f32 v[34:35], v[148:149], v[74:75] op_sel_hi:[1,0]
	v_pk_fma_f32 v[78:79], v[112:113], v[64:65], v[78:79] op_sel_hi:[1,0,1]
	v_pk_fma_f32 v[32:33], v[144:145], v[32:33], v[34:35] op_sel_hi:[1,0,1]
	v_pk_add_f32 v[8:9], v[8:9], v[78:79]
	v_pk_mul_f32 v[78:79], v[124:125], v[168:169] op_sel_hi:[1,0]
	v_pk_add_f32 v[18:19], v[18:19], v[32:33]
	v_pk_fma_f32 v[78:79], v[120:121], v[70:71], v[78:79] op_sel_hi:[1,0,1]
	v_pk_mul_f32 v[32:33], v[148:149], v[172:173] op_sel_hi:[1,0]
	v_pk_add_f32 v[8:9], v[8:9], v[78:79]
	v_pk_mul_f32 v[78:79], v[132:133], v[170:171] op_sel_hi:[1,0]
	v_pk_fma_f32 v[32:33], v[144:145], v[136:137], v[32:33] op_sel_hi:[1,0,1]
	v_pk_fma_f32 v[78:79], v[128:129], v[134:135], v[78:79] op_sel_hi:[1,0,1]
	v_add_u32_e32 v73, 0x100, v73
	v_pk_add_f32 v[8:9], v[8:9], v[78:79]
	s_nop 0
	v_pk_add_f32 v[8:9], v[8:9], v[32:33]
	s_andn2_b64 exec, exec, s[18:19]
	s_cbranch_execnz .LBB0_126
	s_or_b64 exec, exec, s[18:19]
	s_and_saveexec_b64 s[0:1], s[8:9]
	s_cbranch_execz .LBB0_129
	s_add_i32 s12, 16, 0x18000
	v_add_u32_e32 v0, s12, v43
	v_add_u32_e32 v26, s12, v47
	ds_write2_b64 v0, v[24:25], v[22:23] offset1:1
	ds_write_b128 v26, v[10:13]
	ds_write2_b64 v0, v[20:21], v[18:19] offset0:2 offset1:3
	ds_write_b128 v26, v[6:9] offset:16
; __device__ void gates_partial(const Ctx& p) {
;     ...
;     __syncthreads();
;     if (sub == 0) {
;       float* o0 = gpart + ((long)cg_ * NTOK + (long)b * SEQ + ta) * 8;
;       float* o1 = gpart + ((long)cg_ * NTOK + (long)b * SEQ + tb) * 8;
; #pragma unroll
;       for (int k = 0; k < 8; ++k) { o0[k] = g0[k] + red[tl * 8 + k]; o1[k] = g1[k] + red[(256 + tl) * 8 + k]; }
;     }
.LBB0_129:
	s_or_b64 exec, exec, s[0:1]
	s_waitcnt lgkmcnt(0)
	s_barrier
	s_and_saveexec_b64 s[0:1], s[10:11]
	s_cbranch_execz .LBB0_118
	v_add_u32_e32 v0, 16, v47
	v_add_u32_e32 v0, 0x18000, v0
	s_lshl_b32 s12, s23, 14
	ds_read_b32 v30, v0
	s_add_u32 s12, s16, s12
	s_addc_u32 s13, s17, 0
	v_or_b32_e32 v26, s12, v71
	v_mov_b32_e32 v27, s13
	v_lshlrev_b64 v[28:29], 5, v[26:27]
	v_lshl_add_u64 v[28:29], s[14:15], 0, v[28:29]
	s_waitcnt lgkmcnt(0)
	v_add_f32_e32 v24, v24, v30
	global_store_dword v[28:29], v24, off
	ds_read_b32 v24, v0 offset:8192
	v_or_b32_e32 v26, 1, v26
	v_lshlrev_b64 v[26:27], 5, v[26:27]
	v_lshl_add_u64 v[26:27], s[14:15], 0, v[26:27]
	s_waitcnt lgkmcnt(0)
	v_add_f32_e32 v10, v10, v24
	global_store_dword v[26:27], v10, off
	ds_read_b32 v10, v0 offset:4
	s_waitcnt lgkmcnt(0)
	v_add_f32_e32 v10, v25, v10
	global_store_dword v[28:29], v10, off offset:4
	ds_read_b32 v10, v0 offset:8196
	s_waitcnt lgkmcnt(0)
	v_add_f32_e32 v10, v11, v10
	global_store_dword v[26:27], v10, off offset:4
	ds_read_b32 v10, v0 offset:8
	s_waitcnt lgkmcnt(0)
	v_add_f32_e32 v10, v22, v10
	global_store_dword v[28:29], v10, off offset:8
	ds_read_b32 v10, v0 offset:8200
	s_waitcnt lgkmcnt(0)
	v_add_f32_e32 v10, v12, v10
	global_store_dword v[26:27], v10, off offset:8
	ds_read_b32 v10, v0 offset:12
	s_waitcnt lgkmcnt(0)
	v_add_f32_e32 v10, v23, v10
	global_store_dword v[28:29], v10, off offset:12
	ds_read_b32 v10, v0 offset:8204
	s_waitcnt lgkmcnt(0)
	v_add_f32_e32 v10, v13, v10
	global_store_dword v[26:27], v10, off offset:12
	ds_read_b32 v10, v0 offset:16
	s_waitcnt lgkmcnt(0)
	v_add_f32_e32 v10, v20, v10
	global_store_dword v[28:29], v10, off offset:16
	ds_read_b32 v10, v0 offset:8208
	s_waitcnt lgkmcnt(0)
	v_add_f32_e32 v6, v6, v10
	global_store_dword v[26:27], v6, off offset:16
	ds_read_b32 v6, v0 offset:20
	s_waitcnt lgkmcnt(0)
	v_add_f32_e32 v6, v21, v6
	global_store_dword v[28:29], v6, off offset:20
	ds_read_b32 v6, v0 offset:8212
	s_waitcnt lgkmcnt(0)
	v_add_f32_e32 v6, v7, v6
	global_store_dword v[26:27], v6, off offset:20
	ds_read_b32 v6, v0 offset:24
	s_waitcnt lgkmcnt(0)
	v_add_f32_e32 v6, v18, v6
	global_store_dword v[28:29], v6, off offset:24
	ds_read_b32 v6, v0 offset:8216
	s_waitcnt lgkmcnt(0)
	v_add_f32_e32 v6, v8, v6
	global_store_dword v[26:27], v6, off offset:24
	ds_read_b32 v6, v0 offset:28
	s_waitcnt lgkmcnt(0)
	v_add_f32_e32 v6, v19, v6
	global_store_dword v[28:29], v6, off offset:28
	ds_read_b32 v0, v0 offset:8220
	s_waitcnt lgkmcnt(0)
	v_add_f32_e32 v0, v9, v0
	global_store_dword v[26:27], v0, off offset:28
	s_branch .LBB0_118

;     ...
;   for (int item = (int)blockIdx.x - blk0; item < 128 * 4; item += nblk) {
;     const int tt = item >> 2, h = item & 3;
;     const long t0 = (long)tt * 128 + w * 16;
;     const int b = (int)(t0 >> 13);
;     bf16x8 aQ[4];
; #pragma unroll
;     for (int ks = 0; ks < 4; ++ks) aQ[ks] = *(const bf16x8*)(qg + (t0 + fr) * ldq + qcol + h * 128 + ks * 32 + fq * 8);
;     f32x4 s[16];
; #pragma unroll
;     for (int nb = 0; nb < 4; ++nb) {
;       bf16x8 bk[4][4];
; #pragma unroll
;       for (int n4 = 0; n4 < 4; ++n4)
; #pragma unroll
;         for (int ks = 0; ks < 4; ++ks)
;           bk[n4][ks] = *(const bf16x8*)(Km + (long)(b * 256 + (nb * 4 + n4) * 16 + fr) * 512 + h * 128 + ks * 32 + fq * 8);
;       asm volatile("" ::: "memory");
; #pragma unroll
;       for (int n4 = 0; n4 < 4; ++n4) {
;         f32x4 a = {0.f, 0.f, 0.f, 0.f};
; #pragma unroll
;         for (int ks = 0; ks < 4; ++ks) a = __builtin_amdgcn_mfma_f32_16x16x32_bf16(aQ[ks], bk[n4][ks], a, 0, 0, 0);
;         s[nb * 4 + n4] = a;
;       }
;     }
.LBB0_133:
	s_ashr_i32 s10, s7, 2
	s_ashr_i32 s11, s10, 31
	s_lshl_b64 s[10:11], s[10:11], 7
	v_lshl_add_u64 v[152:153], s[10:11], 0, v[132:133]
	v_or_b32_e32 v2, v152, v130
	v_mov_b32_e32 v3, v153
	s_and_b32 s8, s7, 3
	v_lshlrev_b64 v[2:3], 11, v[2:3]
	v_lshl_add_u64 v[2:3], s[0:1], 0, v[2:3]
	s_lshl_b32 s52, s8, 8
	v_lshl_add_u64 v[2:3], v[2:3], 0, s[52:53]
	v_lshl_add_u64 v[2:3], v[2:3], 0, v[0:1]
	global_load_dwordx4 v[26:29], v[2:3], off
	global_load_dwordx4 v[30:33], v[2:3], off offset:64
	s_waitcnt vmcnt(0)
	global_load_dwordx4 v[34:37], v[2:3], off offset:128
	global_load_dwordx4 v[38:41], v[2:3], off offset:192
	v_alignbit_b32 v2, v153, v152, 5
	v_and_b32_e32 v154, 0xffffff00, v2
	v_or_b32_e32 v116, v154, v130
	v_ashrrev_i32_e32 v117, 31, v116
	v_lshl_add_u64 v[114:115], v[134:135], 0, s[52:53]
	v_lshlrev_b64 v[2:3], 10, v[116:117]
	v_lshl_add_u64 v[14:15], v[114:115], 0, v[2:3]
	global_load_dwordx4 v[2:5], v[14:15], off
	global_load_dwordx4 v[6:9], v[14:15], off offset:64
	global_load_dwordx4 v[10:13], v[14:15], off offset:128
	s_nop 0
	global_load_dwordx4 v[14:17], v[14:15], off offset:192
	v_or_b32_e32 v18, 16, v116
	v_ashrrev_i32_e32 v19, 31, v18
	v_lshlrev_b64 v[18:19], 10, v[18:19]
	v_lshl_add_u64 v[46:47], v[114:115], 0, v[18:19]
	global_load_dwordx4 v[18:21], v[46:47], off
	global_load_dwordx4 v[22:25], v[46:47], off offset:64
	global_load_dwordx4 v[42:45], v[46:47], off offset:128
	s_nop 0
	global_load_dwordx4 v[46:49], v[46:47], off offset:192
	v_or_b32_e32 v50, 32, v116
	v_ashrrev_i32_e32 v51, 31, v50
	v_lshlrev_b64 v[50:51], 10, v[50:51]
	v_lshl_add_u64 v[62:63], v[114:115], 0, v[50:51]
	global_load_dwordx4 v[50:53], v[62:63], off
	global_load_dwordx4 v[54:57], v[62:63], off offset:64
	global_load_dwordx4 v[58:61], v[62:63], off offset:128
	s_nop 0
	global_load_dwordx4 v[62:65], v[62:63], off offset:192
	v_or_b32_e32 v66, 48, v116
	v_ashrrev_i32_e32 v67, 31, v66
	v_lshlrev_b64 v[66:67], 10, v[66:67]
	v_lshl_add_u64 v[78:79], v[114:115], 0, v[66:67]
	global_load_dwordx4 v[66:69], v[78:79], off
	global_load_dwordx4 v[70:73], v[78:79], off offset:64
	global_load_dwordx4 v[74:77], v[78:79], off offset:128
	s_nop 0
	global_load_dwordx4 v[78:81], v[78:79], off offset:192
	v_or_b32_e32 v82, 0x70, v116
	v_ashrrev_i32_e32 v83, 31, v82
	v_lshlrev_b64 v[82:83], 10, v[82:83]
	v_lshl_add_u64 v[94:95], v[114:115], 0, v[82:83]
	v_or_b32_e32 v98, 0xb0, v116
	v_ashrrev_i32_e32 v99, 31, v98
	v_lshlrev_b64 v[98:99], 10, v[98:99]
	v_lshl_add_u64 v[110:111], v[114:115], 0, v[98:99]
	v_ashrrev_i32_e32 v155, 31, v154
	s_add_i32 s7, s7, s6
	s_cmpk_gt_i32 s7, 0x1ff
	s_waitcnt vmcnt(0) lgkmcnt(0)
	v_mfma_f32_16x16x32_bf16 v[2:5], v[26:29], v[2:5], 0
	v_mfma_f32_16x16x32_bf16 v[2:5], v[30:33], v[6:9], v[2:5]
	v_mfma_f32_16x16x32_bf16 v[2:5], v[34:37], v[10:13], v[2:5]
	v_mfma_f32_16x16x32_bf16 v[14:17], v[38:41], v[14:17], v[2:5]
	v_mfma_f32_16x16x32_bf16 v[2:5], v[26:29], v[18:21], 0
	v_or_b32_e32 v18, 64, v116
	v_ashrrev_i32_e32 v19, 31, v18
	v_lshlrev_b64 v[18:19], 10, v[18:19]
	v_mfma_f32_16x16x32_bf16 v[2:5], v[30:33], v[22:25], v[2:5]
	v_mfma_f32_16x16x32_bf16 v[2:5], v[34:37], v[42:45], v[2:5]
	v_mfma_f32_16x16x32_bf16 v[10:13], v[38:41], v[46:49], v[2:5]
	v_lshl_add_u64 v[46:47], v[114:115], 0, v[18:19]
	global_load_dwordx4 v[18:21], v[46:47], off
	global_load_dwordx4 v[22:25], v[46:47], off offset:64
	global_load_dwordx4 v[42:45], v[46:47], off offset:128
	s_nop 0
	global_load_dwordx4 v[46:49], v[46:47], off offset:192
	v_mfma_f32_16x16x32_bf16 v[2:5], v[26:29], v[50:53], 0
	v_or_b32_e32 v50, 0x50, v116
	v_ashrrev_i32_e32 v51, 31, v50
	v_lshlrev_b64 v[50:51], 10, v[50:51]
	v_mfma_f32_16x16x32_bf16 v[2:5], v[30:33], v[54:57], v[2:5]
	v_mfma_f32_16x16x32_bf16 v[2:5], v[34:37], v[58:61], v[2:5]
	v_mfma_f32_16x16x32_bf16 v[6:9], v[38:41], v[62:65], v[2:5]
	v_lshl_add_u64 v[62:63], v[114:115], 0, v[50:51]
	global_load_dwordx4 v[50:53], v[62:63], off
	global_load_dwordx4 v[54:57], v[62:63], off offset:64
	global_load_dwordx4 v[58:61], v[62:63], off offset:128
	s_nop 0
	global_load_dwordx4 v[62:65], v[62:63], off offset:192
	v_mfma_f32_16x16x32_bf16 v[2:5], v[26:29], v[66:69], 0
	v_or_b32_e32 v66, 0x60, v116
	v_ashrrev_i32_e32 v67, 31, v66
	v_lshlrev_b64 v[66:67], 10, v[66:67]
	v_mfma_f32_16x16x32_bf16 v[2:5], v[30:33], v[70:73], v[2:5]
	v_mfma_f32_16x16x32_bf16 v[2:5], v[34:37], v[74:77], v[2:5]
	v_mfma_f32_16x16x32_bf16 v[2:5], v[38:41], v[78:81], v[2:5]
	v_lshl_add_u64 v[78:79], v[114:115], 0, v[66:67]
	global_load_dwordx4 v[66:69], v[78:79], off
	global_load_dwordx4 v[70:73], v[78:79], off offset:64
	global_load_dwordx4 v[74:77], v[78:79], off offset:128
	s_nop 0
	global_load_dwordx4 v[78:81], v[78:79], off offset:192
	s_nop 0
	global_load_dwordx4 v[82:85], v[94:95], off
	global_load_dwordx4 v[86:89], v[94:95], off offset:64
	global_load_dwordx4 v[90:93], v[94:95], off offset:128
	s_nop 0
	global_load_dwordx4 v[94:97], v[94:95], off offset:192
	s_waitcnt vmcnt(0) lgkmcnt(0)
;     ...
;     for (int nb = 0; nb < 4; ++nb) {
;       bf16x8 bk[4][4];
; #pragma unroll
;       for (int n4 = 0; n4 < 4; ++n4)
; #pragma unroll
;         for (int ks = 0; ks < 4; ++ks)
;           bk[n4][ks] = *(const bf16x8*)(Km + (long)(b * 256 + (nb * 4 + n4) * 16 + fr) * 512 + h * 128 + ks * 32 + fq * 8);
;       asm volatile("" ::: "memory");
; #pragma unroll
;       for (int n4 = 0; n4 < 4; ++n4) {
;         f32x4 a = {0.f, 0.f, 0.f, 0.f};
; #pragma unroll
;         for (int ks = 0; ks < 4; ++ks) a = __builtin_amdgcn_mfma_f32_16x16x32_bf16(aQ[ks], bk[n4][ks], a, 0, 0, 0);
;         s[nb * 4 + n4] = a;
;       }
;     }
;     const float scale = 0.08838834764831845f;
;     float mx[4], sm[4];
; #pragma unroll
;     for (int r = 0; r < 4; ++r) {
;       float v = s[0][r];
; #pragma unroll
;       for (int nt = 1; nt < 16; ++nt) v = fmaxf(v, s[nt][r]);
; #pragma unroll
;       for (int o = 1; o < 16; o <<= 1) v = fmaxf(v, __shfl_xor(v, o, 64));
;       mx[r] = v; sm[r] = 0.f;
;     }
;     __syncthreads();
	v_mfma_f32_16x16x32_bf16 v[18:21], v[26:29], v[18:21], 0
	v_mfma_f32_16x16x32_bf16 v[18:21], v[30:33], v[22:25], v[18:21]
	v_mfma_f32_16x16x32_bf16 v[18:21], v[34:37], v[42:45], v[18:21]
	v_mfma_f32_16x16x32_bf16 v[46:49], v[38:41], v[46:49], v[18:21]
	v_mfma_f32_16x16x32_bf16 v[18:21], v[26:29], v[50:53], 0
	v_or_b32_e32 v50, 0x80, v116
	v_ashrrev_i32_e32 v51, 31, v50
	v_lshlrev_b64 v[50:51], 10, v[50:51]
	v_mfma_f32_16x16x32_bf16 v[18:21], v[30:33], v[54:57], v[18:21]
	v_mfma_f32_16x16x32_bf16 v[18:21], v[34:37], v[58:61], v[18:21]
	v_mfma_f32_16x16x32_bf16 v[42:45], v[38:41], v[62:65], v[18:21]
	v_lshl_add_u64 v[62:63], v[114:115], 0, v[50:51]
	global_load_dwordx4 v[50:53], v[62:63], off
	global_load_dwordx4 v[54:57], v[62:63], off offset:64
	global_load_dwordx4 v[58:61], v[62:63], off offset:128
	s_nop 0
	global_load_dwordx4 v[62:65], v[62:63], off offset:192
	v_mfma_f32_16x16x32_bf16 v[18:21], v[26:29], v[66:69], 0
	v_or_b32_e32 v66, 0x90, v116
	v_ashrrev_i32_e32 v67, 31, v66
	v_lshlrev_b64 v[66:67], 10, v[66:67]
	v_mfma_f32_16x16x32_bf16 v[18:21], v[30:33], v[70:73], v[18:21]
	v_mfma_f32_16x16x32_bf16 v[18:21], v[34:37], v[74:77], v[18:21]
	v_mfma_f32_16x16x32_bf16 v[22:25], v[38:41], v[78:81], v[18:21]
	v_lshl_add_u64 v[78:79], v[114:115], 0, v[66:67]
	global_load_dwordx4 v[66:69], v[78:79], off
	global_load_dwordx4 v[70:73], v[78:79], off offset:64
	global_load_dwordx4 v[74:77], v[78:79], off offset:128
	s_nop 0
	global_load_dwordx4 v[78:81], v[78:79], off offset:192
	v_mfma_f32_16x16x32_bf16 v[18:21], v[26:29], v[82:85], 0
	v_or_b32_e32 v82, 0xa0, v116
	v_ashrrev_i32_e32 v83, 31, v82
	v_lshlrev_b64 v[82:83], 10, v[82:83]
	v_mfma_f32_16x16x32_bf16 v[18:21], v[30:33], v[86:89], v[18:21]
	v_mfma_f32_16x16x32_bf16 v[18:21], v[34:37], v[90:93], v[18:21]
	v_mfma_f32_16x16x32_bf16 v[18:21], v[38:41], v[94:97], v[18:21]
	v_lshl_add_u64 v[94:95], v[114:115], 0, v[82:83]
	global_load_dwordx4 v[82:85], v[94:95], off
	global_load_dwordx4 v[86:89], v[94:95], off offset:64
	global_load_dwordx4 v[90:93], v[94:95], off offset:128
	s_nop 0
	global_load_dwordx4 v[94:97], v[94:95], off offset:192
	s_nop 0
	global_load_dwordx4 v[98:101], v[110:111], off
	global_load_dwordx4 v[102:105], v[110:111], off offset:64
	global_load_dwordx4 v[106:109], v[110:111], off offset:128
	s_nop 0
	global_load_dwordx4 v[110:113], v[110:111], off offset:192
	s_waitcnt vmcnt(0) lgkmcnt(0)
	v_mfma_f32_16x16x32_bf16 v[50:53], v[26:29], v[50:53], 0
	v_mfma_f32_16x16x32_bf16 v[50:53], v[30:33], v[54:57], v[50:53]
	v_mfma_f32_16x16x32_bf16 v[50:53], v[34:37], v[58:61], v[50:53]
	v_mfma_f32_16x16x32_bf16 v[62:65], v[38:41], v[62:65], v[50:53]
	v_mfma_f32_16x16x32_bf16 v[50:53], v[26:29], v[66:69], 0
	v_or_b32_e32 v66, 0xc0, v116
	v_ashrrev_i32_e32 v67, 31, v66
	v_lshlrev_b64 v[66:67], 10, v[66:67]
	v_mfma_f32_16x16x32_bf16 v[50:53], v[30:33], v[70:73], v[50:53]
	v_mfma_f32_16x16x32_bf16 v[50:53], v[34:37], v[74:77], v[50:53]
	v_mfma_f32_16x16x32_bf16 v[58:61], v[38:41], v[78:81], v[50:53]
	v_lshl_add_u64 v[78:79], v[114:115], 0, v[66:67]
	global_load_dwordx4 v[66:69], v[78:79], off
	global_load_dwordx4 v[70:73], v[78:79], off offset:64
	global_load_dwordx4 v[74:77], v[78:79], off offset:128
	s_nop 0
	global_load_dwordx4 v[78:81], v[78:79], off offset:192
	v_mfma_f32_16x16x32_bf16 v[50:53], v[26:29], v[82:85], 0
	v_or_b32_e32 v82, 0xd0, v116
	v_ashrrev_i32_e32 v83, 31, v82
	v_lshlrev_b64 v[82:83], 10, v[82:83]
	v_mfma_f32_16x16x32_bf16 v[50:53], v[30:33], v[86:89], v[50:53]
	v_mfma_f32_16x16x32_bf16 v[50:53], v[34:37], v[90:93], v[50:53]
	v_mfma_f32_16x16x32_bf16 v[54:57], v[38:41], v[94:97], v[50:53]
	v_lshl_add_u64 v[94:95], v[114:115], 0, v[82:83]
	global_load_dwordx4 v[82:85], v[94:95], off
	global_load_dwordx4 v[86:89], v[94:95], off offset:64
	global_load_dwordx4 v[90:93], v[94:95], off offset:128
	s_nop 0
	global_load_dwordx4 v[94:97], v[94:95], off offset:192
	v_mfma_f32_16x16x32_bf16 v[50:53], v[26:29], v[98:101], 0
	v_or_b32_e32 v98, 0xe0, v116
	v_or_b32_e32 v116, 0xf0, v116
	v_ashrrev_i32_e32 v99, 31, v98
	v_mfma_f32_16x16x32_bf16 v[50:53], v[30:33], v[102:105], v[50:53]
	v_ashrrev_i32_e32 v117, 31, v116
	v_lshlrev_b64 v[98:99], 10, v[98:99]
	v_lshlrev_b64 v[116:117], 10, v[116:117]
	v_mfma_f32_16x16x32_bf16 v[50:53], v[34:37], v[106:109], v[50:53]
	v_lshl_add_u64 v[126:127], v[114:115], 0, v[116:117]
	v_mfma_f32_16x16x32_bf16 v[50:53], v[38:41], v[110:113], v[50:53]
	v_lshl_add_u64 v[110:111], v[114:115], 0, v[98:99]
	global_load_dwordx4 v[98:101], v[110:111], off
	global_load_dwordx4 v[102:105], v[110:111], off offset:64
	global_load_dwordx4 v[106:109], v[110:111], off offset:128
	s_nop 0
	global_load_dwordx4 v[110:113], v[110:111], off offset:192
	s_nop 0
	global_load_dwordx4 v[114:117], v[126:127], off
	global_load_dwordx4 v[118:121], v[126:127], off offset:64
	global_load_dwordx4 v[122:125], v[126:127], off offset:128
	s_nop 0
	global_load_dwordx4 v[126:129], v[126:127], off offset:192
	s_waitcnt lgkmcnt(0)
	s_barrier
;     ...
;     const float scale = 0.08838834764831845f;
;     float mx[4], sm[4];
; #pragma unroll
;     for (int r = 0; r < 4; ++r) {
;       float v = s[0][r];
; #pragma unroll
;       for (int nt = 1; nt < 16; ++nt) v = fmaxf(v, s[nt][r]);
; #pragma unroll
;       for (int o = 1; o < 16; o <<= 1) v = fmaxf(v, __shfl_xor(v, o, 64));
;       mx[r] = v; sm[r] = 0.f;
;     }
;     __syncthreads();
; #pragma unroll
;     for (int nt = 0; nt < 16; ++nt)
; #pragma unroll
;       for (int r = 0; r < 4; ++r) {
;         float e = __expf((s[nt][r] - mx[r]) * scale);
	s_waitcnt vmcnt(0)
	v_mfma_f32_16x16x32_bf16 v[66:69], v[26:29], v[66:69], 0
	v_mfma_f32_16x16x32_bf16 v[66:69], v[30:33], v[70:73], v[66:69]
	v_mfma_f32_16x16x32_bf16 v[66:69], v[34:37], v[74:77], v[66:69]
	v_mfma_f32_16x16x32_bf16 v[74:77], v[38:41], v[78:81], v[66:69]
	v_mfma_f32_16x16x32_bf16 v[66:69], v[26:29], v[82:85], 0
	v_lshl_or_b32 v82, v130, 1, s52
	v_mov_b32_e32 v83, v1
	v_lshl_add_u64 v[82:83], s[4:5], 0, v[82:83]
	v_mfma_f32_16x16x32_bf16 v[66:69], v[30:33], v[86:89], v[66:69]
	v_mfma_f32_16x16x32_bf16 v[66:69], v[34:37], v[90:93], v[66:69]
	v_mfma_f32_16x16x32_bf16 v[70:73], v[38:41], v[94:97], v[66:69]
	v_mfma_f32_16x16x32_bf16 v[66:69], v[26:29], v[98:101], 0
	v_mfma_f32_16x16x32_bf16 v[26:29], v[26:29], v[114:117], 0
	v_mfma_f32_16x16x32_bf16 v[66:69], v[30:33], v[102:105], v[66:69]
	v_mfma_f32_16x16x32_bf16 v[26:29], v[30:33], v[118:121], v[26:29]
	v_max_f32_e32 v30, v10, v10
	v_max_f32_e32 v31, v14, v14
	v_max_f32_e32 v30, v31, v30
	v_mfma_f32_16x16x32_bf16 v[66:69], v[34:37], v[106:109], v[66:69]
	v_max3_f32 v30, v30, v6, v2
	v_max3_f32 v30, v30, v46, v42
	v_max3_f32 v30, v30, v22, v18
	v_mfma_f32_16x16x32_bf16 v[26:29], v[34:37], v[122:125], v[26:29]
	v_max3_f32 v30, v30, v62, v58
	v_max3_f32 v30, v30, v54, v50
	v_max3_f32 v30, v30, v74, v70
	v_mfma_f32_16x16x32_bf16 v[66:69], v[38:41], v[110:113], v[66:69]
	v_add_u32_e32 v33, 64, v196
	v_max_f32_e32 v36, v15, v15
	v_max_f32_e32 v37, v16, v16
	v_mfma_f32_16x16x32_bf16 v[26:29], v[38:41], v[126:129], v[26:29]
	v_max_f32_e32 v38, v17, v17
	v_mov_b32_e32 v39, v1
	s_nop 5
	v_max3_f32 v31, v30, v66, v26
	v_xor_b32_e32 v30, 1, v195
	v_cmp_lt_i32_e32 vcc, v30, v33
	s_nop 1
	v_cndmask_b32_e32 v30, v195, v30, vcc
	v_lshlrev_b32_e32 v30, 2, v30
	ds_bpermute_b32 v32, v30, v31
	s_waitcnt lgkmcnt(0)
	v_max_f32_e32 v32, v32, v32
	v_max_f32_e32 v32, v31, v32
	v_xor_b32_e32 v31, 2, v195
	v_cmp_lt_i32_e32 vcc, v31, v33
	s_nop 1
	v_cndmask_b32_e32 v31, v195, v31, vcc
	v_lshlrev_b32_e32 v31, 2, v31
	ds_bpermute_b32 v34, v31, v32
	s_waitcnt lgkmcnt(0)
	v_max_f32_e32 v34, v34, v34
	v_max_f32_e32 v34, v32, v34
	v_xor_b32_e32 v32, 4, v195
	v_cmp_lt_i32_e32 vcc, v32, v33
	s_nop 1
	v_cndmask_b32_e32 v32, v195, v32, vcc
	v_lshlrev_b32_e32 v32, 2, v32
	ds_bpermute_b32 v35, v32, v34
	s_waitcnt lgkmcnt(0)
	v_max_f32_e32 v35, v35, v35
	v_max_f32_e32 v34, v34, v35
	v_xor_b32_e32 v35, 8, v195
	v_cmp_lt_i32_e32 vcc, v35, v33
	s_nop 1
	v_cndmask_b32_e32 v33, v195, v35, vcc
	v_lshlrev_b32_e32 v33, 2, v33
	ds_bpermute_b32 v35, v33, v34
	s_waitcnt lgkmcnt(0)
	v_max_f32_e32 v35, v35, v35
	v_max_f32_e32 v34, v34, v35
	v_max_f32_e32 v35, v11, v11
	v_max_f32_e32 v35, v36, v35
	v_max3_f32 v35, v35, v7, v3
	v_max3_f32 v35, v35, v47, v43
	v_max3_f32 v35, v35, v23, v19
	v_max3_f32 v35, v35, v63, v59
	v_max3_f32 v35, v35, v55, v51
	v_max3_f32 v35, v35, v75, v71
	v_max3_f32 v35, v35, v67, v27
	ds_bpermute_b32 v36, v30, v35
	v_sub_f32_e32 v14, v14, v34
	v_mul_f32_e32 v14, 0x3db504f3, v14
	v_mul_f32_e32 v14, 0x3fb8aa3b, v14
	v_exp_f32_e32 v14, v14
	s_waitcnt lgkmcnt(0)
	v_max_f32_e32 v36, v36, v36
	v_max_f32_e32 v35, v35, v36
	ds_bpermute_b32 v36, v31, v35
	v_sub_f32_e32 v10, v10, v34
	v_mul_f32_e32 v10, 0x3db504f3, v10
	v_mul_f32_e32 v10, 0x3fb8aa3b, v10
	v_exp_f32_e32 v10, v10
	s_waitcnt lgkmcnt(0)
	v_max_f32_e32 v36, v36, v36
	v_max_f32_e32 v35, v35, v36
	ds_bpermute_b32 v36, v32, v35
	v_sub_f32_e32 v6, v6, v34
	v_mul_f32_e32 v6, 0x3db504f3, v6
	v_mul_f32_e32 v6, 0x3fb8aa3b, v6
	v_exp_f32_e32 v6, v6
	s_waitcnt lgkmcnt(0)
	v_max_f32_e32 v36, v36, v36
	v_max_f32_e32 v35, v35, v36
	ds_bpermute_b32 v36, v33, v35
	v_sub_f32_e32 v2, v2, v34
	v_mul_f32_e32 v2, 0x3db504f3, v2
	v_mul_f32_e32 v2, 0x3fb8aa3b, v2
	v_exp_f32_e32 v2, v2
	s_waitcnt lgkmcnt(0)
	v_max_f32_e32 v36, v36, v36
	v_max_f32_e32 v35, v35, v36
	v_max_f32_e32 v36, v12, v12
	v_max_f32_e32 v36, v37, v36
	v_max3_f32 v36, v36, v8, v4
	v_max3_f32 v36, v36, v48, v44
	v_max3_f32 v36, v36, v24, v20
	v_max3_f32 v36, v36, v64, v60
	v_max3_f32 v36, v36, v56, v52
	v_max3_f32 v36, v36, v76, v72
	v_max3_f32 v36, v36, v68, v28
	ds_bpermute_b32 v37, v30, v36
	s_waitcnt lgkmcnt(0)
	v_max_f32_e32 v37, v37, v37
	v_max_f32_e32 v36, v36, v37
	ds_bpermute_b32 v37, v31, v36
	s_waitcnt lgkmcnt(0)
	v_max_f32_e32 v37, v37, v37
	v_max_f32_e32 v36, v36, v37
	ds_bpermute_b32 v37, v32, v36
	s_waitcnt lgkmcnt(0)
	v_max_f32_e32 v37, v37, v37
	v_max_f32_e32 v36, v36, v37
	ds_bpermute_b32 v37, v33, v36
	s_waitcnt lgkmcnt(0)
	v_max_f32_e32 v37, v37, v37
	v_max_f32_e32 v36, v36, v37
	v_max_f32_e32 v37, v13, v13
	v_max_f32_e32 v37, v38, v37
	v_max3_f32 v37, v37, v9, v5
	v_max3_f32 v37, v37, v49, v45
	v_max3_f32 v37, v37, v25, v21
	v_max3_f32 v37, v37, v65, v61
	v_max3_f32 v37, v37, v57, v53
	v_max3_f32 v37, v37, v77, v73
	v_max3_f32 v37, v37, v69, v29
	ds_bpermute_b32 v38, v30, v37
	s_waitcnt lgkmcnt(0)
	v_max_f32_e32 v38, v38, v38
	v_max_f32_e32 v37, v37, v38
	ds_bpermute_b32 v38, v31, v37
	s_waitcnt lgkmcnt(0)
	v_max_f32_e32 v38, v38, v38
	v_max_f32_e32 v37, v37, v38
	ds_bpermute_b32 v38, v32, v37
	s_waitcnt lgkmcnt(0)
	v_max_f32_e32 v38, v38, v38
	v_max_f32_e32 v37, v37, v38
	ds_bpermute_b32 v38, v33, v37
	s_waitcnt lgkmcnt(0)
; __device__ __forceinline__ u16 f2bf(float f) { return (u16)(pack2(f, 0.f) & 0xffffu); }
;     ...
; #pragma unroll
;     for (int nt = 0; nt < 16; ++nt)
; #pragma unroll
;       for (int r = 0; r < 4; ++r) {
;         float e = __expf((s[nt][r] - mx[r]) * scale);
;         sm[r] += e;
;         Pw[(fq * 4 + r) * 264 + nt * 16 + fr] = f2bf(e);
;       }
	v_max_f32_e32 v38, v38, v38
	v_max_f32_e32 v37, v37, v38
	v_add_f32_e32 v38, 0, v14
	v_cvt_pk_bf16_f32 v14, v14, s0
	ds_write_b16 v131, v14
	v_sub_f32_e32 v14, v15, v35
	v_mul_f32_e32 v14, 0x3db504f3, v14
	v_mul_f32_e32 v14, 0x3fb8aa3b, v14
	v_exp_f32_e32 v14, v14
	s_nop 0
	v_add_f32_e32 v15, 0, v14
	v_cvt_pk_bf16_f32 v14, v14, s0
	ds_write_b16 v141, v14
	v_sub_f32_e32 v14, v16, v36
	v_mul_f32_e32 v14, 0x3db504f3, v14
	v_mul_f32_e32 v14, 0x3fb8aa3b, v14
	v_exp_f32_e32 v14, v14
	s_nop 0
	v_add_f32_e32 v16, 0, v14
	v_cvt_pk_bf16_f32 v14, v14, s0
	ds_write_b16 v141, v14 offset:528
	v_sub_f32_e32 v14, v17, v37
	v_mul_f32_e32 v14, 0x3db504f3, v14
	v_mul_f32_e32 v14, 0x3fb8aa3b, v14
	v_exp_f32_e32 v14, v14
	s_nop 0
	v_add_f32_e32 v17, 0, v14
	v_cvt_pk_bf16_f32 v14, v14, s0
	ds_write_b16 v141, v14 offset:1056
	v_add_f32_e32 v14, v10, v38
	v_cvt_pk_bf16_f32 v10, v10, s0
	ds_write_b16 v131, v10 offset:32
	v_sub_f32_e32 v10, v11, v35
	v_mul_f32_e32 v10, 0x3db504f3, v10
	v_mul_f32_e32 v10, 0x3fb8aa3b, v10
	v_exp_f32_e32 v10, v10
	v_lshl_or_b32 v38, s8, 17, v149
	v_add_f32_e32 v11, v10, v15
	v_cvt_pk_bf16_f32 v10, v10, s0
	ds_write_b16 v141, v10 offset:32
	v_sub_f32_e32 v10, v12, v36
	v_mul_f32_e32 v10, 0x3db504f3, v10
	v_mul_f32_e32 v10, 0x3fb8aa3b, v10
	v_exp_f32_e32 v10, v10
	s_nop 0
	v_add_f32_e32 v12, v10, v16
	v_cvt_pk_bf16_f32 v10, v10, s0
	ds_write_b16 v141, v10 offset:560
	v_sub_f32_e32 v10, v13, v37
	v_mul_f32_e32 v10, 0x3db504f3, v10
	v_mul_f32_e32 v10, 0x3fb8aa3b, v10
	v_exp_f32_e32 v10, v10
	s_nop 0
	v_add_f32_e32 v13, v10, v17
	v_cvt_pk_bf16_f32 v10, v10, s0
	ds_write_b16 v141, v10 offset:1088
	v_add_f32_e32 v10, v6, v14
	v_cvt_pk_bf16_f32 v6, v6, s0
	ds_write_b16 v131, v6 offset:64
	v_sub_f32_e32 v6, v7, v35
	v_mul_f32_e32 v6, 0x3db504f3, v6
	v_mul_f32_e32 v6, 0x3fb8aa3b, v6
	v_exp_f32_e32 v6, v6
	s_nop 0
	v_add_f32_e32 v7, v6, v11
	v_cvt_pk_bf16_f32 v6, v6, s0
	ds_write_b16 v141, v6 offset:64
	v_sub_f32_e32 v6, v8, v36
	v_mul_f32_e32 v6, 0x3db504f3, v6
	v_mul_f32_e32 v6, 0x3fb8aa3b, v6
	v_exp_f32_e32 v6, v6
	s_nop 0
	v_add_f32_e32 v8, v6, v12
	v_cvt_pk_bf16_f32 v6, v6, s0
	ds_write_b16 v141, v6 offset:592
	v_sub_f32_e32 v6, v9, v37
	v_mul_f32_e32 v6, 0x3db504f3, v6
	v_mul_f32_e32 v6, 0x3fb8aa3b, v6
	v_exp_f32_e32 v6, v6
	s_nop 0
	v_add_f32_e32 v9, v6, v13
	v_cvt_pk_bf16_f32 v6, v6, s0
	ds_write_b16 v141, v6 offset:1120
	v_add_f32_e32 v6, v2, v10
	v_cvt_pk_bf16_f32 v2, v2, s0
	ds_write_b16 v131, v2 offset:96
	v_sub_f32_e32 v2, v3, v35
	v_mul_f32_e32 v2, 0x3db504f3, v2
	v_mul_f32_e32 v2, 0x3fb8aa3b, v2
	v_exp_f32_e32 v2, v2
	s_nop 0
	v_add_f32_e32 v3, v2, v7
	v_cvt_pk_bf16_f32 v2, v2, s0
	ds_write_b16 v141, v2 offset:96
	v_sub_f32_e32 v2, v4, v36
	v_mul_f32_e32 v2, 0x3db504f3, v2
	v_mul_f32_e32 v2, 0x3fb8aa3b, v2
	v_exp_f32_e32 v2, v2
	s_nop 0
	v_add_f32_e32 v4, v2, v8
	v_cvt_pk_bf16_f32 v2, v2, s0
	ds_write_b16 v141, v2 offset:624
	v_sub_f32_e32 v2, v5, v37
	v_mul_f32_e32 v2, 0x3db504f3, v2
	v_mul_f32_e32 v2, 0x3fb8aa3b, v2
	v_exp_f32_e32 v2, v2
	s_nop 0
	v_add_f32_e32 v5, v2, v9
	v_cvt_pk_bf16_f32 v2, v2, s0
	ds_write_b16 v141, v2 offset:1152
	v_sub_f32_e32 v2, v46, v34
	v_mul_f32_e32 v2, 0x3db504f3, v2
	v_mul_f32_e32 v2, 0x3fb8aa3b, v2
	v_exp_f32_e32 v2, v2
	s_nop 0
	v_add_f32_e32 v6, v2, v6
	v_cvt_pk_bf16_f32 v2, v2, s0
	ds_write_b16 v131, v2 offset:128
	v_sub_f32_e32 v2, v47, v35
	v_mul_f32_e32 v2, 0x3db504f3, v2
	v_mul_f32_e32 v2, 0x3fb8aa3b, v2
	v_exp_f32_e32 v2, v2
	s_nop 0
	v_add_f32_e32 v3, v2, v3
	v_cvt_pk_bf16_f32 v2, v2, s0
	ds_write_b16 v141, v2 offset:128
	v_sub_f32_e32 v2, v48, v36
	v_mul_f32_e32 v2, 0x3db504f3, v2
	v_mul_f32_e32 v2, 0x3fb8aa3b, v2
	v_exp_f32_e32 v2, v2
	s_nop 0
	v_add_f32_e32 v4, v2, v4
	v_cvt_pk_bf16_f32 v2, v2, s0
	ds_write_b16 v141, v2 offset:656
	v_sub_f32_e32 v2, v49, v37
	v_mul_f32_e32 v2, 0x3db504f3, v2
	v_mul_f32_e32 v2, 0x3fb8aa3b, v2
	v_exp_f32_e32 v2, v2
	s_nop 0
	v_add_f32_e32 v5, v2, v5
	v_cvt_pk_bf16_f32 v2, v2, s0
	ds_write_b16 v141, v2 offset:1184
	v_sub_f32_e32 v2, v42, v34
	v_mul_f32_e32 v2, 0x3db504f3, v2
	v_mul_f32_e32 v2, 0x3fb8aa3b, v2
	v_exp_f32_e32 v2, v2
	s_nop 0
	v_add_f32_e32 v6, v2, v6
	v_cvt_pk_bf16_f32 v2, v2, s0
	ds_write_b16 v131, v2 offset:160
	v_sub_f32_e32 v2, v43, v35
	v_mul_f32_e32 v2, 0x3db504f3, v2
	v_mul_f32_e32 v2, 0x3fb8aa3b, v2
	v_exp_f32_e32 v2, v2
	s_nop 0
	v_add_f32_e32 v3, v2, v3
	v_cvt_pk_bf16_f32 v2, v2, s0
	ds_write_b16 v141, v2 offset:160
	v_sub_f32_e32 v2, v44, v36
	v_mul_f32_e32 v2, 0x3db504f3, v2
	v_mul_f32_e32 v2, 0x3fb8aa3b, v2
	v_exp_f32_e32 v2, v2
	s_nop 0
	v_add_f32_e32 v4, v2, v4
	v_cvt_pk_bf16_f32 v2, v2, s0
	ds_write_b16 v141, v2 offset:688
	v_sub_f32_e32 v2, v45, v37
	v_mul_f32_e32 v2, 0x3db504f3, v2
	v_mul_f32_e32 v2, 0x3fb8aa3b, v2
	v_exp_f32_e32 v2, v2
	s_nop 0
	v_add_f32_e32 v5, v2, v5
	v_cvt_pk_bf16_f32 v2, v2, s0
	ds_write_b16 v141, v2 offset:1216
	v_sub_f32_e32 v2, v22, v34
	v_mul_f32_e32 v2, 0x3db504f3, v2
	v_mul_f32_e32 v2, 0x3fb8aa3b, v2
	v_exp_f32_e32 v2, v2
	s_nop 0
	v_add_f32_e32 v6, v2, v6
	v_cvt_pk_bf16_f32 v2, v2, s0
	ds_write_b16 v131, v2 offset:192
	v_sub_f32_e32 v2, v23, v35
	v_mul_f32_e32 v2, 0x3db504f3, v2
	v_mul_f32_e32 v2, 0x3fb8aa3b, v2
	v_exp_f32_e32 v2, v2
	s_nop 0
	v_add_f32_e32 v3, v2, v3
	v_cvt_pk_bf16_f32 v2, v2, s0
	ds_write_b16 v141, v2 offset:192
	v_sub_f32_e32 v2, v24, v36
	v_mul_f32_e32 v2, 0x3db504f3, v2
	v_mul_f32_e32 v2, 0x3fb8aa3b, v2
	v_exp_f32_e32 v2, v2
	s_nop 0
	v_add_f32_e32 v4, v2, v4
	v_cvt_pk_bf16_f32 v2, v2, s0
	ds_write_b16 v141, v2 offset:720
	v_sub_f32_e32 v2, v25, v37
	v_mul_f32_e32 v2, 0x3db504f3, v2
	v_mul_f32_e32 v2, 0x3fb8aa3b, v2
	v_exp_f32_e32 v2, v2
	s_nop 0
	v_add_f32_e32 v5, v2, v5
; __device__ __forceinline__ u16 f2bf(float f) { return (u16)(pack2(f, 0.f) & 0xffffu); }
;     ...
; #pragma unroll
;     for (int nt = 0; nt < 16; ++nt)
; #pragma unroll
;       for (int r = 0; r < 4; ++r) {
;         float e = __expf((s[nt][r] - mx[r]) * scale);
;         sm[r] += e;
;         Pw[(fq * 4 + r) * 264 + nt * 16 + fr] = f2bf(e);
;       }
	v_cvt_pk_bf16_f32 v2, v2, s0
	ds_write_b16 v141, v2 offset:1248
	v_sub_f32_e32 v2, v18, v34
	v_mul_f32_e32 v2, 0x3db504f3, v2
	v_mul_f32_e32 v2, 0x3fb8aa3b, v2
	v_exp_f32_e32 v2, v2
	s_nop 0
	v_add_f32_e32 v6, v2, v6
	v_cvt_pk_bf16_f32 v2, v2, s0
	ds_write_b16 v131, v2 offset:224
	v_sub_f32_e32 v2, v19, v35
	v_mul_f32_e32 v2, 0x3db504f3, v2
	v_mul_f32_e32 v2, 0x3fb8aa3b, v2
	v_exp_f32_e32 v2, v2
	s_nop 0
	v_add_f32_e32 v3, v2, v3
	v_cvt_pk_bf16_f32 v2, v2, s0
	ds_write_b16 v141, v2 offset:224
	v_sub_f32_e32 v2, v20, v36
	v_mul_f32_e32 v2, 0x3db504f3, v2
	v_mul_f32_e32 v2, 0x3fb8aa3b, v2
	v_exp_f32_e32 v2, v2
	s_nop 0
	v_add_f32_e32 v4, v2, v4
	v_cvt_pk_bf16_f32 v2, v2, s0
	ds_write_b16 v141, v2 offset:752
	v_sub_f32_e32 v2, v21, v37
	v_mul_f32_e32 v2, 0x3db504f3, v2
	v_mul_f32_e32 v2, 0x3fb8aa3b, v2
	v_exp_f32_e32 v2, v2
	s_nop 0
	v_add_f32_e32 v5, v2, v5
	v_cvt_pk_bf16_f32 v2, v2, s0
	ds_write_b16 v141, v2 offset:1280
	v_sub_f32_e32 v2, v62, v34
	v_mul_f32_e32 v2, 0x3db504f3, v2
	v_mul_f32_e32 v2, 0x3fb8aa3b, v2
	v_exp_f32_e32 v2, v2
	s_nop 0
	v_add_f32_e32 v6, v2, v6
	v_cvt_pk_bf16_f32 v2, v2, s0
	ds_write_b16 v131, v2 offset:256
	v_sub_f32_e32 v2, v63, v35
	v_mul_f32_e32 v2, 0x3db504f3, v2
	v_mul_f32_e32 v2, 0x3fb8aa3b, v2
	v_exp_f32_e32 v2, v2
	s_nop 0
	v_add_f32_e32 v3, v2, v3
	v_cvt_pk_bf16_f32 v2, v2, s0
	ds_write_b16 v141, v2 offset:256
	v_sub_f32_e32 v2, v64, v36
	v_mul_f32_e32 v2, 0x3db504f3, v2
	v_mul_f32_e32 v2, 0x3fb8aa3b, v2
	v_exp_f32_e32 v2, v2
	s_nop 0
	v_add_f32_e32 v4, v2, v4
	v_cvt_pk_bf16_f32 v2, v2, s0
	ds_write_b16 v141, v2 offset:784
	v_sub_f32_e32 v2, v65, v37
	v_mul_f32_e32 v2, 0x3db504f3, v2
	v_mul_f32_e32 v2, 0x3fb8aa3b, v2
	v_exp_f32_e32 v2, v2
	s_nop 0
	v_add_f32_e32 v5, v2, v5
	v_cvt_pk_bf16_f32 v2, v2, s0
	ds_write_b16 v141, v2 offset:1312
	v_sub_f32_e32 v2, v58, v34
	v_mul_f32_e32 v2, 0x3db504f3, v2
	v_mul_f32_e32 v2, 0x3fb8aa3b, v2
	v_exp_f32_e32 v2, v2
	s_nop 0
	v_add_f32_e32 v6, v2, v6
	v_cvt_pk_bf16_f32 v2, v2, s0
	ds_write_b16 v131, v2 offset:288
	v_sub_f32_e32 v2, v59, v35
	v_mul_f32_e32 v2, 0x3db504f3, v2
	v_mul_f32_e32 v2, 0x3fb8aa3b, v2
	v_exp_f32_e32 v2, v2
	s_nop 0
	v_add_f32_e32 v3, v2, v3
	v_cvt_pk_bf16_f32 v2, v2, s0
	ds_write_b16 v141, v2 offset:288
	v_sub_f32_e32 v2, v60, v36
	v_mul_f32_e32 v2, 0x3db504f3, v2
	v_mul_f32_e32 v2, 0x3fb8aa3b, v2
	v_exp_f32_e32 v2, v2
	s_nop 0
	v_add_f32_e32 v4, v2, v4
	v_cvt_pk_bf16_f32 v2, v2, s0
	ds_write_b16 v141, v2 offset:816
	v_sub_f32_e32 v2, v61, v37
	v_mul_f32_e32 v2, 0x3db504f3, v2
	v_mul_f32_e32 v2, 0x3fb8aa3b, v2
	v_exp_f32_e32 v2, v2
	s_nop 0
	v_add_f32_e32 v5, v2, v5
	v_cvt_pk_bf16_f32 v2, v2, s0
	ds_write_b16 v141, v2 offset:1344
	v_sub_f32_e32 v2, v54, v34
	v_mul_f32_e32 v2, 0x3db504f3, v2
	v_mul_f32_e32 v2, 0x3fb8aa3b, v2
	v_exp_f32_e32 v2, v2
	s_nop 0
	v_add_f32_e32 v6, v2, v6
	v_cvt_pk_bf16_f32 v2, v2, s0
	ds_write_b16 v131, v2 offset:320
	v_sub_f32_e32 v2, v55, v35
	v_mul_f32_e32 v2, 0x3db504f3, v2
	v_mul_f32_e32 v2, 0x3fb8aa3b, v2
	v_exp_f32_e32 v2, v2
	s_nop 0
	v_add_f32_e32 v3, v2, v3
	v_cvt_pk_bf16_f32 v2, v2, s0
	ds_write_b16 v141, v2 offset:320
	v_sub_f32_e32 v2, v56, v36
	v_mul_f32_e32 v2, 0x3db504f3, v2
	v_mul_f32_e32 v2, 0x3fb8aa3b, v2
	v_exp_f32_e32 v2, v2
	s_nop 0
	v_add_f32_e32 v4, v2, v4
	v_cvt_pk_bf16_f32 v2, v2, s0
	ds_write_b16 v141, v2 offset:848
	v_sub_f32_e32 v2, v57, v37
	v_mul_f32_e32 v2, 0x3db504f3, v2
	v_mul_f32_e32 v2, 0x3fb8aa3b, v2
	v_exp_f32_e32 v2, v2
	s_nop 0
	v_add_f32_e32 v5, v2, v5
	v_cvt_pk_bf16_f32 v2, v2, s0
	ds_write_b16 v141, v2 offset:1376
	v_sub_f32_e32 v2, v50, v34
	v_mul_f32_e32 v2, 0x3db504f3, v2
	v_mul_f32_e32 v2, 0x3fb8aa3b, v2
	v_exp_f32_e32 v2, v2
	s_nop 0
	v_add_f32_e32 v6, v2, v6
	v_cvt_pk_bf16_f32 v2, v2, s0
	ds_write_b16 v131, v2 offset:352
	v_sub_f32_e32 v2, v51, v35
	v_mul_f32_e32 v2, 0x3db504f3, v2
	v_mul_f32_e32 v2, 0x3fb8aa3b, v2
	v_exp_f32_e32 v2, v2
	s_nop 0
	v_add_f32_e32 v3, v2, v3
	v_cvt_pk_bf16_f32 v2, v2, s0
	ds_write_b16 v141, v2 offset:352
	v_sub_f32_e32 v2, v52, v36
	v_mul_f32_e32 v2, 0x3db504f3, v2
	v_mul_f32_e32 v2, 0x3fb8aa3b, v2
	v_exp_f32_e32 v2, v2
	s_nop 0
	v_add_f32_e32 v4, v2, v4
	v_cvt_pk_bf16_f32 v2, v2, s0
	ds_write_b16 v141, v2 offset:880
	v_sub_f32_e32 v2, v53, v37
	v_mul_f32_e32 v2, 0x3db504f3, v2
	v_mul_f32_e32 v2, 0x3fb8aa3b, v2
	v_exp_f32_e32 v2, v2
	s_nop 0
	v_add_f32_e32 v5, v2, v5
	v_cvt_pk_bf16_f32 v2, v2, s0
	ds_write_b16 v141, v2 offset:1408
	v_sub_f32_e32 v2, v74, v34
	v_mul_f32_e32 v2, 0x3db504f3, v2
	v_mul_f32_e32 v2, 0x3fb8aa3b, v2
	v_exp_f32_e32 v2, v2
	s_nop 0
	v_add_f32_e32 v6, v2, v6
	v_cvt_pk_bf16_f32 v2, v2, s0
	ds_write_b16 v131, v2 offset:384
	v_sub_f32_e32 v2, v75, v35
	v_mul_f32_e32 v2, 0x3db504f3, v2
	v_mul_f32_e32 v2, 0x3fb8aa3b, v2
	v_exp_f32_e32 v2, v2
	s_nop 0
	v_add_f32_e32 v3, v2, v3
	v_cvt_pk_bf16_f32 v2, v2, s0
	ds_write_b16 v141, v2 offset:384
	v_sub_f32_e32 v2, v76, v36
	v_mul_f32_e32 v2, 0x3db504f3, v2
	v_mul_f32_e32 v2, 0x3fb8aa3b, v2
	v_exp_f32_e32 v2, v2
	s_nop 0
	v_add_f32_e32 v4, v2, v4
	v_cvt_pk_bf16_f32 v2, v2, s0
	ds_write_b16 v141, v2 offset:912
	v_sub_f32_e32 v2, v77, v37
	v_mul_f32_e32 v2, 0x3db504f3, v2
	v_mul_f32_e32 v2, 0x3fb8aa3b, v2
	v_exp_f32_e32 v2, v2
	s_nop 0
	v_add_f32_e32 v5, v2, v5
	v_cvt_pk_bf16_f32 v2, v2, s0
	ds_write_b16 v141, v2 offset:1440
	v_sub_f32_e32 v2, v70, v34
	v_mul_f32_e32 v2, 0x3db504f3, v2
	v_mul_f32_e32 v2, 0x3fb8aa3b, v2
	v_exp_f32_e32 v2, v2
	v_or_b32_e32 v70, v152, v136
	v_add_f32_e32 v6, v2, v6
	v_cvt_pk_bf16_f32 v2, v2, s0
	ds_write_b16 v131, v2 offset:416
	v_sub_f32_e32 v2, v71, v35
	v_mul_f32_e32 v2, 0x3db504f3, v2
	v_mul_f32_e32 v2, 0x3fb8aa3b, v2
	v_exp_f32_e32 v2, v2
; __device__ __forceinline__ u16 f2bf(float f) { return (u16)(pack2(f, 0.f) & 0xffffu); }
;     ...
; #pragma unroll
;     for (int nt = 0; nt < 16; ++nt)
; #pragma unroll
;       for (int r = 0; r < 4; ++r) {
;         float e = __expf((s[nt][r] - mx[r]) * scale);
;         sm[r] += e;
;         Pw[(fq * 4 + r) * 264 + nt * 16 + fr] = f2bf(e);
;       }
; #pragma unroll
;     for (int r = 0; r < 4; ++r) {
;       float v = sm[r];
; #pragma unroll
;       for (int o = 1; o < 16; o <<= 1) v += __shfl_xor(v, o, 64);
;       sm[r] = 1.f / v;
;     }
;     __syncthreads();
	v_mov_b32_e32 v71, v153
	v_add_f32_e32 v3, v2, v3
	v_cvt_pk_bf16_f32 v2, v2, s0
	ds_write_b16 v141, v2 offset:416
	v_sub_f32_e32 v2, v72, v36
	v_mul_f32_e32 v2, 0x3db504f3, v2
	v_mul_f32_e32 v2, 0x3fb8aa3b, v2
	v_exp_f32_e32 v2, v2
	s_nop 0
	v_add_f32_e32 v4, v2, v4
	v_cvt_pk_bf16_f32 v2, v2, s0
	ds_write_b16 v141, v2 offset:944
	v_sub_f32_e32 v2, v73, v37
	v_mul_f32_e32 v2, 0x3db504f3, v2
	v_mul_f32_e32 v2, 0x3fb8aa3b, v2
	v_exp_f32_e32 v2, v2
	s_nop 0
	v_add_f32_e32 v5, v2, v5
	v_cvt_pk_bf16_f32 v2, v2, s0
	ds_write_b16 v141, v2 offset:1472
	v_sub_f32_e32 v2, v66, v34
	v_mul_f32_e32 v2, 0x3db504f3, v2
	v_mul_f32_e32 v2, 0x3fb8aa3b, v2
	v_exp_f32_e32 v2, v2
	s_nop 0
	v_add_f32_e32 v6, v2, v6
	v_cvt_pk_bf16_f32 v2, v2, s0
	ds_write_b16 v131, v2 offset:448
	v_sub_f32_e32 v2, v67, v35
	v_mul_f32_e32 v2, 0x3db504f3, v2
	v_mul_f32_e32 v2, 0x3fb8aa3b, v2
	v_exp_f32_e32 v2, v2
	s_nop 0
	v_add_f32_e32 v3, v2, v3
	v_cvt_pk_bf16_f32 v2, v2, s0
	ds_write_b16 v141, v2 offset:448
	v_sub_f32_e32 v2, v68, v36
	v_mul_f32_e32 v2, 0x3db504f3, v2
	v_mul_f32_e32 v2, 0x3fb8aa3b, v2
	v_exp_f32_e32 v2, v2
	s_nop 0
	v_add_f32_e32 v4, v2, v4
	v_cvt_pk_bf16_f32 v2, v2, s0
	ds_write_b16 v141, v2 offset:976
	v_sub_f32_e32 v2, v69, v37
	v_mul_f32_e32 v2, 0x3db504f3, v2
	v_mul_f32_e32 v2, 0x3fb8aa3b, v2
	v_exp_f32_e32 v2, v2
	s_nop 0
	v_add_f32_e32 v5, v2, v5
	v_cvt_pk_bf16_f32 v2, v2, s0
	ds_write_b16 v141, v2 offset:1504
	v_sub_f32_e32 v2, v26, v34
	v_mul_f32_e32 v2, 0x3db504f3, v2
	v_mul_f32_e32 v2, 0x3fb8aa3b, v2
	v_exp_f32_e32 v2, v2
	s_nop 0
	v_add_f32_e32 v6, v2, v6
	v_cvt_pk_bf16_f32 v2, v2, s0
	ds_write_b16 v131, v2 offset:480
	v_sub_f32_e32 v2, v27, v35
	v_mul_f32_e32 v2, 0x3db504f3, v2
	v_mul_f32_e32 v2, 0x3fb8aa3b, v2
	v_exp_f32_e32 v2, v2
	v_lshl_add_u64 v[34:35], v[144:145], 0, s[52:53]
	v_add_f32_e32 v3, v2, v3
	v_cvt_pk_bf16_f32 v2, v2, s0
	ds_write_b16 v141, v2 offset:480
	v_sub_f32_e32 v2, v28, v36
	v_mul_f32_e32 v2, 0x3db504f3, v2
	v_mul_f32_e32 v2, 0x3fb8aa3b, v2
	v_exp_f32_e32 v2, v2
	s_nop 0
	v_add_f32_e32 v4, v2, v4
	v_cvt_pk_bf16_f32 v2, v2, s0
	ds_write_b16 v141, v2 offset:1008
	v_sub_f32_e32 v2, v29, v37
	v_mul_f32_e32 v2, 0x3db504f3, v2
	v_mul_f32_e32 v2, 0x3fb8aa3b, v2
	v_exp_f32_e32 v2, v2
	v_lshl_add_u64 v[36:37], v[154:155], 1, v[142:143]
	v_lshl_add_u64 v[74:75], v[36:37], 0, v[38:39]
	v_lshlrev_b64 v[36:37], 11, v[70:71]
	v_add_f32_e32 v5, v2, v5
	v_cvt_pk_bf16_f32 v2, v2, s0
	ds_write_b16 v141, v2 offset:1536
	ds_bpermute_b32 v2, v30, v6
	s_waitcnt lgkmcnt(0)
	s_barrier
	v_lshl_add_u64 v[72:73], v[34:35], 0, v[36:37]
	v_add_f32_e32 v2, v6, v2
	ds_bpermute_b32 v6, v31, v2
	v_or_b32_e32 v36, v152, v146
	v_mov_b32_e32 v37, v153
	v_lshlrev_b64 v[36:37], 11, v[36:37]
	v_lshl_add_u64 v[76:77], v[34:35], 0, v[36:37]
	s_waitcnt lgkmcnt(0)
	v_add_f32_e32 v2, v2, v6
	ds_bpermute_b32 v6, v32, v2
	v_or_b32_e32 v36, v152, v148
	v_mov_b32_e32 v37, v153
	v_lshlrev_b64 v[36:37], 11, v[36:37]
	v_or_b32_e32 v152, v152, v150
	s_waitcnt lgkmcnt(0)
	v_add_f32_e32 v2, v2, v6
	ds_bpermute_b32 v6, v33, v2
	v_lshl_add_u64 v[78:79], v[34:35], 0, v[36:37]
	v_lshlrev_b64 v[36:37], 11, v[152:153]
	v_lshl_add_u64 v[80:81], v[34:35], 0, v[36:37]
	s_waitcnt lgkmcnt(0)
	v_add_f32_e32 v2, v2, v6
	v_div_scale_f32 v6, s[10:11], v2, v2, 1.0
	v_rcp_f32_e32 v7, v6
	s_nop 0
	v_fma_f32 v8, -v6, v7, 1.0
	v_fmac_f32_e32 v7, v8, v7
	v_div_scale_f32 v8, vcc, 1.0, v2, 1.0
	v_mul_f32_e32 v9, v8, v7
	v_fma_f32 v10, -v6, v9, v8
	v_fmac_f32_e32 v9, v10, v7
	v_fma_f32 v6, -v6, v9, v8
	v_div_fmas_f32 v6, v6, v7, v9
	v_div_fixup_f32 v84, v6, v2, 1.0
	ds_bpermute_b32 v2, v30, v3
	s_waitcnt lgkmcnt(0)
	v_add_f32_e32 v2, v3, v2
	ds_bpermute_b32 v3, v31, v2
	s_waitcnt lgkmcnt(0)
	v_add_f32_e32 v2, v2, v3
	ds_bpermute_b32 v3, v32, v2
	s_waitcnt lgkmcnt(0)
	v_add_f32_e32 v2, v2, v3
	ds_bpermute_b32 v3, v33, v2
	s_waitcnt lgkmcnt(0)
	v_add_f32_e32 v2, v2, v3
	v_div_scale_f32 v3, s[10:11], v2, v2, 1.0
	v_rcp_f32_e32 v6, v3
	s_nop 0
	v_fma_f32 v7, -v3, v6, 1.0
	v_fmac_f32_e32 v6, v7, v6
	v_div_scale_f32 v7, vcc, 1.0, v2, 1.0
	v_mul_f32_e32 v8, v7, v6
	v_fma_f32 v9, -v3, v8, v7
	v_fmac_f32_e32 v8, v9, v6
	v_fma_f32 v3, -v3, v8, v7
	v_div_fmas_f32 v3, v3, v6, v8
	v_div_fixup_f32 v85, v3, v2, 1.0
	ds_bpermute_b32 v2, v30, v4
	s_waitcnt lgkmcnt(0)
	v_add_f32_e32 v2, v4, v2
	ds_bpermute_b32 v3, v31, v2
	s_waitcnt lgkmcnt(0)
	v_add_f32_e32 v2, v2, v3
	ds_bpermute_b32 v3, v32, v2
	s_waitcnt lgkmcnt(0)
	v_add_f32_e32 v2, v2, v3
	ds_bpermute_b32 v3, v33, v2
	s_waitcnt lgkmcnt(0)
	v_add_f32_e32 v2, v2, v3
	v_div_scale_f32 v3, s[10:11], v2, v2, 1.0
	v_rcp_f32_e32 v4, v3
	s_nop 0
	v_fma_f32 v6, -v3, v4, 1.0
	v_fmac_f32_e32 v4, v6, v4
	v_div_scale_f32 v6, vcc, 1.0, v2, 1.0
	v_mul_f32_e32 v7, v6, v4
	v_fma_f32 v8, -v3, v7, v6
	v_fmac_f32_e32 v7, v8, v4
	v_fma_f32 v3, -v3, v7, v6
	v_div_fmas_f32 v3, v3, v4, v7
	v_div_fixup_f32 v86, v3, v2, 1.0
	ds_bpermute_b32 v2, v30, v5
	s_waitcnt lgkmcnt(0)
	v_add_f32_e32 v2, v5, v2
	ds_bpermute_b32 v3, v31, v2
	s_waitcnt lgkmcnt(0)
	v_add_f32_e32 v2, v2, v3
	ds_bpermute_b32 v3, v32, v2
	s_waitcnt lgkmcnt(0)
	v_add_f32_e32 v2, v2, v3
	ds_bpermute_b32 v3, v33, v2
	s_waitcnt lgkmcnt(0)
; __device__ __forceinline__ float bf2f(u16 h) { return __uint_as_float(((unsigned)h) << 16); }
; __device__ __forceinline__ u16 f2bf(float f) { return (u16)(pack2(f, 0.f) & 0xffffu); }
; __device__ __forceinline__ float siluf(float x) { return x * __builtin_amdgcn_rcpf(1.f + __expf(-x)); }
;     ...
;     for (int r = 0; r < 4; ++r) {
;       float v = sm[r];
; #pragma unroll
;       for (int o = 1; o < 16; o <<= 1) v += __shfl_xor(v, o, 64);
;       sm[r] = 1.f / v;
;     }
;     __syncthreads();
;     bf16x8 aP[8];
; #pragma unroll
;     for (int ks = 0; ks < 8; ++ks) aP[ks] = *(const bf16x8*)(Pw + fr * 264 + ks * 32 + fq * 8);
; #pragma unroll
;     for (int db = 0; db < 4; ++db) {
;       bf16x8 bv[2][8];
;       u16 gt[2][4];
; #pragma unroll
;       for (int d2 = 0; d2 < 2; ++d2) {
; #pragma unroll
;         for (int ks = 0; ks < 8; ++ks)
;           bv[d2][ks] = *(const bf16x8*)(VT + (long)(h * 128 + (db * 2 + d2) * 16 + fr) * 512 + b * 256 + ks * 32 + fq * 8);
; #pragma unroll
;         for (int r = 0; r < 4; ++r) gt[d2][r] = qg[(t0 + fq * 4 + r) * ldq + gcol + h * 128 + (db * 2 + d2) * 16 + fr];
;       }
;       asm volatile("" ::: "memory");
; #pragma unroll
;       for (int d2 = 0; d2 < 2; ++d2) {
;         f32x4 a = {0.f, 0.f, 0.f, 0.f};
; #pragma unroll
;         for (int ks = 0; ks < 8; ++ks) a = __builtin_amdgcn_mfma_f32_16x16x32_bf16(aP[ks], bv[d2][ks], a, 0, 0, 0);
; #pragma unroll
;         for (int r = 0; r < 4; ++r) {
;           long row = t0 + fq * 4 + r;
;           int dcol = h * 128 + (db * 2 + d2) * 16 + fr;
;           og[row * ldo + ocol + dcol] = f2bf(a[r] * sm[r] * siluf(bf2f(gt[d2][r])));
;         }
;       }
	v_add_f32_e32 v2, v2, v3
	v_div_scale_f32 v3, s[10:11], v2, v2, 1.0
	v_rcp_f32_e32 v4, v3
	s_nop 0
	v_fma_f32 v5, -v3, v4, 1.0
	v_fmac_f32_e32 v4, v5, v4
	v_div_scale_f32 v5, vcc, 1.0, v2, 1.0
	v_mul_f32_e32 v6, v5, v4
	v_fma_f32 v7, -v3, v6, v5
	v_fmac_f32_e32 v6, v7, v4
	v_fma_f32 v3, -v3, v6, v5
	v_div_fmas_f32 v3, v3, v4, v6
	v_div_fixup_f32 v87, v3, v2, 1.0
	ds_read_b128 v[2:5], v147
	ds_read_b128 v[6:9], v147 offset:64
	ds_read_b128 v[10:13], v147 offset:128
	ds_read_b128 v[14:17], v147 offset:192
	ds_read_b128 v[18:21], v147 offset:256
	ds_read_b128 v[22:25], v147 offset:320
	ds_read_b128 v[26:29], v147 offset:384
	ds_read_b128 v[30:33], v147 offset:448
	global_load_dwordx4 v[66:69], v[74:75], off
	global_load_dwordx4 v[88:91], v[74:75], off offset:64
	global_load_dwordx4 v[92:95], v[74:75], off offset:128
	global_load_dwordx4 v[96:99], v[74:75], off offset:192
	global_load_dwordx4 v[100:103], v[74:75], off offset:256
	global_load_dwordx4 v[104:107], v[74:75], off offset:320
	global_load_dwordx4 v[108:111], v[74:75], off offset:384
	global_load_dwordx4 v[112:115], v[74:75], off offset:448
	v_add_co_u32_e32 v62, vcc, s62, v74
	s_waitcnt vmcnt(0) lgkmcnt(0)
	v_mfma_f32_16x16x32_bf16 v[66:69], v[2:5], v[66:69], 0
	v_addc_co_u32_e32 v63, vcc, 0, v75, vcc
	global_load_dwordx4 v[34:37], v[62:63], off
	global_load_dwordx4 v[38:41], v[62:63], off offset:64
	global_load_dwordx4 v[42:45], v[62:63], off offset:128
	global_load_dwordx4 v[46:49], v[62:63], off offset:192
	global_load_dwordx4 v[50:53], v[62:63], off offset:256
	global_load_dwordx4 v[54:57], v[62:63], off offset:320
	global_load_dwordx4 v[58:61], v[62:63], off offset:384
	s_nop 0
	global_load_dwordx4 v[62:65], v[62:63], off offset:448
	s_nop 0
	global_load_ushort v71, v[72:73], off
	global_load_ushort v116, v[76:77], off
	global_load_ushort v117, v[78:79], off
	global_load_ushort v118, v[80:81], off
	global_load_ushort v119, v[72:73], off offset:32
	global_load_ushort v120, v[76:77], off offset:32
	global_load_ushort v121, v[78:79], off offset:32
	global_load_ushort v122, v[80:81], off offset:32
	v_mfma_f32_16x16x32_bf16 v[66:69], v[6:9], v[88:91], v[66:69]
	s_waitcnt vmcnt(0) lgkmcnt(0)
	v_lshlrev_b32_e32 v71, 16, v71
	v_mfma_f32_16x16x32_bf16 v[34:37], v[2:5], v[34:37], 0
	v_mul_f32_e32 v88, 0xbfb8aa3b, v71
	v_exp_f32_e32 v88, v88
	v_mfma_f32_16x16x32_bf16 v[66:69], v[10:13], v[92:95], v[66:69]
	v_add_f32_e32 v88, 1.0, v88
	v_rcp_f32_e32 v88, v88
	v_mfma_f32_16x16x32_bf16 v[34:37], v[6:9], v[38:41], v[34:37]
	v_lshlrev_b32_e32 v38, 16, v119
	v_mul_f32_e32 v39, 0xbfb8aa3b, v38
	v_exp_f32_e32 v39, v39
	v_mfma_f32_16x16x32_bf16 v[66:69], v[14:17], v[96:99], v[66:69]
	v_mul_f32_e32 v71, v88, v71
	v_add_f32_e32 v39, 1.0, v39
	v_mfma_f32_16x16x32_bf16 v[34:37], v[10:13], v[42:45], v[34:37]
	v_rcp_f32_e32 v39, v39
	s_nop 0
	v_mul_f32_e32 v38, v39, v38
	v_mfma_f32_16x16x32_bf16 v[66:69], v[18:21], v[100:103], v[66:69]
	v_mfma_f32_16x16x32_bf16 v[34:37], v[14:17], v[46:49], v[34:37]
	v_mfma_f32_16x16x32_bf16 v[66:69], v[22:25], v[104:107], v[66:69]
	v_mfma_f32_16x16x32_bf16 v[34:37], v[18:21], v[50:53], v[34:37]
	v_mfma_f32_16x16x32_bf16 v[66:69], v[26:29], v[108:111], v[66:69]
	v_mfma_f32_16x16x32_bf16 v[34:37], v[22:25], v[54:57], v[34:37]
	v_mfma_f32_16x16x32_bf16 v[66:69], v[30:33], v[112:115], v[66:69]
	v_mfma_f32_16x16x32_bf16 v[34:37], v[26:29], v[58:61], v[34:37]
	v_mfma_f32_16x16x32_bf16 v[34:37], v[30:33], v[62:65], v[34:37]
	s_nop 5
	v_mul_f32_e32 v66, v84, v66
	v_mul_f32_e32 v66, v71, v66
	v_mad_u64_u32 v[70:71], s[8:9], v70, s45, v[82:83]
	v_cvt_pk_bf16_f32 v66, v66, s0
	v_mad_i32_i24 v71, v153, s45, v71
	global_store_short v[70:71], v66, off
	v_mul_f32_e32 v66, v85, v67
	v_lshlrev_b32_e32 v67, 16, v116
	v_mul_f32_e32 v82, 0xbfb8aa3b, v67
	v_exp_f32_e32 v82, v82
	v_mul_f32_e32 v34, v84, v34
	v_mul_f32_e32 v34, v38, v34
	v_cvt_pk_bf16_f32 v34, v34, s0
	v_add_f32_e32 v82, 1.0, v82
	global_store_short v[70:71], v34, off offset:32
	v_mul_f32_e32 v34, v85, v35
	v_lshlrev_b32_e32 v35, 16, v120
	v_rcp_f32_e32 v82, v82
	v_mul_f32_e32 v38, 0xbfb8aa3b, v35
	v_exp_f32_e32 v38, v38
	v_mul_f32_e32 v68, v86, v68
	v_mul_f32_e32 v67, v82, v67
	v_mul_f32_e32 v66, v67, v66
	v_add_f32_e32 v38, 1.0, v38
	v_cvt_pk_bf16_f32 v82, v66, s0
	v_add_co_u32_e32 v66, vcc, s62, v70
	v_rcp_f32_e32 v38, v38
	s_nop 0
	v_addc_co_u32_e32 v67, vcc, 0, v71, vcc
	global_store_short v[66:67], v82, off offset:1024
	v_lshlrev_b32_e32 v82, 16, v117
	v_mul_f32_e32 v83, 0xbfb8aa3b, v82
	v_exp_f32_e32 v83, v83
	v_mul_f32_e32 v35, v38, v35
	v_mul_f32_e32 v34, v35, v34
	v_cvt_pk_bf16_f32 v34, v34, s0
	v_lshlrev_b32_e32 v35, 16, v121
	global_store_short v[66:67], v34, off offset:1056
	v_mul_f32_e32 v34, v86, v36
	v_mul_f32_e32 v36, 0xbfb8aa3b, v35
	v_add_f32_e32 v83, 1.0, v83
	v_exp_f32_e32 v36, v36
	v_rcp_f32_e32 v83, v83
	v_add_f32_e32 v36, 1.0, v36
	v_mul_f32_e32 v82, v83, v82
	v_rcp_f32_e32 v36, v36
	v_mul_f32_e32 v68, v82, v68
	v_add_co_u32_e32 v82, vcc, s12, v70
	v_cvt_pk_bf16_f32 v68, v68, s0
	s_nop 0
	v_addc_co_u32_e32 v83, vcc, 0, v71, vcc
	global_store_short v[82:83], v68, off offset:2048
	v_mul_f32_e32 v68, v87, v69
	v_lshlrev_b32_e32 v69, 16, v118
	v_mul_f32_e32 v88, 0xbfb8aa3b, v69
	v_mul_f32_e32 v35, v36, v35
	v_exp_f32_e32 v88, v88
	v_mul_f32_e32 v34, v35, v34
	v_lshlrev_b32_e32 v35, 16, v122
	v_mul_f32_e32 v36, 0xbfb8aa3b, v35
	v_exp_f32_e32 v36, v36
	v_add_f32_e32 v88, 1.0, v88
	v_rcp_f32_e32 v88, v88
	v_cvt_pk_bf16_f32 v34, v34, s0
	v_add_f32_e32 v36, 1.0, v36
	v_rcp_f32_e32 v36, v36
	v_mul_f32_e32 v69, v88, v69
	v_mul_f32_e32 v68, v69, v68
	v_cvt_pk_bf16_f32 v88, v68, s0
	v_add_co_u32_e32 v68, vcc, s13, v70
	global_store_short v[82:83], v34, off offset:2080
	v_mul_f32_e32 v34, v87, v37
	v_mul_f32_e32 v35, v36, v35
	v_addc_co_u32_e32 v69, vcc, 0, v71, vcc
	v_mul_f32_e32 v34, v35, v34
	v_cvt_pk_bf16_f32 v34, v34, s0
	v_add_co_u32_e32 v62, vcc, s12, v74
	global_store_short v[68:69], v88, off offset:3072
	global_store_short v[68:69], v34, off offset:3104
	v_addc_co_u32_e32 v63, vcc, 0, v75, vcc
	global_load_dwordx4 v[34:37], v[62:63], off
	global_load_dwordx4 v[38:41], v[62:63], off offset:64
	global_load_dwordx4 v[42:45], v[62:63], off offset:128
	global_load_dwordx4 v[46:49], v[62:63], off offset:192
	global_load_dwordx4 v[50:53], v[62:63], off offset:256
	global_load_dwordx4 v[54:57], v[62:63], off offset:320
	global_load_dwordx4 v[58:61], v[62:63], off offset:384
	s_nop 0
	global_load_dwordx4 v[62:65], v[62:63], off offset:448
	v_add_co_u32_e32 v116, vcc, s13, v74
	s_waitcnt vmcnt(0) lgkmcnt(0)
; __device__ __forceinline__ float bf2f(u16 h) { return __uint_as_float(((unsigned)h) << 16); }
; __device__ __forceinline__ u16 f2bf(float f) { return (u16)(pack2(f, 0.f) & 0xffffu); }
; __device__ __forceinline__ float siluf(float x) { return x * __builtin_amdgcn_rcpf(1.f + __expf(-x)); }
;     ...
; #pragma unroll
;     for (int db = 0; db < 4; ++db) {
;       bf16x8 bv[2][8];
;       u16 gt[2][4];
; #pragma unroll
;       for (int d2 = 0; d2 < 2; ++d2) {
; #pragma unroll
;         for (int ks = 0; ks < 8; ++ks)
;           bv[d2][ks] = *(const bf16x8*)(VT + (long)(h * 128 + (db * 2 + d2) * 16 + fr) * 512 + b * 256 + ks * 32 + fq * 8);
; #pragma unroll
;         for (int r = 0; r < 4; ++r) gt[d2][r] = qg[(t0 + fq * 4 + r) * ldq + gcol + h * 128 + (db * 2 + d2) * 16 + fr];
;       }
;       asm volatile("" ::: "memory");
; #pragma unroll
;       for (int d2 = 0; d2 < 2; ++d2) {
;         f32x4 a = {0.f, 0.f, 0.f, 0.f};
; #pragma unroll
;         for (int ks = 0; ks < 8; ++ks) a = __builtin_amdgcn_mfma_f32_16x16x32_bf16(aP[ks], bv[d2][ks], a, 0, 0, 0);
; #pragma unroll
;         for (int r = 0; r < 4; ++r) {
;           long row = t0 + fq * 4 + r;
;           int dcol = h * 128 + (db * 2 + d2) * 16 + fr;
;           og[row * ldo + ocol + dcol] = f2bf(a[r] * sm[r] * siluf(bf2f(gt[d2][r])));
;         }
;       }
	v_mfma_f32_16x16x32_bf16 v[34:37], v[2:5], v[34:37], 0
	v_addc_co_u32_e32 v117, vcc, 0, v75, vcc
	global_load_dwordx4 v[88:91], v[116:117], off
	global_load_dwordx4 v[92:95], v[116:117], off offset:64
	global_load_dwordx4 v[96:99], v[116:117], off offset:128
	global_load_dwordx4 v[100:103], v[116:117], off offset:192
	global_load_dwordx4 v[104:107], v[116:117], off offset:256
	global_load_dwordx4 v[108:111], v[116:117], off offset:320
	global_load_dwordx4 v[112:115], v[116:117], off offset:384
	s_nop 0
	global_load_dwordx4 v[116:119], v[116:117], off offset:448
	s_nop 0
	global_load_ushort v120, v[72:73], off offset:64
	global_load_ushort v121, v[76:77], off offset:64
	global_load_ushort v122, v[78:79], off offset:64
	global_load_ushort v123, v[80:81], off offset:64
	global_load_ushort v124, v[72:73], off offset:96
	global_load_ushort v125, v[76:77], off offset:96
	global_load_ushort v126, v[78:79], off offset:96
	global_load_ushort v127, v[80:81], off offset:96
	v_mfma_f32_16x16x32_bf16 v[34:37], v[6:9], v[38:41], v[34:37]
	s_waitcnt vmcnt(0) lgkmcnt(0)
	v_lshlrev_b32_e32 v38, 16, v120
	v_mfma_f32_16x16x32_bf16 v[34:37], v[10:13], v[42:45], v[34:37]
	v_mul_f32_e32 v39, 0xbfb8aa3b, v38
	v_exp_f32_e32 v39, v39
	v_mfma_f32_16x16x32_bf16 v[34:37], v[14:17], v[46:49], v[34:37]
	v_add_f32_e32 v39, 1.0, v39
	v_rcp_f32_e32 v39, v39
	v_mfma_f32_16x16x32_bf16 v[34:37], v[18:21], v[50:53], v[34:37]
	v_mul_f32_e32 v38, v39, v38
	v_mfma_f32_16x16x32_bf16 v[34:37], v[22:25], v[54:57], v[34:37]
	v_mfma_f32_16x16x32_bf16 v[34:37], v[26:29], v[58:61], v[34:37]
	v_mfma_f32_16x16x32_bf16 v[34:37], v[30:33], v[62:65], v[34:37]
	v_add_co_u32_e32 v62, vcc, s14, v74
	s_nop 1
	v_addc_co_u32_e32 v63, vcc, 0, v75, vcc
	s_nop 3
	v_mul_f32_e32 v34, v84, v34
	v_mul_f32_e32 v34, v38, v34
	v_cvt_pk_bf16_f32 v34, v34, s0
	global_store_short v[70:71], v34, off offset:64
	v_mul_f32_e32 v34, v85, v35
	v_lshlrev_b32_e32 v35, 16, v121
	v_mul_f32_e32 v38, 0xbfb8aa3b, v35
	v_exp_f32_e32 v38, v38
	s_nop 0
	v_add_f32_e32 v38, 1.0, v38
	v_rcp_f32_e32 v38, v38
	s_nop 0
	v_mul_f32_e32 v35, v38, v35
	v_mul_f32_e32 v34, v35, v34
	v_cvt_pk_bf16_f32 v34, v34, s0
	v_lshlrev_b32_e32 v35, 16, v122
	global_store_short v[66:67], v34, off offset:1088
	v_mul_f32_e32 v34, v86, v36
	v_mul_f32_e32 v36, 0xbfb8aa3b, v35
	v_exp_f32_e32 v36, v36
	v_lshlrev_b32_e32 v38, 16, v124
	v_mul_f32_e32 v39, 0xbfb8aa3b, v38
	v_exp_f32_e32 v39, v39
	v_add_f32_e32 v36, 1.0, v36
	v_rcp_f32_e32 v36, v36
	v_add_f32_e32 v39, 1.0, v39
	v_rcp_f32_e32 v39, v39
	v_mul_f32_e32 v35, v36, v35
	v_mul_f32_e32 v34, v35, v34
	v_lshlrev_b32_e32 v35, 16, v123
	v_mul_f32_e32 v36, 0xbfb8aa3b, v35
	v_exp_f32_e32 v36, v36
	v_cvt_pk_bf16_f32 v34, v34, s0
	global_store_short v[82:83], v34, off offset:2112
	v_mul_f32_e32 v34, v87, v37
	v_add_f32_e32 v36, 1.0, v36
	v_rcp_f32_e32 v36, v36
	v_mul_f32_e32 v38, v39, v38
	v_mul_f32_e32 v35, v36, v35
	v_mul_f32_e32 v34, v35, v34
	v_cvt_pk_bf16_f32 v34, v34, s0
	global_store_short v[68:69], v34, off offset:3136
	v_mfma_f32_16x16x32_bf16 v[34:37], v[2:5], v[88:91], 0
	v_mfma_f32_16x16x32_bf16 v[34:37], v[6:9], v[92:95], v[34:37]
	v_mfma_f32_16x16x32_bf16 v[34:37], v[10:13], v[96:99], v[34:37]
	v_mfma_f32_16x16x32_bf16 v[34:37], v[14:17], v[100:103], v[34:37]
	v_mfma_f32_16x16x32_bf16 v[34:37], v[18:21], v[104:107], v[34:37]
	v_mfma_f32_16x16x32_bf16 v[34:37], v[22:25], v[108:111], v[34:37]
	v_mfma_f32_16x16x32_bf16 v[34:37], v[26:29], v[112:115], v[34:37]
	v_mfma_f32_16x16x32_bf16 v[34:37], v[30:33], v[116:119], v[34:37]
	v_add_co_u32_e32 v116, vcc, s41, v74
	s_nop 1
	v_addc_co_u32_e32 v117, vcc, 0, v75, vcc
	s_nop 3
	v_mul_f32_e32 v34, v84, v34
	v_mul_f32_e32 v34, v38, v34
	v_cvt_pk_bf16_f32 v34, v34, s0
	global_store_short v[70:71], v34, off offset:96
	v_mul_f32_e32 v34, v85, v35
	v_lshlrev_b32_e32 v35, 16, v125
	v_mul_f32_e32 v38, 0xbfb8aa3b, v35
	v_exp_f32_e32 v38, v38
	s_nop 0
	v_add_f32_e32 v38, 1.0, v38
	v_rcp_f32_e32 v38, v38
	s_nop 0
	v_mul_f32_e32 v35, v38, v35
	v_mul_f32_e32 v34, v35, v34
	v_cvt_pk_bf16_f32 v34, v34, s0
	v_lshlrev_b32_e32 v35, 16, v126
	global_store_short v[66:67], v34, off offset:1120
	v_mul_f32_e32 v34, v86, v36
	v_mul_f32_e32 v36, 0xbfb8aa3b, v35
	v_exp_f32_e32 v36, v36
	s_nop 0
	v_add_f32_e32 v36, 1.0, v36
	v_rcp_f32_e32 v36, v36
	s_nop 0
	v_mul_f32_e32 v35, v36, v35
	v_mul_f32_e32 v34, v35, v34
	v_lshlrev_b32_e32 v35, 16, v127
	v_mul_f32_e32 v36, 0xbfb8aa3b, v35
	v_exp_f32_e32 v36, v36
	v_cvt_pk_bf16_f32 v34, v34, s0
	global_store_short v[82:83], v34, off offset:2144
	v_mul_f32_e32 v34, v87, v37
	v_add_f32_e32 v36, 1.0, v36
	v_rcp_f32_e32 v36, v36
	s_nop 0
	v_mul_f32_e32 v35, v36, v35
	v_mul_f32_e32 v34, v35, v34
	v_cvt_pk_bf16_f32 v34, v34, s0
	global_store_short v[68:69], v34, off offset:3168
	global_load_dwordx4 v[34:37], v[62:63], off
	s_nop 0
	global_load_dwordx4 v[38:41], v[62:63], off offset:64
	global_load_dwordx4 v[42:45], v[62:63], off offset:128
	global_load_dwordx4 v[46:49], v[62:63], off offset:192
	global_load_dwordx4 v[50:53], v[62:63], off offset:256
	global_load_dwordx4 v[54:57], v[62:63], off offset:320
	global_load_dwordx4 v[58:61], v[62:63], off offset:384
	s_nop 0
	global_load_dwordx4 v[62:65], v[62:63], off offset:448
	s_nop 0
	global_load_dwordx4 v[88:91], v[116:117], off
	global_load_dwordx4 v[92:95], v[116:117], off offset:64
	global_load_dwordx4 v[96:99], v[116:117], off offset:128
	global_load_dwordx4 v[100:103], v[116:117], off offset:192
	global_load_dwordx4 v[104:107], v[116:117], off offset:256
	global_load_dwordx4 v[108:111], v[116:117], off offset:320
	global_load_dwordx4 v[112:115], v[116:117], off offset:384
	s_nop 0
	global_load_dwordx4 v[116:119], v[116:117], off offset:448
	s_nop 0
	global_load_ushort v120, v[72:73], off offset:128
	global_load_ushort v121, v[76:77], off offset:128
	global_load_ushort v122, v[78:79], off offset:128
	global_load_ushort v123, v[80:81], off offset:128
	global_load_ushort v124, v[72:73], off offset:160
	global_load_ushort v125, v[76:77], off offset:160
	global_load_ushort v126, v[78:79], off offset:160
	global_load_ushort v127, v[80:81], off offset:160
	s_waitcnt vmcnt(0) lgkmcnt(0)
; __device__ __forceinline__ float bf2f(u16 h) { return __uint_as_float(((unsigned)h) << 16); }
; __device__ __forceinline__ u16 f2bf(float f) { return (u16)(pack2(f, 0.f) & 0xffffu); }
; __device__ __forceinline__ float siluf(float x) { return x * __builtin_amdgcn_rcpf(1.f + __expf(-x)); }
;     ...
; #pragma unroll
;     for (int db = 0; db < 4; ++db) {
;       bf16x8 bv[2][8];
;       u16 gt[2][4];
; #pragma unroll
;       for (int d2 = 0; d2 < 2; ++d2) {
; #pragma unroll
;         for (int ks = 0; ks < 8; ++ks)
;           bv[d2][ks] = *(const bf16x8*)(VT + (long)(h * 128 + (db * 2 + d2) * 16 + fr) * 512 + b * 256 + ks * 32 + fq * 8);
; #pragma unroll
;         for (int r = 0; r < 4; ++r) gt[d2][r] = qg[(t0 + fq * 4 + r) * ldq + gcol + h * 128 + (db * 2 + d2) * 16 + fr];
;       }
;       asm volatile("" ::: "memory");
; #pragma unroll
;       for (int d2 = 0; d2 < 2; ++d2) {
;         f32x4 a = {0.f, 0.f, 0.f, 0.f};
; #pragma unroll
;         for (int ks = 0; ks < 8; ++ks) a = __builtin_amdgcn_mfma_f32_16x16x32_bf16(aP[ks], bv[d2][ks], a, 0, 0, 0);
; #pragma unroll
;         for (int r = 0; r < 4; ++r) {
;           long row = t0 + fq * 4 + r;
;           int dcol = h * 128 + (db * 2 + d2) * 16 + fr;
;           og[row * ldo + ocol + dcol] = f2bf(a[r] * sm[r] * siluf(bf2f(gt[d2][r])));
;         }
;       }
	v_mfma_f32_16x16x32_bf16 v[34:37], v[2:5], v[34:37], 0
	v_mfma_f32_16x16x32_bf16 v[34:37], v[6:9], v[38:41], v[34:37]
	v_lshlrev_b32_e32 v38, 16, v120
	v_mul_f32_e32 v39, 0xbfb8aa3b, v38
	v_exp_f32_e32 v39, v39
	v_mfma_f32_16x16x32_bf16 v[34:37], v[10:13], v[42:45], v[34:37]
	v_add_f32_e32 v39, 1.0, v39
	v_mfma_f32_16x16x32_bf16 v[34:37], v[14:17], v[46:49], v[34:37]
	v_rcp_f32_e32 v39, v39
	s_nop 0
	v_mul_f32_e32 v38, v39, v38
	v_mfma_f32_16x16x32_bf16 v[34:37], v[18:21], v[50:53], v[34:37]
	v_mfma_f32_16x16x32_bf16 v[34:37], v[22:25], v[54:57], v[34:37]
	v_mfma_f32_16x16x32_bf16 v[34:37], v[26:29], v[58:61], v[34:37]
	v_mfma_f32_16x16x32_bf16 v[34:37], v[30:33], v[62:65], v[34:37]
	v_add_co_u32_e32 v62, vcc, s87, v74
	s_nop 1
	v_addc_co_u32_e32 v63, vcc, 0, v75, vcc
	v_add_co_u32_e32 v74, vcc, s42, v74
	s_nop 2
	v_mul_f32_e32 v34, v84, v34
	v_mul_f32_e32 v34, v38, v34
	v_cvt_pk_bf16_f32 v34, v34, s0
	global_store_short v[70:71], v34, off offset:128
	v_mul_f32_e32 v34, v85, v35
	v_lshlrev_b32_e32 v35, 16, v121
	v_mul_f32_e32 v38, 0xbfb8aa3b, v35
	v_exp_f32_e32 v38, v38
	v_addc_co_u32_e32 v75, vcc, 0, v75, vcc
	v_add_f32_e32 v38, 1.0, v38
	v_rcp_f32_e32 v38, v38
	s_nop 0
	v_mul_f32_e32 v35, v38, v35
	v_mul_f32_e32 v34, v35, v34
	v_cvt_pk_bf16_f32 v34, v34, s0
	v_lshlrev_b32_e32 v35, 16, v122
	global_store_short v[66:67], v34, off offset:1152
	v_mul_f32_e32 v34, v86, v36
	v_mul_f32_e32 v36, 0xbfb8aa3b, v35
	v_exp_f32_e32 v36, v36
	v_lshlrev_b32_e32 v38, 16, v124
	v_mul_f32_e32 v39, 0xbfb8aa3b, v38
	v_exp_f32_e32 v39, v39
	v_add_f32_e32 v36, 1.0, v36
	v_rcp_f32_e32 v36, v36
	v_add_f32_e32 v39, 1.0, v39
	v_rcp_f32_e32 v39, v39
	v_mul_f32_e32 v35, v36, v35
	v_mul_f32_e32 v34, v35, v34
	v_lshlrev_b32_e32 v35, 16, v123
	v_mul_f32_e32 v36, 0xbfb8aa3b, v35
	v_exp_f32_e32 v36, v36
	v_cvt_pk_bf16_f32 v34, v34, s0
	global_store_short v[82:83], v34, off offset:2176
	v_mul_f32_e32 v34, v87, v37
	v_add_f32_e32 v36, 1.0, v36
	v_rcp_f32_e32 v36, v36
	v_mul_f32_e32 v38, v39, v38
	v_mul_f32_e32 v35, v36, v35
	v_mul_f32_e32 v34, v35, v34
	v_cvt_pk_bf16_f32 v34, v34, s0
	global_store_short v[68:69], v34, off offset:3200
	v_mfma_f32_16x16x32_bf16 v[34:37], v[2:5], v[88:91], 0
	v_mfma_f32_16x16x32_bf16 v[34:37], v[6:9], v[92:95], v[34:37]
	v_mfma_f32_16x16x32_bf16 v[34:37], v[10:13], v[96:99], v[34:37]
	v_mfma_f32_16x16x32_bf16 v[34:37], v[14:17], v[100:103], v[34:37]
	v_mfma_f32_16x16x32_bf16 v[34:37], v[18:21], v[104:107], v[34:37]
	v_mfma_f32_16x16x32_bf16 v[34:37], v[22:25], v[108:111], v[34:37]
	v_mfma_f32_16x16x32_bf16 v[34:37], v[26:29], v[112:115], v[34:37]
	v_mfma_f32_16x16x32_bf16 v[34:37], v[30:33], v[116:119], v[34:37]
	s_nop 7
	v_mul_f32_e32 v34, v84, v34
	v_mul_f32_e32 v34, v38, v34
	v_cvt_pk_bf16_f32 v34, v34, s0
	global_store_short v[70:71], v34, off offset:160
	v_mul_f32_e32 v34, v85, v35
	v_lshlrev_b32_e32 v35, 16, v125
	v_mul_f32_e32 v38, 0xbfb8aa3b, v35
	v_exp_f32_e32 v38, v38
	s_nop 0
	v_add_f32_e32 v38, 1.0, v38
	v_rcp_f32_e32 v38, v38
	s_nop 0
	v_mul_f32_e32 v35, v38, v35
	v_mul_f32_e32 v34, v35, v34
	v_cvt_pk_bf16_f32 v34, v34, s0
	v_lshlrev_b32_e32 v35, 16, v126
	global_store_short v[66:67], v34, off offset:1184
	v_mul_f32_e32 v34, v86, v36
	v_mul_f32_e32 v36, 0xbfb8aa3b, v35
	v_exp_f32_e32 v36, v36
	s_nop 0
	v_add_f32_e32 v36, 1.0, v36
	v_rcp_f32_e32 v36, v36
	s_nop 0
	v_mul_f32_e32 v35, v36, v35
	v_mul_f32_e32 v34, v35, v34
	v_lshlrev_b32_e32 v35, 16, v127
	v_mul_f32_e32 v36, 0xbfb8aa3b, v35
	v_exp_f32_e32 v36, v36
	v_cvt_pk_bf16_f32 v34, v34, s0
	global_store_short v[82:83], v34, off offset:2208
	v_mul_f32_e32 v34, v87, v37
	v_add_f32_e32 v36, 1.0, v36
	v_rcp_f32_e32 v36, v36
	s_nop 0
	v_mul_f32_e32 v35, v36, v35
	v_mul_f32_e32 v34, v35, v34
	v_cvt_pk_bf16_f32 v34, v34, s0
	global_store_short v[68:69], v34, off offset:3232
	global_load_dwordx4 v[34:37], v[62:63], off
	s_nop 0
	global_load_dwordx4 v[38:41], v[62:63], off offset:64
	global_load_dwordx4 v[42:45], v[62:63], off offset:128
	global_load_dwordx4 v[46:49], v[62:63], off offset:192
	global_load_dwordx4 v[50:53], v[62:63], off offset:256
	global_load_dwordx4 v[54:57], v[62:63], off offset:320
	global_load_dwordx4 v[58:61], v[62:63], off offset:384
	s_nop 0
	global_load_dwordx4 v[62:65], v[62:63], off offset:448
	s_nop 0
	global_load_dwordx4 v[88:91], v[74:75], off
	global_load_dwordx4 v[92:95], v[74:75], off offset:64
	global_load_dwordx4 v[96:99], v[74:75], off offset:128
	global_load_dwordx4 v[100:103], v[74:75], off offset:192
	global_load_dwordx4 v[104:107], v[74:75], off offset:256
	global_load_dwordx4 v[108:111], v[74:75], off offset:320
	global_load_dwordx4 v[112:115], v[74:75], off offset:384
	global_load_dwordx4 v[116:119], v[74:75], off offset:448
	s_nop 0
	global_load_ushort v74, v[72:73], off offset:192
	global_load_ushort v75, v[76:77], off offset:192
	global_load_ushort v120, v[78:79], off offset:192
	global_load_ushort v121, v[80:81], off offset:192
	s_nop 0
	global_load_ushort v72, v[72:73], off offset:224
	s_nop 0
	global_load_ushort v73, v[76:77], off offset:224
	s_nop 0
	global_load_ushort v76, v[78:79], off offset:224
	global_load_ushort v77, v[80:81], off offset:224
	s_waitcnt vmcnt(0) lgkmcnt(0)
; __device__ __forceinline__ float bf2f(u16 h) { return __uint_as_float(((unsigned)h) << 16); }
; __device__ __forceinline__ u16 f2bf(float f) { return (u16)(pack2(f, 0.f) & 0xffffu); }
; __device__ __forceinline__ float siluf(float x) { return x * __builtin_amdgcn_rcpf(1.f + __expf(-x)); }
;     ...
; #pragma unroll
;     for (int db = 0; db < 4; ++db) {
;       bf16x8 bv[2][8];
;       u16 gt[2][4];
; #pragma unroll
;       for (int d2 = 0; d2 < 2; ++d2) {
; #pragma unroll
;         for (int ks = 0; ks < 8; ++ks)
;           bv[d2][ks] = *(const bf16x8*)(VT + (long)(h * 128 + (db * 2 + d2) * 16 + fr) * 512 + b * 256 + ks * 32 + fq * 8);
; #pragma unroll
;         for (int r = 0; r < 4; ++r) gt[d2][r] = qg[(t0 + fq * 4 + r) * ldq + gcol + h * 128 + (db * 2 + d2) * 16 + fr];
;       }
;       asm volatile("" ::: "memory");
; #pragma unroll
;       for (int d2 = 0; d2 < 2; ++d2) {
;         f32x4 a = {0.f, 0.f, 0.f, 0.f};
; #pragma unroll
;         for (int ks = 0; ks < 8; ++ks) a = __builtin_amdgcn_mfma_f32_16x16x32_bf16(aP[ks], bv[d2][ks], a, 0, 0, 0);
; #pragma unroll
;         for (int r = 0; r < 4; ++r) {
;           long row = t0 + fq * 4 + r;
;           int dcol = h * 128 + (db * 2 + d2) * 16 + fr;
;           og[row * ldo + ocol + dcol] = f2bf(a[r] * sm[r] * siluf(bf2f(gt[d2][r])));
;         }
;       }
	v_mfma_f32_16x16x32_bf16 v[34:37], v[2:5], v[34:37], 0
	v_mfma_f32_16x16x32_bf16 v[2:5], v[2:5], v[88:91], 0
	v_mfma_f32_16x16x32_bf16 v[34:37], v[6:9], v[38:41], v[34:37]
	v_lshlrev_b32_e32 v38, 16, v74
	v_mul_f32_e32 v39, 0xbfb8aa3b, v38
	v_exp_f32_e32 v39, v39
	v_mfma_f32_16x16x32_bf16 v[2:5], v[6:9], v[92:95], v[2:5]
	v_lshlrev_b32_e32 v6, 16, v72
	v_mul_f32_e32 v7, 0xbfb8aa3b, v6
	v_exp_f32_e32 v7, v7
	v_mfma_f32_16x16x32_bf16 v[34:37], v[10:13], v[42:45], v[34:37]
	v_add_f32_e32 v39, 1.0, v39
	v_rcp_f32_e32 v39, v39
	v_add_f32_e32 v7, 1.0, v7
	v_mfma_f32_16x16x32_bf16 v[2:5], v[10:13], v[96:99], v[2:5]
	v_rcp_f32_e32 v7, v7
	v_mul_f32_e32 v38, v39, v38
	v_mul_f32_e32 v6, v7, v6
	v_mfma_f32_16x16x32_bf16 v[34:37], v[14:17], v[46:49], v[34:37]
	v_mfma_f32_16x16x32_bf16 v[2:5], v[14:17], v[100:103], v[2:5]
	v_mfma_f32_16x16x32_bf16 v[34:37], v[18:21], v[50:53], v[34:37]
	v_mfma_f32_16x16x32_bf16 v[2:5], v[18:21], v[104:107], v[2:5]
	v_mfma_f32_16x16x32_bf16 v[34:37], v[22:25], v[54:57], v[34:37]
	v_mfma_f32_16x16x32_bf16 v[2:5], v[22:25], v[108:111], v[2:5]
	v_mfma_f32_16x16x32_bf16 v[34:37], v[26:29], v[58:61], v[34:37]
	v_mfma_f32_16x16x32_bf16 v[2:5], v[26:29], v[112:115], v[2:5]
	v_mfma_f32_16x16x32_bf16 v[34:37], v[30:33], v[62:65], v[34:37]
	v_mfma_f32_16x16x32_bf16 v[2:5], v[30:33], v[116:119], v[2:5]
	s_nop 6
	v_mul_f32_e32 v34, v84, v34
	v_mul_f32_e32 v2, v84, v2
	v_mul_f32_e32 v34, v38, v34
	v_mul_f32_e32 v2, v6, v2
	v_cvt_pk_bf16_f32 v34, v34, s0
	v_cvt_pk_bf16_f32 v2, v2, s0
	global_store_short v[70:71], v34, off offset:192
	v_mul_f32_e32 v34, v85, v35
	v_lshlrev_b32_e32 v35, 16, v75
	global_store_short v[70:71], v2, off offset:224
	v_mul_f32_e32 v2, v85, v3
	v_lshlrev_b32_e32 v3, 16, v73
	v_mul_f32_e32 v38, 0xbfb8aa3b, v35
	v_mul_f32_e32 v6, 0xbfb8aa3b, v3
	v_exp_f32_e32 v38, v38
	v_exp_f32_e32 v6, v6
	v_add_f32_e32 v38, 1.0, v38
	v_add_f32_e32 v6, 1.0, v6
	v_rcp_f32_e32 v38, v38
	v_rcp_f32_e32 v6, v6
	v_mul_f32_e32 v35, v38, v35
	v_mul_f32_e32 v3, v6, v3
	v_mul_f32_e32 v34, v35, v34
	v_mul_f32_e32 v2, v3, v2
	v_cvt_pk_bf16_f32 v34, v34, s0
	v_lshlrev_b32_e32 v35, 16, v120
	v_cvt_pk_bf16_f32 v2, v2, s0
	v_lshlrev_b32_e32 v3, 16, v76
	global_store_short v[66:67], v34, off offset:1216
	v_mul_f32_e32 v34, v86, v36
	v_mul_f32_e32 v36, 0xbfb8aa3b, v35
	global_store_short v[66:67], v2, off offset:1248
	v_mul_f32_e32 v2, v86, v4
	v_mul_f32_e32 v4, 0xbfb8aa3b, v3
	v_exp_f32_e32 v36, v36
	v_exp_f32_e32 v4, v4
	v_add_f32_e32 v36, 1.0, v36
	v_add_f32_e32 v4, 1.0, v4
	v_rcp_f32_e32 v36, v36
	v_rcp_f32_e32 v4, v4
	v_mul_f32_e32 v35, v36, v35
	v_mul_f32_e32 v3, v4, v3
	v_mul_f32_e32 v34, v35, v34
	v_lshlrev_b32_e32 v35, 16, v121
	v_mul_f32_e32 v2, v3, v2
	v_lshlrev_b32_e32 v3, 16, v77
	v_mul_f32_e32 v36, 0xbfb8aa3b, v35
	v_mul_f32_e32 v4, 0xbfb8aa3b, v3
	v_exp_f32_e32 v36, v36
	v_exp_f32_e32 v4, v4
	v_cvt_pk_bf16_f32 v34, v34, s0
	v_cvt_pk_bf16_f32 v2, v2, s0
	v_add_f32_e32 v36, 1.0, v36
	v_add_f32_e32 v4, 1.0, v4
	v_rcp_f32_e32 v36, v36
	v_rcp_f32_e32 v4, v4
	global_store_short v[82:83], v34, off offset:2240
	v_mul_f32_e32 v34, v87, v37
	v_mul_f32_e32 v35, v36, v35
	global_store_short v[82:83], v2, off offset:2272
	v_mul_f32_e32 v2, v87, v5
	v_mul_f32_e32 v3, v4, v3
	v_mul_f32_e32 v34, v35, v34
	v_mul_f32_e32 v2, v3, v2
	v_cvt_pk_bf16_f32 v34, v34, s0
	v_cvt_pk_bf16_f32 v2, v2, s0
	global_store_short v[68:69], v34, off offset:3264
	global_store_short v[68:69], v2, off offset:3296
	s_cbranch_scc0 .LBB0_133

; __device__ __forceinline__ int ltid() { int t = threadIdx.x; asm volatile("" : "+v"(t)); return t; }
; __device__ __forceinline__ void emit_rm(const float* stage, u16* dst, long ld, const float* rs) {
;   const int tid = ltid(), c4 = (tid & 31) * 4, rr = tid >> 5;
; #pragma unroll 1
;   for (int ps = 0; ps < 8; ++ps) {
;     const int r = ps * 16 + rr;
;     const float* s = stage + r * SP + c4;
;     const float4 a = *(const float4*)s, b = *(const float4*)(s + 128);
;     const float f = rs ? rs[r] : 1.f;
;     uint2 o0, o1;
;     o0.x = pack2(a.x * f, a.y * f); o0.y = pack2(a.z * f, a.w * f);
;     o1.x = pack2(b.x * f, b.y * f); o1.y = pack2(b.z * f, b.w * f);
;     *(uint2*)(dst + (long)r * ld + c4) = o0;
;     *(uint2*)(dst + (long)r * ld + 128 + c4) = o1;
;   }
; }
; template <int KIND>
; __device__ __forceinline__ void tile_emit(const Ctx& p, int t, int hd, int s, int half, const float* stage) {
;     ...
;     } else if (col0 < 16384) {
;       emit_rm(stage, (u16*)(ws + OFF_CAT1) + ((long)pm * 256 + hr) * 8704 + (col0 - 8192), 8704, nullptr);
;     } else {
;       emit_rm(stage, (u16*)(ws + OFF_MQG) + ((long)pm * 256 + hr) * 1024 + (col0 - 16384), 1024, nullptr);
;     }
.LBB0_149:
	ds_read_b128 v[132:135], v0
	ds_read_b128 v[142:145], v0 offset:512
	s_mov_b32 s11, 0x317f8000
	v_add_u32_e32 v0, 0x4100, v0
	s_waitcnt lgkmcnt(0)
	v_cvt_pk_bf16_f32 v132, v132, v133
	v_cvt_pk_bf16_f32 v133, v134, v135
	s_waitcnt lgkmcnt(0)
	v_cvt_pk_bf16_f32 v134, v142, v143
	v_lshl_add_u64 v[142:143], v[2:3], 0, s[6:7]
	s_add_u32 s6, s6, 0x8000
	v_add_co_u32_e32 v142, vcc, s11, v142
	s_addc_u32 s7, s7, 0
	s_nop 0
	v_addc_co_u32_e32 v143, vcc, 0, v143, vcc
	s_cmp_lg_u32 s6, 0x40000
	v_cvt_pk_bf16_f32 v135, v144, v145
	global_store_dwordx2 v[142:143], v[132:133], off
	global_store_dwordx2 v[142:143], v[134:135], off offset:256
	s_cbranch_scc1 .LBB0_149
	s_mov_b64 s[6:7], 0

; __device__ __forceinline__ int ltid() { int t = threadIdx.x; asm volatile("" : "+v"(t)); return t; }
; __device__ __forceinline__ void emit_rm(const float* stage, u16* dst, long ld, const float* rs) {
;   const int tid = ltid(), c4 = (tid & 31) * 4, rr = tid >> 5;
; #pragma unroll 1
;   for (int ps = 0; ps < 8; ++ps) {
;     const int r = ps * 16 + rr;
;     const float* s = stage + r * SP + c4;
;     const float4 a = *(const float4*)s, b = *(const float4*)(s + 128);
;     const float f = rs ? rs[r] : 1.f;
;     uint2 o0, o1;
;     o0.x = pack2(a.x * f, a.y * f); o0.y = pack2(a.z * f, a.w * f);
;     o1.x = pack2(b.x * f, b.y * f); o1.y = pack2(b.z * f, b.w * f);
;     *(uint2*)(dst + (long)r * ld + c4) = o0;
;     *(uint2*)(dst + (long)r * ld + 128 + c4) = o1;
;   }
; }
; template <int KIND>
; __device__ __forceinline__ void tile_emit(const Ctx& p, int t, int hd, int s, int half, const float* stage) {
;     ...
;     } else if (col0 < 16384) {
;       emit_rm(stage, (u16*)(ws + OFF_CAT1) + ((long)pm * 256 + hr) * 8704 + (col0 - 8192), 8704, nullptr);
;     } else {
;       emit_rm(stage, (u16*)(ws + OFF_MQG) + ((long)pm * 256 + hr) * 1024 + (col0 - 16384), 1024, nullptr);
;     }
.LBB0_153:
	ds_read_b128 v[132:135], v0
	ds_read_b128 v[142:145], v0 offset:512
	s_mov_b32 s11, 0x207fc000
	v_add_u32_e32 v0, 0x4100, v0
	s_waitcnt lgkmcnt(0)
	v_cvt_pk_bf16_f32 v132, v132, v133
	v_cvt_pk_bf16_f32 v133, v134, v135
	v_cvt_pk_bf16_f32 v134, v142, v143
	v_lshl_add_u64 v[142:143], v[2:3], 0, s[6:7]
	s_add_u32 s6, s6, 0x44000
	v_add_co_u32_e32 v142, vcc, s11, v142
	s_addc_u32 s7, s7, 0
	s_nop 0
	v_addc_co_u32_e32 v143, vcc, 0, v143, vcc
	s_cmp_eq_u32 s6, 0x220000
	v_cvt_pk_bf16_f32 v135, v144, v145
	global_store_dwordx2 v[142:143], v[132:133], off
	global_store_dwordx2 v[142:143], v[134:135], off offset:256
	s_cbranch_scc0 .LBB0_153

; __device__ __forceinline__ int ltid() { int t = threadIdx.x; asm volatile("" : "+v"(t)); return t; }
; __device__ __forceinline__ void emit_rm(const float* stage, u16* dst, long ld, const float* rs) {
;   const int tid = ltid(), c4 = (tid & 31) * 4, rr = tid >> 5;
; #pragma unroll 1
;   for (int ps = 0; ps < 8; ++ps) {
;     const int r = ps * 16 + rr;
;     const float* s = stage + r * SP + c4;
;     const float4 a = *(const float4*)s, b = *(const float4*)(s + 128);
;     const float f = rs ? rs[r] : 1.f;
;     uint2 o0, o1;
;     o0.x = pack2(a.x * f, a.y * f); o0.y = pack2(a.z * f, a.w * f);
;     o1.x = pack2(b.x * f, b.y * f); o1.y = pack2(b.z * f, b.w * f);
;     *(uint2*)(dst + (long)r * ld + c4) = o0;
;     *(uint2*)(dst + (long)r * ld + 128 + c4) = o1;
;   }
; }
; template <int KIND>
; __device__ __forceinline__ void tile_emit(const Ctx& p, int t, int hd, int s, int half, const float* stage) {
;     ...
;     } else if (col0 < 16384) {
;       emit_rm(stage, (u16*)(ws + OFF_CAT1) + ((long)pm * 256 + hr) * 8704 + (col0 - 8192), 8704, nullptr);
;     } else {
;       emit_rm(stage, (u16*)(ws + OFF_MQG) + ((long)pm * 256 + hr) * 1024 + (col0 - 16384), 1024, nullptr);
;     }
.LBB0_156:
	ds_read_b128 v[132:135], v0
	ds_read_b128 v[142:145], v0 offset:512
	s_mov_b32 s1, 0x31838000
	v_add_u32_e32 v0, 0x4100, v0
	s_waitcnt lgkmcnt(0)
	v_cvt_pk_bf16_f32 v132, v132, v133
	v_cvt_pk_bf16_f32 v133, v134, v135
	v_cvt_pk_bf16_f32 v134, v142, v143
	v_lshl_add_u64 v[142:143], v[2:3], 0, s[4:5]
	s_add_u32 s4, s4, 0x8000
	v_add_co_u32_e32 v142, vcc, s1, v142
	s_addc_u32 s5, s5, 0
	s_nop 0
	v_addc_co_u32_e32 v143, vcc, 0, v143, vcc
	s_cmp_lg_u32 s4, 0x40000
	v_cvt_pk_bf16_f32 v135, v144, v145
	global_store_dwordx2 v[142:143], v[132:133], off
	global_store_dwordx2 v[142:143], v[134:135], off offset:256
	s_cbranch_scc1 .LBB0_156
	s_mov_b64 s[6:7], 0

; __device__ __forceinline__ int ltid() { int t = threadIdx.x; asm volatile("" : "+v"(t)); return t; }
; __device__ __forceinline__ void emit_rm(const float* stage, u16* dst, long ld, const float* rs) {
;   const int tid = ltid(), c4 = (tid & 31) * 4, rr = tid >> 5;
; #pragma unroll 1
;   for (int ps = 0; ps < 8; ++ps) {
;     const int r = ps * 16 + rr;
;     const float* s = stage + r * SP + c4;
;     const float4 a = *(const float4*)s, b = *(const float4*)(s + 128);
;     const float f = rs ? rs[r] : 1.f;
;     uint2 o0, o1;
;     o0.x = pack2(a.x * f, a.y * f); o0.y = pack2(a.z * f, a.w * f);
;     o1.x = pack2(b.x * f, b.y * f); o1.y = pack2(b.z * f, b.w * f);
;     *(uint2*)(dst + (long)r * ld + c4) = o0;
;     *(uint2*)(dst + (long)r * ld + 128 + c4) = o1;
;   }
; }
; template <int KIND>
; __device__ __forceinline__ void tile_emit(const Ctx& p, int t, int hd, int s, int half, const float* stage) {
;     ...
;     } else if (col0 < 16384) {
;       emit_rm(stage, (u16*)(ws + OFF_CAT1) + ((long)pm * 256 + hr) * 8704 + (col0 - 8192), 8704, nullptr);
;     } else {
;       emit_rm(stage, (u16*)(ws + OFF_MQG) + ((long)pm * 256 + hr) * 1024 + (col0 - 16384), 1024, nullptr);
;     }
.LBB0_160:
	ds_read_b128 v[132:135], v0
	ds_read_b128 v[142:145], v0 offset:512
	s_mov_b32 s4, 0x20a1c000
	v_add_u32_e32 v0, 0x4100, v0
	s_waitcnt lgkmcnt(0)
	v_cvt_pk_bf16_f32 v132, v132, v133
	v_cvt_pk_bf16_f32 v133, v134, v135
	v_cvt_pk_bf16_f32 v134, v142, v143
	v_lshl_add_u64 v[142:143], v[2:3], 0, s[0:1]
	s_add_u32 s0, s0, 0x44000
	v_add_co_u32_e32 v142, vcc, s4, v142
	s_addc_u32 s1, s1, 0
	s_nop 0
	v_addc_co_u32_e32 v143, vcc, 0, v143, vcc
	s_cmp_eq_u32 s0, 0x220000
	v_cvt_pk_bf16_f32 v135, v144, v145
	global_store_dwordx2 v[142:143], v[132:133], off
	global_store_dwordx2 v[142:143], v[134:135], off offset:256
	s_cbranch_scc0 .LBB0_160

; __device__ __forceinline__ int ltid() { int t = threadIdx.x; asm volatile("" : "+v"(t)); return t; }
; template <int AI>
; __device__ __forceinline__ void dump_halfT(const f32x4 (&acc)[2][2][4][2], float* stage) {
;   const int wid = ltid() >> 6, lane = ltid() & 63, wr = wid >> 2, wc = wid & 3, fr = lane & 15, fq = lane >> 4;
; #pragma unroll
;   for (int bj = 0; bj < 2; ++bj)
; #pragma unroll
;     for (int m = 0; m < 4; ++m)
; #pragma unroll
;       for (int n = 0; n < 2; ++n) {
;         const int r0 = wr * 64 + m * 16 + fq * 4, c = bj * 128 + wc * 32 + n * 16 + fr;
;         *(f32x4*)(stage + c * SPT + r0) = acc[AI][bj][m][n];
;       }
; }
; __device__ __forceinline__ void emit_trT(const float* stage, u16* dst, long ld) {
;   const int tid = ltid(), lane = tid & 63, w = tid >> 6;
; #pragma unroll 1
;   for (int ps = 0; ps < 8; ++ps) {
;     const int wp = ps * 8 + w;
;     const int col = (wp & 15) * 16 + (lane & 15), rg = (wp >> 4) * 4 + (lane >> 4);
;     const float* s = stage + col * SPT + rg * 8;
;     const float4 a = *(const float4*)s, b = *(const float4*)(s + 4);
;     uint4 o; o.x = pack2(a.x, a.y); o.y = pack2(a.z, a.w); o.z = pack2(b.x, b.y); o.w = pack2(b.z, b.w);
;     *(uint4*)(dst + (long)col * ld + rg * 8) = o;
;   }
; }
; template <int KIND>
; __device__ void gemm_phase(const Ctx& p, int hd, const int ntiles, const int blk0, const int nblk) {
;     ...
;         dump_halfT<0>(acc, stage); __syncthreads();
;         emit_trT(stage, xo, SEQ); __syncthreads();
;         dump_halfT<1>(acc, stage); __syncthreads();
;         emit_trT(stage, xo + 128, SEQ); __syncthreads();
.LBB0_164:
	v_add_u32_e32 v0, s4, v2
	v_lshrrev_b32_e32 v0, 2, v0
	v_and_or_b32 v80, v69, s91, v3
	v_and_or_b32 v0, v0, s82, v68
	v_mul_u32_u24_e32 v70, 0x210, v80
	v_lshlrev_b32_e32 v78, 3, v0
	v_lshlrev_b32_e32 v0, 5, v0
	v_add3_u32 v0, 16, v70, v0
	ds_read_b128 v[70:73], v0
	ds_read_b128 v[74:77], v0 offset:16
	v_lshlrev_b32_e32 v0, 14, v80
	v_ashrrev_i32_e32 v79, 31, v78
	s_add_i32 s4, s4, 8
	s_waitcnt lgkmcnt(0)
	v_cvt_pk_bf16_f32 v70, v70, v71
	v_cvt_pk_bf16_f32 v71, v72, v73
	v_cvt_pk_bf16_f32 v72, v74, v75
	v_lshl_add_u64 v[74:75], s[0:1], 0, v[0:1]
	v_cvt_pk_bf16_f32 v73, v76, v77
	v_lshl_add_u64 v[74:75], v[78:79], 1, v[74:75]
	v_add_u32_e32 v69, 0x80, v69
	s_cmp_lg_u32 s4, 64
	global_store_dwordx4 v[74:75], v[70:73], off
	s_cbranch_scc1 .LBB0_164
	v_mov_b32_e32 v0, v139
	v_mov_b32_e32 v2, v139
	s_waitcnt lgkmcnt(0)
	s_barrier
	s_movk_i32 s4, 0x60
	v_and_b32_e32 v3, 15, v2
	v_lshrrev_b32_e32 v68, 1, v0
	v_and_b32_e32 v0, 0xffffff00, v0
	v_and_b32_e32 v2, 48, v2
	v_and_or_b32 v3, v68, s4, v3
	v_add3_u32 v0, 16, v0, v2
	s_movk_i32 s4, 0x210
	v_mad_u32_u24 v2, v3, s4, v0
	ds_write_b128 v2, v[64:67]
	ds_write_b128 v2, v[60:63] offset:8448
	ds_write_b128 v2, v[56:59] offset:64
	ds_write_b128 v2, v[52:55] offset:8512
	ds_write_b128 v2, v[48:51] offset:128
	ds_write_b128 v2, v[44:47] offset:8576
	ds_write_b128 v2, v[40:43] offset:192
	ds_write_b128 v2, v[36:39] offset:8640
	v_mad_u32_u24 v2, v3, s4, v206
	v_mad_u32_u24 v3, v3, s4, v207
	v_add_u32_e32 v60, 64, v0
	v_add_u32_e32 v52, 0x80, v0
	v_add_u32_e32 v44, 0xc0, v0
	v_add_u32_e32 v36, v0, v2
	v_add_u32_e32 v0, v0, v3
	ds_write_b128 v0, v[28:31]
	v_add_u32_e32 v0, v60, v2
	ds_write_b128 v0, v[24:27]
	v_add_u32_e32 v0, v60, v3
	ds_write_b128 v0, v[20:23]
	v_add_u32_e32 v0, v52, v2
	ds_write_b128 v0, v[16:19]
	v_add_u32_e32 v0, v52, v3
	ds_write_b128 v0, v[12:15]
	v_add_u32_e32 v0, v44, v2
	ds_write_b128 v0, v[8:11]
	v_add_u32_e32 v0, v44, v3
	ds_write_b128 v0, v[4:7]
	v_mov_b32_e32 v0, v139
	ds_write_b128 v36, v[32:35]
	s_waitcnt lgkmcnt(0)
	s_barrier
	s_mov_b32 s4, 0
	v_ashrrev_i32_e32 v2, 6, v0
	v_and_b32_e32 v3, 15, v0
	v_bfe_u32 v4, v0, 4, 2
	v_lshlrev_b32_e32 v5, 4, v2
.LBB0_166:
	v_add_u32_e32 v0, s4, v2
	v_lshrrev_b32_e32 v0, 2, v0
	v_and_or_b32 v16, v5, s91, v3
	v_and_or_b32 v0, v0, s82, v4
	v_mul_u32_u24_e32 v6, 0x210, v16
	v_lshlrev_b32_e32 v14, 3, v0
	v_lshlrev_b32_e32 v0, 5, v0
	v_add3_u32 v0, 16, v6, v0
	ds_read_b128 v[6:9], v0
	ds_read_b128 v[10:13], v0 offset:16
	v_lshlrev_b32_e32 v0, 14, v16
	v_ashrrev_i32_e32 v15, 31, v14
	s_add_i32 s4, s4, 8
	s_waitcnt lgkmcnt(0)
	v_cvt_pk_bf16_f32 v6, v6, v7
	v_cvt_pk_bf16_f32 v7, v8, v9
	v_cvt_pk_bf16_f32 v8, v10, v11
	v_lshl_add_u64 v[10:11], s[0:1], 0, v[0:1]
	v_cvt_pk_bf16_f32 v9, v12, v13
	v_lshl_add_u64 v[10:11], v[14:15], 1, v[10:11]
	v_add_u32_e32 v5, 0x80, v5
	s_cmp_lg_u32 s4, 64
	global_store_dwordx4 v[10:11], v[6:9], off offset:256
	s_cbranch_scc1 .LBB0_166
	s_waitcnt lgkmcnt(0)
	s_barrier
	s_branch .LBB0_137

; __device__ __forceinline__ int ltid() { int t = threadIdx.x; asm volatile("" : "+v"(t)); return t; }
; __device__ void ln_phase(const Ctx& p, const float* __restrict__ g, const float* __restrict__ bt, u16* __restrict__ xb,
;                          const float* res, const u16* __restrict__ yb) {
;   const int tid = ltid(), w = tid >> 6, lane = tid & 63;
;   float* gl = (float*)g_smem; float* bl = gl + DM;
;   __syncthreads();
;   for (int c = tid * 4; c < DM; c += 512 * 4) { *(float4*)(gl + c) = *(const float4*)(g + c); *(float4*)(bl + c) = *(const float4*)(bt + c); }
;   __syncthreads();
.LBB0_169:
	v_readlane_b32 s0, v252, 53
	v_readlane_b32 s1, v252, 54
	s_cmp_gt_i32 s0, 6
	s_mov_b64 s[0:1], -1
	s_cbranch_scc0 .LBB0_196
	v_mov_b32_e32 v0, s66
	s_waitcnt vmcnt(0) lgkmcnt(0)
	v_add_co_u32_e32 v6, vcc, 0x4375c000, v0
	v_mov_b32_e32 v0, s67
	s_nop 0
	v_addc_co_u32_e32 v7, vcc, 0, v0, vcc
	global_load_dwordx4 v[2:5], v[6:7], off offset:88
	global_load_dwordx2 v[10:11], v[6:7], off
	v_mov_b32_e32 v0, v139
	s_movk_i32 s0, 0x400
	s_waitcnt lgkmcnt(0)
	v_cmp_gt_i32_e32 vcc, s0, v0
	v_lshlrev_b32_e32 v8, 2, v0
	s_barrier
	s_and_saveexec_b64 s[0:1], vcc
	s_movk_i32 s6, 0x7ff
	s_mov_b64 s[8:9], 0x2000
	s_cbranch_execz .LBB0_173
	v_ashrrev_i32_e32 v9, 31, v8
	v_lshlrev_b64 v[12:13], 2, v[8:9]
	v_add_u32_e32 v6, 0xfffff800, v8
	v_lshl_add_u32 v7, v0, 4, 16
	s_waitcnt vmcnt(0)
	v_lshl_add_u64 v[4:5], v[4:5], 0, v[12:13]
	v_lshl_add_u64 v[2:3], v[2:3], 0, v[12:13]
	s_mov_b64 s[4:5], 0
.LBB0_172:
	global_load_dwordx4 v[12:15], v[2:3], off
	v_add_u32_e32 v6, 0x800, v6
	v_lshl_add_u64 v[2:3], v[2:3], 0, s[8:9]
	v_cmp_lt_i32_e32 vcc, s6, v6
	s_mov_b64 s[8:9], 0x2000
	s_or_b64 s[4:5], vcc, s[4:5]
	s_waitcnt vmcnt(0) lgkmcnt(0)
	ds_write_b128 v7, v[12:15]
	global_load_dwordx4 v[12:15], v[4:5], off
	v_lshl_add_u64 v[4:5], v[4:5], 0, s[8:9]
	s_waitcnt vmcnt(0) lgkmcnt(0)
	ds_write_b128 v7, v[12:15] offset:16384
	v_add_u32_e32 v7, 0x2000, v7
	s_andn2_b64 exec, exec, s[4:5]
	s_cbranch_execnz .LBB0_172

;   __device__ __forceinline__ float* out() const { return ((float* const*)(ws + OFF_TBL))[28]; }
; __device__ void ln_phase(const Ctx& p, const float* __restrict__ g, const float* __restrict__ bt, u16* __restrict__ xb,
;                          const float* res, const u16* __restrict__ yb) {
;     ...
;   for (int row = blockIdx.x * 8 + w; row < NTOK; row += gridDim.x * 8) {
;     float* x = p.out() + (long)row * DM;
;     float4 v[16];
;     const float* rx = res + (long)row * DM;
;     const u16* ry = yb + (long)row * DM;
; #pragma unroll
;     for (int k = 0; k < 16; ++k) {
;       const float4 r4 = *(const float4*)(rx + k * 256 + lane * 4);
;       const uint2 y2 = *(const uint2*)(ry + k * 256 + lane * 4);
;       v[k] = make_float4(ALPHA_F * r4.x + __uint_as_float(y2.x << 16), ALPHA_F * r4.y + __uint_as_float(y2.x & 0xffff0000u),
;                          ALPHA_F * r4.z + __uint_as_float(y2.y << 16), ALPHA_F * r4.w + __uint_as_float(y2.y & 0xffff0000u));
;     }
;     float s = 0.f;
; #pragma unroll
;     for (int k = 0; k < 16; ++k) s += (v[k].x + v[k].y) + (v[k].z + v[k].w);
.LBB0_175:
	v_ashrrev_i32_e32 v7, 31, v6
	v_lshlrev_b64 v[58:59], 13, v[6:7]
	v_mov_b64_e32 v[2:3], s[4:5]
	v_lshlrev_b64 v[42:43], 14, v[6:7]
	v_lshl_add_u64 v[4:5], v[12:13], 0, v[58:59]
	global_load_dwordx2 v[38:39], v[2:3], off
	v_lshl_add_u64 v[2:3], v[10:11], 0, v[42:43]
	global_load_dwordx2 v[44:45], v[4:5], off
	global_load_dwordx2 v[46:47], v[4:5], off offset:1536
	global_load_dwordx2 v[54:55], v[4:5], off offset:3584
	global_load_dwordx4 v[102:105], v[2:3], off
	v_add_co_u32_e32 v64, vcc, s9, v4
	v_lshlrev_b32_e32 v0, 2, v8
	s_nop 0
	v_addc_co_u32_e32 v65, vcc, 0, v5, vcc
	v_mov_b32_e32 v31, v1
	v_mov_b32_e32 v33, v1
	v_mov_b32_e32 v35, v1
	v_mov_b32_e32 v37, v1
	v_add_u32_e32 v6, s56, v6
	global_load_dwordx2 v[48:49], v[4:5], off offset:2048
	global_load_dwordx2 v[52:53], v[4:5], off offset:3072
	s_waitcnt vmcnt(0) lgkmcnt(0)
	v_lshl_add_u64 v[114:115], v[38:39], 0, v[42:43]
	v_lshl_add_u64 v[38:39], s[66:67], 0, v[58:59]
	v_lshlrev_b32_e32 v40, 16, v44
	v_and_b32_e32 v41, 0xffff0000, v44
	v_lshlrev_b32_e32 v60, 16, v45
	v_and_b32_e32 v61, 0xffff0000, v45
	global_load_dwordx2 v[44:45], v[4:5], off offset:512
	v_pk_fma_f32 v[58:59], v[102:103], s[44:45], v[40:41] op_sel_hi:[1,0,1]
	v_pk_fma_f32 v[60:61], v[104:105], s[44:45], v[60:61] op_sel_hi:[1,0,1]
	global_load_dwordx4 v[102:105], v[2:3], off offset:1024
	v_mov_b32_e32 v40, v58
	v_mov_b32_e32 v41, v60
	v_mov_b32_e32 v82, v59
	v_mov_b32_e32 v83, v61
	v_pk_add_f32 v[40:41], v[40:41], v[82:83]
	v_lshlrev_b32_e32 v84, 16, v47
	v_and_b32_e32 v85, 0xffff0000, v47
	v_and_b32_e32 v47, 0xffff0000, v48
	v_lshlrev_b32_e32 v94, 16, v49
	v_and_b32_e32 v95, 0xffff0000, v49
	v_lshl_add_u64 v[42:43], v[114:115], 0, v[0:1]
	v_add_f32_e32 v0, v40, v41
	v_add_f32_e32 v92, 0, v0
	v_lshlrev_b32_e32 v112, 16, v55
	v_and_b32_e32 v113, 0xffff0000, v55
	v_lshlrev_b32_e32 v0, 1, v8
	v_lshl_add_u64 v[40:41], v[38:39], 0, v[0:1]
	v_lshlrev_b32_e32 v0, 2, v14
	v_lshlrev_b32_e32 v50, 16, v52
	v_and_b32_e32 v51, 0xffff0000, v52
	v_lshlrev_b32_e32 v106, 16, v53
	v_and_b32_e32 v107, 0xffff0000, v53
	v_lshlrev_b32_e32 v52, 16, v54
	v_and_b32_e32 v53, 0xffff0000, v54
	s_waitcnt vmcnt(0) lgkmcnt(0)
	v_lshlrev_b32_e32 v70, 16, v44
	v_and_b32_e32 v71, 0xffff0000, v44
	v_lshlrev_b32_e32 v72, 16, v45
	v_and_b32_e32 v73, 0xffff0000, v45
	v_pk_fma_f32 v[70:71], v[102:103], s[44:45], v[70:71] op_sel_hi:[1,0,1]
	v_pk_fma_f32 v[72:73], v[104:105], s[44:45], v[72:73] op_sel_hi:[1,0,1]
	global_load_dwordx2 v[44:45], v[4:5], off offset:1024
	v_mov_b32_e32 v82, v70
	v_mov_b32_e32 v83, v72
	v_mov_b32_e32 v102, v71
	v_mov_b32_e32 v103, v73
	v_pk_add_f32 v[82:83], v[82:83], v[102:103]
	global_load_dwordx4 v[102:105], v[2:3], off offset:2048
	v_pk_add_f32 v[116:117], v[82:83], v[82:83] op_sel:[0,1] op_sel_hi:[1,0]
	s_waitcnt vmcnt(0) lgkmcnt(0)
	v_lshlrev_b32_e32 v76, 16, v44
	v_and_b32_e32 v77, 0xffff0000, v44
	v_lshlrev_b32_e32 v78, 16, v45
	v_and_b32_e32 v79, 0xffff0000, v45
	v_lshlrev_b32_e32 v44, 16, v46
	v_and_b32_e32 v45, 0xffff0000, v46
	v_pk_fma_f32 v[76:77], v[102:103], s[44:45], v[76:77] op_sel_hi:[1,0,1]
	v_pk_fma_f32 v[78:79], v[104:105], s[44:45], v[78:79] op_sel_hi:[1,0,1]
	global_load_dwordx4 v[102:105], v[2:3], off offset:3072
	v_lshlrev_b32_e32 v46, 16, v48
	global_load_dwordx2 v[48:49], v[4:5], off offset:2560
	v_pk_add_f32 v[118:119], v[76:77], v[76:77] op_sel:[0,1] op_sel_hi:[1,0]
	global_load_dwordx2 v[4:5], v[64:65], off
	v_pk_add_f32 v[120:121], v[78:79], v[78:79] op_sel:[0,1] op_sel_hi:[1,0]
	s_waitcnt vmcnt(0) lgkmcnt(0)
	v_pk_fma_f32 v[82:83], v[102:103], s[44:45], v[44:45] op_sel_hi:[1,0,1]
	s_nop 0
	v_mov_b32_e32 v93, v82
	v_mov_b32_e32 v117, v83
	v_pk_add_f32 v[44:45], v[92:93], v[116:117]
	v_add_co_u32_e32 v116, vcc, s9, v2
	v_pk_fma_f32 v[84:85], v[104:105], s[44:45], v[84:85] op_sel_hi:[1,0,1]
	s_nop 0
	v_addc_co_u32_e32 v117, vcc, 0, v3, vcc
	global_load_dwordx4 v[102:105], v[116:117], off
	v_lshlrev_b32_e32 v62, 16, v4
	v_and_b32_e32 v63, 0xffff0000, v4
	v_lshlrev_b32_e32 v54, 16, v5
	v_and_b32_e32 v55, 0xffff0000, v5
	global_load_dwordx2 v[4:5], v[64:65], off offset:512
	v_mov_b32_e32 v119, v84
	v_mov_b32_e32 v121, v85
	v_pk_add_f32 v[92:93], v[118:119], v[120:121]
	global_load_dwordx4 v[118:121], v[116:117], off offset:2048
	v_pk_add_f32 v[44:45], v[44:45], v[92:93]
	v_lshlrev_b32_e32 v98, 16, v48
	v_and_b32_e32 v99, 0xffff0000, v48
	v_lshlrev_b32_e32 v48, 16, v49
	v_and_b32_e32 v49, 0xffff0000, v49
	v_pk_add_f32 v[122:123], v[44:45], v[44:45] op_sel:[0,1] op_sel_hi:[1,0]
	v_lshl_add_u64 v[44:45], v[114:115], 0, v[30:31]
	s_waitcnt vmcnt(0) lgkmcnt(0)
	v_pk_fma_f32 v[92:93], v[102:103], s[44:45], v[46:47] op_sel_hi:[1,0,1]
	v_pk_fma_f32 v[94:95], v[104:105], s[44:45], v[94:95] op_sel_hi:[1,0,1]
	v_mov_b32_e32 v46, v92
	v_mov_b32_e32 v47, v94
	v_mov_b32_e32 v102, v93
	v_mov_b32_e32 v103, v95
	v_pk_add_f32 v[46:47], v[46:47], v[102:103]
	global_load_dwordx4 v[102:105], v[116:117], off offset:1024
	v_lshlrev_b32_e32 v56, 16, v4
	v_and_b32_e32 v57, 0xffff0000, v4
	v_lshlrev_b32_e32 v68, 16, v5
	v_and_b32_e32 v69, 0xffff0000, v5
	global_load_dwordx2 v[4:5], v[64:65], off offset:1024
	v_pk_add_f32 v[124:125], v[46:47], v[46:47] op_sel:[0,1] op_sel_hi:[1,0]
	v_pk_fma_f32 v[106:107], v[120:121], s[44:45], v[106:107] op_sel_hi:[1,0,1]
	v_lshl_add_u64 v[46:47], v[114:115], 0, v[32:33]
	s_waitcnt vmcnt(0) lgkmcnt(0)
; __device__ void ln_phase(const Ctx& p, const float* __restrict__ g, const float* __restrict__ bt, u16* __restrict__ xb,
;                          const float* res, const u16* __restrict__ yb) {
;     ...
;     const float* rx = res + (long)row * DM;
;     const u16* ry = yb + (long)row * DM;
; #pragma unroll
;     for (int k = 0; k < 16; ++k) {
;       const float4 r4 = *(const float4*)(rx + k * 256 + lane * 4);
;       const uint2 y2 = *(const uint2*)(ry + k * 256 + lane * 4);
;       v[k] = make_float4(ALPHA_F * r4.x + __uint_as_float(y2.x << 16), ALPHA_F * r4.y + __uint_as_float(y2.x & 0xffff0000u),
;                          ALPHA_F * r4.z + __uint_as_float(y2.y << 16), ALPHA_F * r4.w + __uint_as_float(y2.y & 0xffff0000u));
;     }
;     float s = 0.f;
; #pragma unroll
;     for (int k = 0; k < 16; ++k) s += (v[k].x + v[k].y) + (v[k].z + v[k].w);
	v_pk_fma_f32 v[98:99], v[102:103], s[44:45], v[98:99] op_sel_hi:[1,0,1]
	v_pk_fma_f32 v[102:103], v[104:105], s[44:45], v[48:49] op_sel_hi:[1,0,1]
	v_pk_add_f32 v[126:127], v[98:99], v[98:99] op_sel:[0,1] op_sel_hi:[1,0]
	v_pk_add_f32 v[128:129], v[102:103], v[102:103] op_sel:[0,1] op_sel_hi:[1,0]
	v_pk_fma_f32 v[104:105], v[118:119], s[44:45], v[50:51] op_sel_hi:[1,0,1]
	v_mov_b32_e32 v127, v106
	v_mov_b32_e32 v123, v104
	v_mov_b32_e32 v125, v105
	v_mov_b32_e32 v129, v107
	v_pk_add_f32 v[50:51], v[122:123], v[124:125]
	v_pk_add_f32 v[118:119], v[126:127], v[128:129]
	v_lshlrev_b32_e32 v74, 16, v4
	v_pk_add_f32 v[50:51], v[50:51], v[118:119]
	global_load_dwordx4 v[116:119], v[116:117], off offset:3072
	v_and_b32_e32 v75, 0xffff0000, v4
	v_lshlrev_b32_e32 v80, 16, v5
	v_and_b32_e32 v81, 0xffff0000, v5
	global_load_dwordx2 v[4:5], v[64:65], off offset:1536
	v_pk_add_f32 v[128:129], v[50:51], v[50:51] op_sel:[0,1] op_sel_hi:[1,0]
	v_lshl_add_u64 v[48:49], v[114:115], 0, v[34:35]
	v_lshl_add_u64 v[50:51], v[114:115], 0, v[36:37]
	s_waitcnt vmcnt(0) lgkmcnt(0)
	v_pk_fma_f32 v[116:117], v[116:117], s[44:45], v[52:53] op_sel_hi:[1,0,1]
	v_pk_fma_f32 v[118:119], v[118:119], s[44:45], v[112:113] op_sel_hi:[1,0,1]
	v_mov_b32_e32 v52, v116
	v_mov_b32_e32 v53, v118
	v_mov_b32_e32 v112, v117
	v_mov_b32_e32 v113, v119
	v_pk_add_f32 v[52:53], v[52:53], v[112:113]
	v_add_co_u32_e32 v112, vcc, s8, v2
	v_lshlrev_b32_e32 v90, 16, v4
	s_nop 0
	v_addc_co_u32_e32 v113, vcc, 0, v3, vcc
	global_load_dwordx4 v[120:123], v[112:113], off
	global_load_dwordx4 v[124:127], v[112:113], off offset:1024
	v_and_b32_e32 v91, 0xffff0000, v4
	v_lshlrev_b32_e32 v86, 16, v5
	v_and_b32_e32 v87, 0xffff0000, v5
	global_load_dwordx2 v[4:5], v[64:65], off offset:2048
	v_pk_add_f32 v[130:131], v[52:53], v[52:53] op_sel:[0,1] op_sel_hi:[1,0]
	v_add_co_u32_e32 v2, vcc, s43, v2
	v_lshl_add_u64 v[52:53], v[114:115], 0, v[0:1]
	s_nop 0
	v_addc_co_u32_e32 v3, vcc, 0, v3, vcc
	global_load_dwordx4 v[142:145], v[2:3], off
	v_lshlrev_b32_e32 v0, 1, v14
	s_waitcnt vmcnt(0) lgkmcnt(0)
	v_pk_fma_f32 v[120:121], v[120:121], s[44:45], v[62:63] op_sel_hi:[1,0,1]
	v_pk_fma_f32 v[124:125], v[124:125], s[44:45], v[56:57] op_sel_hi:[1,0,1]
	v_pk_fma_f32 v[122:123], v[122:123], s[44:45], v[54:55] op_sel_hi:[1,0,1]
	v_mov_b32_e32 v129, v124
	v_mov_b32_e32 v131, v125
	v_pk_add_f32 v[132:133], v[120:121], v[120:121] op_sel:[0,1] op_sel_hi:[1,0]
	v_pk_add_f32 v[134:135], v[122:123], v[122:123] op_sel:[0,1] op_sel_hi:[1,0]
	v_pk_fma_f32 v[126:127], v[126:127], s[44:45], v[68:69] op_sel_hi:[1,0,1]
	v_pk_add_f32 v[56:57], v[128:129], v[130:131]
	global_load_dwordx4 v[128:131], v[112:113], off offset:2048
	v_mov_b32_e32 v133, v126
	v_mov_b32_e32 v135, v127
	v_pk_add_f32 v[68:69], v[132:133], v[134:135]
	global_load_dwordx4 v[132:135], v[112:113], off offset:3072
	v_lshlrev_b32_e32 v88, 16, v4
	v_and_b32_e32 v89, 0xffff0000, v4
	v_lshlrev_b32_e32 v96, 16, v5
	v_and_b32_e32 v97, 0xffff0000, v5
	global_load_dwordx2 v[4:5], v[64:65], off offset:2560
	v_pk_add_f32 v[56:57], v[56:57], v[68:69]
	v_pk_fma_f32 v[142:143], v[142:143], s[44:45], v[88:89] op_sel_hi:[1,0,1]
	v_pk_add_f32 v[146:147], v[56:57], v[56:57] op_sel:[0,1] op_sel_hi:[1,0]
	v_pk_fma_f32 v[144:145], v[144:145], s[44:45], v[96:97] op_sel_hi:[1,0,1]
	v_mov_b32_e32 v147, v142
	v_lshl_add_u64 v[62:63], v[38:39], 0, v[0:1]
	v_lshlrev_b32_e32 v0, 2, v16
	v_lshl_add_u64 v[54:55], v[114:115], 0, v[0:1]
	v_lshlrev_b32_e32 v0, 1, v16
	v_lshl_add_u64 v[68:69], v[38:39], 0, v[0:1]
	v_lshlrev_b32_e32 v0, 2, v18
	v_lshl_add_u64 v[56:57], v[114:115], 0, v[0:1]
	v_lshlrev_b32_e32 v0, 1, v18
	s_waitcnt vmcnt(0) lgkmcnt(0)
	v_pk_fma_f32 v[128:129], v[128:129], s[44:45], v[74:75] op_sel_hi:[1,0,1]
	v_pk_fma_f32 v[130:131], v[130:131], s[44:45], v[80:81] op_sel_hi:[1,0,1]
	v_mov_b32_e32 v74, v128
	v_mov_b32_e32 v75, v130
	v_mov_b32_e32 v80, v129
	v_mov_b32_e32 v81, v131
	v_pk_add_f32 v[74:75], v[74:75], v[80:81]
	v_pk_fma_f32 v[132:133], v[132:133], s[44:45], v[90:91] op_sel_hi:[1,0,1]
	v_pk_fma_f32 v[134:135], v[134:135], s[44:45], v[86:87] op_sel_hi:[1,0,1]
	v_pk_add_f32 v[148:149], v[74:75], v[74:75] op_sel:[0,1] op_sel_hi:[1,0]
	v_pk_add_f32 v[112:113], v[132:133], v[132:133] op_sel:[0,1] op_sel_hi:[1,0]
	v_pk_add_f32 v[150:151], v[134:135], v[134:135] op_sel:[0,1] op_sel_hi:[1,0]
	v_lshlrev_b32_e32 v100, 16, v4
	v_and_b32_e32 v101, 0xffff0000, v4
	v_lshlrev_b32_e32 v108, 16, v5
	v_and_b32_e32 v109, 0xffff0000, v5
	global_load_dwordx2 v[4:5], v[64:65], off offset:3072
	v_mov_b32_e32 v149, v143
	v_mov_b32_e32 v113, v144
	v_mov_b32_e32 v151, v145
	v_pk_add_f32 v[88:89], v[146:147], v[148:149]
	v_pk_add_f32 v[96:97], v[112:113], v[150:151]
	global_load_dwordx4 v[146:149], v[2:3], off offset:1024
	global_load_dwordx4 v[150:153], v[2:3], off offset:2048
	v_lshl_add_u64 v[80:81], v[38:39], 0, v[0:1]
	global_load_dwordx2 v[64:65], v[64:65], off offset:3584
	v_lshlrev_b32_e32 v0, 2, v20
	v_lshl_add_u64 v[74:75], v[114:115], 0, v[0:1]
	v_lshlrev_b32_e32 v0, 1, v20
	v_lshl_add_u64 v[90:91], v[38:39], 0, v[0:1]
	v_lshlrev_b32_e32 v0, 2, v22
	v_lshl_add_u64 v[86:87], v[114:115], 0, v[0:1]
	v_lshlrev_b32_e32 v0, 1, v22
	v_pk_add_f32 v[88:89], v[88:89], v[96:97]
	v_lshl_add_u64 v[96:97], v[38:39], 0, v[0:1]
	v_lshlrev_b32_e32 v0, 2, v24
	v_pk_add_f32 v[154:155], v[88:89], v[88:89] op_sel:[0,1] op_sel_hi:[1,0]
	v_lshl_add_u64 v[88:89], v[114:115], 0, v[0:1]
	v_lshlrev_b32_e32 v0, 1, v24
	s_waitcnt vmcnt(0) lgkmcnt(0)
; __device__ void ln_phase(const Ctx& p, const float* __restrict__ g, const float* __restrict__ bt, u16* __restrict__ xb,
;                          const float* res, const u16* __restrict__ yb) {
;     ...
;     float s = 0.f;
; #pragma unroll
;     for (int k = 0; k < 16; ++k) s += (v[k].x + v[k].y) + (v[k].z + v[k].w);
;     s = wave_sum(s);
;     const float mu = s * (1.f / DM);
;     float q = 0.f;
; #pragma unroll
;     for (int k = 0; k < 16; ++k) {
;       v[k].x -= mu; v[k].y -= mu; v[k].z -= mu; v[k].w -= mu;
;       q += (v[k].x * v[k].x + v[k].y * v[k].y) + (v[k].z * v[k].z + v[k].w * v[k].w);
;     }
	v_lshlrev_b32_e32 v110, 16, v4
	v_and_b32_e32 v111, 0xffff0000, v4
	v_lshlrev_b32_e32 v4, 16, v5
	v_and_b32_e32 v5, 0xffff0000, v5
	v_pk_fma_f32 v[146:147], v[146:147], s[44:45], v[100:101] op_sel_hi:[1,0,1]
	v_pk_fma_f32 v[152:153], v[152:153], s[44:45], v[4:5] op_sel_hi:[1,0,1]
	global_load_dwordx4 v[2:5], v[2:3], off offset:3072
	v_pk_fma_f32 v[148:149], v[148:149], s[44:45], v[108:109] op_sel_hi:[1,0,1]
	v_mov_b32_e32 v100, v146
	v_mov_b32_e32 v101, v148
	v_mov_b32_e32 v108, v147
	v_mov_b32_e32 v109, v149
	v_lshlrev_b32_e32 v66, 16, v64
	v_and_b32_e32 v67, 0xffff0000, v64
	v_lshlrev_b32_e32 v64, 16, v65
	v_and_b32_e32 v65, 0xffff0000, v65
	v_pk_add_f32 v[100:101], v[100:101], v[108:109]
	v_pk_fma_f32 v[150:151], v[150:151], s[44:45], v[110:111] op_sel_hi:[1,0,1]
	v_pk_add_f32 v[156:157], v[100:101], v[100:101] op_sel:[0,1] op_sel_hi:[1,0]
	v_pk_add_f32 v[158:159], v[150:151], v[150:151] op_sel:[0,1] op_sel_hi:[1,0]
	v_pk_add_f32 v[160:161], v[152:153], v[152:153] op_sel:[0,1] op_sel_hi:[1,0]
	v_lshl_add_u64 v[108:109], v[38:39], 0, v[0:1]
	v_lshlrev_b32_e32 v0, 2, v26
	v_lshl_add_u64 v[100:101], v[114:115], 0, v[0:1]
	v_lshlrev_b32_e32 v0, 1, v26
	v_lshl_add_u64 v[112:113], v[38:39], 0, v[0:1]
	v_lshlrev_b32_e32 v0, 2, v28
	v_lshl_add_u64 v[110:111], v[114:115], 0, v[0:1]
	s_waitcnt vmcnt(0) lgkmcnt(0)
	v_pk_fma_f32 v[2:3], v[2:3], s[44:45], v[66:67] op_sel_hi:[1,0,1]
	v_pk_fma_f32 v[180:181], v[4:5], s[44:45], v[64:65] op_sel_hi:[1,0,1]
	v_mov_b32_e32 v155, v2
	v_mov_b32_e32 v157, v3
	v_mov_b32_e32 v159, v180
	v_mov_b32_e32 v161, v181
	v_pk_add_f32 v[4:5], v[154:155], v[156:157]
	v_pk_add_f32 v[64:65], v[158:159], v[160:161]
	s_nop 0
	v_pk_add_f32 v[4:5], v[4:5], v[64:65]
	s_nop 0
	v_add_f32_e32 v0, v4, v5
	ds_bpermute_b32 v4, v9, v0
	s_waitcnt lgkmcnt(0)
	v_add_f32_e32 v0, v0, v4
	ds_bpermute_b32 v4, v15, v0
	s_waitcnt lgkmcnt(0)
	v_add_f32_e32 v0, v0, v4
	ds_bpermute_b32 v4, v17, v0
	s_waitcnt lgkmcnt(0)
	v_add_f32_e32 v0, v0, v4
	ds_bpermute_b32 v4, v19, v0
	s_waitcnt lgkmcnt(0)
	v_add_f32_e32 v0, v0, v4
	ds_bpermute_b32 v4, v21, v0
	s_waitcnt lgkmcnt(0)
	v_add_f32_e32 v0, v0, v4
	ds_bpermute_b32 v4, v23, v0
	s_waitcnt lgkmcnt(0)
	v_add_f32_e32 v0, v0, v4
	v_mul_f32_e32 v0, 0x39800000, v0
	v_pk_add_f32 v[178:179], v[58:59], v[0:1] op_sel_hi:[1,0] neg_lo:[0,1] neg_hi:[0,1]
	v_pk_add_f32 v[176:177], v[60:61], v[0:1] op_sel_hi:[1,0] neg_lo:[0,1] neg_hi:[0,1]
	v_mov_b32_e32 v58, v179
	v_mov_b32_e32 v59, v177
	v_mov_b32_e32 v4, v178
	v_mov_b32_e32 v5, v176
	v_pk_mul_f32 v[58:59], v[58:59], v[58:59]
	v_pk_add_f32 v[174:175], v[70:71], v[0:1] op_sel_hi:[1,0] neg_lo:[0,1] neg_hi:[0,1]
	v_pk_fma_f32 v[4:5], v[4:5], v[4:5], v[58:59]
	v_pk_add_f32 v[172:173], v[72:73], v[0:1] op_sel_hi:[1,0] neg_lo:[0,1] neg_hi:[0,1]
	v_pk_add_f32 v[4:5], v[4:5], v[4:5] op_sel_hi:[0,1]
	v_mov_b32_e32 v60, v175
	v_mov_b32_e32 v61, v173
	v_pk_add_f32 v[170:171], v[76:77], v[0:1] op_sel_hi:[1,0] neg_lo:[0,1] neg_hi:[0,1]
	v_mov_b32_e32 v58, v174
	v_mov_b32_e32 v59, v172
	v_pk_mul_f32 v[60:61], v[60:61], v[60:61]
	v_pk_add_f32 v[168:169], v[78:79], v[0:1] op_sel_hi:[1,0] neg_lo:[0,1] neg_hi:[0,1]
	v_mul_f32_e32 v4, v170, v170
	v_pk_fma_f32 v[58:59], v[58:59], v[58:59], v[60:61]
	v_pk_fma_f32 v[60:61], v[170:171], v[170:171], v[4:5] op_sel_hi:[1,1,0]
	v_mul_f32_e32 v4, v168, v168
	v_pk_add_f32 v[166:167], v[82:83], v[0:1] op_sel_hi:[1,0] neg_lo:[0,1] neg_hi:[0,1]
	v_pk_add_f32 v[164:165], v[84:85], v[0:1] op_sel_hi:[1,0] neg_lo:[0,1] neg_hi:[0,1]
	v_pk_add_f32 v[58:59], v[58:59], v[58:59] op_sel_hi:[0,1]
	v_pk_fma_f32 v[64:65], v[168:169], v[168:169], v[4:5] op_sel_hi:[1,1,0]
	v_pk_mul_f32 v[66:67], v[166:167], v[166:167]
	v_pk_mul_f32 v[70:71], v[164:165], v[164:165]
	v_mov_b32_e32 v60, v66
	v_mov_b32_e32 v64, v67
	v_mov_b32_e32 v4, v70
	v_mov_b32_e32 v58, v71
	v_pk_add_f32 v[60:61], v[60:61], v[64:65]
	v_pk_add_f32 v[4:5], v[4:5], v[58:59]
	v_pk_add_f32 v[162:163], v[92:93], v[0:1] op_sel_hi:[1,0] neg_lo:[0,1] neg_hi:[0,1]
	v_pk_add_f32 v[4:5], v[60:61], v[4:5]
	v_pk_add_f32 v[160:161], v[94:95], v[0:1] op_sel_hi:[1,0] neg_lo:[0,1] neg_hi:[0,1]
	v_pk_add_f32 v[4:5], v[4:5], v[4:5] op_sel_hi:[0,1]
	v_mov_b32_e32 v60, v163
	v_mov_b32_e32 v61, v161
	v_pk_add_f32 v[158:159], v[98:99], v[0:1] op_sel_hi:[1,0] neg_lo:[0,1] neg_hi:[0,1]
	v_mov_b32_e32 v58, v162
	v_mov_b32_e32 v59, v160
	v_pk_mul_f32 v[60:61], v[60:61], v[60:61]
	v_pk_add_f32 v[156:157], v[102:103], v[0:1] op_sel_hi:[1,0] neg_lo:[0,1] neg_hi:[0,1]
	v_mul_f32_e32 v4, v158, v158
	v_pk_fma_f32 v[58:59], v[58:59], v[58:59], v[60:61]
	v_pk_fma_f32 v[60:61], v[158:159], v[158:159], v[4:5] op_sel_hi:[1,1,0]
	v_mul_f32_e32 v4, v156, v156
	v_pk_add_f32 v[154:155], v[104:105], v[0:1] op_sel_hi:[1,0] neg_lo:[0,1] neg_hi:[0,1]
	v_pk_add_f32 v[114:115], v[106:107], v[0:1] op_sel_hi:[1,0] neg_lo:[0,1] neg_hi:[0,1]
	v_pk_add_f32 v[58:59], v[58:59], v[58:59] op_sel_hi:[0,1]
	v_pk_fma_f32 v[64:65], v[156:157], v[156:157], v[4:5] op_sel_hi:[1,1,0]
	v_pk_mul_f32 v[66:67], v[154:155], v[154:155]
	v_pk_mul_f32 v[70:71], v[114:115], v[114:115]
	v_mov_b32_e32 v60, v66
	v_mov_b32_e32 v64, v67
	v_mov_b32_e32 v58, v70
	v_mov_b32_e32 v4, v71
	v_pk_add_f32 v[60:61], v[60:61], v[64:65]
	v_pk_add_f32 v[4:5], v[58:59], v[4:5]
	v_pk_add_f32 v[106:107], v[116:117], v[0:1] op_sel_hi:[1,0] neg_lo:[0,1] neg_hi:[0,1]
	v_pk_add_f32 v[4:5], v[60:61], v[4:5]
	v_pk_add_f32 v[104:105], v[118:119], v[0:1] op_sel_hi:[1,0] neg_lo:[0,1] neg_hi:[0,1]
	v_pk_add_f32 v[4:5], v[4:5], v[4:5] op_sel_hi:[0,1]
	v_mov_b32_e32 v60, v107
	v_mov_b32_e32 v61, v105
	v_pk_add_f32 v[102:103], v[120:121], v[0:1] op_sel_hi:[1,0] neg_lo:[0,1] neg_hi:[0,1]
; __device__ void ln_phase(const Ctx& p, const float* __restrict__ g, const float* __restrict__ bt, u16* __restrict__ xb,
;                          const float* res, const u16* __restrict__ yb) {
;     ...
;     q = wave_sum(q);
;     const float rs = rsqrtf(q * (1.f / DM) + 1e-5f);
; #pragma unroll
;     for (int k = 0; k < 16; ++k) {
;       if ((k & 3) == 0) asm volatile("" ::: "memory");
;       const int c = k * 256 + lane * 4;
;       const float4 gg = *(const float4*)(gl + c), bb = *(const float4*)(bl + c);
;       float4 o = make_float4(v[k].x * rs * gg.x + bb.x, v[k].y * rs * gg.y + bb.y, v[k].z * rs * gg.z + bb.z, v[k].w * rs * gg.w + bb.w);
;       if (!p.dry) *(float4*)(x + c) = o;
;       if (xb && !p.dry) { uint2 ov; ov.x = pack2(o.x, o.y); ov.y = pack2(o.z, o.w); *(uint2*)(xb + (long)row * DM + c) = ov; }
	v_mov_b32_e32 v58, v106
	v_mov_b32_e32 v59, v104
	v_pk_mul_f32 v[60:61], v[60:61], v[60:61]
	v_pk_add_f32 v[98:99], v[122:123], v[0:1] op_sel_hi:[1,0] neg_lo:[0,1] neg_hi:[0,1]
	v_mul_f32_e32 v4, v102, v102
	v_pk_fma_f32 v[58:59], v[58:59], v[58:59], v[60:61]
	v_pk_fma_f32 v[60:61], v[102:103], v[102:103], v[4:5] op_sel_hi:[1,1,0]
	v_mul_f32_e32 v4, v98, v98
	v_pk_add_f32 v[94:95], v[124:125], v[0:1] op_sel_hi:[1,0] neg_lo:[0,1] neg_hi:[0,1]
	v_pk_add_f32 v[92:93], v[126:127], v[0:1] op_sel_hi:[1,0] neg_lo:[0,1] neg_hi:[0,1]
	v_pk_add_f32 v[58:59], v[58:59], v[58:59] op_sel_hi:[0,1]
	v_pk_fma_f32 v[64:65], v[98:99], v[98:99], v[4:5] op_sel_hi:[1,1,0]
	v_pk_mul_f32 v[66:67], v[94:95], v[94:95]
	v_pk_mul_f32 v[70:71], v[92:93], v[92:93]
	v_mov_b32_e32 v60, v66
	v_mov_b32_e32 v64, v67
	v_mov_b32_e32 v58, v70
	v_mov_b32_e32 v4, v71
	v_pk_add_f32 v[60:61], v[60:61], v[64:65]
	v_pk_add_f32 v[4:5], v[58:59], v[4:5]
	v_pk_add_f32 v[84:85], v[128:129], v[0:1] op_sel_hi:[1,0] neg_lo:[0,1] neg_hi:[0,1]
	v_pk_add_f32 v[4:5], v[60:61], v[4:5]
	v_pk_add_f32 v[82:83], v[130:131], v[0:1] op_sel_hi:[1,0] neg_lo:[0,1] neg_hi:[0,1]
	v_pk_add_f32 v[4:5], v[4:5], v[4:5] op_sel_hi:[0,1]
	v_mov_b32_e32 v60, v85
	v_mov_b32_e32 v61, v83
	v_pk_add_f32 v[78:79], v[132:133], v[0:1] op_sel_hi:[1,0] neg_lo:[0,1] neg_hi:[0,1]
	v_mov_b32_e32 v58, v84
	v_mov_b32_e32 v59, v82
	v_pk_mul_f32 v[60:61], v[60:61], v[60:61]
	v_pk_add_f32 v[76:77], v[134:135], v[0:1] op_sel_hi:[1,0] neg_lo:[0,1] neg_hi:[0,1]
	v_mul_f32_e32 v4, v78, v78
	v_pk_fma_f32 v[58:59], v[58:59], v[58:59], v[60:61]
	v_pk_fma_f32 v[60:61], v[78:79], v[78:79], v[4:5] op_sel_hi:[1,1,0]
	v_mul_f32_e32 v4, v76, v76
	v_pk_add_f32 v[72:73], v[142:143], v[0:1] op_sel_hi:[1,0] neg_lo:[0,1] neg_hi:[0,1]
	v_pk_add_f32 v[70:71], v[144:145], v[0:1] op_sel_hi:[1,0] neg_lo:[0,1] neg_hi:[0,1]
	v_pk_add_f32 v[58:59], v[58:59], v[58:59] op_sel_hi:[0,1]
	v_pk_fma_f32 v[64:65], v[76:77], v[76:77], v[4:5] op_sel_hi:[1,1,0]
	v_pk_mul_f32 v[66:67], v[72:73], v[72:73]
	v_pk_mul_f32 v[116:117], v[70:71], v[70:71]
	v_mov_b32_e32 v60, v66
	v_mov_b32_e32 v64, v67
	v_mov_b32_e32 v58, v116
	v_mov_b32_e32 v4, v117
	v_pk_add_f32 v[60:61], v[60:61], v[64:65]
	v_pk_add_f32 v[4:5], v[58:59], v[4:5]
	v_pk_add_f32 v[66:67], v[146:147], v[0:1] op_sel_hi:[1,0] neg_lo:[0,1] neg_hi:[0,1]
	v_pk_add_f32 v[64:65], v[148:149], v[0:1] op_sel_hi:[1,0] neg_lo:[0,1] neg_hi:[0,1]
	v_pk_add_f32 v[4:5], v[60:61], v[4:5]
	v_mov_b32_e32 v58, v67
	v_mov_b32_e32 v59, v65
	v_pk_add_f32 v[116:117], v[4:5], v[4:5] op_sel_hi:[0,1]
	v_mov_b32_e32 v4, v66
	v_mov_b32_e32 v5, v64
	v_pk_mul_f32 v[58:59], v[58:59], v[58:59]
	v_pk_add_f32 v[60:61], v[150:151], v[0:1] op_sel_hi:[1,0] neg_lo:[0,1] neg_hi:[0,1]
	v_pk_fma_f32 v[4:5], v[4:5], v[4:5], v[58:59]
	v_pk_add_f32 v[58:59], v[152:153], v[0:1] op_sel_hi:[1,0] neg_lo:[0,1] neg_hi:[0,1]
	v_pk_add_f32 v[118:119], v[4:5], v[4:5] op_sel_hi:[0,1]
	v_mul_f32_e32 v4, v60, v60
	v_pk_fma_f32 v[120:121], v[60:61], v[60:61], v[4:5] op_sel_hi:[1,1,0]
	v_mul_f32_e32 v4, v58, v58
	v_pk_fma_f32 v[122:123], v[58:59], v[58:59], v[4:5] op_sel_hi:[1,1,0]
	v_pk_add_f32 v[4:5], v[2:3], v[0:1] op_sel_hi:[1,0] neg_lo:[0,1] neg_hi:[0,1]
	v_pk_add_f32 v[2:3], v[180:181], v[0:1] op_sel_hi:[1,0] neg_lo:[0,1] neg_hi:[0,1]
	v_pk_mul_f32 v[124:125], v[4:5], v[4:5]
	v_pk_mul_f32 v[126:127], v[2:3], v[2:3]
	v_mov_b32_e32 v120, v124
	v_mov_b32_e32 v122, v125
	v_mov_b32_e32 v118, v126
	v_mov_b32_e32 v116, v127
	v_pk_add_f32 v[120:121], v[120:121], v[122:123]
	v_pk_add_f32 v[116:117], v[118:119], v[116:117]
	s_nop 0
	v_pk_add_f32 v[116:117], v[120:121], v[116:117]
	s_nop 0
	v_add_f32_e32 v0, v116, v117
	ds_bpermute_b32 v7, v9, v0
	ds_read_b128 v[116:119], v25
	ds_read_b128 v[120:123], v25 offset:16384
	s_waitcnt lgkmcnt(2)
	v_add_f32_e32 v0, v0, v7
	ds_bpermute_b32 v7, v15, v0
	s_waitcnt lgkmcnt(0)
	v_add_f32_e32 v0, v0, v7
	ds_bpermute_b32 v7, v17, v0
	s_waitcnt lgkmcnt(0)
	v_add_f32_e32 v0, v0, v7
	ds_bpermute_b32 v7, v19, v0
	s_waitcnt lgkmcnt(0)
	v_add_f32_e32 v0, v0, v7
	ds_bpermute_b32 v7, v21, v0
	s_waitcnt lgkmcnt(0)
	v_add_f32_e32 v0, v0, v7
	ds_bpermute_b32 v7, v23, v0
	s_waitcnt lgkmcnt(0)
	v_add_f32_e32 v0, v0, v7
	v_fmamk_f32 v0, v0, 0x39800000, v193
	v_cmp_gt_f32_e32 vcc, s48, v0
	v_mul_f32_e32 v7, 0x4b800000, v0
	s_nop 0
	v_cndmask_b32_e32 v0, v0, v7, vcc
	v_rsq_f32_e32 v0, v0
	s_nop 0
	v_mul_f32_e32 v7, 0x45800000, v0
	v_cndmask_b32_e32 v0, v0, v7, vcc
	v_pk_mul_f32 v[124:125], v[178:179], v[0:1] op_sel_hi:[1,0]
	v_pk_mul_f32 v[106:107], v[106:107], v[0:1] op_sel_hi:[1,0]
	v_pk_fma_f32 v[116:117], v[116:117], v[124:125], v[120:121]
	v_pk_mul_f32 v[120:121], v[176:177], v[0:1] op_sel_hi:[1,0]
	v_pk_mul_f32 v[124:125], v[174:175], v[0:1] op_sel_hi:[1,0]
	v_pk_fma_f32 v[118:119], v[118:119], v[120:121], v[122:123]
	global_store_dwordx4 v[42:43], v[116:119], off
	v_pk_mul_f32 v[4:5], v[4:5], v[0:1] op_sel_hi:[1,0]
	v_pk_mul_f32 v[2:3], v[2:3], v[0:1] op_sel_hi:[1,0]
	v_cvt_pk_bf16_f32 v116, v116, v117
	v_cvt_pk_bf16_f32 v117, v118, v119
	global_store_dwordx2 v[40:41], v[116:117], off
	ds_read_b128 v[116:119], v25 offset:1024
	ds_read_b128 v[120:123], v25 offset:17408
	v_cmp_lt_i32_e32 vcc, s10, v6
	s_or_b64 s[6:7], vcc, s[6:7]
	s_waitcnt lgkmcnt(0)
	v_pk_fma_f32 v[116:117], v[116:117], v[124:125], v[120:121]
	v_pk_mul_f32 v[120:121], v[172:173], v[0:1] op_sel_hi:[1,0]
	v_pk_mul_f32 v[124:125], v[170:171], v[0:1] op_sel_hi:[1,0]
	v_pk_fma_f32 v[118:119], v[118:119], v[120:121], v[122:123]
	global_store_dwordx4 v[42:43], v[116:119], off offset:1024
	s_nop 1
	v_cvt_pk_bf16_f32 v116, v116, v117
	v_cvt_pk_bf16_f32 v117, v118, v119
	global_store_dwordx2 v[40:41], v[116:117], off offset:512
	ds_read_b128 v[116:119], v25 offset:2048
	ds_read_b128 v[120:123], v25 offset:18432
	s_waitcnt lgkmcnt(0)
; __device__ void ln_phase(const Ctx& p, const float* __restrict__ g, const float* __restrict__ bt, u16* __restrict__ xb,
;                          const float* res, const u16* __restrict__ yb) {
;     ...
; #pragma unroll
;     for (int k = 0; k < 16; ++k) {
;       if ((k & 3) == 0) asm volatile("" ::: "memory");
;       const int c = k * 256 + lane * 4;
;       const float4 gg = *(const float4*)(gl + c), bb = *(const float4*)(bl + c);
;       float4 o = make_float4(v[k].x * rs * gg.x + bb.x, v[k].y * rs * gg.y + bb.y, v[k].z * rs * gg.z + bb.z, v[k].w * rs * gg.w + bb.w);
;       if (!p.dry) *(float4*)(x + c) = o;
;       if (xb && !p.dry) { uint2 ov; ov.x = pack2(o.x, o.y); ov.y = pack2(o.z, o.w); *(uint2*)(xb + (long)row * DM + c) = ov; }
;     }
	v_pk_fma_f32 v[116:117], v[116:117], v[124:125], v[120:121]
	v_pk_mul_f32 v[120:121], v[168:169], v[0:1] op_sel_hi:[1,0]
	v_pk_mul_f32 v[124:125], v[166:167], v[0:1] op_sel_hi:[1,0]
	v_pk_fma_f32 v[118:119], v[118:119], v[120:121], v[122:123]
	global_store_dwordx4 v[42:43], v[116:119], off offset:2048
	s_nop 1
	v_cvt_pk_bf16_f32 v116, v116, v117
	v_cvt_pk_bf16_f32 v117, v118, v119
	global_store_dwordx2 v[40:41], v[116:117], off offset:1024
	ds_read_b128 v[116:119], v25 offset:3072
	ds_read_b128 v[120:123], v25 offset:19456
	s_waitcnt lgkmcnt(0)
	v_pk_fma_f32 v[116:117], v[124:125], v[116:117], v[120:121]
	v_pk_mul_f32 v[120:121], v[164:165], v[0:1] op_sel_hi:[1,0]
	s_nop 0
	v_pk_fma_f32 v[118:119], v[120:121], v[118:119], v[122:123]
	global_store_dwordx4 v[42:43], v[116:119], off offset:3072
	v_cvt_pk_bf16_f32 v42, v116, v117
	v_cvt_pk_bf16_f32 v43, v118, v119
	global_store_dwordx2 v[40:41], v[42:43], off offset:1536
	ds_read_b128 v[116:119], v25 offset:4096
	ds_read_b128 v[120:123], v25 offset:20480
	v_pk_mul_f32 v[42:43], v[162:163], v[0:1] op_sel_hi:[1,0]
	s_waitcnt lgkmcnt(0)
	v_pk_fma_f32 v[116:117], v[42:43], v[116:117], v[120:121]
	v_pk_mul_f32 v[42:43], v[160:161], v[0:1] op_sel_hi:[1,0]
	v_pk_mul_f32 v[120:121], v[158:159], v[0:1] op_sel_hi:[1,0]
	v_pk_fma_f32 v[118:119], v[42:43], v[118:119], v[122:123]
	v_cvt_pk_bf16_f32 v42, v116, v117
	v_cvt_pk_bf16_f32 v43, v118, v119
	global_store_dwordx4 v[44:45], v[116:119], off
	global_store_dwordx2 v[40:41], v[42:43], off offset:2048
	ds_read_b128 v[42:45], v25 offset:5120
	ds_read_b128 v[116:119], v25 offset:21504
	s_waitcnt lgkmcnt(0)
	v_pk_fma_f32 v[42:43], v[120:121], v[42:43], v[116:117]
	v_pk_mul_f32 v[116:117], v[156:157], v[0:1] op_sel_hi:[1,0]
	s_nop 0
	v_pk_fma_f32 v[44:45], v[116:117], v[44:45], v[118:119]
	global_store_dwordx4 v[46:47], v[42:45], off
	v_pk_mul_f32 v[46:47], v[154:155], v[0:1] op_sel_hi:[1,0]
	s_nop 0
	v_cvt_pk_bf16_f32 v42, v42, v43
	v_cvt_pk_bf16_f32 v43, v44, v45
	global_store_dwordx2 v[40:41], v[42:43], off offset:2560
	ds_read_b128 v[42:45], v25 offset:6144
	ds_read_b128 v[116:119], v25 offset:22528
	s_waitcnt lgkmcnt(0)
	v_pk_fma_f32 v[42:43], v[46:47], v[42:43], v[116:117]
	v_pk_mul_f32 v[46:47], v[114:115], v[0:1] op_sel_hi:[1,0]
	s_nop 0
	v_pk_fma_f32 v[44:45], v[46:47], v[44:45], v[118:119]
	global_store_dwordx4 v[48:49], v[42:45], off
	s_nop 1
	v_cvt_pk_bf16_f32 v42, v42, v43
	v_cvt_pk_bf16_f32 v43, v44, v45
	global_store_dwordx2 v[40:41], v[42:43], off offset:3072
	ds_read_b128 v[42:45], v25 offset:7168
	ds_read_b128 v[46:49], v25 offset:23552
	s_waitcnt lgkmcnt(0)
	v_pk_fma_f32 v[42:43], v[106:107], v[42:43], v[46:47]
	v_pk_mul_f32 v[46:47], v[104:105], v[0:1] op_sel_hi:[1,0]
	s_nop 0
	v_pk_fma_f32 v[44:45], v[46:47], v[44:45], v[48:49]
	global_store_dwordx4 v[50:51], v[42:45], off
	v_pk_mul_f32 v[48:49], v[102:103], v[0:1] op_sel_hi:[1,0]
	s_nop 0
	v_cvt_pk_bf16_f32 v42, v42, v43
	v_cvt_pk_bf16_f32 v43, v44, v45
	global_store_dwordx2 v[40:41], v[42:43], off offset:3584
	ds_read_b128 v[40:43], v25 offset:8192
	ds_read_b128 v[44:47], v25 offset:24576
	s_waitcnt lgkmcnt(0)
	v_pk_fma_f32 v[40:41], v[48:49], v[40:41], v[44:45]
	v_pk_mul_f32 v[44:45], v[98:99], v[0:1] op_sel_hi:[1,0]
	v_pk_mul_f32 v[48:49], v[94:95], v[0:1] op_sel_hi:[1,0]
	v_pk_fma_f32 v[42:43], v[44:45], v[42:43], v[46:47]
	global_store_dwordx4 v[52:53], v[40:43], off
	s_nop 1
	v_cvt_pk_bf16_f32 v40, v40, v41
	v_cvt_pk_bf16_f32 v41, v42, v43
	global_store_dwordx2 v[62:63], v[40:41], off
	ds_read_b128 v[40:43], v25 offset:9216
	ds_read_b128 v[44:47], v25 offset:25600
	s_waitcnt lgkmcnt(0)
	v_pk_fma_f32 v[40:41], v[48:49], v[40:41], v[44:45]
	v_pk_mul_f32 v[44:45], v[92:93], v[0:1] op_sel_hi:[1,0]
	v_pk_mul_f32 v[48:49], v[84:85], v[0:1] op_sel_hi:[1,0]
	v_pk_fma_f32 v[42:43], v[44:45], v[42:43], v[46:47]
	global_store_dwordx4 v[54:55], v[40:43], off
	s_nop 1
	v_cvt_pk_bf16_f32 v40, v40, v41
	v_cvt_pk_bf16_f32 v41, v42, v43
	global_store_dwordx2 v[68:69], v[40:41], off
	ds_read_b128 v[40:43], v25 offset:10240
	ds_read_b128 v[44:47], v25 offset:26624
	s_waitcnt lgkmcnt(0)
	v_pk_fma_f32 v[40:41], v[48:49], v[40:41], v[44:45]
	v_pk_mul_f32 v[44:45], v[82:83], v[0:1] op_sel_hi:[1,0]
	v_pk_mul_f32 v[48:49], v[78:79], v[0:1] op_sel_hi:[1,0]
	v_pk_fma_f32 v[42:43], v[44:45], v[42:43], v[46:47]
	global_store_dwordx4 v[56:57], v[40:43], off
	s_nop 1
	v_cvt_pk_bf16_f32 v40, v40, v41
	v_cvt_pk_bf16_f32 v41, v42, v43
	global_store_dwordx2 v[80:81], v[40:41], off
	ds_read_b128 v[40:43], v25 offset:11264
	ds_read_b128 v[44:47], v25 offset:27648
	s_waitcnt lgkmcnt(0)
	v_pk_fma_f32 v[40:41], v[48:49], v[40:41], v[44:45]
	v_pk_mul_f32 v[44:45], v[76:77], v[0:1] op_sel_hi:[1,0]
	v_pk_mul_f32 v[48:49], v[72:73], v[0:1] op_sel_hi:[1,0]
	v_pk_fma_f32 v[42:43], v[44:45], v[42:43], v[46:47]
	global_store_dwordx4 v[74:75], v[40:43], off
	s_nop 1
	v_cvt_pk_bf16_f32 v40, v40, v41
	v_cvt_pk_bf16_f32 v41, v42, v43
	global_store_dwordx2 v[90:91], v[40:41], off
	ds_read_b128 v[40:43], v25 offset:12288
	ds_read_b128 v[44:47], v25 offset:28672
	s_waitcnt lgkmcnt(0)
	v_pk_fma_f32 v[40:41], v[48:49], v[40:41], v[44:45]
	v_pk_mul_f32 v[44:45], v[70:71], v[0:1] op_sel_hi:[1,0]
	v_pk_mul_f32 v[48:49], v[66:67], v[0:1] op_sel_hi:[1,0]
	v_pk_fma_f32 v[42:43], v[44:45], v[42:43], v[46:47]
	global_store_dwordx4 v[86:87], v[40:43], off
	s_nop 1
	v_cvt_pk_bf16_f32 v40, v40, v41
	v_cvt_pk_bf16_f32 v41, v42, v43
	global_store_dwordx2 v[96:97], v[40:41], off
	ds_read_b128 v[40:43], v25 offset:13312
	ds_read_b128 v[44:47], v25 offset:29696
	s_waitcnt lgkmcnt(0)
	v_pk_fma_f32 v[40:41], v[48:49], v[40:41], v[44:45]
	v_pk_mul_f32 v[44:45], v[64:65], v[0:1] op_sel_hi:[1,0]
	v_pk_mul_f32 v[48:49], v[60:61], v[0:1] op_sel_hi:[1,0]
	v_pk_fma_f32 v[42:43], v[44:45], v[42:43], v[46:47]
	global_store_dwordx4 v[88:89], v[40:43], off
	s_nop 1
	v_cvt_pk_bf16_f32 v40, v40, v41
	v_cvt_pk_bf16_f32 v41, v42, v43
	global_store_dwordx2 v[108:109], v[40:41], off
	ds_read_b128 v[40:43], v25 offset:14336
	ds_read_b128 v[44:47], v25 offset:30720
	s_waitcnt lgkmcnt(0)
	v_pk_fma_f32 v[40:41], v[48:49], v[40:41], v[44:45]
	v_pk_mul_f32 v[44:45], v[58:59], v[0:1] op_sel_hi:[1,0]
	v_lshlrev_b32_e32 v0, 1, v28
	v_pk_fma_f32 v[42:43], v[44:45], v[42:43], v[46:47]
	global_store_dwordx4 v[100:101], v[40:43], off
	s_nop 1
	v_cvt_pk_bf16_f32 v40, v40, v41
	v_cvt_pk_bf16_f32 v41, v42, v43
	global_store_dwordx2 v[112:113], v[40:41], off
	ds_read_b128 v[40:43], v25 offset:15360
	ds_read_b128 v[44:47], v25 offset:31744
	s_waitcnt lgkmcnt(0)
	v_pk_fma_f32 v[40:41], v[4:5], v[40:41], v[44:45]
	v_pk_fma_f32 v[42:43], v[2:3], v[42:43], v[46:47]
	v_cvt_pk_bf16_f32 v2, v40, v41
	v_cvt_pk_bf16_f32 v3, v42, v43
	v_lshl_add_u64 v[4:5], v[38:39], 0, v[0:1]
	global_store_dwordx4 v[110:111], v[40:43], off
	global_store_dwordx2 v[4:5], v[2:3], off
	s_andn2_b64 exec, exec, s[6:7]
	s_cbranch_execnz .LBB0_175
; __device__ __forceinline__ int ltid() { int t = threadIdx.x; asm volatile("" : "+v"(t)); return t; }
;   const int tid = ltid();
;   const int kg = tid & 7, ng = tid >> 3;
;   const int tn = Nd / 256, tk = R / 64;
;   if (nblk == 0) nblk = gridDim.x;
;   if ((int)blockIdx.x < blk0 || (int)blockIdx.x >= blk0 + nblk) return;
;   for (int t = (int)blockIdx.x - blk0; t < tn * tk; t += nblk) {
;     const int n0 = (t / tk) * 256 + ng * 4, k0 = (t % tk) * 64 + kg * 8;
;     int c = n0;
;     if (mode == 1) c = (n0 < 6144) ? n0 : (n0 < 15360 ? n0 + 16 : (n0 < 15376 ? 6144 + (n0 - 15360) : -1));
;     float4 v[8];
; #pragma unroll
;     for (int r = 0; r < 8; ++r) v[r] = (c >= 0) ? *(const float4*)(src + (long)(k0 + r) * C + c) : make_float4(0.f, 0.f, 0.f, 0.f);
;     uint4 o;
;     o.x = pack2(v[0].x, v[1].x); o.y = pack2(v[2].x, v[3].x); o.z = pack2(v[4].x, v[5].x); o.w = pack2(v[6].x, v[7].x);
;     *(uint4*)(dst + (long)(n0 + 0) * R + k0) = o;
;     o.x = pack2(v[0].y, v[1].y); o.y = pack2(v[2].y, v[3].y); o.z = pack2(v[4].y, v[5].y); o.w = pack2(v[6].y, v[7].y);
;     *(uint4*)(dst + (long)(n0 + 1) * R + k0) = o;
;     o.x = pack2(v[0].z, v[1].z); o.y = pack2(v[2].z, v[3].z); o.z = pack2(v[4].z, v[5].z); o.w = pack2(v[6].z, v[7].z);
;     *(uint4*)(dst + (long)(n0 + 2) * R + k0) = o;
;     o.x = pack2(v[0].w, v[1].w); o.y = pack2(v[2].w, v[3].w); o.z = pack2(v[4].w, v[5].w); o.w = pack2(v[6].w, v[7].w);
;     *(uint4*)(dst + (long)(n0 + 3) * R + k0) = o;
;   }
.LBB0_176:
	s_movk_i32 s86, 0x1000
	s_or_b64 exec, exec, s[0:1]
	v_mov_b32_e32 v0, s66
	s_waitcnt vmcnt(0)
	v_add_co_u32_e32 v2, vcc, 0x4375c000, v0
	v_mov_b32_e32 v0, s67
	s_nop 0
	v_addc_co_u32_e32 v3, vcc, 0, v0, vcc
	s_waitcnt lgkmcnt(0)
	s_barrier
	global_load_dwordx2 v[34:35], v[2:3], off offset:104
	v_readlane_b32 s4, v253, 0
	v_mov_b32_e32 v0, v139
	v_readlane_b32 s5, v253, 1
	s_load_dword s0, s[4:5], 0x10
	s_nop 0
	s_load_dword s4, s[4:5], 0x0
	s_waitcnt lgkmcnt(0)
	s_lshr_b32 s0, s0, 16
	s_cmp_lg_u32 s0, 0
	s_cselect_b64 s[0:1], -1, 0
	s_cmp_lg_u64 s[0:1], 0
	s_addc_u32 s8, s4, 0
	s_cmp_lt_i32 s63, s8
	v_readlane_b32 s4, v253, 13
	s_cselect_b64 s[0:1], -1, 0
	v_readlane_b32 s5, v253, 14
	s_and_b64 s[0:1], s[4:5], s[0:1]
	s_andn2_b64 vcc, exec, s[0:1]
	s_cbranch_vccnz .LBB0_195
	v_ashrrev_i32_e32 v2, 1, v0
	s_mul_i32 s0, s63, 0x110000
	v_and_b32_e32 v40, -4, v2
	v_lshlrev_b32_e32 v2, 3, v0
	v_and_b32_e32 v0, 7, v0
	v_mov_b32_e32 v3, s0
	s_mov_b32 s0, 0x22000
	s_add_u32 s4, s66, 0x8000000
	v_and_b32_e32 v2, 56, v2
	v_mad_u32_u24 v41, v0, s0, v3
	v_readlane_b32 s0, v252, 14
	s_addc_u32 s5, s67, 0
	s_lshl_b32 s9, s8, 6
	v_add_u32_e32 v42, s0, v2
	s_mov_b32 s10, s63
	s_branch .LBB0_179
.LBB0_178:
	s_or_b64 exec, exec, s[6:7]
	s_lshl_b32 s0, s11, 12
	v_subrev_u32_e32 v44, s0, v42
	v_ashrrev_i32_e32 v47, 31, v0
	v_mov_b32_e32 v46, v0
	v_lshlrev_b64 v[46:47], 13, v[46:47]
	v_ashrrev_i32_e32 v45, 31, v44
	v_lshl_add_u64 v[46:47], s[4:5], 0, v[46:47]
	v_lshlrev_b64 v[44:45], 1, v[44:45]
	s_waitcnt vmcnt(0) lgkmcnt(0)
	v_cvt_pk_bf16_f32 v36, v2, v6
	v_cvt_pk_bf16_f32 v37, v14, v10
	v_cvt_pk_bf16_f32 v38, v22, v18
	v_cvt_pk_bf16_f32 v39, v30, v26
	v_lshl_add_u64 v[46:47], v[46:47], 0, v[44:45]
	v_or_b32_e32 v2, 1, v0
	global_store_dwordx4 v[46:47], v[36:39], off
	v_or_b32_e32 v6, 3, v0
	s_add_i32 s10, s10, s8
	v_cvt_pk_bf16_f32 v36, v3, v7
	v_ashrrev_i32_e32 v3, 31, v2
	v_lshlrev_b64 v[2:3], 13, v[2:3]
	v_lshl_add_u64 v[2:3], s[4:5], 0, v[2:3]
	v_cvt_pk_bf16_f32 v37, v15, v11
	v_cvt_pk_bf16_f32 v38, v23, v19
	v_cvt_pk_bf16_f32 v39, v31, v27
	v_lshl_add_u64 v[2:3], v[2:3], 0, v[44:45]
	global_store_dwordx4 v[2:3], v[36:39], off
	v_or_b32_e32 v2, 2, v0
	v_ashrrev_i32_e32 v3, 31, v2
	v_lshlrev_b64 v[2:3], 13, v[2:3]
	v_ashrrev_i32_e32 v7, 31, v6
	v_lshl_add_u64 v[2:3], s[4:5], 0, v[2:3]
	v_lshlrev_b64 v[6:7], 13, v[6:7]
	v_cvt_pk_bf16_f32 v36, v4, v8
	v_cvt_pk_bf16_f32 v37, v16, v12
	v_cvt_pk_bf16_f32 v38, v24, v20
	v_cvt_pk_bf16_f32 v39, v32, v28
	v_lshl_add_u64 v[2:3], v[2:3], 0, v[44:45]
	v_lshl_add_u64 v[6:7], s[4:5], 0, v[6:7]
	s_mul_i32 s0, s8, 0x110000
	global_store_dwordx4 v[2:3], v[36:39], off
	v_cvt_pk_bf16_f32 v2, v5, v9
	v_cvt_pk_bf16_f32 v3, v17, v13
	v_cvt_pk_bf16_f32 v4, v25, v21
	v_cvt_pk_bf16_f32 v5, v33, v29
	v_lshl_add_u64 v[6:7], v[6:7], 0, v[44:45]
	v_add_u32_e32 v41, s0, v41
	s_cmpk_gt_i32 s10, 0x10ff
	v_add_u32_e32 v42, s9, v42
	global_store_dwordx4 v[6:7], v[2:5], off
	s_cbranch_scc1 .LBB0_195
.LBB0_179:
	s_ashr_i32 s0, s10, 31
	s_lshr_b32 s0, s0, 26
	s_add_i32 s0, s10, s0
	s_ashr_i32 s11, s0, 6
	v_lshl_add_u32 v0, s11, 8, v40
	s_mul_i32 s6, s11, 0xfbc00000
	v_cmp_lt_i32_e64 s[0:1], -1, v0
	s_waitcnt vmcnt(0)
	v_lshl_add_u64 v[36:37], v[0:1], 2, v[34:35]
	v_mov_b32_e32 v8, 0
	v_add_u32_e32 v38, s6, v41
	v_mov_b32_e32 v4, 0
	v_mov_b32_e32 v5, 0
	v_mov_b32_e32 v2, 0
	v_mov_b32_e32 v3, 0
	s_and_saveexec_b64 s[6:7], s[0:1]
	s_cbranch_execz .LBB0_181
	v_ashrrev_i32_e32 v39, 31, v38
	v_lshl_add_u64 v[2:3], v[38:39], 2, v[36:37]
	global_load_dwordx4 v[2:5], v[2:3], off
.LBB0_181:
	s_or_b64 exec, exec, s[6:7]
	v_mov_b32_e32 v9, 0
	v_mov_b32_e32 v6, 0
	v_mov_b32_e32 v7, 0
	s_and_saveexec_b64 s[6:7], s[0:1]
	s_cbranch_execz .LBB0_183
	v_ashrrev_i32_e32 v39, 31, v38
	v_lshl_add_u64 v[6:7], v[38:39], 2, v[36:37]
	v_add_co_u32_e32 v6, vcc, 0x11000, v6
	s_nop 1
	v_addc_co_u32_e32 v7, vcc, 0, v7, vcc
	global_load_dwordx4 v[6:9], v[6:7], off
.LBB0_183:
	s_or_b64 exec, exec, s[6:7]
	v_mov_b32_e32 v12, 0
	v_mov_b32_e32 v16, 0
	v_mov_b32_e32 v17, 0
	v_mov_b32_e32 v14, 0
	v_mov_b32_e32 v15, 0
	s_and_saveexec_b64 s[6:7], s[0:1]
	s_cbranch_execz .LBB0_185
	v_ashrrev_i32_e32 v39, 31, v38
	v_lshl_add_u64 v[10:11], v[38:39], 2, v[36:37]
	v_add_co_u32_e32 v10, vcc, 0x22000, v10
	s_nop 1
	v_addc_co_u32_e32 v11, vcc, 0, v11, vcc
	global_load_dwordx4 v[14:17], v[10:11], off
.LBB0_185:
	s_or_b64 exec, exec, s[6:7]
	v_mov_b32_e32 v13, 0
	v_mov_b32_e32 v10, 0
	v_mov_b32_e32 v11, 0
	s_and_saveexec_b64 s[6:7], s[0:1]
	s_cbranch_execz .LBB0_187
	v_ashrrev_i32_e32 v39, 31, v38
	v_lshl_add_u64 v[10:11], v[38:39], 2, v[36:37]
	v_add_co_u32_e32 v10, vcc, 0x33000, v10
	s_nop 1
	v_addc_co_u32_e32 v11, vcc, 0, v11, vcc
	global_load_dwordx4 v[10:13], v[10:11], off
.LBB0_187:
	s_or_b64 exec, exec, s[6:7]
	v_mov_b32_e32 v20, 0
	v_mov_b32_e32 v24, 0
	v_mov_b32_e32 v25, 0
	v_mov_b32_e32 v22, 0
	v_mov_b32_e32 v23, 0
	s_and_saveexec_b64 s[6:7], s[0:1]
	s_cbranch_execz .LBB0_189
	v_ashrrev_i32_e32 v39, 31, v38
	v_lshl_add_u64 v[18:19], v[38:39], 2, v[36:37]
	v_add_co_u32_e32 v18, vcc, 0x44000, v18
	s_nop 1
	v_addc_co_u32_e32 v19, vcc, 0, v19, vcc
	global_load_dwordx4 v[22:25], v[18:19], off
.LBB0_189:
	s_or_b64 exec, exec, s[6:7]
	v_mov_b32_e32 v21, 0
	v_mov_b32_e32 v18, 0
	v_mov_b32_e32 v19, 0
	s_and_saveexec_b64 s[6:7], s[0:1]
	s_cbranch_execz .LBB0_191
	v_ashrrev_i32_e32 v39, 31, v38
	v_lshl_add_u64 v[18:19], v[38:39], 2, v[36:37]
	v_add_co_u32_e32 v18, vcc, 0x55000, v18
	s_nop 1
	v_addc_co_u32_e32 v19, vcc, 0, v19, vcc
	global_load_dwordx4 v[18:21], v[18:19], off
.LBB0_191:
	s_or_b64 exec, exec, s[6:7]
	v_mov_b32_e32 v28, 0
	v_mov_b32_e32 v32, 0
	v_mov_b32_e32 v33, 0
	v_mov_b32_e32 v30, 0
	v_mov_b32_e32 v31, 0
	s_and_saveexec_b64 s[6:7], s[0:1]
	s_cbranch_execz .LBB0_193
	v_ashrrev_i32_e32 v39, 31, v38
	v_lshl_add_u64 v[26:27], v[38:39], 2, v[36:37]
	v_add_co_u32_e32 v26, vcc, 0x66000, v26
	s_nop 1
	v_addc_co_u32_e32 v27, vcc, 0, v27, vcc
	global_load_dwordx4 v[30:33], v[26:27], off
.LBB0_193:
	s_or_b64 exec, exec, s[6:7]
	v_mov_b32_e32 v29, 0
	v_mov_b32_e32 v26, 0
	v_mov_b32_e32 v27, 0
	s_and_saveexec_b64 s[6:7], s[0:1]
	s_cbranch_execz .LBB0_178
	v_ashrrev_i32_e32 v39, 31, v38
	v_lshl_add_u64 v[26:27], v[38:39], 2, v[36:37]
	v_add_co_u32_e32 v26, vcc, 0x77000, v26
	s_nop 1
	v_addc_co_u32_e32 v27, vcc, 0, v27, vcc
	global_load_dwordx4 v[26:29], v[26:27], off
	s_branch .LBB0_178

; __device__ __forceinline__ int ltid() { int t = threadIdx.x; asm volatile("" : "+v"(t)); return t; }
; template <int AI>
; __device__ __forceinline__ void dump_half(const f32x4 (&acc)[2][2][4][2], float* stage) {
;   const int wid = ltid() >> 6, lane = ltid() & 63, wr = wid >> 2, wc = wid & 3, fr = lane & 15, fq = lane >> 4;
; #pragma unroll
;   for (int bj = 0; bj < 2; ++bj)
; #pragma unroll
;     for (int m = 0; m < 4; ++m)
; #pragma unroll
;       for (int n = 0; n < 2; ++n) {
;         const int r0 = wr * 64 + m * 16 + fq * 4, c = bj * 128 + wc * 32 + n * 16 + fr;
; #pragma unroll
;         for (int j = 0; j < 4; ++j) stage[(r0 + j) * SP + c] = acc[AI][bj][m][n][j];
;       }
; }
; __device__ __forceinline__ void emit_rm(const float* stage, u16* dst, long ld, const float* rs) {
;   const int tid = ltid(), c4 = (tid & 31) * 4, rr = tid >> 5;
; #pragma unroll 1
;   for (int ps = 0; ps < 8; ++ps) {
;     const int r = ps * 16 + rr;
;     const float* s = stage + r * SP + c4;
;     const float4 a = *(const float4*)s, b = *(const float4*)(s + 128);
;     const float f = rs ? rs[r] : 1.f;
;     uint2 o0, o1;
;     o0.x = pack2(a.x * f, a.y * f); o0.y = pack2(a.z * f, a.w * f);
;     o1.x = pack2(b.x * f, b.y * f); o1.y = pack2(b.z * f, b.w * f);
;     *(uint2*)(dst + (long)r * ld + c4) = o0;
;     *(uint2*)(dst + (long)r * ld + 128 + c4) = o1;
;   }
; }
.LBB0_208:
	ds_read_b128 v[68:71], v0
	ds_read_b128 v[72:75], v0 offset:512
	s_mov_b32 s13, 0x12c00000
	v_add_u32_e32 v0, 0x4100, v0
	s_waitcnt lgkmcnt(0)
	v_cvt_pk_bf16_f32 v68, v68, v69
	v_cvt_pk_bf16_f32 v69, v70, v71
	s_waitcnt lgkmcnt(0)
	v_cvt_pk_bf16_f32 v70, v72, v73
	v_lshl_add_u64 v[72:73], v[2:3], 0, s[6:7]
	s_add_u32 s6, s6, 0x20000
	v_add_co_u32_e32 v72, vcc, s13, v72
	s_addc_u32 s7, s7, 0
	s_nop 0
	v_addc_co_u32_e32 v73, vcc, 0, v73, vcc
	s_cmp_lg_u32 s6, 0x100000
	v_cvt_pk_bf16_f32 v71, v74, v75
	global_store_dwordx2 v[72:73], v[68:69], off
	global_store_dwordx2 v[72:73], v[70:71], off offset:256
	s_cbranch_scc1 .LBB0_208
	v_mov_b32_e32 v0, v139
	v_mov_b32_e32 v2, v139
	s_waitcnt lgkmcnt(0)
	s_barrier
	s_nop 0
	v_lshrrev_b32_e32 v68, 2, v0
	v_and_b32_e32 v3, 15, v2
	v_and_b32_e32 v68, 0xfffffc0, v68
	v_lshrrev_b32_e32 v2, 2, v2
	v_lshlrev_b32_e32 v0, 1, v0
	v_and_or_b32 v2, v2, 12, v68
	v_and_b32_e32 v0, 0x180, v0
	v_add_u32_e32 v0, 16, v0
	v_lshlrev_b32_e32 v3, 2, v3
	v_mul_lo_u32 v2, v2, s81
	v_add3_u32 v0, v0, v3, v2
	v_add_u32_e32 v2, 0x400, v0
	ds_write2_b32 v2, v65, v61 offset0:4 offset1:20
	v_add_u32_e32 v61, 0x4000, v0
	ds_write2_b32 v61, v56, v52 offset0:64 offset1:80
	v_add_u32_e32 v52, 0x4400, v0
	ds_write2_b32 v52, v57, v53 offset0:68 offset1:84
	v_add_u32_e32 v53, 0x4800, v0
	ds_write2_b32 v53, v58, v54 offset0:72 offset1:88
	v_add_u32_e32 v54, 0x4c00, v0
	ds_write2_b32 v54, v59, v55 offset0:76 offset1:92
	v_add_u32_e32 v55, 0x8000, v0
	ds_write2_b32 v55, v48, v44 offset0:128 offset1:144
	v_add_u32_e32 v44, 0x8400, v0
	ds_write2_b32 v44, v49, v45 offset0:132 offset1:148
	v_add_u32_e32 v45, 0x8800, v0
	ds_write2_b32 v45, v50, v46 offset0:136 offset1:152
	v_add_u32_e32 v46, 0x8c00, v0
	ds_write2_b32 v46, v51, v47 offset0:140 offset1:156
	v_add_u32_e32 v47, 0xc000, v0
	ds_write2_b32 v47, v40, v36 offset0:192 offset1:208
	v_add_u32_e32 v36, 0xc400, v0
	ds_write2_b32 v36, v41, v37 offset0:196 offset1:212
	v_add_u32_e32 v37, 0xc800, v0
	ds_write2_b32 v0, v64, v60 offset1:16
	v_add_u32_e32 v3, 0x800, v0
	v_add_u32_e32 v60, 0xc00, v0
	ds_write2_b32 v37, v42, v38 offset0:200 offset1:216
	v_add_u32_e32 v38, 0xcc00, v0
	ds_write2_b32 v3, v66, v62 offset0:8 offset1:24
	ds_write2_b32 v60, v67, v63 offset0:12 offset1:28
	ds_write2_b32 v38, v43, v39 offset0:204 offset1:220
	ds_write2_b32 v0, v32, v28 offset0:128 offset1:144
	ds_write2_b32 v2, v33, v29 offset0:132 offset1:148
	ds_write2_b32 v3, v34, v30 offset0:136 offset1:152
	ds_write2_b32 v60, v35, v31 offset0:140 offset1:156
	ds_write2_b32 v61, v24, v20 offset0:192 offset1:208
	ds_write2_b32 v52, v25, v21 offset0:196 offset1:212
	ds_write2_b32 v53, v26, v22 offset0:200 offset1:216
	ds_write2_b32 v54, v27, v23 offset0:204 offset1:220
	ds_write2_b32 v44, v16, v12 offset1:16
	ds_write2_b32 v45, v17, v13 offset0:4 offset1:20
	ds_write2_b32 v46, v18, v14 offset0:8 offset1:24
	v_add_u32_e32 v2, 0x9000, v0
	v_add_u32_e32 v0, 0xd000, v0
	ds_write2_b32 v2, v19, v15 offset0:12 offset1:28
	ds_write2_b32 v36, v8, v4 offset0:64 offset1:80
	ds_write2_b32 v37, v9, v5 offset0:68 offset1:84
	ds_write2_b32 v38, v10, v6 offset0:72 offset1:88
	ds_write2_b32 v0, v11, v7 offset0:76 offset1:92
	v_mov_b32_e32 v0, v139
	s_waitcnt lgkmcnt(0)
	s_barrier
	s_nop 0
	v_ashrrev_i32_e32 v4, 5, v0
	v_ashrrev_i32_e32 v5, 31, v4
	v_lshlrev_b64 v[2:3], 13, v[4:5]
	v_and_b32_e32 v5, 31, v0
	v_lshl_add_u64 v[2:3], s[0:1], 0, v[2:3]
	v_lshlrev_b32_e32 v0, 3, v5
	s_add_u32 s0, s66, s4
	v_lshl_add_u64 v[2:3], v[2:3], 0, v[0:1]
	s_addc_u32 s1, s67, s5
	v_mul_lo_u32 v0, v4, s81
	v_lshlrev_b32_e32 v4, 4, v5
	v_lshl_add_u64 v[2:3], s[0:1], 0, v[2:3]
	v_add3_u32 v0, v0, v4, 16
	s_mov_b64 s[0:1], 0
.LBB0_210:
	ds_read_b128 v[4:7], v0
	ds_read_b128 v[8:11], v0 offset:512
	s_mov_b32 s4, 0x12d00000
	v_add_u32_e32 v0, 0x4100, v0
	s_waitcnt lgkmcnt(0)
	v_cvt_pk_bf16_f32 v4, v4, v5
	v_cvt_pk_bf16_f32 v5, v6, v7
	v_cvt_pk_bf16_f32 v6, v8, v9
	v_lshl_add_u64 v[8:9], v[2:3], 0, s[0:1]
	s_add_u32 s0, s0, 0x20000
	v_add_co_u32_e32 v8, vcc, s4, v8
	s_addc_u32 s1, s1, 0
	s_nop 0
	v_addc_co_u32_e32 v9, vcc, 0, v9, vcc
	s_cmp_lg_u32 s0, 0x100000
	v_cvt_pk_bf16_f32 v7, v10, v11
	global_store_dwordx2 v[8:9], v[4:5], off
	global_store_dwordx2 v[8:9], v[6:7], off offset:256
	s_cbranch_scc1 .LBB0_210
	s_add_i32 s12, s12, 1
	s_mul_i32 s0, s12, s96
	s_add_i32 s13, s0, s63
	s_cmpk_gt_i32 s13, 0x3ff
	s_waitcnt lgkmcnt(0)
	s_barrier
	s_cbranch_scc0 .LBB0_199

;   __device__ __forceinline__ const float* in(int i) const { return ((const float* const*)(ws + OFF_TBL))[i]; }
; __device__ __forceinline__ int ltid() { int t = threadIdx.x; asm volatile("" : "+v"(t)); return t; }
; __device__ void post0_phase(const Ctx& p) {
;   char* ws = p.ws;
;   const u16* h0 = (const u16*)(ws + OFF_H0);
;   const u16* og = (const u16*)(ws + OFF_OGLA); const u16* oh = (const u16*)(ws + OFF_OHGRN);
;   u16* cat = (u16*)(ws + OFF_CAT0);
;   const int tid = ltid(), w = tid >> 6, lane = tid & 63;
;   const int part = w & 3;
;   const int c0 = part * 512 + lane * 8;
;   float gg_[8], gh_[8];
; #pragma unroll
;   for (int e = 0; e < 8; ++e) { gg_[e] = p.in(6)[lane * 8 + e]; gh_[e] = p.in(7)[(lane & 15) * 8 + e]; }
;   for (int item = blockIdx.x; item < NTOK / 8; item += gridDim.x) {
;     const long rbase = (long)item * 8 + (w >> 2) * 4;
;     uint4 r1[4], r2[4], r3[4], r4[4];
; #pragma unroll
;     for (int rr = 0; rr < 4; ++rr) {
;       const long row = rbase + rr;
;       r1[rr] = *(const uint4*)(og + row * 2048 + c0);
;       r2[rr] = *(const uint4*)(h0 + row * H0LD + C_GG + c0);
;       r3[rr] = *(const uint4*)(oh + row * 2048 + c0);
;       r4[rr] = *(const uint4*)(h0 + row * H0LD + C_HG + c0);
;     }
.LBB0_213:
	s_and_b64 vcc, exec, s[0:1]
	s_cbranch_vccz .LBB0_385
	v_readlane_b32 s0, v252, 53
	v_readlane_b32 s1, v252, 54
	s_cmp_gt_i32 s0, 2
	s_mov_b64 s[0:1], -1
	s_cbranch_scc0 .LBB0_358
	v_readlane_b32 s0, v252, 53
	v_readlane_b32 s1, v252, 54
	s_cmp_lt_i32 s0, 4
	s_mov_b64 s[0:1], -1
	s_cbranch_scc1 .LBB0_273
	v_readlane_b32 s0, v252, 53
	v_readlane_b32 s1, v252, 54
	s_cmp_gt_i32 s0, 4
	s_mov_b64 s[0:1], -1
	s_mov_b32 s12, 0x1c000
	s_movk_i32 s13, 0x2000
	s_movk_i32 s15, 0x6000
	s_movk_i32 s18, 0x2400
	s_cbranch_scc0 .LBB0_221
	v_readlane_b32 s0, v253, 20
	v_readlane_b32 s1, v253, 21
	s_brev_b32 s10, 60
	v_mov_b32_e32 v18, v139
	s_andn2_b64 vcc, exec, s[0:1]
	s_mov_b32 s11, 0x3b000000
	s_movk_i32 s14, 0x1000
	s_mov_b32 s16, 0x9000
	s_mov_b32 s17, 0xd000
	s_movk_i32 s19, 0x5000
	s_cbranch_vccnz .LBB0_220
	v_mov_b32_e32 v0, s66
	s_waitcnt vmcnt(0) lgkmcnt(0)
	v_add_co_u32_e32 v2, vcc, 0x4375c000, v0
	v_mov_b32_e32 v0, s67
	s_nop 0
	v_addc_co_u32_e32 v3, vcc, 0, v0, vcc
	global_load_dwordx4 v[2:5], v[2:3], off offset:48
	v_lshlrev_b32_e32 v8, 5, v18
	v_and_b32_e32 v0, 0x7e0, v8
	s_add_u32 s4, s66, 0xfa00000
	s_addc_u32 s5, s67, 0
	s_add_u32 s6, s66, 0x2e200000
	s_mov_b64 s[0:1], 0x4000000
	s_addc_u32 s7, s67, 0
	s_mov_b32 s8, s63
	s_waitcnt vmcnt(0) lgkmcnt(0)
	v_lshl_add_u64 v[6:7], v[2:3], 0, v[0:1]
	v_and_b32_e32 v0, 0x1e0, v8
	v_lshl_add_u64 v[14:15], v[4:5], 0, v[0:1]
	global_load_dwordx4 v[2:5], v[6:7], off
	s_nop 0
	global_load_dwordx4 v[6:9], v[6:7], off offset:16
	s_nop 0
	global_load_dwordx4 v[10:13], v[14:15], off
	s_nop 0
	global_load_dwordx4 v[14:17], v[14:15], off offset:16
	v_lshlrev_b32_e32 v0, 3, v18
	v_and_b32_e32 v20, 0x7f8, v0
	v_ashrrev_i32_e32 v0, 6, v18
	v_and_b32_e32 v70, -4, v0
	v_lshlrev_b32_e32 v0, 1, v20
	v_lshl_add_u64 v[72:73], s[66:67], 0, v[0:1]
	v_add_u32_e32 v0, 64, v196
	v_xor_b32_e32 v18, 32, v195
	v_cmp_lt_i32_e32 vcc, v18, v0
	v_ashrrev_i32_e32 v71, 31, v70
	v_lshl_add_u64 v[74:75], v[72:73], 0, s[0:1]
	v_cndmask_b32_e32 v18, v195, v18, vcc
	v_lshlrev_b32_e32 v86, 2, v18
	v_xor_b32_e32 v18, 16, v195
	v_cmp_lt_i32_e32 vcc, v18, v0
	s_nop 1
	v_cndmask_b32_e32 v18, v195, v18, vcc
	v_lshlrev_b32_e32 v87, 2, v18
	v_xor_b32_e32 v18, 8, v195
	v_cmp_lt_i32_e32 vcc, v18, v0
	s_nop 1
	v_cndmask_b32_e32 v18, v195, v18, vcc
	v_lshlrev_b32_e32 v88, 2, v18
	v_xor_b32_e32 v18, 4, v195
	v_cmp_lt_i32_e32 vcc, v18, v0
	s_nop 1
	v_cndmask_b32_e32 v18, v195, v18, vcc
	v_lshlrev_b32_e32 v89, 2, v18
	v_xor_b32_e32 v18, 2, v195
	v_cmp_lt_i32_e32 vcc, v18, v0
	s_nop 1
	v_cndmask_b32_e32 v18, v195, v18, vcc
	v_lshlrev_b32_e32 v90, 2, v18
	v_xor_b32_e32 v18, 1, v195
	v_cmp_lt_i32_e32 vcc, v18, v0
	s_nop 1
	v_cndmask_b32_e32 v0, v195, v18, vcc
	v_lshlrev_b32_e32 v91, 2, v0
	v_lshlrev_b32_e32 v0, 1, v20
.LBB0_219:
	s_ashr_i32 s9, s8, 31
	v_lshl_add_u64 v[76:77], s[8:9], 3, v[70:71]
	v_lshlrev_b64 v[18:19], 12, v[76:77]
	v_lshl_add_u64 v[20:21], v[72:73], 0, v[18:19]
	global_load_dwordx4 v[92:95], v[20:21], off
	v_mov_b64_e32 v[20:21], s[4:5]
	v_mad_u64_u32 v[20:21], s[0:1], v76, s51, v[20:21]
	v_mad_i32_i24 v21, v77, s51, v21
	v_lshl_add_u64 v[46:47], v[20:21], 0, v[0:1]
	v_add_co_u32_e32 v20, vcc, s13, v46
	v_or_b32_e32 v22, 0x1000, v18
	s_nop 0
	v_addc_co_u32_e32 v21, vcc, 0, v47, vcc
	global_load_dwordx4 v[96:99], v[20:21], off
	v_lshl_add_u64 v[20:21], v[74:75], 0, v[18:19]
	v_mov_b32_e32 v23, v19
	v_or_b32_e32 v24, 0x2000, v18
	v_mov_b32_e32 v25, v19
	global_load_dwordx4 v[66:69], v[20:21], off
	v_lshl_add_u64 v[20:21], v[72:73], 0, v[22:23]
	s_mov_b32 s0, 0x11000
	v_lshl_add_u64 v[22:23], v[74:75], 0, v[22:23]
	v_lshl_add_u64 v[26:27], v[72:73], 0, v[24:25]
	global_load_dwordx4 v[54:57], v[20:21], off
	global_load_dwordx4 v[50:53], v[22:23], off
	global_load_dwordx4 v[38:41], v[26:27], off
	v_add_co_u32_e32 v20, vcc, s0, v46
	v_or_b32_e32 v18, 0x3000, v18
	s_nop 0
	v_addc_co_u32_e32 v21, vcc, 0, v47, vcc
	v_add_co_u32_e32 v26, vcc, s87, v46
	v_lshl_add_u64 v[24:25], v[74:75], 0, v[24:25]
	v_lshl_add_u64 v[28:29], v[72:73], 0, v[18:19]
	v_lshl_add_u64 v[18:19], v[74:75], 0, v[18:19]
	v_addc_co_u32_e32 v27, vcc, 0, v47, vcc
	global_load_dwordx4 v[34:37], v[24:25], off
	global_load_dwordx4 v[30:33], v[28:29], off
	s_mov_b32 s0, 0x15000
	global_load_dwordx4 v[22:25], v[18:19], off
	v_add_co_u32_e32 v18, vcc, s12, v46
	s_add_i32 s8, s8, s96
	s_nop 0
	v_addc_co_u32_e32 v19, vcc, 0, v47, vcc
	v_add_co_u32_e32 v48, vcc, s15, v46
	global_load_dwordx4 v[42:45], v[20:21], off offset:1024
	s_nop 0
	global_load_dwordx4 v[26:29], v[26:27], off offset:3584
	s_nop 0
	global_load_dwordx4 v[18:21], v[18:19], off offset:3584
	v_addc_co_u32_e32 v49, vcc, 0, v47, vcc
	global_load_dwordx4 v[100:103], v[48:49], off
	v_add_co_u32_e32 v58, vcc, s16, v46
	s_cmpk_gt_i32 s8, 0x7ff
	s_nop 0
	v_addc_co_u32_e32 v59, vcc, 0, v47, vcc
	v_add_co_u32_e32 v48, vcc, s17, v46
	global_load_dwordx4 v[58:61], v[58:59], off offset:2560
	s_nop 0
	v_addc_co_u32_e32 v49, vcc, 0, v47, vcc
	v_add_co_u32_e32 v46, vcc, s0, v46
	global_load_dwordx4 v[62:65], v[48:49], off offset:2560
	s_nop 0
	v_addc_co_u32_e32 v47, vcc, 0, v47, vcc
	global_load_dwordx4 v[46:49], v[46:47], off offset:1024
	s_waitcnt vmcnt(0) lgkmcnt(0)
; __device__ __forceinline__ float bf2f(u16 h) { return __uint_as_float(((unsigned)h) << 16); }
; __device__ __forceinline__ float siluf(float x) { return x * __builtin_amdgcn_rcpf(1.f + __expf(-x)); }
; __device__ void post0_phase(const Ctx& p) {
;     ...
;     for (int rr = 0; rr < 4; ++rr) {
;       const long row = rbase + rr;
;       {
;         const uint4 raw = r1[rr], gr = r2[rr];
;         float v[8] = {bf2f(raw.x & 0xffff), bf2f(raw.x >> 16), bf2f(raw.y & 0xffff), bf2f(raw.y >> 16),
;                       bf2f(raw.z & 0xffff), bf2f(raw.z >> 16), bf2f(raw.w & 0xffff), bf2f(raw.w >> 16)};
;         float gt[8] = {bf2f(gr.x & 0xffff), bf2f(gr.x >> 16), bf2f(gr.y & 0xffff), bf2f(gr.y >> 16),
;                        bf2f(gr.z & 0xffff), bf2f(gr.z >> 16), bf2f(gr.w & 0xffff), bf2f(gr.w >> 16)};
;         float ss = 0.f;
; #pragma unroll
;         for (int e = 0; e < 8; ++e) ss += v[e] * v[e];
;         ss = wave_sum(ss);
;         const float rs = rsqrtf(ss * (1.f / 512.f) + 1e-6f);
;         float o[8];
; #pragma unroll
;         for (int e = 0; e < 8; ++e) o[e] = v[e] * rs * gg_[e] * siluf(gt[e]);
;         uint4 ov; ov.x = pack2(o[0], o[1]); ov.y = pack2(o[2], o[3]); ov.z = pack2(o[4], o[5]); ov.w = pack2(o[6], o[7]);
;         *(uint4*)(cat + row * 4608 + c0) = ov;
;       }
;       {
;         const uint4 raw = r3[rr], gr = r4[rr];
;         float v[8] = {bf2f(raw.x & 0xffff), bf2f(raw.x >> 16), bf2f(raw.y & 0xffff), bf2f(raw.y >> 16),
;                       bf2f(raw.z & 0xffff), bf2f(raw.z >> 16), bf2f(raw.w & 0xffff), bf2f(raw.w >> 16)};
;         float gt[8] = {bf2f(gr.x & 0xffff), bf2f(gr.x >> 16), bf2f(gr.y & 0xffff), bf2f(gr.y >> 16),
;                        bf2f(gr.z & 0xffff), bf2f(gr.z >> 16), bf2f(gr.w & 0xffff), bf2f(gr.w >> 16)};
;         float ss = 0.f;
; #pragma unroll
;         for (int e = 0; e < 8; ++e) ss += v[e] * v[e];
; #pragma unroll
;         for (int o = 1; o < 16; o <<= 1) ss += __shfl_xor(ss, o, 64);
;         const float rs = rsqrtf(ss * (1.f / 128.f) + 1e-6f);
	v_lshlrev_b32_e32 v84, 16, v92
	v_and_b32_e32 v85, 0xffff0000, v92
	v_lshlrev_b32_e32 v82, 16, v93
	v_and_b32_e32 v83, 0xffff0000, v93
	v_lshlrev_b32_e32 v80, 16, v94
	v_and_b32_e32 v81, 0xffff0000, v94
	v_lshlrev_b32_e32 v78, 16, v95
	v_and_b32_e32 v79, 0xffff0000, v95
	v_pk_mul_f32 v[110:111], v[80:81], v[80:81]
	v_mov_b32_e32 v127, v83
	v_pk_mul_f32 v[108:109], v[78:79], v[78:79]
	v_lshlrev_b32_e32 v92, 16, v96
	v_and_b32_e32 v93, 0xffff0000, v96
	v_lshlrev_b32_e32 v94, 16, v97
	v_and_b32_e32 v95, 0xffff0000, v97
	v_lshlrev_b32_e32 v96, 16, v98
	v_and_b32_e32 v97, 0xffff0000, v98
	v_mul_f32_e32 v104, 0xbfb8aa3b, v96
	v_mul_f32_e32 v105, 0xbfb8aa3b, v97
	v_exp_f32_e32 v104, v104
	v_exp_f32_e32 v105, v105
	v_mul_f32_e32 v106, 0xbfb8aa3b, v94
	v_mul_f32_e32 v107, 0xbfb8aa3b, v95
	v_exp_f32_e32 v106, v106
	v_exp_f32_e32 v107, v107
	v_add_f32_e32 v104, 1.0, v104
	v_add_f32_e32 v105, 1.0, v105
	v_rcp_f32_e32 v104, v104
	v_rcp_f32_e32 v105, v105
	v_add_f32_e32 v106, 1.0, v106
	v_add_f32_e32 v107, 1.0, v107
	v_rcp_f32_e32 v106, v106
	v_rcp_f32_e32 v107, v107
	v_pk_mul_f32 v[96:97], v[104:105], v[96:97]
	v_mul_f32_e32 v105, 0xbfb8aa3b, v92
	v_lshlrev_b32_e32 v98, 16, v99
	v_pk_mul_f32 v[94:95], v[106:107], v[94:95]
	v_exp_f32_e32 v106, v105
	v_mul_f32_e32 v105, 0xbfb8aa3b, v93
	v_exp_f32_e32 v107, v105
	v_and_b32_e32 v99, 0xffff0000, v99
	v_add_f32_e32 v106, 1.0, v106
	v_mul_f32_e32 v112, 0xbfb8aa3b, v98
	v_add_f32_e32 v107, 1.0, v107
	v_mul_f32_e32 v113, 0xbfb8aa3b, v99
	v_rcp_f32_e32 v106, v106
	v_rcp_f32_e32 v107, v107
	v_exp_f32_e32 v112, v112
	v_exp_f32_e32 v113, v113
	v_mov_b32_e32 v104, v84
	v_pk_mul_f32 v[92:93], v[106:107], v[92:93]
	v_add_f32_e32 v106, 1.0, v112
	v_add_f32_e32 v107, 1.0, v113
	v_rcp_f32_e32 v106, v106
	v_rcp_f32_e32 v107, v107
	v_mul_f32_e32 v112, v84, v84
	v_mov_b32_e32 v105, v82
	v_fmac_f32_e32 v112, v85, v85
	v_pk_mul_f32 v[98:99], v[106:107], v[98:99]
	v_mov_b64_e32 v[106:107], s[6:7]
	v_mad_u64_u32 v[106:107], s[0:1], v76, s18, v[106:107]
	v_mad_i32_i24 v107, v77, s18, v107
	v_pk_fma_f32 v[104:105], v[104:105], v[104:105], v[112:113] op_sel_hi:[1,1,0]
	v_lshl_add_u64 v[76:77], v[106:107], 0, v[0:1]
	v_lshlrev_b32_e32 v106, 16, v66
	v_and_b32_e32 v107, 0xffff0000, v66
	v_lshlrev_b32_e32 v118, 16, v102
	v_lshlrev_b32_e32 v112, 16, v67
	v_and_b32_e32 v113, 0xffff0000, v67
	v_mul_f32_e32 v104, 0xbfb8aa3b, v118
	v_pk_mul_f32 v[124:125], v[106:107], v[106:107]
	v_exp_f32_e32 v128, v104
	v_pk_mul_f32 v[122:123], v[112:113], v[112:113]
	v_mov_b32_e32 v126, v106
	v_mov_b32_e32 v104, v125
	v_lshlrev_b32_e32 v114, 16, v68
	v_and_b32_e32 v115, 0xffff0000, v68
	v_pk_fma_f32 v[104:105], v[126:127], v[126:127], v[104:105]
	v_mov_b32_e32 v124, v122
	v_mov_b32_e32 v125, v110
	v_pk_mul_f32 v[120:121], v[114:115], v[114:115]
	v_pk_add_f32 v[104:105], v[104:105], v[124:125]
	v_mov_b32_e32 v110, v123
	v_pk_add_f32 v[104:105], v[110:111], v[104:105]
	v_mov_b32_e32 v110, v120
	v_mov_b32_e32 v111, v108
	v_pk_add_f32 v[104:105], v[110:111], v[104:105]
	v_mov_b32_e32 v108, v121
	v_pk_add_f32 v[104:105], v[108:109], v[104:105]
	ds_bpermute_b32 v109, v86, v105
	v_lshlrev_b32_e32 v68, 16, v69
	v_and_b32_e32 v69, 0xffff0000, v69
	v_and_b32_e32 v119, 0xffff0000, v102
	v_pk_mul_f32 v[66:67], v[68:69], v[68:69]
	v_mul_f32_e32 v108, 0xbfb8aa3b, v119
	v_exp_f32_e32 v111, v108
	v_mov_b32_e32 v108, v66
	s_waitcnt lgkmcnt(0)
	v_pk_add_f32 v[104:105], v[108:109], v[104:105]
	ds_bpermute_b32 v109, v87, v105
	v_add_f32_e32 v66, 1.0, v111
	v_mov_b32_e32 v108, v67
	v_rcp_f32_e32 v111, v66
	v_lshlrev_b32_e32 v116, 16, v100
	s_waitcnt lgkmcnt(0)
	v_pk_add_f32 v[66:67], v[108:109], v[104:105]
	ds_bpermute_b32 v105, v88, v67
	ds_bpermute_b32 v104, v91, v66
	v_and_b32_e32 v117, 0xffff0000, v100
	v_lshlrev_b32_e32 v100, 16, v101
	v_and_b32_e32 v101, 0xffff0000, v101
	v_mul_f32_e32 v108, 0xbfb8aa3b, v100
	s_waitcnt lgkmcnt(0)
	v_pk_add_f32 v[66:67], v[66:67], v[104:105]
	ds_bpermute_b32 v105, v89, v67
	ds_bpermute_b32 v104, v90, v66
	v_mul_f32_e32 v109, 0xbfb8aa3b, v101
	v_mul_f32_e32 v120, 0xbfb8aa3b, v116
	v_mul_f32_e32 v121, 0xbfb8aa3b, v117
	v_exp_f32_e32 v108, v108
	s_waitcnt lgkmcnt(0)
	v_pk_add_f32 v[66:67], v[66:67], v[104:105]
	ds_bpermute_b32 v105, v90, v67
	ds_bpermute_b32 v104, v89, v66
	v_exp_f32_e32 v109, v109
	v_exp_f32_e32 v120, v120
	v_exp_f32_e32 v121, v121
	s_mov_b32 s0, 0x358637bd
	s_waitcnt lgkmcnt(0)
	v_pk_add_f32 v[66:67], v[66:67], v[104:105]
	ds_bpermute_b32 v105, v91, v67
	ds_bpermute_b32 v104, v88, v66
	v_add_f32_e32 v108, 1.0, v108
	v_add_f32_e32 v109, 1.0, v109
	v_add_f32_e32 v120, 1.0, v120
	v_add_f32_e32 v121, 1.0, v121
	s_waitcnt lgkmcnt(0)
; __device__ __forceinline__ float bf2f(u16 h) { return __uint_as_float(((unsigned)h) << 16); }
; __device__ __forceinline__ float siluf(float x) { return x * __builtin_amdgcn_rcpf(1.f + __expf(-x)); }
; __device__ void post0_phase(const Ctx& p) {
;     ...
;     for (int rr = 0; rr < 4; ++rr) {
;       const long row = rbase + rr;
;       {
;         const uint4 raw = r1[rr], gr = r2[rr];
;         float v[8] = {bf2f(raw.x & 0xffff), bf2f(raw.x >> 16), bf2f(raw.y & 0xffff), bf2f(raw.y >> 16),
;                       bf2f(raw.z & 0xffff), bf2f(raw.z >> 16), bf2f(raw.w & 0xffff), bf2f(raw.w >> 16)};
;         float gt[8] = {bf2f(gr.x & 0xffff), bf2f(gr.x >> 16), bf2f(gr.y & 0xffff), bf2f(gr.y >> 16),
;                        bf2f(gr.z & 0xffff), bf2f(gr.z >> 16), bf2f(gr.w & 0xffff), bf2f(gr.w >> 16)};
;         float ss = 0.f;
; #pragma unroll
;         for (int e = 0; e < 8; ++e) ss += v[e] * v[e];
;         ss = wave_sum(ss);
;         const float rs = rsqrtf(ss * (1.f / 512.f) + 1e-6f);
;         float o[8];
; #pragma unroll
;         for (int e = 0; e < 8; ++e) o[e] = v[e] * rs * gg_[e] * siluf(gt[e]);
;         uint4 ov; ov.x = pack2(o[0], o[1]); ov.y = pack2(o[2], o[3]); ov.z = pack2(o[4], o[5]); ov.w = pack2(o[6], o[7]);
;         *(uint4*)(cat + row * 4608 + c0) = ov;
;       }
;       {
;         const uint4 raw = r3[rr], gr = r4[rr];
;         float v[8] = {bf2f(raw.x & 0xffff), bf2f(raw.x >> 16), bf2f(raw.y & 0xffff), bf2f(raw.y >> 16),
;                       bf2f(raw.z & 0xffff), bf2f(raw.z >> 16), bf2f(raw.w & 0xffff), bf2f(raw.w >> 16)};
;         float gt[8] = {bf2f(gr.x & 0xffff), bf2f(gr.x >> 16), bf2f(gr.y & 0xffff), bf2f(gr.y >> 16),
;                        bf2f(gr.z & 0xffff), bf2f(gr.z >> 16), bf2f(gr.w & 0xffff), bf2f(gr.w >> 16)};
;         float ss = 0.f;
; #pragma unroll
;         for (int e = 0; e < 8; ++e) ss += v[e] * v[e];
; #pragma unroll
;         for (int o = 1; o < 16; o <<= 1) ss += __shfl_xor(ss, o, 64);
;         const float rs = rsqrtf(ss * (1.f / 128.f) + 1e-6f);
;         float o[8];
; #pragma unroll
;         for (int e = 0; e < 8; ++e) o[e] = v[e] * rs * gh_[e] * siluf(gt[e]);
;         uint4 ov; ov.x = pack2(o[0], o[1]); ov.y = pack2(o[2], o[3]); ov.z = pack2(o[4], o[5]); ov.w = pack2(o[6], o[7]);
;         *(uint4*)(cat + row * 4608 + 2048 + c0) = ov;
;       }
	v_pk_add_f32 v[104:105], v[66:67], v[104:105]
	v_mov_b64_e32 v[66:67], s[0:1]
	v_pk_fma_f32 v[104:105], v[104:105], s[10:11], v[66:67] op_sel_hi:[1,1,0]
	v_rcp_f32_e32 v108, v108
	v_mul_f32_e32 v122, 0x4b800000, v105
	v_cmp_gt_f32_e32 vcc, s48, v105
	v_rcp_f32_e32 v109, v109
	v_rcp_f32_e32 v120, v120
	v_cndmask_b32_e32 v105, v105, v122, vcc
	v_rcp_f32_e32 v121, v121
	v_rsq_f32_e32 v105, v105
	v_pk_mul_f32 v[100:101], v[108:109], v[100:101]
	v_lshlrev_b32_e32 v102, 16, v103
	v_pk_mul_f32 v[108:109], v[120:121], v[116:117]
	v_mul_f32_e32 v116, 0x45800000, v105
	v_cndmask_b32_e32 v116, v105, v116, vcc
	v_pk_mul_f32 v[82:83], v[116:117], v[82:83] op_sel_hi:[0,1]
	v_pk_mul_f32 v[84:85], v[116:117], v[84:85] op_sel_hi:[0,1]
	v_pk_mul_f32 v[82:83], v[4:5], v[82:83]
	v_pk_mul_f32 v[78:79], v[116:117], v[78:79] op_sel_hi:[0,1]
	v_pk_mul_f32 v[84:85], v[2:3], v[84:85]
	v_pk_mul_f32 v[82:83], v[94:95], v[82:83]
	v_pk_mul_f32 v[78:79], v[8:9], v[78:79]
	v_pk_mul_f32 v[84:85], v[92:93], v[84:85]
	v_pk_mul_f32 v[92:93], v[98:99], v[78:79]
	v_cvt_pk_bf16_f32 v79, v82, v83
	v_mul_f32_e32 v82, 0x4b800000, v104
	v_cmp_gt_f32_e32 vcc, s48, v104
	v_pk_mul_f32 v[80:81], v[116:117], v[80:81] op_sel_hi:[0,1]
	v_pk_mul_f32 v[80:81], v[6:7], v[80:81]
	v_cndmask_b32_e32 v82, v104, v82, vcc
	v_rsq_f32_e32 v82, v82
	v_pk_mul_f32 v[80:81], v[96:97], v[80:81]
	v_cvt_pk_bf16_f32 v78, v84, v85
	v_cvt_pk_bf16_f32 v80, v80, v81
	v_cvt_pk_bf16_f32 v81, v92, v93
	global_store_dwordx4 v[76:77], v[78:81], off
	v_and_b32_e32 v103, 0xffff0000, v103
	v_mul_f32_e32 v92, 0xbfb8aa3b, v103
	v_mul_f32_e32 v78, 0x45800000, v82
	v_cndmask_b32_e32 v78, v82, v78, vcc
	v_pk_mul_f32 v[80:81], v[78:79], v[106:107] op_sel_hi:[0,1]
	v_pk_mul_f32 v[82:83], v[78:79], v[112:113] op_sel_hi:[0,1]
	v_pk_mul_f32 v[84:85], v[78:79], v[114:115] op_sel_hi:[0,1]
	v_mul_f32_e32 v79, 0xbfb8aa3b, v102
	v_exp_f32_e32 v79, v79
	v_exp_f32_e32 v93, v92
	v_add_f32_e32 v110, 1.0, v128
	v_rcp_f32_e32 v110, v110
	v_add_f32_e32 v79, 1.0, v79
	v_rcp_f32_e32 v92, v79
	v_add_f32_e32 v79, 1.0, v93
	v_rcp_f32_e32 v93, v79
	v_pk_mul_f32 v[68:69], v[78:79], v[68:69] op_sel_hi:[0,1]
	v_pk_mul_f32 v[80:81], v[10:11], v[80:81]
	v_pk_mul_f32 v[68:69], v[16:17], v[68:69]
	v_pk_mul_f32 v[78:79], v[92:93], v[102:103]
	v_pk_mul_f32 v[110:111], v[110:111], v[118:119]
	v_pk_mul_f32 v[80:81], v[108:109], v[80:81]
	v_pk_mul_f32 v[82:83], v[12:13], v[82:83]
	v_pk_mul_f32 v[84:85], v[14:15], v[84:85]
	v_pk_mul_f32 v[68:69], v[78:79], v[68:69]
	v_pk_mul_f32 v[82:83], v[100:101], v[82:83]
	v_pk_mul_f32 v[84:85], v[110:111], v[84:85]
	v_cvt_pk_bf16_f32 v78, v80, v81
	v_cvt_pk_bf16_f32 v81, v68, v69
	v_add_co_u32_e32 v68, vcc, s14, v76
	v_cvt_pk_bf16_f32 v79, v82, v83
	v_cvt_pk_bf16_f32 v80, v84, v85
	v_addc_co_u32_e32 v69, vcc, 0, v77, vcc
	v_lshlrev_b32_e32 v82, 16, v60
	v_and_b32_e32 v83, 0xffff0000, v60
	global_store_dwordx4 v[68:69], v[78:81], off
	v_lshlrev_b32_e32 v68, 16, v56
	v_and_b32_e32 v69, 0xffff0000, v56
	v_lshlrev_b32_e32 v80, 16, v54
	v_and_b32_e32 v81, 0xffff0000, v54
	v_lshlrev_b32_e32 v78, 16, v55
	v_and_b32_e32 v79, 0xffff0000, v55
	v_lshlrev_b32_e32 v54, 16, v57
	v_and_b32_e32 v55, 0xffff0000, v57
	v_lshlrev_b32_e32 v56, 16, v58
	v_and_b32_e32 v57, 0xffff0000, v58
	v_lshlrev_b32_e32 v58, 16, v59
	v_and_b32_e32 v59, 0xffff0000, v59
	v_mul_f32_e32 v84, 0xbfb8aa3b, v82
	v_mul_f32_e32 v85, 0xbfb8aa3b, v83
	v_exp_f32_e32 v84, v84
	v_exp_f32_e32 v85, v85
	v_mul_f32_e32 v92, 0xbfb8aa3b, v58
	v_mul_f32_e32 v93, 0xbfb8aa3b, v59
	v_exp_f32_e32 v92, v92
	v_exp_f32_e32 v93, v93
	v_add_f32_e32 v84, 1.0, v84
	v_add_f32_e32 v85, 1.0, v85
	v_rcp_f32_e32 v84, v84
	v_rcp_f32_e32 v85, v85
	v_add_f32_e32 v92, 1.0, v92
	v_add_f32_e32 v93, 1.0, v93
	v_rcp_f32_e32 v92, v92
	v_rcp_f32_e32 v93, v93
	v_pk_mul_f32 v[82:83], v[84:85], v[82:83]
	v_mul_f32_e32 v85, 0xbfb8aa3b, v56
	v_lshlrev_b32_e32 v60, 16, v61
	v_pk_mul_f32 v[58:59], v[92:93], v[58:59]
	v_exp_f32_e32 v92, v85
	v_mul_f32_e32 v85, 0xbfb8aa3b, v57
	v_exp_f32_e32 v93, v85
	v_and_b32_e32 v61, 0xffff0000, v61
	v_add_f32_e32 v92, 1.0, v92
	v_mul_f32_e32 v98, 0xbfb8aa3b, v60
	v_add_f32_e32 v93, 1.0, v93
	v_mul_f32_e32 v99, 0xbfb8aa3b, v61
	v_rcp_f32_e32 v92, v92
	v_rcp_f32_e32 v93, v93
	v_exp_f32_e32 v98, v98
	v_exp_f32_e32 v99, v99
	v_mov_b32_e32 v84, v80
	v_pk_mul_f32 v[56:57], v[92:93], v[56:57]
	v_add_f32_e32 v92, 1.0, v98
	v_add_f32_e32 v93, 1.0, v99
	v_rcp_f32_e32 v92, v92
	v_rcp_f32_e32 v93, v93
	v_mul_f32_e32 v98, v80, v80
	v_mov_b32_e32 v85, v78
	v_fmac_f32_e32 v98, v81, v81
	v_pk_fma_f32 v[84:85], v[84:85], v[84:85], v[98:99] op_sel_hi:[1,1,0]
	v_pk_mul_f32 v[60:61], v[92:93], v[60:61]
	v_lshlrev_b32_e32 v92, 16, v50
	v_and_b32_e32 v93, 0xffff0000, v50
	v_lshlrev_b32_e32 v98, 16, v51
	v_and_b32_e32 v99, 0xffff0000, v51
	v_lshlrev_b32_e32 v50, 16, v62
	v_and_b32_e32 v51, 0xffff0000, v62
	v_lshlrev_b32_e32 v62, 16, v64
	v_mul_f32_e32 v84, 0xbfb8aa3b, v62
	v_pk_mul_f32 v[110:111], v[92:93], v[92:93]
	v_pk_mul_f32 v[96:97], v[68:69], v[68:69]
	v_exp_f32_e32 v114, v84
	v_pk_mul_f32 v[108:109], v[98:99], v[98:99]
	v_mov_b32_e32 v112, v92
	v_mov_b32_e32 v113, v79
	v_mov_b32_e32 v84, v111
	v_lshlrev_b32_e32 v100, 16, v52
	v_and_b32_e32 v101, 0xffff0000, v52
	v_pk_fma_f32 v[84:85], v[112:113], v[112:113], v[84:85]
	v_mov_b32_e32 v110, v108
	v_mov_b32_e32 v111, v96
	v_pk_mul_f32 v[94:95], v[54:55], v[54:55]
	v_pk_mul_f32 v[106:107], v[100:101], v[100:101]
	v_pk_add_f32 v[84:85], v[84:85], v[110:111]
	v_mov_b32_e32 v96, v109
	v_pk_add_f32 v[84:85], v[96:97], v[84:85]
	v_mov_b32_e32 v96, v106
	v_mov_b32_e32 v97, v94
	v_pk_add_f32 v[84:85], v[96:97], v[84:85]
	v_mov_b32_e32 v94, v107
	v_pk_add_f32 v[84:85], v[94:95], v[84:85]
	ds_bpermute_b32 v95, v86, v85
	v_lshlrev_b32_e32 v102, 16, v53
	v_and_b32_e32 v103, 0xffff0000, v53
	v_lshlrev_b32_e32 v52, 16, v63
	v_and_b32_e32 v53, 0xffff0000, v63
	v_and_b32_e32 v63, 0xffff0000, v64
	v_pk_mul_f32 v[104:105], v[102:103], v[102:103]
	v_mul_f32_e32 v94, 0xbfb8aa3b, v63
	v_exp_f32_e32 v97, v94
	v_mov_b32_e32 v94, v104
	s_waitcnt lgkmcnt(0)
; __device__ __forceinline__ float bf2f(u16 h) { return __uint_as_float(((unsigned)h) << 16); }
; __device__ __forceinline__ float siluf(float x) { return x * __builtin_amdgcn_rcpf(1.f + __expf(-x)); }
; __device__ void post0_phase(const Ctx& p) {
;     ...
;     for (int rr = 0; rr < 4; ++rr) {
;       const long row = rbase + rr;
;       {
;         const uint4 raw = r1[rr], gr = r2[rr];
;         float v[8] = {bf2f(raw.x & 0xffff), bf2f(raw.x >> 16), bf2f(raw.y & 0xffff), bf2f(raw.y >> 16),
;                       bf2f(raw.z & 0xffff), bf2f(raw.z >> 16), bf2f(raw.w & 0xffff), bf2f(raw.w >> 16)};
;         float gt[8] = {bf2f(gr.x & 0xffff), bf2f(gr.x >> 16), bf2f(gr.y & 0xffff), bf2f(gr.y >> 16),
;                        bf2f(gr.z & 0xffff), bf2f(gr.z >> 16), bf2f(gr.w & 0xffff), bf2f(gr.w >> 16)};
;         float ss = 0.f;
; #pragma unroll
;         for (int e = 0; e < 8; ++e) ss += v[e] * v[e];
;         ss = wave_sum(ss);
;         const float rs = rsqrtf(ss * (1.f / 512.f) + 1e-6f);
;         float o[8];
; #pragma unroll
;         for (int e = 0; e < 8; ++e) o[e] = v[e] * rs * gg_[e] * siluf(gt[e]);
;         uint4 ov; ov.x = pack2(o[0], o[1]); ov.y = pack2(o[2], o[3]); ov.z = pack2(o[4], o[5]); ov.w = pack2(o[6], o[7]);
;         *(uint4*)(cat + row * 4608 + c0) = ov;
;       }
;       {
;         const uint4 raw = r3[rr], gr = r4[rr];
;         float v[8] = {bf2f(raw.x & 0xffff), bf2f(raw.x >> 16), bf2f(raw.y & 0xffff), bf2f(raw.y >> 16),
;                       bf2f(raw.z & 0xffff), bf2f(raw.z >> 16), bf2f(raw.w & 0xffff), bf2f(raw.w >> 16)};
;         float gt[8] = {bf2f(gr.x & 0xffff), bf2f(gr.x >> 16), bf2f(gr.y & 0xffff), bf2f(gr.y >> 16),
;                        bf2f(gr.z & 0xffff), bf2f(gr.z >> 16), bf2f(gr.w & 0xffff), bf2f(gr.w >> 16)};
;         float ss = 0.f;
; #pragma unroll
;         for (int e = 0; e < 8; ++e) ss += v[e] * v[e];
; #pragma unroll
;         for (int o = 1; o < 16; o <<= 1) ss += __shfl_xor(ss, o, 64);
;         const float rs = rsqrtf(ss * (1.f / 128.f) + 1e-6f);
;         float o[8];
; #pragma unroll
;         for (int e = 0; e < 8; ++e) o[e] = v[e] * rs * gh_[e] * siluf(gt[e]);
;         uint4 ov; ov.x = pack2(o[0], o[1]); ov.y = pack2(o[2], o[3]); ov.z = pack2(o[4], o[5]); ov.w = pack2(o[6], o[7]);
;         *(uint4*)(cat + row * 4608 + 2048 + c0) = ov;
;       }
	v_pk_add_f32 v[84:85], v[94:95], v[84:85]
	ds_bpermute_b32 v95, v87, v85
	v_add_f32_e32 v94, 1.0, v97
	v_rcp_f32_e32 v97, v94
	v_mov_b32_e32 v94, v105
	v_mul_f32_e32 v106, 0xbfb8aa3b, v50
	s_waitcnt lgkmcnt(0)
	v_pk_add_f32 v[84:85], v[94:95], v[84:85]
	ds_bpermute_b32 v95, v88, v85
	ds_bpermute_b32 v94, v91, v84
	v_mul_f32_e32 v107, 0xbfb8aa3b, v51
	v_exp_f32_e32 v106, v106
	v_exp_f32_e32 v107, v107
	v_mul_f32_e32 v104, 0xbfb8aa3b, v52
	s_waitcnt lgkmcnt(0)
	v_pk_add_f32 v[84:85], v[84:85], v[94:95]
	ds_bpermute_b32 v95, v89, v85
	ds_bpermute_b32 v94, v90, v84
	v_mul_f32_e32 v105, 0xbfb8aa3b, v53
	v_exp_f32_e32 v104, v104
	v_exp_f32_e32 v105, v105
	v_add_f32_e32 v96, 1.0, v114
	s_waitcnt lgkmcnt(0)
	v_pk_add_f32 v[84:85], v[84:85], v[94:95]
	ds_bpermute_b32 v95, v90, v85
	ds_bpermute_b32 v94, v89, v84
	v_add_f32_e32 v106, 1.0, v106
	v_add_f32_e32 v107, 1.0, v107
	v_rcp_f32_e32 v96, v96
	v_rcp_f32_e32 v106, v106
	s_waitcnt lgkmcnt(0)
	v_pk_add_f32 v[84:85], v[84:85], v[94:95]
	ds_bpermute_b32 v95, v91, v85
	ds_bpermute_b32 v94, v88, v84
	v_rcp_f32_e32 v107, v107
	v_add_f32_e32 v104, 1.0, v104
	v_add_f32_e32 v105, 1.0, v105
	v_rcp_f32_e32 v104, v104
	s_waitcnt lgkmcnt(0)
	v_pk_add_f32 v[84:85], v[84:85], v[94:95]
	v_rcp_f32_e32 v105, v105
	v_pk_fma_f32 v[84:85], v[84:85], s[10:11], v[66:67] op_sel_hi:[1,1,0]
	v_pk_mul_f32 v[62:63], v[96:97], v[62:63]
	v_mul_f32_e32 v94, 0x4b800000, v85
	v_cmp_gt_f32_e32 vcc, s48, v85
	v_pk_mul_f32 v[96:97], v[106:107], v[50:51]
	v_lshlrev_b32_e32 v64, 16, v65
	v_cndmask_b32_e32 v85, v85, v94, vcc
	v_rsq_f32_e32 v85, v85
	v_pk_mul_f32 v[94:95], v[104:105], v[52:53]
	v_and_b32_e32 v65, 0xffff0000, v65
	v_mul_f32_e32 v50, 0x45800000, v85
	v_cndmask_b32_e32 v50, v85, v50, vcc
	v_pk_mul_f32 v[52:53], v[50:51], v[80:81] op_sel_hi:[0,1]
	v_pk_mul_f32 v[52:53], v[2:3], v[52:53]
	v_cmp_gt_f32_e32 vcc, s48, v84
	v_pk_mul_f32 v[52:53], v[56:57], v[52:53]
	v_pk_mul_f32 v[56:57], v[50:51], v[78:79] op_sel_hi:[0,1]
	v_pk_mul_f32 v[56:57], v[4:5], v[56:57]
	v_lshlrev_b32_e32 v78, 16, v36
	v_pk_mul_f32 v[56:57], v[58:59], v[56:57]
	v_pk_mul_f32 v[58:59], v[50:51], v[68:69] op_sel_hi:[0,1]
	v_pk_mul_f32 v[50:51], v[50:51], v[54:55] op_sel_hi:[0,1]
	v_pk_mul_f32 v[50:51], v[8:9], v[50:51]
	v_pk_mul_f32 v[58:59], v[6:7], v[58:59]
	v_pk_mul_f32 v[54:55], v[60:61], v[50:51]
	v_cvt_pk_bf16_f32 v50, v52, v53
	v_cvt_pk_bf16_f32 v53, v54, v55
	v_mul_f32_e32 v54, 0x4b800000, v84
	v_cndmask_b32_e32 v54, v84, v54, vcc
	v_cvt_pk_bf16_f32 v51, v56, v57
	v_rsq_f32_e32 v56, v54
	v_pk_mul_f32 v[58:59], v[82:83], v[58:59]
	v_add_co_u32_e64 v54, s[0:1], s13, v76
	v_cvt_pk_bf16_f32 v52, v58, v59
	s_nop 0
	v_addc_co_u32_e64 v55, s[0:1], 0, v77, s[0:1]
	global_store_dwordx4 v[54:55], v[50:53], off offset:1024
	v_mul_f32_e32 v58, 0xbfb8aa3b, v65
	v_exp_f32_e32 v59, v58
	v_mul_f32_e32 v50, 0x45800000, v56
	v_cndmask_b32_e32 v50, v56, v50, vcc
	v_pk_mul_f32 v[52:53], v[50:51], v[92:93] op_sel_hi:[0,1]
	v_pk_mul_f32 v[54:55], v[50:51], v[98:99] op_sel_hi:[0,1]
	v_pk_mul_f32 v[56:57], v[50:51], v[100:101] op_sel_hi:[0,1]
	v_mul_f32_e32 v51, 0xbfb8aa3b, v64
	v_exp_f32_e32 v51, v51
	v_pk_mul_f32 v[54:55], v[12:13], v[54:55]
	v_pk_mul_f32 v[52:53], v[10:11], v[52:53]
	v_pk_mul_f32 v[54:55], v[94:95], v[54:55]
	v_add_f32_e32 v51, 1.0, v51
	v_rcp_f32_e32 v58, v51
	v_add_f32_e32 v51, 1.0, v59
	v_rcp_f32_e32 v59, v51
	v_pk_mul_f32 v[50:51], v[50:51], v[102:103] op_sel_hi:[0,1]
	v_pk_mul_f32 v[56:57], v[14:15], v[56:57]
	v_pk_mul_f32 v[50:51], v[16:17], v[50:51]
	v_pk_mul_f32 v[58:59], v[58:59], v[64:65]
	v_pk_mul_f32 v[52:53], v[96:97], v[52:53]
	v_pk_mul_f32 v[56:57], v[62:63], v[56:57]
	v_pk_mul_f32 v[58:59], v[58:59], v[50:51]
	v_cvt_pk_bf16_f32 v51, v54, v55
	v_add_co_u32_e32 v54, vcc, s43, v76
	v_cvt_pk_bf16_f32 v50, v52, v53
	v_cvt_pk_bf16_f32 v52, v56, v57
	v_cvt_pk_bf16_f32 v53, v58, v59
	v_addc_co_u32_e32 v55, vcc, 0, v77, vcc
	v_lshlrev_b32_e32 v56, 16, v44
	v_and_b32_e32 v57, 0xffff0000, v44
	global_store_dwordx4 v[54:55], v[50:53], off offset:1024
	v_lshlrev_b32_e32 v54, 16, v38
	v_and_b32_e32 v55, 0xffff0000, v38
	v_lshlrev_b32_e32 v52, 16, v39
	v_and_b32_e32 v53, 0xffff0000, v39
	v_lshlrev_b32_e32 v50, 16, v40
	v_and_b32_e32 v51, 0xffff0000, v40
	v_lshlrev_b32_e32 v38, 16, v41
	v_and_b32_e32 v39, 0xffff0000, v41
	v_lshlrev_b32_e32 v40, 16, v42
	v_and_b32_e32 v41, 0xffff0000, v42
	v_lshlrev_b32_e32 v42, 16, v43
	v_and_b32_e32 v43, 0xffff0000, v43
	v_mul_f32_e32 v58, 0xbfb8aa3b, v56
	v_mul_f32_e32 v59, 0xbfb8aa3b, v57
	v_exp_f32_e32 v58, v58
	v_exp_f32_e32 v59, v59
	v_mul_f32_e32 v60, 0xbfb8aa3b, v42
	v_mul_f32_e32 v61, 0xbfb8aa3b, v43
	v_exp_f32_e32 v60, v60
	v_exp_f32_e32 v61, v61
	v_add_f32_e32 v58, 1.0, v58
	v_add_f32_e32 v59, 1.0, v59
	v_rcp_f32_e32 v58, v58
	v_rcp_f32_e32 v59, v59
	v_add_f32_e32 v60, 1.0, v60
	v_add_f32_e32 v61, 1.0, v61
	v_rcp_f32_e32 v60, v60
	v_rcp_f32_e32 v61, v61
	v_pk_mul_f32 v[56:57], v[58:59], v[56:57]
	v_mul_f32_e32 v59, 0xbfb8aa3b, v40
	v_lshlrev_b32_e32 v44, 16, v45
	v_pk_mul_f32 v[42:43], v[60:61], v[42:43]
	v_exp_f32_e32 v60, v59
	v_mul_f32_e32 v59, 0xbfb8aa3b, v41
	v_exp_f32_e32 v61, v59
	v_and_b32_e32 v45, 0xffff0000, v45
	v_add_f32_e32 v60, 1.0, v60
	v_mul_f32_e32 v68, 0xbfb8aa3b, v44
	v_add_f32_e32 v61, 1.0, v61
	v_mul_f32_e32 v69, 0xbfb8aa3b, v45
	v_rcp_f32_e32 v60, v60
	v_rcp_f32_e32 v61, v61
	v_exp_f32_e32 v68, v68
	v_exp_f32_e32 v69, v69
	v_mov_b32_e32 v58, v54
	v_pk_mul_f32 v[40:41], v[60:61], v[40:41]
	v_add_f32_e32 v60, 1.0, v68
	v_add_f32_e32 v61, 1.0, v69
	v_rcp_f32_e32 v60, v60
	v_rcp_f32_e32 v61, v61
	v_mul_f32_e32 v68, v54, v54
	v_mov_b32_e32 v59, v52
	v_fmac_f32_e32 v68, v55, v55
; __device__ __forceinline__ float bf2f(u16 h) { return __uint_as_float(((unsigned)h) << 16); }
; __device__ __forceinline__ float siluf(float x) { return x * __builtin_amdgcn_rcpf(1.f + __expf(-x)); }
; __device__ void post0_phase(const Ctx& p) {
;     ...
;     for (int rr = 0; rr < 4; ++rr) {
;       const long row = rbase + rr;
;       {
;         const uint4 raw = r1[rr], gr = r2[rr];
;         float v[8] = {bf2f(raw.x & 0xffff), bf2f(raw.x >> 16), bf2f(raw.y & 0xffff), bf2f(raw.y >> 16),
;                       bf2f(raw.z & 0xffff), bf2f(raw.z >> 16), bf2f(raw.w & 0xffff), bf2f(raw.w >> 16)};
;         float gt[8] = {bf2f(gr.x & 0xffff), bf2f(gr.x >> 16), bf2f(gr.y & 0xffff), bf2f(gr.y >> 16),
;                        bf2f(gr.z & 0xffff), bf2f(gr.z >> 16), bf2f(gr.w & 0xffff), bf2f(gr.w >> 16)};
;         float ss = 0.f;
; #pragma unroll
;         for (int e = 0; e < 8; ++e) ss += v[e] * v[e];
;         ss = wave_sum(ss);
;         const float rs = rsqrtf(ss * (1.f / 512.f) + 1e-6f);
;         float o[8];
; #pragma unroll
;         for (int e = 0; e < 8; ++e) o[e] = v[e] * rs * gg_[e] * siluf(gt[e]);
;         uint4 ov; ov.x = pack2(o[0], o[1]); ov.y = pack2(o[2], o[3]); ov.z = pack2(o[4], o[5]); ov.w = pack2(o[6], o[7]);
;         *(uint4*)(cat + row * 4608 + c0) = ov;
;       }
;       {
;         const uint4 raw = r3[rr], gr = r4[rr];
;         float v[8] = {bf2f(raw.x & 0xffff), bf2f(raw.x >> 16), bf2f(raw.y & 0xffff), bf2f(raw.y >> 16),
;                       bf2f(raw.z & 0xffff), bf2f(raw.z >> 16), bf2f(raw.w & 0xffff), bf2f(raw.w >> 16)};
;         float gt[8] = {bf2f(gr.x & 0xffff), bf2f(gr.x >> 16), bf2f(gr.y & 0xffff), bf2f(gr.y >> 16),
;                        bf2f(gr.z & 0xffff), bf2f(gr.z >> 16), bf2f(gr.w & 0xffff), bf2f(gr.w >> 16)};
;         float ss = 0.f;
; #pragma unroll
;         for (int e = 0; e < 8; ++e) ss += v[e] * v[e];
; #pragma unroll
;         for (int o = 1; o < 16; o <<= 1) ss += __shfl_xor(ss, o, 64);
;         const float rs = rsqrtf(ss * (1.f / 128.f) + 1e-6f);
	v_pk_fma_f32 v[58:59], v[58:59], v[58:59], v[68:69] op_sel_hi:[1,1,0]
	v_pk_mul_f32 v[44:45], v[60:61], v[44:45]
	v_lshlrev_b32_e32 v60, 16, v34
	v_and_b32_e32 v61, 0xffff0000, v34
	v_lshlrev_b32_e32 v68, 16, v35
	v_and_b32_e32 v69, 0xffff0000, v35
	v_lshlrev_b32_e32 v34, 16, v46
	v_and_b32_e32 v35, 0xffff0000, v46
	v_lshlrev_b32_e32 v46, 16, v48
	v_mul_f32_e32 v58, 0xbfb8aa3b, v46
	v_pk_mul_f32 v[94:95], v[60:61], v[60:61]
	v_pk_mul_f32 v[64:65], v[50:51], v[50:51]
	v_exp_f32_e32 v98, v58
	v_pk_mul_f32 v[92:93], v[68:69], v[68:69]
	v_mov_b32_e32 v96, v60
	v_mov_b32_e32 v97, v53
	v_mov_b32_e32 v58, v95
	v_and_b32_e32 v79, 0xffff0000, v36
	v_pk_fma_f32 v[58:59], v[96:97], v[96:97], v[58:59]
	v_mov_b32_e32 v94, v92
	v_mov_b32_e32 v95, v64
	v_pk_mul_f32 v[62:63], v[38:39], v[38:39]
	v_pk_mul_f32 v[84:85], v[78:79], v[78:79]
	v_pk_add_f32 v[58:59], v[58:59], v[94:95]
	v_mov_b32_e32 v64, v93
	v_pk_add_f32 v[58:59], v[64:65], v[58:59]
	v_mov_b32_e32 v64, v84
	v_mov_b32_e32 v65, v62
	v_pk_add_f32 v[58:59], v[64:65], v[58:59]
	v_mov_b32_e32 v62, v85
	v_pk_add_f32 v[58:59], v[62:63], v[58:59]
	ds_bpermute_b32 v63, v86, v59
	v_lshlrev_b32_e32 v80, 16, v37
	v_and_b32_e32 v81, 0xffff0000, v37
	v_lshlrev_b32_e32 v36, 16, v47
	v_and_b32_e32 v37, 0xffff0000, v47
	v_and_b32_e32 v47, 0xffff0000, v48
	v_pk_mul_f32 v[82:83], v[80:81], v[80:81]
	v_mul_f32_e32 v62, 0xbfb8aa3b, v47
	v_exp_f32_e32 v65, v62
	v_mov_b32_e32 v62, v82
	s_waitcnt lgkmcnt(0)
	v_pk_add_f32 v[58:59], v[62:63], v[58:59]
	ds_bpermute_b32 v63, v87, v59
	v_add_f32_e32 v62, 1.0, v65
	v_rcp_f32_e32 v65, v62
	v_mov_b32_e32 v62, v83
	v_mul_f32_e32 v84, 0xbfb8aa3b, v34
	s_waitcnt lgkmcnt(0)
	v_pk_add_f32 v[58:59], v[62:63], v[58:59]
	ds_bpermute_b32 v63, v88, v59
	ds_bpermute_b32 v62, v91, v58
	v_mul_f32_e32 v85, 0xbfb8aa3b, v35
	v_exp_f32_e32 v84, v84
	v_exp_f32_e32 v85, v85
	v_mul_f32_e32 v82, 0xbfb8aa3b, v36
	s_waitcnt lgkmcnt(0)
	v_pk_add_f32 v[58:59], v[58:59], v[62:63]
	ds_bpermute_b32 v63, v89, v59
	ds_bpermute_b32 v62, v90, v58
	v_mul_f32_e32 v83, 0xbfb8aa3b, v37
	v_exp_f32_e32 v82, v82
	v_exp_f32_e32 v83, v83
	v_add_f32_e32 v64, 1.0, v98
	s_waitcnt lgkmcnt(0)
	v_pk_add_f32 v[58:59], v[58:59], v[62:63]
	ds_bpermute_b32 v63, v90, v59
	ds_bpermute_b32 v62, v89, v58
	v_add_f32_e32 v84, 1.0, v84
	v_add_f32_e32 v85, 1.0, v85
	v_rcp_f32_e32 v64, v64
	v_rcp_f32_e32 v84, v84
	s_waitcnt lgkmcnt(0)
	v_pk_add_f32 v[58:59], v[58:59], v[62:63]
	ds_bpermute_b32 v63, v91, v59
	ds_bpermute_b32 v62, v88, v58
	v_rcp_f32_e32 v85, v85
	v_add_f32_e32 v82, 1.0, v82
	v_add_f32_e32 v83, 1.0, v83
	v_rcp_f32_e32 v82, v82
	s_waitcnt lgkmcnt(0)
	v_pk_add_f32 v[58:59], v[58:59], v[62:63]
	v_rcp_f32_e32 v83, v83
	v_pk_fma_f32 v[58:59], v[58:59], s[10:11], v[66:67] op_sel_hi:[1,1,0]
	v_pk_mul_f32 v[46:47], v[64:65], v[46:47]
	v_mul_f32_e32 v62, 0x4b800000, v59
	v_cmp_gt_f32_e32 vcc, s48, v59
	v_pk_mul_f32 v[64:65], v[84:85], v[34:35]
	v_lshlrev_b32_e32 v48, 16, v49
	v_cndmask_b32_e32 v59, v59, v62, vcc
	v_rsq_f32_e32 v59, v59
	v_pk_mul_f32 v[62:63], v[82:83], v[36:37]
	v_and_b32_e32 v49, 0xffff0000, v49
	v_mul_f32_e32 v34, 0x45800000, v59
	v_cndmask_b32_e32 v34, v59, v34, vcc
	v_pk_mul_f32 v[36:37], v[34:35], v[54:55] op_sel_hi:[0,1]
	v_pk_mul_f32 v[36:37], v[2:3], v[36:37]
	v_cmp_gt_f32_e32 vcc, s48, v58
	v_pk_mul_f32 v[36:37], v[40:41], v[36:37]
	v_pk_mul_f32 v[40:41], v[34:35], v[52:53] op_sel_hi:[0,1]
	v_pk_mul_f32 v[40:41], v[4:5], v[40:41]
	v_lshlrev_b32_e32 v54, 16, v20
	v_pk_mul_f32 v[40:41], v[42:43], v[40:41]
	v_pk_mul_f32 v[42:43], v[34:35], v[50:51] op_sel_hi:[0,1]
	v_pk_mul_f32 v[34:35], v[34:35], v[38:39] op_sel_hi:[0,1]
	v_pk_mul_f32 v[34:35], v[8:9], v[34:35]
	v_pk_mul_f32 v[42:43], v[6:7], v[42:43]
	v_pk_mul_f32 v[38:39], v[44:45], v[34:35]
	v_cvt_pk_bf16_f32 v34, v36, v37
	v_cvt_pk_bf16_f32 v37, v38, v39
	v_mul_f32_e32 v38, 0x4b800000, v58
	v_cndmask_b32_e32 v38, v58, v38, vcc
	v_cvt_pk_bf16_f32 v35, v40, v41
	v_rsq_f32_e32 v40, v38
	v_pk_mul_f32 v[42:43], v[56:57], v[42:43]
	v_add_co_u32_e64 v38, s[0:1], s62, v76
	v_cvt_pk_bf16_f32 v36, v42, v43
	s_nop 0
	v_addc_co_u32_e64 v39, s[0:1], 0, v77, s[0:1]
	global_store_dwordx4 v[38:39], v[34:37], off offset:2048
	v_mul_f32_e32 v42, 0xbfb8aa3b, v49
	v_exp_f32_e32 v43, v42
	v_mul_f32_e32 v34, 0x45800000, v40
	v_cndmask_b32_e32 v34, v40, v34, vcc
	v_pk_mul_f32 v[36:37], v[34:35], v[60:61] op_sel_hi:[0,1]
	v_pk_mul_f32 v[38:39], v[34:35], v[68:69] op_sel_hi:[0,1]
	v_pk_mul_f32 v[40:41], v[34:35], v[78:79] op_sel_hi:[0,1]
	v_mul_f32_e32 v35, 0xbfb8aa3b, v48
	v_exp_f32_e32 v35, v35
	v_pk_mul_f32 v[38:39], v[12:13], v[38:39]
	v_pk_mul_f32 v[36:37], v[10:11], v[36:37]
	v_pk_mul_f32 v[38:39], v[62:63], v[38:39]
	v_add_f32_e32 v35, 1.0, v35
	v_rcp_f32_e32 v42, v35
	v_add_f32_e32 v35, 1.0, v43
	v_rcp_f32_e32 v43, v35
	v_pk_mul_f32 v[34:35], v[34:35], v[80:81] op_sel_hi:[0,1]
	v_pk_mul_f32 v[40:41], v[14:15], v[40:41]
	v_pk_mul_f32 v[34:35], v[16:17], v[34:35]
	v_pk_mul_f32 v[42:43], v[42:43], v[48:49]
	v_pk_mul_f32 v[36:37], v[64:65], v[36:37]
	v_pk_mul_f32 v[40:41], v[46:47], v[40:41]
	v_pk_mul_f32 v[42:43], v[42:43], v[34:35]
	v_cvt_pk_bf16_f32 v35, v38, v39
	v_add_co_u32_e32 v38, vcc, s19, v76
	v_cvt_pk_bf16_f32 v34, v36, v37
	v_cvt_pk_bf16_f32 v36, v40, v41
	v_cvt_pk_bf16_f32 v37, v42, v43
	v_addc_co_u32_e32 v39, vcc, 0, v77, vcc
	v_lshlrev_b32_e32 v40, 16, v28
	v_and_b32_e32 v41, 0xffff0000, v28
	global_store_dwordx4 v[38:39], v[34:37], off offset:2048
	v_lshlrev_b32_e32 v38, 16, v30
	v_and_b32_e32 v39, 0xffff0000, v30
	v_lshlrev_b32_e32 v36, 16, v31
	v_and_b32_e32 v37, 0xffff0000, v31
	v_lshlrev_b32_e32 v34, 16, v32
	v_and_b32_e32 v35, 0xffff0000, v32
; __device__ __forceinline__ float bf2f(u16 h) { return __uint_as_float(((unsigned)h) << 16); }
; __device__ __forceinline__ float siluf(float x) { return x * __builtin_amdgcn_rcpf(1.f + __expf(-x)); }
; __device__ void post0_phase(const Ctx& p) {
;     ...
;     for (int rr = 0; rr < 4; ++rr) {
;       const long row = rbase + rr;
;       {
;         const uint4 raw = r1[rr], gr = r2[rr];
;         float v[8] = {bf2f(raw.x & 0xffff), bf2f(raw.x >> 16), bf2f(raw.y & 0xffff), bf2f(raw.y >> 16),
;                       bf2f(raw.z & 0xffff), bf2f(raw.z >> 16), bf2f(raw.w & 0xffff), bf2f(raw.w >> 16)};
;         float gt[8] = {bf2f(gr.x & 0xffff), bf2f(gr.x >> 16), bf2f(gr.y & 0xffff), bf2f(gr.y >> 16),
;                        bf2f(gr.z & 0xffff), bf2f(gr.z >> 16), bf2f(gr.w & 0xffff), bf2f(gr.w >> 16)};
;         float ss = 0.f;
; #pragma unroll
;         for (int e = 0; e < 8; ++e) ss += v[e] * v[e];
;         ss = wave_sum(ss);
;         const float rs = rsqrtf(ss * (1.f / 512.f) + 1e-6f);
;         float o[8];
; #pragma unroll
;         for (int e = 0; e < 8; ++e) o[e] = v[e] * rs * gg_[e] * siluf(gt[e]);
;         uint4 ov; ov.x = pack2(o[0], o[1]); ov.y = pack2(o[2], o[3]); ov.z = pack2(o[4], o[5]); ov.w = pack2(o[6], o[7]);
;         *(uint4*)(cat + row * 4608 + c0) = ov;
;       }
;       {
;         const uint4 raw = r3[rr], gr = r4[rr];
;         float v[8] = {bf2f(raw.x & 0xffff), bf2f(raw.x >> 16), bf2f(raw.y & 0xffff), bf2f(raw.y >> 16),
;                       bf2f(raw.z & 0xffff), bf2f(raw.z >> 16), bf2f(raw.w & 0xffff), bf2f(raw.w >> 16)};
;         float gt[8] = {bf2f(gr.x & 0xffff), bf2f(gr.x >> 16), bf2f(gr.y & 0xffff), bf2f(gr.y >> 16),
;                        bf2f(gr.z & 0xffff), bf2f(gr.z >> 16), bf2f(gr.w & 0xffff), bf2f(gr.w >> 16)};
;         float ss = 0.f;
; #pragma unroll
;         for (int e = 0; e < 8; ++e) ss += v[e] * v[e];
; #pragma unroll
;         for (int o = 1; o < 16; o <<= 1) ss += __shfl_xor(ss, o, 64);
;         const float rs = rsqrtf(ss * (1.f / 128.f) + 1e-6f);
;         float o[8];
; #pragma unroll
;         for (int e = 0; e < 8; ++e) o[e] = v[e] * rs * gh_[e] * siluf(gt[e]);
;         uint4 ov; ov.x = pack2(o[0], o[1]); ov.y = pack2(o[2], o[3]); ov.z = pack2(o[4], o[5]); ov.w = pack2(o[6], o[7]);
;         *(uint4*)(cat + row * 4608 + 2048 + c0) = ov;
;       }
	v_lshlrev_b32_e32 v30, 16, v33
	v_and_b32_e32 v31, 0xffff0000, v33
	v_lshlrev_b32_e32 v32, 16, v26
	v_and_b32_e32 v33, 0xffff0000, v26
	v_lshlrev_b32_e32 v26, 16, v27
	v_and_b32_e32 v27, 0xffff0000, v27
	v_mul_f32_e32 v42, 0xbfb8aa3b, v40
	v_mul_f32_e32 v43, 0xbfb8aa3b, v41
	v_exp_f32_e32 v42, v42
	v_exp_f32_e32 v43, v43
	v_mul_f32_e32 v44, 0xbfb8aa3b, v26
	v_mul_f32_e32 v45, 0xbfb8aa3b, v27
	v_exp_f32_e32 v44, v44
	v_exp_f32_e32 v45, v45
	v_add_f32_e32 v42, 1.0, v42
	v_add_f32_e32 v43, 1.0, v43
	v_rcp_f32_e32 v42, v42
	v_rcp_f32_e32 v43, v43
	v_add_f32_e32 v44, 1.0, v44
	v_add_f32_e32 v45, 1.0, v45
	v_rcp_f32_e32 v44, v44
	v_rcp_f32_e32 v45, v45
	v_pk_mul_f32 v[40:41], v[42:43], v[40:41]
	v_mul_f32_e32 v43, 0xbfb8aa3b, v32
	v_lshlrev_b32_e32 v28, 16, v29
	v_pk_mul_f32 v[26:27], v[44:45], v[26:27]
	v_exp_f32_e32 v44, v43
	v_mul_f32_e32 v43, 0xbfb8aa3b, v33
	v_exp_f32_e32 v45, v43
	v_and_b32_e32 v29, 0xffff0000, v29
	v_add_f32_e32 v44, 1.0, v44
	v_mul_f32_e32 v50, 0xbfb8aa3b, v28
	v_add_f32_e32 v45, 1.0, v45
	v_mul_f32_e32 v51, 0xbfb8aa3b, v29
	v_rcp_f32_e32 v44, v44
	v_rcp_f32_e32 v45, v45
	v_exp_f32_e32 v50, v50
	v_exp_f32_e32 v51, v51
	v_mov_b32_e32 v42, v38
	v_pk_mul_f32 v[32:33], v[44:45], v[32:33]
	v_add_f32_e32 v44, 1.0, v50
	v_add_f32_e32 v45, 1.0, v51
	v_rcp_f32_e32 v44, v44
	v_rcp_f32_e32 v45, v45
	v_mul_f32_e32 v50, v38, v38
	v_mov_b32_e32 v43, v36
	v_fmac_f32_e32 v50, v39, v39
	v_pk_fma_f32 v[42:43], v[42:43], v[42:43], v[50:51] op_sel_hi:[1,1,0]
	v_pk_mul_f32 v[28:29], v[44:45], v[28:29]
	v_lshlrev_b32_e32 v44, 16, v22
	v_and_b32_e32 v45, 0xffff0000, v22
	v_lshlrev_b32_e32 v22, 16, v23
	v_and_b32_e32 v23, 0xffff0000, v23
	v_mul_f32_e32 v42, 0xbfb8aa3b, v54
	v_pk_mul_f32 v[62:63], v[44:45], v[44:45]
	v_pk_mul_f32 v[48:49], v[34:35], v[34:35]
	v_exp_f32_e32 v68, v42
	v_pk_mul_f32 v[60:61], v[22:23], v[22:23]
	v_mov_b32_e32 v64, v44
	v_mov_b32_e32 v65, v37
	v_mov_b32_e32 v42, v63
	v_lshlrev_b32_e32 v50, 16, v24
	v_and_b32_e32 v51, 0xffff0000, v24
	v_pk_fma_f32 v[42:43], v[64:65], v[64:65], v[42:43]
	v_mov_b32_e32 v62, v60
	v_mov_b32_e32 v63, v48
	v_pk_mul_f32 v[46:47], v[30:31], v[30:31]
	v_pk_mul_f32 v[58:59], v[50:51], v[50:51]
	v_pk_add_f32 v[42:43], v[42:43], v[62:63]
	v_mov_b32_e32 v48, v61
	v_pk_add_f32 v[42:43], v[48:49], v[42:43]
	v_mov_b32_e32 v48, v58
	v_mov_b32_e32 v49, v46
	v_pk_add_f32 v[42:43], v[48:49], v[42:43]
	v_mov_b32_e32 v46, v59
	v_pk_add_f32 v[42:43], v[46:47], v[42:43]
	ds_bpermute_b32 v47, v86, v43
	v_lshlrev_b32_e32 v24, 16, v25
	v_and_b32_e32 v25, 0xffff0000, v25
	v_and_b32_e32 v55, 0xffff0000, v20
	v_lshlrev_b32_e32 v56, 16, v21
	v_and_b32_e32 v57, 0xffff0000, v21
	v_pk_mul_f32 v[20:21], v[24:25], v[24:25]
	v_mul_f32_e32 v46, 0xbfb8aa3b, v55
	v_exp_f32_e32 v49, v46
	v_mov_b32_e32 v46, v20
	s_waitcnt lgkmcnt(0)
	v_pk_add_f32 v[42:43], v[46:47], v[42:43]
	ds_bpermute_b32 v47, v87, v43
	v_add_f32_e32 v20, 1.0, v49
	v_mov_b32_e32 v46, v21
	v_rcp_f32_e32 v49, v20
	v_lshlrev_b32_e32 v52, 16, v18
	s_waitcnt lgkmcnt(0)
	v_pk_add_f32 v[20:21], v[46:47], v[42:43]
	ds_bpermute_b32 v43, v88, v21
	ds_bpermute_b32 v42, v91, v20
	v_and_b32_e32 v53, 0xffff0000, v18
	v_lshlrev_b32_e32 v18, 16, v19
	v_and_b32_e32 v19, 0xffff0000, v19
	v_mul_f32_e32 v46, 0xbfb8aa3b, v18
	s_waitcnt lgkmcnt(0)
	v_pk_add_f32 v[20:21], v[20:21], v[42:43]
	ds_bpermute_b32 v43, v89, v21
	ds_bpermute_b32 v42, v90, v20
	v_mul_f32_e32 v47, 0xbfb8aa3b, v19
	v_exp_f32_e32 v46, v46
	v_exp_f32_e32 v47, v47
	v_mul_f32_e32 v58, 0xbfb8aa3b, v52
	s_waitcnt lgkmcnt(0)
	v_pk_add_f32 v[20:21], v[20:21], v[42:43]
	ds_bpermute_b32 v43, v90, v21
	ds_bpermute_b32 v42, v89, v20
	v_add_f32_e32 v46, 1.0, v46
	v_add_f32_e32 v47, 1.0, v47
	v_rcp_f32_e32 v46, v46
	v_rcp_f32_e32 v47, v47
	s_waitcnt lgkmcnt(0)
	v_pk_add_f32 v[20:21], v[20:21], v[42:43]
	ds_bpermute_b32 v43, v91, v21
	ds_bpermute_b32 v42, v88, v20
	v_pk_mul_f32 v[46:47], v[46:47], v[18:19]
	v_mul_f32_e32 v59, 0xbfb8aa3b, v53
	v_exp_f32_e32 v58, v58
	v_exp_f32_e32 v59, v59
	s_waitcnt lgkmcnt(0)
	v_pk_add_f32 v[20:21], v[20:21], v[42:43]
	v_add_f32_e32 v48, 1.0, v68
	v_pk_fma_f32 v[42:43], v[20:21], s[10:11], v[66:67] op_sel_hi:[1,1,0]
	v_add_f32_e32 v58, 1.0, v58
	v_mul_f32_e32 v20, 0x4b800000, v43
	v_cmp_gt_f32_e32 vcc, s48, v43
	v_add_f32_e32 v59, 1.0, v59
	v_rcp_f32_e32 v48, v48
	v_cndmask_b32_e32 v20, v43, v20, vcc
	v_rsq_f32_e32 v20, v20
	v_rcp_f32_e32 v58, v58
	v_rcp_f32_e32 v59, v59
	v_pk_mul_f32 v[48:49], v[48:49], v[54:55]
	v_mul_f32_e32 v18, 0x45800000, v20
	v_cndmask_b32_e32 v18, v20, v18, vcc
	v_pk_mul_f32 v[20:21], v[18:19], v[38:39] op_sel_hi:[0,1]
	v_pk_mul_f32 v[20:21], v[2:3], v[20:21]
	v_cmp_gt_f32_e32 vcc, s48, v42
	v_pk_mul_f32 v[20:21], v[32:33], v[20:21]
	v_pk_mul_f32 v[32:33], v[18:19], v[36:37] op_sel_hi:[0,1]
	v_pk_mul_f32 v[32:33], v[4:5], v[32:33]
	v_pk_mul_f32 v[52:53], v[58:59], v[52:53]
	v_pk_mul_f32 v[26:27], v[26:27], v[32:33]
	v_pk_mul_f32 v[32:33], v[18:19], v[34:35] op_sel_hi:[0,1]
	v_pk_mul_f32 v[18:19], v[18:19], v[30:31] op_sel_hi:[0,1]
	v_pk_mul_f32 v[18:19], v[8:9], v[18:19]
	v_pk_mul_f32 v[32:33], v[6:7], v[32:33]
	v_pk_mul_f32 v[28:29], v[28:29], v[18:19]
	v_cvt_pk_bf16_f32 v19, v26, v27
	v_mul_f32_e32 v26, 0x4b800000, v42
	v_cndmask_b32_e32 v26, v42, v26, vcc
	v_cvt_pk_bf16_f32 v18, v20, v21
	v_cvt_pk_bf16_f32 v21, v28, v29
	v_rsq_f32_e32 v28, v26
	v_pk_mul_f32 v[32:33], v[40:41], v[32:33]
	v_add_co_u32_e64 v26, s[0:1], s15, v76
	v_cvt_pk_bf16_f32 v20, v32, v33
	s_nop 0
	v_addc_co_u32_e64 v27, s[0:1], 0, v77, s[0:1]
	global_store_dwordx4 v[26:27], v[18:21], off offset:3072
	s_nop 1
	v_mul_f32_e32 v18, 0x45800000, v28
	v_cndmask_b32_e32 v18, v28, v18, vcc
	v_pk_mul_f32 v[20:21], v[18:19], v[44:45] op_sel_hi:[0,1]
	v_pk_mul_f32 v[22:23], v[18:19], v[22:23] op_sel_hi:[0,1]
	v_pk_mul_f32 v[26:27], v[18:19], v[50:51] op_sel_hi:[0,1]
	v_mul_f32_e32 v19, 0xbfb8aa3b, v56
	v_exp_f32_e32 v19, v19
	v_mul_f32_e32 v28, 0xbfb8aa3b, v57
	v_exp_f32_e32 v29, v28
	v_pk_mul_f32 v[22:23], v[12:13], v[22:23]
	v_add_f32_e32 v19, 1.0, v19
	v_rcp_f32_e32 v28, v19
	v_add_f32_e32 v19, 1.0, v29
	v_rcp_f32_e32 v29, v19
	v_pk_mul_f32 v[18:19], v[18:19], v[24:25] op_sel_hi:[0,1]
	v_pk_mul_f32 v[20:21], v[10:11], v[20:21]
	v_pk_mul_f32 v[22:23], v[46:47], v[22:23]
	v_pk_mul_f32 v[26:27], v[14:15], v[26:27]
	v_pk_mul_f32 v[18:19], v[16:17], v[18:19]
	v_pk_mul_f32 v[24:25], v[28:29], v[56:57]
	v_pk_mul_f32 v[20:21], v[52:53], v[20:21]
	v_pk_mul_f32 v[26:27], v[48:49], v[26:27]
	v_pk_mul_f32 v[24:25], v[24:25], v[18:19]
	v_cvt_pk_bf16_f32 v19, v22, v23
	v_add_co_u32_e32 v22, vcc, 0x7000, v76
	v_cvt_pk_bf16_f32 v18, v20, v21
	v_cvt_pk_bf16_f32 v20, v26, v27
	v_cvt_pk_bf16_f32 v21, v24, v25
	v_addc_co_u32_e32 v23, vcc, 0, v77, vcc
	global_store_dwordx4 v[22:23], v[18:21], off offset:3072
	s_cbranch_scc0 .LBB0_219

; template <int DK> ...
;     ...
;   auto scan_load = [&](const int c_) {
;     const long row_ = (long)c_ * 64;
;     SL1(0, rq0, rk0, rt0) SL1(1, rq1, rk1, rt1) SL1(2, rq2, rk2, rt2) SL1(3, rq3, rk3, rt3)
;     if (tid < 256) rv = *(const uint4*)(vg + (row_ + (tid >> 2)) * H0LD + (tid & 3) * 8);
;     {
;       const int d0_ = (w * NA + 0) * 16 + fq * 4;
;       e4n0 = *(const float4*)(em + (long)(ck0 + c_) * CH + d0_);
;       l4n0 = *(const float4*)(elm + (long)(ck0 + c_) * CH + d0_);
;     }
;     if (NA > 1) {
;       const int d0_ = (w * NA + 1) * 16 + fq * 4;
;       e4n1 = *(const float4*)(em + (long)(ck0 + c_) * CH + d0_);
;       l4n1 = *(const float4*)(elm + (long)(ck0 + c_) * CH + d0_);
;     }
;   };
;   scan_load(0);
; __device__ void scan_phase(const Ctx& p) {
;     ...
;       int it = item - 128; int b = it >> 6, h = (it >> 2) & 15, s = it & 3;
;       if (xmap) { const int x = it & 7, j = it >> 3; const int bhh = x * 4 + (j >> 2); b = bhh >> 4; h = bhh & 15; s = j & 3; }
;       const u16* base = h0 + (long)b * SEQ * H0LD;
;       scan_item<128>(base + C_HQ + h * 128, base + C_HF + h * 128, (const u16*)(ws + OFF_KT0H) + (long)h * 128 * 64, base + C_HI + h * 128 + s * 32,
;                      hem + h * 128, helm + h * 128, 2048, b * 128,
;                      (u16*)(ws + OFF_OHGRN) + (long)b * SEQ * 2048 + h * 128 + s * 32);
.LBB0_226:
	s_cmpk_gt_i32 s62, 0x7f
	s_mov_b64 s[4:5], -1
	s_cbranch_scc0 .LBB0_244
	s_add_i32 s4, s62, 0xffffff80
	s_lshl_b32 s5, s62, 2
	s_lshr_b32 s6, s4, 6
	s_and_b32 s5, s5, 28
	s_lshr_b32 s4, s4, 5
	s_add_i32 s9, s5, s4
	s_lshr_b32 s7, s62, 2
	s_lshr_b32 s8, s62, 3
	s_lshr_b32 s10, s9, 4
	s_and_b64 s[4:5], s[0:1], exec
	s_cselect_b32 s52, s10, s6
	s_cselect_b32 s4, s9, s7
	s_cselect_b32 s42, s8, s62
	s_and_b32 s10, s4, 15
	s_mul_i32 s30, s52, 0xf400000
	s_mul_hi_u32 s31, s52, 0xf400000
	s_add_u32 s8, s61, s30
	v_mov_b32_e32 v42, v139
	s_addc_u32 s9, s68, s31
	s_lshl_b32 s28, s10, 8
	s_add_u32 s6, s8, s28
	v_ashrrev_i32_e32 v43, 31, v42
	v_lshrrev_b32_e32 v0, 28, v43
	s_addc_u32 s7, s9, 0
	v_add_u32_e32 v0, v42, v0
	s_add_u32 s4, s6, 0x3000
	v_ashrrev_i32_e32 v50, 4, v0
	v_and_b32_e32 v0, 0x1ffffff0, v0
	v_add_u32_e32 v44, 0x200, v42
	s_addc_u32 s5, s7, 0
	v_sub_u32_e32 v0, v42, v0
	v_ashrrev_i32_e32 v45, 31, v44
	s_add_u32 s6, s6, 0x4000
	v_lshlrev_b32_e32 v38, 3, v0
	v_lshrrev_b32_e32 v0, 28, v45
	s_addc_u32 s7, s7, 0
	s_lshl_b32 s11, s10, 14
	v_add_u32_e32 v0, v44, v0
	s_add_u32 s54, s41, s11
	v_mov_b64_e32 v[14:15], s[4:5]
	v_mov_b64_e32 v[16:17], s[6:7]
	s_waitcnt vmcnt(0)
	v_lshlrev_b64 v[66:67], 4, v[42:43]
	v_ashrrev_i32_e32 v43, 4, v0
	v_and_b32_e32 v0, 0x1ffffff0, v0
	s_addc_u32 s55, s46, 0
	s_lshl_b32 s34, s52, 7
	v_mad_i64_i32 v[2:3], s[4:5], v50, s51, v[14:15]
	v_mad_i64_i32 v[6:7], s[4:5], v50, s51, v[16:17]
	s_mov_b32 s35, s53
	v_sub_u32_e32 v0, v44, v0
	s_lshl_b64 s[4:5], s[34:35], 18
	v_lshlrev_b32_e32 v40, 3, v0
	v_ashrrev_i32_e32 v39, 31, v38
	s_add_u32 s4, s54, s4
	v_ashrrev_i32_e32 v41, 31, v40
	v_lshlrev_b64 v[4:5], 1, v[38:39]
	s_addc_u32 s5, s55, s5
	v_mad_i64_i32 v[14:15], s[6:7], v43, s51, v[14:15]
	v_lshlrev_b64 v[18:19], 1, v[40:41]
	v_mad_i64_i32 v[16:17], s[6:7], v43, s51, v[16:17]
	v_lshlrev_b64 v[68:69], 4, v[44:45]
	v_lshl_add_u64 v[2:3], v[2:3], 0, v[4:5]
	v_lshl_add_u64 v[6:7], v[6:7], 0, v[4:5]
	v_lshl_add_u64 v[10:11], s[4:5], 0, v[66:67]
	v_lshl_add_u64 v[14:15], v[14:15], 0, v[18:19]
	v_lshl_add_u64 v[18:19], v[16:17], 0, v[18:19]
	v_lshl_add_u64 v[22:23], s[4:5], 0, v[68:69]
	global_load_dwordx4 v[2:5], v[2:3], off
	s_nop 0
	global_load_dwordx4 v[6:9], v[6:7], off
	s_movk_i32 s6, 0xff
	global_load_dwordx4 v[10:13], v[10:11], off
	s_nop 0
	global_load_dwordx4 v[14:17], v[14:15], off
	s_nop 0
	global_load_dwordx4 v[18:21], v[18:19], off
	v_cmp_gt_i32_e64 s[4:5], s97, v42
	global_load_dwordx4 v[22:25], v[22:23], off
	v_cmp_lt_i32_e32 vcc, s6, v42
	v_lshlrev_b32_e32 v45, 3, v42
	s_and_saveexec_b64 s[6:7], vcc
	s_xor_b64 s[6:7], exec, s[6:7]
	v_lshlrev_b32_e32 v45, 3, v42
	v_lshrrev_b32_e32 v51, 2, v42
	v_and_b32_e32 v0, 24, v45
	v_mad_u64_u32 v[46:47], s[12:13], v51, s51, 0
	v_mov_b32_e32 v52, v0
	v_mov_b64_e32 v[48:49], v[0:1]
	s_or_saveexec_b64 s[6:7], s[6:7]
	v_mov_b32_e32 v0, v1
	s_lshl_b32 s10, s10, 7
	v_mov_b64_e32 v[26:27], v[0:1]
	v_mov_b64_e32 v[28:29], v[0:1]
	s_xor_b64 exec, exec, s[6:7]
	s_cbranch_execz .LBB0_231
	s_lshl_b32 s11, s10, 1
	s_add_u32 s8, s8, s11
	s_addc_u32 s9, s9, 0
	s_lshl_b32 s11, s42, 6
	s_and_b32 s11, s11, 0xc0
	s_add_u32 s8, s8, s11
	s_addc_u32 s9, s9, 0
	s_add_u32 s8, s8, 0x5000
	s_addc_u32 s9, s9, 0
	v_ashrrev_i32_e32 v51, 2, v42
	v_mov_b64_e32 v[26:27], s[8:9]
	v_and_b32_e32 v0, 24, v45
	v_mad_i64_i32 v[26:27], s[8:9], v51, s51, v[26:27]
	v_lshlrev_b32_e32 v28, 1, v0
	v_mov_b32_e32 v29, v1
	v_lshl_add_u64 v[26:27], v[26:27], 0, v[28:29]
	global_load_dwordx4 v[26:29], v[26:27], off
	v_mad_i64_i32 v[46:47], s[8:9], v51, s51, 0
	v_mov_b64_e32 v[48:49], v[0:1]
	v_mov_b32_e32 v52, v0
.LBB0_231:
	s_or_b64 exec, exec, s[6:7]
	s_lshl_b32 s8, s10, 2
	s_add_u32 s6, s27, s8
	s_addc_u32 s7, s60, 0
	s_add_u32 s8, s84, s8
	s_addc_u32 s9, s87, 0
	s_lshl_b64 s[38:39], s[52:53], 25
	v_ashrrev_i32_e32 v53, 6, v42
	v_bfe_u32 v59, v42, 4, 2
	s_lshl_b64 s[10:11], s[34:35], 13
	v_lshlrev_b32_e32 v60, 4, v53
	v_lshlrev_b32_e32 v61, 2, v59
	s_add_u32 s12, s6, s10
	v_or_b32_e32 v54, v61, v60
	s_addc_u32 s13, s7, s11
	v_ashrrev_i32_e32 v55, 31, v54
	s_add_u32 s10, s8, s10
	v_lshlrev_b64 v[56:57], 2, v[54:55]
	s_addc_u32 s11, s9, s11
	v_lshl_add_u64 v[30:31], s[12:13], 0, v[56:57]
	v_lshl_add_u64 v[32:33], s[10:11], 0, v[56:57]
	s_waitcnt vmcnt(0)
; __device__ __forceinline__ int ltid() { int t = threadIdx.x; asm volatile("" : "+v"(t)); return t; }
; #define RAWSYNC do { asm volatile("s_waitcnt lgkmcnt(0)" ::: "memory"); __builtin_amdgcn_s_barrier(); asm volatile("" ::: "memory"); } while (0)
; template <int DK> ...
;     ...
;   const int tid = ltid(), w = tid >> 6, lane = tid & 63, fr = lane & 15, fq = lane >> 4;
;   f32x4 S[NA][2];
; #pragma unroll
;   for (int a = 0; a < NA; ++a) { S[a][0] = (f32x4){0.f, 0.f, 0.f, 0.f}; S[a][1] = (f32x4){0.f, 0.f, 0.f, 0.f}; }
;   uint4 rq0, rq1, rq2, rq3, rk0, rk1, rk2, rk3, rt0, rt1, rt2, rt3, rv;
;   float4 e4n0, e4n1, l4n0, l4n1;
;   rv = make_uint4(0, 0, 0, 0);
;   rq2 = rq3 = rk2 = rk3 = rt2 = rt3 = rv;
;   e4n1 = l4n1 = make_float4(0.f, 0.f, 0.f, 0.f);
;     ...
;   auto scan_load = [&](const int c_) {
;     const long row_ = (long)c_ * 64;
;     SL1(0, rq0, rk0, rt0) SL1(1, rq1, rk1, rt1) SL1(2, rq2, rk2, rt2) SL1(3, rq3, rk3, rt3)
;     if (tid < 256) rv = *(const uint4*)(vg + (row_ + (tid >> 2)) * H0LD + (tid & 3) * 8);
;     {
;       const int d0_ = (w * NA + 0) * 16 + fq * 4;
;       e4n0 = *(const float4*)(em + (long)(ck0 + c_) * CH + d0_);
;       l4n0 = *(const float4*)(elm + (long)(ck0 + c_) * CH + d0_);
;     }
;     if (NA > 1) {
;       const int d0_ = (w * NA + 1) * 16 + fq * 4;
;       e4n1 = *(const float4*)(em + (long)(ck0 + c_) * CH + d0_);
;       l4n1 = *(const float4*)(elm + (long)(ck0 + c_) * CH + d0_);
;     }
;   };
;   scan_load(0);
; #pragma unroll 1
;   for (int c = 0; c < 128; ++c) {
;     const long row = (long)c * 64;
;     RAWSYNC;
	global_load_dwordx4 v[34:37], v[30:31], off
	s_nop 0
	global_load_dwordx4 v[30:33], v[32:33], off
	v_lshl_add_u64 v[70:71], s[6:7], 0, v[56:57]
	s_movk_i32 s6, 0x110
	s_lshl_b32 s35, s42, 6
	v_lshlrev_b32_e32 v0, 1, v38
	v_lshl_add_u64 v[72:73], s[8:9], 0, v[56:57]
	v_mul_lo_u32 v56, v50, s6
	s_add_i32 s34, s34, 1
	s_and_b32 s35, s35, 0xc0
	v_add3_u32 v0, 16, v0, v56
	v_lshrrev_b32_e32 v56, 3, v42
	s_movk_i32 s8, 0x90
	v_lshlrev_b32_e32 v45, 1, v45
	v_lshrrev_b32_e32 v44, 3, v44
	s_add_u32 s56, s35, s30
	v_mul_lo_u32 v56, v56, s8
	v_and_b32_e32 v45, 0x70, v45
	v_mul_lo_u32 v44, v44, s8
	s_addc_u32 s57, 0, s31
	v_add3_u32 v92, 16, v56, v45
	v_add3_u32 v94, 16, v44, v45
	v_mul_u32_u24_e32 v44, 0x90, v52
	v_lshlrev_b32_e32 v45, 1, v51
	v_ashrrev_i32_e32 v52, 7, v42
	v_lshl_add_u64 v[46:47], s[56:57], 0, v[46:47]
	v_and_b32_e32 v58, 15, v42
	v_add3_u32 v95, 16, v44, v45
	v_readlane_b32 s7, v252, 35
	v_lshlrev_b32_e32 v44, 4, v52
	v_lshl_add_u64 v[46:47], v[48:49], 1, v[46:47]
	v_lshl_add_u32 v51, v54, 1, s7
	v_or_b32_e32 v54, v44, v58
	v_lshl_add_u64 v[76:77], s[66:67], 0, v[46:47]
	v_mov_b64_e32 v[46:47], s[30:31]
	v_lshlrev_b32_e32 v55, 1, v40
	v_mul_lo_u32 v56, v43, s6
	v_mov_b32_e32 v45, s7
	v_mul_lo_u32 v42, v54, s6
	v_and_or_b32 v57, v60, 16, v58
	v_mad_i64_i32 v[48:49], s[30:31], v43, s51, v[46:47]
	v_add3_u32 v93, 16, v55, v56
	v_add_u32_e32 v96, 16, v42
	v_or_b32_e32 v56, v61, v44
	v_mad_u32_u24 v61, v57, s6, v45
	v_lshlrev_b32_e32 v45, 7, v54
	v_lshl_add_u64 v[40:41], v[40:41], 1, v[48:49]
	v_lshlrev_b32_e32 v97, 4, v59
	v_sub_u32_e32 v45, v96, v45
	v_lshl_add_u64 v[78:79], s[66:67], 0, v[40:41]
	v_mad_i64_i32 v[40:41], s[30:31], v50, s51, v[46:47]
	v_add_u32_e32 v98, v45, v97
	v_ashrrev_i32_e32 v45, 31, v44
	v_lshl_add_u64 v[38:39], v[38:39], 1, v[40:41]
	v_lshlrev_b32_e32 v42, 1, v53
	v_lshl_add_u64 v[80:81], s[66:67], 0, v[38:39]
	v_lshl_or_b32 v38, v59, 14, s38
	v_mov_b32_e32 v39, s39
	v_lshlrev_b64 v[40:41], 12, v[44:45]
	v_and_b32_e32 v55, 2, v42
	v_add_u32_e32 v42, 16, v97
	v_or_b32_e32 v54, v60, v58
	v_lshl_add_u64 v[38:39], v[38:39], 0, v[40:41]
	v_lshlrev_b32_e32 v40, 5, v53
	v_mad_u32_u24 v99, v57, s8, v42
	v_mad_u64_u32 v[74:75], s[6:7], v54, s8, v[42:43]
	v_lshl_or_b32 v57, v55, 4, v58
	v_or_b32_e32 v38, s35, v38
	v_and_b32_e32 v40, 32, v40
	v_lshlrev_b32_e32 v41, 1, v58
	v_mul_u32_u24_e32 v54, 0x110, v58
	v_cmp_le_i32_e64 s[6:7], v55, v52
	v_mul_u32_u24_e32 v60, 0x110, v57
	v_mul_lo_u32 v62, v56, s8
	v_or_b32_e32 v63, 1, v56
	v_or_b32_e32 v64, 2, v56
	v_or_b32_e32 v65, 3, v56
	v_cmp_ge_i32_e64 s[8:9], v55, v52
	v_or_b32_e32 v52, 16, v57
	v_mul_u32_u24_e32 v55, 0x90, v58
	v_lshl_add_u32 v85, v57, 1, 16
	v_or3_b32 v38, v38, v40, v41
	v_mov_b32_e32 v84, 0
	v_cmp_gt_i32_e64 s[10:11], v57, v56
	v_cmp_gt_i32_e64 s[12:13], v57, v63
	v_cmp_gt_i32_e64 s[14:15], v57, v64
	v_cmp_gt_i32_e64 s[16:17], v57, v65
	v_cmp_gt_i32_e64 s[18:19], v52, v56
	v_cmp_gt_i32_e64 s[20:21], v52, v63
	v_cmp_gt_i32_e64 s[22:23], v52, v64
	v_cmp_gt_i32_e64 s[24:25], v52, v65
	s_mov_b32 s29, s53
	v_lshl_add_u64 v[82:83], s[66:67], 0, v[38:39]
	s_mov_b32 s35, 0
	v_add_u32_e32 v75, v51, v54
	v_add_u32_e32 v100, v61, v97
	v_add_u32_e32 v101, v42, v55
	v_add_u32_e32 v102, v42, v60
	v_add_u32_e32 v103, v85, v62
	v_mov_b32_e32 v85, v84
	v_mov_b32_e32 v86, v84
	v_mov_b32_e32 v87, v84
	v_mov_b32_e32 v88, v84
	v_mov_b32_e32 v89, v84
	v_mov_b32_e32 v90, v84
	v_mov_b32_e32 v91, v84
	s_branch .LBB0_233
; __device__ __forceinline__ u16 f2bf(float f) { return (u16)(pack2(f, 0.f) & 0xffffu); }
; #define RAWSYNC do { asm volatile("s_waitcnt lgkmcnt(0)" ::: "memory"); __builtin_amdgcn_s_barrier(); asm volatile("" ::: "memory"); } while (0)
; template <int DK> ...
;     ...
;     RAWSYNC;
;     {
;       const int ti = w >> 1, tv = w & 1;
;       f32x4 a = {0.f, 0.f, 0.f, 0.f};
; #pragma unroll
;       for (int ks = 0; ks < DK / 32; ++ks) {
;         bf16x8 fb = *(const bf16x8*)(ST + (tv * 16 + fr) * PQ + ks * 32 + fq * 8);
;         a = __builtin_amdgcn_mfma_f32_16x16x32_bf16(qf[ks], fb, a, 0, 0, 0);
;       }
; #pragma unroll
;       for (int ks = 0; ks < 2; ++ks) {
;         bf16x8 fa = *(const bf16x8*)(Pm + (ti * 16 + fr) * 72 + ks * 32 + fq * 8);
;         bf16x8 fb = *(const bf16x8*)(VT + (tv * 16 + fr) * 72 + ks * 32 + fq * 8);
;         a = __builtin_amdgcn_mfma_f32_16x16x32_bf16(fa, fb, a, 0, 0, 0);
;       }
; #pragma unroll
;       for (int r = 0; r < 4; ++r) og[(row + ti * 16 + fq * 4 + r) * 2048 + tv * 16 + fr] = f2bf(a[r]);
;     }
; #pragma unroll
;     for (int a = 0; a < NA; ++a) {
;       const int dt = w * NA + a;
; #pragma unroll
;       for (int tv = 0; tv < 2; ++tv) {
;         f32x4 u = {0.f, 0.f, 0.f, 0.f};
; #pragma unroll
;         for (int ks = 0; ks < 2; ++ks) {
;           bf16x8 fa = *(const bf16x8*)(KtT + (dt * 16 + fr) * 72 + ks * 32 + fq * 8);
;           bf16x8 fb = *(const bf16x8*)(VT + (tv * 16 + fr) * 72 + ks * 32 + fq * 8);
;           u = __builtin_amdgcn_mfma_f32_16x16x32_bf16(fa, fb, u, 0, 0, 0);
;         }
;         S[a][tv][0] = e4[a].x * l4[a].x * S[a][tv][0] + l4[a].x * u[0];
;         S[a][tv][1] = e4[a].y * l4[a].y * S[a][tv][1] + l4[a].y * u[1];
;         S[a][tv][2] = e4[a].z * l4[a].z * S[a][tv][2] + l4[a].z * u[2];
;         S[a][tv][3] = e4[a].w * l4[a].w * S[a][tv][3] + l4[a].w * u[3];
;       }
;     }
.LBB0_232:
	s_or_b64 exec, exec, s[30:31]
	s_nop 5
	v_cvt_pk_bf16_f32 v62, v62, s0
	v_cndmask_b32_e64 v62, v62, 0, s[18:19]
	ds_write_b16 v103, v62 offset:57888
	v_cvt_pk_bf16_f32 v62, v63, s0
	v_cndmask_b32_e64 v62, v62, 0, s[20:21]
	ds_write_b16 v103, v62 offset:58032
	v_cvt_pk_bf16_f32 v62, v64, s0
	v_cndmask_b32_e64 v62, v62, 0, s[22:23]
	ds_write_b16 v103, v62 offset:58176
	v_cvt_pk_bf16_f32 v62, v65, s0
	v_cndmask_b32_e64 v62, v62, 0, s[24:25]
	ds_write_b16 v103, v62 offset:58320
	s_waitcnt lgkmcnt(0)
	s_barrier
	ds_read_b128 v[216:219], v100
	ds_read_b128 v[220:223], v100 offset:64
	ds_read_b128 v[224:227], v100 offset:128
	ds_read_b128 v[228:231], v100 offset:192
	ds_read_b128 v[232:235], v98 offset:57856
	ds_read_b128 v[236:239], v99 offset:53248
	ds_read_b128 v[240:243], v98 offset:57920
	ds_read_b128 v[244:247], v99 offset:53312
	s_brev_b32 s30, 32
	s_add_i32 s35, s35, 1
	v_lshl_add_u64 v[76:77], v[76:77], 0, s[70:71]
	v_lshl_add_u64 v[78:79], v[78:79], 0, s[70:71]
	v_lshl_add_u64 v[80:81], v[80:81], 0, s[70:71]
	s_cmpk_lg_i32 s35, 0x80
	s_waitcnt lgkmcnt(7)
	v_mfma_f32_16x16x32_bf16 v[58:61], v[58:61], v[216:219], 0
	s_waitcnt lgkmcnt(6)
	v_mfma_f32_16x16x32_bf16 v[54:57], v[54:57], v[220:223], v[58:61]
	s_waitcnt lgkmcnt(5)
	v_mfma_f32_16x16x32_bf16 v[50:53], v[50:53], v[224:227], v[54:57]
	s_waitcnt lgkmcnt(4)
	v_mfma_f32_16x16x32_bf16 v[46:49], v[46:49], v[228:231], v[50:53]
	v_pk_mul_f32 v[58:59], v[30:31], v[34:35]
	v_pk_mul_f32 v[60:61], v[32:33], v[36:37]
	s_waitcnt lgkmcnt(2)
	v_mfma_f32_16x16x32_bf16 v[46:49], v[232:235], v[236:239], v[46:49]
	s_waitcnt lgkmcnt(0)
	v_mfma_f32_16x16x32_bf16 v[46:49], v[240:243], v[244:247], v[46:49]
	v_lshl_add_u64 v[50:51], v[82:83], 0, s[28:29]
	v_add_co_u32_e32 v52, vcc, s30, v50
	s_mov_b32 s30, 0x4001000
	s_nop 4
	v_cvt_pk_bf16_f32 v46, v46, s0
	v_addc_co_u32_e32 v53, vcc, 0, v51, vcc
	global_store_short v[52:53], v46, off
	v_add_co_u32_e32 v46, vcc, s30, v50
	v_cvt_pk_bf16_f32 v52, v47, s0
	s_nop 0
	v_addc_co_u32_e32 v47, vcc, 0, v51, vcc
	s_mov_b32 s30, 0x4002000
	global_store_short v[46:47], v52, off
	v_add_co_u32_e32 v46, vcc, s30, v50
	v_cvt_pk_bf16_f32 v48, v48, s0
	s_nop 0
	v_addc_co_u32_e32 v47, vcc, 0, v51, vcc
	s_mov_b32 s30, 0x4003000
	global_store_short v[46:47], v48, off
	v_add_co_u32_e32 v46, vcc, s30, v50
	v_cvt_pk_bf16_f32 v48, v49, s0
	s_nop 0
	v_addc_co_u32_e32 v47, vcc, 0, v51, vcc
	global_store_short v[46:47], v48, off
	ds_read_b128 v[216:219], v74 offset:34816
	ds_read_b128 v[224:227], v101 offset:53248
	ds_read_b128 v[220:223], v74 offset:34880
	ds_read_b128 v[228:231], v101 offset:53312
	ds_read_b128 v[232:235], v101 offset:55552
	ds_read_b128 v[236:239], v101 offset:55616
	s_mov_b64 s[30:31], 0x40000
	v_lshl_add_u64 v[82:83], v[82:83], 0, s[30:31]
	s_waitcnt lgkmcnt(4)
	v_mfma_f32_16x16x32_bf16 v[46:49], v[216:219], v[224:227], 0
	s_waitcnt lgkmcnt(2)
	v_mfma_f32_16x16x32_bf16 v[46:49], v[220:223], v[228:231], v[46:49]
	s_waitcnt lgkmcnt(1)
	v_mfma_f32_16x16x32_bf16 v[34:37], v[216:219], v[232:235], 0
	s_waitcnt lgkmcnt(0)
	v_mfma_f32_16x16x32_bf16 v[34:37], v[220:223], v[236:239], v[34:37]
	s_nop 7
	v_pk_mul_f32 v[48:49], v[32:33], v[48:49]
	v_pk_mul_f32 v[46:47], v[30:31], v[46:47]
	v_pk_fma_f32 v[86:87], v[86:87], v[60:61], v[48:49]
	v_pk_fma_f32 v[84:85], v[84:85], v[58:59], v[46:47]
	s_nop 7
	v_pk_mul_f32 v[32:33], v[32:33], v[36:37]
	v_pk_mul_f32 v[30:31], v[30:31], v[34:35]
	v_pk_fma_f32 v[90:91], v[90:91], v[60:61], v[32:33]
	v_pk_fma_f32 v[88:89], v[88:89], v[58:59], v[30:31]
	s_waitcnt vmcnt(0)
	v_mov_b64_e32 v[30:31], v[42:43]
	v_mov_b64_e32 v[34:35], v[38:39]
	v_mov_b64_e32 v[32:33], v[44:45]
	v_mov_b64_e32 v[36:37], v[40:41]
	s_cbranch_scc0 .LBB0_245

; template <int DK> ...
;     ...
;     SW1(0, rq0, rk0, rt0) SW1(1, rq1, rk1, rt1) SW1(2, rq2, rk2, rt2) SW1(3, rq3, rk3, rt3)
;     if (tid < 256) {
;       const int r = tid >> 2, c8 = (tid & 3) * 8;
;       VT[(c8 + 0) * 72 + r] = (u16)(rv.x & 0xffff); VT[(c8 + 1) * 72 + r] = (u16)(rv.x >> 16);
;       VT[(c8 + 2) * 72 + r] = (u16)(rv.y & 0xffff); VT[(c8 + 3) * 72 + r] = (u16)(rv.y >> 16);
;       VT[(c8 + 4) * 72 + r] = (u16)(rv.z & 0xffff); VT[(c8 + 5) * 72 + r] = (u16)(rv.z >> 16);
;       VT[(c8 + 6) * 72 + r] = (u16)(rv.w & 0xffff); VT[(c8 + 7) * 72 + r] = (u16)(rv.w >> 16);
;     }
; #pragma unroll
;     for (int a = 0; a < NA; ++a) {
;       const int d0 = (w * NA + a) * 16 + fq * 4;
;       e4[a] = (a == 0) ? e4n0 : e4n1; l4[a] = (a == 0) ? l4n0 : l4n1;
; #pragma unroll
;       for (int tv = 0; tv < 2; ++tv) {
;         uint2 v;
;         v.x = pack2(S[a][tv][0] * e4[a].x, S[a][tv][1] * e4[a].y);
;         v.y = pack2(S[a][tv][2] * e4[a].z, S[a][tv][3] * e4[a].w);
;         *(uint2*)(ST + (tv * 16 + fr) * PQ + d0) = v;
;       }
;     }
;     if (c + 1 < 128) scan_load(c + 1);
.LBB0_235:
	s_or_b64 exec, exec, s[30:31]
	s_waitcnt vmcnt(0)
	v_pk_mul_f32 v[38:39], v[84:85], v[34:35]
	v_pk_mul_f32 v[40:41], v[86:87], v[36:37]
	v_cvt_pk_bf16_f32 v38, v38, v39
	v_cvt_pk_bf16_f32 v39, v40, v41
	ds_write_b64 v75, v[38:39]
	v_pk_mul_f32 v[38:39], v[88:89], v[34:35]
	v_pk_mul_f32 v[40:41], v[90:91], v[36:37]
	v_cvt_pk_bf16_f32 v38, v38, v39
	v_cvt_pk_bf16_f32 v39, v40, v41
	s_cmpk_eq_i32 s35, 0x7f
	ds_write_b64 v75, v[38:39] offset:4352
	s_cbranch_scc1 .LBB0_239
	v_lshl_add_u64 v[2:3], v[80:81], 0, s[28:29]
	v_add_co_u32_e32 v4, vcc, 0xfbeb000, v2
	s_add_i32 s52, s34, s35
	s_nop 0
	v_addc_co_u32_e32 v5, vcc, 0, v3, vcc
	v_add_co_u32_e32 v6, vcc, 0xfbec000, v2
	v_lshl_add_u64 v[14:15], v[78:79], 0, s[28:29]
	s_nop 0
	v_addc_co_u32_e32 v7, vcc, 0, v3, vcc
	s_lshl_b64 s[30:31], s[52:53], 18
	v_add_co_u32_e32 v16, vcc, 0xfbeb000, v14
	s_add_u32 s30, s54, s30
	s_nop 0
	v_addc_co_u32_e32 v17, vcc, 0, v15, vcc
	s_addc_u32 s31, s55, s31
	v_add_co_u32_e32 v18, vcc, 0xfbec000, v14
	v_lshl_add_u64 v[10:11], s[30:31], 0, v[66:67]
	s_nop 0
	v_addc_co_u32_e32 v19, vcc, 0, v15, vcc
	v_lshl_add_u64 v[22:23], s[30:31], 0, v[68:69]
	global_load_dwordx4 v[2:5], v[4:5], off
	s_nop 0
	global_load_dwordx4 v[6:9], v[6:7], off
	s_nop 0
	global_load_dwordx4 v[10:13], v[10:11], off
	s_nop 0
	global_load_dwordx4 v[14:17], v[16:17], off
	s_nop 0
	global_load_dwordx4 v[18:21], v[18:19], off
	s_nop 0
	global_load_dwordx4 v[22:25], v[22:23], off
	s_and_saveexec_b64 s[30:31], s[4:5]
	s_cbranch_execz .LBB0_238
	v_lshl_add_u64 v[26:27], v[76:77], 0, s[28:29]
	v_add_co_u32_e32 v26, vcc, 0xfbed000, v26
	s_nop 1
	v_addc_co_u32_e32 v27, vcc, 0, v27, vcc
	global_load_dwordx4 v[26:29], v[26:27], off
.LBB0_238:
	s_or_b64 exec, exec, s[30:31]
	s_lshl_b64 s[30:31], s[52:53], 13
	v_lshl_add_u64 v[38:39], v[70:71], 0, s[30:31]
	v_lshl_add_u64 v[42:43], v[72:73], 0, s[30:31]
	global_load_dwordx4 v[38:41], v[38:39], off
	s_nop 0
	global_load_dwordx4 v[42:45], v[42:43], off
	s_branch .LBB0_240

; __device__ __forceinline__ u16 f2bf(float f) { return (u16)(pack2(f, 0.f) & 0xffffu); }
; template <int DK> ...
;     ...
;     bf16x8 qf[DK / 32];
;     {
;       const int ti = w >> 1;
; #pragma unroll
;       for (int ks = 0; ks < DK / 32; ++ks) qf[ks] = *(const bf16x8*)(Qt + (ti * 16 + fr) * PQ + ks * 32 + fq * 8);
; #pragma unroll
;       for (int x = 0; x < 2; ++x) {
;         const int tj = (w & 1) * 2 + x;
;         f32x4 a = {0.f, 0.f, 0.f, 0.f};
;         if (tj <= ti) {
; #pragma unroll
;           for (int ks = 0; ks < DK / 32; ++ks) {
;             bf16x8 fb = *(const bf16x8*)(Kt + (tj * 16 + fr) * PQ + ks * 32 + fq * 8);
;             a = __builtin_amdgcn_mfma_f32_16x16x32_bf16(qf[ks], fb, a, 0, 0, 0);
;           }
;         }
; #pragma unroll
;         for (int r = 0; r < 4; ++r) {
;           int i = ti * 16 + fq * 4 + r, j = tj * 16 + fr;
;           Pm[i * 72 + j] = f2bf(j <= i ? a[r] : 0.f);
;         }
;       }
.LBB0_240:
	s_waitcnt lgkmcnt(0)
	s_barrier
	v_add_u32_e32 v46, v96, v97
	ds_read_b128 v[58:61], v46
	ds_read_b128 v[54:57], v46 offset:64
	ds_read_b128 v[50:53], v46 offset:128
	ds_read_b128 v[46:49], v46 offset:192
	v_mov_b32_e32 v62, 0
	v_mov_b32_e32 v63, 0
	v_mov_b32_e32 v64, 0
	v_mov_b32_e32 v65, 0
	s_and_saveexec_b64 s[30:31], s[6:7]
	s_cbranch_execz .LBB0_242
	ds_read_b128 v[216:219], v102 offset:17408
	ds_read_b128 v[220:223], v102 offset:17472
	ds_read_b128 v[224:227], v102 offset:17536
	ds_read_b128 v[228:231], v102 offset:17600
	s_waitcnt lgkmcnt(3)
	v_mfma_f32_16x16x32_bf16 v[62:65], v[58:61], v[216:219], 0
	s_waitcnt lgkmcnt(2)
	v_mfma_f32_16x16x32_bf16 v[62:65], v[54:57], v[220:223], v[62:65]
	s_waitcnt lgkmcnt(1)
	v_mfma_f32_16x16x32_bf16 v[62:65], v[50:53], v[224:227], v[62:65]
	s_waitcnt lgkmcnt(0)
	v_mfma_f32_16x16x32_bf16 v[62:65], v[46:49], v[228:231], v[62:65]
.LBB0_242:
	s_or_b64 exec, exec, s[30:31]
	s_nop 6
	v_cvt_pk_bf16_f32 v62, v62, s0
	v_cndmask_b32_e64 v62, v62, 0, s[10:11]
	ds_write_b16 v103, v62 offset:57856
	v_cvt_pk_bf16_f32 v62, v63, s0
	v_cndmask_b32_e64 v62, v62, 0, s[12:13]
	ds_write_b16 v103, v62 offset:58000
	v_cvt_pk_bf16_f32 v62, v64, s0
	v_cndmask_b32_e64 v62, v62, 0, s[14:15]
	ds_write_b16 v103, v62 offset:58144
	v_cvt_pk_bf16_f32 v62, v65, s0
	v_cndmask_b32_e64 v62, v62, 0, s[16:17]
	ds_write_b16 v103, v62 offset:58288
	s_and_saveexec_b64 s[30:31], s[8:9]
	s_xor_b64 s[30:31], exec, s[30:31]
	s_or_saveexec_b64 s[30:31], s[30:31]
	v_mov_b32_e32 v62, 0
	v_mov_b32_e32 v63, 0
	v_mov_b32_e32 v64, 0
	v_mov_b32_e32 v65, 0
	s_xor_b64 exec, exec, s[30:31]
	s_cbranch_execz .LBB0_232
	ds_read_b128 v[216:219], v102 offset:21760
	ds_read_b128 v[220:223], v102 offset:21824
	ds_read_b128 v[224:227], v102 offset:21888
	ds_read_b128 v[228:231], v102 offset:21952
	s_waitcnt lgkmcnt(3)
	v_mfma_f32_16x16x32_bf16 v[62:65], v[58:61], v[216:219], 0
	s_waitcnt lgkmcnt(2)
	v_mfma_f32_16x16x32_bf16 v[62:65], v[54:57], v[220:223], v[62:65]
	s_waitcnt lgkmcnt(1)
	v_mfma_f32_16x16x32_bf16 v[62:65], v[50:53], v[224:227], v[62:65]
	s_waitcnt lgkmcnt(0)
	v_mfma_f32_16x16x32_bf16 v[62:65], v[46:49], v[228:231], v[62:65]
	s_branch .LBB0_232

; template <int DK> ...
;     ...
;   auto scan_load = [&](const int c_) {
;     const long row_ = (long)c_ * 64;
;     SL1(0, rq0, rk0, rt0) SL1(1, rq1, rk1, rt1) SL1(2, rq2, rk2, rt2) SL1(3, rq3, rk3, rt3)
;     if (tid < 256) rv = *(const uint4*)(vg + (row_ + (tid >> 2)) * H0LD + (tid & 3) * 8);
; __device__ void scan_phase(const Ctx& p) {
;     ...
;     if (item < 128) {
;       int b = item >> 6, h = (item >> 4) & 3, s = item & 15;
;       if (xmap) { const int x = item & 7; b = x >> 2; h = x & 3; s = item >> 3; }
;       const u16* base = h0 + (long)b * SEQ * H0LD;
;       scan_item<256>(base + C_GQ + h * 256, base + C_GK + h * 256, (const u16*)(ws + OFF_KT0G) + (long)h * 256 * 64, base + C_GV + h * 512 + s * 32,
;                      gem + h * 256, gelm + h * 256, 1024, b * 128,
;                      (u16*)(ws + OFF_OGLA) + (long)b * SEQ * 2048 + h * 512 + s * 32);
.LBB0_246:
	v_mov_b32_e32 v76, v139
	s_ashr_i32 s6, s62, 6
	v_ashrrev_i32_e32 v77, 31, v76
	v_lshrrev_b32_e32 v0, 27, v77
	v_add_u32_e32 v0, v76, v0
	v_ashrrev_i32_e32 v90, 5, v0
	v_and_b32_e32 v0, 0x1fffffe0, v0
	v_add_u32_e32 v80, 0x200, v76
	v_sub_u32_e32 v0, v76, v0
	v_ashrrev_i32_e32 v81, 31, v80
	s_lshr_b32 s7, s62, 4
	s_and_b32 s8, s62, 15
	s_bfe_u32 s9, s62, 0x10002
	s_lshr_b32 s10, s62, 3
	v_lshlrev_b32_e32 v70, 3, v0
	v_lshrrev_b32_e32 v0, 27, v81
	s_and_b64 s[4:5], s[0:1], exec
	v_add_u32_e32 v0, v80, v0
	s_cselect_b32 s57, s62, s7
	s_cselect_b32 s6, s9, s6
	v_lshlrev_b64 v[122:123], 4, v[76:77]
	v_ashrrev_i32_e32 v77, 5, v0
	v_and_b32_e32 v0, 0x1fffffe0, v0
	v_add_u32_e32 v82, 0x400, v76
	s_cselect_b32 s12, s10, s8
	s_and_b32 s13, s57, 3
	s_mul_i32 s42, s6, 0xf400000
	v_sub_u32_e32 v0, v80, v0
	v_ashrrev_i32_e32 v83, 31, v82
	s_mul_hi_i32 s45, s6, 0xf400000
	s_add_u32 s10, s61, s42
	v_lshlrev_b32_e32 v72, 3, v0
	v_lshrrev_b32_e32 v0, 27, v83
	s_addc_u32 s11, s68, s45
	s_lshl_b32 s56, s13, 9
	v_add_u32_e32 v0, v82, v0
	s_add_u32 s4, s10, s56
	v_lshlrev_b64 v[124:125], 4, v[80:81]
	v_ashrrev_i32_e32 v81, 5, v0
	v_and_b32_e32 v0, 0x1fffffe0, v0
	v_add_u32_e32 v86, 0x600, v76
	s_addc_u32 s5, s11, 0
	s_lshl_b32 s7, s13, 15
	v_sub_u32_e32 v0, v82, v0
	v_ashrrev_i32_e32 v87, 31, v86
	s_add_u32 s52, s47, s7
	v_lshlrev_b32_e32 v74, 3, v0
	v_lshrrev_b32_e32 v0, 27, v87
	s_addc_u32 s63, s95, 0
	s_lshl_b32 s28, s6, 7
	v_mov_b64_e32 v[38:39], s[4:5]
	v_add_u32_e32 v0, v86, v0
	s_waitcnt vmcnt(0)
	v_mad_i64_i32 v[2:3], s[4:5], v90, s51, v[38:39]
	s_ashr_i32 s29, s28, 31
	v_lshlrev_b64 v[126:127], 4, v[82:83]
	v_ashrrev_i32_e32 v83, 5, v0
	v_and_b32_e32 v0, 0x1fffffe0, v0
	s_lshl_b64 s[4:5], s[28:29], 17
	v_sub_u32_e32 v0, v86, v0
	s_add_u32 s4, s52, s4
	v_lshlrev_b32_e32 v78, 3, v0
	v_ashrrev_i32_e32 v71, 31, v70
	s_addc_u32 s5, s63, s5
	v_mad_i64_i32 v[14:15], s[8:9], v77, s51, v[38:39]
	v_ashrrev_i32_e32 v73, 31, v72
	v_mad_i64_i32 v[26:27], s[8:9], v81, s51, v[38:39]
	v_ashrrev_i32_e32 v75, 31, v74
	v_mad_i64_i32 v[38:39], s[8:9], v83, s51, v[38:39]
	v_ashrrev_i32_e32 v79, 31, v78
	v_lshlrev_b64 v[128:129], 4, v[86:87]
	v_lshl_add_u64 v[6:7], v[70:71], 1, v[2:3]
	v_lshl_add_u64 v[10:11], s[4:5], 0, v[122:123]
	v_lshl_add_u64 v[18:19], v[72:73], 1, v[14:15]
	v_lshl_add_u64 v[22:23], s[4:5], 0, v[124:125]
	v_lshl_add_u64 v[30:31], v[74:75], 1, v[26:27]
	s_waitcnt vmcnt(0)
	v_lshl_add_u64 v[34:35], s[4:5], 0, v[126:127]
	v_lshl_add_u64 v[42:43], v[78:79], 1, v[38:39]
	v_lshl_add_u64 v[46:47], s[4:5], 0, v[128:129]
	global_load_dwordx4 v[2:5], v[6:7], off
	s_nop 0
	global_load_dwordx4 v[6:9], v[6:7], off offset:2048
	s_movk_i32 s7, 0xff
	global_load_dwordx4 v[10:13], v[10:11], off
	s_nop 0
	global_load_dwordx4 v[14:17], v[18:19], off
	s_nop 0
	global_load_dwordx4 v[18:21], v[18:19], off offset:2048
	v_cmp_gt_i32_e64 s[4:5], s97, v76
	global_load_dwordx4 v[22:25], v[22:23], off
	s_nop 0
	global_load_dwordx4 v[26:29], v[30:31], off
	s_nop 0
	global_load_dwordx4 v[30:33], v[30:31], off offset:2048
	v_cmp_lt_i32_e32 vcc, s7, v76
	global_load_dwordx4 v[34:37], v[34:35], off
	s_nop 0
	global_load_dwordx4 v[38:41], v[42:43], off
	s_nop 0
	global_load_dwordx4 v[42:45], v[42:43], off offset:2048
	v_lshlrev_b32_e32 v91, 3, v76
	global_load_dwordx4 v[46:49], v[46:47], off
	s_and_saveexec_b64 s[8:9], vcc
	s_xor_b64 s[8:9], exec, s[8:9]
	v_lshlrev_b32_e32 v91, 3, v76
	v_lshrrev_b32_e32 v87, 2, v76
	v_and_b32_e32 v0, 24, v91
	v_mad_u64_u32 v[84:85], s[14:15], v87, s51, 0
	v_mov_b32_e32 v92, v0
	v_mov_b64_e32 v[88:89], v[0:1]
	s_or_saveexec_b64 s[8:9], s[8:9]
	s_lshl_b32 s30, s12, 5
	v_mov_b32_e32 v0, v1
	s_ashr_i32 s7, s6, 31
	s_lshl_b32 s13, s13, 8
	s_ashr_i32 s31, s30, 31
	v_mov_b64_e32 v[52:53], v[0:1]
	v_mov_b64_e32 v[50:51], v[0:1]
	s_xor_b64 exec, exec, s[8:9]
	s_cbranch_execz .LBB0_250
	s_lshl_b32 s12, s56, 1
	s_add_u32 s12, s10, s12
	s_addc_u32 s14, s11, 0
	s_lshl_b64 s[10:11], s[30:31], 1
	s_add_u32 s10, s12, s10
	s_addc_u32 s11, s14, s11
	s_add_u32 s10, s10, 0x1000
	s_addc_u32 s11, s11, 0
	v_ashrrev_i32_e32 v87, 2, v76
	v_mov_b64_e32 v[50:51], s[10:11]
	v_and_b32_e32 v0, 24, v91
	v_mad_i64_i32 v[50:51], s[10:11], v87, s51, v[50:51]
	v_lshlrev_b32_e32 v52, 1, v0
	v_mov_b32_e32 v53, v1
	v_lshl_add_u64 v[50:51], v[50:51], 0, v[52:53]
	global_load_dwordx4 v[50:53], v[50:51], off
	v_mad_i64_i32 v[84:85], s[10:11], v87, s51, 0
	v_mov_b64_e32 v[88:89], v[0:1]
	v_mov_b32_e32 v92, v0
; #define RAWSYNC do { asm volatile("s_waitcnt lgkmcnt(0)" ::: "memory"); __builtin_amdgcn_s_barrier(); asm volatile("" ::: "memory"); } while (0)
; template <int DK> ...
;     ...
;     {
;       const int d0_ = (w * NA + 0) * 16 + fq * 4;
;       e4n0 = *(const float4*)(em + (long)(ck0 + c_) * CH + d0_);
;       l4n0 = *(const float4*)(elm + (long)(ck0 + c_) * CH + d0_);
;     }
;     if (NA > 1) {
;       const int d0_ = (w * NA + 1) * 16 + fq * 4;
;       e4n1 = *(const float4*)(em + (long)(ck0 + c_) * CH + d0_);
;       l4n1 = *(const float4*)(elm + (long)(ck0 + c_) * CH + d0_);
;     }
;   };
;   scan_load(0);
; #pragma unroll 1
;   for (int c = 0; c < 128; ++c) {
;     const long row = (long)c * 64;
;     RAWSYNC;
.LBB0_250:
	s_or_b64 exec, exec, s[8:9]
	s_lshl_b32 s8, s13, 2
	v_readlane_b32 s9, v252, 57
	s_add_u32 s38, s9, s8
	v_readlane_b32 s9, v252, 58
	s_addc_u32 s39, s9, 0
	s_add_u32 s54, s85, s8
	s_addc_u32 s55, s26, 0
	s_lshl_b64 s[34:35], s[6:7], 25
	v_ashrrev_i32_e32 v0, 6, v76
	v_bfe_u32 v96, v76, 4, 2
	s_lshl_b64 s[6:7], s[28:29], 12
	v_lshlrev_b32_e32 v97, 5, v0
	v_lshlrev_b32_e32 v98, 2, v96
	s_add_u32 s8, s38, s6
	v_or_b32_e32 v54, v98, v97
	s_addc_u32 s9, s39, s7
	v_ashrrev_i32_e32 v55, 31, v54
	s_add_u32 s6, s54, s6
	v_lshlrev_b64 v[94:95], 2, v[54:55]
	s_addc_u32 s7, s55, s7
	v_lshl_add_u64 v[54:55], s[8:9], 0, v[94:95]
	v_lshl_add_u64 v[56:57], s[6:7], 0, v[94:95]
	global_load_dwordx4 v[66:69], v[54:55], off
	global_load_dwordx4 v[58:61], v[54:55], off offset:64
	global_load_dwordx4 v[62:65], v[56:57], off
	s_nop 0
	global_load_dwordx4 v[54:57], v[56:57], off offset:64
	s_movk_i32 s10, 0x90
	v_lshlrev_b32_e32 v91, 1, v91
	v_lshrrev_b32_e32 v80, 3, v80
	s_movk_i32 s7, 0x210
	s_add_i32 s6, 16, 0x10800
	v_and_b32_e32 v91, 0x70, v91
	v_mul_lo_u32 v80, v80, s10
	v_lshlrev_b32_e32 v101, 1, v74
	v_add3_u32 v169, s6, v80, v91
	v_mul_lo_u32 v80, v81, s7
	v_add3_u32 v170, 16, v101, v80
	v_lshrrev_b32_e32 v80, 3, v82
	v_mul_lo_u32 v80, v80, s10
	v_lshlrev_b32_e32 v102, 1, v78
	v_add3_u32 v171, s6, v80, v91
	v_mul_lo_u32 v80, v83, s7
	v_add3_u32 v172, 16, v102, v80
	v_lshrrev_b32_e32 v80, 3, v86
	v_mul_lo_u32 v80, v80, s10
	v_lshlrev_b32_e32 v99, 1, v70
	v_mul_lo_u32 v103, v90, s7
	v_add3_u32 v173, s6, v80, v91
	v_mul_u32_u24_e32 v80, 0x90, v92
	v_lshlrev_b32_e32 v82, 1, v87
	v_readlane_b32 s8, v252, 36
	v_lshl_add_u64 v[130:131], s[38:39], 0, v[94:95]
	s_add_i32 s38, s28, 1
	s_lshl_b32 s28, s57, 10
	v_and_b32_e32 v93, 15, v76
	v_add3_u32 v136, 16, v99, v103
	v_lshrrev_b32_e32 v99, 3, v76
	v_add3_u32 v174, s8, v80, v82
	v_and_b32_e32 v80, 0xffffffc0, v76
	v_ashrrev_i32_e32 v76, 7, v76
	s_and_b32 s39, s28, 0xc00
	v_lshlrev_b32_e32 v82, 3, v96
	v_readlane_b32 s9, v252, 37
	v_lshlrev_b32_e32 v86, 4, v76
	s_add_u32 s28, s39, s42
	v_add3_u32 v80, s9, v80, v82
	v_or_b32_e32 v82, v86, v93
	s_addc_u32 s29, 0, s45
	v_mul_lo_u32 v99, v99, s10
	v_mul_lo_u32 v87, v82, s7
	v_lshl_add_u64 v[84:85], s[28:29], 0, v[84:85]
	s_lshl_b64 s[28:29], s[30:31], 1
	v_lshlrev_b32_e32 v100, 1, v72
	v_add3_u32 v141, s6, v99, v91
	v_mul_lo_u32 v99, v77, s7
	v_add_u32_e32 v91, 16, v87
	v_lshlrev_b32_e32 v92, 4, v96
	v_lshlrev_b32_e32 v87, 1, v0
	v_lshlrev_b32_e32 v0, 4, v0
	s_add_u32 s30, s56, s42
	v_add3_u32 v168, 16, v100, v99
	v_and_b32_e32 v99, 2, v87
	v_or_b32_e32 v98, v98, v86
	v_and_or_b32 v0, v0, 16, v93
	v_mov_b32_e32 v87, s9
	v_mul_lo_u32 v82, v82, s10
	v_readlane_b32 s20, v252, 38
	v_add_u32_e32 v102, s8, v92
	v_lshl_add_u64 v[84:85], v[88:89], 1, v[84:85]
	s_addc_u32 s31, 0, s45
	v_mad_u32_u24 v101, v0, s7, v87
	v_add3_u32 v175, s20, v82, v92
	v_mad_u32_u24 v176, v0, s10, v102
	v_or_b32_e32 v0, v97, v93
	v_lshl_or_b32 v82, v99, 4, v93
	v_or_b32_e32 v107, 1, v98
	v_or_b32_e32 v108, 2, v98
	v_or_b32_e32 v109, 3, v98
	v_lshl_add_u64 v[134:135], v[84:85], 0, s[28:29]
	v_mov_b64_e32 v[84:85], s[30:31]
	v_add_u32_e32 v103, s6, v92
	v_cmp_le_i32_e64 s[6:7], v99, v76
	v_mul_u32_u24_e32 v105, 0x210, v82
	v_mul_lo_u32 v106, v98, s10
	v_cmp_ge_i32_e64 s[8:9], v99, v76
	v_or_b32_e32 v76, 16, v82
	v_mul_lo_u32 v99, v0, s10
	v_lshl_add_u32 v111, v82, 1, s20
	v_cmp_gt_i32_e64 s[10:11], v82, v98
	v_cmp_gt_i32_e64 s[12:13], v82, v107
	v_cmp_gt_i32_e64 s[14:15], v82, v108
	v_cmp_gt_i32_e64 s[16:17], v82, v109
	v_mad_i64_i32 v[82:83], s[30:31], v83, s51, v[84:85]
	v_lshl_add_u64 v[142:143], v[78:79], 1, v[82:83]
	v_mad_i64_i32 v[78:79], s[30:31], v81, s51, v[84:85]
	v_lshl_add_u64 v[144:145], v[74:75], 1, v[78:79]
	v_mad_i64_i32 v[74:75], s[30:31], v77, s51, v[84:85]
	v_ashrrev_i32_e32 v87, 31, v86
	v_lshl_add_u64 v[146:147], v[72:73], 1, v[74:75]
	v_mad_i64_i32 v[72:73], s[30:31], v90, s51, v[84:85]
	v_lshlrev_b32_e32 v0, 1, v76
	v_lshl_add_u64 v[148:149], v[70:71], 1, v[72:73]
	v_lshl_or_b32 v70, v96, 14, s34
	v_mov_b32_e32 v71, s35
	v_lshlrev_b64 v[72:73], 12, v[86:87]
	v_add3_u32 v177, s20, v106, v0
	v_lshl_add_u64 v[70:71], v[70:71], 0, v[72:73]
	v_and_b32_e32 v0, 32, v97
	v_or3_b32 v70, v70, s39, v0
	v_add_u32_e32 v100, 16, v92
	v_mul_u32_u24_e32 v104, 0x210, v93
	v_mul_u32_u24_e32 v110, 0x90, v93
	v_lshl_add_u64 v[70:71], v[70:71], 0, s[28:29]
	v_lshlrev_b32_e32 v0, 1, v93
	v_mov_b32_e32 v152, 0
	v_cmp_gt_i32_e64 s[18:19], v76, v98
	v_cmp_gt_i32_e64 s[20:21], v76, v107
	v_add_u32_e32 v178, 0x90, v177
	v_cmp_gt_i32_e64 s[22:23], v76, v108
	v_add_u32_e32 v179, 0x120, v177
	v_cmp_gt_i32_e64 s[24:25], v76, v109
	v_add_u32_e32 v180, 0x1b0, v177
	v_lshl_add_u64 v[132:133], s[54:55], 0, v[94:95]
	v_lshl_add_u64 v[150:151], v[70:71], 0, v[0:1]
	s_mov_b32 s34, 0
	v_add_u32_e32 v0, v80, v104
	v_add_u32_e32 v181, v91, v92
	v_add_u32_e32 v182, v111, v106
	v_add_u32_e32 v183, v101, v92
	v_add_u32_e32 v184, v103, v99
	v_add_u32_e32 v185, v102, v110
	v_add_u32_e32 v186, v100, v105
	v_mov_b32_e32 v153, v152
	v_mov_b32_e32 v154, v152
	v_mov_b32_e32 v155, v152
	v_mov_b32_e32 v156, v152
	v_mov_b32_e32 v157, v152
	v_mov_b32_e32 v158, v152
	v_mov_b32_e32 v159, v152
	v_mov_b32_e32 v160, v152
	v_mov_b32_e32 v161, v152
	v_mov_b32_e32 v162, v152
	v_mov_b32_e32 v163, v152
	v_mov_b32_e32 v164, v152
	v_mov_b32_e32 v165, v152
	v_mov_b32_e32 v166, v152
	v_mov_b32_e32 v167, v152
	s_branch .LBB0_252
; __device__ __forceinline__ u16 f2bf(float f) { return (u16)(pack2(f, 0.f) & 0xffffu); }
; #define RAWSYNC do { asm volatile("s_waitcnt lgkmcnt(0)" ::: "memory"); __builtin_amdgcn_s_barrier(); asm volatile("" ::: "memory"); } while (0)
; template <int DK> ...
;     ...
;     RAWSYNC;
;     {
;       const int ti = w >> 1, tv = w & 1;
;       f32x4 a = {0.f, 0.f, 0.f, 0.f};
; #pragma unroll
;       for (int ks = 0; ks < DK / 32; ++ks) {
;         bf16x8 fb = *(const bf16x8*)(ST + (tv * 16 + fr) * PQ + ks * 32 + fq * 8);
;         a = __builtin_amdgcn_mfma_f32_16x16x32_bf16(qf[ks], fb, a, 0, 0, 0);
;       }
; #pragma unroll
;       for (int ks = 0; ks < 2; ++ks) {
;         bf16x8 fa = *(const bf16x8*)(Pm + (ti * 16 + fr) * 72 + ks * 32 + fq * 8);
;         bf16x8 fb = *(const bf16x8*)(VT + (tv * 16 + fr) * 72 + ks * 32 + fq * 8);
;         a = __builtin_amdgcn_mfma_f32_16x16x32_bf16(fa, fb, a, 0, 0, 0);
;       }
; #pragma unroll
;       for (int r = 0; r < 4; ++r) og[(row + ti * 16 + fq * 4 + r) * 2048 + tv * 16 + fr] = f2bf(a[r]);
;     }
; #pragma unroll
;     for (int a = 0; a < NA; ++a) {
;       const int dt = w * NA + a;
; #pragma unroll
;       for (int tv = 0; tv < 2; ++tv) {
;         f32x4 u = {0.f, 0.f, 0.f, 0.f};
; #pragma unroll
;         for (int ks = 0; ks < 2; ++ks) {
;           bf16x8 fa = *(const bf16x8*)(KtT + (dt * 16 + fr) * 72 + ks * 32 + fq * 8);
;           bf16x8 fb = *(const bf16x8*)(VT + (tv * 16 + fr) * 72 + ks * 32 + fq * 8);
;           u = __builtin_amdgcn_mfma_f32_16x16x32_bf16(fa, fb, u, 0, 0, 0);
;         }
;         S[a][tv][0] = e4[a].x * l4[a].x * S[a][tv][0] + l4[a].x * u[0];
;         S[a][tv][1] = e4[a].y * l4[a].y * S[a][tv][1] + l4[a].y * u[1];
;         S[a][tv][2] = e4[a].z * l4[a].z * S[a][tv][2] + l4[a].z * u[2];
;         S[a][tv][3] = e4[a].w * l4[a].w * S[a][tv][3] + l4[a].w * u[3];
;       }
;     }
.LBB0_251:
	s_or_b64 exec, exec, s[28:29]
	s_nop 5
	v_cvt_pk_bf16_f32 v118, v118, s0
	v_cndmask_b32_e64 v118, v118, 0, s[18:19]
	ds_write_b16 v177, v118
	v_cvt_pk_bf16_f32 v118, v119, s0
	v_cndmask_b32_e64 v118, v118, 0, s[20:21]
	ds_write_b16 v178, v118
	v_cvt_pk_bf16_f32 v118, v120, s0
	v_cndmask_b32_e64 v118, v118, 0, s[22:23]
	ds_write_b16 v179, v118
	v_cvt_pk_bf16_f32 v118, v121, s0
	v_cndmask_b32_e64 v118, v118, 0, s[24:25]
	ds_write_b16 v180, v118
	s_waitcnt lgkmcnt(0)
	s_barrier
	ds_read_b128 v[216:219], v183
	ds_read_b128 v[220:223], v183 offset:64
	ds_read_b128 v[224:227], v183 offset:128
	ds_read_b128 v[228:231], v183 offset:192
	ds_read_b128 v[232:235], v183 offset:256
	ds_read_b128 v[236:239], v183 offset:320
	ds_read_b128 v[240:243], v183 offset:384
	ds_read_b128 v[244:247], v183 offset:448
	ds_read_b128 v[248:251], v175
	ds_read_b128 v[212:215], v176
	ds_read_b128 v[118:121], v175 offset:64
	s_movk_i32 s28, 0x1000
	s_add_i32 s34, s34, 1
	s_movk_i32 s86, 0x1000
	v_lshl_add_u64 v[134:135], v[134:135], 0, s[70:71]
	v_lshl_add_u64 v[142:143], v[142:143], 0, s[70:71]
	v_lshl_add_u64 v[144:145], v[144:145], 0, s[70:71]
	v_lshl_add_u64 v[146:147], v[146:147], 0, s[70:71]
	v_lshl_add_u64 v[148:149], v[148:149], 0, s[70:71]
	s_cmpk_lg_i32 s34, 0x80
	s_waitcnt lgkmcnt(10)
	v_mfma_f32_16x16x32_bf16 v[114:117], v[114:117], v[216:219], 0
	s_waitcnt lgkmcnt(9)
	v_mfma_f32_16x16x32_bf16 v[110:113], v[110:113], v[220:223], v[114:117]
	s_waitcnt lgkmcnt(8)
	v_mfma_f32_16x16x32_bf16 v[106:109], v[106:109], v[224:227], v[110:113]
	s_waitcnt lgkmcnt(7)
	v_mfma_f32_16x16x32_bf16 v[102:105], v[102:105], v[228:231], v[106:109]
	s_waitcnt lgkmcnt(6)
	v_mfma_f32_16x16x32_bf16 v[98:101], v[98:101], v[232:235], v[102:105]
	s_waitcnt lgkmcnt(5)
	v_mfma_f32_16x16x32_bf16 v[94:97], v[94:97], v[236:239], v[98:101]
	s_waitcnt lgkmcnt(4)
	v_mfma_f32_16x16x32_bf16 v[90:93], v[90:93], v[240:243], v[94:97]
	s_waitcnt lgkmcnt(3)
	v_mfma_f32_16x16x32_bf16 v[86:89], v[86:89], v[244:247], v[90:93]
	s_nop 2
	ds_read_b128 v[94:97], v176 offset:64
	v_pk_mul_f32 v[106:107], v[62:63], v[66:67]
	v_pk_mul_f32 v[108:109], v[64:65], v[68:69]
	s_waitcnt lgkmcnt(2)
	v_mfma_f32_16x16x32_bf16 v[86:89], v[248:251], v[212:215], v[86:89]
	s_waitcnt lgkmcnt(0)
	v_mfma_f32_16x16x32_bf16 v[86:89], v[118:121], v[94:97], v[86:89]
	v_lshl_add_u64 v[90:91], s[66:67], 0, v[150:151]
	s_nop 6
	v_cvt_pk_bf16_f32 v86, v86, s0
	global_store_short v[90:91], v86, off
	v_add_co_u32_e32 v86, vcc, s28, v90
	v_cvt_pk_bf16_f32 v92, v87, s0
	s_nop 0
	v_addc_co_u32_e32 v87, vcc, 0, v91, vcc
	global_store_short v[86:87], v92, off
	v_add_co_u32_e32 v86, vcc, s43, v90
	v_cvt_pk_bf16_f32 v88, v88, s0
	s_nop 0
	v_addc_co_u32_e32 v87, vcc, 0, v91, vcc
	global_store_short v[86:87], v88, off
	v_add_co_u32_e32 v86, vcc, s69, v90
	v_cvt_pk_bf16_f32 v88, v89, s0
	s_nop 0
	v_addc_co_u32_e32 v87, vcc, 0, v91, vcc
	global_store_short v[86:87], v88, off
	ds_read_b128 v[216:219], v184
	ds_read_b128 v[224:227], v185
	ds_read_b128 v[220:223], v184 offset:64
	ds_read_b128 v[228:231], v185 offset:64
	ds_read_b128 v[232:235], v185 offset:2304
	ds_read_b128 v[236:239], v185 offset:2368
	ds_read_b128 v[240:243], v184 offset:2304
	ds_read_b128 v[244:247], v184 offset:2368
	s_mov_b64 s[28:29], 0x40000
	v_lshl_add_u64 v[150:151], v[150:151], 0, s[28:29]
	s_waitcnt lgkmcnt(6)
	v_mfma_f32_16x16x32_bf16 v[90:93], v[216:219], v[224:227], 0
	s_waitcnt lgkmcnt(4)
	v_mfma_f32_16x16x32_bf16 v[90:93], v[220:223], v[228:231], v[90:93]
	s_waitcnt lgkmcnt(3)
	v_mfma_f32_16x16x32_bf16 v[66:69], v[216:219], v[232:235], 0
	s_waitcnt lgkmcnt(2)
	v_mfma_f32_16x16x32_bf16 v[66:69], v[220:223], v[236:239], v[66:69]
	s_nop 7
	v_pk_mul_f32 v[92:93], v[64:65], v[92:93]
	v_pk_mul_f32 v[90:91], v[62:63], v[90:91]
	v_pk_fma_f32 v[154:155], v[108:109], v[154:155], v[92:93]
	v_pk_fma_f32 v[152:153], v[106:107], v[152:153], v[90:91]
	v_mul_f32_e64 v94, v54, v58
	v_mul_f32_e64 v95, v55, v59
	v_pk_mul_f32 v[96:97], v[56:57], v[60:61]
	s_nop 3
	v_pk_mul_f32 v[64:65], v[64:65], v[68:69]
	v_pk_mul_f32 v[62:63], v[62:63], v[66:67]
	v_pk_fma_f32 v[158:159], v[108:109], v[158:159], v[64:65]
	v_pk_fma_f32 v[156:157], v[106:107], v[156:157], v[62:63]
	s_waitcnt lgkmcnt(1)
	v_mfma_f32_16x16x32_bf16 v[62:65], v[240:243], v[224:227], 0
	v_mfma_f32_16x16x32_bf16 v[58:61], v[240:243], v[232:235], 0
	s_waitcnt lgkmcnt(0)
	v_mfma_f32_16x16x32_bf16 v[62:65], v[244:247], v[228:231], v[62:65]
	v_mfma_f32_16x16x32_bf16 v[58:61], v[244:247], v[236:239], v[58:61]
	s_waitcnt vmcnt(0)
	v_mov_b64_e32 v[66:67], v[70:71]
	s_nop 4
	v_pk_mul_f32 v[64:65], v[56:57], v[64:65]
	v_pk_mul_f32 v[62:63], v[54:55], v[62:63]
	v_pk_fma_f32 v[162:163], v[96:97], v[162:163], v[64:65]
	v_pk_fma_f32 v[160:161], v[94:95], v[160:161], v[62:63]
	v_pk_mul_f32 v[56:57], v[56:57], v[60:61]
	v_pk_mul_f32 v[54:55], v[54:55], v[58:59]
	v_pk_fma_f32 v[166:167], v[96:97], v[166:167], v[56:57]
	v_pk_fma_f32 v[164:165], v[94:95], v[164:165], v[54:55]
	v_mov_b64_e32 v[54:55], v[82:83]
	v_mov_b64_e32 v[58:59], v[78:79]
	v_mov_b64_e32 v[56:57], v[84:85]
	v_mov_b64_e32 v[60:61], v[80:81]
	v_mov_b64_e32 v[62:63], v[74:75]
	v_mov_b64_e32 v[64:65], v[76:77]
	v_mov_b64_e32 v[68:69], v[72:73]
	s_cbranch_scc0 .LBB0_224

; template <int DK> ...
;     ...
;     SW1(0, rq0, rk0, rt0) SW1(1, rq1, rk1, rt1) SW1(2, rq2, rk2, rt2) SW1(3, rq3, rk3, rt3)
;     if (tid < 256) {
;       const int r = tid >> 2, c8 = (tid & 3) * 8;
;       VT[(c8 + 0) * 72 + r] = (u16)(rv.x & 0xffff); VT[(c8 + 1) * 72 + r] = (u16)(rv.x >> 16);
;       VT[(c8 + 2) * 72 + r] = (u16)(rv.y & 0xffff); VT[(c8 + 3) * 72 + r] = (u16)(rv.y >> 16);
;       VT[(c8 + 4) * 72 + r] = (u16)(rv.z & 0xffff); VT[(c8 + 5) * 72 + r] = (u16)(rv.z >> 16);
;       VT[(c8 + 6) * 72 + r] = (u16)(rv.w & 0xffff); VT[(c8 + 7) * 72 + r] = (u16)(rv.w >> 16);
;     }
; #pragma unroll
;     for (int a = 0; a < NA; ++a) {
;       const int d0 = (w * NA + a) * 16 + fq * 4;
;       e4[a] = (a == 0) ? e4n0 : e4n1; l4[a] = (a == 0) ? l4n0 : l4n1;
; #pragma unroll
;       for (int tv = 0; tv < 2; ++tv) {
;         uint2 v;
;         v.x = pack2(S[a][tv][0] * e4[a].x, S[a][tv][1] * e4[a].y);
;         v.y = pack2(S[a][tv][2] * e4[a].z, S[a][tv][3] * e4[a].w);
;         *(uint2*)(ST + (tv * 16 + fr) * PQ + d0) = v;
;       }
;     }
;     if (c + 1 < 128) scan_load(c + 1);
.LBB0_254:
	s_or_b64 exec, exec, s[28:29]
	v_pk_mul_f32 v[70:71], v[66:67], v[152:153]
	v_pk_mul_f32 v[72:73], v[68:69], v[154:155]
	v_cvt_pk_bf16_f32 v70, v70, v71
	v_cvt_pk_bf16_f32 v71, v72, v73
	v_pk_mul_f32 v[72:73], v[66:67], v[156:157]
	v_pk_mul_f32 v[74:75], v[68:69], v[158:159]
	v_cvt_pk_bf16_f32 v72, v72, v73
	v_cvt_pk_bf16_f32 v73, v74, v75
	v_pk_mul_f32 v[74:75], v[58:59], v[160:161]
	v_pk_mul_f32 v[76:77], v[60:61], v[162:163]
	v_cvt_pk_bf16_f32 v74, v74, v75
	v_cvt_pk_bf16_f32 v75, v76, v77
	ds_write2_b64 v0, v[70:71], v[74:75] offset1:4
	v_pk_mul_f32 v[70:71], v[58:59], v[164:165]
	v_pk_mul_f32 v[74:75], v[60:61], v[166:167]
	v_cvt_pk_bf16_f32 v70, v70, v71
	v_cvt_pk_bf16_f32 v71, v74, v75
	v_add_u32_e32 v74, 0x2000, v0
	s_cmpk_eq_i32 s34, 0x7f
	ds_write2_b64 v74, v[72:73], v[70:71] offset0:32 offset1:36
	s_cbranch_scc1 .LBB0_258
	v_lshl_add_u64 v[2:3], s[66:67], 0, v[148:149]
	v_add_co_u32_e32 v6, vcc, 0xfbe8000, v2
	v_lshl_add_u64 v[14:15], s[66:67], 0, v[146:147]
	s_nop 0
	v_addc_co_u32_e32 v7, vcc, 0, v3, vcc
	s_mov_b32 s35, 0xfbe8000
	s_add_i32 s28, s38, s34
	v_add_co_u32_e32 v18, vcc, s35, v14
	s_ashr_i32 s29, s28, 31
	s_nop 0
	v_addc_co_u32_e32 v19, vcc, 0, v15, vcc
	v_lshl_add_u64 v[26:27], s[66:67], 0, v[144:145]
	s_lshl_b64 s[30:31], s[28:29], 17
	v_add_co_u32_e32 v30, vcc, s35, v26
	s_add_u32 s30, s52, s30
	s_nop 0
	v_addc_co_u32_e32 v31, vcc, 0, v27, vcc
	v_lshl_add_u64 v[38:39], s[66:67], 0, v[142:143]
	s_addc_u32 s31, s63, s31
	v_add_co_u32_e32 v42, vcc, 0xfbe8000, v38
	v_lshl_add_u64 v[10:11], s[30:31], 0, v[122:123]
	v_lshl_add_u64 v[22:23], s[30:31], 0, v[124:125]
	v_lshl_add_u64 v[34:35], s[30:31], 0, v[126:127]
	v_addc_co_u32_e32 v43, vcc, 0, v39, vcc
	v_lshl_add_u64 v[46:47], s[30:31], 0, v[128:129]
	global_load_dwordx4 v[2:5], v[6:7], off
	s_nop 0
	global_load_dwordx4 v[6:9], v[6:7], off offset:2048
	s_nop 0
	global_load_dwordx4 v[10:13], v[10:11], off
	s_nop 0
	global_load_dwordx4 v[14:17], v[18:19], off
	s_nop 0
	global_load_dwordx4 v[18:21], v[18:19], off offset:2048
	s_nop 0
	global_load_dwordx4 v[22:25], v[22:23], off
	s_nop 0
	global_load_dwordx4 v[26:29], v[30:31], off
	s_nop 0
	global_load_dwordx4 v[30:33], v[30:31], off offset:2048
	s_nop 0
	global_load_dwordx4 v[34:37], v[34:35], off
	s_nop 0
	global_load_dwordx4 v[38:41], v[42:43], off
	s_nop 0
	global_load_dwordx4 v[42:45], v[42:43], off offset:2048
	s_nop 0
	global_load_dwordx4 v[46:49], v[46:47], off
	s_and_saveexec_b64 s[30:31], s[4:5]
	s_cbranch_execz .LBB0_257
	v_lshl_add_u64 v[50:51], s[66:67], 0, v[134:135]
	v_add_co_u32_e32 v50, vcc, 0xfbe9000, v50
	s_nop 1
	v_addc_co_u32_e32 v51, vcc, 0, v51, vcc
	global_load_dwordx4 v[50:53], v[50:51], off
.LBB0_257:
	s_or_b64 exec, exec, s[30:31]
	s_lshl_b64 s[28:29], s[28:29], 12
	v_lshl_add_u64 v[74:75], v[130:131], 0, s[28:29]
	v_lshl_add_u64 v[82:83], v[132:133], 0, s[28:29]
	global_load_dwordx4 v[70:73], v[74:75], off
	global_load_dwordx4 v[78:81], v[74:75], off offset:64
	s_nop 0
	global_load_dwordx4 v[74:77], v[82:83], off
	s_nop 0
	global_load_dwordx4 v[82:85], v[82:83], off offset:64
	s_branch .LBB0_259

; __device__ __forceinline__ u16 f2bf(float f) { return (u16)(pack2(f, 0.f) & 0xffffu); }
; template <int DK> ...
;     ...
;     bf16x8 qf[DK / 32];
;     {
;       const int ti = w >> 1;
; #pragma unroll
;       for (int ks = 0; ks < DK / 32; ++ks) qf[ks] = *(const bf16x8*)(Qt + (ti * 16 + fr) * PQ + ks * 32 + fq * 8);
; #pragma unroll
;       for (int x = 0; x < 2; ++x) {
;         const int tj = (w & 1) * 2 + x;
;         f32x4 a = {0.f, 0.f, 0.f, 0.f};
;         if (tj <= ti) {
; #pragma unroll
;           for (int ks = 0; ks < DK / 32; ++ks) {
;             bf16x8 fb = *(const bf16x8*)(Kt + (tj * 16 + fr) * PQ + ks * 32 + fq * 8);
;             a = __builtin_amdgcn_mfma_f32_16x16x32_bf16(qf[ks], fb, a, 0, 0, 0);
;           }
;         }
; #pragma unroll
;         for (int r = 0; r < 4; ++r) {
;           int i = ti * 16 + fq * 4 + r, j = tj * 16 + fr;
;           Pm[i * 72 + j] = f2bf(j <= i ? a[r] : 0.f);
;         }
;       }
.LBB0_259:
	s_waitcnt lgkmcnt(0)
	s_barrier
	ds_read_b128 v[114:117], v181
	ds_read_b128 v[110:113], v181 offset:64
	ds_read_b128 v[106:109], v181 offset:128
	ds_read_b128 v[102:105], v181 offset:192
	ds_read_b128 v[98:101], v181 offset:256
	ds_read_b128 v[94:97], v181 offset:320
	ds_read_b128 v[90:93], v181 offset:384
	ds_read_b128 v[86:89], v181 offset:448
	v_mov_b32_e32 v118, 0
	v_mov_b32_e32 v119, 0
	v_mov_b32_e32 v120, 0
	v_mov_b32_e32 v121, 0
	s_and_saveexec_b64 s[28:29], s[6:7]
	s_cbranch_execz .LBB0_261
	ds_read_b128 v[216:219], v186 offset:33792
	ds_read_b128 v[220:223], v186 offset:33856
	ds_read_b128 v[224:227], v186 offset:33920
	ds_read_b128 v[228:231], v186 offset:33984
	ds_read_b128 v[232:235], v186 offset:34048
	ds_read_b128 v[236:239], v186 offset:34112
	ds_read_b128 v[240:243], v186 offset:34176
	ds_read_b128 v[244:247], v186 offset:34240
	s_waitcnt lgkmcnt(7)
	v_mfma_f32_16x16x32_bf16 v[118:121], v[114:117], v[216:219], 0
	s_waitcnt lgkmcnt(6)
	v_mfma_f32_16x16x32_bf16 v[118:121], v[110:113], v[220:223], v[118:121]
	s_waitcnt lgkmcnt(5)
	v_mfma_f32_16x16x32_bf16 v[118:121], v[106:109], v[224:227], v[118:121]
	s_waitcnt lgkmcnt(4)
	v_mfma_f32_16x16x32_bf16 v[118:121], v[102:105], v[228:231], v[118:121]
	s_waitcnt lgkmcnt(3)
	v_mfma_f32_16x16x32_bf16 v[118:121], v[98:101], v[232:235], v[118:121]
	s_waitcnt lgkmcnt(2)
	v_mfma_f32_16x16x32_bf16 v[118:121], v[94:97], v[236:239], v[118:121]
	s_waitcnt lgkmcnt(1)
	v_mfma_f32_16x16x32_bf16 v[118:121], v[90:93], v[240:243], v[118:121]
	s_waitcnt lgkmcnt(0)
	v_mfma_f32_16x16x32_bf16 v[118:121], v[86:89], v[244:247], v[118:121]
.LBB0_261:
	s_or_b64 exec, exec, s[28:29]
	s_nop 6
	v_cvt_pk_bf16_f32 v118, v118, s0
	v_cndmask_b32_e64 v118, v118, 0, s[10:11]
	ds_write_b16 v182, v118
	v_cvt_pk_bf16_f32 v118, v119, s0
	v_cndmask_b32_e64 v118, v118, 0, s[12:13]
	ds_write_b16 v182, v118 offset:144
	v_cvt_pk_bf16_f32 v118, v120, s0
	v_cndmask_b32_e64 v118, v118, 0, s[14:15]
	ds_write_b16 v182, v118 offset:288
	v_cvt_pk_bf16_f32 v118, v121, s0
	v_cndmask_b32_e64 v118, v118, 0, s[16:17]
	ds_write_b16 v182, v118 offset:432
	s_and_saveexec_b64 s[28:29], s[8:9]
	s_xor_b64 s[28:29], exec, s[28:29]
	s_or_saveexec_b64 s[28:29], s[28:29]
	v_mov_b32_e32 v118, 0
	v_mov_b32_e32 v119, 0
	v_mov_b32_e32 v120, 0
	v_mov_b32_e32 v121, 0
	s_xor_b64 exec, exec, s[28:29]
	s_cbranch_execz .LBB0_251
	ds_read_b128 v[216:219], v186 offset:42240
	ds_read_b128 v[220:223], v186 offset:42304
	ds_read_b128 v[224:227], v186 offset:42368
	ds_read_b128 v[228:231], v186 offset:42432
	ds_read_b128 v[232:235], v186 offset:42496
	ds_read_b128 v[236:239], v186 offset:42560
	ds_read_b128 v[240:243], v186 offset:42624
	ds_read_b128 v[244:247], v186 offset:42688
	s_waitcnt lgkmcnt(7)
	v_mfma_f32_16x16x32_bf16 v[118:121], v[114:117], v[216:219], 0
	s_waitcnt lgkmcnt(6)
	v_mfma_f32_16x16x32_bf16 v[118:121], v[110:113], v[220:223], v[118:121]
	s_waitcnt lgkmcnt(5)
	v_mfma_f32_16x16x32_bf16 v[118:121], v[106:109], v[224:227], v[118:121]
	s_waitcnt lgkmcnt(4)
	v_mfma_f32_16x16x32_bf16 v[118:121], v[102:105], v[228:231], v[118:121]
	s_waitcnt lgkmcnt(3)
	v_mfma_f32_16x16x32_bf16 v[118:121], v[98:101], v[232:235], v[118:121]
	s_waitcnt lgkmcnt(2)
	v_mfma_f32_16x16x32_bf16 v[118:121], v[94:97], v[236:239], v[118:121]
	s_waitcnt lgkmcnt(1)
	v_mfma_f32_16x16x32_bf16 v[118:121], v[90:93], v[240:243], v[118:121]
	s_waitcnt lgkmcnt(0)
	v_mfma_f32_16x16x32_bf16 v[118:121], v[86:89], v[244:247], v[118:121]
	s_branch .LBB0_251

;     ...
;   for (int item = (int)blockIdx.x - blk0; item < 128 * 4; item += nblk) {
;     const int tt = item >> 2, h = item & 3;
;     const long t0 = (long)tt * 128 + w * 16;
;     const int b = (int)(t0 >> 13);
;     bf16x8 aQ[4];
; #pragma unroll
;     for (int ks = 0; ks < 4; ++ks) aQ[ks] = *(const bf16x8*)(qg + (t0 + fr) * ldq + qcol + h * 128 + ks * 32 + fq * 8);
;     f32x4 s[16];
; #pragma unroll
;     for (int nb = 0; nb < 4; ++nb) {
;       bf16x8 bk[4][4];
; #pragma unroll
;       for (int n4 = 0; n4 < 4; ++n4)
; #pragma unroll
;         for (int ks = 0; ks < 4; ++ks)
;           bk[n4][ks] = *(const bf16x8*)(Km + (long)(b * 256 + (nb * 4 + n4) * 16 + fr) * 512 + h * 128 + ks * 32 + fq * 8);
;       asm volatile("" ::: "memory");
; #pragma unroll
;       for (int n4 = 0; n4 < 4; ++n4) {
;         f32x4 a = {0.f, 0.f, 0.f, 0.f};
; #pragma unroll
;         for (int ks = 0; ks < 4; ++ks) a = __builtin_amdgcn_mfma_f32_16x16x32_bf16(aQ[ks], bk[n4][ks], a, 0, 0, 0);
;         s[nb * 4 + n4] = a;
;       }
;     }
.LBB0_266:
	s_lshr_b32 s52, s6, 2
	s_lshl_b64 s[8:9], s[52:53], 7
	v_lshl_add_u64 v[152:153], s[8:9], 0, v[132:133]
	v_or_b32_e32 v4, v152, v130
	v_mov_b64_e32 v[2:3], s[0:1]
	s_and_b32 s7, s6, 3
	v_mad_u64_u32 v[2:3], s[8:9], v4, s51, v[2:3]
	v_mad_i32_i24 v3, v153, s51, v3
	s_lshl_b32 s52, s7, 8
	v_lshl_add_u64 v[2:3], v[2:3], 0, s[52:53]
	v_lshl_add_u64 v[2:3], v[2:3], 0, v[0:1]
	global_load_dwordx4 v[30:33], v[2:3], off
	s_waitcnt vmcnt(0)
	global_load_dwordx4 v[34:37], v[2:3], off offset:64
	global_load_dwordx4 v[38:41], v[2:3], off offset:128
	global_load_dwordx4 v[42:45], v[2:3], off offset:192
	v_alignbit_b32 v2, v153, v152, 5
	v_and_b32_e32 v154, 0xffffff00, v2
	v_or_b32_e32 v116, v154, v130
	v_ashrrev_i32_e32 v117, 31, v116
	v_lshl_add_u64 v[114:115], v[134:135], 0, s[52:53]
	v_lshlrev_b64 v[2:3], 10, v[116:117]
	v_lshl_add_u64 v[14:15], v[114:115], 0, v[2:3]
	global_load_dwordx4 v[2:5], v[14:15], off
	global_load_dwordx4 v[6:9], v[14:15], off offset:64
	global_load_dwordx4 v[10:13], v[14:15], off offset:128
	s_nop 0
	global_load_dwordx4 v[14:17], v[14:15], off offset:192
	v_or_b32_e32 v18, 16, v116
	v_ashrrev_i32_e32 v19, 31, v18
	v_lshlrev_b64 v[18:19], 10, v[18:19]
	v_lshl_add_u64 v[46:47], v[114:115], 0, v[18:19]
	global_load_dwordx4 v[18:21], v[46:47], off
	global_load_dwordx4 v[22:25], v[46:47], off offset:64
	global_load_dwordx4 v[26:29], v[46:47], off offset:128
	s_nop 0
	global_load_dwordx4 v[46:49], v[46:47], off offset:192
	v_or_b32_e32 v50, 32, v116
	v_ashrrev_i32_e32 v51, 31, v50
	v_lshlrev_b64 v[50:51], 10, v[50:51]
	v_lshl_add_u64 v[62:63], v[114:115], 0, v[50:51]
	global_load_dwordx4 v[50:53], v[62:63], off
	global_load_dwordx4 v[54:57], v[62:63], off offset:64
	global_load_dwordx4 v[58:61], v[62:63], off offset:128
	s_nop 0
	global_load_dwordx4 v[62:65], v[62:63], off offset:192
	v_or_b32_e32 v66, 48, v116
	v_ashrrev_i32_e32 v67, 31, v66
	v_lshlrev_b64 v[66:67], 10, v[66:67]
	v_lshl_add_u64 v[78:79], v[114:115], 0, v[66:67]
	global_load_dwordx4 v[66:69], v[78:79], off
	global_load_dwordx4 v[70:73], v[78:79], off offset:64
	global_load_dwordx4 v[74:77], v[78:79], off offset:128
	s_nop 0
	global_load_dwordx4 v[78:81], v[78:79], off offset:192
	v_or_b32_e32 v82, 0x70, v116
	v_ashrrev_i32_e32 v83, 31, v82
	v_lshlrev_b64 v[82:83], 10, v[82:83]
	v_lshl_add_u64 v[94:95], v[114:115], 0, v[82:83]
	v_or_b32_e32 v98, 0xb0, v116
	v_ashrrev_i32_e32 v99, 31, v98
	v_lshlrev_b64 v[98:99], 10, v[98:99]
	v_lshl_add_u64 v[110:111], v[114:115], 0, v[98:99]
	v_ashrrev_i32_e32 v155, 31, v154
	s_add_i32 s6, s6, s96
	s_cmpk_gt_i32 s6, 0x1ff
	s_waitcnt vmcnt(0) lgkmcnt(0)
	v_mfma_f32_16x16x32_bf16 v[2:5], v[30:33], v[2:5], 0
	v_mfma_f32_16x16x32_bf16 v[2:5], v[34:37], v[6:9], v[2:5]
	v_mfma_f32_16x16x32_bf16 v[2:5], v[38:41], v[10:13], v[2:5]
	v_mfma_f32_16x16x32_bf16 v[14:17], v[42:45], v[14:17], v[2:5]
	v_mfma_f32_16x16x32_bf16 v[2:5], v[30:33], v[18:21], 0
	v_or_b32_e32 v18, 64, v116
	v_ashrrev_i32_e32 v19, 31, v18
	v_lshlrev_b64 v[18:19], 10, v[18:19]
	v_mfma_f32_16x16x32_bf16 v[2:5], v[34:37], v[22:25], v[2:5]
	v_mfma_f32_16x16x32_bf16 v[2:5], v[38:41], v[26:29], v[2:5]
	v_mfma_f32_16x16x32_bf16 v[10:13], v[42:45], v[46:49], v[2:5]
	v_lshl_add_u64 v[46:47], v[114:115], 0, v[18:19]
	global_load_dwordx4 v[18:21], v[46:47], off
	global_load_dwordx4 v[22:25], v[46:47], off offset:64
	global_load_dwordx4 v[26:29], v[46:47], off offset:128
	s_nop 0
	global_load_dwordx4 v[46:49], v[46:47], off offset:192
	v_mfma_f32_16x16x32_bf16 v[2:5], v[30:33], v[50:53], 0
	v_or_b32_e32 v50, 0x50, v116
	v_ashrrev_i32_e32 v51, 31, v50
	v_lshlrev_b64 v[50:51], 10, v[50:51]
	v_mfma_f32_16x16x32_bf16 v[2:5], v[34:37], v[54:57], v[2:5]
	v_mfma_f32_16x16x32_bf16 v[2:5], v[38:41], v[58:61], v[2:5]
	v_mfma_f32_16x16x32_bf16 v[6:9], v[42:45], v[62:65], v[2:5]
	v_lshl_add_u64 v[62:63], v[114:115], 0, v[50:51]
	global_load_dwordx4 v[50:53], v[62:63], off
	global_load_dwordx4 v[54:57], v[62:63], off offset:64
	global_load_dwordx4 v[58:61], v[62:63], off offset:128
	s_nop 0
	global_load_dwordx4 v[62:65], v[62:63], off offset:192
	v_mfma_f32_16x16x32_bf16 v[2:5], v[30:33], v[66:69], 0
	v_or_b32_e32 v66, 0x60, v116
	v_ashrrev_i32_e32 v67, 31, v66
	v_lshlrev_b64 v[66:67], 10, v[66:67]
	v_mfma_f32_16x16x32_bf16 v[2:5], v[34:37], v[70:73], v[2:5]
	v_mfma_f32_16x16x32_bf16 v[2:5], v[38:41], v[74:77], v[2:5]
	v_mfma_f32_16x16x32_bf16 v[2:5], v[42:45], v[78:81], v[2:5]
	v_lshl_add_u64 v[78:79], v[114:115], 0, v[66:67]
	global_load_dwordx4 v[66:69], v[78:79], off
	global_load_dwordx4 v[70:73], v[78:79], off offset:64
	global_load_dwordx4 v[74:77], v[78:79], off offset:128
	s_nop 0
	global_load_dwordx4 v[78:81], v[78:79], off offset:192
	s_nop 0
	global_load_dwordx4 v[82:85], v[94:95], off
	global_load_dwordx4 v[86:89], v[94:95], off offset:64
	global_load_dwordx4 v[90:93], v[94:95], off offset:128
	s_nop 0
	global_load_dwordx4 v[94:97], v[94:95], off offset:192
	s_waitcnt vmcnt(0) lgkmcnt(0)
;     ...
; #pragma unroll
;     for (int nb = 0; nb < 4; ++nb) {
;       bf16x8 bk[4][4];
; #pragma unroll
;       for (int n4 = 0; n4 < 4; ++n4)
; #pragma unroll
;         for (int ks = 0; ks < 4; ++ks)
;           bk[n4][ks] = *(const bf16x8*)(Km + (long)(b * 256 + (nb * 4 + n4) * 16 + fr) * 512 + h * 128 + ks * 32 + fq * 8);
;       asm volatile("" ::: "memory");
; #pragma unroll
;       for (int n4 = 0; n4 < 4; ++n4) {
;         f32x4 a = {0.f, 0.f, 0.f, 0.f};
; #pragma unroll
;         for (int ks = 0; ks < 4; ++ks) a = __builtin_amdgcn_mfma_f32_16x16x32_bf16(aQ[ks], bk[n4][ks], a, 0, 0, 0);
;         s[nb * 4 + n4] = a;
;       }
;     }
	v_mfma_f32_16x16x32_bf16 v[18:21], v[30:33], v[18:21], 0
	v_mfma_f32_16x16x32_bf16 v[18:21], v[34:37], v[22:25], v[18:21]
	v_mfma_f32_16x16x32_bf16 v[18:21], v[38:41], v[26:29], v[18:21]
	v_mfma_f32_16x16x32_bf16 v[46:49], v[42:45], v[46:49], v[18:21]
	v_mfma_f32_16x16x32_bf16 v[18:21], v[30:33], v[50:53], 0
	v_or_b32_e32 v50, 0x80, v116
	v_ashrrev_i32_e32 v51, 31, v50
	v_lshlrev_b64 v[50:51], 10, v[50:51]
	v_mfma_f32_16x16x32_bf16 v[18:21], v[34:37], v[54:57], v[18:21]
	v_mfma_f32_16x16x32_bf16 v[18:21], v[38:41], v[58:61], v[18:21]
	v_mfma_f32_16x16x32_bf16 v[26:29], v[42:45], v[62:65], v[18:21]
	v_lshl_add_u64 v[62:63], v[114:115], 0, v[50:51]
	global_load_dwordx4 v[50:53], v[62:63], off
	global_load_dwordx4 v[54:57], v[62:63], off offset:64
	global_load_dwordx4 v[58:61], v[62:63], off offset:128
	s_nop 0
	global_load_dwordx4 v[62:65], v[62:63], off offset:192
	v_mfma_f32_16x16x32_bf16 v[18:21], v[30:33], v[66:69], 0
	v_or_b32_e32 v66, 0x90, v116
	v_ashrrev_i32_e32 v67, 31, v66
	v_lshlrev_b64 v[66:67], 10, v[66:67]
	v_mfma_f32_16x16x32_bf16 v[18:21], v[34:37], v[70:73], v[18:21]
	v_mfma_f32_16x16x32_bf16 v[18:21], v[38:41], v[74:77], v[18:21]
	v_mfma_f32_16x16x32_bf16 v[22:25], v[42:45], v[78:81], v[18:21]
	v_lshl_add_u64 v[78:79], v[114:115], 0, v[66:67]
	global_load_dwordx4 v[66:69], v[78:79], off
	global_load_dwordx4 v[70:73], v[78:79], off offset:64
	global_load_dwordx4 v[74:77], v[78:79], off offset:128
	s_nop 0
	global_load_dwordx4 v[78:81], v[78:79], off offset:192
	v_mfma_f32_16x16x32_bf16 v[18:21], v[30:33], v[82:85], 0
	v_or_b32_e32 v82, 0xa0, v116
	v_ashrrev_i32_e32 v83, 31, v82
	v_lshlrev_b64 v[82:83], 10, v[82:83]
	v_mfma_f32_16x16x32_bf16 v[18:21], v[34:37], v[86:89], v[18:21]
	v_mfma_f32_16x16x32_bf16 v[18:21], v[38:41], v[90:93], v[18:21]
	v_mfma_f32_16x16x32_bf16 v[18:21], v[42:45], v[94:97], v[18:21]
	v_lshl_add_u64 v[94:95], v[114:115], 0, v[82:83]
	global_load_dwordx4 v[82:85], v[94:95], off
	global_load_dwordx4 v[86:89], v[94:95], off offset:64
	global_load_dwordx4 v[90:93], v[94:95], off offset:128
	s_nop 0
	global_load_dwordx4 v[94:97], v[94:95], off offset:192
	s_nop 0
	global_load_dwordx4 v[98:101], v[110:111], off
	global_load_dwordx4 v[102:105], v[110:111], off offset:64
	global_load_dwordx4 v[106:109], v[110:111], off offset:128
	s_nop 0
	global_load_dwordx4 v[110:113], v[110:111], off offset:192
	s_waitcnt vmcnt(0) lgkmcnt(0)
	v_mfma_f32_16x16x32_bf16 v[50:53], v[30:33], v[50:53], 0
	v_mfma_f32_16x16x32_bf16 v[50:53], v[34:37], v[54:57], v[50:53]
	v_mfma_f32_16x16x32_bf16 v[50:53], v[38:41], v[58:61], v[50:53]
	v_mfma_f32_16x16x32_bf16 v[62:65], v[42:45], v[62:65], v[50:53]
	v_mfma_f32_16x16x32_bf16 v[50:53], v[30:33], v[66:69], 0
	v_or_b32_e32 v66, 0xc0, v116
	v_ashrrev_i32_e32 v67, 31, v66
	v_lshlrev_b64 v[66:67], 10, v[66:67]
	v_mfma_f32_16x16x32_bf16 v[50:53], v[34:37], v[70:73], v[50:53]
	v_mfma_f32_16x16x32_bf16 v[50:53], v[38:41], v[74:77], v[50:53]
	v_mfma_f32_16x16x32_bf16 v[58:61], v[42:45], v[78:81], v[50:53]
	v_lshl_add_u64 v[78:79], v[114:115], 0, v[66:67]
	global_load_dwordx4 v[66:69], v[78:79], off
	global_load_dwordx4 v[70:73], v[78:79], off offset:64
	global_load_dwordx4 v[74:77], v[78:79], off offset:128
	s_nop 0
	global_load_dwordx4 v[78:81], v[78:79], off offset:192
	v_mfma_f32_16x16x32_bf16 v[50:53], v[30:33], v[82:85], 0
	v_or_b32_e32 v82, 0xd0, v116
	v_ashrrev_i32_e32 v83, 31, v82
	v_lshlrev_b64 v[82:83], 10, v[82:83]
	v_mfma_f32_16x16x32_bf16 v[50:53], v[34:37], v[86:89], v[50:53]
	v_mfma_f32_16x16x32_bf16 v[50:53], v[38:41], v[90:93], v[50:53]
	v_mfma_f32_16x16x32_bf16 v[54:57], v[42:45], v[94:97], v[50:53]
	v_lshl_add_u64 v[94:95], v[114:115], 0, v[82:83]
	global_load_dwordx4 v[82:85], v[94:95], off
	global_load_dwordx4 v[86:89], v[94:95], off offset:64
	global_load_dwordx4 v[90:93], v[94:95], off offset:128
	s_nop 0
	global_load_dwordx4 v[94:97], v[94:95], off offset:192
	v_mfma_f32_16x16x32_bf16 v[50:53], v[30:33], v[98:101], 0
	v_or_b32_e32 v98, 0xe0, v116
	v_or_b32_e32 v116, 0xf0, v116
	v_ashrrev_i32_e32 v99, 31, v98
	v_mfma_f32_16x16x32_bf16 v[50:53], v[34:37], v[102:105], v[50:53]
	v_ashrrev_i32_e32 v117, 31, v116
	v_lshlrev_b64 v[98:99], 10, v[98:99]
	v_lshlrev_b64 v[116:117], 10, v[116:117]
	v_mfma_f32_16x16x32_bf16 v[50:53], v[38:41], v[106:109], v[50:53]
	v_lshl_add_u64 v[126:127], v[114:115], 0, v[116:117]
	v_mfma_f32_16x16x32_bf16 v[50:53], v[42:45], v[110:113], v[50:53]
	v_lshl_add_u64 v[110:111], v[114:115], 0, v[98:99]
	global_load_dwordx4 v[98:101], v[110:111], off
	global_load_dwordx4 v[102:105], v[110:111], off offset:64
	global_load_dwordx4 v[106:109], v[110:111], off offset:128
	s_nop 0
	global_load_dwordx4 v[110:113], v[110:111], off offset:192
	s_nop 0
	global_load_dwordx4 v[114:117], v[126:127], off
	global_load_dwordx4 v[118:121], v[126:127], off offset:64
	global_load_dwordx4 v[122:125], v[126:127], off offset:128
	s_nop 0
	global_load_dwordx4 v[126:129], v[126:127], off offset:192
	s_waitcnt lgkmcnt(0)
	s_barrier
; __device__ __forceinline__ u16 f2bf(float f) { return (u16)(pack2(f, 0.f) & 0xffffu); }
;     ...
;     const float scale = 0.08838834764831845f;
;     float mx[4], sm[4];
; #pragma unroll
;     for (int r = 0; r < 4; ++r) {
;       float v = s[0][r];
; #pragma unroll
;       for (int nt = 1; nt < 16; ++nt) v = fmaxf(v, s[nt][r]);
; #pragma unroll
;       for (int o = 1; o < 16; o <<= 1) v = fmaxf(v, __shfl_xor(v, o, 64));
;       mx[r] = v; sm[r] = 0.f;
;     }
;     __syncthreads();
; #pragma unroll
;     for (int nt = 0; nt < 16; ++nt)
; #pragma unroll
;       for (int r = 0; r < 4; ++r) {
;         float e = __expf((s[nt][r] - mx[r]) * scale);
;         sm[r] += e;
;         Pw[(fq * 4 + r) * 264 + nt * 16 + fr] = f2bf(e);
;       }
	s_waitcnt vmcnt(0)
	v_mfma_f32_16x16x32_bf16 v[66:69], v[30:33], v[66:69], 0
	v_mfma_f32_16x16x32_bf16 v[66:69], v[34:37], v[70:73], v[66:69]
	v_mfma_f32_16x16x32_bf16 v[66:69], v[38:41], v[74:77], v[66:69]
	v_mfma_f32_16x16x32_bf16 v[74:77], v[42:45], v[78:81], v[66:69]
	v_mfma_f32_16x16x32_bf16 v[66:69], v[30:33], v[82:85], 0
	v_mfma_f32_16x16x32_bf16 v[66:69], v[34:37], v[86:89], v[66:69]
	v_mfma_f32_16x16x32_bf16 v[66:69], v[38:41], v[90:93], v[66:69]
	v_mfma_f32_16x16x32_bf16 v[70:73], v[42:45], v[94:97], v[66:69]
	v_mfma_f32_16x16x32_bf16 v[66:69], v[30:33], v[98:101], 0
	v_mfma_f32_16x16x32_bf16 v[30:33], v[30:33], v[114:117], 0
	v_mfma_f32_16x16x32_bf16 v[66:69], v[34:37], v[102:105], v[66:69]
	v_mfma_f32_16x16x32_bf16 v[30:33], v[34:37], v[118:121], v[30:33]
	v_max_f32_e32 v34, v10, v10
	v_max_f32_e32 v35, v14, v14
	v_max_f32_e32 v34, v35, v34
	v_mfma_f32_16x16x32_bf16 v[66:69], v[38:41], v[106:109], v[66:69]
	v_max3_f32 v34, v34, v6, v2
	v_max3_f32 v34, v34, v46, v26
	v_max3_f32 v34, v34, v22, v18
	v_mfma_f32_16x16x32_bf16 v[30:33], v[38:41], v[122:125], v[30:33]
	v_max3_f32 v34, v34, v62, v58
	v_max3_f32 v34, v34, v54, v50
	v_max3_f32 v34, v34, v74, v70
	v_mfma_f32_16x16x32_bf16 v[66:69], v[42:45], v[110:113], v[66:69]
	v_add_u32_e32 v37, 64, v196
	v_max_f32_e32 v40, v15, v15
	v_max_f32_e32 v41, v16, v16
	v_mfma_f32_16x16x32_bf16 v[30:33], v[42:45], v[126:129], v[30:33]
	v_max_f32_e32 v42, v17, v17
	s_nop 6
	v_max3_f32 v35, v34, v66, v30
	v_xor_b32_e32 v34, 1, v195
	v_cmp_lt_i32_e32 vcc, v34, v37
	s_nop 1
	v_cndmask_b32_e32 v34, v195, v34, vcc
	v_lshlrev_b32_e32 v34, 2, v34
	ds_bpermute_b32 v36, v34, v35
	s_waitcnt lgkmcnt(0)
	v_max_f32_e32 v36, v36, v36
	v_max_f32_e32 v36, v35, v36
	v_xor_b32_e32 v35, 2, v195
	v_cmp_lt_i32_e32 vcc, v35, v37
	s_nop 1
	v_cndmask_b32_e32 v35, v195, v35, vcc
	v_lshlrev_b32_e32 v35, 2, v35
	ds_bpermute_b32 v38, v35, v36
	s_waitcnt lgkmcnt(0)
	v_max_f32_e32 v38, v38, v38
	v_max_f32_e32 v38, v36, v38
	v_xor_b32_e32 v36, 4, v195
	v_cmp_lt_i32_e32 vcc, v36, v37
	s_nop 1
	v_cndmask_b32_e32 v36, v195, v36, vcc
	v_lshlrev_b32_e32 v36, 2, v36
	ds_bpermute_b32 v39, v36, v38
	s_waitcnt lgkmcnt(0)
	v_max_f32_e32 v39, v39, v39
	v_max_f32_e32 v38, v38, v39
	v_xor_b32_e32 v39, 8, v195
	v_cmp_lt_i32_e32 vcc, v39, v37
	s_nop 1
	v_cndmask_b32_e32 v37, v195, v39, vcc
	v_lshlrev_b32_e32 v37, 2, v37
	ds_bpermute_b32 v39, v37, v38
	s_waitcnt lgkmcnt(0)
	v_max_f32_e32 v39, v39, v39
	v_max_f32_e32 v38, v38, v39
	v_max_f32_e32 v39, v11, v11
	v_max_f32_e32 v39, v40, v39
	v_max3_f32 v39, v39, v7, v3
	v_max3_f32 v39, v39, v47, v27
	v_max3_f32 v39, v39, v23, v19
	v_max3_f32 v39, v39, v63, v59
	v_max3_f32 v39, v39, v55, v51
	v_max3_f32 v39, v39, v75, v71
	v_max3_f32 v39, v39, v67, v31
	ds_bpermute_b32 v40, v34, v39
	v_sub_f32_e32 v14, v14, v38
	v_mul_f32_e32 v14, 0x3db504f3, v14
	v_mul_f32_e32 v14, 0x3fb8aa3b, v14
	v_exp_f32_e32 v14, v14
	s_waitcnt lgkmcnt(0)
	v_max_f32_e32 v40, v40, v40
	v_max_f32_e32 v39, v39, v40
	ds_bpermute_b32 v40, v35, v39
	v_sub_f32_e32 v10, v10, v38
	v_mul_f32_e32 v10, 0x3db504f3, v10
	v_mul_f32_e32 v10, 0x3fb8aa3b, v10
	v_exp_f32_e32 v10, v10
	s_waitcnt lgkmcnt(0)
	v_max_f32_e32 v40, v40, v40
	v_max_f32_e32 v39, v39, v40
	ds_bpermute_b32 v40, v36, v39
	v_sub_f32_e32 v6, v6, v38
	v_mul_f32_e32 v6, 0x3db504f3, v6
	v_mul_f32_e32 v6, 0x3fb8aa3b, v6
	v_exp_f32_e32 v6, v6
	s_waitcnt lgkmcnt(0)
	v_max_f32_e32 v40, v40, v40
	v_max_f32_e32 v39, v39, v40
	ds_bpermute_b32 v40, v37, v39
	v_sub_f32_e32 v2, v2, v38
	v_mul_f32_e32 v2, 0x3db504f3, v2
	v_mul_f32_e32 v2, 0x3fb8aa3b, v2
	v_exp_f32_e32 v2, v2
	s_waitcnt lgkmcnt(0)
	v_max_f32_e32 v40, v40, v40
	v_max_f32_e32 v39, v39, v40
	v_max_f32_e32 v40, v12, v12
	v_max_f32_e32 v40, v41, v40
	v_max3_f32 v40, v40, v8, v4
	v_max3_f32 v40, v40, v48, v28
	v_max3_f32 v40, v40, v24, v20
	v_max3_f32 v40, v40, v64, v60
	v_max3_f32 v40, v40, v56, v52
	v_max3_f32 v40, v40, v76, v72
	v_max3_f32 v40, v40, v68, v32
	ds_bpermute_b32 v41, v34, v40
	s_waitcnt lgkmcnt(0)
	v_max_f32_e32 v41, v41, v41
	v_max_f32_e32 v40, v40, v41
	ds_bpermute_b32 v41, v35, v40
	s_waitcnt lgkmcnt(0)
	v_max_f32_e32 v41, v41, v41
	v_max_f32_e32 v40, v40, v41
	ds_bpermute_b32 v41, v36, v40
	s_waitcnt lgkmcnt(0)
	v_max_f32_e32 v41, v41, v41
	v_max_f32_e32 v40, v40, v41
	ds_bpermute_b32 v41, v37, v40
	s_waitcnt lgkmcnt(0)
	v_max_f32_e32 v41, v41, v41
	v_max_f32_e32 v40, v40, v41
	v_max_f32_e32 v41, v13, v13
	v_max_f32_e32 v41, v42, v41
	v_max3_f32 v41, v41, v9, v5
	v_max3_f32 v41, v41, v49, v29
	v_max3_f32 v41, v41, v25, v21
	v_max3_f32 v41, v41, v65, v61
	v_max3_f32 v41, v41, v57, v53
	v_max3_f32 v41, v41, v77, v73
	v_max3_f32 v41, v41, v69, v33
	ds_bpermute_b32 v42, v34, v41
	s_waitcnt lgkmcnt(0)
	v_max_f32_e32 v42, v42, v42
	v_max_f32_e32 v41, v41, v42
	ds_bpermute_b32 v42, v35, v41
	s_waitcnt lgkmcnt(0)
	v_max_f32_e32 v42, v42, v42
	v_max_f32_e32 v41, v41, v42
	ds_bpermute_b32 v42, v36, v41
	s_waitcnt lgkmcnt(0)
	v_max_f32_e32 v42, v42, v42
	v_max_f32_e32 v41, v41, v42
	ds_bpermute_b32 v42, v37, v41
	s_waitcnt lgkmcnt(0)
; __device__ __forceinline__ u16 f2bf(float f) { return (u16)(pack2(f, 0.f) & 0xffffu); }
;     ...
;     __syncthreads();
; #pragma unroll
;     for (int nt = 0; nt < 16; ++nt)
; #pragma unroll
;       for (int r = 0; r < 4; ++r) {
;         float e = __expf((s[nt][r] - mx[r]) * scale);
;         sm[r] += e;
;         Pw[(fq * 4 + r) * 264 + nt * 16 + fr] = f2bf(e);
;       }
	v_max_f32_e32 v42, v42, v42
	v_max_f32_e32 v41, v41, v42
	v_add_f32_e32 v42, 0, v14
	v_cvt_pk_bf16_f32 v14, v14, s0
	ds_write_b16 v131, v14
	v_sub_f32_e32 v14, v15, v39
	v_mul_f32_e32 v14, 0x3db504f3, v14
	v_mul_f32_e32 v14, 0x3fb8aa3b, v14
	v_exp_f32_e32 v14, v14
	s_nop 0
	v_add_f32_e32 v15, 0, v14
	v_cvt_pk_bf16_f32 v14, v14, s0
	ds_write_b16 v141, v14
	v_sub_f32_e32 v14, v16, v40
	v_mul_f32_e32 v14, 0x3db504f3, v14
	v_mul_f32_e32 v14, 0x3fb8aa3b, v14
	v_exp_f32_e32 v14, v14
	s_nop 0
	v_add_f32_e32 v16, 0, v14
	v_cvt_pk_bf16_f32 v14, v14, s0
	ds_write_b16 v141, v14 offset:528
	v_sub_f32_e32 v14, v17, v41
	v_mul_f32_e32 v14, 0x3db504f3, v14
	v_mul_f32_e32 v14, 0x3fb8aa3b, v14
	v_exp_f32_e32 v14, v14
	s_nop 0
	v_add_f32_e32 v17, 0, v14
	v_cvt_pk_bf16_f32 v14, v14, s0
	ds_write_b16 v141, v14 offset:1056
	v_add_f32_e32 v14, v10, v42
	v_cvt_pk_bf16_f32 v10, v10, s0
	ds_write_b16 v131, v10 offset:32
	v_sub_f32_e32 v10, v11, v39
	v_mul_f32_e32 v10, 0x3db504f3, v10
	v_mul_f32_e32 v10, 0x3fb8aa3b, v10
	v_exp_f32_e32 v10, v10
	s_nop 0
	v_add_f32_e32 v11, v10, v15
	v_cvt_pk_bf16_f32 v10, v10, s0
	ds_write_b16 v141, v10 offset:32
	v_sub_f32_e32 v10, v12, v40
	v_mul_f32_e32 v10, 0x3db504f3, v10
	v_mul_f32_e32 v10, 0x3fb8aa3b, v10
	v_exp_f32_e32 v10, v10
	s_nop 0
	v_add_f32_e32 v12, v10, v16
	v_cvt_pk_bf16_f32 v10, v10, s0
	ds_write_b16 v141, v10 offset:560
	v_sub_f32_e32 v10, v13, v41
	v_mul_f32_e32 v10, 0x3db504f3, v10
	v_mul_f32_e32 v10, 0x3fb8aa3b, v10
	v_exp_f32_e32 v10, v10
	s_nop 0
	v_add_f32_e32 v13, v10, v17
	v_cvt_pk_bf16_f32 v10, v10, s0
	ds_write_b16 v141, v10 offset:1088
	v_add_f32_e32 v10, v6, v14
	v_cvt_pk_bf16_f32 v6, v6, s0
	ds_write_b16 v131, v6 offset:64
	v_sub_f32_e32 v6, v7, v39
	v_mul_f32_e32 v6, 0x3db504f3, v6
	v_mul_f32_e32 v6, 0x3fb8aa3b, v6
	v_exp_f32_e32 v6, v6
	s_nop 0
	v_add_f32_e32 v7, v6, v11
	v_cvt_pk_bf16_f32 v6, v6, s0
	ds_write_b16 v141, v6 offset:64
	v_sub_f32_e32 v6, v8, v40
	v_mul_f32_e32 v6, 0x3db504f3, v6
	v_mul_f32_e32 v6, 0x3fb8aa3b, v6
	v_exp_f32_e32 v6, v6
	s_nop 0
	v_add_f32_e32 v8, v6, v12
	v_cvt_pk_bf16_f32 v6, v6, s0
	ds_write_b16 v141, v6 offset:592
	v_sub_f32_e32 v6, v9, v41
	v_mul_f32_e32 v6, 0x3db504f3, v6
	v_mul_f32_e32 v6, 0x3fb8aa3b, v6
	v_exp_f32_e32 v6, v6
	s_nop 0
	v_add_f32_e32 v9, v6, v13
	v_cvt_pk_bf16_f32 v6, v6, s0
	ds_write_b16 v141, v6 offset:1120
	v_add_f32_e32 v6, v2, v10
	v_cvt_pk_bf16_f32 v2, v2, s0
	ds_write_b16 v131, v2 offset:96
	v_sub_f32_e32 v2, v3, v39
	v_mul_f32_e32 v2, 0x3db504f3, v2
	v_mul_f32_e32 v2, 0x3fb8aa3b, v2
	v_exp_f32_e32 v2, v2
	s_nop 0
	v_add_f32_e32 v3, v2, v7
	v_cvt_pk_bf16_f32 v2, v2, s0
	ds_write_b16 v141, v2 offset:96
	v_sub_f32_e32 v2, v4, v40
	v_mul_f32_e32 v2, 0x3db504f3, v2
	v_mul_f32_e32 v2, 0x3fb8aa3b, v2
	v_exp_f32_e32 v2, v2
	s_nop 0
	v_add_f32_e32 v4, v2, v8
	v_cvt_pk_bf16_f32 v2, v2, s0
	ds_write_b16 v141, v2 offset:624
	v_sub_f32_e32 v2, v5, v41
	v_mul_f32_e32 v2, 0x3db504f3, v2
	v_mul_f32_e32 v2, 0x3fb8aa3b, v2
	v_exp_f32_e32 v2, v2
	s_nop 0
	v_add_f32_e32 v5, v2, v9
	v_cvt_pk_bf16_f32 v2, v2, s0
	ds_write_b16 v141, v2 offset:1152
	v_sub_f32_e32 v2, v46, v38
	v_mul_f32_e32 v2, 0x3db504f3, v2
	v_mul_f32_e32 v2, 0x3fb8aa3b, v2
	v_exp_f32_e32 v2, v2
	s_nop 0
	v_add_f32_e32 v6, v2, v6
	v_cvt_pk_bf16_f32 v2, v2, s0
	ds_write_b16 v131, v2 offset:128
	v_sub_f32_e32 v2, v47, v39
	v_mul_f32_e32 v2, 0x3db504f3, v2
	v_mul_f32_e32 v2, 0x3fb8aa3b, v2
	v_exp_f32_e32 v2, v2
	s_nop 0
	v_add_f32_e32 v3, v2, v3
	v_cvt_pk_bf16_f32 v2, v2, s0
	ds_write_b16 v141, v2 offset:128
	v_sub_f32_e32 v2, v48, v40
	v_mul_f32_e32 v2, 0x3db504f3, v2
	v_mul_f32_e32 v2, 0x3fb8aa3b, v2
	v_exp_f32_e32 v2, v2
	s_nop 0
	v_add_f32_e32 v4, v2, v4
	v_cvt_pk_bf16_f32 v2, v2, s0
	ds_write_b16 v141, v2 offset:656
	v_sub_f32_e32 v2, v49, v41
	v_mul_f32_e32 v2, 0x3db504f3, v2
	v_mul_f32_e32 v2, 0x3fb8aa3b, v2
	v_exp_f32_e32 v2, v2
	s_nop 0
	v_add_f32_e32 v5, v2, v5
	v_cvt_pk_bf16_f32 v2, v2, s0
	ds_write_b16 v141, v2 offset:1184
	v_sub_f32_e32 v2, v26, v38
	v_mul_f32_e32 v2, 0x3db504f3, v2
	v_mul_f32_e32 v2, 0x3fb8aa3b, v2
	v_exp_f32_e32 v2, v2
	s_nop 0
	v_add_f32_e32 v6, v2, v6
	v_cvt_pk_bf16_f32 v2, v2, s0
	ds_write_b16 v131, v2 offset:160
	v_sub_f32_e32 v2, v27, v39
	v_mul_f32_e32 v2, 0x3db504f3, v2
	v_mul_f32_e32 v2, 0x3fb8aa3b, v2
	v_exp_f32_e32 v2, v2
	s_nop 0
	v_add_f32_e32 v3, v2, v3
	v_cvt_pk_bf16_f32 v2, v2, s0
	ds_write_b16 v141, v2 offset:160
	v_sub_f32_e32 v2, v28, v40
	v_mul_f32_e32 v2, 0x3db504f3, v2
	v_mul_f32_e32 v2, 0x3fb8aa3b, v2
	v_exp_f32_e32 v2, v2
	s_nop 0
	v_add_f32_e32 v4, v2, v4
	v_cvt_pk_bf16_f32 v2, v2, s0
	ds_write_b16 v141, v2 offset:688
	v_sub_f32_e32 v2, v29, v41
	v_mul_f32_e32 v2, 0x3db504f3, v2
	v_mul_f32_e32 v2, 0x3fb8aa3b, v2
	v_exp_f32_e32 v2, v2
	s_nop 0
	v_add_f32_e32 v5, v2, v5
	v_cvt_pk_bf16_f32 v2, v2, s0
	ds_write_b16 v141, v2 offset:1216
	v_sub_f32_e32 v2, v22, v38
	v_mul_f32_e32 v2, 0x3db504f3, v2
	v_mul_f32_e32 v2, 0x3fb8aa3b, v2
	v_exp_f32_e32 v2, v2
	s_nop 0
	v_add_f32_e32 v6, v2, v6
	v_cvt_pk_bf16_f32 v2, v2, s0
	ds_write_b16 v131, v2 offset:192
	v_sub_f32_e32 v2, v23, v39
	v_mul_f32_e32 v2, 0x3db504f3, v2
	v_mul_f32_e32 v2, 0x3fb8aa3b, v2
	v_exp_f32_e32 v2, v2
	s_nop 0
	v_add_f32_e32 v3, v2, v3
	v_cvt_pk_bf16_f32 v2, v2, s0
	ds_write_b16 v141, v2 offset:192
	v_sub_f32_e32 v2, v24, v40
	v_mul_f32_e32 v2, 0x3db504f3, v2
	v_mul_f32_e32 v2, 0x3fb8aa3b, v2
	v_exp_f32_e32 v2, v2
	s_nop 0
	v_add_f32_e32 v4, v2, v4
	v_cvt_pk_bf16_f32 v2, v2, s0
	ds_write_b16 v141, v2 offset:720
	v_sub_f32_e32 v2, v25, v41
	v_mul_f32_e32 v2, 0x3db504f3, v2
	v_mul_f32_e32 v2, 0x3fb8aa3b, v2
	v_exp_f32_e32 v2, v2
	s_nop 0
	v_add_f32_e32 v5, v2, v5
	v_cvt_pk_bf16_f32 v2, v2, s0
; __device__ __forceinline__ u16 f2bf(float f) { return (u16)(pack2(f, 0.f) & 0xffffu); }
;     ...
;     __syncthreads();
; #pragma unroll
;     for (int nt = 0; nt < 16; ++nt)
; #pragma unroll
;       for (int r = 0; r < 4; ++r) {
;         float e = __expf((s[nt][r] - mx[r]) * scale);
;         sm[r] += e;
;         Pw[(fq * 4 + r) * 264 + nt * 16 + fr] = f2bf(e);
;       }
	ds_write_b16 v141, v2 offset:1248
	v_sub_f32_e32 v2, v18, v38
	v_mul_f32_e32 v2, 0x3db504f3, v2
	v_mul_f32_e32 v2, 0x3fb8aa3b, v2
	v_exp_f32_e32 v2, v2
	s_nop 0
	v_add_f32_e32 v6, v2, v6
	v_cvt_pk_bf16_f32 v2, v2, s0
	ds_write_b16 v131, v2 offset:224
	v_sub_f32_e32 v2, v19, v39
	v_mul_f32_e32 v2, 0x3db504f3, v2
	v_mul_f32_e32 v2, 0x3fb8aa3b, v2
	v_exp_f32_e32 v2, v2
	s_nop 0
	v_add_f32_e32 v3, v2, v3
	v_cvt_pk_bf16_f32 v2, v2, s0
	ds_write_b16 v141, v2 offset:224
	v_sub_f32_e32 v2, v20, v40
	v_mul_f32_e32 v2, 0x3db504f3, v2
	v_mul_f32_e32 v2, 0x3fb8aa3b, v2
	v_exp_f32_e32 v2, v2
	s_nop 0
	v_add_f32_e32 v4, v2, v4
	v_cvt_pk_bf16_f32 v2, v2, s0
	ds_write_b16 v141, v2 offset:752
	v_sub_f32_e32 v2, v21, v41
	v_mul_f32_e32 v2, 0x3db504f3, v2
	v_mul_f32_e32 v2, 0x3fb8aa3b, v2
	v_exp_f32_e32 v2, v2
	s_nop 0
	v_add_f32_e32 v5, v2, v5
	v_cvt_pk_bf16_f32 v2, v2, s0
	ds_write_b16 v141, v2 offset:1280
	v_sub_f32_e32 v2, v62, v38
	v_mul_f32_e32 v2, 0x3db504f3, v2
	v_mul_f32_e32 v2, 0x3fb8aa3b, v2
	v_exp_f32_e32 v2, v2
	s_nop 0
	v_add_f32_e32 v6, v2, v6
	v_cvt_pk_bf16_f32 v2, v2, s0
	ds_write_b16 v131, v2 offset:256
	v_sub_f32_e32 v2, v63, v39
	v_mul_f32_e32 v2, 0x3db504f3, v2
	v_mul_f32_e32 v2, 0x3fb8aa3b, v2
	v_exp_f32_e32 v2, v2
	s_nop 0
	v_add_f32_e32 v3, v2, v3
	v_cvt_pk_bf16_f32 v2, v2, s0
	ds_write_b16 v141, v2 offset:256
	v_sub_f32_e32 v2, v64, v40
	v_mul_f32_e32 v2, 0x3db504f3, v2
	v_mul_f32_e32 v2, 0x3fb8aa3b, v2
	v_exp_f32_e32 v2, v2
	s_nop 0
	v_add_f32_e32 v4, v2, v4
	v_cvt_pk_bf16_f32 v2, v2, s0
	ds_write_b16 v141, v2 offset:784
	v_sub_f32_e32 v2, v65, v41
	v_mul_f32_e32 v2, 0x3db504f3, v2
	v_mul_f32_e32 v2, 0x3fb8aa3b, v2
	v_exp_f32_e32 v2, v2
	s_nop 0
	v_add_f32_e32 v5, v2, v5
	v_cvt_pk_bf16_f32 v2, v2, s0
	ds_write_b16 v141, v2 offset:1312
	v_sub_f32_e32 v2, v58, v38
	v_mul_f32_e32 v2, 0x3db504f3, v2
	v_mul_f32_e32 v2, 0x3fb8aa3b, v2
	v_exp_f32_e32 v2, v2
	s_nop 0
	v_add_f32_e32 v6, v2, v6
	v_cvt_pk_bf16_f32 v2, v2, s0
	ds_write_b16 v131, v2 offset:288
	v_sub_f32_e32 v2, v59, v39
	v_mul_f32_e32 v2, 0x3db504f3, v2
	v_mul_f32_e32 v2, 0x3fb8aa3b, v2
	v_exp_f32_e32 v2, v2
	s_nop 0
	v_add_f32_e32 v3, v2, v3
	v_cvt_pk_bf16_f32 v2, v2, s0
	ds_write_b16 v141, v2 offset:288
	v_sub_f32_e32 v2, v60, v40
	v_mul_f32_e32 v2, 0x3db504f3, v2
	v_mul_f32_e32 v2, 0x3fb8aa3b, v2
	v_exp_f32_e32 v2, v2
	s_nop 0
	v_add_f32_e32 v4, v2, v4
	v_cvt_pk_bf16_f32 v2, v2, s0
	ds_write_b16 v141, v2 offset:816
	v_sub_f32_e32 v2, v61, v41
	v_mul_f32_e32 v2, 0x3db504f3, v2
	v_mul_f32_e32 v2, 0x3fb8aa3b, v2
	v_exp_f32_e32 v2, v2
	s_nop 0
	v_add_f32_e32 v5, v2, v5
	v_cvt_pk_bf16_f32 v2, v2, s0
	ds_write_b16 v141, v2 offset:1344
	v_sub_f32_e32 v2, v54, v38
	v_mul_f32_e32 v2, 0x3db504f3, v2
	v_mul_f32_e32 v2, 0x3fb8aa3b, v2
	v_exp_f32_e32 v2, v2
	s_nop 0
	v_add_f32_e32 v6, v2, v6
	v_cvt_pk_bf16_f32 v2, v2, s0
	ds_write_b16 v131, v2 offset:320
	v_sub_f32_e32 v2, v55, v39
	v_mul_f32_e32 v2, 0x3db504f3, v2
	v_mul_f32_e32 v2, 0x3fb8aa3b, v2
	v_exp_f32_e32 v2, v2
	s_nop 0
	v_add_f32_e32 v3, v2, v3
	v_cvt_pk_bf16_f32 v2, v2, s0
	ds_write_b16 v141, v2 offset:320
	v_sub_f32_e32 v2, v56, v40
	v_mul_f32_e32 v2, 0x3db504f3, v2
	v_mul_f32_e32 v2, 0x3fb8aa3b, v2
	v_exp_f32_e32 v2, v2
	s_nop 0
	v_add_f32_e32 v4, v2, v4
	v_cvt_pk_bf16_f32 v2, v2, s0
	ds_write_b16 v141, v2 offset:848
	v_sub_f32_e32 v2, v57, v41
	v_mul_f32_e32 v2, 0x3db504f3, v2
	v_mul_f32_e32 v2, 0x3fb8aa3b, v2
	v_exp_f32_e32 v2, v2
	s_nop 0
	v_add_f32_e32 v5, v2, v5
	v_cvt_pk_bf16_f32 v2, v2, s0
	ds_write_b16 v141, v2 offset:1376
	v_sub_f32_e32 v2, v50, v38
	v_mul_f32_e32 v2, 0x3db504f3, v2
	v_mul_f32_e32 v2, 0x3fb8aa3b, v2
	v_exp_f32_e32 v2, v2
	s_nop 0
	v_add_f32_e32 v6, v2, v6
	v_cvt_pk_bf16_f32 v2, v2, s0
	ds_write_b16 v131, v2 offset:352
	v_sub_f32_e32 v2, v51, v39
	v_mul_f32_e32 v2, 0x3db504f3, v2
	v_mul_f32_e32 v2, 0x3fb8aa3b, v2
	v_exp_f32_e32 v2, v2
	s_nop 0
	v_add_f32_e32 v3, v2, v3
	v_cvt_pk_bf16_f32 v2, v2, s0
	ds_write_b16 v141, v2 offset:352
	v_sub_f32_e32 v2, v52, v40
	v_mul_f32_e32 v2, 0x3db504f3, v2
	v_mul_f32_e32 v2, 0x3fb8aa3b, v2
	v_exp_f32_e32 v2, v2
	s_nop 0
	v_add_f32_e32 v4, v2, v4
	v_cvt_pk_bf16_f32 v2, v2, s0
	ds_write_b16 v141, v2 offset:880
	v_sub_f32_e32 v2, v53, v41
	v_mul_f32_e32 v2, 0x3db504f3, v2
	v_mul_f32_e32 v2, 0x3fb8aa3b, v2
	v_exp_f32_e32 v2, v2
	s_nop 0
	v_add_f32_e32 v5, v2, v5
	v_cvt_pk_bf16_f32 v2, v2, s0
	ds_write_b16 v141, v2 offset:1408
	v_sub_f32_e32 v2, v74, v38
	v_mul_f32_e32 v2, 0x3db504f3, v2
	v_mul_f32_e32 v2, 0x3fb8aa3b, v2
	v_exp_f32_e32 v2, v2
	s_nop 0
	v_add_f32_e32 v6, v2, v6
	v_cvt_pk_bf16_f32 v2, v2, s0
	ds_write_b16 v131, v2 offset:384
	v_sub_f32_e32 v2, v75, v39
	v_mul_f32_e32 v2, 0x3db504f3, v2
	v_mul_f32_e32 v2, 0x3fb8aa3b, v2
	v_exp_f32_e32 v2, v2
	s_nop 0
	v_add_f32_e32 v3, v2, v3
	v_cvt_pk_bf16_f32 v2, v2, s0
	ds_write_b16 v141, v2 offset:384
	v_sub_f32_e32 v2, v76, v40
	v_mul_f32_e32 v2, 0x3db504f3, v2
	v_mul_f32_e32 v2, 0x3fb8aa3b, v2
	v_exp_f32_e32 v2, v2
	v_or_b32_e32 v76, v152, v136
	v_add_f32_e32 v4, v2, v4
	v_cvt_pk_bf16_f32 v2, v2, s0
	ds_write_b16 v141, v2 offset:912
	v_sub_f32_e32 v2, v77, v41
	v_mul_f32_e32 v2, 0x3db504f3, v2
	v_mul_f32_e32 v2, 0x3fb8aa3b, v2
	v_exp_f32_e32 v2, v2
	s_nop 0
	v_add_f32_e32 v5, v2, v5
	v_cvt_pk_bf16_f32 v2, v2, s0
	ds_write_b16 v141, v2 offset:1440
	v_sub_f32_e32 v2, v70, v38
	v_mul_f32_e32 v2, 0x3db504f3, v2
	v_mul_f32_e32 v2, 0x3fb8aa3b, v2
	v_exp_f32_e32 v2, v2
	s_nop 0
	v_add_f32_e32 v6, v2, v6
	v_cvt_pk_bf16_f32 v2, v2, s0
	ds_write_b16 v131, v2 offset:416
	v_sub_f32_e32 v2, v71, v39
	v_mul_f32_e32 v2, 0x3db504f3, v2
	v_mul_f32_e32 v2, 0x3fb8aa3b, v2
	v_exp_f32_e32 v2, v2
	s_nop 0
	v_add_f32_e32 v3, v2, v3
; __device__ __forceinline__ u16 f2bf(float f) { return (u16)(pack2(f, 0.f) & 0xffffu); }
;     ...
;     __syncthreads();
; #pragma unroll
;     for (int nt = 0; nt < 16; ++nt)
; #pragma unroll
;       for (int r = 0; r < 4; ++r) {
;         float e = __expf((s[nt][r] - mx[r]) * scale);
;         sm[r] += e;
;         Pw[(fq * 4 + r) * 264 + nt * 16 + fr] = f2bf(e);
;       }
; #pragma unroll
;     for (int r = 0; r < 4; ++r) {
;       float v = sm[r];
; #pragma unroll
;       for (int o = 1; o < 16; o <<= 1) v += __shfl_xor(v, o, 64);
;       sm[r] = 1.f / v;
;     }
;     __syncthreads();
	v_cvt_pk_bf16_f32 v2, v2, s0
	ds_write_b16 v141, v2 offset:416
	v_sub_f32_e32 v2, v72, v40
	v_mul_f32_e32 v2, 0x3db504f3, v2
	v_mul_f32_e32 v2, 0x3fb8aa3b, v2
	v_exp_f32_e32 v2, v2
	s_nop 0
	v_add_f32_e32 v4, v2, v4
	v_cvt_pk_bf16_f32 v2, v2, s0
	ds_write_b16 v141, v2 offset:944
	v_sub_f32_e32 v2, v73, v41
	v_mul_f32_e32 v2, 0x3db504f3, v2
	v_mul_f32_e32 v2, 0x3fb8aa3b, v2
	v_exp_f32_e32 v2, v2
	s_nop 0
	v_add_f32_e32 v5, v2, v5
	v_cvt_pk_bf16_f32 v2, v2, s0
	ds_write_b16 v141, v2 offset:1472
	v_sub_f32_e32 v2, v66, v38
	v_mul_f32_e32 v2, 0x3db504f3, v2
	v_mul_f32_e32 v2, 0x3fb8aa3b, v2
	v_exp_f32_e32 v2, v2
	s_nop 0
	v_add_f32_e32 v6, v2, v6
	v_cvt_pk_bf16_f32 v2, v2, s0
	ds_write_b16 v131, v2 offset:448
	v_sub_f32_e32 v2, v67, v39
	v_mul_f32_e32 v2, 0x3db504f3, v2
	v_mul_f32_e32 v2, 0x3fb8aa3b, v2
	v_exp_f32_e32 v2, v2
	s_nop 0
	v_add_f32_e32 v3, v2, v3
	v_cvt_pk_bf16_f32 v2, v2, s0
	ds_write_b16 v141, v2 offset:448
	v_sub_f32_e32 v2, v68, v40
	v_mul_f32_e32 v2, 0x3db504f3, v2
	v_mul_f32_e32 v2, 0x3fb8aa3b, v2
	v_exp_f32_e32 v2, v2
	s_nop 0
	v_add_f32_e32 v4, v2, v4
	v_cvt_pk_bf16_f32 v2, v2, s0
	ds_write_b16 v141, v2 offset:976
	v_sub_f32_e32 v2, v69, v41
	v_mul_f32_e32 v2, 0x3db504f3, v2
	v_mul_f32_e32 v2, 0x3fb8aa3b, v2
	v_exp_f32_e32 v2, v2
	s_nop 0
	v_add_f32_e32 v5, v2, v5
	v_cvt_pk_bf16_f32 v2, v2, s0
	ds_write_b16 v141, v2 offset:1504
	v_sub_f32_e32 v2, v30, v38
	v_mul_f32_e32 v2, 0x3db504f3, v2
	v_mul_f32_e32 v2, 0x3fb8aa3b, v2
	v_exp_f32_e32 v2, v2
	v_lshl_or_b32 v38, s7, 17, v149
	v_add_f32_e32 v6, v2, v6
	v_cvt_pk_bf16_f32 v2, v2, s0
	ds_write_b16 v131, v2 offset:480
	v_sub_f32_e32 v2, v31, v39
	v_mul_f32_e32 v2, 0x3db504f3, v2
	v_mul_f32_e32 v2, 0x3fb8aa3b, v2
	v_exp_f32_e32 v2, v2
	v_mov_b32_e32 v39, v1
	v_add_f32_e32 v3, v2, v3
	v_cvt_pk_bf16_f32 v2, v2, s0
	ds_write_b16 v141, v2 offset:480
	v_sub_f32_e32 v2, v32, v40
	v_mul_f32_e32 v2, 0x3db504f3, v2
	v_mul_f32_e32 v2, 0x3fb8aa3b, v2
	v_exp_f32_e32 v2, v2
	s_nop 0
	v_add_f32_e32 v4, v2, v4
	v_cvt_pk_bf16_f32 v2, v2, s0
	ds_write_b16 v141, v2 offset:1008
	v_sub_f32_e32 v2, v33, v41
	v_mul_f32_e32 v2, 0x3db504f3, v2
	v_mul_f32_e32 v2, 0x3fb8aa3b, v2
	v_exp_f32_e32 v2, v2
	s_nop 0
	v_add_f32_e32 v5, v2, v5
	v_cvt_pk_bf16_f32 v2, v2, s0
	ds_write_b16 v141, v2 offset:1536
	ds_bpermute_b32 v2, v34, v6
	s_waitcnt lgkmcnt(0)
	s_barrier
	v_add_f32_e32 v2, v6, v2
	ds_bpermute_b32 v6, v35, v2
	s_waitcnt lgkmcnt(0)
	v_add_f32_e32 v2, v2, v6
	ds_bpermute_b32 v6, v36, v2
	s_waitcnt lgkmcnt(0)
	v_add_f32_e32 v2, v2, v6
	ds_bpermute_b32 v6, v37, v2
	s_waitcnt lgkmcnt(0)
	v_add_f32_e32 v2, v2, v6
	v_div_scale_f32 v6, s[8:9], v2, v2, 1.0
	v_rcp_f32_e32 v7, v6
	s_nop 0
	v_fma_f32 v8, -v6, v7, 1.0
	v_fmac_f32_e32 v7, v8, v7
	v_div_scale_f32 v8, vcc, 1.0, v2, 1.0
	v_mul_f32_e32 v9, v8, v7
	v_fma_f32 v10, -v6, v9, v8
	v_fmac_f32_e32 v9, v10, v7
	v_fma_f32 v6, -v6, v9, v8
	v_div_fmas_f32 v6, v6, v7, v9
	v_div_fixup_f32 v84, v6, v2, 1.0
	ds_bpermute_b32 v2, v34, v3
	s_waitcnt lgkmcnt(0)
	v_add_f32_e32 v2, v3, v2
	ds_bpermute_b32 v3, v35, v2
	s_waitcnt lgkmcnt(0)
	v_add_f32_e32 v2, v2, v3
	ds_bpermute_b32 v3, v36, v2
	s_waitcnt lgkmcnt(0)
	v_add_f32_e32 v2, v2, v3
	ds_bpermute_b32 v3, v37, v2
	s_waitcnt lgkmcnt(0)
	v_add_f32_e32 v2, v2, v3
	v_div_scale_f32 v3, s[8:9], v2, v2, 1.0
	v_rcp_f32_e32 v6, v3
	s_nop 0
	v_fma_f32 v7, -v3, v6, 1.0
	v_fmac_f32_e32 v6, v7, v6
	v_div_scale_f32 v7, vcc, 1.0, v2, 1.0
	v_mul_f32_e32 v8, v7, v6
	v_fma_f32 v9, -v3, v8, v7
	v_fmac_f32_e32 v8, v9, v6
	v_fma_f32 v3, -v3, v8, v7
	v_div_fmas_f32 v3, v3, v6, v8
	v_div_fixup_f32 v85, v3, v2, 1.0
	ds_bpermute_b32 v2, v34, v4
	s_waitcnt lgkmcnt(0)
	v_add_f32_e32 v2, v4, v2
	ds_bpermute_b32 v3, v35, v2
	s_waitcnt lgkmcnt(0)
	v_add_f32_e32 v2, v2, v3
	ds_bpermute_b32 v3, v36, v2
	s_waitcnt lgkmcnt(0)
	v_add_f32_e32 v2, v2, v3
	ds_bpermute_b32 v3, v37, v2
	s_waitcnt lgkmcnt(0)
	v_add_f32_e32 v2, v2, v3
	v_div_scale_f32 v3, s[8:9], v2, v2, 1.0
	v_rcp_f32_e32 v4, v3
	s_nop 0
	v_fma_f32 v6, -v3, v4, 1.0
	v_fmac_f32_e32 v4, v6, v4
	v_div_scale_f32 v6, vcc, 1.0, v2, 1.0
	v_mul_f32_e32 v7, v6, v4
	v_fma_f32 v8, -v3, v7, v6
	v_fmac_f32_e32 v7, v8, v4
	v_fma_f32 v3, -v3, v7, v6
	v_div_fmas_f32 v3, v3, v4, v7
	v_div_fixup_f32 v86, v3, v2, 1.0
	ds_bpermute_b32 v2, v34, v5
	s_waitcnt lgkmcnt(0)
	v_add_f32_e32 v2, v5, v2
	ds_bpermute_b32 v3, v35, v2
	v_lshl_add_u64 v[34:35], v[144:145], 0, s[52:53]
	v_mad_u64_u32 v[66:67], s[8:9], v76, s51, v[34:35]
	v_mad_i32_i24 v67, v153, s51, v67
	s_waitcnt lgkmcnt(0)
	v_add_f32_e32 v2, v2, v3
	ds_bpermute_b32 v3, v36, v2
	s_waitcnt lgkmcnt(0)
	v_add_f32_e32 v2, v2, v3
	ds_bpermute_b32 v3, v37, v2
	v_lshl_add_u64 v[36:37], v[154:155], 1, v[142:143]
	v_lshl_add_u64 v[70:71], v[36:37], 0, v[38:39]
	v_or_b32_e32 v36, v152, v146
	v_mad_u64_u32 v[68:69], s[8:9], v36, s51, v[34:35]
	s_waitcnt lgkmcnt(0)
; __device__ __forceinline__ float bf2f(u16 h) { return __uint_as_float(((unsigned)h) << 16); }
; __device__ __forceinline__ u16 f2bf(float f) { return (u16)(pack2(f, 0.f) & 0xffffu); }
; __device__ __forceinline__ float siluf(float x) { return x * __builtin_amdgcn_rcpf(1.f + __expf(-x)); }
;     ...
;     bf16x8 aP[8];
; #pragma unroll
;     for (int ks = 0; ks < 8; ++ks) aP[ks] = *(const bf16x8*)(Pw + fr * 264 + ks * 32 + fq * 8);
; #pragma unroll
;     for (int db = 0; db < 4; ++db) {
;       bf16x8 bv[2][8];
;       u16 gt[2][4];
; #pragma unroll
;       for (int d2 = 0; d2 < 2; ++d2) {
; #pragma unroll
;         for (int ks = 0; ks < 8; ++ks)
;           bv[d2][ks] = *(const bf16x8*)(VT + (long)(h * 128 + (db * 2 + d2) * 16 + fr) * 512 + b * 256 + ks * 32 + fq * 8);
; #pragma unroll
;         for (int r = 0; r < 4; ++r) gt[d2][r] = qg[(t0 + fq * 4 + r) * ldq + gcol + h * 128 + (db * 2 + d2) * 16 + fr];
;       }
;       asm volatile("" ::: "memory");
; #pragma unroll
;       for (int d2 = 0; d2 < 2; ++d2) {
;         f32x4 a = {0.f, 0.f, 0.f, 0.f};
; #pragma unroll
;         for (int ks = 0; ks < 8; ++ks) a = __builtin_amdgcn_mfma_f32_16x16x32_bf16(aP[ks], bv[d2][ks], a, 0, 0, 0);
; #pragma unroll
;         for (int r = 0; r < 4; ++r) {
;           long row = t0 + fq * 4 + r;
;           int dcol = h * 128 + (db * 2 + d2) * 16 + fr;
;           og[row * ldo + ocol + dcol] = f2bf(a[r] * sm[r] * siluf(bf2f(gt[d2][r])));
;         }
;       }
	v_add_f32_e32 v2, v2, v3
	v_div_scale_f32 v3, s[8:9], v2, v2, 1.0
	v_rcp_f32_e32 v4, v3
	v_or_b32_e32 v36, v152, v148
	v_mad_u64_u32 v[72:73], s[8:9], v36, s51, v[34:35]
	v_fma_f32 v5, -v3, v4, 1.0
	v_fmac_f32_e32 v4, v5, v4
	v_div_scale_f32 v5, vcc, 1.0, v2, 1.0
	v_mul_f32_e32 v6, v5, v4
	v_fma_f32 v7, -v3, v6, v5
	v_fmac_f32_e32 v6, v7, v4
	v_fma_f32 v3, -v3, v6, v5
	v_div_fmas_f32 v3, v3, v4, v6
	v_div_fixup_f32 v87, v3, v2, 1.0
	ds_read_b128 v[2:5], v147
	ds_read_b128 v[6:9], v147 offset:64
	ds_read_b128 v[10:13], v147 offset:128
	ds_read_b128 v[14:17], v147 offset:192
	ds_read_b128 v[18:21], v147 offset:256
	ds_read_b128 v[22:25], v147 offset:320
	ds_read_b128 v[26:29], v147 offset:384
	ds_read_b128 v[30:33], v147 offset:448
	global_load_dwordx4 v[78:81], v[70:71], off
	global_load_dwordx4 v[88:91], v[70:71], off offset:64
	global_load_dwordx4 v[92:95], v[70:71], off offset:128
	global_load_dwordx4 v[96:99], v[70:71], off offset:192
	global_load_dwordx4 v[100:103], v[70:71], off offset:256
	global_load_dwordx4 v[104:107], v[70:71], off offset:320
	global_load_dwordx4 v[108:111], v[70:71], off offset:384
	global_load_dwordx4 v[112:115], v[70:71], off offset:448
	v_or_b32_e32 v36, v152, v150
	v_add_co_u32_e32 v62, vcc, s62, v70
	v_mad_u64_u32 v[74:75], s[8:9], v36, s51, v[34:35]
	s_nop 0
	v_addc_co_u32_e32 v63, vcc, 0, v71, vcc
	v_mad_i32_i24 v69, v153, s51, v69
	v_mad_i32_i24 v73, v153, s51, v73
	v_mad_i32_i24 v75, v153, s51, v75
	global_load_dwordx4 v[34:37], v[62:63], off
	global_load_dwordx4 v[38:41], v[62:63], off offset:64
	global_load_dwordx4 v[42:45], v[62:63], off offset:128
	global_load_dwordx4 v[46:49], v[62:63], off offset:192
	global_load_dwordx4 v[50:53], v[62:63], off offset:256
	global_load_dwordx4 v[54:57], v[62:63], off offset:320
	global_load_dwordx4 v[58:61], v[62:63], off offset:384
	s_nop 0
	global_load_dwordx4 v[62:65], v[62:63], off offset:448
	s_nop 0
	global_load_ushort v77, v[66:67], off
	global_load_ushort v116, v[68:69], off
	global_load_ushort v117, v[72:73], off
	global_load_ushort v118, v[74:75], off
	global_load_ushort v119, v[66:67], off offset:32
	global_load_ushort v120, v[68:69], off offset:32
	global_load_ushort v121, v[72:73], off offset:32
	global_load_ushort v122, v[74:75], off offset:32
	s_waitcnt vmcnt(0) lgkmcnt(0)
	v_mfma_f32_16x16x32_bf16 v[78:81], v[2:5], v[78:81], 0
	v_lshlrev_b32_e32 v77, 16, v77
	v_mfma_f32_16x16x32_bf16 v[78:81], v[6:9], v[88:91], v[78:81]
	v_mul_f32_e32 v88, 0xbfb8aa3b, v77
	v_exp_f32_e32 v88, v88
	v_mfma_f32_16x16x32_bf16 v[34:37], v[2:5], v[34:37], 0
	v_add_f32_e32 v88, 1.0, v88
	v_rcp_f32_e32 v88, v88
	v_mfma_f32_16x16x32_bf16 v[78:81], v[10:13], v[92:95], v[78:81]
	v_mul_f32_e32 v77, v88, v77
	v_mfma_f32_16x16x32_bf16 v[34:37], v[6:9], v[38:41], v[34:37]
	v_lshlrev_b32_e32 v38, 16, v119
	v_mul_f32_e32 v39, 0xbfb8aa3b, v38
	v_exp_f32_e32 v39, v39
	v_mfma_f32_16x16x32_bf16 v[78:81], v[14:17], v[96:99], v[78:81]
	v_add_f32_e32 v39, 1.0, v39
	v_mfma_f32_16x16x32_bf16 v[34:37], v[10:13], v[42:45], v[34:37]
	v_rcp_f32_e32 v39, v39
	s_nop 0
	v_mul_f32_e32 v38, v39, v38
	v_mfma_f32_16x16x32_bf16 v[78:81], v[18:21], v[100:103], v[78:81]
	v_mfma_f32_16x16x32_bf16 v[34:37], v[14:17], v[46:49], v[34:37]
	v_mfma_f32_16x16x32_bf16 v[78:81], v[22:25], v[104:107], v[78:81]
	v_mfma_f32_16x16x32_bf16 v[34:37], v[18:21], v[50:53], v[34:37]
	v_mfma_f32_16x16x32_bf16 v[78:81], v[26:29], v[108:111], v[78:81]
	v_mfma_f32_16x16x32_bf16 v[34:37], v[22:25], v[54:57], v[34:37]
	v_mfma_f32_16x16x32_bf16 v[80:83], v[30:33], v[112:115], v[78:81]
	v_mfma_f32_16x16x32_bf16 v[34:37], v[26:29], v[58:61], v[34:37]
	s_nop 4
	v_lshl_or_b32 v78, v130, 1, s52
	v_mov_b32_e32 v79, v1
	v_mul_f32_e32 v80, v84, v80
	v_lshl_add_u64 v[78:79], s[4:5], 0, v[78:79]
	v_mul_f32_e32 v77, v77, v80
	v_cvt_pk_bf16_f32 v80, v77, s0
	v_mad_u64_u32 v[76:77], s[8:9], v76, s17, v[78:79]
	v_mfma_f32_16x16x32_bf16 v[34:37], v[30:33], v[62:65], v[34:37]
	v_mad_i32_i24 v77, v153, s17, v77
	v_lshlrev_b32_e32 v79, 16, v116
	global_store_short v[76:77], v80, off
	v_mul_f32_e32 v80, 0xbfb8aa3b, v79
	v_exp_f32_e32 v80, v80
	s_nop 2
	v_mul_f32_e32 v34, v84, v34
	v_mul_f32_e32 v34, v38, v34
	v_cvt_pk_bf16_f32 v34, v34, s0
	v_add_f32_e32 v80, 1.0, v80
	global_store_short v[76:77], v34, off offset:32
	v_mul_f32_e32 v34, v85, v35
	v_lshlrev_b32_e32 v35, 16, v120
	v_rcp_f32_e32 v80, v80
	v_mul_f32_e32 v38, 0xbfb8aa3b, v35
	v_exp_f32_e32 v38, v38
	v_mul_f32_e32 v78, v85, v81
	v_mul_f32_e32 v79, v80, v79
	v_mul_f32_e32 v78, v79, v78
	v_add_f32_e32 v38, 1.0, v38
	v_cvt_pk_bf16_f32 v80, v78, s0
	v_add_co_u32_e32 v78, vcc, s15, v76
	v_rcp_f32_e32 v38, v38
	s_nop 0
	v_addc_co_u32_e32 v79, vcc, 0, v77, vcc
	v_lshlrev_b32_e32 v81, 16, v117
	global_store_short v[78:79], v80, off offset:1024
	v_mul_f32_e32 v80, v86, v82
	v_mul_f32_e32 v82, 0xbfb8aa3b, v81
	v_exp_f32_e32 v82, v82
	v_mul_f32_e32 v35, v38, v35
	v_mul_f32_e32 v34, v35, v34
	v_cvt_pk_bf16_f32 v34, v34, s0
	v_lshlrev_b32_e32 v35, 16, v121
	v_add_f32_e32 v82, 1.0, v82
	global_store_short v[78:79], v34, off offset:1056
	v_mul_f32_e32 v34, v86, v36
	v_mul_f32_e32 v36, 0xbfb8aa3b, v35
	v_rcp_f32_e32 v82, v82
	v_exp_f32_e32 v36, v36
	v_mul_f32_e32 v81, v82, v81
	v_add_f32_e32 v36, 1.0, v36
	v_mul_f32_e32 v80, v81, v80
	v_rcp_f32_e32 v36, v36
	v_cvt_pk_bf16_f32 v82, v80, s0
	v_add_co_u32_e32 v80, vcc, s62, v76
	v_mul_f32_e32 v35, v36, v35
	s_nop 0
	v_addc_co_u32_e32 v81, vcc, 0, v77, vcc
	global_store_short v[80:81], v82, off offset:2048
	v_mul_f32_e32 v82, v87, v83
	v_lshlrev_b32_e32 v83, 16, v118
	v_mul_f32_e32 v88, 0xbfb8aa3b, v83
	v_exp_f32_e32 v88, v88
	v_mul_f32_e32 v34, v35, v34
	v_lshlrev_b32_e32 v35, 16, v122
	v_mul_f32_e32 v36, 0xbfb8aa3b, v35
	v_exp_f32_e32 v36, v36
	v_add_f32_e32 v88, 1.0, v88
	v_rcp_f32_e32 v88, v88
	v_cvt_pk_bf16_f32 v34, v34, s0
	v_add_f32_e32 v36, 1.0, v36
	v_rcp_f32_e32 v36, v36
	v_mul_f32_e32 v83, v88, v83
	v_mul_f32_e32 v82, v83, v82
	v_cvt_pk_bf16_f32 v88, v82, s0
	v_add_co_u32_e32 v82, vcc, s16, v76
	global_store_short v[80:81], v34, off offset:2080
	v_mul_f32_e32 v34, v87, v37
	v_mul_f32_e32 v35, v36, v35
	v_addc_co_u32_e32 v83, vcc, 0, v77, vcc
	v_mul_f32_e32 v34, v35, v34
	v_cvt_pk_bf16_f32 v34, v34, s0
	v_add_co_u32_e32 v62, vcc, s10, v70
	global_store_short v[82:83], v88, off offset:3072
	global_store_short v[82:83], v34, off offset:3104
	v_addc_co_u32_e32 v63, vcc, 0, v71, vcc
	global_load_dwordx4 v[34:37], v[62:63], off
	global_load_dwordx4 v[38:41], v[62:63], off offset:64
	global_load_dwordx4 v[42:45], v[62:63], off offset:128
	global_load_dwordx4 v[46:49], v[62:63], off offset:192
	global_load_dwordx4 v[50:53], v[62:63], off offset:256
	global_load_dwordx4 v[54:57], v[62:63], off offset:320
	global_load_dwordx4 v[58:61], v[62:63], off offset:384
	s_nop 0
	global_load_dwordx4 v[62:65], v[62:63], off offset:448
	v_add_co_u32_e32 v116, vcc, s11, v70
	s_waitcnt vmcnt(0) lgkmcnt(0)
; __device__ __forceinline__ float bf2f(u16 h) { return __uint_as_float(((unsigned)h) << 16); }
; __device__ __forceinline__ u16 f2bf(float f) { return (u16)(pack2(f, 0.f) & 0xffffu); }
; __device__ __forceinline__ float siluf(float x) { return x * __builtin_amdgcn_rcpf(1.f + __expf(-x)); }
;     ...
; #pragma unroll
;     for (int db = 0; db < 4; ++db) {
;       bf16x8 bv[2][8];
;       u16 gt[2][4];
; #pragma unroll
;       for (int d2 = 0; d2 < 2; ++d2) {
; #pragma unroll
;         for (int ks = 0; ks < 8; ++ks)
;           bv[d2][ks] = *(const bf16x8*)(VT + (long)(h * 128 + (db * 2 + d2) * 16 + fr) * 512 + b * 256 + ks * 32 + fq * 8);
; #pragma unroll
;         for (int r = 0; r < 4; ++r) gt[d2][r] = qg[(t0 + fq * 4 + r) * ldq + gcol + h * 128 + (db * 2 + d2) * 16 + fr];
;       }
;       asm volatile("" ::: "memory");
; #pragma unroll
;       for (int d2 = 0; d2 < 2; ++d2) {
;         f32x4 a = {0.f, 0.f, 0.f, 0.f};
; #pragma unroll
;         for (int ks = 0; ks < 8; ++ks) a = __builtin_amdgcn_mfma_f32_16x16x32_bf16(aP[ks], bv[d2][ks], a, 0, 0, 0);
; #pragma unroll
;         for (int r = 0; r < 4; ++r) {
;           long row = t0 + fq * 4 + r;
;           int dcol = h * 128 + (db * 2 + d2) * 16 + fr;
;           og[row * ldo + ocol + dcol] = f2bf(a[r] * sm[r] * siluf(bf2f(gt[d2][r])));
;         }
;       }
	v_mfma_f32_16x16x32_bf16 v[34:37], v[2:5], v[34:37], 0
	v_addc_co_u32_e32 v117, vcc, 0, v71, vcc
	global_load_dwordx4 v[88:91], v[116:117], off
	global_load_dwordx4 v[92:95], v[116:117], off offset:64
	global_load_dwordx4 v[96:99], v[116:117], off offset:128
	global_load_dwordx4 v[100:103], v[116:117], off offset:192
	global_load_dwordx4 v[104:107], v[116:117], off offset:256
	global_load_dwordx4 v[108:111], v[116:117], off offset:320
	global_load_dwordx4 v[112:115], v[116:117], off offset:384
	s_nop 0
	global_load_dwordx4 v[116:119], v[116:117], off offset:448
	s_nop 0
	global_load_ushort v120, v[66:67], off offset:64
	global_load_ushort v121, v[68:69], off offset:64
	global_load_ushort v122, v[72:73], off offset:64
	global_load_ushort v123, v[74:75], off offset:64
	global_load_ushort v124, v[66:67], off offset:96
	global_load_ushort v125, v[68:69], off offset:96
	global_load_ushort v126, v[72:73], off offset:96
	global_load_ushort v127, v[74:75], off offset:96
	v_mfma_f32_16x16x32_bf16 v[34:37], v[6:9], v[38:41], v[34:37]
	s_waitcnt vmcnt(0) lgkmcnt(0)
	v_lshlrev_b32_e32 v38, 16, v120
	v_mfma_f32_16x16x32_bf16 v[34:37], v[10:13], v[42:45], v[34:37]
	v_mul_f32_e32 v39, 0xbfb8aa3b, v38
	v_exp_f32_e32 v39, v39
	v_mfma_f32_16x16x32_bf16 v[34:37], v[14:17], v[46:49], v[34:37]
	v_add_f32_e32 v39, 1.0, v39
	v_rcp_f32_e32 v39, v39
	v_mfma_f32_16x16x32_bf16 v[34:37], v[18:21], v[50:53], v[34:37]
	v_mul_f32_e32 v38, v39, v38
	v_mfma_f32_16x16x32_bf16 v[34:37], v[22:25], v[54:57], v[34:37]
	v_mfma_f32_16x16x32_bf16 v[34:37], v[26:29], v[58:61], v[34:37]
	v_mfma_f32_16x16x32_bf16 v[34:37], v[30:33], v[62:65], v[34:37]
	v_add_co_u32_e32 v62, vcc, s12, v70
	s_nop 1
	v_addc_co_u32_e32 v63, vcc, 0, v71, vcc
	s_nop 3
	v_mul_f32_e32 v34, v84, v34
	v_mul_f32_e32 v34, v38, v34
	v_cvt_pk_bf16_f32 v34, v34, s0
	global_store_short v[76:77], v34, off offset:64
	v_mul_f32_e32 v34, v85, v35
	v_lshlrev_b32_e32 v35, 16, v121
	v_mul_f32_e32 v38, 0xbfb8aa3b, v35
	v_exp_f32_e32 v38, v38
	s_nop 0
	v_add_f32_e32 v38, 1.0, v38
	v_rcp_f32_e32 v38, v38
	s_nop 0
	v_mul_f32_e32 v35, v38, v35
	v_mul_f32_e32 v34, v35, v34
	v_cvt_pk_bf16_f32 v34, v34, s0
	v_lshlrev_b32_e32 v35, 16, v122
	global_store_short v[78:79], v34, off offset:1088
	v_mul_f32_e32 v34, v86, v36
	v_mul_f32_e32 v36, 0xbfb8aa3b, v35
	v_exp_f32_e32 v36, v36
	v_lshlrev_b32_e32 v38, 16, v124
	v_mul_f32_e32 v39, 0xbfb8aa3b, v38
	v_exp_f32_e32 v39, v39
	v_add_f32_e32 v36, 1.0, v36
	v_rcp_f32_e32 v36, v36
	v_add_f32_e32 v39, 1.0, v39
	v_rcp_f32_e32 v39, v39
	v_mul_f32_e32 v35, v36, v35
	v_mul_f32_e32 v34, v35, v34
	v_lshlrev_b32_e32 v35, 16, v123
	v_mul_f32_e32 v36, 0xbfb8aa3b, v35
	v_exp_f32_e32 v36, v36
	v_cvt_pk_bf16_f32 v34, v34, s0
	global_store_short v[80:81], v34, off offset:2112
	v_mul_f32_e32 v34, v87, v37
	v_add_f32_e32 v36, 1.0, v36
	v_rcp_f32_e32 v36, v36
	v_mul_f32_e32 v38, v39, v38
	v_mul_f32_e32 v35, v36, v35
	v_mul_f32_e32 v34, v35, v34
	v_cvt_pk_bf16_f32 v34, v34, s0
	global_store_short v[82:83], v34, off offset:3136
	v_mfma_f32_16x16x32_bf16 v[34:37], v[2:5], v[88:91], 0
	v_mfma_f32_16x16x32_bf16 v[34:37], v[6:9], v[92:95], v[34:37]
	v_mfma_f32_16x16x32_bf16 v[34:37], v[10:13], v[96:99], v[34:37]
	v_mfma_f32_16x16x32_bf16 v[34:37], v[14:17], v[100:103], v[34:37]
	v_mfma_f32_16x16x32_bf16 v[34:37], v[18:21], v[104:107], v[34:37]
	v_mfma_f32_16x16x32_bf16 v[34:37], v[22:25], v[108:111], v[34:37]
	v_mfma_f32_16x16x32_bf16 v[34:37], v[26:29], v[112:115], v[34:37]
	v_mfma_f32_16x16x32_bf16 v[34:37], v[30:33], v[116:119], v[34:37]
	v_add_co_u32_e32 v116, vcc, s13, v70
	s_nop 1
	v_addc_co_u32_e32 v117, vcc, 0, v71, vcc
	s_nop 3
	v_mul_f32_e32 v34, v84, v34
	v_mul_f32_e32 v34, v38, v34
	v_cvt_pk_bf16_f32 v34, v34, s0
	global_store_short v[76:77], v34, off offset:96
	v_mul_f32_e32 v34, v85, v35
	v_lshlrev_b32_e32 v35, 16, v125
	v_mul_f32_e32 v38, 0xbfb8aa3b, v35
	v_exp_f32_e32 v38, v38
	s_nop 0
	v_add_f32_e32 v38, 1.0, v38
	v_rcp_f32_e32 v38, v38
	s_nop 0
	v_mul_f32_e32 v35, v38, v35
	v_mul_f32_e32 v34, v35, v34
	v_cvt_pk_bf16_f32 v34, v34, s0
	v_lshlrev_b32_e32 v35, 16, v126
	global_store_short v[78:79], v34, off offset:1120
	v_mul_f32_e32 v34, v86, v36
	v_mul_f32_e32 v36, 0xbfb8aa3b, v35
	v_exp_f32_e32 v36, v36
	s_nop 0
	v_add_f32_e32 v36, 1.0, v36
	v_rcp_f32_e32 v36, v36
	s_nop 0
	v_mul_f32_e32 v35, v36, v35
	v_mul_f32_e32 v34, v35, v34
	v_lshlrev_b32_e32 v35, 16, v127
	v_mul_f32_e32 v36, 0xbfb8aa3b, v35
	v_exp_f32_e32 v36, v36
	v_cvt_pk_bf16_f32 v34, v34, s0
	global_store_short v[80:81], v34, off offset:2144
	v_mul_f32_e32 v34, v87, v37
	v_add_f32_e32 v36, 1.0, v36
	v_rcp_f32_e32 v36, v36
	s_nop 0
	v_mul_f32_e32 v35, v36, v35
	v_mul_f32_e32 v34, v35, v34
	v_cvt_pk_bf16_f32 v34, v34, s0
	global_store_short v[82:83], v34, off offset:3168
	global_load_dwordx4 v[34:37], v[62:63], off
	s_nop 0
	global_load_dwordx4 v[38:41], v[62:63], off offset:64
	global_load_dwordx4 v[42:45], v[62:63], off offset:128
	global_load_dwordx4 v[46:49], v[62:63], off offset:192
	global_load_dwordx4 v[50:53], v[62:63], off offset:256
	global_load_dwordx4 v[54:57], v[62:63], off offset:320
	global_load_dwordx4 v[58:61], v[62:63], off offset:384
	s_nop 0
	global_load_dwordx4 v[62:65], v[62:63], off offset:448
	s_nop 0
	global_load_dwordx4 v[88:91], v[116:117], off
	global_load_dwordx4 v[92:95], v[116:117], off offset:64
	global_load_dwordx4 v[96:99], v[116:117], off offset:128
	global_load_dwordx4 v[100:103], v[116:117], off offset:192
	global_load_dwordx4 v[104:107], v[116:117], off offset:256
	global_load_dwordx4 v[108:111], v[116:117], off offset:320
	global_load_dwordx4 v[112:115], v[116:117], off offset:384
	s_nop 0
	global_load_dwordx4 v[116:119], v[116:117], off offset:448
	s_nop 0
	global_load_ushort v120, v[66:67], off offset:128
	global_load_ushort v121, v[68:69], off offset:128
	global_load_ushort v122, v[72:73], off offset:128
	global_load_ushort v123, v[74:75], off offset:128
	global_load_ushort v124, v[66:67], off offset:160
	global_load_ushort v125, v[68:69], off offset:160
	global_load_ushort v126, v[72:73], off offset:160
	global_load_ushort v127, v[74:75], off offset:160
	s_waitcnt vmcnt(0) lgkmcnt(0)
; __device__ __forceinline__ float bf2f(u16 h) { return __uint_as_float(((unsigned)h) << 16); }
; __device__ __forceinline__ u16 f2bf(float f) { return (u16)(pack2(f, 0.f) & 0xffffu); }
; __device__ __forceinline__ float siluf(float x) { return x * __builtin_amdgcn_rcpf(1.f + __expf(-x)); }
;     ...
; #pragma unroll
;     for (int db = 0; db < 4; ++db) {
;       bf16x8 bv[2][8];
;       u16 gt[2][4];
; #pragma unroll
;       for (int d2 = 0; d2 < 2; ++d2) {
; #pragma unroll
;         for (int ks = 0; ks < 8; ++ks)
;           bv[d2][ks] = *(const bf16x8*)(VT + (long)(h * 128 + (db * 2 + d2) * 16 + fr) * 512 + b * 256 + ks * 32 + fq * 8);
; #pragma unroll
;         for (int r = 0; r < 4; ++r) gt[d2][r] = qg[(t0 + fq * 4 + r) * ldq + gcol + h * 128 + (db * 2 + d2) * 16 + fr];
;       }
;       asm volatile("" ::: "memory");
; #pragma unroll
;       for (int d2 = 0; d2 < 2; ++d2) {
;         f32x4 a = {0.f, 0.f, 0.f, 0.f};
; #pragma unroll
;         for (int ks = 0; ks < 8; ++ks) a = __builtin_amdgcn_mfma_f32_16x16x32_bf16(aP[ks], bv[d2][ks], a, 0, 0, 0);
; #pragma unroll
;         for (int r = 0; r < 4; ++r) {
;           long row = t0 + fq * 4 + r;
;           int dcol = h * 128 + (db * 2 + d2) * 16 + fr;
;           og[row * ldo + ocol + dcol] = f2bf(a[r] * sm[r] * siluf(bf2f(gt[d2][r])));
;         }
;       }
	v_mfma_f32_16x16x32_bf16 v[34:37], v[2:5], v[34:37], 0
	v_mfma_f32_16x16x32_bf16 v[34:37], v[6:9], v[38:41], v[34:37]
	v_lshlrev_b32_e32 v38, 16, v120
	v_mul_f32_e32 v39, 0xbfb8aa3b, v38
	v_exp_f32_e32 v39, v39
	v_mfma_f32_16x16x32_bf16 v[34:37], v[10:13], v[42:45], v[34:37]
	v_add_f32_e32 v39, 1.0, v39
	v_mfma_f32_16x16x32_bf16 v[34:37], v[14:17], v[46:49], v[34:37]
	v_rcp_f32_e32 v39, v39
	s_nop 0
	v_mul_f32_e32 v38, v39, v38
	v_mfma_f32_16x16x32_bf16 v[34:37], v[18:21], v[50:53], v[34:37]
	v_mfma_f32_16x16x32_bf16 v[34:37], v[22:25], v[54:57], v[34:37]
	v_mfma_f32_16x16x32_bf16 v[34:37], v[26:29], v[58:61], v[34:37]
	v_mfma_f32_16x16x32_bf16 v[34:37], v[30:33], v[62:65], v[34:37]
	v_add_co_u32_e32 v62, vcc, s87, v70
	s_nop 1
	v_addc_co_u32_e32 v63, vcc, 0, v71, vcc
	v_add_co_u32_e32 v70, vcc, s14, v70
	s_nop 2
	v_mul_f32_e32 v34, v84, v34
	v_mul_f32_e32 v34, v38, v34
	v_cvt_pk_bf16_f32 v34, v34, s0
	global_store_short v[76:77], v34, off offset:128
	v_mul_f32_e32 v34, v85, v35
	v_lshlrev_b32_e32 v35, 16, v121
	v_mul_f32_e32 v38, 0xbfb8aa3b, v35
	v_exp_f32_e32 v38, v38
	v_addc_co_u32_e32 v71, vcc, 0, v71, vcc
	v_add_f32_e32 v38, 1.0, v38
	v_rcp_f32_e32 v38, v38
	s_nop 0
	v_mul_f32_e32 v35, v38, v35
	v_mul_f32_e32 v34, v35, v34
	v_cvt_pk_bf16_f32 v34, v34, s0
	v_lshlrev_b32_e32 v35, 16, v122
	global_store_short v[78:79], v34, off offset:1152
	v_mul_f32_e32 v34, v86, v36
	v_mul_f32_e32 v36, 0xbfb8aa3b, v35
	v_exp_f32_e32 v36, v36
	v_lshlrev_b32_e32 v38, 16, v124
	v_mul_f32_e32 v39, 0xbfb8aa3b, v38
	v_exp_f32_e32 v39, v39
	v_add_f32_e32 v36, 1.0, v36
	v_rcp_f32_e32 v36, v36
	v_add_f32_e32 v39, 1.0, v39
	v_rcp_f32_e32 v39, v39
	v_mul_f32_e32 v35, v36, v35
	v_mul_f32_e32 v34, v35, v34
	v_lshlrev_b32_e32 v35, 16, v123
	v_mul_f32_e32 v36, 0xbfb8aa3b, v35
	v_exp_f32_e32 v36, v36
	v_cvt_pk_bf16_f32 v34, v34, s0
	global_store_short v[80:81], v34, off offset:2176
	v_mul_f32_e32 v34, v87, v37
	v_add_f32_e32 v36, 1.0, v36
	v_rcp_f32_e32 v36, v36
	v_mul_f32_e32 v38, v39, v38
	v_mul_f32_e32 v35, v36, v35
	v_mul_f32_e32 v34, v35, v34
	v_cvt_pk_bf16_f32 v34, v34, s0
	global_store_short v[82:83], v34, off offset:3200
	v_mfma_f32_16x16x32_bf16 v[34:37], v[2:5], v[88:91], 0
	v_mfma_f32_16x16x32_bf16 v[34:37], v[6:9], v[92:95], v[34:37]
	v_mfma_f32_16x16x32_bf16 v[34:37], v[10:13], v[96:99], v[34:37]
	v_mfma_f32_16x16x32_bf16 v[34:37], v[14:17], v[100:103], v[34:37]
	v_mfma_f32_16x16x32_bf16 v[34:37], v[18:21], v[104:107], v[34:37]
	v_mfma_f32_16x16x32_bf16 v[34:37], v[22:25], v[108:111], v[34:37]
	v_mfma_f32_16x16x32_bf16 v[34:37], v[26:29], v[112:115], v[34:37]
	v_mfma_f32_16x16x32_bf16 v[34:37], v[30:33], v[116:119], v[34:37]
	s_nop 7
	v_mul_f32_e32 v34, v84, v34
	v_mul_f32_e32 v34, v38, v34
	v_cvt_pk_bf16_f32 v34, v34, s0
	global_store_short v[76:77], v34, off offset:160
	v_mul_f32_e32 v34, v85, v35
	v_lshlrev_b32_e32 v35, 16, v125
	v_mul_f32_e32 v38, 0xbfb8aa3b, v35
	v_exp_f32_e32 v38, v38
	s_nop 0
	v_add_f32_e32 v38, 1.0, v38
	v_rcp_f32_e32 v38, v38
	s_nop 0
	v_mul_f32_e32 v35, v38, v35
	v_mul_f32_e32 v34, v35, v34
	v_cvt_pk_bf16_f32 v34, v34, s0
	v_lshlrev_b32_e32 v35, 16, v126
	global_store_short v[78:79], v34, off offset:1184
	v_mul_f32_e32 v34, v86, v36
	v_mul_f32_e32 v36, 0xbfb8aa3b, v35
	v_exp_f32_e32 v36, v36
	s_nop 0
	v_add_f32_e32 v36, 1.0, v36
	v_rcp_f32_e32 v36, v36
	s_nop 0
	v_mul_f32_e32 v35, v36, v35
	v_mul_f32_e32 v34, v35, v34
	v_lshlrev_b32_e32 v35, 16, v127
	v_mul_f32_e32 v36, 0xbfb8aa3b, v35
	v_exp_f32_e32 v36, v36
	v_cvt_pk_bf16_f32 v34, v34, s0
	global_store_short v[80:81], v34, off offset:2208
	v_mul_f32_e32 v34, v87, v37
	v_add_f32_e32 v36, 1.0, v36
	v_rcp_f32_e32 v36, v36
	s_nop 0
	v_mul_f32_e32 v35, v36, v35
	v_mul_f32_e32 v34, v35, v34
	v_cvt_pk_bf16_f32 v34, v34, s0
	global_store_short v[82:83], v34, off offset:3232
	global_load_dwordx4 v[34:37], v[62:63], off
	s_nop 0
	global_load_dwordx4 v[38:41], v[62:63], off offset:64
	global_load_dwordx4 v[42:45], v[62:63], off offset:128
	global_load_dwordx4 v[46:49], v[62:63], off offset:192
	global_load_dwordx4 v[50:53], v[62:63], off offset:256
	global_load_dwordx4 v[54:57], v[62:63], off offset:320
	global_load_dwordx4 v[58:61], v[62:63], off offset:384
	s_nop 0
	global_load_dwordx4 v[62:65], v[62:63], off offset:448
	s_nop 0
	global_load_dwordx4 v[88:91], v[70:71], off
	global_load_dwordx4 v[92:95], v[70:71], off offset:64
	global_load_dwordx4 v[96:99], v[70:71], off offset:128
	global_load_dwordx4 v[100:103], v[70:71], off offset:192
	global_load_dwordx4 v[104:107], v[70:71], off offset:256
	global_load_dwordx4 v[108:111], v[70:71], off offset:320
	global_load_dwordx4 v[112:115], v[70:71], off offset:384
	global_load_dwordx4 v[116:119], v[70:71], off offset:448
	s_nop 0
	global_load_ushort v70, v[66:67], off offset:192
	global_load_ushort v71, v[68:69], off offset:192
	global_load_ushort v120, v[72:73], off offset:192
	global_load_ushort v121, v[74:75], off offset:192
	s_nop 0
	global_load_ushort v66, v[66:67], off offset:224
	s_nop 0
	global_load_ushort v67, v[68:69], off offset:224
	s_nop 0
	global_load_ushort v68, v[72:73], off offset:224
	global_load_ushort v69, v[74:75], off offset:224
	s_waitcnt vmcnt(0) lgkmcnt(0)
; __device__ __forceinline__ float bf2f(u16 h) { return __uint_as_float(((unsigned)h) << 16); }
; __device__ __forceinline__ u16 f2bf(float f) { return (u16)(pack2(f, 0.f) & 0xffffu); }
; __device__ __forceinline__ float siluf(float x) { return x * __builtin_amdgcn_rcpf(1.f + __expf(-x)); }
;     ...
; #pragma unroll
;     for (int db = 0; db < 4; ++db) {
;       bf16x8 bv[2][8];
;       u16 gt[2][4];
; #pragma unroll
;       for (int d2 = 0; d2 < 2; ++d2) {
; #pragma unroll
;         for (int ks = 0; ks < 8; ++ks)
;           bv[d2][ks] = *(const bf16x8*)(VT + (long)(h * 128 + (db * 2 + d2) * 16 + fr) * 512 + b * 256 + ks * 32 + fq * 8);
; #pragma unroll
;         for (int r = 0; r < 4; ++r) gt[d2][r] = qg[(t0 + fq * 4 + r) * ldq + gcol + h * 128 + (db * 2 + d2) * 16 + fr];
;       }
;       asm volatile("" ::: "memory");
; #pragma unroll
;       for (int d2 = 0; d2 < 2; ++d2) {
;         f32x4 a = {0.f, 0.f, 0.f, 0.f};
; #pragma unroll
;         for (int ks = 0; ks < 8; ++ks) a = __builtin_amdgcn_mfma_f32_16x16x32_bf16(aP[ks], bv[d2][ks], a, 0, 0, 0);
; #pragma unroll
;         for (int r = 0; r < 4; ++r) {
;           long row = t0 + fq * 4 + r;
;           int dcol = h * 128 + (db * 2 + d2) * 16 + fr;
;           og[row * ldo + ocol + dcol] = f2bf(a[r] * sm[r] * siluf(bf2f(gt[d2][r])));
;         }
;       }
;     }
	v_mfma_f32_16x16x32_bf16 v[34:37], v[2:5], v[34:37], 0
	v_mfma_f32_16x16x32_bf16 v[2:5], v[2:5], v[88:91], 0
	v_mfma_f32_16x16x32_bf16 v[34:37], v[6:9], v[38:41], v[34:37]
	v_lshlrev_b32_e32 v38, 16, v70
	v_mul_f32_e32 v39, 0xbfb8aa3b, v38
	v_exp_f32_e32 v39, v39
	v_mfma_f32_16x16x32_bf16 v[2:5], v[6:9], v[92:95], v[2:5]
	v_lshlrev_b32_e32 v6, 16, v66
	v_mul_f32_e32 v7, 0xbfb8aa3b, v6
	v_exp_f32_e32 v7, v7
	v_mfma_f32_16x16x32_bf16 v[34:37], v[10:13], v[42:45], v[34:37]
	v_add_f32_e32 v39, 1.0, v39
	v_rcp_f32_e32 v39, v39
	v_add_f32_e32 v7, 1.0, v7
	v_mfma_f32_16x16x32_bf16 v[2:5], v[10:13], v[96:99], v[2:5]
	v_rcp_f32_e32 v7, v7
	v_mul_f32_e32 v38, v39, v38
	v_mul_f32_e32 v6, v7, v6
	v_mfma_f32_16x16x32_bf16 v[34:37], v[14:17], v[46:49], v[34:37]
	v_mfma_f32_16x16x32_bf16 v[2:5], v[14:17], v[100:103], v[2:5]
	v_mfma_f32_16x16x32_bf16 v[34:37], v[18:21], v[50:53], v[34:37]
	v_mfma_f32_16x16x32_bf16 v[2:5], v[18:21], v[104:107], v[2:5]
	v_mfma_f32_16x16x32_bf16 v[34:37], v[22:25], v[54:57], v[34:37]
	v_mfma_f32_16x16x32_bf16 v[2:5], v[22:25], v[108:111], v[2:5]
	v_mfma_f32_16x16x32_bf16 v[34:37], v[26:29], v[58:61], v[34:37]
	v_mfma_f32_16x16x32_bf16 v[2:5], v[26:29], v[112:115], v[2:5]
	v_mfma_f32_16x16x32_bf16 v[34:37], v[30:33], v[62:65], v[34:37]
	v_mfma_f32_16x16x32_bf16 v[2:5], v[30:33], v[116:119], v[2:5]
	s_nop 6
	v_mul_f32_e32 v34, v84, v34
	v_mul_f32_e32 v2, v84, v2
	v_mul_f32_e32 v34, v38, v34
	v_mul_f32_e32 v2, v6, v2
	v_cvt_pk_bf16_f32 v34, v34, s0
	v_cvt_pk_bf16_f32 v2, v2, s0
	global_store_short v[76:77], v34, off offset:192
	v_mul_f32_e32 v34, v85, v35
	v_lshlrev_b32_e32 v35, 16, v71
	global_store_short v[76:77], v2, off offset:224
	v_mul_f32_e32 v2, v85, v3
	v_lshlrev_b32_e32 v3, 16, v67
	v_mul_f32_e32 v38, 0xbfb8aa3b, v35
	v_mul_f32_e32 v6, 0xbfb8aa3b, v3
	v_exp_f32_e32 v38, v38
	v_exp_f32_e32 v6, v6
	v_add_f32_e32 v38, 1.0, v38
	v_add_f32_e32 v6, 1.0, v6
	v_rcp_f32_e32 v38, v38
	v_rcp_f32_e32 v6, v6
	v_mul_f32_e32 v35, v38, v35
	v_mul_f32_e32 v3, v6, v3
	v_mul_f32_e32 v34, v35, v34
	v_mul_f32_e32 v2, v3, v2
	v_cvt_pk_bf16_f32 v34, v34, s0
	v_lshlrev_b32_e32 v35, 16, v120
	v_cvt_pk_bf16_f32 v2, v2, s0
	v_lshlrev_b32_e32 v3, 16, v68
	global_store_short v[78:79], v34, off offset:1216
	v_mul_f32_e32 v34, v86, v36
	v_mul_f32_e32 v36, 0xbfb8aa3b, v35
	global_store_short v[78:79], v2, off offset:1248
	v_mul_f32_e32 v2, v86, v4
	v_mul_f32_e32 v4, 0xbfb8aa3b, v3
	v_exp_f32_e32 v36, v36
	v_exp_f32_e32 v4, v4
	v_add_f32_e32 v36, 1.0, v36
	v_add_f32_e32 v4, 1.0, v4
	v_rcp_f32_e32 v36, v36
	v_rcp_f32_e32 v4, v4
	v_mul_f32_e32 v35, v36, v35
	v_mul_f32_e32 v3, v4, v3
	v_mul_f32_e32 v34, v35, v34
	v_lshlrev_b32_e32 v35, 16, v121
	v_mul_f32_e32 v2, v3, v2
	v_lshlrev_b32_e32 v3, 16, v69
	v_mul_f32_e32 v36, 0xbfb8aa3b, v35
	v_mul_f32_e32 v4, 0xbfb8aa3b, v3
	v_exp_f32_e32 v36, v36
	v_exp_f32_e32 v4, v4
	v_cvt_pk_bf16_f32 v34, v34, s0
	v_cvt_pk_bf16_f32 v2, v2, s0
	v_add_f32_e32 v36, 1.0, v36
	v_add_f32_e32 v4, 1.0, v4
	v_rcp_f32_e32 v36, v36
	v_rcp_f32_e32 v4, v4
	global_store_short v[80:81], v34, off offset:2240
	v_mul_f32_e32 v34, v87, v37
	v_mul_f32_e32 v35, v36, v35
	global_store_short v[80:81], v2, off offset:2272
	v_mul_f32_e32 v2, v87, v5
	v_mul_f32_e32 v3, v4, v3
	v_mul_f32_e32 v34, v35, v34
	v_mul_f32_e32 v2, v3, v2
	v_cvt_pk_bf16_f32 v34, v34, s0
	v_cvt_pk_bf16_f32 v2, v2, s0
	global_store_short v[82:83], v34, off offset:3264
	global_store_short v[82:83], v2, off offset:3296
	s_cbranch_scc0 .LBB0_266

;     ...
;   for (int item = (int)blockIdx.x - blk0; item < 128 * 4; item += nblk) {
;     const int tt = item >> 2, h = item & 3;
;     const long t0 = (long)tt * 128 + w * 16;
;     const int b = (int)(t0 >> 13);
;     bf16x8 aQ[4];
; #pragma unroll
;     for (int ks = 0; ks < 4; ++ks) aQ[ks] = *(const bf16x8*)(qg + (t0 + fr) * ldq + qcol + h * 128 + ks * 32 + fq * 8);
;     f32x4 s[16];
; #pragma unroll
;     for (int nb = 0; nb < 4; ++nb) {
;       bf16x8 bk[4][4];
; #pragma unroll
;       for (int n4 = 0; n4 < 4; ++n4)
; #pragma unroll
;         for (int ks = 0; ks < 4; ++ks)
;           bk[n4][ks] = *(const bf16x8*)(Km + (long)(b * 256 + (nb * 4 + n4) * 16 + fr) * 512 + h * 128 + ks * 32 + fq * 8);
;       asm volatile("" ::: "memory");
; #pragma unroll
;       for (int n4 = 0; n4 < 4; ++n4) {
;         f32x4 a = {0.f, 0.f, 0.f, 0.f};
; #pragma unroll
;         for (int ks = 0; ks < 4; ++ks) a = __builtin_amdgcn_mfma_f32_16x16x32_bf16(aQ[ks], bk[n4][ks], a, 0, 0, 0);
;         s[nb * 4 + n4] = a;
;       }
;     }
.LBB0_271:
	s_ashr_i32 s8, s6, 2
	s_ashr_i32 s9, s8, 31
	s_lshl_b64 s[8:9], s[8:9], 7
	v_lshl_add_u64 v[152:153], s[8:9], 0, v[132:133]
	v_or_b32_e32 v4, v152, v130
	v_mov_b64_e32 v[2:3], s[0:1]
	s_and_b32 s7, s6, 3
	v_mad_u64_u32 v[2:3], s[8:9], v4, s51, v[2:3]
	v_mad_i32_i24 v3, v153, s51, v3
	s_lshl_b32 s52, s7, 8
	v_lshl_add_u64 v[2:3], v[2:3], 0, s[52:53]
	v_lshl_add_u64 v[2:3], v[2:3], 0, v[0:1]
	global_load_dwordx4 v[30:33], v[2:3], off
	s_waitcnt vmcnt(0)
	global_load_dwordx4 v[34:37], v[2:3], off offset:64
	global_load_dwordx4 v[38:41], v[2:3], off offset:128
	global_load_dwordx4 v[42:45], v[2:3], off offset:192
	v_alignbit_b32 v2, v153, v152, 5
	v_and_b32_e32 v154, 0xffffff00, v2
	v_or_b32_e32 v116, v154, v130
	v_ashrrev_i32_e32 v117, 31, v116
	v_lshl_add_u64 v[114:115], v[134:135], 0, s[52:53]
	v_lshlrev_b64 v[2:3], 10, v[116:117]
	v_lshl_add_u64 v[14:15], v[114:115], 0, v[2:3]
	global_load_dwordx4 v[2:5], v[14:15], off
	global_load_dwordx4 v[6:9], v[14:15], off offset:64
	global_load_dwordx4 v[10:13], v[14:15], off offset:128
	s_nop 0
	global_load_dwordx4 v[14:17], v[14:15], off offset:192
	v_or_b32_e32 v18, 16, v116
	v_ashrrev_i32_e32 v19, 31, v18
	v_lshlrev_b64 v[18:19], 10, v[18:19]
	v_lshl_add_u64 v[46:47], v[114:115], 0, v[18:19]
	global_load_dwordx4 v[18:21], v[46:47], off
	global_load_dwordx4 v[22:25], v[46:47], off offset:64
	global_load_dwordx4 v[26:29], v[46:47], off offset:128
	s_nop 0
	global_load_dwordx4 v[46:49], v[46:47], off offset:192
	v_or_b32_e32 v50, 32, v116
	v_ashrrev_i32_e32 v51, 31, v50
	v_lshlrev_b64 v[50:51], 10, v[50:51]
	v_lshl_add_u64 v[62:63], v[114:115], 0, v[50:51]
	global_load_dwordx4 v[50:53], v[62:63], off
	global_load_dwordx4 v[54:57], v[62:63], off offset:64
	global_load_dwordx4 v[58:61], v[62:63], off offset:128
	s_nop 0
	global_load_dwordx4 v[62:65], v[62:63], off offset:192
	v_or_b32_e32 v66, 48, v116
	v_ashrrev_i32_e32 v67, 31, v66
	v_lshlrev_b64 v[66:67], 10, v[66:67]
	v_lshl_add_u64 v[78:79], v[114:115], 0, v[66:67]
	global_load_dwordx4 v[66:69], v[78:79], off
	global_load_dwordx4 v[70:73], v[78:79], off offset:64
	global_load_dwordx4 v[74:77], v[78:79], off offset:128
	s_nop 0
	global_load_dwordx4 v[78:81], v[78:79], off offset:192
	v_or_b32_e32 v82, 0x70, v116
	v_ashrrev_i32_e32 v83, 31, v82
	v_lshlrev_b64 v[82:83], 10, v[82:83]
	v_lshl_add_u64 v[94:95], v[114:115], 0, v[82:83]
	v_or_b32_e32 v98, 0xb0, v116
	v_ashrrev_i32_e32 v99, 31, v98
	v_lshlrev_b64 v[98:99], 10, v[98:99]
	v_lshl_add_u64 v[110:111], v[114:115], 0, v[98:99]
	v_ashrrev_i32_e32 v155, 31, v154
	s_add_i32 s6, s6, s57
	s_cmpk_gt_i32 s6, 0x1ff
	s_waitcnt vmcnt(0) lgkmcnt(0)
	v_mfma_f32_16x16x32_bf16 v[2:5], v[30:33], v[2:5], 0
	v_mfma_f32_16x16x32_bf16 v[2:5], v[34:37], v[6:9], v[2:5]
	v_mfma_f32_16x16x32_bf16 v[2:5], v[38:41], v[10:13], v[2:5]
	v_mfma_f32_16x16x32_bf16 v[14:17], v[42:45], v[14:17], v[2:5]
	v_mfma_f32_16x16x32_bf16 v[2:5], v[30:33], v[18:21], 0
	v_or_b32_e32 v18, 64, v116
	v_ashrrev_i32_e32 v19, 31, v18
	v_lshlrev_b64 v[18:19], 10, v[18:19]
	v_mfma_f32_16x16x32_bf16 v[2:5], v[34:37], v[22:25], v[2:5]
	v_mfma_f32_16x16x32_bf16 v[2:5], v[38:41], v[26:29], v[2:5]
	v_mfma_f32_16x16x32_bf16 v[10:13], v[42:45], v[46:49], v[2:5]
	v_lshl_add_u64 v[46:47], v[114:115], 0, v[18:19]
	global_load_dwordx4 v[18:21], v[46:47], off
	global_load_dwordx4 v[22:25], v[46:47], off offset:64
	global_load_dwordx4 v[26:29], v[46:47], off offset:128
	s_nop 0
	global_load_dwordx4 v[46:49], v[46:47], off offset:192
	v_mfma_f32_16x16x32_bf16 v[2:5], v[30:33], v[50:53], 0
	v_or_b32_e32 v50, 0x50, v116
	v_ashrrev_i32_e32 v51, 31, v50
	v_lshlrev_b64 v[50:51], 10, v[50:51]
	v_mfma_f32_16x16x32_bf16 v[2:5], v[34:37], v[54:57], v[2:5]
	v_mfma_f32_16x16x32_bf16 v[2:5], v[38:41], v[58:61], v[2:5]
	v_mfma_f32_16x16x32_bf16 v[6:9], v[42:45], v[62:65], v[2:5]
	v_lshl_add_u64 v[62:63], v[114:115], 0, v[50:51]
	global_load_dwordx4 v[50:53], v[62:63], off
	global_load_dwordx4 v[54:57], v[62:63], off offset:64
	global_load_dwordx4 v[58:61], v[62:63], off offset:128
	s_nop 0
	global_load_dwordx4 v[62:65], v[62:63], off offset:192
	v_mfma_f32_16x16x32_bf16 v[2:5], v[30:33], v[66:69], 0
	v_or_b32_e32 v66, 0x60, v116
	v_ashrrev_i32_e32 v67, 31, v66
	v_lshlrev_b64 v[66:67], 10, v[66:67]
	v_mfma_f32_16x16x32_bf16 v[2:5], v[34:37], v[70:73], v[2:5]
	v_mfma_f32_16x16x32_bf16 v[2:5], v[38:41], v[74:77], v[2:5]
	v_mfma_f32_16x16x32_bf16 v[2:5], v[42:45], v[78:81], v[2:5]
	v_lshl_add_u64 v[78:79], v[114:115], 0, v[66:67]
	global_load_dwordx4 v[66:69], v[78:79], off
	global_load_dwordx4 v[70:73], v[78:79], off offset:64
	global_load_dwordx4 v[74:77], v[78:79], off offset:128
	s_nop 0
	global_load_dwordx4 v[78:81], v[78:79], off offset:192
	s_nop 0
	global_load_dwordx4 v[82:85], v[94:95], off
	global_load_dwordx4 v[86:89], v[94:95], off offset:64
	global_load_dwordx4 v[90:93], v[94:95], off offset:128
	s_nop 0
	global_load_dwordx4 v[94:97], v[94:95], off offset:192
	s_waitcnt vmcnt(0) lgkmcnt(0)
;     ...
;     bf16x8 aQ[4];
; #pragma unroll
;     for (int ks = 0; ks < 4; ++ks) aQ[ks] = *(const bf16x8*)(qg + (t0 + fr) * ldq + qcol + h * 128 + ks * 32 + fq * 8);
;     f32x4 s[16];
; #pragma unroll
;     for (int nb = 0; nb < 4; ++nb) {
;       bf16x8 bk[4][4];
; #pragma unroll
;       for (int n4 = 0; n4 < 4; ++n4)
; #pragma unroll
;         for (int ks = 0; ks < 4; ++ks)
;           bk[n4][ks] = *(const bf16x8*)(Km + (long)(b * 256 + (nb * 4 + n4) * 16 + fr) * 512 + h * 128 + ks * 32 + fq * 8);
;       asm volatile("" ::: "memory");
; #pragma unroll
;       for (int n4 = 0; n4 < 4; ++n4) {
;         f32x4 a = {0.f, 0.f, 0.f, 0.f};
; #pragma unroll
;         for (int ks = 0; ks < 4; ++ks) a = __builtin_amdgcn_mfma_f32_16x16x32_bf16(aQ[ks], bk[n4][ks], a, 0, 0, 0);
;         s[nb * 4 + n4] = a;
;       }
;     }
	v_mfma_f32_16x16x32_bf16 v[18:21], v[30:33], v[18:21], 0
	v_mfma_f32_16x16x32_bf16 v[18:21], v[34:37], v[22:25], v[18:21]
	v_mfma_f32_16x16x32_bf16 v[18:21], v[38:41], v[26:29], v[18:21]
	v_mfma_f32_16x16x32_bf16 v[46:49], v[42:45], v[46:49], v[18:21]
	v_mfma_f32_16x16x32_bf16 v[18:21], v[30:33], v[50:53], 0
	v_or_b32_e32 v50, 0x80, v116
	v_ashrrev_i32_e32 v51, 31, v50
	v_lshlrev_b64 v[50:51], 10, v[50:51]
	v_mfma_f32_16x16x32_bf16 v[18:21], v[34:37], v[54:57], v[18:21]
	v_mfma_f32_16x16x32_bf16 v[18:21], v[38:41], v[58:61], v[18:21]
	v_mfma_f32_16x16x32_bf16 v[26:29], v[42:45], v[62:65], v[18:21]
	v_lshl_add_u64 v[62:63], v[114:115], 0, v[50:51]
	global_load_dwordx4 v[50:53], v[62:63], off
	global_load_dwordx4 v[54:57], v[62:63], off offset:64
	global_load_dwordx4 v[58:61], v[62:63], off offset:128
	s_nop 0
	global_load_dwordx4 v[62:65], v[62:63], off offset:192
	v_mfma_f32_16x16x32_bf16 v[18:21], v[30:33], v[66:69], 0
	v_or_b32_e32 v66, 0x90, v116
	v_ashrrev_i32_e32 v67, 31, v66
	v_lshlrev_b64 v[66:67], 10, v[66:67]
	v_mfma_f32_16x16x32_bf16 v[18:21], v[34:37], v[70:73], v[18:21]
	v_mfma_f32_16x16x32_bf16 v[18:21], v[38:41], v[74:77], v[18:21]
	v_mfma_f32_16x16x32_bf16 v[22:25], v[42:45], v[78:81], v[18:21]
	v_lshl_add_u64 v[78:79], v[114:115], 0, v[66:67]
	global_load_dwordx4 v[66:69], v[78:79], off
	global_load_dwordx4 v[70:73], v[78:79], off offset:64
	global_load_dwordx4 v[74:77], v[78:79], off offset:128
	s_nop 0
	global_load_dwordx4 v[78:81], v[78:79], off offset:192
	v_mfma_f32_16x16x32_bf16 v[18:21], v[30:33], v[82:85], 0
	v_or_b32_e32 v82, 0xa0, v116
	v_ashrrev_i32_e32 v83, 31, v82
	v_lshlrev_b64 v[82:83], 10, v[82:83]
	v_mfma_f32_16x16x32_bf16 v[18:21], v[34:37], v[86:89], v[18:21]
	v_mfma_f32_16x16x32_bf16 v[18:21], v[38:41], v[90:93], v[18:21]
	v_mfma_f32_16x16x32_bf16 v[18:21], v[42:45], v[94:97], v[18:21]
	v_lshl_add_u64 v[94:95], v[114:115], 0, v[82:83]
	global_load_dwordx4 v[82:85], v[94:95], off
	global_load_dwordx4 v[86:89], v[94:95], off offset:64
	global_load_dwordx4 v[90:93], v[94:95], off offset:128
	s_nop 0
	global_load_dwordx4 v[94:97], v[94:95], off offset:192
	s_nop 0
	global_load_dwordx4 v[98:101], v[110:111], off
	global_load_dwordx4 v[102:105], v[110:111], off offset:64
	global_load_dwordx4 v[106:109], v[110:111], off offset:128
	s_nop 0
	global_load_dwordx4 v[110:113], v[110:111], off offset:192
	s_waitcnt vmcnt(0) lgkmcnt(0)
	v_mfma_f32_16x16x32_bf16 v[50:53], v[30:33], v[50:53], 0
	v_mfma_f32_16x16x32_bf16 v[50:53], v[34:37], v[54:57], v[50:53]
	v_mfma_f32_16x16x32_bf16 v[50:53], v[38:41], v[58:61], v[50:53]
	v_mfma_f32_16x16x32_bf16 v[62:65], v[42:45], v[62:65], v[50:53]
	v_mfma_f32_16x16x32_bf16 v[50:53], v[30:33], v[66:69], 0
	v_or_b32_e32 v66, 0xc0, v116
	v_ashrrev_i32_e32 v67, 31, v66
	v_lshlrev_b64 v[66:67], 10, v[66:67]
	v_mfma_f32_16x16x32_bf16 v[50:53], v[34:37], v[70:73], v[50:53]
	v_mfma_f32_16x16x32_bf16 v[50:53], v[38:41], v[74:77], v[50:53]
	v_mfma_f32_16x16x32_bf16 v[58:61], v[42:45], v[78:81], v[50:53]
	v_lshl_add_u64 v[78:79], v[114:115], 0, v[66:67]
	global_load_dwordx4 v[66:69], v[78:79], off
	global_load_dwordx4 v[70:73], v[78:79], off offset:64
	global_load_dwordx4 v[74:77], v[78:79], off offset:128
	s_nop 0
	global_load_dwordx4 v[78:81], v[78:79], off offset:192
	v_mfma_f32_16x16x32_bf16 v[50:53], v[30:33], v[82:85], 0
	v_or_b32_e32 v82, 0xd0, v116
	v_ashrrev_i32_e32 v83, 31, v82
	v_lshlrev_b64 v[82:83], 10, v[82:83]
	v_mfma_f32_16x16x32_bf16 v[50:53], v[34:37], v[86:89], v[50:53]
	v_mfma_f32_16x16x32_bf16 v[50:53], v[38:41], v[90:93], v[50:53]
	v_mfma_f32_16x16x32_bf16 v[54:57], v[42:45], v[94:97], v[50:53]
	v_lshl_add_u64 v[94:95], v[114:115], 0, v[82:83]
	global_load_dwordx4 v[82:85], v[94:95], off
	global_load_dwordx4 v[86:89], v[94:95], off offset:64
	global_load_dwordx4 v[90:93], v[94:95], off offset:128
	s_nop 0
	global_load_dwordx4 v[94:97], v[94:95], off offset:192
	v_mfma_f32_16x16x32_bf16 v[50:53], v[30:33], v[98:101], 0
	v_or_b32_e32 v98, 0xe0, v116
	v_or_b32_e32 v116, 0xf0, v116
	v_ashrrev_i32_e32 v99, 31, v98
	v_mfma_f32_16x16x32_bf16 v[50:53], v[34:37], v[102:105], v[50:53]
	v_ashrrev_i32_e32 v117, 31, v116
	v_lshlrev_b64 v[98:99], 10, v[98:99]
	v_lshlrev_b64 v[116:117], 10, v[116:117]
	v_mfma_f32_16x16x32_bf16 v[50:53], v[38:41], v[106:109], v[50:53]
	v_lshl_add_u64 v[126:127], v[114:115], 0, v[116:117]
	v_mfma_f32_16x16x32_bf16 v[50:53], v[42:45], v[110:113], v[50:53]
	v_lshl_add_u64 v[110:111], v[114:115], 0, v[98:99]
	global_load_dwordx4 v[98:101], v[110:111], off
	global_load_dwordx4 v[102:105], v[110:111], off offset:64
	global_load_dwordx4 v[106:109], v[110:111], off offset:128
	s_nop 0
	global_load_dwordx4 v[110:113], v[110:111], off offset:192
	s_nop 0
	global_load_dwordx4 v[114:117], v[126:127], off
	global_load_dwordx4 v[118:121], v[126:127], off offset:64
	global_load_dwordx4 v[122:125], v[126:127], off offset:128
	s_nop 0
	global_load_dwordx4 v[126:129], v[126:127], off offset:192
	s_waitcnt lgkmcnt(0)
	s_barrier
;     ...
;     const float scale = 0.08838834764831845f;
;     float mx[4], sm[4];
; #pragma unroll
;     for (int r = 0; r < 4; ++r) {
;       float v = s[0][r];
; #pragma unroll
;       for (int nt = 1; nt < 16; ++nt) v = fmaxf(v, s[nt][r]);
; #pragma unroll
;       for (int o = 1; o < 16; o <<= 1) v = fmaxf(v, __shfl_xor(v, o, 64));
;       mx[r] = v; sm[r] = 0.f;
;     }
	s_waitcnt vmcnt(0)
	v_mfma_f32_16x16x32_bf16 v[66:69], v[30:33], v[66:69], 0
	v_mfma_f32_16x16x32_bf16 v[66:69], v[34:37], v[70:73], v[66:69]
	v_mfma_f32_16x16x32_bf16 v[66:69], v[38:41], v[74:77], v[66:69]
	v_mfma_f32_16x16x32_bf16 v[74:77], v[42:45], v[78:81], v[66:69]
	v_mfma_f32_16x16x32_bf16 v[66:69], v[30:33], v[82:85], 0
	v_mfma_f32_16x16x32_bf16 v[66:69], v[34:37], v[86:89], v[66:69]
	v_mfma_f32_16x16x32_bf16 v[66:69], v[38:41], v[90:93], v[66:69]
	v_mfma_f32_16x16x32_bf16 v[70:73], v[42:45], v[94:97], v[66:69]
	v_mfma_f32_16x16x32_bf16 v[66:69], v[30:33], v[98:101], 0
	v_mfma_f32_16x16x32_bf16 v[30:33], v[30:33], v[114:117], 0
	v_mfma_f32_16x16x32_bf16 v[66:69], v[34:37], v[102:105], v[66:69]
	v_mfma_f32_16x16x32_bf16 v[30:33], v[34:37], v[118:121], v[30:33]
	v_max_f32_e32 v34, v10, v10
	v_max_f32_e32 v35, v14, v14
	v_max_f32_e32 v34, v35, v34
	v_mfma_f32_16x16x32_bf16 v[66:69], v[38:41], v[106:109], v[66:69]
	v_max3_f32 v34, v34, v6, v2
	v_max3_f32 v34, v34, v46, v26
	v_max3_f32 v34, v34, v22, v18
	v_mfma_f32_16x16x32_bf16 v[30:33], v[38:41], v[122:125], v[30:33]
	v_max3_f32 v34, v34, v62, v58
	v_max3_f32 v34, v34, v54, v50
	v_max3_f32 v34, v34, v74, v70
	v_mfma_f32_16x16x32_bf16 v[66:69], v[42:45], v[110:113], v[66:69]
	v_add_u32_e32 v37, 64, v196
	v_max_f32_e32 v40, v15, v15
	v_max_f32_e32 v41, v16, v16
	v_mfma_f32_16x16x32_bf16 v[30:33], v[42:45], v[126:129], v[30:33]
	v_max_f32_e32 v42, v17, v17
	s_nop 6
	v_max3_f32 v35, v34, v66, v30
	v_xor_b32_e32 v34, 1, v195
	v_cmp_lt_i32_e32 vcc, v34, v37
	s_nop 1
	v_cndmask_b32_e32 v34, v195, v34, vcc
	v_lshlrev_b32_e32 v34, 2, v34
	ds_bpermute_b32 v36, v34, v35
	s_waitcnt lgkmcnt(0)
	v_max_f32_e32 v36, v36, v36
	v_max_f32_e32 v36, v35, v36
	v_xor_b32_e32 v35, 2, v195
	v_cmp_lt_i32_e32 vcc, v35, v37
	s_nop 1
	v_cndmask_b32_e32 v35, v195, v35, vcc
	v_lshlrev_b32_e32 v35, 2, v35
	ds_bpermute_b32 v38, v35, v36
	s_waitcnt lgkmcnt(0)
	v_max_f32_e32 v38, v38, v38
	v_max_f32_e32 v38, v36, v38
	v_xor_b32_e32 v36, 4, v195
	v_cmp_lt_i32_e32 vcc, v36, v37
	s_nop 1
	v_cndmask_b32_e32 v36, v195, v36, vcc
	v_lshlrev_b32_e32 v36, 2, v36
	ds_bpermute_b32 v39, v36, v38
	s_waitcnt lgkmcnt(0)
	v_max_f32_e32 v39, v39, v39
	v_max_f32_e32 v38, v38, v39
	v_xor_b32_e32 v39, 8, v195
	v_cmp_lt_i32_e32 vcc, v39, v37
	s_nop 1
	v_cndmask_b32_e32 v37, v195, v39, vcc
	v_lshlrev_b32_e32 v37, 2, v37
	ds_bpermute_b32 v39, v37, v38
	s_waitcnt lgkmcnt(0)
	v_max_f32_e32 v39, v39, v39
	v_max_f32_e32 v38, v38, v39
	v_max_f32_e32 v39, v11, v11
	v_max_f32_e32 v39, v40, v39
	v_max3_f32 v39, v39, v7, v3
	v_max3_f32 v39, v39, v47, v27
	v_max3_f32 v39, v39, v23, v19
	v_max3_f32 v39, v39, v63, v59
	v_max3_f32 v39, v39, v55, v51
	v_max3_f32 v39, v39, v75, v71
	v_max3_f32 v39, v39, v67, v31
	ds_bpermute_b32 v40, v34, v39
	v_sub_f32_e32 v14, v14, v38
	v_mul_f32_e32 v14, 0x3db504f3, v14
	v_mul_f32_e32 v14, 0x3fb8aa3b, v14
	v_exp_f32_e32 v14, v14
	s_waitcnt lgkmcnt(0)
	v_max_f32_e32 v40, v40, v40
	v_max_f32_e32 v39, v39, v40
	ds_bpermute_b32 v40, v35, v39
	v_sub_f32_e32 v10, v10, v38
	v_mul_f32_e32 v10, 0x3db504f3, v10
	v_mul_f32_e32 v10, 0x3fb8aa3b, v10
	v_exp_f32_e32 v10, v10
	s_waitcnt lgkmcnt(0)
	v_max_f32_e32 v40, v40, v40
	v_max_f32_e32 v39, v39, v40
	ds_bpermute_b32 v40, v36, v39
	v_sub_f32_e32 v6, v6, v38
	v_mul_f32_e32 v6, 0x3db504f3, v6
	v_mul_f32_e32 v6, 0x3fb8aa3b, v6
	v_exp_f32_e32 v6, v6
	s_waitcnt lgkmcnt(0)
	v_max_f32_e32 v40, v40, v40
	v_max_f32_e32 v39, v39, v40
	ds_bpermute_b32 v40, v37, v39
	v_sub_f32_e32 v2, v2, v38
	v_mul_f32_e32 v2, 0x3db504f3, v2
	v_mul_f32_e32 v2, 0x3fb8aa3b, v2
	v_exp_f32_e32 v2, v2
	s_waitcnt lgkmcnt(0)
	v_max_f32_e32 v40, v40, v40
	v_max_f32_e32 v39, v39, v40
	v_max_f32_e32 v40, v12, v12
	v_max_f32_e32 v40, v41, v40
	v_max3_f32 v40, v40, v8, v4
	v_max3_f32 v40, v40, v48, v28
	v_max3_f32 v40, v40, v24, v20
	v_max3_f32 v40, v40, v64, v60
	v_max3_f32 v40, v40, v56, v52
	v_max3_f32 v40, v40, v76, v72
	v_max3_f32 v40, v40, v68, v32
	ds_bpermute_b32 v41, v34, v40
	s_waitcnt lgkmcnt(0)
	v_max_f32_e32 v41, v41, v41
	v_max_f32_e32 v40, v40, v41
	ds_bpermute_b32 v41, v35, v40
	s_waitcnt lgkmcnt(0)
	v_max_f32_e32 v41, v41, v41
	v_max_f32_e32 v40, v40, v41
	ds_bpermute_b32 v41, v36, v40
	s_waitcnt lgkmcnt(0)
	v_max_f32_e32 v41, v41, v41
	v_max_f32_e32 v40, v40, v41
	ds_bpermute_b32 v41, v37, v40
	s_waitcnt lgkmcnt(0)
	v_max_f32_e32 v41, v41, v41
	v_max_f32_e32 v40, v40, v41
	v_max_f32_e32 v41, v13, v13
	v_max_f32_e32 v41, v42, v41
	v_max3_f32 v41, v41, v9, v5
	v_max3_f32 v41, v41, v49, v29
	v_max3_f32 v41, v41, v25, v21
	v_max3_f32 v41, v41, v65, v61
	v_max3_f32 v41, v41, v57, v53
	v_max3_f32 v41, v41, v77, v73
	v_max3_f32 v41, v41, v69, v33
	ds_bpermute_b32 v42, v34, v41
	s_waitcnt lgkmcnt(0)
	v_max_f32_e32 v42, v42, v42
	v_max_f32_e32 v41, v41, v42
	ds_bpermute_b32 v42, v35, v41
	s_waitcnt lgkmcnt(0)
	v_max_f32_e32 v42, v42, v42
	v_max_f32_e32 v41, v41, v42
	ds_bpermute_b32 v42, v36, v41
	s_waitcnt lgkmcnt(0)
	v_max_f32_e32 v42, v42, v42
	v_max_f32_e32 v41, v41, v42
	ds_bpermute_b32 v42, v37, v41
	s_waitcnt lgkmcnt(0)
; __device__ __forceinline__ u16 f2bf(float f) { return (u16)(pack2(f, 0.f) & 0xffffu); }
;     ...
;     __syncthreads();
; #pragma unroll
;     for (int nt = 0; nt < 16; ++nt)
; #pragma unroll
;       for (int r = 0; r < 4; ++r) {
;         float e = __expf((s[nt][r] - mx[r]) * scale);
;         sm[r] += e;
;         Pw[(fq * 4 + r) * 264 + nt * 16 + fr] = f2bf(e);
;       }
	v_max_f32_e32 v42, v42, v42
	v_max_f32_e32 v41, v41, v42
	v_add_f32_e32 v42, 0, v14
	v_cvt_pk_bf16_f32 v14, v14, s0
	ds_write_b16 v131, v14
	v_sub_f32_e32 v14, v15, v39
	v_mul_f32_e32 v14, 0x3db504f3, v14
	v_mul_f32_e32 v14, 0x3fb8aa3b, v14
	v_exp_f32_e32 v14, v14
	s_nop 0
	v_add_f32_e32 v15, 0, v14
	v_cvt_pk_bf16_f32 v14, v14, s0
	ds_write_b16 v141, v14
	v_sub_f32_e32 v14, v16, v40
	v_mul_f32_e32 v14, 0x3db504f3, v14
	v_mul_f32_e32 v14, 0x3fb8aa3b, v14
	v_exp_f32_e32 v14, v14
	s_nop 0
	v_add_f32_e32 v16, 0, v14
	v_cvt_pk_bf16_f32 v14, v14, s0
	ds_write_b16 v141, v14 offset:528
	v_sub_f32_e32 v14, v17, v41
	v_mul_f32_e32 v14, 0x3db504f3, v14
	v_mul_f32_e32 v14, 0x3fb8aa3b, v14
	v_exp_f32_e32 v14, v14
	s_nop 0
	v_add_f32_e32 v17, 0, v14
	v_cvt_pk_bf16_f32 v14, v14, s0
	ds_write_b16 v141, v14 offset:1056
	v_add_f32_e32 v14, v10, v42
	v_cvt_pk_bf16_f32 v10, v10, s0
	ds_write_b16 v131, v10 offset:32
	v_sub_f32_e32 v10, v11, v39
	v_mul_f32_e32 v10, 0x3db504f3, v10
	v_mul_f32_e32 v10, 0x3fb8aa3b, v10
	v_exp_f32_e32 v10, v10
	s_nop 0
	v_add_f32_e32 v11, v10, v15
	v_cvt_pk_bf16_f32 v10, v10, s0
	ds_write_b16 v141, v10 offset:32
	v_sub_f32_e32 v10, v12, v40
	v_mul_f32_e32 v10, 0x3db504f3, v10
	v_mul_f32_e32 v10, 0x3fb8aa3b, v10
	v_exp_f32_e32 v10, v10
	s_nop 0
	v_add_f32_e32 v12, v10, v16
	v_cvt_pk_bf16_f32 v10, v10, s0
	ds_write_b16 v141, v10 offset:560
	v_sub_f32_e32 v10, v13, v41
	v_mul_f32_e32 v10, 0x3db504f3, v10
	v_mul_f32_e32 v10, 0x3fb8aa3b, v10
	v_exp_f32_e32 v10, v10
	s_nop 0
	v_add_f32_e32 v13, v10, v17
	v_cvt_pk_bf16_f32 v10, v10, s0
	ds_write_b16 v141, v10 offset:1088
	v_add_f32_e32 v10, v6, v14
	v_cvt_pk_bf16_f32 v6, v6, s0
	ds_write_b16 v131, v6 offset:64
	v_sub_f32_e32 v6, v7, v39
	v_mul_f32_e32 v6, 0x3db504f3, v6
	v_mul_f32_e32 v6, 0x3fb8aa3b, v6
	v_exp_f32_e32 v6, v6
	s_nop 0
	v_add_f32_e32 v7, v6, v11
	v_cvt_pk_bf16_f32 v6, v6, s0
	ds_write_b16 v141, v6 offset:64
	v_sub_f32_e32 v6, v8, v40
	v_mul_f32_e32 v6, 0x3db504f3, v6
	v_mul_f32_e32 v6, 0x3fb8aa3b, v6
	v_exp_f32_e32 v6, v6
	s_nop 0
	v_add_f32_e32 v8, v6, v12
	v_cvt_pk_bf16_f32 v6, v6, s0
	ds_write_b16 v141, v6 offset:592
	v_sub_f32_e32 v6, v9, v41
	v_mul_f32_e32 v6, 0x3db504f3, v6
	v_mul_f32_e32 v6, 0x3fb8aa3b, v6
	v_exp_f32_e32 v6, v6
	s_nop 0
	v_add_f32_e32 v9, v6, v13
	v_cvt_pk_bf16_f32 v6, v6, s0
	ds_write_b16 v141, v6 offset:1120
	v_add_f32_e32 v6, v2, v10
	v_cvt_pk_bf16_f32 v2, v2, s0
	ds_write_b16 v131, v2 offset:96
	v_sub_f32_e32 v2, v3, v39
	v_mul_f32_e32 v2, 0x3db504f3, v2
	v_mul_f32_e32 v2, 0x3fb8aa3b, v2
	v_exp_f32_e32 v2, v2
	s_nop 0
	v_add_f32_e32 v3, v2, v7
	v_cvt_pk_bf16_f32 v2, v2, s0
	ds_write_b16 v141, v2 offset:96
	v_sub_f32_e32 v2, v4, v40
	v_mul_f32_e32 v2, 0x3db504f3, v2
	v_mul_f32_e32 v2, 0x3fb8aa3b, v2
	v_exp_f32_e32 v2, v2
	s_nop 0
	v_add_f32_e32 v4, v2, v8
	v_cvt_pk_bf16_f32 v2, v2, s0
	ds_write_b16 v141, v2 offset:624
	v_sub_f32_e32 v2, v5, v41
	v_mul_f32_e32 v2, 0x3db504f3, v2
	v_mul_f32_e32 v2, 0x3fb8aa3b, v2
	v_exp_f32_e32 v2, v2
	s_nop 0
	v_add_f32_e32 v5, v2, v9
	v_cvt_pk_bf16_f32 v2, v2, s0
	ds_write_b16 v141, v2 offset:1152
	v_sub_f32_e32 v2, v46, v38
	v_mul_f32_e32 v2, 0x3db504f3, v2
	v_mul_f32_e32 v2, 0x3fb8aa3b, v2
	v_exp_f32_e32 v2, v2
	s_nop 0
	v_add_f32_e32 v6, v2, v6
	v_cvt_pk_bf16_f32 v2, v2, s0
	ds_write_b16 v131, v2 offset:128
	v_sub_f32_e32 v2, v47, v39
	v_mul_f32_e32 v2, 0x3db504f3, v2
	v_mul_f32_e32 v2, 0x3fb8aa3b, v2
	v_exp_f32_e32 v2, v2
	s_nop 0
	v_add_f32_e32 v3, v2, v3
	v_cvt_pk_bf16_f32 v2, v2, s0
	ds_write_b16 v141, v2 offset:128
	v_sub_f32_e32 v2, v48, v40
	v_mul_f32_e32 v2, 0x3db504f3, v2
	v_mul_f32_e32 v2, 0x3fb8aa3b, v2
	v_exp_f32_e32 v2, v2
	s_nop 0
	v_add_f32_e32 v4, v2, v4
	v_cvt_pk_bf16_f32 v2, v2, s0
	ds_write_b16 v141, v2 offset:656
	v_sub_f32_e32 v2, v49, v41
	v_mul_f32_e32 v2, 0x3db504f3, v2
	v_mul_f32_e32 v2, 0x3fb8aa3b, v2
	v_exp_f32_e32 v2, v2
	s_nop 0
	v_add_f32_e32 v5, v2, v5
	v_cvt_pk_bf16_f32 v2, v2, s0
	ds_write_b16 v141, v2 offset:1184
	v_sub_f32_e32 v2, v26, v38
	v_mul_f32_e32 v2, 0x3db504f3, v2
	v_mul_f32_e32 v2, 0x3fb8aa3b, v2
	v_exp_f32_e32 v2, v2
	s_nop 0
	v_add_f32_e32 v6, v2, v6
	v_cvt_pk_bf16_f32 v2, v2, s0
	ds_write_b16 v131, v2 offset:160
	v_sub_f32_e32 v2, v27, v39
	v_mul_f32_e32 v2, 0x3db504f3, v2
	v_mul_f32_e32 v2, 0x3fb8aa3b, v2
	v_exp_f32_e32 v2, v2
	s_nop 0
	v_add_f32_e32 v3, v2, v3
	v_cvt_pk_bf16_f32 v2, v2, s0
	ds_write_b16 v141, v2 offset:160
	v_sub_f32_e32 v2, v28, v40
	v_mul_f32_e32 v2, 0x3db504f3, v2
	v_mul_f32_e32 v2, 0x3fb8aa3b, v2
	v_exp_f32_e32 v2, v2
	s_nop 0
	v_add_f32_e32 v4, v2, v4
	v_cvt_pk_bf16_f32 v2, v2, s0
	ds_write_b16 v141, v2 offset:688
	v_sub_f32_e32 v2, v29, v41
	v_mul_f32_e32 v2, 0x3db504f3, v2
	v_mul_f32_e32 v2, 0x3fb8aa3b, v2
	v_exp_f32_e32 v2, v2
	s_nop 0
	v_add_f32_e32 v5, v2, v5
	v_cvt_pk_bf16_f32 v2, v2, s0
	ds_write_b16 v141, v2 offset:1216
	v_sub_f32_e32 v2, v22, v38
	v_mul_f32_e32 v2, 0x3db504f3, v2
	v_mul_f32_e32 v2, 0x3fb8aa3b, v2
	v_exp_f32_e32 v2, v2
	s_nop 0
	v_add_f32_e32 v6, v2, v6
	v_cvt_pk_bf16_f32 v2, v2, s0
	ds_write_b16 v131, v2 offset:192
	v_sub_f32_e32 v2, v23, v39
	v_mul_f32_e32 v2, 0x3db504f3, v2
	v_mul_f32_e32 v2, 0x3fb8aa3b, v2
	v_exp_f32_e32 v2, v2
	s_nop 0
	v_add_f32_e32 v3, v2, v3
	v_cvt_pk_bf16_f32 v2, v2, s0
	ds_write_b16 v141, v2 offset:192
	v_sub_f32_e32 v2, v24, v40
	v_mul_f32_e32 v2, 0x3db504f3, v2
	v_mul_f32_e32 v2, 0x3fb8aa3b, v2
	v_exp_f32_e32 v2, v2
	s_nop 0
	v_add_f32_e32 v4, v2, v4
	v_cvt_pk_bf16_f32 v2, v2, s0
	ds_write_b16 v141, v2 offset:720
	v_sub_f32_e32 v2, v25, v41
	v_mul_f32_e32 v2, 0x3db504f3, v2
	v_mul_f32_e32 v2, 0x3fb8aa3b, v2
	v_exp_f32_e32 v2, v2
	s_nop 0
	v_add_f32_e32 v5, v2, v5
	v_cvt_pk_bf16_f32 v2, v2, s0
; __device__ __forceinline__ u16 f2bf(float f) { return (u16)(pack2(f, 0.f) & 0xffffu); }
;     ...
;     __syncthreads();
; #pragma unroll
;     for (int nt = 0; nt < 16; ++nt)
; #pragma unroll
;       for (int r = 0; r < 4; ++r) {
;         float e = __expf((s[nt][r] - mx[r]) * scale);
;         sm[r] += e;
;         Pw[(fq * 4 + r) * 264 + nt * 16 + fr] = f2bf(e);
;       }
	ds_write_b16 v141, v2 offset:1248
	v_sub_f32_e32 v2, v18, v38
	v_mul_f32_e32 v2, 0x3db504f3, v2
	v_mul_f32_e32 v2, 0x3fb8aa3b, v2
	v_exp_f32_e32 v2, v2
	s_nop 0
	v_add_f32_e32 v6, v2, v6
	v_cvt_pk_bf16_f32 v2, v2, s0
	ds_write_b16 v131, v2 offset:224
	v_sub_f32_e32 v2, v19, v39
	v_mul_f32_e32 v2, 0x3db504f3, v2
	v_mul_f32_e32 v2, 0x3fb8aa3b, v2
	v_exp_f32_e32 v2, v2
	s_nop 0
	v_add_f32_e32 v3, v2, v3
	v_cvt_pk_bf16_f32 v2, v2, s0
	ds_write_b16 v141, v2 offset:224
	v_sub_f32_e32 v2, v20, v40
	v_mul_f32_e32 v2, 0x3db504f3, v2
	v_mul_f32_e32 v2, 0x3fb8aa3b, v2
	v_exp_f32_e32 v2, v2
	s_nop 0
	v_add_f32_e32 v4, v2, v4
	v_cvt_pk_bf16_f32 v2, v2, s0
	ds_write_b16 v141, v2 offset:752
	v_sub_f32_e32 v2, v21, v41
	v_mul_f32_e32 v2, 0x3db504f3, v2
	v_mul_f32_e32 v2, 0x3fb8aa3b, v2
	v_exp_f32_e32 v2, v2
	s_nop 0
	v_add_f32_e32 v5, v2, v5
	v_cvt_pk_bf16_f32 v2, v2, s0
	ds_write_b16 v141, v2 offset:1280
	v_sub_f32_e32 v2, v62, v38
	v_mul_f32_e32 v2, 0x3db504f3, v2
	v_mul_f32_e32 v2, 0x3fb8aa3b, v2
	v_exp_f32_e32 v2, v2
	s_nop 0
	v_add_f32_e32 v6, v2, v6
	v_cvt_pk_bf16_f32 v2, v2, s0
	ds_write_b16 v131, v2 offset:256
	v_sub_f32_e32 v2, v63, v39
	v_mul_f32_e32 v2, 0x3db504f3, v2
	v_mul_f32_e32 v2, 0x3fb8aa3b, v2
	v_exp_f32_e32 v2, v2
	s_nop 0
	v_add_f32_e32 v3, v2, v3
	v_cvt_pk_bf16_f32 v2, v2, s0
	ds_write_b16 v141, v2 offset:256
	v_sub_f32_e32 v2, v64, v40
	v_mul_f32_e32 v2, 0x3db504f3, v2
	v_mul_f32_e32 v2, 0x3fb8aa3b, v2
	v_exp_f32_e32 v2, v2
	s_nop 0
	v_add_f32_e32 v4, v2, v4
	v_cvt_pk_bf16_f32 v2, v2, s0
	ds_write_b16 v141, v2 offset:784
	v_sub_f32_e32 v2, v65, v41
	v_mul_f32_e32 v2, 0x3db504f3, v2
	v_mul_f32_e32 v2, 0x3fb8aa3b, v2
	v_exp_f32_e32 v2, v2
	s_nop 0
	v_add_f32_e32 v5, v2, v5
	v_cvt_pk_bf16_f32 v2, v2, s0
	ds_write_b16 v141, v2 offset:1312
	v_sub_f32_e32 v2, v58, v38
	v_mul_f32_e32 v2, 0x3db504f3, v2
	v_mul_f32_e32 v2, 0x3fb8aa3b, v2
	v_exp_f32_e32 v2, v2
	s_nop 0
	v_add_f32_e32 v6, v2, v6
	v_cvt_pk_bf16_f32 v2, v2, s0
	ds_write_b16 v131, v2 offset:288
	v_sub_f32_e32 v2, v59, v39
	v_mul_f32_e32 v2, 0x3db504f3, v2
	v_mul_f32_e32 v2, 0x3fb8aa3b, v2
	v_exp_f32_e32 v2, v2
	s_nop 0
	v_add_f32_e32 v3, v2, v3
	v_cvt_pk_bf16_f32 v2, v2, s0
	ds_write_b16 v141, v2 offset:288
	v_sub_f32_e32 v2, v60, v40
	v_mul_f32_e32 v2, 0x3db504f3, v2
	v_mul_f32_e32 v2, 0x3fb8aa3b, v2
	v_exp_f32_e32 v2, v2
	s_nop 0
	v_add_f32_e32 v4, v2, v4
	v_cvt_pk_bf16_f32 v2, v2, s0
	ds_write_b16 v141, v2 offset:816
	v_sub_f32_e32 v2, v61, v41
	v_mul_f32_e32 v2, 0x3db504f3, v2
	v_mul_f32_e32 v2, 0x3fb8aa3b, v2
	v_exp_f32_e32 v2, v2
	s_nop 0
	v_add_f32_e32 v5, v2, v5
	v_cvt_pk_bf16_f32 v2, v2, s0
	ds_write_b16 v141, v2 offset:1344
	v_sub_f32_e32 v2, v54, v38
	v_mul_f32_e32 v2, 0x3db504f3, v2
	v_mul_f32_e32 v2, 0x3fb8aa3b, v2
	v_exp_f32_e32 v2, v2
	s_nop 0
	v_add_f32_e32 v6, v2, v6
	v_cvt_pk_bf16_f32 v2, v2, s0
	ds_write_b16 v131, v2 offset:320
	v_sub_f32_e32 v2, v55, v39
	v_mul_f32_e32 v2, 0x3db504f3, v2
	v_mul_f32_e32 v2, 0x3fb8aa3b, v2
	v_exp_f32_e32 v2, v2
	s_nop 0
	v_add_f32_e32 v3, v2, v3
	v_cvt_pk_bf16_f32 v2, v2, s0
	ds_write_b16 v141, v2 offset:320
	v_sub_f32_e32 v2, v56, v40
	v_mul_f32_e32 v2, 0x3db504f3, v2
	v_mul_f32_e32 v2, 0x3fb8aa3b, v2
	v_exp_f32_e32 v2, v2
	s_nop 0
	v_add_f32_e32 v4, v2, v4
	v_cvt_pk_bf16_f32 v2, v2, s0
	ds_write_b16 v141, v2 offset:848
	v_sub_f32_e32 v2, v57, v41
	v_mul_f32_e32 v2, 0x3db504f3, v2
	v_mul_f32_e32 v2, 0x3fb8aa3b, v2
	v_exp_f32_e32 v2, v2
	s_nop 0
	v_add_f32_e32 v5, v2, v5
	v_cvt_pk_bf16_f32 v2, v2, s0
	ds_write_b16 v141, v2 offset:1376
	v_sub_f32_e32 v2, v50, v38
	v_mul_f32_e32 v2, 0x3db504f3, v2
	v_mul_f32_e32 v2, 0x3fb8aa3b, v2
	v_exp_f32_e32 v2, v2
	s_nop 0
	v_add_f32_e32 v6, v2, v6
	v_cvt_pk_bf16_f32 v2, v2, s0
	ds_write_b16 v131, v2 offset:352
	v_sub_f32_e32 v2, v51, v39
	v_mul_f32_e32 v2, 0x3db504f3, v2
	v_mul_f32_e32 v2, 0x3fb8aa3b, v2
	v_exp_f32_e32 v2, v2
	s_nop 0
	v_add_f32_e32 v3, v2, v3
	v_cvt_pk_bf16_f32 v2, v2, s0
	ds_write_b16 v141, v2 offset:352
	v_sub_f32_e32 v2, v52, v40
	v_mul_f32_e32 v2, 0x3db504f3, v2
	v_mul_f32_e32 v2, 0x3fb8aa3b, v2
	v_exp_f32_e32 v2, v2
	s_nop 0
	v_add_f32_e32 v4, v2, v4
	v_cvt_pk_bf16_f32 v2, v2, s0
	ds_write_b16 v141, v2 offset:880
	v_sub_f32_e32 v2, v53, v41
	v_mul_f32_e32 v2, 0x3db504f3, v2
	v_mul_f32_e32 v2, 0x3fb8aa3b, v2
	v_exp_f32_e32 v2, v2
	s_nop 0
	v_add_f32_e32 v5, v2, v5
	v_cvt_pk_bf16_f32 v2, v2, s0
	ds_write_b16 v141, v2 offset:1408
	v_sub_f32_e32 v2, v74, v38
	v_mul_f32_e32 v2, 0x3db504f3, v2
	v_mul_f32_e32 v2, 0x3fb8aa3b, v2
	v_exp_f32_e32 v2, v2
	s_nop 0
	v_add_f32_e32 v6, v2, v6
	v_cvt_pk_bf16_f32 v2, v2, s0
	ds_write_b16 v131, v2 offset:384
	v_sub_f32_e32 v2, v75, v39
	v_mul_f32_e32 v2, 0x3db504f3, v2
	v_mul_f32_e32 v2, 0x3fb8aa3b, v2
	v_exp_f32_e32 v2, v2
	s_nop 0
	v_add_f32_e32 v3, v2, v3
	v_cvt_pk_bf16_f32 v2, v2, s0
	ds_write_b16 v141, v2 offset:384
	v_sub_f32_e32 v2, v76, v40
	v_mul_f32_e32 v2, 0x3db504f3, v2
	v_mul_f32_e32 v2, 0x3fb8aa3b, v2
	v_exp_f32_e32 v2, v2
	v_or_b32_e32 v76, v152, v136
	v_add_f32_e32 v4, v2, v4
	v_cvt_pk_bf16_f32 v2, v2, s0
	ds_write_b16 v141, v2 offset:912
	v_sub_f32_e32 v2, v77, v41
	v_mul_f32_e32 v2, 0x3db504f3, v2
	v_mul_f32_e32 v2, 0x3fb8aa3b, v2
	v_exp_f32_e32 v2, v2
	s_nop 0
	v_add_f32_e32 v5, v2, v5
	v_cvt_pk_bf16_f32 v2, v2, s0
	ds_write_b16 v141, v2 offset:1440
	v_sub_f32_e32 v2, v70, v38
	v_mul_f32_e32 v2, 0x3db504f3, v2
	v_mul_f32_e32 v2, 0x3fb8aa3b, v2
	v_exp_f32_e32 v2, v2
	s_nop 0
	v_add_f32_e32 v6, v2, v6
	v_cvt_pk_bf16_f32 v2, v2, s0
	ds_write_b16 v131, v2 offset:416
	v_sub_f32_e32 v2, v71, v39
	v_mul_f32_e32 v2, 0x3db504f3, v2
	v_mul_f32_e32 v2, 0x3fb8aa3b, v2
	v_exp_f32_e32 v2, v2
	s_nop 0
	v_add_f32_e32 v3, v2, v3
; __device__ __forceinline__ u16 f2bf(float f) { return (u16)(pack2(f, 0.f) & 0xffffu); }
;     ...
;     for (int nt = 0; nt < 16; ++nt)
; #pragma unroll
;       for (int r = 0; r < 4; ++r) {
;         float e = __expf((s[nt][r] - mx[r]) * scale);
;         sm[r] += e;
;         Pw[(fq * 4 + r) * 264 + nt * 16 + fr] = f2bf(e);
;       }
; #pragma unroll
;     for (int r = 0; r < 4; ++r) {
;       float v = sm[r];
; #pragma unroll
;       for (int o = 1; o < 16; o <<= 1) v += __shfl_xor(v, o, 64);
;       sm[r] = 1.f / v;
;     }
	v_cvt_pk_bf16_f32 v2, v2, s0
	ds_write_b16 v141, v2 offset:416
	v_sub_f32_e32 v2, v72, v40
	v_mul_f32_e32 v2, 0x3db504f3, v2
	v_mul_f32_e32 v2, 0x3fb8aa3b, v2
	v_exp_f32_e32 v2, v2
	s_nop 0
	v_add_f32_e32 v4, v2, v4
	v_cvt_pk_bf16_f32 v2, v2, s0
	ds_write_b16 v141, v2 offset:944
	v_sub_f32_e32 v2, v73, v41
	v_mul_f32_e32 v2, 0x3db504f3, v2
	v_mul_f32_e32 v2, 0x3fb8aa3b, v2
	v_exp_f32_e32 v2, v2
	s_nop 0
	v_add_f32_e32 v5, v2, v5
	v_cvt_pk_bf16_f32 v2, v2, s0
	ds_write_b16 v141, v2 offset:1472
	v_sub_f32_e32 v2, v66, v38
	v_mul_f32_e32 v2, 0x3db504f3, v2
	v_mul_f32_e32 v2, 0x3fb8aa3b, v2
	v_exp_f32_e32 v2, v2
	s_nop 0
	v_add_f32_e32 v6, v2, v6
	v_cvt_pk_bf16_f32 v2, v2, s0
	ds_write_b16 v131, v2 offset:448
	v_sub_f32_e32 v2, v67, v39
	v_mul_f32_e32 v2, 0x3db504f3, v2
	v_mul_f32_e32 v2, 0x3fb8aa3b, v2
	v_exp_f32_e32 v2, v2
	s_nop 0
	v_add_f32_e32 v3, v2, v3
	v_cvt_pk_bf16_f32 v2, v2, s0
	ds_write_b16 v141, v2 offset:448
	v_sub_f32_e32 v2, v68, v40
	v_mul_f32_e32 v2, 0x3db504f3, v2
	v_mul_f32_e32 v2, 0x3fb8aa3b, v2
	v_exp_f32_e32 v2, v2
	s_nop 0
	v_add_f32_e32 v4, v2, v4
	v_cvt_pk_bf16_f32 v2, v2, s0
	ds_write_b16 v141, v2 offset:976
	v_sub_f32_e32 v2, v69, v41
	v_mul_f32_e32 v2, 0x3db504f3, v2
	v_mul_f32_e32 v2, 0x3fb8aa3b, v2
	v_exp_f32_e32 v2, v2
	s_nop 0
	v_add_f32_e32 v5, v2, v5
	v_cvt_pk_bf16_f32 v2, v2, s0
	ds_write_b16 v141, v2 offset:1504
	v_sub_f32_e32 v2, v30, v38
	v_mul_f32_e32 v2, 0x3db504f3, v2
	v_mul_f32_e32 v2, 0x3fb8aa3b, v2
	v_exp_f32_e32 v2, v2
	v_lshl_or_b32 v38, s7, 17, v149
	v_add_f32_e32 v6, v2, v6
	v_cvt_pk_bf16_f32 v2, v2, s0
	ds_write_b16 v131, v2 offset:480
	v_sub_f32_e32 v2, v31, v39
	v_mul_f32_e32 v2, 0x3db504f3, v2
	v_mul_f32_e32 v2, 0x3fb8aa3b, v2
	v_exp_f32_e32 v2, v2
	v_mov_b32_e32 v39, v1
	v_add_f32_e32 v3, v2, v3
	v_cvt_pk_bf16_f32 v2, v2, s0
	ds_write_b16 v141, v2 offset:480
	v_sub_f32_e32 v2, v32, v40
	v_mul_f32_e32 v2, 0x3db504f3, v2
	v_mul_f32_e32 v2, 0x3fb8aa3b, v2
	v_exp_f32_e32 v2, v2
	s_nop 0
	v_add_f32_e32 v4, v2, v4
	v_cvt_pk_bf16_f32 v2, v2, s0
	ds_write_b16 v141, v2 offset:1008
	v_sub_f32_e32 v2, v33, v41
	v_mul_f32_e32 v2, 0x3db504f3, v2
	v_mul_f32_e32 v2, 0x3fb8aa3b, v2
	v_exp_f32_e32 v2, v2
	s_nop 0
	v_add_f32_e32 v5, v2, v5
	v_cvt_pk_bf16_f32 v2, v2, s0
	ds_write_b16 v141, v2 offset:1536
	ds_bpermute_b32 v2, v34, v6
	s_waitcnt lgkmcnt(0)
	s_barrier
	v_add_f32_e32 v2, v6, v2
	ds_bpermute_b32 v6, v35, v2
	s_waitcnt lgkmcnt(0)
	v_add_f32_e32 v2, v2, v6
	ds_bpermute_b32 v6, v36, v2
	s_waitcnt lgkmcnt(0)
	v_add_f32_e32 v2, v2, v6
	ds_bpermute_b32 v6, v37, v2
	s_waitcnt lgkmcnt(0)
	v_add_f32_e32 v2, v2, v6
	v_div_scale_f32 v6, s[8:9], v2, v2, 1.0
	v_rcp_f32_e32 v7, v6
	s_nop 0
	v_fma_f32 v8, -v6, v7, 1.0
	v_fmac_f32_e32 v7, v8, v7
	v_div_scale_f32 v8, vcc, 1.0, v2, 1.0
	v_mul_f32_e32 v9, v8, v7
	v_fma_f32 v10, -v6, v9, v8
	v_fmac_f32_e32 v9, v10, v7
	v_fma_f32 v6, -v6, v9, v8
	v_div_fmas_f32 v6, v6, v7, v9
	v_div_fixup_f32 v84, v6, v2, 1.0
	ds_bpermute_b32 v2, v34, v3
	s_waitcnt lgkmcnt(0)
	v_add_f32_e32 v2, v3, v2
	ds_bpermute_b32 v3, v35, v2
	s_waitcnt lgkmcnt(0)
	v_add_f32_e32 v2, v2, v3
	ds_bpermute_b32 v3, v36, v2
	s_waitcnt lgkmcnt(0)
	v_add_f32_e32 v2, v2, v3
	ds_bpermute_b32 v3, v37, v2
	s_waitcnt lgkmcnt(0)
	v_add_f32_e32 v2, v2, v3
	v_div_scale_f32 v3, s[8:9], v2, v2, 1.0
	v_rcp_f32_e32 v6, v3
	s_nop 0
	v_fma_f32 v7, -v3, v6, 1.0
	v_fmac_f32_e32 v6, v7, v6
	v_div_scale_f32 v7, vcc, 1.0, v2, 1.0
	v_mul_f32_e32 v8, v7, v6
	v_fma_f32 v9, -v3, v8, v7
	v_fmac_f32_e32 v8, v9, v6
	v_fma_f32 v3, -v3, v8, v7
	v_div_fmas_f32 v3, v3, v6, v8
	v_div_fixup_f32 v85, v3, v2, 1.0
	ds_bpermute_b32 v2, v34, v4
	s_waitcnt lgkmcnt(0)
	v_add_f32_e32 v2, v4, v2
	ds_bpermute_b32 v3, v35, v2
	s_waitcnt lgkmcnt(0)
	v_add_f32_e32 v2, v2, v3
	ds_bpermute_b32 v3, v36, v2
	s_waitcnt lgkmcnt(0)
	v_add_f32_e32 v2, v2, v3
	ds_bpermute_b32 v3, v37, v2
	s_waitcnt lgkmcnt(0)
	v_add_f32_e32 v2, v2, v3
	v_div_scale_f32 v3, s[8:9], v2, v2, 1.0
	v_rcp_f32_e32 v4, v3
	s_nop 0
	v_fma_f32 v6, -v3, v4, 1.0
	v_fmac_f32_e32 v4, v6, v4
	v_div_scale_f32 v6, vcc, 1.0, v2, 1.0
	v_mul_f32_e32 v7, v6, v4
	v_fma_f32 v8, -v3, v7, v6
	v_fmac_f32_e32 v7, v8, v4
	v_fma_f32 v3, -v3, v7, v6
	v_div_fmas_f32 v3, v3, v4, v7
	v_div_fixup_f32 v86, v3, v2, 1.0
	ds_bpermute_b32 v2, v34, v5
	s_waitcnt lgkmcnt(0)
	v_add_f32_e32 v2, v5, v2
	ds_bpermute_b32 v3, v35, v2
	v_lshl_add_u64 v[34:35], v[144:145], 0, s[52:53]
	v_mad_u64_u32 v[66:67], s[8:9], v76, s51, v[34:35]
	v_mad_i32_i24 v67, v153, s51, v67
	s_waitcnt lgkmcnt(0)
	v_add_f32_e32 v2, v2, v3
	ds_bpermute_b32 v3, v36, v2
	s_waitcnt lgkmcnt(0)
	v_add_f32_e32 v2, v2, v3
	ds_bpermute_b32 v3, v37, v2
	v_lshl_add_u64 v[36:37], v[154:155], 1, v[142:143]
	v_lshl_add_u64 v[70:71], v[36:37], 0, v[38:39]
	v_or_b32_e32 v36, v152, v146
	v_mad_u64_u32 v[68:69], s[8:9], v36, s51, v[34:35]
	s_waitcnt lgkmcnt(0)
; __device__ __forceinline__ float bf2f(u16 h) { return __uint_as_float(((unsigned)h) << 16); }
; __device__ __forceinline__ u16 f2bf(float f) { return (u16)(pack2(f, 0.f) & 0xffffu); }
; __device__ __forceinline__ float siluf(float x) { return x * __builtin_amdgcn_rcpf(1.f + __expf(-x)); }
;     ...
;     bf16x8 aP[8];
; #pragma unroll
;     for (int ks = 0; ks < 8; ++ks) aP[ks] = *(const bf16x8*)(Pw + fr * 264 + ks * 32 + fq * 8);
; #pragma unroll
;     for (int db = 0; db < 4; ++db) {
;       bf16x8 bv[2][8];
;       u16 gt[2][4];
; #pragma unroll
;       for (int d2 = 0; d2 < 2; ++d2) {
; #pragma unroll
;         for (int ks = 0; ks < 8; ++ks)
;           bv[d2][ks] = *(const bf16x8*)(VT + (long)(h * 128 + (db * 2 + d2) * 16 + fr) * 512 + b * 256 + ks * 32 + fq * 8);
; #pragma unroll
;         for (int r = 0; r < 4; ++r) gt[d2][r] = qg[(t0 + fq * 4 + r) * ldq + gcol + h * 128 + (db * 2 + d2) * 16 + fr];
;       }
;       asm volatile("" ::: "memory");
; #pragma unroll
;       for (int d2 = 0; d2 < 2; ++d2) {
;         f32x4 a = {0.f, 0.f, 0.f, 0.f};
; #pragma unroll
;         for (int ks = 0; ks < 8; ++ks) a = __builtin_amdgcn_mfma_f32_16x16x32_bf16(aP[ks], bv[d2][ks], a, 0, 0, 0);
; #pragma unroll
;         for (int r = 0; r < 4; ++r) {
;           long row = t0 + fq * 4 + r;
;           int dcol = h * 128 + (db * 2 + d2) * 16 + fr;
;           og[row * ldo + ocol + dcol] = f2bf(a[r] * sm[r] * siluf(bf2f(gt[d2][r])));
;         }
;       }
	v_add_f32_e32 v2, v2, v3
	v_div_scale_f32 v3, s[8:9], v2, v2, 1.0
	v_rcp_f32_e32 v4, v3
	v_or_b32_e32 v36, v152, v148
	v_mad_u64_u32 v[72:73], s[8:9], v36, s51, v[34:35]
	v_fma_f32 v5, -v3, v4, 1.0
	v_fmac_f32_e32 v4, v5, v4
	v_div_scale_f32 v5, vcc, 1.0, v2, 1.0
	v_mul_f32_e32 v6, v5, v4
	v_fma_f32 v7, -v3, v6, v5
	v_fmac_f32_e32 v6, v7, v4
	v_fma_f32 v3, -v3, v6, v5
	v_div_fmas_f32 v3, v3, v4, v6
	v_div_fixup_f32 v87, v3, v2, 1.0
	ds_read_b128 v[2:5], v147
	ds_read_b128 v[6:9], v147 offset:64
	ds_read_b128 v[10:13], v147 offset:128
	ds_read_b128 v[14:17], v147 offset:192
	ds_read_b128 v[18:21], v147 offset:256
	ds_read_b128 v[22:25], v147 offset:320
	ds_read_b128 v[26:29], v147 offset:384
	ds_read_b128 v[30:33], v147 offset:448
	global_load_dwordx4 v[78:81], v[70:71], off
	global_load_dwordx4 v[88:91], v[70:71], off offset:64
	global_load_dwordx4 v[92:95], v[70:71], off offset:128
	global_load_dwordx4 v[96:99], v[70:71], off offset:192
	global_load_dwordx4 v[100:103], v[70:71], off offset:256
	global_load_dwordx4 v[104:107], v[70:71], off offset:320
	global_load_dwordx4 v[108:111], v[70:71], off offset:384
	global_load_dwordx4 v[112:115], v[70:71], off offset:448
	v_or_b32_e32 v36, v152, v150
	v_add_co_u32_e32 v62, vcc, s62, v70
	v_mad_u64_u32 v[74:75], s[8:9], v36, s51, v[34:35]
	s_nop 0
	v_addc_co_u32_e32 v63, vcc, 0, v71, vcc
	v_mad_i32_i24 v69, v153, s51, v69
	v_mad_i32_i24 v73, v153, s51, v73
	v_mad_i32_i24 v75, v153, s51, v75
	global_load_dwordx4 v[34:37], v[62:63], off
	global_load_dwordx4 v[38:41], v[62:63], off offset:64
	global_load_dwordx4 v[42:45], v[62:63], off offset:128
	global_load_dwordx4 v[46:49], v[62:63], off offset:192
	global_load_dwordx4 v[50:53], v[62:63], off offset:256
	global_load_dwordx4 v[54:57], v[62:63], off offset:320
	global_load_dwordx4 v[58:61], v[62:63], off offset:384
	s_nop 0
	global_load_dwordx4 v[62:65], v[62:63], off offset:448
	s_nop 0
	global_load_ushort v77, v[66:67], off
	global_load_ushort v116, v[68:69], off
	global_load_ushort v117, v[72:73], off
	global_load_ushort v118, v[74:75], off
	global_load_ushort v119, v[66:67], off offset:32
	global_load_ushort v120, v[68:69], off offset:32
	global_load_ushort v121, v[72:73], off offset:32
	global_load_ushort v122, v[74:75], off offset:32
	s_waitcnt vmcnt(0) lgkmcnt(0)
	v_mfma_f32_16x16x32_bf16 v[78:81], v[2:5], v[78:81], 0
	v_lshlrev_b32_e32 v77, 16, v77
	v_mfma_f32_16x16x32_bf16 v[78:81], v[6:9], v[88:91], v[78:81]
	v_mul_f32_e32 v88, 0xbfb8aa3b, v77
	v_exp_f32_e32 v88, v88
	v_mfma_f32_16x16x32_bf16 v[34:37], v[2:5], v[34:37], 0
	v_add_f32_e32 v88, 1.0, v88
	v_rcp_f32_e32 v88, v88
	v_mfma_f32_16x16x32_bf16 v[78:81], v[10:13], v[92:95], v[78:81]
	v_mul_f32_e32 v77, v88, v77
	v_mfma_f32_16x16x32_bf16 v[34:37], v[6:9], v[38:41], v[34:37]
	v_lshlrev_b32_e32 v38, 16, v119
	v_mul_f32_e32 v39, 0xbfb8aa3b, v38
	v_exp_f32_e32 v39, v39
	v_mfma_f32_16x16x32_bf16 v[78:81], v[14:17], v[96:99], v[78:81]
	v_add_f32_e32 v39, 1.0, v39
	v_mfma_f32_16x16x32_bf16 v[34:37], v[10:13], v[42:45], v[34:37]
	v_rcp_f32_e32 v39, v39
	s_nop 0
	v_mul_f32_e32 v38, v39, v38
	v_mfma_f32_16x16x32_bf16 v[78:81], v[18:21], v[100:103], v[78:81]
	v_mfma_f32_16x16x32_bf16 v[34:37], v[14:17], v[46:49], v[34:37]
	v_mfma_f32_16x16x32_bf16 v[78:81], v[22:25], v[104:107], v[78:81]
	v_mfma_f32_16x16x32_bf16 v[34:37], v[18:21], v[50:53], v[34:37]
	v_mfma_f32_16x16x32_bf16 v[78:81], v[26:29], v[108:111], v[78:81]
	v_mfma_f32_16x16x32_bf16 v[34:37], v[22:25], v[54:57], v[34:37]
	v_mfma_f32_16x16x32_bf16 v[80:83], v[30:33], v[112:115], v[78:81]
	v_mfma_f32_16x16x32_bf16 v[34:37], v[26:29], v[58:61], v[34:37]
	s_nop 4
	v_lshl_or_b32 v78, v130, 1, s52
	v_mov_b32_e32 v79, v1
	v_mul_f32_e32 v80, v84, v80
	v_lshl_add_u64 v[78:79], s[4:5], 0, v[78:79]
	v_mul_f32_e32 v77, v77, v80
	v_cvt_pk_bf16_f32 v80, v77, s0
	v_mad_u64_u32 v[76:77], s[8:9], v76, s17, v[78:79]
	v_mfma_f32_16x16x32_bf16 v[34:37], v[30:33], v[62:65], v[34:37]
	v_mad_i32_i24 v77, v153, s17, v77
	v_lshlrev_b32_e32 v79, 16, v116
	global_store_short v[76:77], v80, off
	v_mul_f32_e32 v80, 0xbfb8aa3b, v79
	v_exp_f32_e32 v80, v80
	s_nop 2
	v_mul_f32_e32 v34, v84, v34
	v_mul_f32_e32 v34, v38, v34
	v_cvt_pk_bf16_f32 v34, v34, s0
	v_add_f32_e32 v80, 1.0, v80
	global_store_short v[76:77], v34, off offset:32
	v_mul_f32_e32 v34, v85, v35
	v_lshlrev_b32_e32 v35, 16, v120
	v_rcp_f32_e32 v80, v80
	v_mul_f32_e32 v38, 0xbfb8aa3b, v35
	v_exp_f32_e32 v38, v38
	v_mul_f32_e32 v78, v85, v81
	v_mul_f32_e32 v79, v80, v79
	v_mul_f32_e32 v78, v79, v78
	v_add_f32_e32 v38, 1.0, v38
	v_cvt_pk_bf16_f32 v80, v78, s0
	v_add_co_u32_e32 v78, vcc, s15, v76
	v_rcp_f32_e32 v38, v38
	s_nop 0
	v_addc_co_u32_e32 v79, vcc, 0, v77, vcc
	v_lshlrev_b32_e32 v81, 16, v117
	global_store_short v[78:79], v80, off offset:1024
	v_mul_f32_e32 v80, v86, v82
	v_mul_f32_e32 v82, 0xbfb8aa3b, v81
	v_exp_f32_e32 v82, v82
	v_mul_f32_e32 v35, v38, v35
	v_mul_f32_e32 v34, v35, v34
	v_cvt_pk_bf16_f32 v34, v34, s0
	v_lshlrev_b32_e32 v35, 16, v121
	v_add_f32_e32 v82, 1.0, v82
	global_store_short v[78:79], v34, off offset:1056
	v_mul_f32_e32 v34, v86, v36
	v_mul_f32_e32 v36, 0xbfb8aa3b, v35
	v_rcp_f32_e32 v82, v82
	v_exp_f32_e32 v36, v36
	v_mul_f32_e32 v81, v82, v81
	v_add_f32_e32 v36, 1.0, v36
	v_mul_f32_e32 v80, v81, v80
	v_rcp_f32_e32 v36, v36
	v_cvt_pk_bf16_f32 v82, v80, s0
	v_add_co_u32_e32 v80, vcc, s62, v76
	v_mul_f32_e32 v35, v36, v35
	s_nop 0
	v_addc_co_u32_e32 v81, vcc, 0, v77, vcc
	global_store_short v[80:81], v82, off offset:2048
	v_mul_f32_e32 v82, v87, v83
	v_lshlrev_b32_e32 v83, 16, v118
	v_mul_f32_e32 v88, 0xbfb8aa3b, v83
	v_exp_f32_e32 v88, v88
	v_mul_f32_e32 v34, v35, v34
	v_lshlrev_b32_e32 v35, 16, v122
	v_mul_f32_e32 v36, 0xbfb8aa3b, v35
	v_exp_f32_e32 v36, v36
	v_add_f32_e32 v88, 1.0, v88
	v_rcp_f32_e32 v88, v88
	v_cvt_pk_bf16_f32 v34, v34, s0
	v_add_f32_e32 v36, 1.0, v36
	v_rcp_f32_e32 v36, v36
	v_mul_f32_e32 v83, v88, v83
	v_mul_f32_e32 v82, v83, v82
	v_cvt_pk_bf16_f32 v88, v82, s0
	v_add_co_u32_e32 v82, vcc, s16, v76
	global_store_short v[80:81], v34, off offset:2080
	v_mul_f32_e32 v34, v87, v37
	v_mul_f32_e32 v35, v36, v35
	v_addc_co_u32_e32 v83, vcc, 0, v77, vcc
	v_mul_f32_e32 v34, v35, v34
	v_cvt_pk_bf16_f32 v34, v34, s0
	v_add_co_u32_e32 v62, vcc, s10, v70
	global_store_short v[82:83], v88, off offset:3072
	global_store_short v[82:83], v34, off offset:3104
	v_addc_co_u32_e32 v63, vcc, 0, v71, vcc
	global_load_dwordx4 v[34:37], v[62:63], off
	global_load_dwordx4 v[38:41], v[62:63], off offset:64
	global_load_dwordx4 v[42:45], v[62:63], off offset:128
	global_load_dwordx4 v[46:49], v[62:63], off offset:192
	global_load_dwordx4 v[50:53], v[62:63], off offset:256
	global_load_dwordx4 v[54:57], v[62:63], off offset:320
	global_load_dwordx4 v[58:61], v[62:63], off offset:384
	s_nop 0
	global_load_dwordx4 v[62:65], v[62:63], off offset:448
	v_add_co_u32_e32 v116, vcc, s11, v70
	s_waitcnt vmcnt(0) lgkmcnt(0)
; __device__ __forceinline__ float bf2f(u16 h) { return __uint_as_float(((unsigned)h) << 16); }
; __device__ __forceinline__ u16 f2bf(float f) { return (u16)(pack2(f, 0.f) & 0xffffu); }
; __device__ __forceinline__ float siluf(float x) { return x * __builtin_amdgcn_rcpf(1.f + __expf(-x)); }
;     ...
; #pragma unroll
;     for (int db = 0; db < 4; ++db) {
;       bf16x8 bv[2][8];
;       u16 gt[2][4];
; #pragma unroll
;       for (int d2 = 0; d2 < 2; ++d2) {
; #pragma unroll
;         for (int ks = 0; ks < 8; ++ks)
;           bv[d2][ks] = *(const bf16x8*)(VT + (long)(h * 128 + (db * 2 + d2) * 16 + fr) * 512 + b * 256 + ks * 32 + fq * 8);
; #pragma unroll
;         for (int r = 0; r < 4; ++r) gt[d2][r] = qg[(t0 + fq * 4 + r) * ldq + gcol + h * 128 + (db * 2 + d2) * 16 + fr];
;       }
;       asm volatile("" ::: "memory");
; #pragma unroll
;       for (int d2 = 0; d2 < 2; ++d2) {
;         f32x4 a = {0.f, 0.f, 0.f, 0.f};
; #pragma unroll
;         for (int ks = 0; ks < 8; ++ks) a = __builtin_amdgcn_mfma_f32_16x16x32_bf16(aP[ks], bv[d2][ks], a, 0, 0, 0);
; #pragma unroll
;         for (int r = 0; r < 4; ++r) {
;           long row = t0 + fq * 4 + r;
;           int dcol = h * 128 + (db * 2 + d2) * 16 + fr;
;           og[row * ldo + ocol + dcol] = f2bf(a[r] * sm[r] * siluf(bf2f(gt[d2][r])));
;         }
;       }
	v_mfma_f32_16x16x32_bf16 v[34:37], v[2:5], v[34:37], 0
	v_addc_co_u32_e32 v117, vcc, 0, v71, vcc
	global_load_dwordx4 v[88:91], v[116:117], off
	global_load_dwordx4 v[92:95], v[116:117], off offset:64
	global_load_dwordx4 v[96:99], v[116:117], off offset:128
	global_load_dwordx4 v[100:103], v[116:117], off offset:192
	global_load_dwordx4 v[104:107], v[116:117], off offset:256
	global_load_dwordx4 v[108:111], v[116:117], off offset:320
	global_load_dwordx4 v[112:115], v[116:117], off offset:384
	s_nop 0
	global_load_dwordx4 v[116:119], v[116:117], off offset:448
	s_nop 0
	global_load_ushort v120, v[66:67], off offset:64
	global_load_ushort v121, v[68:69], off offset:64
	global_load_ushort v122, v[72:73], off offset:64
	global_load_ushort v123, v[74:75], off offset:64
	global_load_ushort v124, v[66:67], off offset:96
	global_load_ushort v125, v[68:69], off offset:96
	global_load_ushort v126, v[72:73], off offset:96
	global_load_ushort v127, v[74:75], off offset:96
	v_mfma_f32_16x16x32_bf16 v[34:37], v[6:9], v[38:41], v[34:37]
	s_waitcnt vmcnt(0) lgkmcnt(0)
	v_lshlrev_b32_e32 v38, 16, v120
	v_mfma_f32_16x16x32_bf16 v[34:37], v[10:13], v[42:45], v[34:37]
	v_mul_f32_e32 v39, 0xbfb8aa3b, v38
	v_exp_f32_e32 v39, v39
	v_mfma_f32_16x16x32_bf16 v[34:37], v[14:17], v[46:49], v[34:37]
	v_add_f32_e32 v39, 1.0, v39
	v_rcp_f32_e32 v39, v39
	v_mfma_f32_16x16x32_bf16 v[34:37], v[18:21], v[50:53], v[34:37]
	v_mul_f32_e32 v38, v39, v38
	v_mfma_f32_16x16x32_bf16 v[34:37], v[22:25], v[54:57], v[34:37]
	v_mfma_f32_16x16x32_bf16 v[34:37], v[26:29], v[58:61], v[34:37]
	v_mfma_f32_16x16x32_bf16 v[34:37], v[30:33], v[62:65], v[34:37]
	v_add_co_u32_e32 v62, vcc, s12, v70
	s_nop 1
	v_addc_co_u32_e32 v63, vcc, 0, v71, vcc
	s_nop 3
	v_mul_f32_e32 v34, v84, v34
	v_mul_f32_e32 v34, v38, v34
	v_cvt_pk_bf16_f32 v34, v34, s0
	global_store_short v[76:77], v34, off offset:64
	v_mul_f32_e32 v34, v85, v35
	v_lshlrev_b32_e32 v35, 16, v121
	v_mul_f32_e32 v38, 0xbfb8aa3b, v35
	v_exp_f32_e32 v38, v38
	s_nop 0
	v_add_f32_e32 v38, 1.0, v38
	v_rcp_f32_e32 v38, v38
	s_nop 0
	v_mul_f32_e32 v35, v38, v35
	v_mul_f32_e32 v34, v35, v34
	v_cvt_pk_bf16_f32 v34, v34, s0
	v_lshlrev_b32_e32 v35, 16, v122
	global_store_short v[78:79], v34, off offset:1088
	v_mul_f32_e32 v34, v86, v36
	v_mul_f32_e32 v36, 0xbfb8aa3b, v35
	v_exp_f32_e32 v36, v36
	v_lshlrev_b32_e32 v38, 16, v124
	v_mul_f32_e32 v39, 0xbfb8aa3b, v38
	v_exp_f32_e32 v39, v39
	v_add_f32_e32 v36, 1.0, v36
	v_rcp_f32_e32 v36, v36
	v_add_f32_e32 v39, 1.0, v39
	v_rcp_f32_e32 v39, v39
	v_mul_f32_e32 v35, v36, v35
	v_mul_f32_e32 v34, v35, v34
	v_lshlrev_b32_e32 v35, 16, v123
	v_mul_f32_e32 v36, 0xbfb8aa3b, v35
	v_exp_f32_e32 v36, v36
	v_cvt_pk_bf16_f32 v34, v34, s0
	global_store_short v[80:81], v34, off offset:2112
	v_mul_f32_e32 v34, v87, v37
	v_add_f32_e32 v36, 1.0, v36
	v_rcp_f32_e32 v36, v36
	v_mul_f32_e32 v38, v39, v38
	v_mul_f32_e32 v35, v36, v35
	v_mul_f32_e32 v34, v35, v34
	v_cvt_pk_bf16_f32 v34, v34, s0
	global_store_short v[82:83], v34, off offset:3136
	v_mfma_f32_16x16x32_bf16 v[34:37], v[2:5], v[88:91], 0
	v_mfma_f32_16x16x32_bf16 v[34:37], v[6:9], v[92:95], v[34:37]
	v_mfma_f32_16x16x32_bf16 v[34:37], v[10:13], v[96:99], v[34:37]
	v_mfma_f32_16x16x32_bf16 v[34:37], v[14:17], v[100:103], v[34:37]
	v_mfma_f32_16x16x32_bf16 v[34:37], v[18:21], v[104:107], v[34:37]
	v_mfma_f32_16x16x32_bf16 v[34:37], v[22:25], v[108:111], v[34:37]
	v_mfma_f32_16x16x32_bf16 v[34:37], v[26:29], v[112:115], v[34:37]
	v_mfma_f32_16x16x32_bf16 v[34:37], v[30:33], v[116:119], v[34:37]
	v_add_co_u32_e32 v116, vcc, s13, v70
	s_nop 1
	v_addc_co_u32_e32 v117, vcc, 0, v71, vcc
	s_nop 3
	v_mul_f32_e32 v34, v84, v34
	v_mul_f32_e32 v34, v38, v34
	v_cvt_pk_bf16_f32 v34, v34, s0
	global_store_short v[76:77], v34, off offset:96
	v_mul_f32_e32 v34, v85, v35
	v_lshlrev_b32_e32 v35, 16, v125
	v_mul_f32_e32 v38, 0xbfb8aa3b, v35
	v_exp_f32_e32 v38, v38
	s_nop 0
	v_add_f32_e32 v38, 1.0, v38
	v_rcp_f32_e32 v38, v38
	s_nop 0
	v_mul_f32_e32 v35, v38, v35
	v_mul_f32_e32 v34, v35, v34
	v_cvt_pk_bf16_f32 v34, v34, s0
	v_lshlrev_b32_e32 v35, 16, v126
	global_store_short v[78:79], v34, off offset:1120
	v_mul_f32_e32 v34, v86, v36
	v_mul_f32_e32 v36, 0xbfb8aa3b, v35
	v_exp_f32_e32 v36, v36
	s_nop 0
	v_add_f32_e32 v36, 1.0, v36
	v_rcp_f32_e32 v36, v36
	s_nop 0
	v_mul_f32_e32 v35, v36, v35
	v_mul_f32_e32 v34, v35, v34
	v_lshlrev_b32_e32 v35, 16, v127
	v_mul_f32_e32 v36, 0xbfb8aa3b, v35
	v_exp_f32_e32 v36, v36
	v_cvt_pk_bf16_f32 v34, v34, s0
	global_store_short v[80:81], v34, off offset:2144
	v_mul_f32_e32 v34, v87, v37
	v_add_f32_e32 v36, 1.0, v36
	v_rcp_f32_e32 v36, v36
	s_nop 0
	v_mul_f32_e32 v35, v36, v35
	v_mul_f32_e32 v34, v35, v34
	v_cvt_pk_bf16_f32 v34, v34, s0
	global_store_short v[82:83], v34, off offset:3168
	global_load_dwordx4 v[34:37], v[62:63], off
	s_nop 0
	global_load_dwordx4 v[38:41], v[62:63], off offset:64
	global_load_dwordx4 v[42:45], v[62:63], off offset:128
	global_load_dwordx4 v[46:49], v[62:63], off offset:192
	global_load_dwordx4 v[50:53], v[62:63], off offset:256
	global_load_dwordx4 v[54:57], v[62:63], off offset:320
	global_load_dwordx4 v[58:61], v[62:63], off offset:384
	s_nop 0
	global_load_dwordx4 v[62:65], v[62:63], off offset:448
	s_nop 0
	global_load_dwordx4 v[88:91], v[116:117], off
	global_load_dwordx4 v[92:95], v[116:117], off offset:64
	global_load_dwordx4 v[96:99], v[116:117], off offset:128
	global_load_dwordx4 v[100:103], v[116:117], off offset:192
	global_load_dwordx4 v[104:107], v[116:117], off offset:256
	global_load_dwordx4 v[108:111], v[116:117], off offset:320
	global_load_dwordx4 v[112:115], v[116:117], off offset:384
	s_nop 0
	global_load_dwordx4 v[116:119], v[116:117], off offset:448
	s_nop 0
	global_load_ushort v120, v[66:67], off offset:128
	global_load_ushort v121, v[68:69], off offset:128
	global_load_ushort v122, v[72:73], off offset:128
	global_load_ushort v123, v[74:75], off offset:128
	global_load_ushort v124, v[66:67], off offset:160
	global_load_ushort v125, v[68:69], off offset:160
	global_load_ushort v126, v[72:73], off offset:160
	global_load_ushort v127, v[74:75], off offset:160
	s_waitcnt vmcnt(0) lgkmcnt(0)
; __device__ __forceinline__ float bf2f(u16 h) { return __uint_as_float(((unsigned)h) << 16); }
; __device__ __forceinline__ u16 f2bf(float f) { return (u16)(pack2(f, 0.f) & 0xffffu); }
; __device__ __forceinline__ float siluf(float x) { return x * __builtin_amdgcn_rcpf(1.f + __expf(-x)); }
;     ...
; #pragma unroll
;     for (int db = 0; db < 4; ++db) {
;       bf16x8 bv[2][8];
;       u16 gt[2][4];
; #pragma unroll
;       for (int d2 = 0; d2 < 2; ++d2) {
; #pragma unroll
;         for (int ks = 0; ks < 8; ++ks)
;           bv[d2][ks] = *(const bf16x8*)(VT + (long)(h * 128 + (db * 2 + d2) * 16 + fr) * 512 + b * 256 + ks * 32 + fq * 8);
; #pragma unroll
;         for (int r = 0; r < 4; ++r) gt[d2][r] = qg[(t0 + fq * 4 + r) * ldq + gcol + h * 128 + (db * 2 + d2) * 16 + fr];
;       }
;       asm volatile("" ::: "memory");
; #pragma unroll
;       for (int d2 = 0; d2 < 2; ++d2) {
;         f32x4 a = {0.f, 0.f, 0.f, 0.f};
; #pragma unroll
;         for (int ks = 0; ks < 8; ++ks) a = __builtin_amdgcn_mfma_f32_16x16x32_bf16(aP[ks], bv[d2][ks], a, 0, 0, 0);
; #pragma unroll
;         for (int r = 0; r < 4; ++r) {
;           long row = t0 + fq * 4 + r;
;           int dcol = h * 128 + (db * 2 + d2) * 16 + fr;
;           og[row * ldo + ocol + dcol] = f2bf(a[r] * sm[r] * siluf(bf2f(gt[d2][r])));
;         }
;       }
	v_mfma_f32_16x16x32_bf16 v[34:37], v[2:5], v[34:37], 0
	v_mfma_f32_16x16x32_bf16 v[34:37], v[6:9], v[38:41], v[34:37]
	v_lshlrev_b32_e32 v38, 16, v120
	v_mul_f32_e32 v39, 0xbfb8aa3b, v38
	v_exp_f32_e32 v39, v39
	v_mfma_f32_16x16x32_bf16 v[34:37], v[10:13], v[42:45], v[34:37]
	v_add_f32_e32 v39, 1.0, v39
	v_mfma_f32_16x16x32_bf16 v[34:37], v[14:17], v[46:49], v[34:37]
	v_rcp_f32_e32 v39, v39
	s_nop 0
	v_mul_f32_e32 v38, v39, v38
	v_mfma_f32_16x16x32_bf16 v[34:37], v[18:21], v[50:53], v[34:37]
	v_mfma_f32_16x16x32_bf16 v[34:37], v[22:25], v[54:57], v[34:37]
	v_mfma_f32_16x16x32_bf16 v[34:37], v[26:29], v[58:61], v[34:37]
	v_mfma_f32_16x16x32_bf16 v[34:37], v[30:33], v[62:65], v[34:37]
	v_add_co_u32_e32 v62, vcc, s87, v70
	s_nop 1
	v_addc_co_u32_e32 v63, vcc, 0, v71, vcc
	v_add_co_u32_e32 v70, vcc, s14, v70
	s_nop 2
	v_mul_f32_e32 v34, v84, v34
	v_mul_f32_e32 v34, v38, v34
	v_cvt_pk_bf16_f32 v34, v34, s0
	global_store_short v[76:77], v34, off offset:128
	v_mul_f32_e32 v34, v85, v35
	v_lshlrev_b32_e32 v35, 16, v121
	v_mul_f32_e32 v38, 0xbfb8aa3b, v35
	v_exp_f32_e32 v38, v38
	v_addc_co_u32_e32 v71, vcc, 0, v71, vcc
	v_add_f32_e32 v38, 1.0, v38
	v_rcp_f32_e32 v38, v38
	s_nop 0
	v_mul_f32_e32 v35, v38, v35
	v_mul_f32_e32 v34, v35, v34
	v_cvt_pk_bf16_f32 v34, v34, s0
	v_lshlrev_b32_e32 v35, 16, v122
	global_store_short v[78:79], v34, off offset:1152
	v_mul_f32_e32 v34, v86, v36
	v_mul_f32_e32 v36, 0xbfb8aa3b, v35
	v_exp_f32_e32 v36, v36
	v_lshlrev_b32_e32 v38, 16, v124
	v_mul_f32_e32 v39, 0xbfb8aa3b, v38
	v_exp_f32_e32 v39, v39
	v_add_f32_e32 v36, 1.0, v36
	v_rcp_f32_e32 v36, v36
	v_add_f32_e32 v39, 1.0, v39
	v_rcp_f32_e32 v39, v39
	v_mul_f32_e32 v35, v36, v35
	v_mul_f32_e32 v34, v35, v34
	v_lshlrev_b32_e32 v35, 16, v123
	v_mul_f32_e32 v36, 0xbfb8aa3b, v35
	v_exp_f32_e32 v36, v36
	v_cvt_pk_bf16_f32 v34, v34, s0
	global_store_short v[80:81], v34, off offset:2176
	v_mul_f32_e32 v34, v87, v37
	v_add_f32_e32 v36, 1.0, v36
	v_rcp_f32_e32 v36, v36
	v_mul_f32_e32 v38, v39, v38
	v_mul_f32_e32 v35, v36, v35
	v_mul_f32_e32 v34, v35, v34
	v_cvt_pk_bf16_f32 v34, v34, s0
	global_store_short v[82:83], v34, off offset:3200
	v_mfma_f32_16x16x32_bf16 v[34:37], v[2:5], v[88:91], 0
	v_mfma_f32_16x16x32_bf16 v[34:37], v[6:9], v[92:95], v[34:37]
	v_mfma_f32_16x16x32_bf16 v[34:37], v[10:13], v[96:99], v[34:37]
	v_mfma_f32_16x16x32_bf16 v[34:37], v[14:17], v[100:103], v[34:37]
	v_mfma_f32_16x16x32_bf16 v[34:37], v[18:21], v[104:107], v[34:37]
	v_mfma_f32_16x16x32_bf16 v[34:37], v[22:25], v[108:111], v[34:37]
	v_mfma_f32_16x16x32_bf16 v[34:37], v[26:29], v[112:115], v[34:37]
	v_mfma_f32_16x16x32_bf16 v[34:37], v[30:33], v[116:119], v[34:37]
	s_nop 7
	v_mul_f32_e32 v34, v84, v34
	v_mul_f32_e32 v34, v38, v34
	v_cvt_pk_bf16_f32 v34, v34, s0
	global_store_short v[76:77], v34, off offset:160
	v_mul_f32_e32 v34, v85, v35
	v_lshlrev_b32_e32 v35, 16, v125
	v_mul_f32_e32 v38, 0xbfb8aa3b, v35
	v_exp_f32_e32 v38, v38
	s_nop 0
	v_add_f32_e32 v38, 1.0, v38
	v_rcp_f32_e32 v38, v38
	s_nop 0
	v_mul_f32_e32 v35, v38, v35
	v_mul_f32_e32 v34, v35, v34
	v_cvt_pk_bf16_f32 v34, v34, s0
	v_lshlrev_b32_e32 v35, 16, v126
	global_store_short v[78:79], v34, off offset:1184
	v_mul_f32_e32 v34, v86, v36
	v_mul_f32_e32 v36, 0xbfb8aa3b, v35
	v_exp_f32_e32 v36, v36
	s_nop 0
	v_add_f32_e32 v36, 1.0, v36
	v_rcp_f32_e32 v36, v36
	s_nop 0
	v_mul_f32_e32 v35, v36, v35
	v_mul_f32_e32 v34, v35, v34
	v_lshlrev_b32_e32 v35, 16, v127
	v_mul_f32_e32 v36, 0xbfb8aa3b, v35
	v_exp_f32_e32 v36, v36
	v_cvt_pk_bf16_f32 v34, v34, s0
	global_store_short v[80:81], v34, off offset:2208
	v_mul_f32_e32 v34, v87, v37
	v_add_f32_e32 v36, 1.0, v36
	v_rcp_f32_e32 v36, v36
	s_nop 0
	v_mul_f32_e32 v35, v36, v35
	v_mul_f32_e32 v34, v35, v34
	v_cvt_pk_bf16_f32 v34, v34, s0
	global_store_short v[82:83], v34, off offset:3232
	global_load_dwordx4 v[34:37], v[62:63], off
	s_nop 0
	global_load_dwordx4 v[38:41], v[62:63], off offset:64
	global_load_dwordx4 v[42:45], v[62:63], off offset:128
	global_load_dwordx4 v[46:49], v[62:63], off offset:192
	global_load_dwordx4 v[50:53], v[62:63], off offset:256
	global_load_dwordx4 v[54:57], v[62:63], off offset:320
	global_load_dwordx4 v[58:61], v[62:63], off offset:384
	s_nop 0
	global_load_dwordx4 v[62:65], v[62:63], off offset:448
	s_nop 0
	global_load_dwordx4 v[88:91], v[70:71], off
	global_load_dwordx4 v[92:95], v[70:71], off offset:64
	global_load_dwordx4 v[96:99], v[70:71], off offset:128
	global_load_dwordx4 v[100:103], v[70:71], off offset:192
	global_load_dwordx4 v[104:107], v[70:71], off offset:256
	global_load_dwordx4 v[108:111], v[70:71], off offset:320
	global_load_dwordx4 v[112:115], v[70:71], off offset:384
	global_load_dwordx4 v[116:119], v[70:71], off offset:448
	s_nop 0
	global_load_ushort v70, v[66:67], off offset:192
	global_load_ushort v71, v[68:69], off offset:192
	global_load_ushort v120, v[72:73], off offset:192
	global_load_ushort v121, v[74:75], off offset:192
	s_nop 0
	global_load_ushort v66, v[66:67], off offset:224
	s_nop 0
	global_load_ushort v67, v[68:69], off offset:224
	s_nop 0
	global_load_ushort v68, v[72:73], off offset:224
	global_load_ushort v69, v[74:75], off offset:224
	s_waitcnt vmcnt(0) lgkmcnt(0)
; __device__ __forceinline__ float bf2f(u16 h) { return __uint_as_float(((unsigned)h) << 16); }
; __device__ __forceinline__ u16 f2bf(float f) { return (u16)(pack2(f, 0.f) & 0xffffu); }
; __device__ __forceinline__ float siluf(float x) { return x * __builtin_amdgcn_rcpf(1.f + __expf(-x)); }
;     ...
; #pragma unroll
;     for (int db = 0; db < 4; ++db) {
;       bf16x8 bv[2][8];
;       u16 gt[2][4];
; #pragma unroll
;       for (int d2 = 0; d2 < 2; ++d2) {
; #pragma unroll
;         for (int ks = 0; ks < 8; ++ks)
;           bv[d2][ks] = *(const bf16x8*)(VT + (long)(h * 128 + (db * 2 + d2) * 16 + fr) * 512 + b * 256 + ks * 32 + fq * 8);
; #pragma unroll
;         for (int r = 0; r < 4; ++r) gt[d2][r] = qg[(t0 + fq * 4 + r) * ldq + gcol + h * 128 + (db * 2 + d2) * 16 + fr];
;       }
;       asm volatile("" ::: "memory");
; #pragma unroll
;       for (int d2 = 0; d2 < 2; ++d2) {
;         f32x4 a = {0.f, 0.f, 0.f, 0.f};
; #pragma unroll
;         for (int ks = 0; ks < 8; ++ks) a = __builtin_amdgcn_mfma_f32_16x16x32_bf16(aP[ks], bv[d2][ks], a, 0, 0, 0);
; #pragma unroll
;         for (int r = 0; r < 4; ++r) {
;           long row = t0 + fq * 4 + r;
;           int dcol = h * 128 + (db * 2 + d2) * 16 + fr;
;           og[row * ldo + ocol + dcol] = f2bf(a[r] * sm[r] * siluf(bf2f(gt[d2][r])));
;         }
;       }
	v_mfma_f32_16x16x32_bf16 v[34:37], v[2:5], v[34:37], 0
	v_mfma_f32_16x16x32_bf16 v[2:5], v[2:5], v[88:91], 0
	v_mfma_f32_16x16x32_bf16 v[34:37], v[6:9], v[38:41], v[34:37]
	v_lshlrev_b32_e32 v38, 16, v70
	v_mul_f32_e32 v39, 0xbfb8aa3b, v38
	v_exp_f32_e32 v39, v39
	v_mfma_f32_16x16x32_bf16 v[2:5], v[6:9], v[92:95], v[2:5]
	v_lshlrev_b32_e32 v6, 16, v66
	v_mul_f32_e32 v7, 0xbfb8aa3b, v6
	v_exp_f32_e32 v7, v7
	v_mfma_f32_16x16x32_bf16 v[34:37], v[10:13], v[42:45], v[34:37]
	v_add_f32_e32 v39, 1.0, v39
	v_rcp_f32_e32 v39, v39
	v_add_f32_e32 v7, 1.0, v7
	v_mfma_f32_16x16x32_bf16 v[2:5], v[10:13], v[96:99], v[2:5]
	v_rcp_f32_e32 v7, v7
	v_mul_f32_e32 v38, v39, v38
	v_mul_f32_e32 v6, v7, v6
	v_mfma_f32_16x16x32_bf16 v[34:37], v[14:17], v[46:49], v[34:37]
	v_mfma_f32_16x16x32_bf16 v[2:5], v[14:17], v[100:103], v[2:5]
	v_mfma_f32_16x16x32_bf16 v[34:37], v[18:21], v[50:53], v[34:37]
	v_mfma_f32_16x16x32_bf16 v[2:5], v[18:21], v[104:107], v[2:5]
	v_mfma_f32_16x16x32_bf16 v[34:37], v[22:25], v[54:57], v[34:37]
	v_mfma_f32_16x16x32_bf16 v[2:5], v[22:25], v[108:111], v[2:5]
	v_mfma_f32_16x16x32_bf16 v[34:37], v[26:29], v[58:61], v[34:37]
	v_mfma_f32_16x16x32_bf16 v[2:5], v[26:29], v[112:115], v[2:5]
	v_mfma_f32_16x16x32_bf16 v[34:37], v[30:33], v[62:65], v[34:37]
	v_mfma_f32_16x16x32_bf16 v[2:5], v[30:33], v[116:119], v[2:5]
	s_nop 6
	v_mul_f32_e32 v34, v84, v34
	v_mul_f32_e32 v2, v84, v2
	v_mul_f32_e32 v34, v38, v34
	v_mul_f32_e32 v2, v6, v2
	v_cvt_pk_bf16_f32 v34, v34, s0
	v_cvt_pk_bf16_f32 v2, v2, s0
	global_store_short v[76:77], v34, off offset:192
	v_mul_f32_e32 v34, v85, v35
	v_lshlrev_b32_e32 v35, 16, v71
	global_store_short v[76:77], v2, off offset:224
	v_mul_f32_e32 v2, v85, v3
	v_lshlrev_b32_e32 v3, 16, v67
	v_mul_f32_e32 v38, 0xbfb8aa3b, v35
	v_mul_f32_e32 v6, 0xbfb8aa3b, v3
	v_exp_f32_e32 v38, v38
	v_exp_f32_e32 v6, v6
	v_add_f32_e32 v38, 1.0, v38
	v_add_f32_e32 v6, 1.0, v6
	v_rcp_f32_e32 v38, v38
	v_rcp_f32_e32 v6, v6
	v_mul_f32_e32 v35, v38, v35
	v_mul_f32_e32 v3, v6, v3
	v_mul_f32_e32 v34, v35, v34
	v_mul_f32_e32 v2, v3, v2
	v_cvt_pk_bf16_f32 v34, v34, s0
	v_lshlrev_b32_e32 v35, 16, v120
	v_cvt_pk_bf16_f32 v2, v2, s0
	v_lshlrev_b32_e32 v3, 16, v68
	global_store_short v[78:79], v34, off offset:1216
	v_mul_f32_e32 v34, v86, v36
	v_mul_f32_e32 v36, 0xbfb8aa3b, v35
	global_store_short v[78:79], v2, off offset:1248
	v_mul_f32_e32 v2, v86, v4
	v_mul_f32_e32 v4, 0xbfb8aa3b, v3
	v_exp_f32_e32 v36, v36
	v_exp_f32_e32 v4, v4
	v_add_f32_e32 v36, 1.0, v36
	v_add_f32_e32 v4, 1.0, v4
	v_rcp_f32_e32 v36, v36
	v_rcp_f32_e32 v4, v4
	v_mul_f32_e32 v35, v36, v35
	v_mul_f32_e32 v3, v4, v3
	v_mul_f32_e32 v34, v35, v34
	v_lshlrev_b32_e32 v35, 16, v121
	v_mul_f32_e32 v2, v3, v2
	v_lshlrev_b32_e32 v3, 16, v69
	v_mul_f32_e32 v36, 0xbfb8aa3b, v35
	v_mul_f32_e32 v4, 0xbfb8aa3b, v3
	v_exp_f32_e32 v36, v36
	v_exp_f32_e32 v4, v4
	v_cvt_pk_bf16_f32 v34, v34, s0
	v_cvt_pk_bf16_f32 v2, v2, s0
	v_add_f32_e32 v36, 1.0, v36
	v_add_f32_e32 v4, 1.0, v4
	v_rcp_f32_e32 v36, v36
	v_rcp_f32_e32 v4, v4
	global_store_short v[80:81], v34, off offset:2240
	v_mul_f32_e32 v34, v87, v37
	v_mul_f32_e32 v35, v36, v35
	global_store_short v[80:81], v2, off offset:2272
	v_mul_f32_e32 v2, v87, v5
	v_mul_f32_e32 v3, v4, v3
	v_mul_f32_e32 v34, v35, v34
	v_mul_f32_e32 v2, v3, v2
	v_cvt_pk_bf16_f32 v34, v34, s0
	v_cvt_pk_bf16_f32 v2, v2, s0
	global_store_short v[82:83], v34, off offset:3264
	global_store_short v[82:83], v2, off offset:3296
	s_cbranch_scc0 .LBB0_271

; __device__ __forceinline__ int ltid() { int t = threadIdx.x; asm volatile("" : "+v"(t)); return t; }
; __device__ __forceinline__ void emit_tr(const float* stage, u16* dst, long ld) {
;   const int tid = ltid(), lane = tid & 63, w = tid >> 6;
; #pragma unroll 1
;   for (int ps = 0; ps < 8; ++ps) {
;     const int wp = ps * 8 + w;
;     const int col = (wp & 15) * 16 + (lane & 15), rg = (wp >> 4) * 4 + (lane >> 4);
;     const float* s = stage + (rg * 8) * SP + col;
;     uint4 o; o.x = pack2(s[0], s[SP]); o.y = pack2(s[2 * SP], s[3 * SP]); o.z = pack2(s[4 * SP], s[5 * SP]); o.w = pack2(s[6 * SP], s[7 * SP]);
;     *(uint4*)(dst + (long)col * ld + rg * 8) = o;
;   }
; }
.LBB0_288:
	v_add_u32_e32 v0, s20, v2
	v_and_or_b32 v70, v69, s91, v3
	v_ashrrev_i32_e32 v71, 2, v0
	v_lshlrev_b32_e32 v0, 10, v70
	v_and_or_b32 v74, v71, -4, v68
	v_lshlrev_b32_e32 v73, 2, v70
	v_lshl_add_u64 v[70:71], s[6:7], 0, v[0:1]
	v_mul_lo_u32 v0, v74, s39
	v_add3_u32 v0, 16, v0, v73
	ds_read_b32 v76, v0
	ds_read_b32 v77, v0 offset:1040
	ds_read_b32 v78, v0 offset:2080
	ds_read_b32 v79, v0 offset:3120
	ds_read_b32 v80, v0 offset:4160
	ds_read_b32 v81, v0 offset:5200
	ds_read_b32 v82, v0 offset:6240
	ds_read_b32 v0, v0 offset:7280
	v_lshlrev_b32_e32 v72, 3, v74
	s_add_i32 s20, s20, 8
	v_ashrrev_i32_e32 v73, 31, v72
	v_add_u32_e32 v69, 0x80, v69
	s_cmp_lg_u32 s20, 64
	v_lshl_add_u64 v[74:75], v[72:73], 1, v[70:71]
	s_waitcnt lgkmcnt(0)
	v_cvt_pk_bf16_f32 v70, v76, v77
	s_waitcnt lgkmcnt(4)
	v_cvt_pk_bf16_f32 v71, v78, v79
	s_waitcnt lgkmcnt(2)
	v_cvt_pk_bf16_f32 v72, v80, v81
	s_waitcnt lgkmcnt(0)
	v_cvt_pk_bf16_f32 v73, v82, v0
	global_store_dwordx4 v[74:75], v[70:73], off
	s_cbranch_scc1 .LBB0_288
	s_mov_b64 s[6:7], 0

; __device__ __forceinline__ int ltid() { int t = threadIdx.x; asm volatile("" : "+v"(t)); return t; }
; __device__ __forceinline__ void emit_rm(const float* stage, u16* dst, long ld, const float* rs) {
;   const int tid = ltid(), c4 = (tid & 31) * 4, rr = tid >> 5;
; #pragma unroll 1
;   for (int ps = 0; ps < 8; ++ps) {
;     const int r = ps * 16 + rr;
;     const float* s = stage + r * SP + c4;
;     const float4 a = *(const float4*)s, b = *(const float4*)(s + 128);
;     const float f = rs ? rs[r] : 1.f;
;     uint2 o0, o1;
;     o0.x = pack2(a.x * f, a.y * f); o0.y = pack2(a.z * f, a.w * f);
;     o1.x = pack2(b.x * f, b.y * f); o1.y = pack2(b.z * f, b.w * f);
;     *(uint2*)(dst + (long)r * ld + c4) = o0;
;     *(uint2*)(dst + (long)r * ld + 128 + c4) = o1;
;   }
; }
.LBB0_292:
	ds_read_b128 v[68:71], v0
	ds_read_b128 v[72:75], v0 offset:512
	v_add_u32_e32 v0, 0x4100, v0
	s_waitcnt lgkmcnt(0)
	v_cvt_pk_bf16_f32 v68, v68, v69
	v_cvt_pk_bf16_f32 v69, v70, v71
	v_cvt_pk_bf16_f32 v70, v72, v73
	v_lshl_add_u64 v[72:73], v[2:3], 0, s[6:7]
	s_add_u32 s6, s6, 0x4000
	v_add_co_u32_e32 v72, vcc, s40, v72
	s_addc_u32 s7, s7, 0
	s_nop 0
	v_addc_co_u32_e32 v73, vcc, 0, v73, vcc
	s_cmp_eq_u32 s6, 0x20000
	v_cvt_pk_bf16_f32 v71, v74, v75
	global_store_dwordx2 v[72:73], v[68:69], off
	global_store_dwordx2 v[72:73], v[70:71], off offset:256
	s_cbranch_scc0 .LBB0_292

; __device__ __forceinline__ int ltid() { int t = threadIdx.x; asm volatile("" : "+v"(t)); return t; }
; __device__ __forceinline__ void emit_tr(const float* stage, u16* dst, long ld) {
;   const int tid = ltid(), lane = tid & 63, w = tid >> 6;
; #pragma unroll 1
;   for (int ps = 0; ps < 8; ++ps) {
;     const int wp = ps * 8 + w;
;     const int col = (wp & 15) * 16 + (lane & 15), rg = (wp >> 4) * 4 + (lane >> 4);
;     const float* s = stage + (rg * 8) * SP + col;
;     uint4 o; o.x = pack2(s[0], s[SP]); o.y = pack2(s[2 * SP], s[3 * SP]); o.z = pack2(s[4 * SP], s[5 * SP]); o.w = pack2(s[6 * SP], s[7 * SP]);
;     *(uint4*)(dst + (long)col * ld + rg * 8) = o;
;   }
; }
.LBB0_295:
	v_add_u32_e32 v0, s6, v2
	v_and_or_b32 v6, v5, s91, v3
	v_ashrrev_i32_e32 v7, 2, v0
	v_lshlrev_b32_e32 v0, 10, v6
	v_and_or_b32 v10, v7, -4, v4
	v_lshlrev_b32_e32 v9, 2, v6
	v_lshl_add_u64 v[6:7], s[4:5], 0, v[0:1]
	v_mul_lo_u32 v0, v10, s39
	v_add3_u32 v0, 16, v0, v9
	ds_read_b32 v12, v0
	ds_read_b32 v13, v0 offset:1040
	ds_read_b32 v14, v0 offset:2080
	ds_read_b32 v15, v0 offset:3120
	ds_read_b32 v16, v0 offset:4160
	ds_read_b32 v17, v0 offset:5200
	ds_read_b32 v18, v0 offset:6240
	ds_read_b32 v0, v0 offset:7280
	v_lshlrev_b32_e32 v8, 3, v10
	s_add_i32 s6, s6, 8
	v_ashrrev_i32_e32 v9, 31, v8
	v_add_u32_e32 v5, 0x80, v5
	s_cmp_lg_u32 s6, 64
	v_lshl_add_u64 v[10:11], v[8:9], 1, v[6:7]
	s_waitcnt lgkmcnt(0)
	v_cvt_pk_bf16_f32 v6, v12, v13
	v_cvt_pk_bf16_f32 v7, v14, v15
	v_cvt_pk_bf16_f32 v8, v16, v17
	v_cvt_pk_bf16_f32 v9, v18, v0
	global_store_dwordx4 v[10:11], v[6:9], off offset:256
	s_cbranch_scc1 .LBB0_295
	s_mov_b64 s[6:7], 0

; __device__ __forceinline__ int ltid() { int t = threadIdx.x; asm volatile("" : "+v"(t)); return t; }
; __device__ __forceinline__ void emit_rm(const float* stage, u16* dst, long ld, const float* rs) {
;   const int tid = ltid(), c4 = (tid & 31) * 4, rr = tid >> 5;
; #pragma unroll 1
;   for (int ps = 0; ps < 8; ++ps) {
;     const int r = ps * 16 + rr;
;     const float* s = stage + r * SP + c4;
;     const float4 a = *(const float4*)s, b = *(const float4*)(s + 128);
;     const float f = rs ? rs[r] : 1.f;
;     uint2 o0, o1;
;     o0.x = pack2(a.x * f, a.y * f); o0.y = pack2(a.z * f, a.w * f);
;     o1.x = pack2(b.x * f, b.y * f); o1.y = pack2(b.z * f, b.w * f);
;     *(uint2*)(dst + (long)r * ld + c4) = o0;
;     *(uint2*)(dst + (long)r * ld + 128 + c4) = o1;
;   }
; }
.LBB0_299:
	ds_read_b128 v[4:7], v0
	ds_read_b128 v[8:11], v0 offset:512
	v_add_u32_e32 v0, 0x4100, v0
	s_waitcnt lgkmcnt(0)
	v_cvt_pk_bf16_f32 v4, v4, v5
	v_cvt_pk_bf16_f32 v5, v6, v7
	v_cvt_pk_bf16_f32 v6, v8, v9
	v_lshl_add_u64 v[8:9], v[2:3], 0, s[0:1]
	s_add_u32 s0, s0, 0x4000
	v_add_co_u32_e32 v8, vcc, s41, v8
	s_addc_u32 s1, s1, 0
	s_nop 0
	v_addc_co_u32_e32 v9, vcc, 0, v9, vcc
	s_cmp_eq_u32 s0, 0x20000
	v_cvt_pk_bf16_f32 v7, v10, v11
	global_store_dwordx2 v[8:9], v[4:5], off
	global_store_dwordx2 v[8:9], v[6:7], off offset:256
	s_cbranch_scc0 .LBB0_299
	s_branch .LBB0_277

; __device__ __forceinline__ int ltid() { int t = threadIdx.x; asm volatile("" : "+v"(t)); return t; }
; __device__ __forceinline__ void emit_tr(const float* stage, u16* dst, long ld) {
;   const int tid = ltid(), lane = tid & 63, w = tid >> 6;
; #pragma unroll 1
;   for (int ps = 0; ps < 8; ++ps) {
;     const int wp = ps * 8 + w;
;     const int col = (wp & 15) * 16 + (lane & 15), rg = (wp >> 4) * 4 + (lane >> 4);
;     const float* s = stage + (rg * 8) * SP + col;
;     uint4 o; o.x = pack2(s[0], s[SP]); o.y = pack2(s[2 * SP], s[3 * SP]); o.z = pack2(s[4 * SP], s[5 * SP]); o.w = pack2(s[6 * SP], s[7 * SP]);
;     *(uint4*)(dst + (long)col * ld + rg * 8) = o;
;   }
; }
.LBB0_313:
	v_add_u32_e32 v0, s13, v2
	v_and_or_b32 v70, v69, s91, v3
	v_ashrrev_i32_e32 v71, 2, v0
	v_lshlrev_b32_e32 v0, 10, v70
	v_and_or_b32 v74, v71, -4, v68
	v_lshlrev_b32_e32 v73, 2, v70
	v_lshl_add_u64 v[70:71], s[6:7], 0, v[0:1]
	v_mul_lo_u32 v0, v74, s39
	v_add3_u32 v0, 16, v0, v73
	ds_read_b32 v76, v0
	ds_read_b32 v77, v0 offset:1040
	ds_read_b32 v78, v0 offset:2080
	ds_read_b32 v79, v0 offset:3120
	ds_read_b32 v80, v0 offset:4160
	ds_read_b32 v81, v0 offset:5200
	ds_read_b32 v82, v0 offset:6240
	ds_read_b32 v0, v0 offset:7280
	v_lshlrev_b32_e32 v72, 3, v74
	s_add_i32 s13, s13, 8
	v_ashrrev_i32_e32 v73, 31, v72
	v_add_u32_e32 v69, 0x80, v69
	s_cmp_lg_u32 s13, 64
	v_lshl_add_u64 v[74:75], v[72:73], 1, v[70:71]
	s_waitcnt lgkmcnt(0)
	v_cvt_pk_bf16_f32 v70, v76, v77
	s_waitcnt lgkmcnt(4)
	v_cvt_pk_bf16_f32 v71, v78, v79
	s_waitcnt lgkmcnt(2)
	v_cvt_pk_bf16_f32 v72, v80, v81
	s_waitcnt lgkmcnt(0)
	v_cvt_pk_bf16_f32 v73, v82, v0
	global_store_dwordx4 v[74:75], v[70:73], off
	s_cbranch_scc1 .LBB0_313
	s_mov_b64 s[6:7], 0

; __device__ __forceinline__ int ltid() { int t = threadIdx.x; asm volatile("" : "+v"(t)); return t; }
; __device__ __forceinline__ void emit_rm(const float* stage, u16* dst, long ld, const float* rs) {
;   const int tid = ltid(), c4 = (tid & 31) * 4, rr = tid >> 5;
; #pragma unroll 1
;   for (int ps = 0; ps < 8; ++ps) {
;     const int r = ps * 16 + rr;
;     const float* s = stage + r * SP + c4;
;     const float4 a = *(const float4*)s, b = *(const float4*)(s + 128);
;     const float f = rs ? rs[r] : 1.f;
;     uint2 o0, o1;
;     o0.x = pack2(a.x * f, a.y * f); o0.y = pack2(a.z * f, a.w * f);
;     o1.x = pack2(b.x * f, b.y * f); o1.y = pack2(b.z * f, b.w * f);
;     *(uint2*)(dst + (long)r * ld + c4) = o0;
;     *(uint2*)(dst + (long)r * ld + 128 + c4) = o1;
;   }
; }
.LBB0_324:
	ds_read_b128 v[4:7], v0
	ds_read_b128 v[8:11], v0 offset:512
	v_add_u32_e32 v0, 0x4100, v0
	s_waitcnt lgkmcnt(0)
	v_cvt_pk_bf16_f32 v4, v4, v5
	v_cvt_pk_bf16_f32 v5, v6, v7
	v_cvt_pk_bf16_f32 v6, v8, v9
	v_lshl_add_u64 v[8:9], v[2:3], 0, s[0:1]
	s_add_u32 s0, s0, 0x4000
	v_add_co_u32_e32 v8, vcc, s41, v8
	s_addc_u32 s1, s1, 0
	s_nop 0
	v_addc_co_u32_e32 v9, vcc, 0, v9, vcc
	s_cmp_eq_u32 s0, 0x20000
	v_cvt_pk_bf16_f32 v7, v10, v11
	global_store_dwordx2 v[8:9], v[4:5], off
	global_store_dwordx2 v[8:9], v[6:7], off offset:256
	s_cbranch_scc0 .LBB0_324

;   __device__ __forceinline__ const float* in(int i) const { return ((const float* const*)(ws + OFF_TBL))[i]; }
; __device__ void decay_items(const Ctx& p) {
;     ...
;       for (int r = 0; r < 16; ++r) wa[r] = p.in(4)[r * 1024 + ch];
;       const float ba = p.in(5)[ch];
;       u16* qp = h0 + row0 * H0LD + C_GQ + ch;
;     ...
;       if (half) gelm[ck * 1024 + ch] = __expf(c); else gem[ck * 1024 + ch] = __expf(-c);
;     } else {
;       const int ch = (g - 4) * 256 + d;
;       const float l0 = p.in(2)[ch], l1 = p.in(2)[2048 + ch], l2 = p.in(2)[4096 + ch];
;       const float mx = fmaxf(l0, fmaxf(l1, l2));
;       const float e0 = __expf(l0 - mx), e1 = __expf(l1 - mx), e2 = __expf(l2 - mx);
;       const float lb = e0 / (e0 + e1 + e2);
;       u16* qp = h0 + row0 * H0LD + C_HQ + ch;
;       u16* kp = h0 + row0 * H0LD + C_HF + ch;
;     ...
;       if (half) helm[ck * 2048 + ch] = __expf(c); else hem[ck * 2048 + ch] = __expf(-c);
.LBB0_331:
	v_mul_f32_e32 v0, 0xbfb8aa3b, v35
	s_waitcnt vmcnt(0) lgkmcnt(0)
	v_mul_f32_e32 v21, 0x3fb8aa3b, v62
	v_cndmask_b32_e64 v0, v21, v0, s[8:9]
	s_lshl_b32 s0, s20, s22
	v_exp_f32_e32 v0, v0
	v_add_u32_e32 v4, s0, v30
	v_lshl_add_u64 v[2:3], s[66:67], 0, v[2:3]
	v_ashrrev_i32_e32 v5, 31, v4
	s_add_i32 s34, s54, s34
	v_lshl_add_u64 v[2:3], v[4:5], 2, v[2:3]
	s_cmpk_gt_i32 s34, 0xbff
	global_store_dword v[2:3], v0, off
	s_cbranch_scc1 .LBB0_357
.LBB0_332:
	s_mul_hi_i32 s0, s34, 0x2aaaaaab
	s_lshr_b32 s1, s0, 31
	s_ashr_i32 s0, s0, 1
	s_add_i32 s20, s0, s1
	s_mul_i32 s0, s20, 12
	s_sub_i32 s68, s34, s0
	s_ashr_i32 s21, s20, 31
	s_mov_b64 s[0:1], -1
	s_cmp_gt_i32 s68, 3
	s_mul_hi_i32 s55, s20, 0x1e8000
	s_mul_i32 s61, s20, 0x1e8000
	v_lshlrev_b32_e32 v46, 1, v10
	v_lshlrev_b32_e32 v44, 1, v12
	v_lshlrev_b32_e32 v42, 1, v14
	v_lshlrev_b32_e32 v40, 1, v16
	v_lshlrev_b32_e32 v38, 1, v18
	v_lshlrev_b32_e32 v36, 1, v20
	s_waitcnt vmcnt(0)
	v_lshlrev_b32_e32 v34, 1, v22
	v_lshlrev_b32_e32 v32, 1, v24
	s_cbranch_scc0 .LBB0_340
	v_mov_b64_e32 v[2:3], s[16:17]
	global_load_dwordx2 v[2:3], v[2:3], off
	v_lshl_add_u32 v30, s68, 8, v11
	v_mov_b32_e32 v31, v1
	s_add_u32 s0, s14, s61
	s_addc_u32 s1, s15, s55
	v_mov_b32_e32 v47, v1
	v_mov_b32_e32 v45, v1
	v_mov_b32_e32 v43, v1
	v_mov_b32_e32 v41, v1
	v_mov_b32_e32 v39, v1
	v_mov_b32_e32 v37, v1
	v_mov_b32_e32 v35, v1
	v_mov_b32_e32 v33, v1
	s_mov_b32 s22, 0
	s_mov_b32 s23, -8
	s_mov_b32 s24, 24
	s_waitcnt vmcnt(0) lgkmcnt(0)
	v_lshl_add_u64 v[2:3], v[30:31], 2, v[2:3]
	v_add_co_u32_e32 v4, vcc, 0x2000, v2
	global_load_dword v0, v[2:3], off
	s_nop 0
	v_addc_co_u32_e32 v5, vcc, 0, v3, vcc
	global_load_dword v4, v[4:5], off
	v_add_co_u32_e32 v2, vcc, 0x4000, v2
	s_nop 1
	v_addc_co_u32_e32 v3, vcc, 0, v3, vcc
	global_load_dword v2, v[2:3], off
	s_waitcnt vmcnt(0) lgkmcnt(0)
	v_max3_f32 v3, v0, v4, v2
	v_sub_f32_e32 v0, v0, v3
	v_sub_f32_e32 v4, v4, v3
	v_mul_f32_e32 v0, 0x3fb8aa3b, v0
	v_mul_f32_e32 v4, 0x3fb8aa3b, v4
	v_sub_f32_e32 v2, v2, v3
	v_exp_f32_e32 v0, v0
	v_exp_f32_e32 v4, v4
	v_mul_f32_e32 v2, 0x3fb8aa3b, v2
	v_exp_f32_e32 v2, v2
	v_add_f32_e32 v3, v0, v4
	v_add_f32_e32 v4, v2, v3
	v_lshl_add_u64 v[2:3], v[30:31], 1, s[0:1]
	s_mov_b64 s[0:1], 0x3000
	v_lshl_add_u64 v[48:49], v[2:3], 0, s[0:1]
	s_mov_b64 s[0:1], 0x4000
	v_lshl_add_u64 v[50:51], v[2:3], 0, s[0:1]
	v_lshl_add_u64 v[2:3], v[48:49], 0, v[46:47]
	global_load_ushort v21, v[2:3], off
	v_lshl_add_u64 v[2:3], v[50:51], 0, v[46:47]
	global_load_ushort v23, v[2:3], off
	v_lshl_add_u64 v[2:3], v[48:49], 0, v[44:45]
	global_load_ushort v25, v[2:3], off
	v_lshl_add_u64 v[2:3], v[50:51], 0, v[44:45]
	global_load_ushort v45, v[2:3], off
	v_lshl_add_u64 v[2:3], v[48:49], 0, v[42:43]
	global_load_ushort v47, v[2:3], off
	v_lshl_add_u64 v[2:3], v[50:51], 0, v[42:43]
	global_load_ushort v43, v[2:3], off
	v_lshl_add_u64 v[2:3], v[48:49], 0, v[40:41]
	global_load_ushort v94, v[2:3], off
	v_lshl_add_u64 v[2:3], v[50:51], 0, v[40:41]
	global_load_ushort v41, v[2:3], off
	v_lshl_add_u64 v[2:3], v[48:49], 0, v[38:39]
	global_load_ushort v95, v[2:3], off
	v_lshl_add_u64 v[2:3], v[50:51], 0, v[38:39]
	global_load_ushort v39, v[2:3], off
	v_lshl_add_u64 v[2:3], v[48:49], 0, v[36:37]
	global_load_ushort v96, v[2:3], off
	v_lshl_add_u64 v[2:3], v[50:51], 0, v[36:37]
	global_load_ushort v37, v[2:3], off
	v_lshl_add_u64 v[2:3], v[48:49], 0, v[34:35]
	global_load_ushort v97, v[2:3], off
	v_lshl_add_u64 v[2:3], v[50:51], 0, v[34:35]
	global_load_ushort v98, v[2:3], off
	v_lshl_add_u64 v[2:3], v[48:49], 0, v[32:33]
	global_load_ushort v99, v[2:3], off
	v_lshl_add_u64 v[2:3], v[50:51], 0, v[32:33]
	global_load_ushort v33, v[2:3], off
	v_div_scale_f32 v2, s[0:1], v4, v4, v0
	v_rcp_f32_e32 v3, v2
	s_lshl_b64 s[0:1], s[20:21], 18
	s_add_u32 s0, s39, s0
	s_addc_u32 s1, s52, s1
	v_fma_f32 v5, -v2, v3, 1.0
	v_fmac_f32_e32 v3, v5, v3
	v_div_scale_f32 v5, vcc, v0, v4, v0
	v_mul_f32_e32 v35, v5, v3
	v_fma_f32 v52, -v2, v35, v5
	v_fmac_f32_e32 v35, v52, v3
	v_fma_f32 v2, -v2, v35, v5
	v_div_fmas_f32 v2, v2, v3, v35
	v_div_fixup_f32 v52, v2, v4, v0
	v_sub_f32_e32 v54, 1.0, v52
	v_lshlrev_b64 v[2:3], 7, v[30:31]
	v_lshl_add_u64 v[56:57], s[0:1], 0, v[2:3]
	v_mov_b32_e32 v53, v52
	v_mov_b32_e32 v55, v54
	v_mov_b32_e32 v31, 0
	s_branch .LBB0_335
.LBB0_334:
	s_or_b64 exec, exec, s[0:1]
	v_sub_f32_e32 v35, v35, v63
	s_add_i32 s24, s24, -8
	s_add_i32 s22, s22, 8
	v_cndmask_b32_e64 v31, v62, v35, s[8:9]
	v_lshl_add_u64 v[58:59], v[0:1], 1, v[56:57]
	s_cmp_gt_u32 s23, 23
	global_store_dwordx4 v[58:59], v[2:5], off
	s_cbranch_scc1 .LBB0_339
; __device__ __forceinline__ float bf2f(u16 h) { return __uint_as_float(((unsigned)h) << 16); }
; __device__ __forceinline__ u16 f2bf(float f) { return (u16)(pack2(f, 0.f) & 0xffffu); }
; __device__ __forceinline__ float sigm(float x) { return __builtin_amdgcn_rcpf(1.f + __expf(-x)); }
; __device__ __forceinline__ float siluf(float x) { return x * __builtin_amdgcn_rcpf(1.f + __expf(-x)); }
; __device__ void decay_items(const Ctx& p) {
;     ...
; #pragma unroll 1
;       for (int ib = 0; ib < 32; ib += 8) {
;         u16 qr[8], kr[8], kb[8];
; #pragma unroll
;         for (int e = 0; e < 8; ++e) { qr[e] = qnx[e]; kr[e] = knx[e]; }
;         {
;           const int ibn = min(ib + 8, 24);
; #pragma unroll
;           for (int e = 0; e < 8; ++e) {
;             int i = half ? (32 + ibn + e) : (31 - ibn - e);
;             qnx[e] = qp[(long)i * H0LD]; knx[e] = kp[(long)i * H0LD];
;           }
;         }
; #pragma unroll
;         for (int e = 0; e < 8; ++e) {
;           int i = half ? (32 + ib + e) : (31 - ib - e);
;           float f = lb + (1.f - lb) * sigm(bf2f(kr[e]));
;           float gl = __logf(f);
;           if (half) c += gl;
;           if (!p.dry) qp[(long)i * H0LD] = f2bf(siluf(bf2f(qr[e])) * __expf(c));
;           kb[e] = f2bf((1.f - f) * __expf(-c));
;           if (!p.dry) kp[(long)i * H0LD] = kb[e];
;           if (!half) c -= gl;
;         }
.LBB0_335:
	s_mov_b32 s0, s23
	s_add_i32 s1, s0, 16
	s_min_u32 s1, s1, 24
	s_xor_b32 s25, s1, 31
	s_or_b32 s26, s1, 32
	v_mov_b32_e32 v0, s26
	v_mov_b32_e32 v2, s25
	v_cndmask_b32_e64 v0, v0, v2, s[8:9]
	v_mul_u32_u24_e32 v0, 0x3d00, v0
	v_lshlrev_b32_e32 v0, 1, v0
	v_lshl_add_u64 v[2:3], v[48:49], 0, v[0:1]
	s_waitcnt vmcnt(0) lgkmcnt(0)
	v_mov_b32_e32 v5, v21
	global_load_ushort v21, v[2:3], off
	v_lshl_add_u64 v[2:3], v[50:51], 0, v[0:1]
	s_or_b32 s25, s1, 33
	s_sub_i32 s26, 30, s1
	v_mov_b32_e32 v4, v23
	global_load_ushort v23, v[2:3], off
	v_mov_b32_e32 v0, s25
	v_mov_b32_e32 v2, s26
	v_cndmask_b32_e64 v0, v0, v2, s[8:9]
	v_mul_u32_u24_e32 v0, 0x3d00, v0
	v_lshlrev_b32_e32 v0, 1, v0
	v_lshl_add_u64 v[2:3], v[48:49], 0, v[0:1]
	v_mov_b32_e32 v60, v25
	global_load_ushort v25, v[2:3], off
	v_lshl_add_u64 v[2:3], v[50:51], 0, v[0:1]
	s_or_b32 s25, s1, 34
	s_sub_i32 s26, 29, s1
	v_mov_b32_e32 v58, v45
	global_load_ushort v45, v[2:3], off
	v_mov_b32_e32 v0, s25
	v_mov_b32_e32 v2, s26
	v_cndmask_b32_e64 v0, v0, v2, s[8:9]
	v_mul_u32_u24_e32 v0, 0x3d00, v0
	v_lshlrev_b32_e32 v0, 1, v0
	v_lshl_add_u64 v[2:3], v[48:49], 0, v[0:1]
	v_mov_b32_e32 v61, v47
	global_load_ushort v47, v[2:3], off
	v_lshl_add_u64 v[2:3], v[50:51], 0, v[0:1]
	s_or_b32 s25, s1, 35
	s_sub_i32 s26, 28, s1
	v_mov_b32_e32 v59, v43
	global_load_ushort v43, v[2:3], off
	v_mov_b32_e32 v0, s25
	v_mov_b32_e32 v2, s26
	v_cndmask_b32_e64 v0, v0, v2, s[8:9]
	v_mul_u32_u24_e32 v0, 0x3d00, v0
	v_lshlrev_b32_e32 v0, 1, v0
	v_lshl_add_u64 v[2:3], v[48:49], 0, v[0:1]
	v_mov_b32_e32 v65, v94
	global_load_ushort v94, v[2:3], off
	v_lshl_add_u64 v[2:3], v[50:51], 0, v[0:1]
	s_or_b32 s25, s1, 36
	s_sub_i32 s26, 27, s1
	v_mov_b32_e32 v64, v41
	global_load_ushort v41, v[2:3], off
	v_mov_b32_e32 v0, s25
	v_mov_b32_e32 v2, s26
	v_cndmask_b32_e64 v0, v0, v2, s[8:9]
	v_mul_u32_u24_e32 v0, 0x3d00, v0
	v_lshlrev_b32_e32 v0, 1, v0
	v_lshl_add_u64 v[2:3], v[48:49], 0, v[0:1]
	v_mov_b32_e32 v68, v95
	global_load_ushort v95, v[2:3], off
	v_lshl_add_u64 v[2:3], v[50:51], 0, v[0:1]
	s_or_b32 s25, s1, 37
	s_sub_i32 s26, 26, s1
	v_mov_b32_e32 v69, v39
	global_load_ushort v39, v[2:3], off
	v_mov_b32_e32 v0, s25
	v_mov_b32_e32 v2, s26
	v_cndmask_b32_e64 v0, v0, v2, s[8:9]
	v_mul_u32_u24_e32 v0, 0x3d00, v0
	v_lshlrev_b32_e32 v0, 1, v0
	v_lshl_add_u64 v[2:3], v[48:49], 0, v[0:1]
	v_mov_b32_e32 v78, v96
	global_load_ushort v96, v[2:3], off
	v_lshl_add_u64 v[2:3], v[50:51], 0, v[0:1]
	s_or_b32 s25, s1, 38
	s_sub_i32 s26, 25, s1
	v_mov_b32_e32 v79, v37
	global_load_ushort v37, v[2:3], off
	v_mov_b32_e32 v0, s25
	v_mov_b32_e32 v2, s26
	v_cndmask_b32_e64 v0, v0, v2, s[8:9]
	v_mul_u32_u24_e32 v0, 0x3d00, v0
	v_lshlrev_b32_e32 v0, 1, v0
	v_lshl_add_u64 v[2:3], v[48:49], 0, v[0:1]
	v_mov_b32_e32 v84, v97
	global_load_ushort v97, v[2:3], off
	v_lshl_add_u64 v[2:3], v[50:51], 0, v[0:1]
	s_or_b32 s25, s1, 39
	s_sub_i32 s1, 24, s1
	v_mov_b32_e32 v72, v98
	global_load_ushort v98, v[2:3], off
	v_mov_b32_e32 v0, s25
	v_mov_b32_e32 v2, s1
	v_cndmask_b32_e64 v0, v0, v2, s[8:9]
	v_mul_u32_u24_e32 v0, 0x3d00, v0
	v_lshlrev_b32_e32 v0, 1, v0
	v_lshl_add_u64 v[2:3], v[48:49], 0, v[0:1]
	v_mov_b32_e32 v35, v99
	global_load_ushort v99, v[2:3], off
	v_lshl_add_u64 v[2:3], v[50:51], 0, v[0:1]
	s_add_i32 s0, s0, 40
	s_add_i32 s1, s24, 7
	v_mov_b32_e32 v74, v33
	global_load_ushort v33, v[2:3], off
	v_mov_b32_e32 v0, s0
	v_mov_b32_e32 v2, s1
	v_cndmask_b32_e64 v0, v0, v2, s[8:9]
	v_lshlrev_b32_e32 v2, 16, v4
	v_mul_f32_e32 v2, 0xbfb8aa3b, v2
	v_exp_f32_e32 v2, v2
	s_add_i32 s23, s23, 8
	v_mul_lo_u32 v0, v0, s58
	s_or_b32 s0, s23, 33
	v_add_f32_e32 v2, 1.0, v2
	v_rcp_f32_e32 v73, v2
	v_lshlrev_b32_e32 v2, 16, v5
	v_mul_f32_e32 v3, 0xbfb8aa3b, v2
	v_exp_f32_e32 v3, v3
	s_add_i32 s1, s24, 6
	v_lshlrev_b32_e32 v64, 16, v64
	v_mul_f32_e32 v64, 0xbfb8aa3b, v64
	v_add_f32_e32 v3, 1.0, v3
	v_rcp_f32_e32 v3, v3
	v_exp_f32_e32 v64, v64
	v_lshlrev_b32_e32 v69, 16, v69
	v_mul_f32_e32 v69, 0xbfb8aa3b, v69
	v_mul_f32_e32 v104, v3, v2
	v_lshlrev_b64 v[2:3], 1, v[0:1]
	v_lshl_add_u64 v[76:77], v[48:49], 0, v[2:3]
	v_lshl_add_u64 v[4:5], v[50:51], 0, v[2:3]
	v_mov_b32_e32 v0, s0
	v_mov_b32_e32 v2, s1
	v_cndmask_b32_e64 v0, v0, v2, s[8:9]
	v_lshlrev_b32_e32 v2, 16, v58
	v_mul_f32_e32 v2, 0xbfb8aa3b, v2
	v_exp_f32_e32 v2, v2
	v_mul_lo_u32 v0, v0, s58
	s_or_b32 s0, s23, 34
	s_add_i32 s1, s24, 5
	v_add_f32_e32 v2, 1.0, v2
	v_rcp_f32_e32 v75, v2
	v_lshlrev_b32_e32 v2, 16, v60
	v_mul_f32_e32 v3, 0xbfb8aa3b, v2
	v_exp_f32_e32 v3, v3
	v_mov_b32_e32 v58, s1
	v_add_f32_e32 v64, 1.0, v64
	v_rcp_f32_e32 v83, v64
	v_add_f32_e32 v3, 1.0, v3
	v_rcp_f32_e32 v3, v3
	v_lshlrev_b32_e32 v64, 16, v65
	v_mul_f32_e32 v65, 0xbfb8aa3b, v64
	v_exp_f32_e32 v65, v65
	v_mul_f32_e32 v101, v3, v2
	v_lshlrev_b64 v[2:3], 1, v[0:1]
	v_mov_b32_e32 v0, s0
	v_cndmask_b32_e64 v0, v0, v58, s[8:9]
	v_lshlrev_b32_e32 v58, 16, v59
	v_mul_f32_e32 v58, 0xbfb8aa3b, v58
	v_exp_f32_e32 v58, v58
	v_add_f32_e32 v65, 1.0, v65
	v_exp_f32_e32 v69, v69
	v_mul_lo_u32 v0, v0, s58
	v_add_f32_e32 v58, 1.0, v58
	v_rcp_f32_e32 v81, v58
	v_lshlrev_b32_e32 v58, 16, v61
	v_mul_f32_e32 v59, 0xbfb8aa3b, v58
	v_exp_f32_e32 v59, v59
	s_or_b32 s0, s23, 35
	s_add_i32 s1, s24, 4
	v_rcp_f32_e32 v65, v65
	v_add_f32_e32 v59, 1.0, v59
	v_rcp_f32_e32 v59, v59
	v_mov_b32_e32 v66, s1
	s_add_i32 s1, s24, 3
	v_add_f32_e32 v69, 1.0, v69
	v_mul_f32_e32 v100, v59, v58
	v_lshlrev_b64 v[58:59], 1, v[0:1]
	v_mov_b32_e32 v0, s0
	v_cndmask_b32_e64 v0, v0, v66, s[8:9]
	v_mul_lo_u32 v0, v0, s58
	s_or_b32 s0, s23, 36
	v_mul_f32_e32 v102, v65, v64
	v_lshlrev_b64 v[64:65], 1, v[0:1]
	v_mov_b32_e32 v0, s0
	v_mov_b32_e32 v70, s1
; __device__ __forceinline__ float bf2f(u16 h) { return __uint_as_float(((unsigned)h) << 16); }
; __device__ __forceinline__ u16 f2bf(float f) { return (u16)(pack2(f, 0.f) & 0xffffu); }
; __device__ __forceinline__ float sigm(float x) { return __builtin_amdgcn_rcpf(1.f + __expf(-x)); }
; __device__ __forceinline__ float siluf(float x) { return x * __builtin_amdgcn_rcpf(1.f + __expf(-x)); }
; __device__ void decay_items(const Ctx& p) {
;     ...
;         for (int e = 0; e < 8; ++e) {
;           int i = half ? (32 + ib + e) : (31 - ib - e);
;           float f = lb + (1.f - lb) * sigm(bf2f(kr[e]));
;           float gl = __logf(f);
;           if (half) c += gl;
;           if (!p.dry) qp[(long)i * H0LD] = f2bf(siluf(bf2f(qr[e])) * __expf(c));
;           kb[e] = f2bf((1.f - f) * __expf(-c));
;           if (!p.dry) kp[(long)i * H0LD] = kb[e];
;           if (!half) c -= gl;
;         }
	v_rcp_f32_e32 v80, v69
	v_cndmask_b32_e64 v0, v0, v70, s[8:9]
	v_mul_lo_u32 v0, v0, s58
	s_or_b32 s0, s23, 37
	s_add_i32 s1, s24, 2
	v_lshlrev_b64 v[70:71], 1, v[0:1]
	v_mov_b32_e32 v0, s0
	v_mov_b32_e32 v82, s1
	v_cndmask_b32_e64 v0, v0, v82, s[8:9]
	v_lshlrev_b32_e32 v79, 16, v79
	v_pk_fma_f32 v[80:81], v[54:55], v[80:81], v[52:53]
	v_mul_f32_e32 v79, 0xbfb8aa3b, v79
	v_mul_lo_u32 v0, v0, s58
	v_cmp_gt_f32_e32 vcc, s48, v81
	v_exp_f32_e32 v79, v79
	v_lshlrev_b64 v[86:87], 1, v[0:1]
	v_cndmask_b32_e64 v0, 0, 32, vcc
	v_ldexp_f32 v0, v81, v0
	v_log_f32_e32 v0, v0
	v_add_f32_e32 v79, 1.0, v79
	v_rcp_f32_e32 v82, v79
	v_lshlrev_b32_e32 v78, 16, v78
	v_mul_f32_e32 v85, 0x3f317217, v0
	v_fma_f32 v85, v0, s49, -v85
	v_fmac_f32_e32 v85, 0x3377d1cf, v0
	v_fmac_f32_e32 v85, 0x3f317217, v0
	v_cmp_lt_f32_e64 s[0:1], |v0|, s36
	v_pk_fma_f32 v[82:83], v[54:55], v[82:83], v[52:53]
	v_mul_f32_e32 v79, 0xbfb8aa3b, v78
	v_cndmask_b32_e64 v0, v0, v85, s[0:1]
	v_cndmask_b32_e32 v85, 0, v192, vcc
	v_cmp_gt_f32_e32 vcc, s48, v83
	v_sub_f32_e32 v106, v0, v85
	v_exp_f32_e32 v79, v79
	v_cndmask_b32_e64 v0, 0, 32, vcc
	v_ldexp_f32 v0, v83, v0
	v_log_f32_e32 v0, v0
	v_pk_add_f32 v[92:93], v[80:81], 1.0 op_sel_hi:[1,0] neg_lo:[1,0] neg_hi:[1,0]
	v_add_f32_e32 v79, 1.0, v79
	v_rcp_f32_e32 v79, v79
	v_mul_f32_e32 v85, 0x3f317217, v0
	v_fma_f32 v85, v0, s49, -v85
	v_fmac_f32_e32 v85, 0x3377d1cf, v0
	v_fmac_f32_e32 v85, 0x3f317217, v0
	v_cmp_lt_f32_e64 s[0:1], |v0|, s36
	v_pk_add_f32 v[90:91], v[82:83], 1.0 op_sel_hi:[1,0] neg_lo:[1,0] neg_hi:[1,0]
	v_lshlrev_b32_e32 v72, 16, v72
	v_cndmask_b32_e64 v0, v0, v85, s[0:1]
	v_cndmask_b32_e32 v85, 0, v192, vcc
	v_cmp_gt_f32_e32 vcc, s48, v80
	v_sub_f32_e32 v107, v0, v85
	v_mul_f32_e32 v72, 0xbfb8aa3b, v72
	v_cndmask_b32_e64 v0, 0, 32, vcc
	v_ldexp_f32 v0, v80, v0
	v_log_f32_e32 v0, v0
	v_mul_f32_e32 v105, v79, v78
	v_lshl_add_u64 v[78:79], v[48:49], 0, v[86:87]
	v_exp_f32_e32 v72, v72
	v_mul_f32_e32 v85, 0x3f317217, v0
	v_fma_f32 v85, v0, s49, -v85
	v_fmac_f32_e32 v85, 0x3377d1cf, v0
	v_fmac_f32_e32 v85, 0x3f317217, v0
	v_cmp_lt_f32_e64 s[0:1], |v0|, s36
	v_lshlrev_b32_e32 v35, 16, v35
	v_add_f32_e32 v72, 1.0, v72
	v_cndmask_b32_e64 v0, v0, v85, s[0:1]
	v_cndmask_b32_e32 v85, 0, v192, vcc
	v_cmp_gt_f32_e32 vcc, s48, v82
	v_sub_f32_e32 v108, v0, v85
	v_rcp_f32_e32 v72, v72
	v_cndmask_b32_e64 v0, 0, 32, vcc
	v_ldexp_f32 v0, v82, v0
	v_log_f32_e32 v0, v0
	v_pk_fma_f32 v[72:73], v[54:55], v[72:73], v[52:53]
	v_lshlrev_b32_e32 v74, 16, v74
	v_mul_f32_e32 v74, 0xbfb8aa3b, v74
	v_mul_f32_e32 v80, 0x3f317217, v0
	v_fma_f32 v80, v0, s49, -v80
	v_fmac_f32_e32 v80, 0x3377d1cf, v0
	v_fmac_f32_e32 v80, 0x3f317217, v0
	v_cmp_lt_f32_e64 s[0:1], |v0|, s36
	v_exp_f32_e32 v74, v74
	v_lshl_add_u64 v[62:63], v[48:49], 0, v[2:3]
	v_cndmask_b32_e64 v0, v0, v80, s[0:1]
	v_cndmask_b32_e32 v80, 0, v192, vcc
	s_or_b32 s0, s23, 38
	s_add_i32 s1, s24, 1
	v_sub_f32_e32 v109, v0, v80
	v_mov_b32_e32 v0, s0
	v_mov_b32_e32 v82, s1
	v_cndmask_b32_e64 v0, v0, v82, s[8:9]
	v_mul_lo_u32 v0, v0, s58
	s_or_b32 s0, s23, 39
	v_lshl_add_u64 v[80:81], v[50:51], 0, v[86:87]
	v_lshlrev_b32_e32 v82, 16, v84
	v_lshlrev_b64 v[84:85], 1, v[0:1]
	v_mov_b32_e32 v0, s0
	v_mov_b32_e32 v86, s24
	v_cndmask_b32_e64 v0, v0, v86, s[8:9]
	v_mul_f32_e32 v86, 0xbfb8aa3b, v35
	v_exp_f32_e32 v86, v86
	v_mul_lo_u32 v0, v0, s58
	v_cmp_gt_f32_e32 vcc, s48, v73
	v_add_f32_e32 v74, 1.0, v74
	v_add_f32_e32 v86, 1.0, v86
	v_rcp_f32_e32 v86, v86
	v_rcp_f32_e32 v74, v74
	v_lshl_add_u64 v[2:3], v[50:51], 0, v[2:3]
	v_lshl_add_u64 v[60:61], v[48:49], 0, v[58:59]
	v_mul_f32_e32 v111, v86, v35
	v_lshlrev_b64 v[86:87], 1, v[0:1]
	v_cndmask_b32_e64 v0, 0, 32, vcc
	v_ldexp_f32 v0, v73, v0
	v_log_f32_e32 v0, v0
	v_pk_fma_f32 v[74:75], v[54:55], v[74:75], v[52:53]
	v_lshl_add_u64 v[66:67], v[48:49], 0, v[64:65]
	v_lshlrev_b32_e32 v68, 16, v68
	v_mul_f32_e32 v35, 0x3f317217, v0
	v_fma_f32 v35, v0, s49, -v35
	v_fmac_f32_e32 v35, 0x3377d1cf, v0
	v_fmac_f32_e32 v35, 0x3f317217, v0
	v_cmp_lt_f32_e64 s[0:1], |v0|, s36
	v_mul_f32_e32 v69, 0xbfb8aa3b, v68
	v_exp_f32_e32 v69, v69
	v_cndmask_b32_e64 v0, v0, v35, s[0:1]
	v_cndmask_b32_e32 v35, 0, v192, vcc
	v_sub_f32_e32 v0, v0, v35
	v_add_f32_e32 v35, v31, v0
	v_cndmask_b32_e64 v112, v35, v31, s[8:9]
	v_mul_f32_e32 v113, 0x3fb8aa3b, v112
	v_exp_f32_e32 v113, v113
	v_sub_f32_e32 v0, v31, v0
	v_cmp_gt_f32_e32 vcc, s48, v75
	v_cndmask_b32_e64 v31, v35, v0, s[8:9]
	v_mul_f32_e32 v104, v104, v113
	v_cndmask_b32_e64 v35, 0, 32, vcc
	v_ldexp_f32 v35, v75, v35
	v_log_f32_e32 v35, v35
	v_cvt_pk_bf16_f32 v104, v104, s0
	global_store_short v[76:77], v104, off
	v_mul_f32_e32 v76, 0xbfb8aa3b, v112
	v_exp_f32_e32 v77, v76
	v_mul_f32_e32 v76, 0x3f317217, v35
	v_fma_f32 v76, v35, s49, -v76
	v_fmac_f32_e32 v76, 0x3377d1cf, v35
	v_fmac_f32_e32 v76, 0x3f317217, v35
	v_cmp_lt_f32_e64 s[0:1], |v35|, s36
	v_lshl_add_u64 v[58:59], v[50:51], 0, v[58:59]
	v_add_f32_e32 v69, 1.0, v69
	v_cndmask_b32_e64 v35, v35, v76, s[0:1]
	v_cndmask_b32_e32 v76, 0, v192, vcc
	v_sub_f32_e32 v35, v35, v76
	v_add_f32_e32 v104, v35, v31
	v_sub_f32_e32 v112, v0, v35
	v_cndmask_b32_e64 v31, v104, v112, s[8:9]
	v_cmp_gt_f32_e32 vcc, s48, v72
	v_add_f32_e32 v113, v106, v31
	v_sub_f32_e32 v106, v112, v106
; __device__ __forceinline__ float bf2f(u16 h) { return __uint_as_float(((unsigned)h) << 16); }
; __device__ __forceinline__ u16 f2bf(float f) { return (u16)(pack2(f, 0.f) & 0xffffu); }
; __device__ __forceinline__ float sigm(float x) { return __builtin_amdgcn_rcpf(1.f + __expf(-x)); }
; __device__ __forceinline__ float siluf(float x) { return x * __builtin_amdgcn_rcpf(1.f + __expf(-x)); }
; __device__ void decay_items(const Ctx& p) {
;     ...
;         for (int e = 0; e < 8; ++e) {
;           int i = half ? (32 + ib + e) : (31 - ib - e);
;           float f = lb + (1.f - lb) * sigm(bf2f(kr[e]));
;           float gl = __logf(f);
;           if (half) c += gl;
;           if (!p.dry) qp[(long)i * H0LD] = f2bf(siluf(bf2f(qr[e])) * __expf(c));
;           kb[e] = f2bf((1.f - f) * __expf(-c));
;           if (!p.dry) kp[(long)i * H0LD] = kb[e];
;           if (!half) c -= gl;
;         }
;         {
;           uint4 pk;
;           if (half) { pk.x = kb[0] | ((unsigned)kb[1] << 16); pk.y = kb[2] | ((unsigned)kb[3] << 16); pk.z = kb[4] | ((unsigned)kb[5] << 16); pk.w = kb[6] | ((unsigned)kb[7] << 16); }
;           else { pk.x = kb[7] | ((unsigned)kb[6] << 16); pk.y = kb[5] | ((unsigned)kb[4] << 16); pk.z = kb[3] | ((unsigned)kb[2] << 16); pk.w = kb[1] | ((unsigned)kb[0] << 16); }
;           *(uint4*)(kth + ((long)ck * 2048 + ch) * 64 + (half ? (32 + ib) : (24 - ib))) = pk;
	v_cndmask_b32_e64 v76, 0, 32, vcc
	v_cndmask_b32_e64 v31, v113, v106, s[8:9]
	v_ldexp_f32 v76, v72, v76
	v_add_f32_e32 v114, v107, v31
	v_sub_f32_e32 v107, v106, v107
	v_log_f32_e32 v76, v76
	v_cndmask_b32_e64 v31, v114, v107, s[8:9]
	v_add_f32_e32 v115, v108, v31
	v_sub_f32_e32 v108, v107, v108
	v_cndmask_b32_e64 v31, v115, v108, s[8:9]
	v_add_f32_e32 v116, v109, v31
	v_sub_f32_e32 v35, v108, v109
	v_mul_f32_e32 v109, 0x3f317217, v76
	v_fma_f32 v109, v76, s49, -v109
	v_fmac_f32_e32 v109, 0x3377d1cf, v76
	v_fmac_f32_e32 v109, 0x3f317217, v76
	v_cmp_lt_f32_e64 s[0:1], |v76|, s36
	v_cndmask_b32_e64 v31, v116, v35, s[8:9]
	v_pk_add_f32 v[72:73], v[72:73], 1.0 op_sel_hi:[1,0] neg_lo:[1,0] neg_hi:[1,0]
	v_cndmask_b32_e64 v76, v76, v109, s[0:1]
	v_cndmask_b32_e32 v109, 0, v192, vcc
	v_sub_f32_e32 v109, v76, v109
	v_add_f32_e32 v117, v109, v31
	v_cndmask_b32_e64 v118, v117, v35, s[8:9]
	v_mul_f32_e32 v31, 0xbfb8aa3b, v118
	v_exp_f32_e32 v76, v31
	v_cndmask_b32_e64 v0, v104, v0, s[8:9]
	v_cmp_gt_f32_e32 vcc, s48, v74
	v_sub_f32_e32 v35, v35, v109
	v_pk_mul_f32 v[72:73], v[72:73], v[76:77]
	v_rcp_f32_e32 v69, v69
	v_cvt_pk_bf16_f32 v31, v72, v73
	global_store_short_d16_hi v[4:5], v31, off
	v_mul_f32_e32 v4, 0x3fb8aa3b, v0
	v_exp_f32_e32 v4, v4
	v_mul_f32_e32 v0, 0xbfb8aa3b, v0
	v_exp_f32_e32 v5, v0
	v_cndmask_b32_e64 v0, v117, v35, s[8:9]
	v_mul_f32_e32 v4, v101, v4
	v_cvt_pk_bf16_f32 v4, v4, s0
	global_store_short v[62:63], v4, off
	v_cndmask_b32_e64 v4, 0, 32, vcc
	v_ldexp_f32 v4, v74, v4
	v_log_f32_e32 v4, v4
	v_pk_add_f32 v[72:73], v[74:75], 1.0 op_sel_hi:[1,0] neg_lo:[1,0] neg_hi:[1,0]
	v_mul_f32_e32 v103, v69, v68
	v_lshl_add_u64 v[64:65], v[50:51], 0, v[64:65]
	v_mul_f32_e32 v62, 0x3f317217, v4
	v_fma_f32 v62, v4, s49, -v62
	v_fmac_f32_e32 v62, 0x3377d1cf, v4
	v_fmac_f32_e32 v62, 0x3f317217, v4
	v_cmp_lt_f32_e64 s[0:1], |v4|, s36
	v_lshl_add_u64 v[68:69], v[48:49], 0, v[70:71]
	v_lshl_add_u64 v[70:71], v[50:51], 0, v[70:71]
	v_cndmask_b32_e64 v4, v4, v62, s[0:1]
	v_cndmask_b32_e32 v62, 0, v192, vcc
	v_sub_f32_e32 v63, v4, v62
	v_add_f32_e32 v62, v63, v0
	v_cndmask_b32_e64 v0, v62, v35, s[8:9]
	v_mul_f32_e32 v4, 0xbfb8aa3b, v0
	v_exp_f32_e32 v4, v4
	v_mul_f32_e32 v83, 0xbfb8aa3b, v82
	v_exp_f32_e32 v83, v83
	v_mul_f32_e32 v0, 0x3fb8aa3b, v0
	v_pk_mul_f32 v[4:5], v[72:73], v[4:5]
	v_exp_f32_e32 v0, v0
	v_cvt_pk_bf16_f32 v72, v4, v5
	global_store_short_d16_hi v[2:3], v72, off
	v_cndmask_b32_e64 v2, v113, v112, s[8:9]
	v_mul_f32_e32 v3, 0x3fb8aa3b, v2
	v_exp_f32_e32 v3, v3
	v_mul_f32_e32 v2, 0xbfb8aa3b, v2
	v_cndmask_b32_e64 v4, v115, v107, s[8:9]
	v_cndmask_b32_e64 v5, v116, v108, s[8:9]
	v_mul_f32_e32 v3, v100, v3
	v_cvt_pk_bf16_f32 v3, v3, s0
	global_store_short v[60:61], v3, off
	v_exp_f32_e32 v3, v2
	v_mul_f32_e32 v2, 0xbfb8aa3b, v4
	v_exp_f32_e32 v2, v2
	v_add_f32_e32 v83, 1.0, v83
	v_rcp_f32_e32 v83, v83
	v_mul_f32_e32 v0, v111, v0
	v_pk_mul_f32 v[2:3], v[92:93], v[2:3]
	v_lshl_add_u64 v[88:89], v[48:49], 0, v[86:87]
	v_cvt_pk_bf16_f32 v60, v2, v3
	v_cndmask_b32_e64 v2, v114, v106, s[8:9]
	v_mul_f32_e32 v3, 0x3fb8aa3b, v2
	v_exp_f32_e32 v3, v3
	v_mul_f32_e32 v2, 0xbfb8aa3b, v2
	global_store_short_d16_hi v[58:59], v60, off
	v_mul_f32_e32 v110, v83, v82
	v_mul_f32_e32 v3, v102, v3
	v_cvt_pk_bf16_f32 v3, v3, s0
	global_store_short v[66:67], v3, off
	v_exp_f32_e32 v3, v2
	v_mul_f32_e32 v2, 0xbfb8aa3b, v5
	v_exp_f32_e32 v2, v2
	v_lshl_add_u64 v[82:83], v[48:49], 0, v[84:85]
	v_lshl_add_u64 v[84:85], v[50:51], 0, v[84:85]
	v_cvt_pk_bf16_f32 v0, v0, s0
	v_pk_mul_f32 v[2:3], v[90:91], v[2:3]
	s_nop 0
	v_cvt_pk_bf16_f32 v58, v2, v3
	v_mul_f32_e32 v2, 0x3fb8aa3b, v4
	v_exp_f32_e32 v2, v2
	global_store_short_d16_hi v[64:65], v58, off
	v_mul_f32_e32 v2, v103, v2
	v_cvt_pk_bf16_f32 v2, v2, s0
	global_store_short v[68:69], v2, off
	global_store_short v[70:71], v60, off
	v_mul_f32_e32 v2, 0x3fb8aa3b, v5
	v_exp_f32_e32 v2, v2
	s_nop 0
	v_mul_f32_e32 v2, v105, v2
	v_cvt_pk_bf16_f32 v2, v2, s0
	global_store_short v[78:79], v2, off
	global_store_short v[80:81], v58, off
	v_mul_f32_e32 v2, 0x3fb8aa3b, v118
	v_exp_f32_e32 v2, v2
	s_nop 0
	v_mul_f32_e32 v2, v110, v2
	v_cvt_pk_bf16_f32 v2, v2, s0
	global_store_short v[82:83], v2, off
	global_store_short v[84:85], v31, off
	v_lshl_add_u64 v[2:3], v[50:51], 0, v[86:87]
	global_store_short v[88:89], v0, off
	global_store_short v[2:3], v72, off
	s_and_saveexec_b64 s[0:1], s[4:5]
	s_xor_b64 s[0:1], exec, s[0:1]
	s_or_b32 s25, s22, 32
	s_mov_b32 s26, 0x7060302
	v_perm_b32 v2, v72, v31, s26
	v_perm_b32 v3, v58, v60, s26
	v_perm_b32 v4, v58, v60, s59
	v_perm_b32 v5, v72, v31, s59
	v_mov_b32_e32 v0, s25
	s_andn2_saveexec_b64 s[0:1], s[0:1]
	s_cbranch_execz .LBB0_334
	v_and_b32_e32 v0, 0xffff0000, v60
	v_lshlrev_b32_e32 v2, 16, v60
	v_or_b32_sdwa v4, v0, v58 dst_sel:DWORD dst_unused:UNUSED_PAD src0_sel:DWORD src1_sel:WORD_1
	v_or_b32_sdwa v3, v2, v58 dst_sel:DWORD dst_unused:UNUSED_PAD src0_sel:DWORD src1_sel:WORD_0
	v_and_b32_e32 v0, 0xffff0000, v31
	v_lshlrev_b32_e32 v2, 16, v31
	v_or_b32_sdwa v5, v0, v72 dst_sel:DWORD dst_unused:UNUSED_PAD src0_sel:DWORD src1_sel:WORD_1
	v_or_b32_sdwa v2, v2, v72 dst_sel:DWORD dst_unused:UNUSED_PAD src0_sel:DWORD src1_sel:WORD_0
	v_mov_b32_e32 v0, s24
	s_branch .LBB0_334

; __device__ __forceinline__ float bf2f(u16 h) { return __uint_as_float(((unsigned)h) << 16); }
; __device__ void decay_items(const Ctx& p) {
;     ...
;       __syncthreads();
;       for (int e = tid; e < 1024; e += 512) ldsf[e] = bf2f(h0[(row0 + (e >> 4)) * H0LD + C_GA + (e & 15)]);
;       __syncthreads();
.LBB0_344:
	v_ashrrev_i32_e32 v48, 4, v2
	v_ashrrev_i32_e32 v49, 31, v48
	v_lshl_add_u64 v[48:49], s[22:23], 0, v[48:49]
	v_mov_b64_e32 v[50:51], s[14:15]
	v_ashrrev_i32_e32 v30, 4, v3
	v_mad_u64_u32 v[52:53], s[26:27], v48, s51, v[50:51]
	v_ashrrev_i32_e32 v31, 31, v30
	v_mov_b32_e32 v0, v53
	v_lshl_add_u64 v[30:31], s[28:29], 0, v[30:31]
	v_mad_u64_u32 v[48:49], s[26:27], v49, s51, v[0:1]
	v_mov_b32_e32 v53, v48
	v_mad_u64_u32 v[48:49], s[26:27], v30, s51, v[50:51]
	v_mov_b32_e32 v0, v49
	v_mad_u64_u32 v[30:31], s[26:27], v31, s51, v[0:1]
	v_lshlrev_b32_e32 v0, 1, v8
	v_mov_b32_e32 v49, v30
	v_lshl_add_u64 v[30:31], v[52:53], 0, v[0:1]
	v_add_co_u32_e32 v30, vcc, s40, v30
	v_lshl_add_u64 v[48:49], v[48:49], 0, v[0:1]
	s_nop 0
	v_addc_co_u32_e32 v31, vcc, 0, v31, vcc
	global_load_ushort v0, v[30:31], off offset:2048
	v_add_co_u32_e32 v30, vcc, s40, v48
	v_add_u32_e32 v4, -2, v4
	s_nop 0
	v_addc_co_u32_e32 v31, vcc, 0, v49, vcc
	s_waitcnt vmcnt(0)
	global_load_ushort v21, v[30:31], off offset:2048
	v_cmp_eq_u32_e32 vcc, 0, v4
	v_add_u32_e32 v3, 0x400, v3
	v_add_u32_e32 v2, 0x400, v2
	s_or_b64 s[30:31], vcc, s[30:31]
	s_waitcnt lgkmcnt(0)
	v_lshlrev_b32_e32 v0, 16, v0
	s_waitcnt vmcnt(0)
	v_lshlrev_b32_e32 v21, 16, v21
	ds_write2st64_b32 v5, v0, v21 offset1:8
	v_add_u32_e32 v5, 0x1000, v5
	s_andn2_b64 exec, exec, s[30:31]
	s_cbranch_execnz .LBB0_344
	s_or_b64 exec, exec, s[30:31]
	s_mov_b64 s[28:29], 0
	s_and_saveexec_b64 s[30:31], s[12:13]
	s_mov_b64 s[28:29], exec
	v_lshlrev_b32_e32 v0, 2, v15
	s_or_b64 exec, exec, s[30:31]
	s_orn2_b64 s[28:29], s[28:29], exec
	v_mov_b32_e32 v2, v15

;   __device__ __forceinline__ const float* in(int i) const { return ((const float* const*)(ws + OFF_TBL))[i]; }
; __device__ __forceinline__ float bf2f(u16 h) { return __uint_as_float(((unsigned)h) << 16); }
; __device__ void decay_items(const Ctx& p) {
;     ...
;       __syncthreads();
;       for (int e = tid; e < 1024; e += 512) ldsf[e] = bf2f(h0[(row0 + (e >> 4)) * H0LD + C_GA + (e & 15)]);
;       __syncthreads();
;       const int ch = g * 256 + d;
;       float wa[16];
; #pragma unroll
;       for (int r = 0; r < 16; ++r) wa[r] = p.in(4)[r * 1024 + ch];
;       const float ba = p.in(5)[ch];
;       u16* qp = h0 + row0 * H0LD + C_GQ + ch;
;       u16* kp = h0 + row0 * H0LD + C_GK + ch;
;     ...
;         {
;           uint4 pk;
;           if (half) { pk.x = kb[0] | ((unsigned)kb[1] << 16); pk.y = kb[2] | ((unsigned)kb[3] << 16); pk.z = kb[4] | ((unsigned)kb[5] << 16); pk.w = kb[6] | ((unsigned)kb[7] << 16); }
;           else { pk.x = kb[7] | ((unsigned)kb[6] << 16); pk.y = kb[5] | ((unsigned)kb[4] << 16); pk.z = kb[3] | ((unsigned)kb[2] << 16); pk.w = kb[1] | ((unsigned)kb[0] << 16); }
;           *(uint4*)(ktg + ((long)ck * 1024 + ch) * 64 + (half ? (32 + ib) : (24 - ib))) = pk;
.LBB0_350:
	v_ashrrev_i32_e32 v4, 4, v2
	v_ashrrev_i32_e32 v5, 31, v4
	v_lshl_add_u64 v[4:5], s[22:23], 0, v[4:5]
	v_mov_b64_e32 v[30:31], s[14:15]
	v_mad_u64_u32 v[30:31], s[26:27], v4, s51, v[30:31]
	v_mad_i32_i24 v31, v5, s51, v31
	v_lshlrev_b32_e32 v0, 1, v8
	v_lshl_add_u64 v[4:5], v[30:31], 0, v[0:1]
	v_add_co_u32_e32 v4, vcc, 0x7000, v4
	s_nop 1
	v_addc_co_u32_e32 v5, vcc, 0, v5, vcc
	global_load_ushort v0, v[4:5], off offset:2048
	v_cmp_lt_i32_e32 vcc, s60, v2
	s_or_b64 s[24:25], vcc, s[24:25]
	s_waitcnt vmcnt(0) lgkmcnt(0)
	v_lshlrev_b32_e32 v0, 16, v0
	ds_write_b32 v3, v0
	v_add_u32_e32 v0, 0x200, v2
	v_add_u32_e32 v3, 0x800, v3
	v_mov_b32_e32 v2, v0
	s_andn2_b64 exec, exec, s[24:25]
	s_cbranch_execnz .LBB0_350
.LBB0_351:
	s_or_b64 exec, exec, s[0:1]
	v_mov_b64_e32 v[2:3], s[18:19]
	s_waitcnt lgkmcnt(0)
	s_barrier
	global_load_dwordx4 v[2:5], v[2:3], off
	v_lshl_or_b32 v30, s68, 8, v9
	v_ashrrev_i32_e32 v31, 31, v30
	v_lshlrev_b64 v[58:59], 2, v[30:31]
	s_waitcnt vmcnt(0)
	v_mov_b32_e32 v47, v1
	v_mov_b32_e32 v45, v1
	v_mov_b32_e32 v43, v1
	v_mov_b32_e32 v41, v1
	v_mov_b32_e32 v39, v1
	v_mov_b32_e32 v37, v1
	v_mov_b32_e32 v35, v1
	v_mov_b32_e32 v33, v1
	s_mov_b32 s22, 0
	s_mov_b32 s23, -8
	s_waitcnt lgkmcnt(0)
	v_lshl_add_u64 v[54:55], v[2:3], 0, v[58:59]
	v_add_co_u32_e64 v50, s[0:1], s84, v54
	v_add_co_u32_e32 v48, vcc, 0x1000, v54
	s_nop 0
	v_addc_co_u32_e64 v51, s[0:1], 0, v55, s[0:1]
	v_add_co_u32_e64 v2, s[0:1], s85, v54
	v_addc_co_u32_e32 v49, vcc, 0, v55, vcc
	s_nop 0
	v_addc_co_u32_e64 v3, s[0:1], 0, v55, s[0:1]
	s_mov_b32 s0, 0xd000
	s_nop 0
	v_add_co_u32_e64 v56, s[0:1], s0, v54
	s_nop 1
	v_addc_co_u32_e64 v57, s[0:1], 0, v55, s[0:1]
	s_movk_i32 s0, 0x2000
	s_nop 0
	v_add_co_u32_e32 v60, vcc, s0, v54
	s_movk_i32 s0, 0x5000
	s_nop 0
	v_addc_co_u32_e32 v61, vcc, 0, v55, vcc
	v_add_co_u32_e32 v62, vcc, s43, v54
	s_nop 1
	v_addc_co_u32_e32 v63, vcc, 0, v55, vcc
	v_add_co_u32_e32 v64, vcc, s62, v54
	s_nop 1
	v_addc_co_u32_e32 v65, vcc, 0, v55, vcc
	v_add_co_u32_e32 v66, vcc, s0, v54
	s_movk_i32 s0, 0x6000
	s_nop 0
	v_addc_co_u32_e32 v67, vcc, 0, v55, vcc
	v_add_co_u32_e32 v68, vcc, s0, v54
	s_movk_i32 s0, 0x7000
	s_nop 0
	v_addc_co_u32_e32 v69, vcc, 0, v55, vcc
	v_add_co_u32_e32 v70, vcc, s0, v54
	s_mov_b32 s0, 0x9000
	s_nop 0
	v_addc_co_u32_e32 v71, vcc, 0, v55, vcc
	v_add_co_u32_e32 v52, vcc, s0, v54
	s_mov_b32 s0, 0xa000
	s_nop 0
	v_addc_co_u32_e32 v53, vcc, 0, v55, vcc
	global_load_dword v21, v[54:55], off
	global_load_dword v23, v[48:49], off
	global_load_dword v25, v[60:61], off
	s_nop 0
	global_load_dword v60, v[62:63], off
	global_load_dword v61, v[64:65], off
	s_nop 0
	global_load_dword v64, v[66:67], off
	global_load_dword v48, v[68:69], off
	global_load_dword v49, v[70:71], off
	v_add_co_u32_e32 v62, vcc, s0, v54
	s_mov_b32 s0, 0xb000
	s_nop 0
	v_addc_co_u32_e32 v63, vcc, 0, v55, vcc
	v_add_co_u32_e32 v66, vcc, s0, v54
	s_mov_b32 s0, 0xe000
	s_nop 0
	v_addc_co_u32_e32 v67, vcc, 0, v55, vcc
	v_add_co_u32_e32 v68, vcc, s0, v54
	s_mov_b32 s0, 0xf000
	s_nop 0
	v_addc_co_u32_e32 v69, vcc, 0, v55, vcc
	v_add_co_u32_e32 v70, vcc, s0, v54
	s_add_u32 s0, s14, s61
	s_nop 0
	v_addc_co_u32_e32 v71, vcc, 0, v55, vcc
	global_load_dword v50, v[50:51], off
	s_nop 0
	global_load_dword v51, v[52:53], off
	s_nop 0
	global_load_dword v52, v[62:63], off
	global_load_dword v53, v[66:67], off
	global_load_dword v54, v[2:3], off
	global_load_dword v55, v[56:57], off
	s_nop 0
	global_load_dword v56, v[68:69], off
	global_load_dword v57, v[70:71], off
	s_addc_u32 s1, s15, s55
	v_lshl_add_u64 v[2:3], v[4:5], 0, v[58:59]
	v_lshl_add_u64 v[58:59], v[30:31], 1, s[0:1]
	global_load_dword v65, v[2:3], off
	v_lshl_add_u64 v[2:3], v[58:59], 0, v[46:47]
	v_lshl_add_u64 v[4:5], v[58:59], 0, v[44:45]
	v_lshl_add_u64 v[44:45], v[58:59], 0, v[42:43]
	v_lshl_add_u64 v[46:47], v[58:59], 0, v[40:41]
	global_load_ushort v41, v[2:3], off
	global_load_ushort v40, v[2:3], off offset:2048
	global_load_ushort v42, v[4:5], off
	global_load_ushort v0, v[4:5], off offset:2048
	global_load_ushort v43, v[44:45], off
	global_load_ushort v62, v[44:45], off offset:2048
	s_nop 0
	global_load_ushort v44, v[46:47], off
	global_load_ushort v63, v[46:47], off offset:2048
	v_lshl_add_u64 v[2:3], v[58:59], 0, v[38:39]
	v_lshl_add_u64 v[4:5], v[58:59], 0, v[36:37]
	v_lshl_add_u64 v[34:35], v[58:59], 0, v[34:35]
	v_lshl_add_u64 v[32:33], v[58:59], 0, v[32:33]
	global_load_ushort v45, v[2:3], off
	global_load_ushort v36, v[2:3], off offset:2048
	global_load_ushort v37, v[4:5], off offset:2048
	global_load_ushort v38, v[34:35], off offset:2048
	global_load_ushort v46, v[4:5], off
	global_load_ushort v47, v[34:35], off
	global_load_ushort v67, v[32:33], off
	global_load_ushort v66, v[32:33], off offset:2048
	s_lshl_b64 s[0:1], s[20:21], 17
	s_add_u32 s0, s35, s0
	s_addc_u32 s1, s38, s1
	v_lshlrev_b64 v[2:3], 7, v[30:31]
	v_lshl_add_u64 v[32:33], s[0:1], 0, v[2:3]
	v_mov_b32_e32 v34, 0
	s_mov_b32 s21, 24
	s_waitcnt vmcnt(0) lgkmcnt(0)
	v_perm_b32 v3, v62, v0, s59
	v_perm_b32 v63, v36, v63, s59
	v_perm_b32 v4, v38, v37, s59
	s_branch .LBB0_353
.LBB0_352:
	s_or_b64 exec, exec, s[0:1]
	v_pk_add_f32 v[34:35], v[34:35], v[36:37] neg_lo:[0,1] neg_hi:[0,1]
	v_lshl_add_u64 v[36:37], v[0:1], 1, v[32:33]
	s_add_i32 s21, s21, -8
	s_add_i32 s22, s22, 8
	v_cndmask_b32_e64 v34, v62, v35, s[8:9]
	global_store_dwordx4 v[36:37], v[2:5], off
	s_waitcnt vmcnt(0)
	v_perm_b32 v63, v70, v39, s59
	s_cmp_gt_u32 s23, 23
	v_perm_b32 v3, v38, v31, s59
	v_perm_b32 v4, v69, v68, s59
	s_cbranch_scc1 .LBB0_330
; __device__ __forceinline__ float bf2f(u16 h) { return __uint_as_float(((unsigned)h) << 16); }
; __device__ __forceinline__ u16 f2bf(float f) { return (u16)(pack2(f, 0.f) & 0xffffu); }
; __device__ __forceinline__ float logsig(float x) { return fminf(x, 0.f) - __logf(1.f + __expf(-fabsf(x))); }
; __device__ void decay_items(const Ctx& p) {
;     ...
;       for (int ib = 0; ib < 32; ib += 8) {
;         u16 qr[8], kr[8], kb[8];
; #pragma unroll
;         for (int e = 0; e < 8; ++e) { qr[e] = qnx[e]; kr[e] = knx[e]; }
;         {
;           const int ibn = min(ib + 8, 24);
; #pragma unroll
;           for (int e = 0; e < 8; ++e) {
;             int i = half ? (32 + ibn + e) : (31 - ibn - e);
;             qnx[e] = qp[(long)i * H0LD]; knx[e] = kp[(long)i * H0LD];
;           }
;         }
; #pragma unroll
;         for (int e = 0; e < 8; ++e) {
;           int i = half ? (32 + ib + e) : (31 - ib - e);
;           float s = ba;
; #pragma unroll
;           for (int r = 0; r < 16; ++r) s += ldsf[i * 16 + r] * wa[r];
;           float gl = logsig(s) * (1.f / 16.f);
;           if (half) c += gl;
;           if (!p.dry) qp[(long)i * H0LD] = f2bf(bf2f(qr[e]) * __expf(c) * (1.f / 16.f));
;           kb[e] = f2bf(bf2f(kr[e]) * __expf(-c));
;           if (!p.dry) kp[(long)i * H0LD] = kb[e];
;           if (!half) c -= gl;
;         }
.LBB0_353:
	s_mov_b32 s0, s23
	s_add_i32 s1, s0, 16
	s_min_u32 s1, s1, 24
	s_xor_b32 s24, s1, 31
	s_or_b32 s25, s1, 32
	v_mov_b32_e32 v0, s25
	v_mov_b32_e32 v31, s24
	v_cndmask_b32_e64 v0, v0, v31, s[8:9]
	v_mul_u32_u24_e32 v0, 0x3d00, v0
	v_lshlrev_b32_e32 v0, 1, v0
	s_or_b32 s24, s1, 33
	s_sub_i32 s25, 30, s1
	v_lshl_add_u64 v[38:39], v[58:59], 0, v[0:1]
	v_mov_b32_e32 v0, s24
	v_mov_b32_e32 v31, s25
	v_cndmask_b32_e64 v0, v0, v31, s[8:9]
	v_mul_u32_u24_e32 v0, 0x3d00, v0
	v_lshlrev_b32_e32 v0, 1, v0
	s_or_b32 s24, s1, 34
	s_sub_i32 s25, 29, s1
	v_mov_b32_e32 v62, v45
	v_mov_b32_e32 v94, v44
	v_lshl_add_u64 v[44:45], v[58:59], 0, v[0:1]
	v_mov_b32_e32 v0, s24
	v_mov_b32_e32 v31, s25
	v_cndmask_b32_e64 v0, v0, v31, s[8:9]
	v_mul_u32_u24_e32 v0, 0x3d00, v0
	v_lshlrev_b32_e32 v0, 1, v0
	s_or_b32 s24, s1, 35
	s_sub_i32 s25, 28, s1
	v_mov_b32_e32 v2, v47
	v_mov_b32_e32 v37, v46
	v_lshl_add_u64 v[46:47], v[58:59], 0, v[0:1]
	v_mov_b32_e32 v0, s24
	v_mov_b32_e32 v31, s25
	v_cndmask_b32_e64 v0, v0, v31, s[8:9]
	v_mul_u32_u24_e32 v0, 0x3d00, v0
	v_lshlrev_b32_e32 v0, 1, v0
	s_or_b32 s24, s1, 36
	s_sub_i32 s25, 27, s1
	v_mov_b32_e32 v36, v67
	v_mov_b32_e32 v35, v43
	v_mov_b32_e32 v90, v42
	v_mov_b32_e32 v86, v41
	v_mov_b32_e32 v5, v66
	v_mov_b32_e32 v91, v40
	v_lshl_add_u64 v[66:67], v[58:59], 0, v[0:1]
	global_load_ushort v41, v[38:39], off
	global_load_ushort v40, v[38:39], off offset:2048
	global_load_ushort v42, v[44:45], off
	global_load_ushort v31, v[44:45], off offset:2048
	global_load_ushort v43, v[46:47], off
	s_nop 0
	global_load_ushort v38, v[46:47], off offset:2048
	global_load_ushort v44, v[66:67], off
	global_load_ushort v39, v[66:67], off offset:2048
	v_mov_b32_e32 v0, s24
	v_mov_b32_e32 v45, s25
	v_cndmask_b32_e64 v0, v0, v45, s[8:9]
	v_mul_u32_u24_e32 v0, 0x3d00, v0
	v_lshlrev_b32_e32 v0, 1, v0
	s_or_b32 s24, s1, 37
	s_sub_i32 s25, 26, s1
	v_lshl_add_u64 v[46:47], v[58:59], 0, v[0:1]
	v_mov_b32_e32 v0, s24
	v_mov_b32_e32 v45, s25
	v_cndmask_b32_e64 v0, v0, v45, s[8:9]
	v_mul_u32_u24_e32 v0, 0x3d00, v0
	v_lshlrev_b32_e32 v0, 1, v0
	s_or_b32 s24, s1, 38
	s_sub_i32 s25, 25, s1
	v_lshl_add_u64 v[82:83], v[58:59], 0, v[0:1]
	v_mov_b32_e32 v0, s24
	v_mov_b32_e32 v45, s25
	v_cndmask_b32_e64 v0, v0, v45, s[8:9]
	v_mul_u32_u24_e32 v0, 0x3d00, v0
	v_lshlrev_b32_e32 v0, 1, v0
	s_add_i32 s0, s0, 40
	s_add_i32 s25, s21, 7
	v_lshl_add_u64 v[84:85], v[58:59], 0, v[0:1]
	v_mov_b32_e32 v0, s0
	v_mov_b32_e32 v45, s25
	v_cndmask_b32_e64 v87, v0, v45, s[8:9]
	v_lshl_add_u32 v0, v87, 6, 16
	ds_read_b128 v[66:69], v0
	ds_read_b128 v[70:73], v0 offset:16
	ds_read_b128 v[74:77], v0 offset:32
	ds_read_b128 v[78:81], v0 offset:48
	s_or_b32 s24, s1, 39
	s_sub_i32 s1, 24, s1
	v_mov_b32_e32 v45, s24
	s_waitcnt lgkmcnt(0)
	v_fma_f32 v0, v21, v66, v65
	v_fmac_f32_e32 v0, v23, v67
	v_fmac_f32_e32 v0, v25, v68
	v_fmac_f32_e32 v0, v60, v69
	v_fmac_f32_e32 v0, v61, v70
	v_fmac_f32_e32 v0, v64, v71
	v_fmac_f32_e32 v0, v48, v72
	v_fmac_f32_e32 v0, v49, v73
	v_pk_mul_f32 v[66:67], v[50:51], v[74:75]
	s_add_i32 s23, s23, 8
	v_add_f32_e32 v0, v0, v66
	v_add_f32_e32 v0, v0, v67
	v_pk_mul_f32 v[66:67], v[52:53], v[76:77]
	v_lshlrev_b32_e32 v62, 16, v62
	v_add_f32_e32 v0, v0, v66
	v_add_f32_e32 v0, v0, v67
	v_pk_mul_f32 v[66:67], v[54:55], v[78:79]
	s_nop 0
	v_add_f32_e32 v0, v0, v66
	v_add_f32_e32 v0, v0, v67
	v_pk_mul_f32 v[66:67], v[56:57], v[80:81]
	s_nop 0
	v_add_f32_e32 v0, v0, v66
	v_add_f32_e32 v66, v0, v67
	v_mul_f32_e64 v0, |v66|, s94
	v_exp_f32_e32 v0, v0
	v_mov_b32_e32 v67, s1
	v_cndmask_b32_e64 v45, v45, v67, s[8:9]
	v_mul_u32_u24_e32 v45, 0x3d00, v45
	v_add_f32_e32 v0, 1.0, v0
	v_cmp_gt_f32_e32 vcc, s48, v0
	s_nop 1
	v_cndmask_b32_e64 v67, 0, 32, vcc
	v_ldexp_f32 v0, v0, v67
	v_log_f32_e32 v67, v0
	v_lshlrev_b32_e32 v0, 1, v45
	v_lshl_add_u64 v[72:73], v[58:59], 0, v[0:1]
	v_min_f32_e32 v0, 0, v66
	v_mul_f32_e32 v45, 0x3f317217, v67
	v_fma_f32 v45, v67, s49, -v45
	v_fmac_f32_e32 v45, 0x3377d1cf, v67
	v_fmac_f32_e32 v45, 0x3f317217, v67
	v_cmp_lt_f32_e64 s[0:1], |v67|, s36
	v_cndmask_b32_e32 v66, 0, v192, vcc
	s_nop 0
	v_cndmask_b32_e64 v45, v67, v45, s[0:1]
	v_sub_f32_e32 v45, v45, v66
	v_sub_f32_e32 v92, v0, v45
	v_fmamk_f32 v93, v92, 0x3d800000, v34
	v_cndmask_b32_e64 v71, v93, v34, s[8:9]
	v_mul_f32_e32 v0, 0x3fb8aa3b, v71
	v_exp_f32_e32 v0, v0
	global_load_ushort v45, v[46:47], off
	global_load_ushort v70, v[46:47], off offset:2048
	s_nop 0
	global_load_ushort v46, v[82:83], off
	global_load_ushort v68, v[82:83], off offset:2048
	global_load_ushort v47, v[84:85], off
	global_load_ushort v69, v[84:85], off offset:2048
	global_load_ushort v67, v[72:73], off
	global_load_ushort v66, v[72:73], off offset:2048
	v_lshlrev_b32_e32 v72, 16, v86
	s_add_i32 s1, s21, 6
	v_mul_f32_e32 v0, v0, v72
	v_mul_f32_e32 v0, 0x3d800000, v0
	v_cvt_pk_bf16_f32 v72, v0, s0
	v_mul_lo_u32 v0, v87, s58
	v_lshl_add_u64 v[88:89], v[0:1], 1, v[58:59]
	s_or_b32 s0, s23, 33
	global_store_short v[88:89], v72, off
	v_mul_f32_e32 v0, 0xbfb8aa3b, v71
	v_mov_b32_e32 v71, s0
	v_mov_b32_e32 v72, s1
	v_cndmask_b32_e64 v95, v71, v72, s[8:9]
	v_lshl_add_u32 v71, v95, 6, 16
	ds_read_b128 v[72:75], v71
	ds_read_b128 v[76:79], v71 offset:16
	ds_read_b128 v[80:83], v71 offset:32
	ds_read_b128 v[84:87], v71 offset:48
	v_exp_f32_e32 v0, v0
	v_fmac_f32_e32 v34, 0xbd800000, v92
	v_cndmask_b32_e64 v93, v93, v34, s[8:9]
	s_waitcnt lgkmcnt(0)
; __device__ __forceinline__ float bf2f(u16 h) { return __uint_as_float(((unsigned)h) << 16); }
; __device__ __forceinline__ u16 f2bf(float f) { return (u16)(pack2(f, 0.f) & 0xffffu); }
; __device__ __forceinline__ float logsig(float x) { return fminf(x, 0.f) - __logf(1.f + __expf(-fabsf(x))); }
; __device__ void decay_items(const Ctx& p) {
;     ...
; #pragma unroll
;         for (int e = 0; e < 8; ++e) {
;           int i = half ? (32 + ib + e) : (31 - ib - e);
;           float s = ba;
; #pragma unroll
;           for (int r = 0; r < 16; ++r) s += ldsf[i * 16 + r] * wa[r];
;           float gl = logsig(s) * (1.f / 16.f);
;           if (half) c += gl;
;           if (!p.dry) qp[(long)i * H0LD] = f2bf(bf2f(qr[e]) * __expf(c) * (1.f / 16.f));
;           kb[e] = f2bf(bf2f(kr[e]) * __expf(-c));
;           if (!p.dry) kp[(long)i * H0LD] = kb[e];
;           if (!half) c -= gl;
;         }
	v_fma_f32 v71, v21, v72, v65
	v_fmac_f32_e32 v71, v23, v73
	v_fmac_f32_e32 v71, v25, v74
	v_fmac_f32_e32 v71, v60, v75
	v_fmac_f32_e32 v71, v61, v76
	v_fmac_f32_e32 v71, v64, v77
	v_fmac_f32_e32 v71, v48, v78
	v_fmac_f32_e32 v71, v49, v79
	v_pk_mul_f32 v[72:73], v[50:51], v[80:81]
	s_nop 0
	v_add_f32_e32 v71, v71, v72
	v_add_f32_e32 v71, v71, v73
	v_pk_mul_f32 v[72:73], v[52:53], v[82:83]
	s_nop 0
	v_add_f32_e32 v71, v71, v72
	v_add_f32_e32 v71, v71, v73
	v_pk_mul_f32 v[72:73], v[54:55], v[84:85]
	s_nop 0
	v_add_f32_e32 v71, v71, v72
	v_add_f32_e32 v71, v71, v73
	v_pk_mul_f32 v[72:73], v[56:57], v[86:87]
	s_nop 0
	v_add_f32_e32 v71, v71, v72
	v_add_f32_e32 v72, v71, v73
	v_mul_f32_e64 v71, |v72|, s94
	v_exp_f32_e32 v73, v71
	v_lshlrev_b32_e32 v71, 16, v91
	v_mul_f32_e32 v0, v0, v71
	v_cvt_pk_bf16_f32 v71, v0, s0
	v_add_f32_e32 v0, 1.0, v73
	v_cmp_gt_f32_e32 vcc, s48, v0
	v_min_f32_e32 v72, 0, v72
	global_store_short v[88:89], v71, off offset:2048
	v_cndmask_b32_e64 v73, 0, 32, vcc
	v_ldexp_f32 v0, v0, v73
	v_log_f32_e32 v0, v0
	s_nop 0
	v_mul_f32_e32 v73, 0x3f317217, v0
	v_fma_f32 v73, v0, s49, -v73
	v_fmac_f32_e32 v73, 0x3377d1cf, v0
	v_fmac_f32_e32 v73, 0x3f317217, v0
	v_cmp_lt_f32_e64 s[0:1], |v0|, s36
	s_nop 1
	v_cndmask_b32_e64 v0, v0, v73, s[0:1]
	v_cndmask_b32_e32 v73, 0, v192, vcc
	v_sub_f32_e32 v0, v0, v73
	v_sub_f32_e32 v0, v72, v0
	v_fmac_f32_e32 v93, 0x3d800000, v0
	v_cndmask_b32_e64 v92, v93, v34, s[8:9]
	v_mul_f32_e32 v72, 0x3fb8aa3b, v92
	v_exp_f32_e32 v72, v72
	v_mul_f32_e32 v88, 0x3d800000, v0
	v_lshlrev_b32_e32 v0, 16, v90
	s_or_b32 s0, s23, 34
	s_add_i32 s1, s21, 5
	v_mul_f32_e32 v0, v72, v0
	v_mov_b32_e32 v72, s0
	v_mov_b32_e32 v73, s1
	v_cndmask_b32_e64 v89, v72, v73, s[8:9]
	v_lshl_add_u32 v84, v89, 6, 16
	ds_read_b128 v[72:75], v84
	v_mul_f32_e32 v0, 0x3d800000, v0
	v_cvt_pk_bf16_f32 v96, v0, s0
	ds_read_b128 v[76:79], v84 offset:16
	ds_read_b128 v[80:83], v84 offset:32
	ds_read_b128 v[84:87], v84 offset:48
	s_or_b32 s0, s23, 35
	s_waitcnt lgkmcnt(0)
	v_fma_f32 v0, v21, v72, v65
	v_fmac_f32_e32 v0, v23, v73
	v_fmac_f32_e32 v0, v25, v74
	v_fmac_f32_e32 v0, v60, v75
	v_fmac_f32_e32 v0, v61, v76
	v_fmac_f32_e32 v0, v64, v77
	v_fmac_f32_e32 v0, v48, v78
	v_fmac_f32_e32 v0, v49, v79
	v_pk_mul_f32 v[72:73], v[50:51], v[80:81]
	s_add_i32 s1, s21, 4
	v_add_f32_e32 v0, v0, v72
	v_add_f32_e32 v0, v0, v73
	v_pk_mul_f32 v[72:73], v[52:53], v[82:83]
	s_nop 0
	v_add_f32_e32 v0, v0, v72
	v_add_f32_e32 v0, v0, v73
	v_pk_mul_f32 v[72:73], v[54:55], v[84:85]
	s_nop 0
	v_add_f32_e32 v0, v0, v72
	v_add_f32_e32 v0, v0, v73
	v_pk_mul_f32 v[72:73], v[56:57], v[86:87]
	s_nop 0
	v_add_f32_e32 v0, v0, v72
	v_add_f32_e32 v72, v0, v73
	v_mul_f32_e64 v0, |v72|, s94
	v_exp_f32_e32 v73, v0
	v_mul_lo_u32 v0, v95, s58
	v_lshl_add_u64 v[90:91], v[0:1], 1, v[58:59]
	v_min_f32_e32 v95, 0, v72
	v_add_f32_e32 v0, 1.0, v73
	v_cmp_gt_f32_e32 vcc, s48, v0
	global_store_short v[90:91], v96, off
	s_nop 0
	v_cndmask_b32_e64 v73, 0, 32, vcc
	v_ldexp_f32 v0, v0, v73
	v_log_f32_e32 v0, v0
	v_mul_f32_e32 v73, 0xbfb8aa3b, v92
	v_exp_f32_e32 v92, v73
	v_mov_b32_e32 v73, s1
	v_mul_f32_e32 v72, 0x3f317217, v0
	v_fma_f32 v76, v0, s49, -v72
	v_mov_b32_e32 v72, s0
	v_cndmask_b32_e64 v96, v72, v73, s[8:9]
	v_lshl_add_u32 v84, v96, 6, 16
	ds_read_b128 v[72:75], v84
	v_fmac_f32_e32 v76, 0x3377d1cf, v0
	v_fmac_f32_e32 v76, 0x3f317217, v0
	v_cmp_lt_f32_e64 s[0:1], |v0|, s36
	s_waitcnt lgkmcnt(0)
	v_fma_f32 v97, v21, v72, v65
	v_cndmask_b32_e64 v0, v0, v76, s[0:1]
	ds_read_b128 v[76:79], v84 offset:16
	ds_read_b128 v[80:83], v84 offset:32
	ds_read_b128 v[84:87], v84 offset:48
	v_fmac_f32_e32 v97, v23, v73
	v_fmac_f32_e32 v97, v25, v74
	v_fmac_f32_e32 v97, v60, v75
	s_waitcnt lgkmcnt(0)
	v_fmac_f32_e32 v97, v61, v76
	v_fmac_f32_e32 v97, v64, v77
	v_pk_mul_f32 v[72:73], v[48:49], v[78:79]
	v_lshlrev_b32_e32 v77, 16, v35
	v_add_f32_e32 v72, v97, v72
	v_add_f32_e32 v74, v72, v73
	v_pk_mul_f32 v[72:73], v[50:51], v[80:81]
	s_nop 0
	v_add_f32_e32 v72, v74, v72
	v_add_f32_e32 v74, v72, v73
	v_pk_mul_f32 v[72:73], v[52:53], v[82:83]
	s_nop 0
	v_add_f32_e32 v72, v74, v72
	v_add_f32_e32 v74, v72, v73
	v_pk_mul_f32 v[72:73], v[54:55], v[84:85]
	s_nop 0
	v_add_f32_e32 v72, v74, v72
	v_add_f32_e32 v74, v72, v73
	v_pk_mul_f32 v[72:73], v[56:57], v[86:87]
	s_nop 0
	v_add_f32_e32 v72, v74, v72
	v_add_f32_e32 v72, v72, v73
	v_mul_f32_e64 v73, |v72|, s94
	v_exp_f32_e32 v73, v73
	v_cndmask_b32_e32 v74, 0, v192, vcc
	v_sub_f32_e32 v0, v0, v74
	v_sub_f32_e32 v76, v95, v0
	v_add_f32_e32 v0, 1.0, v73
	v_cmp_gt_f32_e32 vcc, s48, v0
	v_min_f32_e32 v35, 0, v72
	v_and_b32_e32 v95, 0xffff0000, v63
	v_cndmask_b32_e64 v73, 0, 32, vcc
	v_ldexp_f32 v0, v0, v73
	v_log_f32_e32 v73, v0
	v_mul_lo_u32 v0, v89, s58
	v_lshl_add_u64 v[74:75], v[0:1], 1, v[58:59]
	v_mul_f32_e32 v72, 0x3f317217, v73
	v_fma_f32 v72, v73, s49, -v72
	v_fmac_f32_e32 v72, 0x3377d1cf, v73
	v_fmac_f32_e32 v72, 0x3f317217, v73
	v_cmp_lt_f32_e64 s[0:1], |v73|, s36
	s_nop 1
	v_cndmask_b32_e64 v72, v73, v72, s[0:1]
	v_cndmask_b32_e32 v73, 0, v192, vcc
	v_sub_f32_e32 v89, v72, v73
	v_pk_add_f32 v[34:35], v[34:35], v[88:89] neg_lo:[0,1] neg_hi:[0,1]
	v_and_b32_e32 v73, 0xffff0000, v3
	v_cndmask_b32_e64 v78, v93, v34, s[8:9]
	v_fmac_f32_e32 v78, 0x3d800000, v76
	v_cndmask_b32_e64 v79, v78, v34, s[8:9]
	v_mul_f32_e32 v72, 0x3fb8aa3b, v79
	v_exp_f32_e32 v80, v72
	v_lshlrev_b32_e32 v72, 16, v3
	v_mul_f32_e32 v3, 0xbfb8aa3b, v79
	v_exp_f32_e32 v93, v3
	v_fmamk_f32 v3, v76, 0xbd800000, v34
	v_mul_f32_e32 v0, v80, v77
	v_cndmask_b32_e64 v34, v78, v3, s[8:9]
	v_mul_f32_e32 v0, 0x3d800000, v0
	v_pk_mul_f32 v[72:73], v[92:93], v[72:73]
	v_fmac_f32_e32 v34, 0x3d800000, v35
	v_cvt_pk_bf16_f32 v0, v0, s0
	v_cvt_pk_bf16_f32 v72, v72, v73
	v_cndmask_b32_e64 v73, v34, v3, s[8:9]
	global_store_short v[74:75], v0, off
	v_mul_f32_e32 v0, 0x3fb8aa3b, v73
	v_exp_f32_e32 v0, v0
	global_store_short v[90:91], v72, off offset:2048
	global_store_short_d16_hi v[74:75], v72, off offset:2048
	v_lshlrev_b32_e32 v74, 16, v94
	s_or_b32 s0, s23, 36
	s_add_i32 s1, s21, 3
	v_mul_f32_e32 v0, v0, v74
	v_mov_b32_e32 v74, s0
	v_mov_b32_e32 v75, s1
	v_cndmask_b32_e64 v92, v74, v75, s[8:9]
	v_lshl_add_u32 v86, v92, 6, 16
	ds_read_b128 v[74:77], v86
	v_mul_f32_e32 v0, 0x3d800000, v0
	v_cvt_pk_bf16_f32 v93, v0, s0
	ds_read_b128 v[78:81], v86 offset:16
	ds_read_b128 v[82:85], v86 offset:32
	ds_read_b128 v[86:89], v86 offset:48
	v_fmac_f32_e32 v3, 0xbd800000, v35
	s_waitcnt lgkmcnt(0)
; __device__ __forceinline__ float bf2f(u16 h) { return __uint_as_float(((unsigned)h) << 16); }
; __device__ __forceinline__ u16 f2bf(float f) { return (u16)(pack2(f, 0.f) & 0xffffu); }
; __device__ __forceinline__ float logsig(float x) { return fminf(x, 0.f) - __logf(1.f + __expf(-fabsf(x))); }
; __device__ void decay_items(const Ctx& p) {
;     ...
; #pragma unroll
;         for (int e = 0; e < 8; ++e) {
;           int i = half ? (32 + ib + e) : (31 - ib - e);
;           float s = ba;
; #pragma unroll
;           for (int r = 0; r < 16; ++r) s += ldsf[i * 16 + r] * wa[r];
;           float gl = logsig(s) * (1.f / 16.f);
;           if (half) c += gl;
;           if (!p.dry) qp[(long)i * H0LD] = f2bf(bf2f(qr[e]) * __expf(c) * (1.f / 16.f));
;           kb[e] = f2bf(bf2f(kr[e]) * __expf(-c));
;           if (!p.dry) kp[(long)i * H0LD] = kb[e];
;           if (!half) c -= gl;
;         }
	v_fma_f32 v0, v21, v74, v65
	v_fmac_f32_e32 v0, v23, v75
	v_fmac_f32_e32 v0, v25, v76
	v_fmac_f32_e32 v0, v60, v77
	v_fmac_f32_e32 v0, v61, v78
	v_fmac_f32_e32 v0, v64, v79
	v_fmac_f32_e32 v0, v48, v80
	v_fmac_f32_e32 v0, v49, v81
	v_pk_mul_f32 v[74:75], v[50:51], v[82:83]
	v_lshlrev_b32_e32 v94, 16, v63
	v_add_f32_e32 v0, v0, v74
	v_add_f32_e32 v0, v0, v75
	v_pk_mul_f32 v[74:75], v[52:53], v[84:85]
	s_nop 0
	v_add_f32_e32 v0, v0, v74
	v_add_f32_e32 v0, v0, v75
	v_pk_mul_f32 v[74:75], v[54:55], v[86:87]
	s_nop 0
	v_add_f32_e32 v0, v0, v74
	v_add_f32_e32 v0, v0, v75
	v_pk_mul_f32 v[74:75], v[56:57], v[88:89]
	s_nop 0
	v_add_f32_e32 v0, v0, v74
	v_add_f32_e32 v74, v0, v75
	v_mul_f32_e64 v0, |v74|, s94
	v_exp_f32_e32 v75, v0
	v_mul_lo_u32 v0, v96, s58
	v_lshl_add_u64 v[90:91], v[0:1], 1, v[58:59]
	v_cndmask_b32_e64 v96, v34, v3, s[8:9]
	v_add_f32_e32 v0, 1.0, v75
	v_cmp_gt_f32_e32 vcc, s48, v0
	v_min_f32_e32 v34, 0, v74
	global_store_short v[90:91], v93, off
	v_cndmask_b32_e64 v75, 0, 32, vcc
	v_ldexp_f32 v0, v0, v75
	v_log_f32_e32 v0, v0
	s_nop 0
	v_mul_f32_e32 v35, 0x3f317217, v0
	v_fma_f32 v35, v0, s49, -v35
	v_fmac_f32_e32 v35, 0x3377d1cf, v0
	v_fmac_f32_e32 v35, 0x3f317217, v0
	v_cmp_lt_f32_e64 s[0:1], |v0|, s36
	s_nop 1
	v_cndmask_b32_e64 v0, v0, v35, s[0:1]
	v_cndmask_b32_e32 v35, 0, v192, vcc
	v_sub_f32_e32 v0, v0, v35
	v_sub_f32_e32 v97, v34, v0
	v_fmac_f32_e32 v96, 0x3d800000, v97
	v_cndmask_b32_e64 v35, v96, v3, s[8:9]
	v_mul_f32_e32 v0, 0x3fb8aa3b, v35
	v_exp_f32_e32 v0, v0
	s_add_i32 s1, s21, 2
	v_mul_f32_e32 v34, 0xbfb8aa3b, v73
	v_exp_f32_e32 v34, v34
	v_mul_f32_e32 v0, v0, v62
	v_mul_f32_e32 v0, 0x3d800000, v0
	v_cvt_pk_bf16_f32 v62, v0, s0
	v_mul_lo_u32 v0, v92, s58
	v_lshl_add_u64 v[92:93], v[0:1], 1, v[58:59]
	v_mul_f32_e32 v0, 0xbfb8aa3b, v35
	s_or_b32 s0, s23, 37
	global_store_short v[92:93], v62, off
	v_exp_f32_e32 v35, v0
	v_mov_b32_e32 v0, s0
	v_mov_b32_e32 v62, s1
	v_cndmask_b32_e64 v0, v0, v62, s[8:9]
	v_lshl_add_u32 v62, v0, 6, 16
	ds_read_b128 v[74:77], v62
	ds_read_b128 v[78:81], v62 offset:16
	ds_read_b128 v[82:85], v62 offset:32
	ds_read_b128 v[86:89], v62 offset:48
	v_pk_mul_f32 v[34:35], v[34:35], v[94:95]
	v_fmac_f32_e32 v3, 0xbd800000, v97
	v_cndmask_b32_e64 v94, v96, v3, s[8:9]
	s_waitcnt lgkmcnt(0)
	v_fma_f32 v73, v21, v74, v65
	v_fmac_f32_e32 v73, v23, v75
	v_fmac_f32_e32 v73, v25, v76
	v_fmac_f32_e32 v73, v60, v77
	v_fmac_f32_e32 v73, v61, v78
	v_fmac_f32_e32 v73, v64, v79
	v_fmac_f32_e32 v73, v48, v80
	v_fmac_f32_e32 v73, v49, v81
	v_pk_mul_f32 v[62:63], v[50:51], v[82:83]
	v_mul_lo_u32 v0, v0, s58
	v_add_f32_e32 v62, v73, v62
	v_add_f32_e32 v73, v62, v63
	v_pk_mul_f32 v[62:63], v[52:53], v[84:85]
	s_nop 0
	v_add_f32_e32 v62, v73, v62
	v_add_f32_e32 v73, v62, v63
	v_pk_mul_f32 v[62:63], v[54:55], v[86:87]
	s_nop 0
	v_add_f32_e32 v62, v73, v62
	v_add_f32_e32 v73, v62, v63
	v_pk_mul_f32 v[62:63], v[56:57], v[88:89]
	s_nop 0
	v_add_f32_e32 v62, v73, v62
	v_add_f32_e32 v62, v62, v63
	v_mul_f32_e64 v63, |v62|, s94
	v_exp_f32_e32 v63, v63
	v_cvt_pk_bf16_f32 v73, v34, v35
	global_store_short v[90:91], v73, off offset:2048
	global_store_short_d16_hi v[92:93], v73, off offset:2048
	v_add_f32_e32 v34, 1.0, v63
	v_cmp_gt_f32_e32 vcc, s48, v34
	v_lshl_add_u64 v[90:91], v[0:1], 1, v[58:59]
	s_nop 0
	v_cndmask_b32_e64 v35, 0, 32, vcc
	v_ldexp_f32 v34, v34, v35
	v_log_f32_e32 v34, v34
	v_min_f32_e32 v35, 0, v62
	v_mul_f32_e32 v62, 0x3f317217, v34
	v_fma_f32 v62, v34, s49, -v62
	v_fmac_f32_e32 v62, 0x3377d1cf, v34
	v_fmac_f32_e32 v62, 0x3f317217, v34
	v_cmp_lt_f32_e64 s[0:1], |v34|, s36
	s_nop 1
	v_cndmask_b32_e64 v34, v34, v62, s[0:1]
	v_cndmask_b32_e32 v62, 0, v192, vcc
	v_sub_f32_e32 v34, v34, v62
	v_sub_f32_e32 v34, v35, v34
	v_fmac_f32_e32 v94, 0x3d800000, v34
	v_cndmask_b32_e64 v95, v94, v3, s[8:9]
	v_mul_f32_e32 v35, 0x3fb8aa3b, v95
	v_exp_f32_e32 v62, v35
	v_mul_f32_e32 v35, 0x3d800000, v34
	v_lshlrev_b32_e32 v34, 16, v37
	s_or_b32 s0, s23, 38
	s_add_i32 s1, s21, 1
	v_mul_f32_e32 v34, v62, v34
	v_mov_b32_e32 v37, s0
	v_mov_b32_e32 v62, s1
	v_cndmask_b32_e64 v37, v37, v62, s[8:9]
	v_lshl_add_u32 v62, v37, 6, 16
	ds_read_b128 v[74:77], v62
	ds_read_b128 v[78:81], v62 offset:16
	ds_read_b128 v[82:85], v62 offset:32
	ds_read_b128 v[86:89], v62 offset:48
	v_mul_f32_e32 v34, 0x3d800000, v34
	v_cvt_pk_bf16_f32 v34, v34, s0
	global_store_short v[90:91], v34, off
	s_waitcnt lgkmcnt(0)
; __device__ __forceinline__ float bf2f(u16 h) { return __uint_as_float(((unsigned)h) << 16); }
; __device__ __forceinline__ u16 f2bf(float f) { return (u16)(pack2(f, 0.f) & 0xffffu); }
; __device__ __forceinline__ float logsig(float x) { return fminf(x, 0.f) - __logf(1.f + __expf(-fabsf(x))); }
; __device__ void decay_items(const Ctx& p) {
;     ...
; #pragma unroll
;         for (int e = 0; e < 8; ++e) {
;           int i = half ? (32 + ib + e) : (31 - ib - e);
;           float s = ba;
; #pragma unroll
;           for (int r = 0; r < 16; ++r) s += ldsf[i * 16 + r] * wa[r];
;           float gl = logsig(s) * (1.f / 16.f);
;           if (half) c += gl;
;           if (!p.dry) qp[(long)i * H0LD] = f2bf(bf2f(qr[e]) * __expf(c) * (1.f / 16.f));
;           kb[e] = f2bf(bf2f(kr[e]) * __expf(-c));
;           if (!p.dry) kp[(long)i * H0LD] = kb[e];
;           if (!half) c -= gl;
;         }
;         {
;           uint4 pk;
;           if (half) { pk.x = kb[0] | ((unsigned)kb[1] << 16); pk.y = kb[2] | ((unsigned)kb[3] << 16); pk.z = kb[4] | ((unsigned)kb[5] << 16); pk.w = kb[6] | ((unsigned)kb[7] << 16); }
;           else { pk.x = kb[7] | ((unsigned)kb[6] << 16); pk.y = kb[5] | ((unsigned)kb[4] << 16); pk.z = kb[3] | ((unsigned)kb[2] << 16); pk.w = kb[1] | ((unsigned)kb[0] << 16); }
;           *(uint4*)(ktg + ((long)ck * 1024 + ch) * 64 + (half ? (32 + ib) : (24 - ib))) = pk;
	v_fma_f32 v74, v21, v74, v65
	v_fmac_f32_e32 v74, v23, v75
	v_fmac_f32_e32 v74, v25, v76
	v_fmac_f32_e32 v74, v60, v77
	v_fmac_f32_e32 v74, v61, v78
	v_fmac_f32_e32 v74, v64, v79
	v_fmac_f32_e32 v74, v48, v80
	v_fmac_f32_e32 v74, v49, v81
	v_pk_mul_f32 v[62:63], v[50:51], v[82:83]
	v_mov_b32_e32 v75, s21
	v_add_f32_e32 v62, v74, v62
	v_add_f32_e32 v74, v62, v63
	v_pk_mul_f32 v[62:63], v[52:53], v[84:85]
	s_nop 0
	v_add_f32_e32 v62, v74, v62
	v_add_f32_e32 v74, v62, v63
	v_pk_mul_f32 v[62:63], v[54:55], v[86:87]
	s_nop 0
	v_add_f32_e32 v62, v74, v62
	v_add_f32_e32 v74, v62, v63
	v_pk_mul_f32 v[62:63], v[56:57], v[88:89]
	s_nop 0
	v_add_f32_e32 v62, v74, v62
	v_add_f32_e32 v63, v62, v63
	v_mul_f32_e64 v62, |v63|, s94
	v_exp_f32_e32 v62, v62
	s_nop 0
	v_add_f32_e32 v0, 1.0, v62
	v_cmp_gt_f32_e32 vcc, s48, v0
	s_nop 1
	v_cndmask_b32_e64 v34, 0, 32, vcc
	v_ldexp_f32 v0, v0, v34
	v_log_f32_e32 v0, v0
	v_mul_f32_e32 v34, 0xbfb8aa3b, v95
	v_exp_f32_e32 v62, v34
	v_min_f32_e32 v34, 0, v63
	v_mul_f32_e32 v63, 0x3f317217, v0
	v_fma_f32 v63, v0, s49, -v63
	v_fmac_f32_e32 v63, 0x3377d1cf, v0
	v_fmac_f32_e32 v63, 0x3f317217, v0
	v_cmp_lt_f32_e64 s[0:1], |v0|, s36
	s_nop 1
	v_cndmask_b32_e64 v0, v0, v63, s[0:1]
	s_or_b32 s0, s23, 39
	v_mov_b32_e32 v74, s0
	v_cndmask_b32_e64 v92, v74, v75, s[8:9]
	v_lshl_add_u32 v86, v92, 6, 16
	ds_read_b128 v[74:77], v86
	v_cndmask_b32_e32 v63, 0, v192, vcc
	v_sub_f32_e32 v0, v0, v63
	ds_read_b128 v[78:81], v86 offset:16
	ds_read_b128 v[82:85], v86 offset:32
	ds_read_b128 v[86:89], v86 offset:48
	s_waitcnt lgkmcnt(0)
	v_fma_f32 v63, v21, v74, v65
	v_fmac_f32_e32 v63, v23, v75
	v_fmac_f32_e32 v63, v25, v76
	v_fmac_f32_e32 v63, v60, v77
	v_fmac_f32_e32 v63, v61, v78
	v_fmac_f32_e32 v63, v64, v79
	v_pk_mul_f32 v[74:75], v[48:49], v[80:81]
	v_sub_f32_e32 v76, v34, v0
	v_add_f32_e32 v63, v63, v74
	v_add_f32_e32 v63, v63, v75
	v_pk_mul_f32 v[74:75], v[50:51], v[82:83]
	v_lshlrev_b32_e32 v78, 16, v2
	v_add_f32_e32 v63, v63, v74
	v_add_f32_e32 v63, v63, v75
	v_pk_mul_f32 v[74:75], v[52:53], v[84:85]
	v_lshlrev_b32_e32 v79, 16, v36
	v_add_f32_e32 v63, v63, v74
	v_add_f32_e32 v63, v63, v75
	v_pk_mul_f32 v[74:75], v[54:55], v[86:87]
	v_mul_f32_e32 v141, 0x3d800000, v76
	v_add_f32_e32 v63, v63, v74
	v_add_f32_e32 v63, v63, v75
	v_pk_mul_f32 v[74:75], v[56:57], v[88:89]
	s_nop 0
	v_add_f32_e32 v63, v63, v74
	v_add_f32_e32 v63, v63, v75
	v_mul_f32_e64 v74, |v63|, s94
	v_exp_f32_e32 v74, v74
	s_nop 0
	v_add_f32_e32 v0, 1.0, v74
	v_cmp_gt_f32_e32 vcc, s48, v0
	s_nop 1
	v_cndmask_b32_e64 v2, 0, 32, vcc
	v_ldexp_f32 v0, v0, v2
	v_log_f32_e32 v34, v0
	v_mul_lo_u32 v0, v37, s58
	v_lshl_add_u64 v[74:75], v[0:1], 1, v[58:59]
	v_min_f32_e32 v2, 0, v63
	v_mul_f32_e32 v0, 0x3f317217, v34
	v_fma_f32 v0, v34, s49, -v0
	v_fmac_f32_e32 v0, 0x3377d1cf, v34
	v_fmac_f32_e32 v0, 0x3f317217, v34
	v_cmp_lt_f32_e64 s[0:1], |v34|, s36
	s_nop 1
	v_cndmask_b32_e64 v0, v34, v0, s[0:1]
	v_cndmask_b32_e32 v34, 0, v192, vcc
	v_sub_f32_e32 v34, v0, v34
	v_pk_add_f32 v[2:3], v[2:3], v[34:35] neg_lo:[0,1] neg_hi:[0,1]
	s_nop 0
	v_cndmask_b32_e64 v36, v94, v3, s[8:9]
	v_fmac_f32_e32 v36, 0x3d800000, v76
	v_cndmask_b32_e64 v34, v36, v3, s[8:9]
	v_mul_f32_e32 v0, 0x3fb8aa3b, v34
	v_exp_f32_e32 v35, v0
	v_mul_lo_u32 v0, v92, s58
	v_mul_f32_e32 v34, 0xbfb8aa3b, v34
	v_lshl_add_u64 v[76:77], v[0:1], 1, v[58:59]
	v_lshlrev_b32_e32 v0, 16, v5
	v_mul_f32_e32 v5, v35, v78
	v_exp_f32_e32 v63, v34
	v_mul_f32_e32 v5, 0x3d800000, v5
	v_cvt_pk_bf16_f32 v5, v5, s0
	v_pk_mul_f32 v[34:35], v[2:3], v[140:141]
	v_pk_add_f32 v[2:3], v[2:3], v[140:141] neg_lo:[0,1] neg_hi:[0,1]
	global_store_short v[74:75], v5, off
	v_and_b32_e32 v5, 0xffff0000, v4
	v_lshlrev_b32_e32 v4, 16, v4
	v_mov_b32_e32 v35, v3
	v_cndmask_b32_e64 v36, v36, v3, s[8:9]
	v_mov_b32_e32 v37, v34
	v_pk_mul_f32 v[4:5], v[62:63], v[4:5]
	v_pk_add_f32 v[62:63], v[34:35], v[36:37]
	s_nop 0
	v_cndmask_b32_e64 v2, v62, v3, s[8:9]
	v_mul_f32_e32 v3, 0x3fb8aa3b, v2
	v_exp_f32_e32 v3, v3
	v_mul_f32_e32 v2, 0xbfb8aa3b, v2
	v_exp_f32_e32 v2, v2
	v_cvt_pk_bf16_f32 v63, v4, v5
	v_mul_f32_e32 v3, v3, v79
	v_mul_f32_e32 v3, 0x3d800000, v3
	v_mul_f32_e32 v0, v2, v0
	global_store_short v[90:91], v63, off offset:2048
	global_store_short_d16_hi v[74:75], v63, off offset:2048
	v_cvt_pk_bf16_f32 v3, v3, s0
	v_cvt_pk_bf16_f32 v74, v0, s0
	global_store_short v[76:77], v3, off
	global_store_short v[76:77], v74, off offset:2048
	s_and_saveexec_b64 s[0:1], s[4:5]
	s_xor_b64 s[0:1], exec, s[0:1]
	s_or_b32 s24, s22, 32
	v_perm_b32 v2, v72, v71, s59
	v_alignbit_b32 v3, v73, v72, 16
	v_alignbit_b32 v4, v63, v73, 16
	v_alignbit_b32 v5, v74, v63, 16
	v_mov_b32_e32 v0, s24
	s_andn2_saveexec_b64 s[0:1], s[0:1]
	s_cbranch_execz .LBB0_352
	s_mov_b32 s24, 0x3020504
	v_perm_b32 v2, v74, v63, s24
	v_perm_b32 v3, v63, v73, s24
	v_perm_b32 v4, v73, v72, s24
	s_mov_b32 s24, 0x1000504
	v_perm_b32 v5, v72, v71, s24
	v_mov_b32_e32 v0, s21
	s_branch .LBB0_352

; __device__ __forceinline__ int ltid() { int t = threadIdx.x; asm volatile("" : "+v"(t)); return t; }
; template <int AI>
; __device__ __forceinline__ void dump_half(const f32x4 (&acc)[2][2][4][2], float* stage) {
;   const int wid = ltid() >> 6, lane = ltid() & 63, wr = wid >> 2, wc = wid & 3, fr = lane & 15, fq = lane >> 4;
; #pragma unroll
;   for (int bj = 0; bj < 2; ++bj)
; #pragma unroll
;     for (int m = 0; m < 4; ++m)
; #pragma unroll
;       for (int n = 0; n < 2; ++n) {
;         const int r0 = wr * 64 + m * 16 + fq * 4, c = bj * 128 + wc * 32 + n * 16 + fr;
; #pragma unroll
;         for (int j = 0; j < 4; ++j) stage[(r0 + j) * SP + c] = acc[AI][bj][m][n][j];
;       }
; }
; __device__ __forceinline__ void emit_rm(const float* stage, u16* dst, long ld, const float* rs) {
;   const int tid = ltid(), c4 = (tid & 31) * 4, rr = tid >> 5;
; #pragma unroll 1
;   for (int ps = 0; ps < 8; ++ps) {
;     const int r = ps * 16 + rr;
;     const float* s = stage + r * SP + c4;
;     const float4 a = *(const float4*)s, b = *(const float4*)(s + 128);
;     const float f = rs ? rs[r] : 1.f;
;     uint2 o0, o1;
;     o0.x = pack2(a.x * f, a.y * f); o0.y = pack2(a.z * f, a.w * f);
;     o1.x = pack2(b.x * f, b.y * f); o1.y = pack2(b.z * f, b.w * f);
;     *(uint2*)(dst + (long)r * ld + c4) = o0;
;     *(uint2*)(dst + (long)r * ld + 128 + c4) = o1;
;   }
; }
; template <int KIND>
; __device__ void gemm_phase(const Ctx& p, int hd, const int ntiles, const int blk0, const int nblk) {
;     ...
;         dump_half<0>(acc, stage); __syncthreads();
;         tile_emit<KIND>(p, t, hd, 0, 0, stage); __syncthreads();
;         dump_half<1>(acc, stage); __syncthreads();
;         tile_emit<KIND>(p, t, hd, 0, 1, stage); __syncthreads();
.LBB0_371:
	ds_read_b128 v[68:71], v0
	ds_read_b128 v[72:75], v0 offset:512
	s_mov_b32 s8, 0xfa00000
	v_add_u32_e32 v0, 0x4100, v0
	s_waitcnt lgkmcnt(0)
	v_cvt_pk_bf16_f32 v68, v68, v69
	v_cvt_pk_bf16_f32 v69, v70, v71
	s_waitcnt lgkmcnt(0)
	v_cvt_pk_bf16_f32 v70, v72, v73
	v_lshl_add_u64 v[72:73], v[2:3], 0, s[6:7]
	s_add_u32 s6, s6, 0x7a000
	v_add_co_u32_e32 v72, vcc, s8, v72
	s_addc_u32 s7, s7, 0
	s_nop 0
	v_addc_co_u32_e32 v73, vcc, 0, v73, vcc
	s_cmp_lg_u32 s6, 0x3d0000
	v_cvt_pk_bf16_f32 v71, v74, v75
	global_store_dwordx2 v[72:73], v[68:69], off
	global_store_dwordx2 v[72:73], v[70:71], off offset:256
	s_cbranch_scc1 .LBB0_371
	v_mov_b32_e32 v0, v139
	v_mov_b32_e32 v2, v139
	s_waitcnt lgkmcnt(0)
	s_barrier
	s_nop 0
	v_lshrrev_b32_e32 v68, 2, v0
	v_and_b32_e32 v3, 15, v2
	v_and_b32_e32 v68, 0xfffffc0, v68
	v_lshrrev_b32_e32 v2, 2, v2
	v_lshlrev_b32_e32 v0, 1, v0
	v_and_or_b32 v2, v2, 12, v68
	v_and_b32_e32 v0, 0x180, v0
	v_add_u32_e32 v0, 16, v0
	v_lshlrev_b32_e32 v3, 2, v3
	v_mul_lo_u32 v2, v2, s81
	v_add3_u32 v0, v0, v3, v2
	v_add_u32_e32 v2, 0x400, v0
	ds_write2_b32 v2, v65, v61 offset0:4 offset1:20
	v_add_u32_e32 v61, 0x4000, v0
	ds_write2_b32 v61, v56, v52 offset0:64 offset1:80
	v_add_u32_e32 v52, 0x4400, v0
	ds_write2_b32 v52, v57, v53 offset0:68 offset1:84
	v_add_u32_e32 v53, 0x4800, v0
	ds_write2_b32 v53, v58, v54 offset0:72 offset1:88
	v_add_u32_e32 v54, 0x4c00, v0
	ds_write2_b32 v54, v59, v55 offset0:76 offset1:92
	v_add_u32_e32 v55, 0x8000, v0
	ds_write2_b32 v55, v48, v44 offset0:128 offset1:144
	v_add_u32_e32 v44, 0x8400, v0
	ds_write2_b32 v44, v49, v45 offset0:132 offset1:148
	v_add_u32_e32 v45, 0x8800, v0
	ds_write2_b32 v45, v50, v46 offset0:136 offset1:152
	v_add_u32_e32 v46, 0x8c00, v0
	ds_write2_b32 v46, v51, v47 offset0:140 offset1:156
	v_add_u32_e32 v47, 0xc000, v0
	ds_write2_b32 v47, v40, v36 offset0:192 offset1:208
	v_add_u32_e32 v36, 0xc400, v0
	ds_write2_b32 v36, v41, v37 offset0:196 offset1:212
	v_add_u32_e32 v37, 0xc800, v0
	ds_write2_b32 v0, v64, v60 offset1:16
	v_add_u32_e32 v3, 0x800, v0
	v_add_u32_e32 v60, 0xc00, v0
	ds_write2_b32 v37, v42, v38 offset0:200 offset1:216
	v_add_u32_e32 v38, 0xcc00, v0
	ds_write2_b32 v3, v66, v62 offset0:8 offset1:24
	ds_write2_b32 v60, v67, v63 offset0:12 offset1:28
	ds_write2_b32 v38, v43, v39 offset0:204 offset1:220
	ds_write2_b32 v0, v32, v28 offset0:128 offset1:144
	ds_write2_b32 v2, v33, v29 offset0:132 offset1:148
	ds_write2_b32 v3, v34, v30 offset0:136 offset1:152
	ds_write2_b32 v60, v35, v31 offset0:140 offset1:156
	ds_write2_b32 v61, v24, v20 offset0:192 offset1:208
	ds_write2_b32 v52, v25, v21 offset0:196 offset1:212
	ds_write2_b32 v53, v26, v22 offset0:200 offset1:216
	ds_write2_b32 v54, v27, v23 offset0:204 offset1:220
	ds_write2_b32 v44, v16, v12 offset1:16
	ds_write2_b32 v45, v17, v13 offset0:4 offset1:20
	ds_write2_b32 v46, v18, v14 offset0:8 offset1:24
	v_add_u32_e32 v2, 0x9000, v0
	v_add_u32_e32 v0, 0xd000, v0
	ds_write2_b32 v2, v19, v15 offset0:12 offset1:28
	ds_write2_b32 v36, v8, v4 offset0:64 offset1:80
	ds_write2_b32 v37, v9, v5 offset0:68 offset1:84
	ds_write2_b32 v38, v10, v6 offset0:72 offset1:88
	ds_write2_b32 v0, v11, v7 offset0:76 offset1:92
	v_mov_b32_e32 v0, v139
	s_waitcnt lgkmcnt(0)
	s_barrier
	v_mov_b64_e32 v[2:3], s[0:1]
	v_ashrrev_i32_e32 v4, 5, v0
	v_mad_i64_i32 v[2:3], s[0:1], v4, s51, v[2:3]
	v_and_b32_e32 v5, 31, v0
	v_lshlrev_b32_e32 v0, 3, v5
	s_add_u32 s0, s66, s4
	v_lshl_add_u64 v[2:3], v[2:3], 0, v[0:1]
	s_addc_u32 s1, s67, s5
	v_mul_lo_u32 v0, v4, s81
	v_lshlrev_b32_e32 v4, 4, v5
	v_lshl_add_u64 v[2:3], s[0:1], 0, v[2:3]
	v_add3_u32 v0, v0, v4, 16
	s_mov_b64 s[0:1], 0
.LBB0_373:
	ds_read_b128 v[4:7], v0
	ds_read_b128 v[8:11], v0 offset:512
	s_mov_b32 s4, 0xfdd0000
	v_add_u32_e32 v0, 0x4100, v0
	s_waitcnt lgkmcnt(0)
	v_cvt_pk_bf16_f32 v4, v4, v5
	v_cvt_pk_bf16_f32 v5, v6, v7
	v_cvt_pk_bf16_f32 v6, v8, v9
	v_lshl_add_u64 v[8:9], v[2:3], 0, s[0:1]
	s_add_u32 s0, s0, 0x7a000
	v_add_co_u32_e32 v8, vcc, s4, v8
	s_addc_u32 s1, s1, 0
	s_nop 0
	v_addc_co_u32_e32 v9, vcc, 0, v9, vcc
	s_cmp_lg_u32 s0, 0x3d0000
	v_cvt_pk_bf16_f32 v7, v10, v11
	global_store_dwordx2 v[8:9], v[4:5], off
	global_store_dwordx2 v[8:9], v[6:7], off offset:256
	s_cbranch_scc1 .LBB0_373
	s_add_i32 s14, s14, 1
	s_mul_i32 s0, s14, s96
	s_add_i32 s15, s0, s63
	s_cmpk_gt_i32 s15, 0xeff
	s_waitcnt lgkmcnt(0)
	s_barrier
	s_cbranch_scc0 .LBB0_362

; __device__ __forceinline__ u16 f2bf(float f) { return (u16)(pack2(f, 0.f) & 0xffffu); }
; __device__ void ga_items(const Ctx& p) {
;     ...
;   for (int item = blockIdx.x; item < NTOK / 64; item += gridDim.x) {
;     const long row0 = (long)item * 64 + (w >> 1) * 16;
;     const u16* ap = xb + (row0 + fr) * DM + (w & 1) * 2048 + fq * 8;
;     const u16* bp = wt + (long)fr * DM + (w & 1) * 2048 + fq * 8;
;     f32x4 acc = {0.f, 0.f, 0.f, 0.f};
; #pragma unroll 1
;     for (int k0 = 0; k0 < 64; k0 += 8) {
;       bf16x8 fa[8], fb[8];
; #pragma unroll
;       for (int u = 0; u < 8; ++u) { fa[u] = *(const bf16x8*)(ap + (k0 + u) * 32); fb[u] = *(const bf16x8*)(bp + (k0 + u) * 32); }
; #pragma unroll
;       for (int u = 0; u < 8; ++u) acc = __builtin_amdgcn_mfma_f32_16x16x32_bf16(fa[u], fb[u], acc, 0, 0, 0);
;     }
;     __syncthreads();
;     *(f32x4*)(red + (w * 64 + lane) * 4) = acc;
;     __syncthreads();
;     if ((w & 1) == 0) {
;       const f32x4 o = *(const f32x4*)(red + ((w + 1) * 64 + lane) * 4);
; #pragma unroll
;       for (int r = 0; r < 4; ++r) h0[(row0 + fq * 4 + r) * H0LD + C_GA + fr] = f2bf(acc[r] + o[r]);
;     }
;   }
.LBB0_379:
	v_lshl_add_u64 v[60:61], v[26:27], 0, v[0:1]
	v_add_co_u32_e32 v64, vcc, 0xf800000, v60
	v_lshl_add_u64 v[56:57], v[24:25], 0, v[0:1]
	s_nop 0
	v_addc_co_u32_e32 v65, vcc, 0, v61, vcc
	global_load_dwordx4 v[28:31], v[56:57], off
	s_waitcnt vmcnt(0)
	global_load_dwordx4 v[32:35], v[56:57], off offset:64
	global_load_dwordx4 v[36:39], v[56:57], off offset:128
	global_load_dwordx4 v[40:43], v[56:57], off offset:192
	global_load_dwordx4 v[44:47], v[56:57], off offset:256
	global_load_dwordx4 v[48:51], v[56:57], off offset:320
	global_load_dwordx4 v[52:55], v[56:57], off offset:384
	s_nop 0
	global_load_dwordx4 v[56:59], v[56:57], off offset:448
	s_add_i32 s5, s5, 8
	global_load_dwordx4 v[60:63], v[64:65], off
	v_lshl_add_u64 v[24:25], v[24:25], 0, s[74:75]
	s_cmp_gt_u32 s5, 55
	v_lshl_add_u64 v[26:27], v[26:27], 0, s[74:75]
	s_waitcnt vmcnt(0) lgkmcnt(0)
	v_mfma_f32_16x16x32_bf16 v[2:5], v[28:31], v[60:63], v[2:5]
	global_load_dwordx4 v[28:31], v[64:65], off offset:64
	s_waitcnt vmcnt(0) lgkmcnt(0)
	v_mfma_f32_16x16x32_bf16 v[2:5], v[32:35], v[28:31], v[2:5]
	global_load_dwordx4 v[28:31], v[64:65], off offset:128
	s_waitcnt vmcnt(0) lgkmcnt(0)
	v_mfma_f32_16x16x32_bf16 v[2:5], v[36:39], v[28:31], v[2:5]
	global_load_dwordx4 v[28:31], v[64:65], off offset:192
	s_waitcnt vmcnt(0) lgkmcnt(0)
	v_mfma_f32_16x16x32_bf16 v[2:5], v[40:43], v[28:31], v[2:5]
	global_load_dwordx4 v[28:31], v[64:65], off offset:256
	s_waitcnt vmcnt(0) lgkmcnt(0)
	v_mfma_f32_16x16x32_bf16 v[2:5], v[44:47], v[28:31], v[2:5]
	global_load_dwordx4 v[28:31], v[64:65], off offset:320
	s_waitcnt vmcnt(0) lgkmcnt(0)
	v_mfma_f32_16x16x32_bf16 v[2:5], v[48:51], v[28:31], v[2:5]
	global_load_dwordx4 v[28:31], v[64:65], off offset:384
	s_waitcnt vmcnt(0) lgkmcnt(0)
	v_mfma_f32_16x16x32_bf16 v[2:5], v[52:55], v[28:31], v[2:5]
	global_load_dwordx4 v[28:31], v[64:65], off offset:448
	s_waitcnt vmcnt(0) lgkmcnt(0)
	v_mfma_f32_16x16x32_bf16 v[2:5], v[56:59], v[28:31], v[2:5]
	s_cbranch_scc0 .LBB0_379
	s_barrier
	s_nop 5
	ds_write_b128 v9, v[2:5]
	s_waitcnt lgkmcnt(0)
	s_barrier
	s_and_saveexec_b64 s[8:9], s[0:1]
	s_cbranch_execz .LBB0_377
	ds_read_b128 v[24:27], v13
	v_lshl_add_u64 v[28:29], s[6:7], 0, v[6:7]
	v_or_b32_e32 v15, v28, v8
	v_mad_u64_u32 v[30:31], s[6:7], v15, s51, v[10:11]
	s_waitcnt lgkmcnt(0)
	v_add_f32_e32 v2, v2, v24
	v_cvt_pk_bf16_f32 v2, v2, s0
	v_mad_i32_i24 v31, v29, s51, v31
	global_store_short v[30:31], v2, off
	v_add_f32_e32 v2, v3, v25
	v_cvt_pk_bf16_f32 v15, v2, s0
	v_or_b32_e32 v2, v28, v12
	v_mad_u64_u32 v[2:3], s[6:7], v2, s51, v[10:11]
	v_mad_i32_i24 v3, v29, s51, v3
	global_store_short v[2:3], v15, off
	v_add_f32_e32 v2, v4, v26
	v_cvt_pk_bf16_f32 v4, v2, s0
	v_or_b32_e32 v2, v28, v14
	v_mad_u64_u32 v[2:3], s[6:7], v2, s51, v[10:11]
	v_mad_i32_i24 v3, v29, s51, v3
	global_store_short v[2:3], v4, off
	v_add_f32_e32 v2, v5, v27
	v_cvt_pk_bf16_f32 v4, v2, s0
	v_or_b32_e32 v2, v28, v16
	v_mad_u64_u32 v[2:3], s[6:7], v2, s51, v[10:11]
	v_mad_i32_i24 v3, v29, s51, v3
	global_store_short v[2:3], v4, off
	s_branch .LBB0_377

;   __device__ __forceinline__ const float* in(int i) const { return ((const float* const*)(ws + OFF_TBL))[i]; }
;   __device__ __forceinline__ float* out() const { return ((float* const*)(ws + OFF_TBL))[28]; }
; __device__ __forceinline__ int ltid() { int t = threadIdx.x; asm volatile("" : "+v"(t)); return t; }
; __device__ void ln_phase(const Ctx& p, const float* __restrict__ g, const float* __restrict__ bt, u16* __restrict__ xb,
;                          const float* res, const u16* __restrict__ yb) {
;   const int tid = ltid(), w = tid >> 6, lane = tid & 63;
;   float* gl = (float*)g_smem; float* bl = gl + DM;
;   __syncthreads();
;   for (int c = tid * 4; c < DM; c += 512 * 4) { *(float4*)(gl + c) = *(const float4*)(g + c); *(float4*)(bl + c) = *(const float4*)(bt + c); }
;   __syncthreads();
; __device__ __forceinline__ void run_phase(char* ws_in, int ph, int dry) {
;     ...
;   if (ph == 31) { ln_phase(p, p.in(26), p.in(27), nullptr, p.out(), (const u16*)(ws + OFF_Y1)); return; }
.LBB0_385:
	s_and_b64 vcc, exec, s[46:47]
	s_cbranch_vccz .LBB0_606
	v_readlane_b32 s0, v252, 53
	v_readlane_b32 s1, v252, 54
	s_add_i32 s8, s0, -11
	s_cmp_gt_u32 s8, 19
	s_mov_b64 s[0:1], -1
	s_cbranch_scc0 .LBB0_415
	v_readlane_b32 s0, v252, 53
	v_readlane_b32 s1, v252, 54
	s_cmp_lt_i32 s0, 32
	s_mov_b64 s[0:1], -1
	s_cbranch_scc1 .LBB0_397
	v_readlane_b32 s0, v252, 53
	s_cmp_eq_u32 s0, 32
	v_readlane_b32 s1, v252, 54
	s_cbranch_scc0 .LBB0_396
	v_mov_b32_e32 v0, s66
	s_waitcnt vmcnt(0) lgkmcnt(0)
	v_add_co_u32_e32 v6, vcc, 0x4375c000, v0
	v_mov_b32_e32 v0, s67
	s_nop 0
	v_addc_co_u32_e32 v7, vcc, 0, v0, vcc
	global_load_dwordx4 v[2:5], v[6:7], off offset:208
	global_load_dwordx2 v[8:9], v[6:7], off offset:224
	s_add_u32 s0, s66, 0x4375c0e0
	v_mov_b32_e32 v0, v139
	s_movk_i32 s4, 0x400
	s_addc_u32 s1, s67, 0
	s_waitcnt lgkmcnt(0)
	v_cmp_gt_i32_e32 vcc, s4, v0
	v_lshlrev_b32_e32 v10, 2, v0
	s_barrier
	s_and_saveexec_b64 s[4:5], vcc
	s_movk_i32 s9, 0x7ff
	s_mov_b64 s[10:11], 0x2000
	s_cbranch_execz .LBB0_392
	v_ashrrev_i32_e32 v11, 31, v10
	v_lshlrev_b64 v[12:13], 2, v[10:11]
	v_add_u32_e32 v6, 0xfffff800, v10
	v_lshl_add_u32 v7, v0, 4, 16
	s_waitcnt vmcnt(0)
	v_lshl_add_u64 v[4:5], v[4:5], 0, v[12:13]
	v_lshl_add_u64 v[2:3], v[2:3], 0, v[12:13]
	s_mov_b64 s[6:7], 0
.LBB0_391:
	global_load_dwordx4 v[12:15], v[2:3], off
	v_add_u32_e32 v6, 0x800, v6
	v_lshl_add_u64 v[2:3], v[2:3], 0, s[10:11]
	v_cmp_lt_i32_e32 vcc, s9, v6
	s_mov_b64 s[10:11], 0x2000
	s_or_b64 s[6:7], vcc, s[6:7]
	s_waitcnt vmcnt(0) lgkmcnt(0)
	ds_write_b128 v7, v[12:15]
	global_load_dwordx4 v[12:15], v[4:5], off
	v_lshl_add_u64 v[4:5], v[4:5], 0, s[10:11]
	s_waitcnt vmcnt(0) lgkmcnt(0)
	ds_write_b128 v7, v[12:15] offset:16384
	v_add_u32_e32 v7, 0x2000, v7
	s_andn2_b64 exec, exec, s[6:7]
	s_cbranch_execnz .LBB0_391

;   __device__ __forceinline__ float* out() const { return ((float* const*)(ws + OFF_TBL))[28]; }
; __device__ void ln_phase(const Ctx& p, const float* __restrict__ g, const float* __restrict__ bt, u16* __restrict__ xb,
;                          const float* res, const u16* __restrict__ yb) {
;     ...
;   for (int row = blockIdx.x * 8 + w; row < NTOK; row += gridDim.x * 8) {
;     float* x = p.out() + (long)row * DM;
;     float4 v[16];
;     const float* rx = res + (long)row * DM;
;     const u16* ry = yb + (long)row * DM;
; #pragma unroll
;     for (int k = 0; k < 16; ++k) {
;       const float4 r4 = *(const float4*)(rx + k * 256 + lane * 4);
;       const uint2 y2 = *(const uint2*)(ry + k * 256 + lane * 4);
;       v[k] = make_float4(ALPHA_F * r4.x + __uint_as_float(y2.x << 16), ALPHA_F * r4.y + __uint_as_float(y2.x & 0xffff0000u),
;                          ALPHA_F * r4.z + __uint_as_float(y2.y << 16), ALPHA_F * r4.w + __uint_as_float(y2.y & 0xffff0000u));
;     }
;     float s = 0.f;
; #pragma unroll
;     for (int k = 0; k < 16; ++k) s += (v[k].x + v[k].y) + (v[k].z + v[k].w);
;     s = wave_sum(s);
.LBB0_394:
	v_ashrrev_i32_e32 v7, 31, v6
	v_lshlrev_b64 v[4:5], 13, v[6:7]
	v_mov_b64_e32 v[2:3], s[0:1]
	v_lshlrev_b64 v[62:63], 14, v[6:7]
	v_lshl_add_u64 v[4:5], v[10:11], 0, v[4:5]
	global_load_dwordx2 v[36:37], v[2:3], off
	v_lshl_add_u64 v[2:3], v[8:9], 0, v[62:63]
	global_load_dwordx2 v[38:39], v[4:5], off
	global_load_dwordx2 v[40:41], v[4:5], off offset:1536
	global_load_dwordx4 v[116:119], v[2:3], off
	v_mov_b32_e32 v13, v1
	v_mov_b32_e32 v15, v1
	v_mov_b32_e32 v17, v1
	v_mov_b32_e32 v19, v1
	v_mov_b32_e32 v21, v1
	v_mov_b32_e32 v23, v1
	v_mov_b32_e32 v25, v1
	v_mov_b32_e32 v27, v1
	v_mov_b32_e32 v29, v1
	v_mov_b32_e32 v31, v1
	v_mov_b32_e32 v33, v1
	v_mov_b32_e32 v35, v1
	v_add_u32_e32 v6, s56, v6
	global_load_dwordx2 v[42:43], v[4:5], off offset:2048
	global_load_dwordx2 v[50:51], v[4:5], off offset:3072
	s_waitcnt vmcnt(0) lgkmcnt(0)
	v_lshl_add_u64 v[88:89], v[36:37], 0, v[62:63]
	v_lshl_add_u64 v[36:37], v[88:89], 0, v[0:1]
	v_lshlrev_b32_e32 v46, 16, v38
	v_and_b32_e32 v47, 0xffff0000, v38
	v_lshlrev_b32_e32 v48, 16, v39
	v_and_b32_e32 v49, 0xffff0000, v39
	global_load_dwordx2 v[38:39], v[4:5], off offset:512
	v_pk_fma_f32 v[46:47], v[116:117], s[44:45], v[46:47] op_sel_hi:[1,0,1]
	v_pk_fma_f32 v[48:49], v[118:119], s[44:45], v[48:49] op_sel_hi:[1,0,1]
	global_load_dwordx4 v[116:119], v[2:3], off offset:1024
	v_lshlrev_b32_e32 v64, 16, v41
	v_and_b32_e32 v65, 0xffff0000, v41
	v_mov_b32_e32 v62, v46
	v_mov_b32_e32 v63, v48
	v_mov_b32_e32 v66, v47
	v_mov_b32_e32 v67, v49
	v_pk_add_f32 v[62:63], v[62:63], v[66:67]
	v_and_b32_e32 v41, 0xffff0000, v42
	v_lshlrev_b32_e32 v68, 16, v43
	v_and_b32_e32 v69, 0xffff0000, v43
	v_add_f32_e32 v7, v62, v63
	v_add_f32_e32 v66, 0, v7
	v_lshlrev_b32_e32 v44, 16, v50
	v_and_b32_e32 v45, 0xffff0000, v50
	v_lshlrev_b32_e32 v80, 16, v51
	v_and_b32_e32 v81, 0xffff0000, v51
	global_load_dwordx2 v[50:51], v[4:5], off offset:3584
	s_waitcnt vmcnt(0) lgkmcnt(0)
	v_lshlrev_b32_e32 v54, 16, v38
	v_and_b32_e32 v55, 0xffff0000, v38
	v_lshlrev_b32_e32 v56, 16, v39
	v_and_b32_e32 v57, 0xffff0000, v39
	global_load_dwordx2 v[38:39], v[4:5], off offset:1024
	v_pk_fma_f32 v[54:55], v[116:117], s[44:45], v[54:55] op_sel_hi:[1,0,1]
	v_pk_fma_f32 v[56:57], v[118:119], s[44:45], v[56:57] op_sel_hi:[1,0,1]
	global_load_dwordx4 v[116:119], v[2:3], off offset:2048
	v_mov_b32_e32 v62, v54
	v_mov_b32_e32 v63, v56
	v_mov_b32_e32 v74, v55
	v_mov_b32_e32 v75, v57
	v_pk_add_f32 v[62:63], v[62:63], v[74:75]
	v_lshlrev_b32_e32 v70, 16, v50
	v_and_b32_e32 v71, 0xffff0000, v50
	v_add_co_u32_e32 v50, vcc, s10, v4
	v_pk_add_f32 v[74:75], v[62:63], v[62:63] op_sel:[0,1] op_sel_hi:[1,0]
	v_lshlrev_b32_e32 v102, 16, v51
	v_and_b32_e32 v103, 0xffff0000, v51
	v_addc_co_u32_e32 v51, vcc, 0, v5, vcc
	s_waitcnt vmcnt(0) lgkmcnt(0)
	v_lshlrev_b32_e32 v58, 16, v38
	v_and_b32_e32 v59, 0xffff0000, v38
	v_lshlrev_b32_e32 v60, 16, v39
	v_and_b32_e32 v61, 0xffff0000, v39
	v_lshlrev_b32_e32 v38, 16, v40
	v_and_b32_e32 v39, 0xffff0000, v40
	v_lshlrev_b32_e32 v40, 16, v42
	global_load_dwordx2 v[42:43], v[4:5], off offset:2560
	v_pk_fma_f32 v[58:59], v[116:117], s[44:45], v[58:59] op_sel_hi:[1,0,1]
	v_pk_fma_f32 v[60:61], v[118:119], s[44:45], v[60:61] op_sel_hi:[1,0,1]
	global_load_dwordx4 v[116:119], v[2:3], off offset:3072
	v_pk_add_f32 v[78:79], v[58:59], v[58:59] op_sel:[0,1] op_sel_hi:[1,0]
	v_pk_add_f32 v[100:101], v[60:61], v[60:61] op_sel:[0,1] op_sel_hi:[1,0]
	global_load_dwordx2 v[4:5], v[50:51], off
	s_waitcnt vmcnt(0) lgkmcnt(0)
	v_lshlrev_b32_e32 v72, 16, v42
	v_and_b32_e32 v73, 0xffff0000, v42
	v_lshlrev_b32_e32 v42, 16, v43
	v_pk_fma_f32 v[62:63], v[116:117], s[44:45], v[38:39] op_sel_hi:[1,0,1]
	v_pk_fma_f32 v[64:65], v[118:119], s[44:45], v[64:65] op_sel_hi:[1,0,1]
	v_mov_b32_e32 v67, v62
	v_mov_b32_e32 v75, v63
	v_mov_b32_e32 v79, v64
	v_mov_b32_e32 v101, v65
	v_pk_add_f32 v[38:39], v[66:67], v[74:75]
	v_pk_add_f32 v[66:67], v[78:79], v[100:101]
	v_add_co_u32_e32 v100, vcc, s10, v2
	v_pk_add_f32 v[38:39], v[38:39], v[66:67]
	s_nop 0
	v_addc_co_u32_e32 v101, vcc, 0, v3, vcc
	global_load_dwordx4 v[116:119], v[100:101], off
	v_and_b32_e32 v43, 0xffff0000, v43
	v_pk_add_f32 v[108:109], v[38:39], v[38:39] op_sel:[0,1] op_sel_hi:[1,0]
	v_add_co_u32_e32 v124, vcc, s9, v2
	v_lshl_add_u64 v[38:39], v[88:89], 0, v[12:13]
	s_nop 0
	v_addc_co_u32_e32 v125, vcc, 0, v3, vcc
	v_add_co_u32_e32 v2, vcc, s43, v2
	v_lshlrev_b32_e32 v106, 16, v4
	v_and_b32_e32 v107, 0xffff0000, v4
	v_lshlrev_b32_e32 v76, 16, v5
	v_and_b32_e32 v77, 0xffff0000, v5
	global_load_dwordx2 v[4:5], v[50:51], off offset:512
	v_addc_co_u32_e32 v3, vcc, 0, v3, vcc
	s_waitcnt vmcnt(0) lgkmcnt(0)
	v_pk_fma_f32 v[66:67], v[116:117], s[44:45], v[40:41] op_sel_hi:[1,0,1]
	v_pk_fma_f32 v[68:69], v[118:119], s[44:45], v[68:69] op_sel_hi:[1,0,1]
	global_load_dwordx4 v[116:119], v[100:101], off offset:1024
	v_mov_b32_e32 v40, v66
	v_mov_b32_e32 v41, v68
	v_mov_b32_e32 v74, v67
	v_mov_b32_e32 v75, v69
	v_pk_add_f32 v[40:41], v[40:41], v[74:75]
	v_lshlrev_b32_e32 v82, 16, v4
	v_pk_add_f32 v[112:113], v[40:41], v[40:41] op_sel:[0,1] op_sel_hi:[1,0]
	v_and_b32_e32 v83, 0xffff0000, v4
	v_lshlrev_b32_e32 v114, 16, v5
	v_and_b32_e32 v115, 0xffff0000, v5
	global_load_dwordx2 v[4:5], v[50:51], off offset:1024
	v_lshl_add_u64 v[40:41], v[88:89], 0, v[14:15]
	s_waitcnt vmcnt(0) lgkmcnt(0)
; __device__ void ln_phase(const Ctx& p, const float* __restrict__ g, const float* __restrict__ bt, u16* __restrict__ xb,
;                          const float* res, const u16* __restrict__ yb) {
;     ...
; #pragma unroll
;     for (int k = 0; k < 16; ++k) {
;       const float4 r4 = *(const float4*)(rx + k * 256 + lane * 4);
;       const uint2 y2 = *(const uint2*)(ry + k * 256 + lane * 4);
;       v[k] = make_float4(ALPHA_F * r4.x + __uint_as_float(y2.x << 16), ALPHA_F * r4.y + __uint_as_float(y2.x & 0xffff0000u),
;                          ALPHA_F * r4.z + __uint_as_float(y2.y << 16), ALPHA_F * r4.w + __uint_as_float(y2.y & 0xffff0000u));
;     }
;     float s = 0.f;
; #pragma unroll
;     for (int k = 0; k < 16; ++k) s += (v[k].x + v[k].y) + (v[k].z + v[k].w);
	v_pk_fma_f32 v[72:73], v[116:117], s[44:45], v[72:73] op_sel_hi:[1,0,1]
	v_pk_fma_f32 v[74:75], v[118:119], s[44:45], v[42:43] op_sel_hi:[1,0,1]
	global_load_dwordx4 v[116:119], v[100:101], off offset:2048
	v_pk_add_f32 v[120:121], v[72:73], v[72:73] op_sel:[0,1] op_sel_hi:[1,0]
	v_pk_add_f32 v[122:123], v[74:75], v[74:75] op_sel:[0,1] op_sel_hi:[1,0]
	v_lshl_add_u64 v[42:43], v[88:89], 0, v[16:17]
	v_lshlrev_b32_e32 v86, 16, v4
	v_and_b32_e32 v87, 0xffff0000, v4
	v_lshlrev_b32_e32 v110, 16, v5
	v_and_b32_e32 v111, 0xffff0000, v5
	global_load_dwordx2 v[4:5], v[50:51], off offset:1536
	s_waitcnt vmcnt(0) lgkmcnt(0)
	v_pk_fma_f32 v[78:79], v[116:117], s[44:45], v[44:45] op_sel_hi:[1,0,1]
	v_pk_fma_f32 v[80:81], v[118:119], s[44:45], v[80:81] op_sel_hi:[1,0,1]
	v_mov_b32_e32 v109, v78
	v_mov_b32_e32 v113, v79
	v_mov_b32_e32 v121, v80
	v_mov_b32_e32 v123, v81
	v_pk_add_f32 v[44:45], v[108:109], v[112:113]
	v_pk_add_f32 v[108:109], v[120:121], v[122:123]
	global_load_dwordx4 v[118:121], v[100:101], off offset:3072
	v_pk_add_f32 v[44:45], v[44:45], v[108:109]
	v_lshlrev_b32_e32 v104, 16, v4
	v_pk_add_f32 v[116:117], v[44:45], v[44:45] op_sel:[0,1] op_sel_hi:[1,0]
	v_and_b32_e32 v105, 0xffff0000, v4
	v_lshlrev_b32_e32 v90, 16, v5
	v_and_b32_e32 v91, 0xffff0000, v5
	global_load_dwordx2 v[4:5], v[50:51], off offset:2048
	v_lshl_add_u64 v[44:45], v[88:89], 0, v[18:19]
	s_waitcnt vmcnt(0) lgkmcnt(0)
	v_pk_fma_f32 v[100:101], v[118:119], s[44:45], v[70:71] op_sel_hi:[1,0,1]
	v_pk_fma_f32 v[102:103], v[120:121], s[44:45], v[102:103] op_sel_hi:[1,0,1]
	global_load_dwordx4 v[118:121], v[124:125], off
	v_mov_b32_e32 v70, v100
	v_mov_b32_e32 v71, v102
	v_mov_b32_e32 v108, v101
	v_mov_b32_e32 v109, v103
	v_pk_add_f32 v[70:71], v[70:71], v[108:109]
	v_lshlrev_b32_e32 v96, 16, v4
	v_pk_add_f32 v[122:123], v[70:71], v[70:71] op_sel:[0,1] op_sel_hi:[1,0]
	v_and_b32_e32 v97, 0xffff0000, v4
	v_lshlrev_b32_e32 v98, 16, v5
	v_and_b32_e32 v99, 0xffff0000, v5
	global_load_dwordx2 v[4:5], v[50:51], off offset:2560
	v_lshl_add_u64 v[70:71], v[88:89], 0, v[20:21]
	s_waitcnt vmcnt(0) lgkmcnt(0)
	v_pk_fma_f32 v[106:107], v[118:119], s[44:45], v[106:107] op_sel_hi:[1,0,1]
	v_pk_fma_f32 v[108:109], v[120:121], s[44:45], v[76:77] op_sel_hi:[1,0,1]
	global_load_dwordx4 v[118:121], v[124:125], off offset:1024
	v_pk_add_f32 v[126:127], v[106:107], v[106:107] op_sel:[0,1] op_sel_hi:[1,0]
	v_pk_add_f32 v[128:129], v[108:109], v[108:109] op_sel:[0,1] op_sel_hi:[1,0]
	v_lshl_add_u64 v[76:77], v[88:89], 0, v[22:23]
	v_lshlrev_b32_e32 v92, 16, v4
	v_and_b32_e32 v93, 0xffff0000, v4
	v_lshlrev_b32_e32 v94, 16, v5
	v_and_b32_e32 v95, 0xffff0000, v5
	global_load_dwordx2 v[4:5], v[50:51], off offset:3072
	s_waitcnt vmcnt(0) lgkmcnt(0)
	v_pk_fma_f32 v[112:113], v[118:119], s[44:45], v[82:83] op_sel_hi:[1,0,1]
	v_pk_fma_f32 v[114:115], v[120:121], s[44:45], v[114:115] op_sel_hi:[1,0,1]
	v_mov_b32_e32 v117, v112
	v_mov_b32_e32 v123, v113
	v_mov_b32_e32 v127, v114
	v_mov_b32_e32 v129, v115
	v_pk_add_f32 v[82:83], v[116:117], v[122:123]
	v_pk_add_f32 v[116:117], v[126:127], v[128:129]
	global_load_dwordx2 v[50:51], v[50:51], off offset:3584
	v_pk_add_f32 v[82:83], v[82:83], v[116:117]
	global_load_dwordx4 v[116:119], v[124:125], off offset:2048
	v_pk_add_f32 v[126:127], v[82:83], v[82:83] op_sel:[0,1] op_sel_hi:[1,0]
	v_lshl_add_u64 v[82:83], v[88:89], 0, v[24:25]
	v_lshlrev_b32_e32 v84, 16, v4
	v_and_b32_e32 v85, 0xffff0000, v4
	v_lshlrev_b32_e32 v4, 16, v5
	v_and_b32_e32 v5, 0xffff0000, v5
	s_waitcnt vmcnt(0) lgkmcnt(0)
	v_lshlrev_b32_e32 v52, 16, v50
	v_and_b32_e32 v53, 0xffff0000, v50
	v_pk_fma_f32 v[116:117], v[116:117], s[44:45], v[86:87] op_sel_hi:[1,0,1]
	v_pk_fma_f32 v[110:111], v[118:119], s[44:45], v[110:111] op_sel_hi:[1,0,1]
	v_mov_b32_e32 v86, v116
	v_mov_b32_e32 v87, v110
	v_mov_b32_e32 v118, v117
	v_mov_b32_e32 v119, v111
	v_pk_add_f32 v[86:87], v[86:87], v[118:119]
	global_load_dwordx4 v[118:121], v[124:125], off offset:3072
	v_pk_add_f32 v[128:129], v[86:87], v[86:87] op_sel:[0,1] op_sel_hi:[1,0]
	v_lshlrev_b32_e32 v50, 16, v51
	v_and_b32_e32 v51, 0xffff0000, v51
	v_lshl_add_u64 v[86:87], v[88:89], 0, v[26:27]
	s_waitcnt vmcnt(0) lgkmcnt(0)
	v_pk_fma_f32 v[104:105], v[118:119], s[44:45], v[104:105] op_sel_hi:[1,0,1]
	v_pk_fma_f32 v[118:119], v[120:121], s[44:45], v[90:91] op_sel_hi:[1,0,1]
	global_load_dwordx4 v[120:123], v[2:3], off
	v_pk_add_f32 v[124:125], v[104:105], v[104:105] op_sel:[0,1] op_sel_hi:[1,0]
	v_pk_add_f32 v[130:131], v[118:119], v[118:119] op_sel:[0,1] op_sel_hi:[1,0]
	v_lshl_add_u64 v[90:91], v[88:89], 0, v[28:29]
	s_waitcnt vmcnt(0) lgkmcnt(0)
	v_pk_fma_f32 v[120:121], v[120:121], s[44:45], v[96:97] op_sel_hi:[1,0,1]
	v_pk_fma_f32 v[98:99], v[122:123], s[44:45], v[98:99] op_sel_hi:[1,0,1]
	v_mov_b32_e32 v127, v120
	v_mov_b32_e32 v129, v121
	v_mov_b32_e32 v125, v98
	v_mov_b32_e32 v131, v99
	v_pk_add_f32 v[96:97], v[126:127], v[128:129]
	v_pk_add_f32 v[122:123], v[124:125], v[130:131]
	s_nop 0
	v_pk_add_f32 v[96:97], v[96:97], v[122:123]
	global_load_dwordx4 v[122:125], v[2:3], off offset:1024
	v_pk_add_f32 v[128:129], v[96:97], v[96:97] op_sel:[0,1] op_sel_hi:[1,0]
	v_lshl_add_u64 v[96:97], v[88:89], 0, v[30:31]
	s_waitcnt vmcnt(0) lgkmcnt(0)
	v_pk_fma_f32 v[122:123], v[122:123], s[44:45], v[92:93] op_sel_hi:[1,0,1]
	v_pk_fma_f32 v[94:95], v[124:125], s[44:45], v[94:95] op_sel_hi:[1,0,1]
	v_mov_b32_e32 v92, v122
	v_mov_b32_e32 v93, v94
	v_mov_b32_e32 v124, v123
	v_mov_b32_e32 v125, v95
	v_pk_add_f32 v[92:93], v[92:93], v[124:125]
	global_load_dwordx4 v[124:127], v[2:3], off offset:2048
	v_pk_add_f32 v[130:131], v[92:93], v[92:93] op_sel:[0,1] op_sel_hi:[1,0]
	v_lshl_add_u64 v[92:93], v[88:89], 0, v[32:33]
	s_waitcnt vmcnt(0) lgkmcnt(0)
; __device__ void ln_phase(const Ctx& p, const float* __restrict__ g, const float* __restrict__ bt, u16* __restrict__ xb,
;                          const float* res, const u16* __restrict__ yb) {
;     ...
;     s = wave_sum(s);
;     const float mu = s * (1.f / DM);
;     float q = 0.f;
; #pragma unroll
;     for (int k = 0; k < 16; ++k) {
;       v[k].x -= mu; v[k].y -= mu; v[k].z -= mu; v[k].w -= mu;
;       q += (v[k].x * v[k].x + v[k].y * v[k].y) + (v[k].z * v[k].z + v[k].w * v[k].w);
;     }
;     q = wave_sum(q);
	v_pk_fma_f32 v[126:127], v[126:127], s[44:45], v[4:5] op_sel_hi:[1,0,1]
	global_load_dwordx4 v[2:5], v[2:3], off offset:3072
	v_pk_fma_f32 v[124:125], v[124:125], s[44:45], v[84:85] op_sel_hi:[1,0,1]
	v_pk_add_f32 v[134:135], v[126:127], v[126:127] op_sel:[0,1] op_sel_hi:[1,0]
	v_pk_add_f32 v[132:133], v[124:125], v[124:125] op_sel:[0,1] op_sel_hi:[1,0]
	v_lshl_add_u64 v[84:85], v[88:89], 0, v[34:35]
	s_waitcnt vmcnt(0) lgkmcnt(0)
	v_pk_fma_f32 v[2:3], v[2:3], s[44:45], v[52:53] op_sel_hi:[1,0,1]
	v_pk_fma_f32 v[164:165], v[4:5], s[44:45], v[50:51] op_sel_hi:[1,0,1]
	v_mov_b32_e32 v129, v2
	v_mov_b32_e32 v131, v3
	v_mov_b32_e32 v133, v164
	v_mov_b32_e32 v135, v165
	v_pk_add_f32 v[4:5], v[128:129], v[130:131]
	v_pk_add_f32 v[50:51], v[132:133], v[134:135]
	s_nop 0
	v_pk_add_f32 v[4:5], v[4:5], v[50:51]
	s_nop 0
	v_add_f32_e32 v4, v4, v5
	ds_bpermute_b32 v5, v136, v4
	s_waitcnt lgkmcnt(0)
	v_add_f32_e32 v4, v4, v5
	ds_bpermute_b32 v5, v141, v4
	s_waitcnt lgkmcnt(0)
	v_add_f32_e32 v4, v4, v5
	ds_bpermute_b32 v5, v158, v4
	s_waitcnt lgkmcnt(0)
	v_add_f32_e32 v4, v4, v5
	ds_bpermute_b32 v5, v159, v4
	s_waitcnt lgkmcnt(0)
	v_add_f32_e32 v4, v4, v5
	ds_bpermute_b32 v5, v160, v4
	s_waitcnt lgkmcnt(0)
	v_add_f32_e32 v4, v4, v5
	ds_bpermute_b32 v5, v161, v4
	s_waitcnt lgkmcnt(0)
	v_add_f32_e32 v4, v4, v5
	v_mul_f32_e32 v166, 0x39800000, v4
	v_pk_add_f32 v[168:169], v[46:47], v[166:167] op_sel_hi:[1,0] neg_lo:[0,1] neg_hi:[0,1]
	v_pk_add_f32 v[170:171], v[48:49], v[166:167] op_sel_hi:[1,0] neg_lo:[0,1] neg_hi:[0,1]
	v_mov_b32_e32 v46, v169
	v_mov_b32_e32 v47, v171
	v_mov_b32_e32 v4, v168
	v_mov_b32_e32 v5, v170
	v_pk_mul_f32 v[46:47], v[46:47], v[46:47]
	v_pk_add_f32 v[156:157], v[54:55], v[166:167] op_sel_hi:[1,0] neg_lo:[0,1] neg_hi:[0,1]
	v_pk_fma_f32 v[4:5], v[4:5], v[4:5], v[46:47]
	v_pk_add_f32 v[154:155], v[56:57], v[166:167] op_sel_hi:[1,0] neg_lo:[0,1] neg_hi:[0,1]
	v_pk_add_f32 v[4:5], v[4:5], v[4:5] op_sel_hi:[0,1]
	v_mov_b32_e32 v48, v157
	v_mov_b32_e32 v49, v155
	v_pk_add_f32 v[152:153], v[58:59], v[166:167] op_sel_hi:[1,0] neg_lo:[0,1] neg_hi:[0,1]
	v_mov_b32_e32 v46, v156
	v_mov_b32_e32 v47, v154
	v_pk_mul_f32 v[48:49], v[48:49], v[48:49]
	v_pk_add_f32 v[150:151], v[60:61], v[166:167] op_sel_hi:[1,0] neg_lo:[0,1] neg_hi:[0,1]
	v_mul_f32_e32 v4, v152, v152
	v_pk_fma_f32 v[46:47], v[46:47], v[46:47], v[48:49]
	v_pk_fma_f32 v[48:49], v[152:153], v[152:153], v[4:5] op_sel_hi:[1,1,0]
	v_mul_f32_e32 v4, v150, v150
	v_pk_add_f32 v[148:149], v[62:63], v[166:167] op_sel_hi:[1,0] neg_lo:[0,1] neg_hi:[0,1]
	v_pk_add_f32 v[146:147], v[64:65], v[166:167] op_sel_hi:[1,0] neg_lo:[0,1] neg_hi:[0,1]
	v_pk_add_f32 v[46:47], v[46:47], v[46:47] op_sel_hi:[0,1]
	v_pk_fma_f32 v[50:51], v[150:151], v[150:151], v[4:5] op_sel_hi:[1,1,0]
	v_pk_mul_f32 v[52:53], v[148:149], v[148:149]
	v_pk_mul_f32 v[54:55], v[146:147], v[146:147]
	v_mov_b32_e32 v48, v52
	v_mov_b32_e32 v50, v53
	v_mov_b32_e32 v4, v54
	v_mov_b32_e32 v46, v55
	v_pk_add_f32 v[48:49], v[48:49], v[50:51]
	v_pk_add_f32 v[4:5], v[4:5], v[46:47]
	v_pk_add_f32 v[144:145], v[66:67], v[166:167] op_sel_hi:[1,0] neg_lo:[0,1] neg_hi:[0,1]
	v_pk_add_f32 v[4:5], v[48:49], v[4:5]
	v_pk_add_f32 v[142:143], v[68:69], v[166:167] op_sel_hi:[1,0] neg_lo:[0,1] neg_hi:[0,1]
	v_pk_add_f32 v[4:5], v[4:5], v[4:5] op_sel_hi:[0,1]
	v_mov_b32_e32 v48, v145
	v_mov_b32_e32 v49, v143
	v_pk_add_f32 v[134:135], v[72:73], v[166:167] op_sel_hi:[1,0] neg_lo:[0,1] neg_hi:[0,1]
	v_mov_b32_e32 v46, v144
	v_mov_b32_e32 v47, v142
	v_pk_mul_f32 v[48:49], v[48:49], v[48:49]
	v_pk_add_f32 v[132:133], v[74:75], v[166:167] op_sel_hi:[1,0] neg_lo:[0,1] neg_hi:[0,1]
	v_mul_f32_e32 v4, v134, v134
	v_pk_fma_f32 v[46:47], v[46:47], v[46:47], v[48:49]
	v_pk_fma_f32 v[48:49], v[134:135], v[134:135], v[4:5] op_sel_hi:[1,1,0]
	v_mul_f32_e32 v4, v132, v132
	v_pk_add_f32 v[130:131], v[78:79], v[166:167] op_sel_hi:[1,0] neg_lo:[0,1] neg_hi:[0,1]
	v_pk_add_f32 v[128:129], v[80:81], v[166:167] op_sel_hi:[1,0] neg_lo:[0,1] neg_hi:[0,1]
	v_pk_add_f32 v[46:47], v[46:47], v[46:47] op_sel_hi:[0,1]
	v_pk_fma_f32 v[50:51], v[132:133], v[132:133], v[4:5] op_sel_hi:[1,1,0]
	v_pk_mul_f32 v[52:53], v[130:131], v[130:131]
	v_pk_mul_f32 v[54:55], v[128:129], v[128:129]
	v_mov_b32_e32 v48, v52
	v_mov_b32_e32 v50, v53
	v_mov_b32_e32 v46, v54
	v_mov_b32_e32 v4, v55
	v_pk_add_f32 v[48:49], v[48:49], v[50:51]
	v_pk_add_f32 v[4:5], v[46:47], v[4:5]
	v_pk_add_f32 v[88:89], v[100:101], v[166:167] op_sel_hi:[1,0] neg_lo:[0,1] neg_hi:[0,1]
	v_pk_add_f32 v[4:5], v[48:49], v[4:5]
	v_pk_add_f32 v[80:81], v[102:103], v[166:167] op_sel_hi:[1,0] neg_lo:[0,1] neg_hi:[0,1]
	v_pk_add_f32 v[4:5], v[4:5], v[4:5] op_sel_hi:[0,1]
	v_mov_b32_e32 v48, v89
	v_mov_b32_e32 v49, v81
	v_pk_add_f32 v[78:79], v[106:107], v[166:167] op_sel_hi:[1,0] neg_lo:[0,1] neg_hi:[0,1]
	v_mov_b32_e32 v46, v88
	v_mov_b32_e32 v47, v80
	v_pk_mul_f32 v[48:49], v[48:49], v[48:49]
	v_pk_add_f32 v[74:75], v[108:109], v[166:167] op_sel_hi:[1,0] neg_lo:[0,1] neg_hi:[0,1]
	v_mul_f32_e32 v4, v78, v78
	v_pk_fma_f32 v[46:47], v[46:47], v[46:47], v[48:49]
	v_pk_fma_f32 v[48:49], v[78:79], v[78:79], v[4:5] op_sel_hi:[1,1,0]
	v_mul_f32_e32 v4, v74, v74
	v_pk_add_f32 v[72:73], v[112:113], v[166:167] op_sel_hi:[1,0] neg_lo:[0,1] neg_hi:[0,1]
	v_pk_add_f32 v[68:69], v[114:115], v[166:167] op_sel_hi:[1,0] neg_lo:[0,1] neg_hi:[0,1]
	v_pk_add_f32 v[46:47], v[46:47], v[46:47] op_sel_hi:[0,1]
	v_pk_fma_f32 v[50:51], v[74:75], v[74:75], v[4:5] op_sel_hi:[1,1,0]
	v_pk_mul_f32 v[52:53], v[72:73], v[72:73]
	v_pk_mul_f32 v[54:55], v[68:69], v[68:69]
	v_mov_b32_e32 v48, v52
	v_mov_b32_e32 v50, v53
	v_mov_b32_e32 v46, v54
	v_mov_b32_e32 v4, v55
; __device__ void ln_phase(const Ctx& p, const float* __restrict__ g, const float* __restrict__ bt, u16* __restrict__ xb,
;                          const float* res, const u16* __restrict__ yb) {
;     ...
;     q = wave_sum(q);
;     const float rs = rsqrtf(q * (1.f / DM) + 1e-5f);
; #pragma unroll
;     for (int k = 0; k < 16; ++k) {
;       if ((k & 3) == 0) asm volatile("" ::: "memory");
;       const int c = k * 256 + lane * 4;
;       const float4 gg = *(const float4*)(gl + c), bb = *(const float4*)(bl + c);
;       float4 o = make_float4(v[k].x * rs * gg.x + bb.x, v[k].y * rs * gg.y + bb.y, v[k].z * rs * gg.z + bb.z, v[k].w * rs * gg.w + bb.w);
;       if (!p.dry) *(float4*)(x + c) = o;
	v_pk_add_f32 v[48:49], v[48:49], v[50:51]
	v_pk_add_f32 v[4:5], v[46:47], v[4:5]
	v_pk_add_f32 v[66:67], v[116:117], v[166:167] op_sel_hi:[1,0] neg_lo:[0,1] neg_hi:[0,1]
	v_pk_add_f32 v[4:5], v[48:49], v[4:5]
	v_pk_add_f32 v[64:65], v[110:111], v[166:167] op_sel_hi:[1,0] neg_lo:[0,1] neg_hi:[0,1]
	v_pk_add_f32 v[4:5], v[4:5], v[4:5] op_sel_hi:[0,1]
	v_mov_b32_e32 v48, v67
	v_mov_b32_e32 v49, v65
	v_pk_add_f32 v[62:63], v[104:105], v[166:167] op_sel_hi:[1,0] neg_lo:[0,1] neg_hi:[0,1]
	v_mov_b32_e32 v46, v66
	v_mov_b32_e32 v47, v64
	v_pk_mul_f32 v[48:49], v[48:49], v[48:49]
	v_pk_add_f32 v[60:61], v[118:119], v[166:167] op_sel_hi:[1,0] neg_lo:[0,1] neg_hi:[0,1]
	v_mul_f32_e32 v4, v62, v62
	v_pk_fma_f32 v[46:47], v[46:47], v[46:47], v[48:49]
	v_pk_fma_f32 v[48:49], v[62:63], v[62:63], v[4:5] op_sel_hi:[1,1,0]
	v_mul_f32_e32 v4, v60, v60
	v_pk_add_f32 v[56:57], v[120:121], v[166:167] op_sel_hi:[1,0] neg_lo:[0,1] neg_hi:[0,1]
	v_pk_add_f32 v[54:55], v[98:99], v[166:167] op_sel_hi:[1,0] neg_lo:[0,1] neg_hi:[0,1]
	v_pk_add_f32 v[46:47], v[46:47], v[46:47] op_sel_hi:[0,1]
	v_pk_fma_f32 v[50:51], v[60:61], v[60:61], v[4:5] op_sel_hi:[1,1,0]
	v_pk_mul_f32 v[52:53], v[56:57], v[56:57]
	v_pk_mul_f32 v[58:59], v[54:55], v[54:55]
	v_mov_b32_e32 v48, v52
	v_mov_b32_e32 v50, v53
	v_mov_b32_e32 v46, v58
	v_mov_b32_e32 v4, v59
	v_pk_add_f32 v[48:49], v[48:49], v[50:51]
	v_pk_add_f32 v[4:5], v[46:47], v[4:5]
	v_pk_add_f32 v[52:53], v[122:123], v[166:167] op_sel_hi:[1,0] neg_lo:[0,1] neg_hi:[0,1]
	v_pk_add_f32 v[50:51], v[94:95], v[166:167] op_sel_hi:[1,0] neg_lo:[0,1] neg_hi:[0,1]
	v_pk_add_f32 v[4:5], v[48:49], v[4:5]
	v_mov_b32_e32 v46, v53
	v_mov_b32_e32 v47, v51
	v_pk_add_f32 v[58:59], v[4:5], v[4:5] op_sel_hi:[0,1]
	v_mov_b32_e32 v4, v52
	v_mov_b32_e32 v5, v50
	v_pk_mul_f32 v[46:47], v[46:47], v[46:47]
	v_pk_add_f32 v[48:49], v[124:125], v[166:167] op_sel_hi:[1,0] neg_lo:[0,1] neg_hi:[0,1]
	v_pk_fma_f32 v[4:5], v[4:5], v[4:5], v[46:47]
	v_pk_add_f32 v[46:47], v[126:127], v[166:167] op_sel_hi:[1,0] neg_lo:[0,1] neg_hi:[0,1]
	v_pk_add_f32 v[94:95], v[4:5], v[4:5] op_sel_hi:[0,1]
	v_mul_f32_e32 v4, v48, v48
	v_pk_fma_f32 v[98:99], v[48:49], v[48:49], v[4:5] op_sel_hi:[1,1,0]
	v_mul_f32_e32 v4, v46, v46
	v_pk_fma_f32 v[100:101], v[46:47], v[46:47], v[4:5] op_sel_hi:[1,1,0]
	v_pk_add_f32 v[4:5], v[2:3], v[166:167] op_sel_hi:[1,0] neg_lo:[0,1] neg_hi:[0,1]
	v_pk_add_f32 v[2:3], v[164:165], v[166:167] op_sel_hi:[1,0] neg_lo:[0,1] neg_hi:[0,1]
	v_pk_mul_f32 v[102:103], v[4:5], v[4:5]
	v_pk_mul_f32 v[104:105], v[2:3], v[2:3]
	v_mov_b32_e32 v98, v102
	v_mov_b32_e32 v100, v103
	v_mov_b32_e32 v94, v104
	v_mov_b32_e32 v58, v105
	v_pk_add_f32 v[98:99], v[98:99], v[100:101]
	v_pk_add_f32 v[58:59], v[94:95], v[58:59]
	s_nop 0
	v_pk_add_f32 v[58:59], v[98:99], v[58:59]
	ds_read_b128 v[98:101], v162
	ds_read_b128 v[102:105], v162 offset:16384
	v_add_f32_e32 v7, v58, v59
	ds_bpermute_b32 v13, v136, v7
	s_waitcnt lgkmcnt(0)
	v_add_f32_e32 v7, v7, v13
	ds_bpermute_b32 v13, v141, v7
	s_waitcnt lgkmcnt(0)
	v_add_f32_e32 v7, v7, v13
	ds_bpermute_b32 v13, v158, v7
	s_waitcnt lgkmcnt(0)
	v_add_f32_e32 v7, v7, v13
	ds_bpermute_b32 v13, v159, v7
	s_waitcnt lgkmcnt(0)
	v_add_f32_e32 v7, v7, v13
	ds_bpermute_b32 v13, v160, v7
	s_waitcnt lgkmcnt(0)
	v_add_f32_e32 v7, v7, v13
	ds_bpermute_b32 v13, v161, v7
	s_waitcnt lgkmcnt(0)
	v_add_f32_e32 v7, v7, v13
	v_fmamk_f32 v7, v7, 0x39800000, v193
	v_cmp_gt_f32_e32 vcc, s48, v7
	v_mul_f32_e32 v13, 0x4b800000, v7
	s_nop 0
	v_cndmask_b32_e32 v7, v7, v13, vcc
	v_rsq_f32_e32 v7, v7
	s_nop 0
	v_mul_f32_e32 v13, 0x45800000, v7
	v_cndmask_b32_e32 v58, v7, v13, vcc
	v_pk_mul_f32 v[94:95], v[168:169], v[58:59] op_sel_hi:[1,0]
	v_pk_mul_f32 v[88:89], v[88:89], v[58:59] op_sel_hi:[1,0]
	v_pk_fma_f32 v[98:99], v[98:99], v[94:95], v[102:103]
	v_pk_mul_f32 v[94:95], v[170:171], v[58:59] op_sel_hi:[1,0]
	v_pk_mul_f32 v[4:5], v[4:5], v[58:59] op_sel_hi:[1,0]
	v_pk_fma_f32 v[100:101], v[100:101], v[94:95], v[104:105]
	global_store_dwordx4 v[36:37], v[98:101], off
	ds_read_b128 v[98:101], v162 offset:1024
	ds_read_b128 v[102:105], v162 offset:17408
	v_pk_mul_f32 v[94:95], v[156:157], v[58:59] op_sel_hi:[1,0]
	v_pk_mul_f32 v[2:3], v[2:3], v[58:59] op_sel_hi:[1,0]
	v_cmp_lt_i32_e32 vcc, s11, v6
	s_or_b64 s[6:7], vcc, s[6:7]
	s_waitcnt lgkmcnt(0)
	v_pk_fma_f32 v[98:99], v[98:99], v[94:95], v[102:103]
	v_pk_mul_f32 v[94:95], v[154:155], v[58:59] op_sel_hi:[1,0]
	s_nop 0
	v_pk_fma_f32 v[100:101], v[100:101], v[94:95], v[104:105]
	global_store_dwordx4 v[36:37], v[98:101], off offset:1024
	ds_read_b128 v[98:101], v162 offset:2048
	ds_read_b128 v[102:105], v162 offset:18432
	v_pk_mul_f32 v[94:95], v[152:153], v[58:59] op_sel_hi:[1,0]
	s_waitcnt lgkmcnt(0)
; __device__ void ln_phase(const Ctx& p, const float* __restrict__ g, const float* __restrict__ bt, u16* __restrict__ xb,
;                          const float* res, const u16* __restrict__ yb) {
;     ...
; #pragma unroll
;     for (int k = 0; k < 16; ++k) {
;       if ((k & 3) == 0) asm volatile("" ::: "memory");
;       const int c = k * 256 + lane * 4;
;       const float4 gg = *(const float4*)(gl + c), bb = *(const float4*)(bl + c);
;       float4 o = make_float4(v[k].x * rs * gg.x + bb.x, v[k].y * rs * gg.y + bb.y, v[k].z * rs * gg.z + bb.z, v[k].w * rs * gg.w + bb.w);
;       if (!p.dry) *(float4*)(x + c) = o;
;       if (xb && !p.dry) { uint2 ov; ov.x = pack2(o.x, o.y); ov.y = pack2(o.z, o.w); *(uint2*)(xb + (long)row * DM + c) = ov; }
;     }
	v_pk_fma_f32 v[98:99], v[98:99], v[94:95], v[102:103]
	v_pk_mul_f32 v[94:95], v[150:151], v[58:59] op_sel_hi:[1,0]
	s_nop 0
	v_pk_fma_f32 v[100:101], v[100:101], v[94:95], v[104:105]
	global_store_dwordx4 v[36:37], v[98:101], off offset:2048
	ds_read_b128 v[98:101], v162 offset:3072
	ds_read_b128 v[102:105], v162 offset:19456
	v_pk_mul_f32 v[94:95], v[148:149], v[58:59] op_sel_hi:[1,0]
	s_waitcnt lgkmcnt(0)
	v_pk_fma_f32 v[98:99], v[94:95], v[98:99], v[102:103]
	v_pk_mul_f32 v[94:95], v[146:147], v[58:59] op_sel_hi:[1,0]
	s_nop 0
	v_pk_fma_f32 v[100:101], v[94:95], v[100:101], v[104:105]
	global_store_dwordx4 v[36:37], v[98:101], off offset:3072
	ds_read_b128 v[98:101], v162 offset:4096
	ds_read_b128 v[102:105], v162 offset:20480
	v_pk_mul_f32 v[36:37], v[144:145], v[58:59] op_sel_hi:[1,0]
	v_pk_mul_f32 v[94:95], v[134:135], v[58:59] op_sel_hi:[1,0]
	s_waitcnt lgkmcnt(0)
	v_pk_fma_f32 v[98:99], v[36:37], v[98:99], v[102:103]
	v_pk_mul_f32 v[36:37], v[142:143], v[58:59] op_sel_hi:[1,0]
	s_nop 0
	v_pk_fma_f32 v[100:101], v[36:37], v[100:101], v[104:105]
	global_store_dwordx4 v[38:39], v[98:101], off
	ds_read_b128 v[36:39], v162 offset:5120
	ds_read_b128 v[98:101], v162 offset:21504
	s_waitcnt lgkmcnt(0)
	v_pk_fma_f32 v[36:37], v[94:95], v[36:37], v[98:99]
	v_pk_mul_f32 v[94:95], v[132:133], v[58:59] op_sel_hi:[1,0]
	s_nop 0
	v_pk_fma_f32 v[38:39], v[94:95], v[38:39], v[100:101]
	global_store_dwordx4 v[40:41], v[36:39], off
	ds_read_b128 v[36:39], v162 offset:6144
	ds_read_b128 v[98:101], v162 offset:22528
	v_pk_mul_f32 v[40:41], v[130:131], v[58:59] op_sel_hi:[1,0]
	s_waitcnt lgkmcnt(0)
	v_pk_fma_f32 v[36:37], v[40:41], v[36:37], v[98:99]
	v_pk_mul_f32 v[40:41], v[128:129], v[58:59] op_sel_hi:[1,0]
	s_nop 0
	v_pk_fma_f32 v[38:39], v[40:41], v[38:39], v[100:101]
	global_store_dwordx4 v[42:43], v[36:39], off
	ds_read_b128 v[36:39], v162 offset:7168
	ds_read_b128 v[40:43], v162 offset:23552
	s_waitcnt lgkmcnt(0)
	v_pk_fma_f32 v[36:37], v[88:89], v[36:37], v[40:41]
	v_pk_mul_f32 v[40:41], v[80:81], v[58:59] op_sel_hi:[1,0]
	s_nop 0
	v_pk_fma_f32 v[38:39], v[40:41], v[38:39], v[42:43]
	global_store_dwordx4 v[44:45], v[36:39], off
	ds_read_b128 v[36:39], v162 offset:8192
	ds_read_b128 v[40:43], v162 offset:24576
	v_pk_mul_f32 v[44:45], v[78:79], v[58:59] op_sel_hi:[1,0]
	s_waitcnt lgkmcnt(0)
	v_pk_fma_f32 v[36:37], v[44:45], v[36:37], v[40:41]
	v_pk_mul_f32 v[40:41], v[74:75], v[58:59] op_sel_hi:[1,0]
	v_pk_mul_f32 v[44:45], v[72:73], v[58:59] op_sel_hi:[1,0]
	v_pk_fma_f32 v[38:39], v[40:41], v[38:39], v[42:43]
	global_store_dwordx4 v[70:71], v[36:39], off
	ds_read_b128 v[36:39], v162 offset:9216
	ds_read_b128 v[40:43], v162 offset:25600
	s_waitcnt lgkmcnt(0)
	v_pk_fma_f32 v[36:37], v[44:45], v[36:37], v[40:41]
	v_pk_mul_f32 v[40:41], v[68:69], v[58:59] op_sel_hi:[1,0]
	v_pk_mul_f32 v[44:45], v[66:67], v[58:59] op_sel_hi:[1,0]
	v_pk_fma_f32 v[38:39], v[40:41], v[38:39], v[42:43]
	global_store_dwordx4 v[76:77], v[36:39], off
	ds_read_b128 v[36:39], v162 offset:10240
	ds_read_b128 v[40:43], v162 offset:26624
	s_waitcnt lgkmcnt(0)
	v_pk_fma_f32 v[36:37], v[44:45], v[36:37], v[40:41]
	v_pk_mul_f32 v[40:41], v[64:65], v[58:59] op_sel_hi:[1,0]
	v_pk_mul_f32 v[44:45], v[62:63], v[58:59] op_sel_hi:[1,0]
	v_pk_fma_f32 v[38:39], v[40:41], v[38:39], v[42:43]
	global_store_dwordx4 v[82:83], v[36:39], off
	ds_read_b128 v[36:39], v162 offset:11264
	ds_read_b128 v[40:43], v162 offset:27648
	s_waitcnt lgkmcnt(0)
	v_pk_fma_f32 v[36:37], v[44:45], v[36:37], v[40:41]
	v_pk_mul_f32 v[40:41], v[60:61], v[58:59] op_sel_hi:[1,0]
	v_pk_mul_f32 v[44:45], v[56:57], v[58:59] op_sel_hi:[1,0]
	v_pk_fma_f32 v[38:39], v[40:41], v[38:39], v[42:43]
	global_store_dwordx4 v[86:87], v[36:39], off
	ds_read_b128 v[36:39], v162 offset:12288
	ds_read_b128 v[40:43], v162 offset:28672
	s_waitcnt lgkmcnt(0)
	v_pk_fma_f32 v[36:37], v[44:45], v[36:37], v[40:41]
	v_pk_mul_f32 v[40:41], v[54:55], v[58:59] op_sel_hi:[1,0]
	v_pk_mul_f32 v[44:45], v[52:53], v[58:59] op_sel_hi:[1,0]
	v_pk_fma_f32 v[38:39], v[40:41], v[38:39], v[42:43]
	global_store_dwordx4 v[90:91], v[36:39], off
	ds_read_b128 v[36:39], v162 offset:13312
	ds_read_b128 v[40:43], v162 offset:29696
	s_waitcnt lgkmcnt(0)
	v_pk_fma_f32 v[36:37], v[44:45], v[36:37], v[40:41]
	v_pk_mul_f32 v[40:41], v[50:51], v[58:59] op_sel_hi:[1,0]
	v_pk_mul_f32 v[44:45], v[48:49], v[58:59] op_sel_hi:[1,0]
	v_pk_fma_f32 v[38:39], v[40:41], v[38:39], v[42:43]
	global_store_dwordx4 v[96:97], v[36:39], off
	ds_read_b128 v[36:39], v162 offset:14336
	ds_read_b128 v[40:43], v162 offset:30720
	s_waitcnt lgkmcnt(0)
	v_pk_fma_f32 v[36:37], v[44:45], v[36:37], v[40:41]
	v_pk_mul_f32 v[40:41], v[46:47], v[58:59] op_sel_hi:[1,0]
	s_nop 0
	v_pk_fma_f32 v[38:39], v[40:41], v[38:39], v[42:43]
	global_store_dwordx4 v[92:93], v[36:39], off
	ds_read_b128 v[36:39], v162 offset:15360
	ds_read_b128 v[40:43], v162 offset:31744
	s_waitcnt lgkmcnt(0)
	v_pk_fma_f32 v[36:37], v[4:5], v[36:37], v[40:41]
	v_pk_fma_f32 v[38:39], v[2:3], v[38:39], v[42:43]
	global_store_dwordx4 v[84:85], v[36:39], off
	s_andn2_b64 exec, exec, s[6:7]
	s_cbranch_execnz .LBB0_394

; __device__ __forceinline__ int ltid() { int t = threadIdx.x; asm volatile("" : "+v"(t)); return t; }
; template <int AI>
; __device__ __forceinline__ void dump_half(const f32x4 (&acc)[2][2][4][2], float* stage) {
;   const int wid = ltid() >> 6, lane = ltid() & 63, wr = wid >> 2, wc = wid & 3, fr = lane & 15, fq = lane >> 4;
; #pragma unroll
;   for (int bj = 0; bj < 2; ++bj)
; #pragma unroll
;     for (int m = 0; m < 4; ++m)
; #pragma unroll
;       for (int n = 0; n < 2; ++n) {
;         const int r0 = wr * 64 + m * 16 + fq * 4, c = bj * 128 + wc * 32 + n * 16 + fr;
; #pragma unroll
;         for (int j = 0; j < 4; ++j) stage[(r0 + j) * SP + c] = acc[AI][bj][m][n][j];
;       }
; }
; __device__ __forceinline__ void emit_rm(const float* stage, u16* dst, long ld, const float* rs) {
;   const int tid = ltid(), c4 = (tid & 31) * 4, rr = tid >> 5;
; #pragma unroll 1
;   for (int ps = 0; ps < 8; ++ps) {
;     const int r = ps * 16 + rr;
;     const float* s = stage + r * SP + c4;
;     const float4 a = *(const float4*)s, b = *(const float4*)(s + 128);
;     const float f = rs ? rs[r] : 1.f;
;     uint2 o0, o1;
;     o0.x = pack2(a.x * f, a.y * f); o0.y = pack2(a.z * f, a.w * f);
;     o1.x = pack2(b.x * f, b.y * f); o1.y = pack2(b.z * f, b.w * f);
;     *(uint2*)(dst + (long)r * ld + c4) = o0;
;     *(uint2*)(dst + (long)r * ld + 128 + c4) = o1;
;   }
; }
.LBB0_410:
	v_add_u32_e32 v72, s6, v0
	ds_read_b128 v[68:71], v72
	ds_read_b128 v[72:75], v72 offset:512
	s_addk_i32 s6, 0x4100
	s_cmp_lg_u32 s6, 0x20800
	s_waitcnt lgkmcnt(0)
	v_cvt_pk_bf16_f32 v68, v68, v69
	v_cvt_pk_bf16_f32 v69, v70, v71
	s_waitcnt lgkmcnt(0)
	v_cvt_pk_bf16_f32 v70, v72, v73
	v_cvt_pk_bf16_f32 v71, v74, v75
	global_store_dwordx2 v[2:3], v[68:69], off
	global_store_dwordx2 v[2:3], v[70:71], off offset:256
	v_lshl_add_u64 v[2:3], v[2:3], 0, s[88:89]
	s_cbranch_scc1 .LBB0_410
	v_mov_b32_e32 v0, v139
	v_mov_b32_e32 v2, v139
	s_waitcnt lgkmcnt(0)
	s_barrier
	s_nop 0
	v_lshrrev_b32_e32 v68, 2, v0
	v_and_b32_e32 v3, 15, v2
	v_and_b32_e32 v68, 0xfffffc0, v68
	v_lshrrev_b32_e32 v2, 2, v2
	v_lshlrev_b32_e32 v0, 1, v0
	v_and_or_b32 v2, v2, 12, v68
	v_and_b32_e32 v0, 0x180, v0
	v_add_u32_e32 v0, 16, v0
	v_lshlrev_b32_e32 v3, 2, v3
	v_mul_lo_u32 v2, v2, s81
	v_add3_u32 v0, v0, v3, v2
	v_add_u32_e32 v2, 0x400, v0
	ds_write2_b32 v2, v65, v61 offset0:4 offset1:20
	v_add_u32_e32 v61, 0x4000, v0
	ds_write2_b32 v61, v56, v52 offset0:64 offset1:80
	v_add_u32_e32 v52, 0x4400, v0
	ds_write2_b32 v52, v57, v53 offset0:68 offset1:84
	v_add_u32_e32 v53, 0x4800, v0
	ds_write2_b32 v53, v58, v54 offset0:72 offset1:88
	v_add_u32_e32 v54, 0x4c00, v0
	ds_write2_b32 v54, v59, v55 offset0:76 offset1:92
	v_add_u32_e32 v55, 0x8000, v0
	ds_write2_b32 v55, v48, v44 offset0:128 offset1:144
	v_add_u32_e32 v44, 0x8400, v0
	ds_write2_b32 v44, v49, v45 offset0:132 offset1:148
	v_add_u32_e32 v45, 0x8800, v0
	ds_write2_b32 v45, v50, v46 offset0:136 offset1:152
	v_add_u32_e32 v46, 0x8c00, v0
	ds_write2_b32 v46, v51, v47 offset0:140 offset1:156
	v_add_u32_e32 v47, 0xc000, v0
	ds_write2_b32 v47, v40, v36 offset0:192 offset1:208
	v_add_u32_e32 v36, 0xc400, v0
	ds_write2_b32 v36, v41, v37 offset0:196 offset1:212
	v_add_u32_e32 v37, 0xc800, v0
	ds_write2_b32 v0, v64, v60 offset1:16
	v_add_u32_e32 v3, 0x800, v0
	v_add_u32_e32 v60, 0xc00, v0
	ds_write2_b32 v37, v42, v38 offset0:200 offset1:216
	v_add_u32_e32 v38, 0xcc00, v0
	ds_write2_b32 v3, v66, v62 offset0:8 offset1:24
	ds_write2_b32 v60, v67, v63 offset0:12 offset1:28
	ds_write2_b32 v38, v43, v39 offset0:204 offset1:220
	ds_write2_b32 v0, v32, v28 offset0:128 offset1:144
	ds_write2_b32 v2, v33, v29 offset0:132 offset1:148
	ds_write2_b32 v3, v34, v30 offset0:136 offset1:152
	ds_write2_b32 v60, v35, v31 offset0:140 offset1:156
	ds_write2_b32 v61, v24, v20 offset0:192 offset1:208
	ds_write2_b32 v52, v25, v21 offset0:196 offset1:212
	ds_write2_b32 v53, v26, v22 offset0:200 offset1:216
	ds_write2_b32 v54, v27, v23 offset0:204 offset1:220
	ds_write2_b32 v44, v16, v12 offset1:16
	ds_write2_b32 v45, v17, v13 offset0:4 offset1:20
	ds_write2_b32 v46, v18, v14 offset0:8 offset1:24
	v_add_u32_e32 v2, 0x9000, v0
	v_add_u32_e32 v0, 0xd000, v0
	ds_write2_b32 v2, v19, v15 offset0:12 offset1:28
	ds_write2_b32 v36, v8, v4 offset0:64 offset1:80
	ds_write2_b32 v37, v9, v5 offset0:68 offset1:84
	ds_write2_b32 v38, v10, v6 offset0:72 offset1:88
	ds_write2_b32 v0, v11, v7 offset0:76 offset1:92
	v_mov_b32_e32 v0, v139
	s_waitcnt lgkmcnt(0)
	s_barrier
	s_nop 0
	v_ashrrev_i32_e32 v4, 5, v0
	v_ashrrev_i32_e32 v5, 31, v4
	v_lshlrev_b64 v[2:3], 13, v[4:5]
	v_and_b32_e32 v5, 31, v0
	v_lshl_add_u64 v[2:3], s[0:1], 0, v[2:3]
	v_lshlrev_b32_e32 v0, 3, v5
	s_add_u32 s0, s66, s4
	v_lshl_add_u64 v[2:3], v[2:3], 0, v[0:1]
	s_addc_u32 s1, s67, s5
	v_mul_lo_u32 v0, v4, s81
	v_lshlrev_b32_e32 v4, 4, v5
	v_lshl_add_u64 v[2:3], s[0:1], 0, v[2:3]
	v_add3_u32 v0, v0, v4, 16
	s_mov_b64 s[0:1], 0
.LBB0_412:
	ds_read_b128 v[4:7], v0
	ds_read_b128 v[8:11], v0 offset:512
	v_add_u32_e32 v0, 0x4100, v0
	s_waitcnt lgkmcnt(0)
	v_cvt_pk_bf16_f32 v4, v4, v5
	v_cvt_pk_bf16_f32 v5, v6, v7
	v_cvt_pk_bf16_f32 v6, v8, v9
	v_lshl_add_u64 v[8:9], v[2:3], 0, s[0:1]
	s_add_u32 s0, s0, 0x20000
	v_add_co_u32_e32 v8, vcc, s69, v8
	s_addc_u32 s1, s1, 0
	s_nop 0
	v_addc_co_u32_e32 v9, vcc, 0, v9, vcc
	s_cmp_lg_u32 s0, 0x100000
	v_cvt_pk_bf16_f32 v7, v10, v11
	global_store_dwordx2 v[8:9], v[4:5], off
	global_store_dwordx2 v[8:9], v[6:7], off offset:256
	s_cbranch_scc1 .LBB0_412
	s_add_i32 s13, s13, 1
	s_mul_i32 s0, s13, s96
	s_add_i32 s14, s0, s63
	s_cmpk_gt_i32 s14, 0x3ff
	s_waitcnt lgkmcnt(0)
	s_barrier
	s_cbranch_scc0 .LBB0_401

;   __device__ __forceinline__ const float* in(int i) const { return ((const float* const*)(ws + OFF_TBL))[i]; }
; __device__ __forceinline__ int ltid() { int t = threadIdx.x; asm volatile("" : "+v"(t)); return t; }
; __device__ void hp_phase(const Ctx& p, const int hd) {
;   char* ws = p.ws;
;   const u16* hh = (const u16*)(ws + OFF_KH); const u16* Uh = (const u16*)(ws + OFF_UH);
;   u16* cat = (u16*)(ws + OFF_CAT1);
;   const float* wv = p.in(18); const float* ng = p.in(21); const float* sk = p.in(22);
;   const int tid = ltid(), w = tid >> 6, lane = tid & 63;
;   float ngr[32], skr[32];
; #pragma unroll
;   for (int k = 0; k < 4; ++k)
; #pragma unroll
;     for (int e = 0; e < 8; ++e) { ngr[k * 8 + e] = ng[hd * 2048 + k * 512 + lane * 8 + e]; skr[k * 8 + e] = sk[hd * 2048 + k * 512 + lane * 8 + e]; }
;   for (int item = blockIdx.x; item < NTOK / 8; item += gridDim.x) {
; __device__ __forceinline__ void run_phase(char* ws_in, int ph, int dry) {
;     ...
;   if (ph >= 10 && ph < 30) {
;     const int hd = (ph - 10) / 5, sub = (ph - 10) % 5;
;     if (sub == 0) hq_phase(p, hd);
;     else if (sub == 1) { if (gridDim.x >= 256) { gemm_phase<G_G>(p, hd, 128, 0, 128); gemm_phase<G_S>(p, hd, 288, 128, gridDim.x - 128); } else { gemm_phase<G_G>(p, hd, 128, 0, gridDim.x); gemm_phase<G_S>(p, hd, 288, 0, gridDim.x); } __syncthreads(); nvec_items(p, hd); }
;     else if (sub == 2) den_phase(p, hd);
;     else if (sub == 3) gemm_phase<G_NUM>(p, hd, 512, 0, gridDim.x);
;     else hp_phase(p, hd);
.LBB0_415:
	s_and_b64 vcc, exec, s[0:1]
	s_cbranch_vccz .LBB0_605
	s_mul_i32 s0, s8, 0xcd
	s_bfe_u32 s16, s0, 0x6000a
	s_mul_i32 s0, s16, 5
	s_sub_i32 s0, s8, s0
	s_and_b32 s14, s0, 0xff
	s_lshl_b32 s20, s16, 13
	s_lshl_b32 s21, s16, 11
	s_cmp_lt_i32 s14, 2
	s_mov_b64 s[0:1], -1
	s_cbranch_scc1 .LBB0_484
	s_and_b32 s4, 0xffff, s14
	s_cmp_lt_i32 s4, 3
	s_cbranch_scc1 .LBB0_475
	s_cmp_lg_u32 s4, 3
	s_cbranch_scc0 .LBB0_423
	v_mov_b32_e32 v0, s66
	s_waitcnt vmcnt(0) lgkmcnt(0)
	v_add_co_u32_e32 v2, vcc, 0x4375c000, v0
	v_mov_b32_e32 v0, s67
	s_nop 0
	v_addc_co_u32_e32 v3, vcc, 0, v0, vcc
	global_load_dwordx2 v[66:67], v[2:3], off offset:144
	global_load_dwordx4 v[58:61], v[2:3], off offset:168
	v_readlane_b32 s0, v253, 20
	v_readlane_b32 s1, v253, 21
	v_mov_b32_e32 v68, v139
	s_andn2_b64 vcc, exec, s[0:1]
	s_movk_i32 s6, 0x4400
	s_movk_i32 s7, 0x1080
	s_cbranch_vccnz .LBB0_422
	v_lshlrev_b32_e32 v0, 3, v68
	v_and_b32_e32 v69, 0x1f8, v0
	v_or_b32_e32 v70, s21, v69
	v_lshlrev_b32_e32 v0, 2, v70
	s_waitcnt vmcnt(0) lgkmcnt(0)
	v_lshl_add_u64 v[22:23], v[58:59], 0, v[0:1]
	v_lshl_add_u64 v[30:31], v[60:61], 0, v[0:1]
	global_load_dwordx4 v[2:5], v[22:23], off
	global_load_dwordx4 v[6:9], v[22:23], off offset:16
	global_load_dwordx4 v[10:13], v[30:31], off
	global_load_dwordx4 v[14:17], v[30:31], off offset:16
	global_load_dwordx4 v[18:21], v[22:23], off offset:2048
	s_nop 0
	global_load_dwordx4 v[22:25], v[22:23], off offset:2064
	s_nop 0
	global_load_dwordx4 v[26:29], v[30:31], off offset:2048
	s_nop 0
	global_load_dwordx4 v[30:33], v[30:31], off offset:2064
	v_or_b32_e32 v71, 0x400, v70
	v_or_b32_e32 v72, 0x600, v70
	v_lshlrev_b32_e32 v34, 2, v71
	v_mov_b32_e32 v35, v1
	v_or_b32_e32 v42, 0x1010, v0
	v_mov_b32_e32 v43, v1
	v_lshlrev_b32_e32 v50, 2, v72
	v_mov_b32_e32 v51, v1
	v_or_b32_e32 v0, 0x1810, v0
	v_lshl_add_u64 v[36:37], v[58:59], 0, v[34:35]
	v_lshl_add_u64 v[38:39], v[60:61], 0, v[34:35]
	v_lshl_add_u64 v[44:45], v[58:59], 0, v[42:43]
	v_lshl_add_u64 v[46:47], v[60:61], 0, v[42:43]
	v_lshl_add_u64 v[52:53], v[58:59], 0, v[50:51]
	v_lshl_add_u64 v[54:55], v[60:61], 0, v[50:51]
	v_lshl_add_u64 v[58:59], v[58:59], 0, v[0:1]
	v_lshl_add_u64 v[62:63], v[60:61], 0, v[0:1]
	global_load_dwordx4 v[34:37], v[36:37], off
	s_nop 0
	global_load_dwordx4 v[38:41], v[38:39], off
	s_nop 0
	global_load_dwordx4 v[42:45], v[44:45], off
	s_nop 0
	global_load_dwordx4 v[46:49], v[46:47], off
	s_nop 0
	global_load_dwordx4 v[50:53], v[52:53], off
	s_nop 0
	global_load_dwordx4 v[54:57], v[54:55], off
	s_nop 0
	global_load_dwordx4 v[58:61], v[58:59], off
	s_nop 0
	global_load_dwordx4 v[62:65], v[62:63], off
	v_ashrrev_i32_e32 v82, 6, v68
	v_add_u32_e32 v0, 64, v196
	v_xor_b32_e32 v68, 32, v195
	v_cmp_lt_i32_e32 vcc, v68, v0
	s_lshl_b32 s0, s21, 1
	s_add_u32 s0, s66, s0
	v_cndmask_b32_e32 v68, v195, v68, vcc
	v_lshlrev_b32_e32 v141, 2, v68
	v_xor_b32_e32 v68, 16, v195
	v_cmp_lt_i32_e32 vcc, v68, v0
	s_mov_b64 s[4:5], 0x4200000
	s_addc_u32 s1, s67, 0
	v_cndmask_b32_e32 v68, v195, v68, vcc
	v_lshlrev_b32_e32 v211, 2, v68
	v_xor_b32_e32 v68, 8, v195
	v_cmp_lt_i32_e32 vcc, v68, v0
	v_ashrrev_i32_e32 v83, 31, v82
	s_nop 0
	v_cndmask_b32_e32 v68, v195, v68, vcc
	v_lshlrev_b32_e32 v212, 2, v68
	v_xor_b32_e32 v68, 4, v195
	v_cmp_lt_i32_e32 vcc, v68, v0
	s_nop 1
	v_cndmask_b32_e32 v68, v195, v68, vcc
	v_lshlrev_b32_e32 v213, 2, v68
	v_xor_b32_e32 v68, 2, v195
	v_cmp_lt_i32_e32 vcc, v68, v0
	s_nop 1
	v_cndmask_b32_e32 v68, v195, v68, vcc
	v_lshlrev_b32_e32 v214, 2, v68
	v_xor_b32_e32 v68, 1, v195
	v_cmp_lt_i32_e32 vcc, v68, v0
	s_nop 1
	v_cndmask_b32_e32 v0, v195, v68, vcc
	v_lshlrev_b32_e32 v215, 2, v0
	v_lshlrev_b32_e32 v0, 4, v70
	v_lshl_add_u64 v[84:85], v[66:67], 0, v[0:1]
	v_or_b32_e32 v0, 0x2000, v0
	v_lshl_add_u64 v[86:87], v[66:67], 0, v[0:1]
	v_lshlrev_b32_e32 v0, 4, v71
	v_lshl_add_u64 v[88:89], v[66:67], 0, v[0:1]
	v_lshlrev_b32_e32 v0, 4, v72
	v_lshl_add_u64 v[90:91], v[66:67], 0, v[0:1]
	v_lshlrev_b32_e32 v0, 1, v69
	v_lshl_add_u64 v[66:67], s[66:67], 0, v[0:1]
	v_lshl_add_u64 v[92:93], v[66:67], 0, s[4:5]
	s_mov_b64 s[4:5], 0x3b000000
	v_lshl_add_u64 v[94:95], v[66:67], 0, s[4:5]
	v_lshl_add_u64 v[66:67], s[0:1], 0, v[0:1]
	s_mov_b64 s[0:1], 0x20800000
	v_lshl_add_u64 v[96:97], v[66:67], 0, s[0:1]
	s_mov_b32 s0, s63
; __device__ __forceinline__ float bf2f(u16 h) { return __uint_as_float(((unsigned)h) << 16); }
; __device__ void hp_phase(const Ctx& p, const int hd) {
;     ...
;   for (int item = blockIdx.x; item < NTOK / 8; item += gridDim.x) {
;     const long row = (long)item * 8 + w;
;     float hv[32];
;     float s = 0.f;
; #pragma unroll
;     for (int k = 0; k < 4; ++k) {
;       const int c = k * 512 + lane * 8;
;       uint4 r = *(const uint4*)(hh + row * LDQ + c);
;       float x[8] = {bf2f(r.x & 0xffff), bf2f(r.x >> 16), bf2f(r.y & 0xffff), bf2f(r.y >> 16),
;                     bf2f(r.z & 0xffff), bf2f(r.z >> 16), bf2f(r.w & 0xffff), bf2f(r.w >> 16)};
; #pragma unroll
;       for (int nb = 0; nb < 2; ++nb) {
;         const float* W = wv + ((hd * 2048 + c) / 4 + nb) * 16;
; #pragma unroll
;         for (int o = 0; o < 4; ++o) {
;           float a = 0.f;
; #pragma unroll
;           for (int i = 0; i < 4; ++i) a += x[nb * 4 + i] * W[i * 4 + o];
;           hv[k * 8 + nb * 4 + o] = a; s += a;
;         }
;       }
;     }
;     s = wave_sum(s);
;     const float mu = s * (1.f / 2048.f);
;     float q = 0.f;
; #pragma unroll
;     for (int e = 0; e < 32; ++e) { hv[e] -= mu; q += hv[e] * hv[e]; }
;     q = wave_sum(q);
;     const float rs = rsqrtf(q * (1.f / 2048.f) + 1e-6f);
; #pragma unroll
;     for (int k = 0; k < 4; ++k) {
;       const int c = k * 512 + lane * 8;
;       uint4 ur = *(const uint4*)(Uh + row * LDQ + c);
;       uint4 zr = *(const uint4*)(cat + row * 8704 + hd * 2048 + c);
;       float u[8] = {bf2f(ur.x & 0xffff), bf2f(ur.x >> 16), bf2f(ur.y & 0xffff), bf2f(ur.y >> 16),
;                     bf2f(ur.z & 0xffff), bf2f(ur.z >> 16), bf2f(ur.w & 0xffff), bf2f(ur.w >> 16)};
;       float z[8] = {bf2f(zr.x & 0xffff), bf2f(zr.x >> 16), bf2f(zr.y & 0xffff), bf2f(zr.y >> 16),
;                     bf2f(zr.z & 0xffff), bf2f(zr.z >> 16), bf2f(zr.w & 0xffff), bf2f(zr.w >> 16)};
.LBB0_421:
	s_ashr_i32 s1, s0, 31
	v_lshl_add_u64 v[146:147], s[0:1], 3, v[82:83]
	v_mad_u64_u32 v[98:99], s[4:5], v146, s7, v[92:93]
	v_mad_i32_i24 v99, v147, s7, v99
	global_load_dwordx4 v[66:69], v[98:99], off
	global_load_dwordx4 v[106:109], v[90:91], off offset:96
	global_load_dwordx4 v[158:161], v[90:91], off offset:112
	global_load_dwordx4 v[172:175], v[84:85], off offset:32
	global_load_dwordx4 v[176:179], v[84:85], off offset:48
	s_add_i32 s0, s0, s96
	s_cmpk_gt_i32 s0, 0x7ff
	global_load_dwordx4 v[102:105], v[90:91], off offset:80
	global_load_dwordx4 v[168:171], v[84:85], off offset:16
	s_waitcnt vmcnt(0) lgkmcnt(0)
	v_lshlrev_b32_e32 v112, 16, v66
	v_and_b32_e32 v116, 0xffff0000, v66
	v_lshlrev_b32_e32 v148, 16, v67
	v_and_b32_e32 v150, 0xffff0000, v67
	v_lshlrev_b32_e32 v118, 16, v68
	v_and_b32_e32 v120, 0xffff0000, v68
	v_lshlrev_b32_e32 v152, 16, v69
	v_and_b32_e32 v156, 0xffff0000, v69
	global_load_dwordx4 v[66:69], v[98:99], off offset:1024
	s_waitcnt vmcnt(0) lgkmcnt(0)
	v_lshlrev_b32_e32 v122, 16, v66
	v_and_b32_e32 v132, 0xffff0000, v66
	v_lshlrev_b32_e32 v144, 16, v67
	v_and_b32_e32 v154, 0xffff0000, v67
	v_lshlrev_b32_e32 v124, 16, v68
	v_and_b32_e32 v134, 0xffff0000, v68
	v_lshlrev_b32_e32 v136, 16, v69
	v_and_b32_e32 v142, 0xffff0000, v69
	global_load_dwordx4 v[66:69], v[98:99], off offset:2048
	s_waitcnt vmcnt(0) lgkmcnt(0)
	v_lshlrev_b32_e32 v78, 16, v67
	global_load_dwordx4 v[98:101], v[98:99], off offset:3072
	v_and_b32_e32 v80, 0xffff0000, v67
	v_lshlrev_b32_e32 v74, 16, v66
	v_and_b32_e32 v76, 0xffff0000, v66
	v_lshlrev_b32_e32 v66, 16, v68
	v_and_b32_e32 v68, 0xffff0000, v68
	v_lshlrev_b32_e32 v70, 16, v69
	v_and_b32_e32 v72, 0xffff0000, v69
	s_waitcnt vmcnt(0) lgkmcnt(0)
	v_lshlrev_b32_e32 v0, 16, v98
	v_and_b32_e32 v126, 0xffff0000, v98
	v_lshlrev_b32_e32 v128, 16, v99
	v_and_b32_e32 v130, 0xffff0000, v99
	v_lshlrev_b32_e32 v110, 16, v100
	v_and_b32_e32 v162, 0xffff0000, v100
	v_lshlrev_b32_e32 v164, 16, v101
	v_and_b32_e32 v166, 0xffff0000, v101
	global_load_dwordx4 v[98:101], v[90:91], off offset:64
	s_waitcnt vmcnt(0) lgkmcnt(0)
	v_pk_fma_f32 v[98:99], v[98:99], v[110:111], 0 op_sel_hi:[1,0,0]
	s_nop 0
	v_pk_fma_f32 v[98:99], v[102:103], v[162:163], v[98:99] op_sel_hi:[1,0,1]
	s_nop 0
	v_pk_fma_f32 v[98:99], v[106:107], v[164:165], v[98:99] op_sel_hi:[1,0,1]
	s_nop 0
	v_pk_fma_f32 v[114:115], v[158:159], v[166:167], v[98:99] op_sel_hi:[1,0,1]
	v_pk_fma_f32 v[98:99], v[100:101], v[110:111], 0 op_sel_hi:[1,0,0]
	v_mad_u64_u32 v[100:101], s[4:5], v146, s7, v[94:95]
	v_pk_fma_f32 v[98:99], v[104:105], v[162:163], v[98:99] op_sel_hi:[1,0,1]
	v_mad_i32_i24 v101, v147, s7, v101
	v_pk_fma_f32 v[98:99], v[108:109], v[164:165], v[98:99] op_sel_hi:[1,0,1]
	global_load_dwordx4 v[104:107], v[100:101], off
	v_pk_fma_f32 v[110:111], v[160:161], v[166:167], v[98:99] op_sel_hi:[1,0,1]
	global_load_dwordx4 v[164:167], v[84:85], off
	v_mad_u64_u32 v[98:99], s[4:5], v146, s6, v[96:97]
	v_mad_i32_i24 v99, v147, s6, v99
	global_load_dwordx4 v[160:163], v[98:99], off
	s_waitcnt vmcnt(0) lgkmcnt(0)
	v_and_b32_e32 v103, 0xffff0000, v107
	v_lshlrev_b32_e32 v102, 16, v107
	v_pk_fma_f32 v[146:147], v[164:165], v[112:113], 0 op_sel_hi:[1,0,0]
	v_pk_fma_f32 v[112:113], v[166:167], v[112:113], 0 op_sel_hi:[1,0,0]
	global_load_dwordx4 v[164:167], v[84:85], off offset:64
	v_pk_fma_f32 v[146:147], v[168:169], v[116:117], v[146:147] op_sel_hi:[1,0,1]
	v_pk_fma_f32 v[112:113], v[170:171], v[116:117], v[112:113] op_sel_hi:[1,0,1]
	global_load_dwordx4 v[168:171], v[84:85], off offset:80
	v_pk_fma_f32 v[146:147], v[172:173], v[148:149], v[146:147] op_sel_hi:[1,0,1]
	v_pk_fma_f32 v[112:113], v[174:175], v[148:149], v[112:113] op_sel_hi:[1,0,1]
	global_load_dwordx4 v[172:175], v[84:85], off offset:96
	v_pk_fma_f32 v[146:147], v[176:177], v[150:151], v[146:147] op_sel_hi:[1,0,1]
	v_pk_fma_f32 v[148:149], v[178:179], v[150:151], v[112:113] op_sel_hi:[1,0,1]
	global_load_dwordx4 v[176:179], v[84:85], off offset:112
	v_and_b32_e32 v181, 0xffff0000, v161
	v_mul_f32_e32 v67, 0xbfb8aa3b, v181
	v_exp_f32_e32 v67, v67
	v_lshlrev_b32_e32 v180, 16, v161
	v_and_b32_e32 v159, 0xffff0000, v163
	v_lshlrev_b32_e32 v158, 16, v163
	v_add_f32_e32 v67, 1.0, v67
	v_rcp_f32_e32 v113, v67
	v_mul_f32_e32 v67, 0xbfb8aa3b, v180
	v_exp_f32_e32 v67, v67
	v_and_b32_e32 v163, 0xffff0000, v162
	v_lshlrev_b32_e32 v162, 16, v162
	v_and_b32_e32 v161, 0xffff0000, v160
	v_add_f32_e32 v67, 1.0, v67
	v_rcp_f32_e32 v112, v67
	v_mul_f32_e32 v67, 0xbfb8aa3b, v163
	v_exp_f32_e32 v67, v67
	v_lshlrev_b32_e32 v160, 16, v160
	v_pk_mul_f32 v[112:113], v[112:113], v[180:181]
	v_and_b32_e32 v107, 0xffff0000, v106
	v_add_f32_e32 v67, 1.0, v67
	v_lshlrev_b32_e32 v106, 16, v106
	v_and_b32_e32 v109, 0xffff0000, v105
	v_lshlrev_b32_e32 v108, 16, v105
	v_and_b32_e32 v105, 0xffff0000, v104
	v_lshlrev_b32_e32 v104, 16, v104
	global_load_dwordx4 v[180:183], v[86:87], off offset:112
	s_waitcnt vmcnt(0) lgkmcnt(0)
; __device__ __forceinline__ float bf2f(u16 h) { return __uint_as_float(((unsigned)h) << 16); }
; __device__ __forceinline__ float siluf(float x) { return x * __builtin_amdgcn_rcpf(1.f + __expf(-x)); }
; __device__ void hp_phase(const Ctx& p, const int hd) {
;     ...
;     for (int k = 0; k < 4; ++k) {
;       const int c = k * 512 + lane * 8;
;       uint4 r = *(const uint4*)(hh + row * LDQ + c);
;       float x[8] = {bf2f(r.x & 0xffff), bf2f(r.x >> 16), bf2f(r.y & 0xffff), bf2f(r.y >> 16),
;                     bf2f(r.z & 0xffff), bf2f(r.z >> 16), bf2f(r.w & 0xffff), bf2f(r.w >> 16)};
; #pragma unroll
;       for (int nb = 0; nb < 2; ++nb) {
;         const float* W = wv + ((hd * 2048 + c) / 4 + nb) * 16;
; #pragma unroll
;         for (int o = 0; o < 4; ++o) {
;           float a = 0.f;
; #pragma unroll
;           for (int i = 0; i < 4; ++i) a += x[nb * 4 + i] * W[i * 4 + o];
;           hv[k * 8 + nb * 4 + o] = a; s += a;
;         }
;       }
;     }
;     s = wave_sum(s);
;     const float mu = s * (1.f / 2048.f);
;     float q = 0.f;
; #pragma unroll
;     for (int e = 0; e < 32; ++e) { hv[e] -= mu; q += hv[e] * hv[e]; }
;     q = wave_sum(q);
;     const float rs = rsqrtf(q * (1.f / 2048.f) + 1e-6f);
; #pragma unroll
;     for (int k = 0; k < 4; ++k) {
;       const int c = k * 512 + lane * 8;
;       uint4 ur = *(const uint4*)(Uh + row * LDQ + c);
;       uint4 zr = *(const uint4*)(cat + row * 8704 + hd * 2048 + c);
;       float u[8] = {bf2f(ur.x & 0xffff), bf2f(ur.x >> 16), bf2f(ur.y & 0xffff), bf2f(ur.y >> 16),
;                     bf2f(ur.z & 0xffff), bf2f(ur.z >> 16), bf2f(ur.w & 0xffff), bf2f(ur.w >> 16)};
;       float z[8] = {bf2f(zr.x & 0xffff), bf2f(zr.x >> 16), bf2f(zr.y & 0xffff), bf2f(zr.y >> 16),
;                     bf2f(zr.z & 0xffff), bf2f(zr.z >> 16), bf2f(zr.w & 0xffff), bf2f(zr.w >> 16)};
;       float o[8];
; #pragma unroll
;       for (int e = 0; e < 8; ++e) {
;         o[e] = (hv[k * 8 + e] * rs * ngr[k * 8 + e] + skr[k * 8 + e] * u[e]) * siluf(z[e]);
	v_pk_fma_f32 v[116:117], v[164:165], v[118:119], 0 op_sel_hi:[1,0,0]
	v_pk_fma_f32 v[118:119], v[166:167], v[118:119], 0 op_sel_hi:[1,0,0]
	v_pk_fma_f32 v[116:117], v[168:169], v[120:121], v[116:117] op_sel_hi:[1,0,1]
	v_pk_fma_f32 v[118:119], v[170:171], v[120:121], v[118:119] op_sel_hi:[1,0,1]
	global_load_dwordx4 v[168:171], v[86:87], off offset:16
	v_pk_fma_f32 v[116:117], v[172:173], v[152:153], v[116:117] op_sel_hi:[1,0,1]
	v_pk_fma_f32 v[118:119], v[174:175], v[152:153], v[118:119] op_sel_hi:[1,0,1]
	global_load_dwordx4 v[172:175], v[86:87], off offset:32
	v_pk_fma_f32 v[150:151], v[176:177], v[156:157], v[116:117] op_sel_hi:[1,0,1]
	v_rcp_f32_e32 v117, v67
	v_mul_f32_e32 v67, 0xbfb8aa3b, v162
	v_exp_f32_e32 v67, v67
	v_pk_fma_f32 v[152:153], v[178:179], v[156:157], v[118:119] op_sel_hi:[1,0,1]
	global_load_dwordx4 v[176:179], v[86:87], off offset:48
	v_add_f32_e32 v67, 1.0, v67
	v_rcp_f32_e32 v116, v67
	v_mul_f32_e32 v67, 0xbfb8aa3b, v159
	v_exp_f32_e32 v67, v67
	v_pk_mul_f32 v[116:117], v[116:117], v[162:163]
	v_add_f32_e32 v67, 1.0, v67
	v_rcp_f32_e32 v119, v67
	v_mul_f32_e32 v67, 0xbfb8aa3b, v158
	v_exp_f32_e32 v67, v67
	s_nop 0
	v_add_f32_e32 v67, 1.0, v67
	v_rcp_f32_e32 v118, v67
	v_mul_f32_e32 v67, 0xbfb8aa3b, v161
	v_exp_f32_e32 v67, v67
	v_pk_mul_f32 v[120:121], v[118:119], v[158:159]
	v_add_f32_e32 v67, 1.0, v67
	v_rcp_f32_e32 v119, v67
	v_mul_f32_e32 v67, 0xbfb8aa3b, v160
	v_exp_f32_e32 v67, v67
	s_nop 0
	v_add_f32_e32 v67, 1.0, v67
	v_rcp_f32_e32 v118, v67
	s_nop 0
	v_pk_mul_f32 v[118:119], v[118:119], v[160:161]
	global_load_dwordx4 v[160:163], v[98:99], off offset:1024
	s_waitcnt vmcnt(0) lgkmcnt(0)
	v_and_b32_e32 v159, 0xffff0000, v163
	v_lshlrev_b32_e32 v158, 16, v163
	v_and_b32_e32 v167, 0xffff0000, v162
	v_lshlrev_b32_e32 v166, 16, v162
	v_and_b32_e32 v165, 0xffff0000, v161
	v_lshlrev_b32_e32 v164, 16, v161
	v_and_b32_e32 v157, 0xffff0000, v160
	v_lshlrev_b32_e32 v156, 16, v160
	global_load_dwordx4 v[160:163], v[86:87], off
	v_mul_f32_e32 v67, 0xbfb8aa3b, v165
	v_exp_f32_e32 v67, v67
	s_waitcnt vmcnt(0) lgkmcnt(0)
	v_pk_fma_f32 v[160:161], v[160:161], v[122:123], 0 op_sel_hi:[1,0,0]
	v_pk_fma_f32 v[122:123], v[162:163], v[122:123], 0 op_sel_hi:[1,0,0]
	v_pk_fma_f32 v[160:161], v[168:169], v[132:133], v[160:161] op_sel_hi:[1,0,1]
	v_pk_fma_f32 v[122:123], v[170:171], v[132:133], v[122:123] op_sel_hi:[1,0,1]
	global_load_dwordx4 v[168:171], v[86:87], off offset:64
	v_pk_fma_f32 v[160:161], v[172:173], v[144:145], v[160:161] op_sel_hi:[1,0,1]
	v_pk_fma_f32 v[122:123], v[174:175], v[144:145], v[122:123] op_sel_hi:[1,0,1]
	global_load_dwordx4 v[172:175], v[86:87], off offset:80
	v_pk_fma_f32 v[160:161], v[176:177], v[154:155], v[160:161] op_sel_hi:[1,0,1]
	v_pk_fma_f32 v[162:163], v[178:179], v[154:155], v[122:123] op_sel_hi:[1,0,1]
	global_load_dwordx4 v[176:179], v[86:87], off offset:96
	v_add_f32_e32 v67, 1.0, v67
	v_rcp_f32_e32 v123, v67
	v_mul_f32_e32 v67, 0xbfb8aa3b, v164
	v_exp_f32_e32 v67, v67
	s_waitcnt vmcnt(0) lgkmcnt(0)
	v_pk_fma_f32 v[132:133], v[168:169], v[124:125], 0 op_sel_hi:[1,0,0]
	v_pk_fma_f32 v[124:125], v[170:171], v[124:125], 0 op_sel_hi:[1,0,0]
	global_load_dwordx4 v[168:171], v[98:99], off offset:2048
	v_add_f32_e32 v67, 1.0, v67
	v_rcp_f32_e32 v122, v67
	v_mul_f32_e32 v67, 0xbfb8aa3b, v167
	v_exp_f32_e32 v67, v67
	v_pk_fma_f32 v[132:133], v[172:173], v[134:135], v[132:133] op_sel_hi:[1,0,1]
	v_pk_mul_f32 v[122:123], v[122:123], v[164:165]
	v_pk_fma_f32 v[132:133], v[176:177], v[136:137], v[132:133] op_sel_hi:[1,0,1]
	v_add_f32_e32 v67, 1.0, v67
	v_pk_fma_f32 v[164:165], v[180:181], v[142:143], v[132:133] op_sel_hi:[1,0,1]
	v_rcp_f32_e32 v133, v67
	v_mul_f32_e32 v67, 0xbfb8aa3b, v166
	v_exp_f32_e32 v67, v67
	v_pk_fma_f32 v[124:125], v[174:175], v[134:135], v[124:125] op_sel_hi:[1,0,1]
	global_load_dwordx4 v[172:175], v[88:89], off offset:16
	v_pk_fma_f32 v[124:125], v[178:179], v[136:137], v[124:125] op_sel_hi:[1,0,1]
	v_add_f32_e32 v67, 1.0, v67
	v_rcp_f32_e32 v132, v67
	v_mul_f32_e32 v67, 0xbfb8aa3b, v159
	v_exp_f32_e32 v67, v67
	global_load_dwordx4 v[176:179], v[88:89], off offset:32
	v_pk_mul_f32 v[132:133], v[132:133], v[166:167]
	v_pk_fma_f32 v[166:167], v[182:183], v[142:143], v[124:125] op_sel_hi:[1,0,1]
	v_add_f32_e32 v67, 1.0, v67
	v_rcp_f32_e32 v125, v67
	v_mul_f32_e32 v67, 0xbfb8aa3b, v158
	v_exp_f32_e32 v67, v67
	global_load_dwordx4 v[180:183], v[88:89], off offset:48
	v_add_f32_e32 v67, 1.0, v67
	v_rcp_f32_e32 v124, v67
	v_mul_f32_e32 v67, 0xbfb8aa3b, v157
	v_exp_f32_e32 v67, v67
	v_pk_mul_f32 v[142:143], v[124:125], v[158:159]
	v_add_f32_e32 v67, 1.0, v67
	v_rcp_f32_e32 v125, v67
	v_mul_f32_e32 v67, 0xbfb8aa3b, v156
	v_exp_f32_e32 v67, v67
	s_waitcnt vmcnt(0) lgkmcnt(0)
	v_and_b32_e32 v155, 0xffff0000, v170
	v_add_f32_e32 v67, 1.0, v67
	v_rcp_f32_e32 v124, v67
	v_lshlrev_b32_e32 v154, 16, v170
	v_and_b32_e32 v145, 0xffff0000, v169
	v_lshlrev_b32_e32 v144, 16, v169
	v_pk_mul_f32 v[134:135], v[124:125], v[156:157]
	v_and_b32_e32 v157, 0xffff0000, v171
	v_lshlrev_b32_e32 v156, 16, v171
	v_and_b32_e32 v125, 0xffff0000, v168
	v_lshlrev_b32_e32 v124, 16, v168
	global_load_dwordx4 v[168:171], v[88:89], off
	v_mul_f32_e32 v67, 0xbfb8aa3b, v145
	v_exp_f32_e32 v67, v67
	s_waitcnt vmcnt(0) lgkmcnt(0)
; __device__ __forceinline__ float bf2f(u16 h) { return __uint_as_float(((unsigned)h) << 16); }
; __device__ void hp_phase(const Ctx& p, const int hd) {
;     ...
;     for (int k = 0; k < 4; ++k) {
;       const int c = k * 512 + lane * 8;
;       uint4 r = *(const uint4*)(hh + row * LDQ + c);
;       float x[8] = {bf2f(r.x & 0xffff), bf2f(r.x >> 16), bf2f(r.y & 0xffff), bf2f(r.y >> 16),
;                     bf2f(r.z & 0xffff), bf2f(r.z >> 16), bf2f(r.w & 0xffff), bf2f(r.w >> 16)};
; #pragma unroll
;       for (int nb = 0; nb < 2; ++nb) {
;         const float* W = wv + ((hd * 2048 + c) / 4 + nb) * 16;
; #pragma unroll
;         for (int o = 0; o < 4; ++o) {
;           float a = 0.f;
; #pragma unroll
;           for (int i = 0; i < 4; ++i) a += x[nb * 4 + i] * W[i * 4 + o];
;           hv[k * 8 + nb * 4 + o] = a; s += a;
;         }
;       }
;     }
;     s = wave_sum(s);
	v_pk_fma_f32 v[158:159], v[168:169], v[74:75], 0 op_sel_hi:[1,0,0]
	v_pk_fma_f32 v[74:75], v[170:171], v[74:75], 0 op_sel_hi:[1,0,0]
	v_add_f32_e32 v67, 1.0, v67
	v_pk_fma_f32 v[74:75], v[174:175], v[76:77], v[74:75] op_sel_hi:[1,0,1]
	v_pk_fma_f32 v[158:159], v[172:173], v[76:77], v[158:159] op_sel_hi:[1,0,1]
	v_pk_fma_f32 v[74:75], v[178:179], v[78:79], v[74:75] op_sel_hi:[1,0,1]
	v_pk_fma_f32 v[158:159], v[176:177], v[78:79], v[158:159] op_sel_hi:[1,0,1]
	v_pk_fma_f32 v[170:171], v[182:183], v[80:81], v[74:75] op_sel_hi:[1,0,1]
	v_rcp_f32_e32 v75, v67
	v_mul_f32_e32 v67, 0xbfb8aa3b, v144
	v_exp_f32_e32 v67, v67
	v_pk_fma_f32 v[168:169], v[180:181], v[80:81], v[158:159] op_sel_hi:[1,0,1]
	global_load_dwordx4 v[78:81], v[88:89], off offset:80
	global_load_dwordx4 v[174:177], v[88:89], off offset:96
	global_load_dwordx4 v[178:181], v[88:89], off offset:112
	v_add_f32_e32 v67, 1.0, v67
	v_rcp_f32_e32 v74, v67
	s_nop 0
	v_pk_mul_f32 v[144:145], v[74:75], v[144:145]
	global_load_dwordx4 v[74:77], v[88:89], off offset:64
	s_waitcnt vmcnt(0) lgkmcnt(0)
	v_pk_fma_f32 v[74:75], v[74:75], v[66:67], 0 op_sel_hi:[1,0,0]
	v_mul_f32_e32 v67, 0xbfb8aa3b, v155
	v_exp_f32_e32 v67, v67
	v_pk_fma_f32 v[74:75], v[78:79], v[68:69], v[74:75] op_sel_hi:[1,0,1]
	v_add_f32_e32 v67, 1.0, v67
	v_pk_fma_f32 v[74:75], v[174:175], v[70:71], v[74:75] op_sel_hi:[1,0,1]
	s_nop 0
	v_pk_fma_f32 v[174:175], v[178:179], v[72:73], v[74:75] op_sel_hi:[1,0,1]
	v_rcp_f32_e32 v75, v67
	v_mul_f32_e32 v67, 0xbfb8aa3b, v154
	v_exp_f32_e32 v67, v67
	s_nop 0
	v_add_f32_e32 v67, 1.0, v67
	v_rcp_f32_e32 v74, v67
	v_pk_fma_f32 v[66:67], v[76:77], v[66:67], 0 op_sel_hi:[1,0,0]
	v_pk_mul_f32 v[154:155], v[74:75], v[154:155]
	v_pk_fma_f32 v[66:67], v[80:81], v[68:69], v[66:67] op_sel_hi:[1,0,1]
	global_load_dwordx4 v[74:77], v[90:91], off offset:32
	global_load_dwordx4 v[78:81], v[90:91], off offset:48
	v_pk_fma_f32 v[66:67], v[176:177], v[70:71], v[66:67] op_sel_hi:[1,0,1]
	s_nop 0
	v_pk_fma_f32 v[176:177], v[180:181], v[72:73], v[66:67] op_sel_hi:[1,0,1]
	v_mul_f32_e32 v66, 0xbfb8aa3b, v157
	v_exp_f32_e32 v66, v66
	global_load_dwordx4 v[70:73], v[90:91], off offset:16
	v_add_f32_e32 v66, 1.0, v66
	v_rcp_f32_e32 v67, v66
	v_mul_f32_e32 v66, 0xbfb8aa3b, v156
	v_exp_f32_e32 v66, v66
	s_nop 0
	v_add_f32_e32 v66, 1.0, v66
	v_rcp_f32_e32 v66, v66
	s_nop 0
	v_pk_mul_f32 v[158:159], v[66:67], v[156:157]
	v_mul_f32_e32 v66, 0xbfb8aa3b, v125
	v_exp_f32_e32 v66, v66
	s_nop 0
	v_add_f32_e32 v66, 1.0, v66
	v_rcp_f32_e32 v67, v66
	v_mul_f32_e32 v66, 0xbfb8aa3b, v124
	v_exp_f32_e32 v66, v66
	s_nop 0
	v_add_f32_e32 v66, 1.0, v66
	v_rcp_f32_e32 v66, v66
	s_nop 0
	v_pk_mul_f32 v[156:157], v[66:67], v[124:125]
	global_load_dwordx4 v[66:69], v[98:99], off offset:3072
	s_waitcnt vmcnt(0) lgkmcnt(0)
	v_and_b32_e32 v173, 0xffff0000, v69
	v_lshlrev_b32_e32 v172, 16, v69
	v_and_b32_e32 v179, 0xffff0000, v68
	v_lshlrev_b32_e32 v178, 16, v68
	v_and_b32_e32 v181, 0xffff0000, v67
	v_lshlrev_b32_e32 v180, 16, v67
	v_and_b32_e32 v125, 0xffff0000, v66
	v_lshlrev_b32_e32 v124, 16, v66
	global_load_dwordx4 v[66:69], v[90:91], off
	s_waitcnt vmcnt(0) lgkmcnt(0)
	v_pk_fma_f32 v[66:67], v[66:67], v[0:1], 0 op_sel_hi:[1,0,0]
	s_nop 0
	v_pk_fma_f32 v[66:67], v[70:71], v[126:127], v[66:67] op_sel_hi:[1,0,1]
	s_nop 0
	v_pk_fma_f32 v[66:67], v[74:75], v[128:129], v[66:67] op_sel_hi:[1,0,1]
	s_nop 0
	v_pk_fma_f32 v[70:71], v[78:79], v[130:131], v[66:67] op_sel_hi:[1,0,1]
	v_pk_fma_f32 v[66:67], v[68:69], v[0:1], 0 op_sel_hi:[1,0,0]
	v_mul_f32_e32 v0, 0xbfb8aa3b, v181
	v_exp_f32_e32 v0, v0
	v_pk_fma_f32 v[66:67], v[72:73], v[126:127], v[66:67] op_sel_hi:[1,0,1]
	v_add_f32_e32 v0, 1.0, v0
	v_pk_fma_f32 v[66:67], v[76:77], v[128:129], v[66:67] op_sel_hi:[1,0,1]
	v_mul_f32_e32 v76, 0xbfb8aa3b, v173
	v_pk_fma_f32 v[72:73], v[80:81], v[130:131], v[66:67] op_sel_hi:[1,0,1]
	v_rcp_f32_e32 v67, v0
	v_mul_f32_e32 v0, 0xbfb8aa3b, v180
	v_exp_f32_e32 v0, v0
	v_exp_f32_e32 v76, v76
	v_add_f32_e32 v0, 1.0, v0
	v_rcp_f32_e32 v66, v0
	v_add_f32_e32 v0, v146, v147
	v_add_f32_e32 v0, v0, v148
	v_add_f32_e32 v0, v0, v149
	v_add_f32_e32 v0, v0, v150
	v_add_f32_e32 v0, v0, v151
	v_add_f32_e32 v0, v0, v152
	v_add_f32_e32 v0, v0, v153
	v_add_f32_e32 v0, v0, v160
	v_add_f32_e32 v0, v0, v161
	v_add_f32_e32 v0, v0, v162
	v_add_f32_e32 v0, v0, v163
	v_add_f32_e32 v0, v0, v164
	v_add_f32_e32 v0, v0, v165
	v_add_f32_e32 v0, v0, v166
	v_add_f32_e32 v0, v0, v167
	v_add_f32_e32 v0, v0, v168
	v_add_f32_e32 v0, v0, v169
	v_add_f32_e32 v0, v0, v170
	v_add_f32_e32 v0, v0, v171
	v_add_f32_e32 v0, v0, v174
	v_add_f32_e32 v0, v0, v175
	v_add_f32_e32 v0, v0, v176
	v_add_f32_e32 v0, v0, v177
	v_add_f32_e32 v0, v0, v70
	v_add_f32_e32 v0, v0, v71
	v_add_f32_e32 v0, v0, v72
	v_add_f32_e32 v0, v0, v73
	v_add_f32_e32 v0, v0, v114
	v_add_f32_e32 v0, v0, v115
	v_add_f32_e32 v0, v0, v110
	v_add_f32_e32 v0, v0, v111
	ds_bpermute_b32 v68, v141, v0
	v_pk_mul_f32 v[66:67], v[66:67], v[180:181]
	v_add_f32_e32 v76, 1.0, v76
	v_rcp_f32_e32 v77, v76
	v_mul_f32_e32 v76, 0xbfb8aa3b, v172
	s_waitcnt lgkmcnt(0)
	v_add_f32_e32 v0, v0, v68
	ds_bpermute_b32 v68, v211, v0
	v_exp_f32_e32 v76, v76
	s_waitcnt lgkmcnt(0)
	v_add_f32_e32 v0, v0, v68
	ds_bpermute_b32 v68, v212, v0
	v_add_f32_e32 v76, 1.0, v76
	v_rcp_f32_e32 v76, v76
	s_waitcnt lgkmcnt(0)
	v_add_f32_e32 v0, v0, v68
	ds_bpermute_b32 v68, v213, v0
	v_pk_mul_f32 v[76:77], v[76:77], v[172:173]
	s_waitcnt lgkmcnt(0)
	v_add_f32_e32 v0, v0, v68
	ds_bpermute_b32 v68, v214, v0
	s_waitcnt lgkmcnt(0)
	v_add_f32_e32 v0, v0, v68
	ds_bpermute_b32 v68, v215, v0
	s_waitcnt lgkmcnt(0)
; __device__ void hp_phase(const Ctx& p, const int hd) {
;     ...
;     s = wave_sum(s);
;     const float mu = s * (1.f / 2048.f);
;     float q = 0.f;
; #pragma unroll
;     for (int e = 0; e < 32; ++e) { hv[e] -= mu; q += hv[e] * hv[e]; }
;     q = wave_sum(q);
	v_add_f32_e32 v0, v0, v68
	v_mul_f32_e32 v0, 0x3a000000, v0
	v_pk_add_f32 v[180:181], v[146:147], v[0:1] op_sel_hi:[1,0] neg_lo:[0,1] neg_hi:[0,1]
	v_pk_add_f32 v[182:183], v[148:149], v[0:1] op_sel_hi:[1,0] neg_lo:[0,1] neg_hi:[0,1]
	v_pk_mul_f32 v[216:217], v[180:181], v[180:181]
	v_pk_mul_f32 v[218:219], v[182:183], v[182:183]
	v_pk_add_f32 v[184:185], v[150:151], v[0:1] op_sel_hi:[1,0] neg_lo:[0,1] neg_hi:[0,1]
	v_pk_add_f32 v[186:187], v[152:153], v[0:1] op_sel_hi:[1,0] neg_lo:[0,1] neg_hi:[0,1]
	v_pk_add_f32 v[146:147], v[160:161], v[0:1] op_sel_hi:[1,0] neg_lo:[0,1] neg_hi:[0,1]
	v_pk_add_f32 v[148:149], v[162:163], v[0:1] op_sel_hi:[1,0] neg_lo:[0,1] neg_hi:[0,1]
	v_pk_add_f32 v[150:151], v[164:165], v[0:1] op_sel_hi:[1,0] neg_lo:[0,1] neg_hi:[0,1]
	v_pk_add_f32 v[152:153], v[166:167], v[0:1] op_sel_hi:[1,0] neg_lo:[0,1] neg_hi:[0,1]
	v_pk_add_f32 v[80:81], v[168:169], v[0:1] op_sel_hi:[1,0] neg_lo:[0,1] neg_hi:[0,1]
	v_pk_add_f32 v[126:127], v[170:171], v[0:1] op_sel_hi:[1,0] neg_lo:[0,1] neg_hi:[0,1]
	v_pk_add_f32 v[128:129], v[174:175], v[0:1] op_sel_hi:[1,0] neg_lo:[0,1] neg_hi:[0,1]
	v_pk_add_f32 v[130:131], v[176:177], v[0:1] op_sel_hi:[1,0] neg_lo:[0,1] neg_hi:[0,1]
	v_pk_add_f32 v[68:69], v[70:71], v[0:1] op_sel_hi:[1,0] neg_lo:[0,1] neg_hi:[0,1]
	v_pk_add_f32 v[70:71], v[72:73], v[0:1] op_sel_hi:[1,0] neg_lo:[0,1] neg_hi:[0,1]
	v_pk_add_f32 v[74:75], v[114:115], v[0:1] op_sel_hi:[1,0] neg_lo:[0,1] neg_hi:[0,1]
	v_pk_add_f32 v[78:79], v[110:111], v[0:1] op_sel_hi:[1,0] neg_lo:[0,1] neg_hi:[0,1]
	v_add_f32_e32 v0, v216, v217
	v_add_f32_e32 v0, v218, v0
	v_pk_mul_f32 v[220:221], v[184:185], v[184:185]
	v_add_f32_e32 v0, v219, v0
	v_add_f32_e32 v0, v220, v0
	v_pk_mul_f32 v[222:223], v[186:187], v[186:187]
	v_add_f32_e32 v0, v221, v0
	v_add_f32_e32 v0, v222, v0
	v_pk_mul_f32 v[160:161], v[146:147], v[146:147]
	v_add_f32_e32 v0, v223, v0
	v_add_f32_e32 v0, v160, v0
	v_pk_mul_f32 v[162:163], v[148:149], v[148:149]
	v_add_f32_e32 v0, v161, v0
	v_add_f32_e32 v0, v162, v0
	v_pk_mul_f32 v[164:165], v[150:151], v[150:151]
	v_add_f32_e32 v0, v163, v0
	v_add_f32_e32 v0, v164, v0
	v_pk_mul_f32 v[166:167], v[152:153], v[152:153]
	v_add_f32_e32 v0, v165, v0
	v_add_f32_e32 v0, v166, v0
	v_pk_mul_f32 v[168:169], v[80:81], v[80:81]
	v_add_f32_e32 v0, v167, v0
	v_add_f32_e32 v0, v168, v0
	v_pk_mul_f32 v[170:171], v[126:127], v[126:127]
	v_add_f32_e32 v0, v169, v0
	v_add_f32_e32 v0, v170, v0
	v_pk_mul_f32 v[174:175], v[128:129], v[128:129]
	v_add_f32_e32 v0, v171, v0
	v_add_f32_e32 v0, v174, v0
	v_pk_mul_f32 v[176:177], v[130:131], v[130:131]
	v_add_f32_e32 v0, v175, v0
	v_add_f32_e32 v0, v176, v0
	v_pk_mul_f32 v[224:225], v[68:69], v[68:69]
	v_add_f32_e32 v0, v177, v0
	v_add_f32_e32 v0, v224, v0
	v_pk_mul_f32 v[226:227], v[70:71], v[70:71]
	v_add_f32_e32 v0, v225, v0
	v_add_f32_e32 v0, v226, v0
	v_pk_mul_f32 v[114:115], v[74:75], v[74:75]
	v_add_f32_e32 v0, v227, v0
	v_add_f32_e32 v0, v114, v0
	v_pk_mul_f32 v[110:111], v[78:79], v[78:79]
	v_add_f32_e32 v0, v115, v0
	v_add_f32_e32 v0, v110, v0
	v_add_f32_e32 v0, v111, v0
	ds_bpermute_b32 v110, v141, v0
	v_mul_f32_e32 v72, 0xbfb8aa3b, v179
	v_exp_f32_e32 v72, v72
	s_waitcnt lgkmcnt(0)
	v_add_f32_e32 v0, v0, v110
	ds_bpermute_b32 v110, v211, v0
	v_add_f32_e32 v72, 1.0, v72
	v_rcp_f32_e32 v73, v72
	v_mul_f32_e32 v72, 0xbfb8aa3b, v178
	v_exp_f32_e32 v72, v72
	s_waitcnt lgkmcnt(0)
	v_add_f32_e32 v0, v0, v110
	ds_bpermute_b32 v110, v212, v0
	v_add_f32_e32 v72, 1.0, v72
	v_rcp_f32_e32 v72, v72
	s_waitcnt lgkmcnt(0)
	v_add_f32_e32 v0, v0, v110
	ds_bpermute_b32 v110, v213, v0
	v_pk_mul_f32 v[72:73], v[72:73], v[178:179]
	s_waitcnt lgkmcnt(0)
	v_add_f32_e32 v0, v0, v110
	ds_bpermute_b32 v110, v214, v0
	s_waitcnt lgkmcnt(0)
	v_add_f32_e32 v0, v0, v110
	ds_bpermute_b32 v110, v215, v0
	s_waitcnt lgkmcnt(0)
; __device__ __forceinline__ float bf2f(u16 h) { return __uint_as_float(((unsigned)h) << 16); }
; __device__ __forceinline__ float siluf(float x) { return x * __builtin_amdgcn_rcpf(1.f + __expf(-x)); }
; __device__ void hp_phase(const Ctx& p, const int hd) {
;     ...
;     const float rs = rsqrtf(q * (1.f / 2048.f) + 1e-6f);
; #pragma unroll
;     for (int k = 0; k < 4; ++k) {
;       const int c = k * 512 + lane * 8;
;       uint4 ur = *(const uint4*)(Uh + row * LDQ + c);
;       uint4 zr = *(const uint4*)(cat + row * 8704 + hd * 2048 + c);
;       float u[8] = {bf2f(ur.x & 0xffff), bf2f(ur.x >> 16), bf2f(ur.y & 0xffff), bf2f(ur.y >> 16),
;                     bf2f(ur.z & 0xffff), bf2f(ur.z >> 16), bf2f(ur.w & 0xffff), bf2f(ur.w >> 16)};
;       float z[8] = {bf2f(zr.x & 0xffff), bf2f(zr.x >> 16), bf2f(zr.y & 0xffff), bf2f(zr.y >> 16),
;                     bf2f(zr.z & 0xffff), bf2f(zr.z >> 16), bf2f(zr.w & 0xffff), bf2f(zr.w >> 16)};
;       float o[8];
; #pragma unroll
;       for (int e = 0; e < 8; ++e) {
;         o[e] = (hv[k * 8 + e] * rs * ngr[k * 8 + e] + skr[k * 8 + e] * u[e]) * siluf(z[e]);
;       }
;       uint4 ov; ov.x = pack2(o[0], o[1]); ov.y = pack2(o[2], o[3]); ov.z = pack2(o[4], o[5]); ov.w = pack2(o[6], o[7]);
;       if (!p.dry) *(uint4*)(cat + row * 8704 + hd * 2048 + c) = ov;
;     }
	v_add_f32_e32 v0, v0, v110
	v_mov_b32_e32 v110, 0x358637bd
	v_fmamk_f32 v0, v0, 0x3a000000, v110
	v_cmp_gt_f32_e32 vcc, s48, v0
	v_mul_f32_e32 v110, 0x4b800000, v0
	s_nop 0
	v_cndmask_b32_e32 v0, v0, v110, vcc
	v_rsq_f32_e32 v0, v0
	s_nop 0
	v_mul_f32_e32 v110, 0x45800000, v0
	v_cndmask_b32_e32 v0, v0, v110, vcc
	v_pk_mul_f32 v[110:111], v[186:187], v[0:1] op_sel_hi:[1,0]
	v_pk_mul_f32 v[80:81], v[80:81], v[0:1] op_sel_hi:[1,0]
	v_pk_mul_f32 v[110:111], v[8:9], v[110:111]
	v_pk_mul_f32 v[80:81], v[34:35], v[80:81]
	v_pk_fma_f32 v[102:103], v[16:17], v[102:103], v[110:111]
	v_pk_mul_f32 v[110:111], v[184:185], v[0:1] op_sel_hi:[1,0]
	v_pk_mul_f32 v[102:103], v[120:121], v[102:103]
	v_pk_mul_f32 v[110:111], v[6:7], v[110:111]
	v_pk_mul_f32 v[78:79], v[78:79], v[0:1] op_sel_hi:[1,0]
	v_pk_fma_f32 v[106:107], v[14:15], v[106:107], v[110:111]
	v_pk_mul_f32 v[110:111], v[182:183], v[0:1] op_sel_hi:[1,0]
	v_pk_mul_f32 v[106:107], v[116:117], v[106:107]
	v_pk_mul_f32 v[110:111], v[4:5], v[110:111]
	v_pk_mul_f32 v[78:79], v[60:61], v[78:79]
	v_pk_fma_f32 v[108:109], v[12:13], v[108:109], v[110:111]
	v_pk_mul_f32 v[110:111], v[180:181], v[0:1] op_sel_hi:[1,0]
	v_pk_mul_f32 v[108:109], v[112:113], v[108:109]
	v_pk_mul_f32 v[110:111], v[2:3], v[110:111]
	v_pk_mul_f32 v[74:75], v[74:75], v[0:1] op_sel_hi:[1,0]
	v_pk_fma_f32 v[104:105], v[10:11], v[104:105], v[110:111]
	v_pk_mul_f32 v[74:75], v[58:59], v[74:75]
	v_pk_mul_f32 v[110:111], v[118:119], v[104:105]
	v_cvt_pk_bf16_f32 v105, v102, v103
	v_cvt_pk_bf16_f32 v104, v106, v107
	v_cvt_pk_bf16_f32 v103, v108, v109
	v_cvt_pk_bf16_f32 v102, v110, v111
	global_store_dwordx4 v[98:99], v[102:105], off
	global_load_dwordx4 v[102:105], v[100:101], off offset:1024
	v_pk_mul_f32 v[108:109], v[152:153], v[0:1] op_sel_hi:[1,0]
	v_pk_mul_f32 v[110:111], v[148:149], v[0:1] op_sel_hi:[1,0]
	v_pk_mul_f32 v[108:109], v[24:25], v[108:109]
	v_pk_mul_f32 v[110:111], v[20:21], v[110:111]
	v_pk_mul_f32 v[70:71], v[70:71], v[0:1] op_sel_hi:[1,0]
	v_pk_mul_f32 v[68:69], v[68:69], v[0:1] op_sel_hi:[1,0]
	v_pk_mul_f32 v[70:71], v[52:53], v[70:71]
	s_waitcnt vmcnt(0) lgkmcnt(0)
	v_and_b32_e32 v107, 0xffff0000, v105
	v_lshlrev_b32_e32 v106, 16, v105
	v_pk_fma_f32 v[106:107], v[32:33], v[106:107], v[108:109]
	v_pk_mul_f32 v[108:109], v[150:151], v[0:1] op_sel_hi:[1,0]
	v_and_b32_e32 v105, 0xffff0000, v104
	v_pk_mul_f32 v[108:109], v[22:23], v[108:109]
	v_lshlrev_b32_e32 v104, 16, v104
	v_pk_fma_f32 v[104:105], v[30:31], v[104:105], v[108:109]
	v_pk_mul_f32 v[106:107], v[142:143], v[106:107]
	v_pk_mul_f32 v[108:109], v[132:133], v[104:105]
	v_and_b32_e32 v105, 0xffff0000, v103
	v_lshlrev_b32_e32 v104, 16, v103
	v_pk_fma_f32 v[104:105], v[28:29], v[104:105], v[110:111]
	v_and_b32_e32 v103, 0xffff0000, v102
	v_pk_mul_f32 v[110:111], v[122:123], v[104:105]
	v_pk_mul_f32 v[104:105], v[146:147], v[0:1] op_sel_hi:[1,0]
	v_lshlrev_b32_e32 v102, 16, v102
	v_pk_mul_f32 v[104:105], v[18:19], v[104:105]
	s_nop 0
	v_pk_fma_f32 v[102:103], v[26:27], v[102:103], v[104:105]
	v_cvt_pk_bf16_f32 v105, v106, v107
	v_pk_mul_f32 v[112:113], v[134:135], v[102:103]
	v_cvt_pk_bf16_f32 v104, v108, v109
	v_cvt_pk_bf16_f32 v103, v110, v111
	v_cvt_pk_bf16_f32 v102, v112, v113
	global_store_dwordx4 v[98:99], v[102:105], off offset:1024
	global_load_dwordx4 v[102:105], v[100:101], off offset:2048
	v_pk_mul_f32 v[108:109], v[130:131], v[0:1] op_sel_hi:[1,0]
	v_pk_mul_f32 v[110:111], v[126:127], v[0:1] op_sel_hi:[1,0]
	v_pk_mul_f32 v[108:109], v[44:45], v[108:109]
	v_pk_mul_f32 v[110:111], v[36:37], v[110:111]
	s_waitcnt vmcnt(0) lgkmcnt(0)
	v_and_b32_e32 v107, 0xffff0000, v105
	v_lshlrev_b32_e32 v106, 16, v105
	v_pk_fma_f32 v[106:107], v[48:49], v[106:107], v[108:109]
	v_pk_mul_f32 v[108:109], v[128:129], v[0:1] op_sel_hi:[1,0]
	v_and_b32_e32 v105, 0xffff0000, v104
	v_pk_mul_f32 v[108:109], v[42:43], v[108:109]
	v_lshlrev_b32_e32 v104, 16, v104
	v_pk_fma_f32 v[104:105], v[46:47], v[104:105], v[108:109]
	v_pk_mul_f32 v[106:107], v[158:159], v[106:107]
	v_pk_mul_f32 v[108:109], v[154:155], v[104:105]
	v_and_b32_e32 v105, 0xffff0000, v103
	v_lshlrev_b32_e32 v104, 16, v103
	v_and_b32_e32 v103, 0xffff0000, v102
	v_lshlrev_b32_e32 v102, 16, v102
	v_pk_fma_f32 v[104:105], v[40:41], v[104:105], v[110:111]
	v_pk_fma_f32 v[80:81], v[38:39], v[102:103], v[80:81]
	v_pk_mul_f32 v[110:111], v[144:145], v[104:105]
	v_pk_mul_f32 v[80:81], v[156:157], v[80:81]
	v_cvt_pk_bf16_f32 v105, v106, v107
	v_cvt_pk_bf16_f32 v104, v108, v109
	v_cvt_pk_bf16_f32 v103, v110, v111
	v_cvt_pk_bf16_f32 v102, v80, v81
	global_store_dwordx4 v[98:99], v[102:105], off offset:2048
	global_load_dwordx4 v[100:103], v[100:101], off offset:3072
	v_mul_f32_e32 v0, 0xbfb8aa3b, v124
	v_exp_f32_e32 v0, v0
	s_waitcnt vmcnt(0) lgkmcnt(0)
	v_and_b32_e32 v81, 0xffff0000, v103
	v_lshlrev_b32_e32 v80, 16, v103
	v_pk_fma_f32 v[78:79], v[64:65], v[80:81], v[78:79]
	v_add_f32_e32 v0, 1.0, v0
	v_pk_mul_f32 v[76:77], v[76:77], v[78:79]
	v_and_b32_e32 v79, 0xffff0000, v102
	v_lshlrev_b32_e32 v78, 16, v102
	v_pk_fma_f32 v[74:75], v[62:63], v[78:79], v[74:75]
	s_nop 0
	v_pk_mul_f32 v[72:73], v[74:75], v[72:73]
	v_and_b32_e32 v75, 0xffff0000, v101
	v_lshlrev_b32_e32 v74, 16, v101
	v_pk_fma_f32 v[70:71], v[56:57], v[74:75], v[70:71]
	v_rcp_f32_e32 v74, v0
	v_pk_mul_f32 v[66:67], v[70:71], v[66:67]
	v_mul_f32_e32 v70, 0xbfb8aa3b, v125
	v_exp_f32_e32 v70, v70
	v_and_b32_e32 v71, 0xffff0000, v100
	v_cvt_pk_bf16_f32 v67, v66, v67
	v_add_f32_e32 v70, 1.0, v70
	v_rcp_f32_e32 v75, v70
	v_lshlrev_b32_e32 v70, 16, v100
	v_pk_mul_f32 v[70:71], v[54:55], v[70:71]
	s_nop 0
	v_pk_fma_f32 v[68:69], v[50:51], v[68:69], v[70:71]
	v_pk_mul_f32 v[70:71], v[74:75], v[124:125]
	s_nop 0
	v_pk_mul_f32 v[70:71], v[68:69], v[70:71]
	v_cvt_pk_bf16_f32 v69, v76, v77
	v_cvt_pk_bf16_f32 v68, v72, v73
	v_cvt_pk_bf16_f32 v66, v70, v71
	global_store_dwordx4 v[98:99], v[66:69], off offset:3072
	s_cbranch_scc0 .LBB0_421

; __device__ __forceinline__ int ltid() { int t = threadIdx.x; asm volatile("" : "+v"(t)); return t; }
; template <int KIND>
; __device__ void gemm_phase(const Ctx& p, int hd, const int ntiles, const int blk0, const int nblk) {
;     ...
;         if (KIND == G_NUM && s == 0) {
;           int tb, tc, tr, tv; num_decode(t, tb, tc, tr, tv);
;           const int bh = tb * 4 + hd;
;           const float Ap = gA[bh * SEQ + tc * 2048 - 1];
;           const float* Ar = gA + bh * SEQ + tc * 2048 + tr * 256;
;           const int wid = ltid() >> 6, lane = ltid() & 63, wr = wid >> 2, fq = lane >> 4;
; #pragma unroll
;           for (int ai = 0; ai < 2; ++ai)
; #pragma unroll
;             for (int m = 0; m < 4; ++m) {
;               int r0 = ai * 128 + wr * 64 + m * 16 + fq * 4;
;               float4 a4 = *(const float4*)(Ar + r0);
;               float w0 = __expf(Ap - a4.x), w1 = __expf(Ap - a4.y), w2 = __expf(Ap - a4.z), w3 = __expf(Ap - a4.w);
; #pragma unroll
;               for (int bj = 0; bj < 2; ++bj)
; #pragma unroll
;                 for (int n = 0; n < 2; ++n) {
;                   acc[ai][bj][m][n][0] *= w0; acc[ai][bj][m][n][1] *= w1;
;                   acc[ai][bj][m][n][2] *= w2; acc[ai][bj][m][n][3] *= w3;
;                 }
;             }
;         }
.LBB0_459:
	s_lshl_b32 s1, s6, 15
	s_and_b32 s1, s1, 0x8000
	s_add_i32 s1, s1, s20
	s_add_i32 s6, s1, s0
	s_ashr_i32 s7, s6, 31
	s_lshl_b64 s[6:7], s[6:7], 2
	s_add_u32 s6, s15, s6
	s_addc_u32 s7, s17, s7
	s_lshl_b32 s1, s1, 2
	v_add_co_u32_e64 v2, vcc, -4, s6
	s_add_u32 s6, s15, s1
	v_mov_b32_e32 v0, s7
	s_addc_u32 s7, s17, 0
	s_ashr_i32 s1, s0, 31
	v_addc_co_u32_e32 v3, vcc, -1, v0, vcc
	s_lshl_b64 s[0:1], s[0:1], 2
	global_load_dword v0, v[2:3], off
	s_add_u32 s6, s6, s0
	v_mov_b32_e32 v2, v139
	s_addc_u32 s7, s7, s1
	s_lshl_b32 s0, s5, 8
	v_mov_b32_e32 v3, v139
	s_ashr_i32 s1, s0, 31
	v_ashrrev_i32_e32 v2, 2, v2
	s_lshl_b64 s[0:1], s[0:1], 2
	v_and_b32_e32 v2, 0xffffffc0, v2
	v_lshrrev_b32_e32 v3, 2, v3
	s_add_u32 s0, s6, s0
	v_and_or_b32 v2, v3, 12, v2
	s_addc_u32 s1, s7, s1
	v_ashrrev_i32_e32 v3, 31, v2
	v_lshl_add_u64 v[2:3], v[2:3], 2, s[0:1]
	global_load_dwordx4 v[132:135], v[2:3], off
	s_waitcnt vmcnt(0) lgkmcnt(0)
	v_sub_f32_e32 v132, v0, v132
	v_sub_f32_e32 v133, v0, v133
	v_sub_f32_e32 v134, v0, v134
	v_sub_f32_e32 v135, v0, v135
	v_mul_f32_e32 v132, 0x3fb8aa3b, v132
	v_mul_f32_e32 v133, 0x3fb8aa3b, v133
	v_mul_f32_e32 v134, 0x3fb8aa3b, v134
	v_mul_f32_e32 v135, 0x3fb8aa3b, v135
	v_exp_f32_e32 v132, v132
	v_exp_f32_e32 v133, v133
	v_exp_f32_e32 v134, v134
	v_exp_f32_e32 v135, v135
	v_pk_mul_f32 v[128:129], v[128:129], v[132:133]
	v_pk_mul_f32 v[124:125], v[124:125], v[132:133]
	v_pk_mul_f32 v[130:131], v[130:131], v[134:135]
	v_pk_mul_f32 v[126:127], v[126:127], v[134:135]
	v_pk_mul_f32 v[98:99], v[98:99], v[134:135]
	v_pk_mul_f32 v[96:97], v[96:97], v[132:133]
	v_pk_mul_f32 v[94:95], v[94:95], v[134:135]
	v_pk_mul_f32 v[92:93], v[92:93], v[132:133]
	global_load_dwordx4 v[132:135], v[2:3], off offset:64
	s_waitcnt vmcnt(0) lgkmcnt(0)
	v_sub_f32_e32 v132, v0, v132
	v_sub_f32_e32 v133, v0, v133
	v_sub_f32_e32 v134, v0, v134
	v_sub_f32_e32 v135, v0, v135
	v_mul_f32_e32 v132, 0x3fb8aa3b, v132
	v_mul_f32_e32 v133, 0x3fb8aa3b, v133
	v_mul_f32_e32 v134, 0x3fb8aa3b, v134
	v_mul_f32_e32 v135, 0x3fb8aa3b, v135
	v_exp_f32_e32 v132, v132
	v_exp_f32_e32 v133, v133
	v_exp_f32_e32 v134, v134
	v_exp_f32_e32 v135, v135
	v_pk_mul_f32 v[120:121], v[120:121], v[132:133]
	v_pk_mul_f32 v[116:117], v[116:117], v[132:133]
	v_pk_mul_f32 v[122:123], v[122:123], v[134:135]
	v_pk_mul_f32 v[118:119], v[118:119], v[134:135]
	v_pk_mul_f32 v[90:91], v[90:91], v[134:135]
	v_pk_mul_f32 v[88:89], v[88:89], v[132:133]
	v_pk_mul_f32 v[86:87], v[86:87], v[134:135]
	v_pk_mul_f32 v[84:85], v[84:85], v[132:133]
	global_load_dwordx4 v[132:135], v[2:3], off offset:128
	s_waitcnt vmcnt(0) lgkmcnt(0)
	v_sub_f32_e32 v132, v0, v132
	v_sub_f32_e32 v133, v0, v133
	v_sub_f32_e32 v134, v0, v134
	v_sub_f32_e32 v135, v0, v135
	v_mul_f32_e32 v132, 0x3fb8aa3b, v132
	v_mul_f32_e32 v133, 0x3fb8aa3b, v133
	v_mul_f32_e32 v134, 0x3fb8aa3b, v134
	v_mul_f32_e32 v135, 0x3fb8aa3b, v135
	v_exp_f32_e32 v132, v132
	v_exp_f32_e32 v133, v133
	v_exp_f32_e32 v134, v134
	v_exp_f32_e32 v135, v135
	v_pk_mul_f32 v[112:113], v[112:113], v[132:133]
	v_pk_mul_f32 v[108:109], v[108:109], v[132:133]
	v_pk_mul_f32 v[114:115], v[114:115], v[134:135]
	v_pk_mul_f32 v[110:111], v[110:111], v[134:135]
	v_pk_mul_f32 v[82:83], v[82:83], v[134:135]
	v_pk_mul_f32 v[80:81], v[80:81], v[132:133]
	v_pk_mul_f32 v[78:79], v[78:79], v[134:135]
	v_pk_mul_f32 v[76:77], v[76:77], v[132:133]
	global_load_dwordx4 v[132:135], v[2:3], off offset:192
	s_waitcnt vmcnt(0) lgkmcnt(0)
; template <int KIND>
; __device__ void gemm_phase(const Ctx& p, int hd, const int ntiles, const int blk0, const int nblk) {
;     ...
; #pragma unroll
;           for (int ai = 0; ai < 2; ++ai)
; #pragma unroll
;             for (int m = 0; m < 4; ++m) {
;               int r0 = ai * 128 + wr * 64 + m * 16 + fq * 4;
;               float4 a4 = *(const float4*)(Ar + r0);
;               float w0 = __expf(Ap - a4.x), w1 = __expf(Ap - a4.y), w2 = __expf(Ap - a4.z), w3 = __expf(Ap - a4.w);
; #pragma unroll
;               for (int bj = 0; bj < 2; ++bj)
; #pragma unroll
;                 for (int n = 0; n < 2; ++n) {
;                   acc[ai][bj][m][n][0] *= w0; acc[ai][bj][m][n][1] *= w1;
;                   acc[ai][bj][m][n][2] *= w2; acc[ai][bj][m][n][3] *= w3;
;                 }
;             }
	v_sub_f32_e32 v132, v0, v132
	v_sub_f32_e32 v133, v0, v133
	v_sub_f32_e32 v134, v0, v134
	v_sub_f32_e32 v135, v0, v135
	v_mul_f32_e32 v132, 0x3fb8aa3b, v132
	v_mul_f32_e32 v133, 0x3fb8aa3b, v133
	v_mul_f32_e32 v134, 0x3fb8aa3b, v134
	v_mul_f32_e32 v135, 0x3fb8aa3b, v135
	v_exp_f32_e32 v132, v132
	v_exp_f32_e32 v133, v133
	v_exp_f32_e32 v134, v134
	v_exp_f32_e32 v135, v135
	v_pk_mul_f32 v[104:105], v[104:105], v[132:133]
	v_pk_mul_f32 v[100:101], v[100:101], v[132:133]
	v_pk_mul_f32 v[106:107], v[106:107], v[134:135]
	v_pk_mul_f32 v[102:103], v[102:103], v[134:135]
	v_pk_mul_f32 v[74:75], v[74:75], v[134:135]
	v_pk_mul_f32 v[72:73], v[72:73], v[132:133]
	v_pk_mul_f32 v[70:71], v[70:71], v[134:135]
	v_pk_mul_f32 v[68:69], v[68:69], v[132:133]
	global_load_dwordx4 v[132:135], v[2:3], off offset:512
	s_waitcnt vmcnt(0) lgkmcnt(0)
	v_sub_f32_e32 v132, v0, v132
	v_sub_f32_e32 v133, v0, v133
	v_sub_f32_e32 v134, v0, v134
	v_sub_f32_e32 v135, v0, v135
	v_mul_f32_e32 v132, 0x3fb8aa3b, v132
	v_mul_f32_e32 v133, 0x3fb8aa3b, v133
	v_mul_f32_e32 v134, 0x3fb8aa3b, v134
	v_mul_f32_e32 v135, 0x3fb8aa3b, v135
	v_exp_f32_e32 v132, v132
	v_exp_f32_e32 v133, v133
	v_exp_f32_e32 v134, v134
	v_exp_f32_e32 v135, v135
	v_pk_mul_f32 v[64:65], v[64:65], v[132:133]
	v_pk_mul_f32 v[60:61], v[60:61], v[132:133]
	v_pk_mul_f32 v[66:67], v[66:67], v[134:135]
	v_pk_mul_f32 v[62:63], v[62:63], v[134:135]
	v_pk_mul_f32 v[34:35], v[34:35], v[134:135]
	v_pk_mul_f32 v[32:33], v[32:33], v[132:133]
	v_pk_mul_f32 v[30:31], v[30:31], v[134:135]
	v_pk_mul_f32 v[28:29], v[28:29], v[132:133]
	global_load_dwordx4 v[132:135], v[2:3], off offset:576
	s_waitcnt vmcnt(0) lgkmcnt(0)
	v_sub_f32_e32 v132, v0, v132
	v_sub_f32_e32 v133, v0, v133
	v_sub_f32_e32 v134, v0, v134
	v_sub_f32_e32 v135, v0, v135
	v_mul_f32_e32 v132, 0x3fb8aa3b, v132
	v_mul_f32_e32 v133, 0x3fb8aa3b, v133
	v_mul_f32_e32 v134, 0x3fb8aa3b, v134
	v_mul_f32_e32 v135, 0x3fb8aa3b, v135
	v_exp_f32_e32 v132, v132
	v_exp_f32_e32 v133, v133
	v_exp_f32_e32 v134, v134
	v_exp_f32_e32 v135, v135
	v_pk_mul_f32 v[56:57], v[56:57], v[132:133]
	v_pk_mul_f32 v[52:53], v[52:53], v[132:133]
	v_pk_mul_f32 v[58:59], v[58:59], v[134:135]
	v_pk_mul_f32 v[54:55], v[54:55], v[134:135]
	v_pk_mul_f32 v[26:27], v[26:27], v[134:135]
	v_pk_mul_f32 v[24:25], v[24:25], v[132:133]
	v_pk_mul_f32 v[22:23], v[22:23], v[134:135]
	v_pk_mul_f32 v[20:21], v[20:21], v[132:133]
	global_load_dwordx4 v[132:135], v[2:3], off offset:640
	s_waitcnt vmcnt(0) lgkmcnt(0)
	v_sub_f32_e32 v132, v0, v132
	v_sub_f32_e32 v133, v0, v133
	v_sub_f32_e32 v134, v0, v134
	v_sub_f32_e32 v135, v0, v135
	v_mul_f32_e32 v132, 0x3fb8aa3b, v132
	v_mul_f32_e32 v133, 0x3fb8aa3b, v133
	v_mul_f32_e32 v134, 0x3fb8aa3b, v134
	v_mul_f32_e32 v135, 0x3fb8aa3b, v135
	v_exp_f32_e32 v132, v132
	v_exp_f32_e32 v133, v133
	v_exp_f32_e32 v134, v134
	v_exp_f32_e32 v135, v135
	v_pk_mul_f32 v[48:49], v[48:49], v[132:133]
	v_pk_mul_f32 v[44:45], v[44:45], v[132:133]
	v_pk_mul_f32 v[50:51], v[50:51], v[134:135]
	v_pk_mul_f32 v[46:47], v[46:47], v[134:135]
	v_pk_mul_f32 v[18:19], v[18:19], v[134:135]
	v_pk_mul_f32 v[16:17], v[16:17], v[132:133]
	v_pk_mul_f32 v[14:15], v[14:15], v[134:135]
	v_pk_mul_f32 v[12:13], v[12:13], v[132:133]
	global_load_dwordx4 v[132:135], v[2:3], off offset:704
	s_waitcnt vmcnt(0) lgkmcnt(0)
	v_sub_f32_e32 v2, v0, v132
	v_sub_f32_e32 v3, v0, v133
	v_sub_f32_e32 v132, v0, v134
	v_sub_f32_e32 v0, v0, v135
	v_mul_f32_e32 v2, 0x3fb8aa3b, v2
	v_mul_f32_e32 v3, 0x3fb8aa3b, v3
	v_mul_f32_e32 v132, 0x3fb8aa3b, v132
	v_mul_f32_e32 v0, 0x3fb8aa3b, v0
	v_exp_f32_e32 v2, v2
	v_exp_f32_e32 v3, v3
	v_exp_f32_e32 v132, v132
	v_exp_f32_e32 v133, v0
	v_pk_mul_f32 v[40:41], v[40:41], v[2:3]
	v_pk_mul_f32 v[36:37], v[36:37], v[2:3]
	v_pk_mul_f32 v[42:43], v[42:43], v[132:133]
	v_pk_mul_f32 v[38:39], v[38:39], v[132:133]
	v_pk_mul_f32 v[10:11], v[10:11], v[132:133]
	v_pk_mul_f32 v[8:9], v[8:9], v[2:3]
	v_pk_mul_f32 v[6:7], v[6:7], v[132:133]
	v_pk_mul_f32 v[4:5], v[4:5], v[2:3]

; __device__ __forceinline__ int ltid() { int t = threadIdx.x; asm volatile("" : "+v"(t)); return t; }
; template <int AI>
; __device__ __forceinline__ void dump_half(const f32x4 (&acc)[2][2][4][2], float* stage) {
;   const int wid = ltid() >> 6, lane = ltid() & 63, wr = wid >> 2, wc = wid & 3, fr = lane & 15, fq = lane >> 4;
; #pragma unroll
;   for (int bj = 0; bj < 2; ++bj)
; #pragma unroll
;     for (int m = 0; m < 4; ++m)
; #pragma unroll
;       for (int n = 0; n < 2; ++n) {
;         const int r0 = wr * 64 + m * 16 + fq * 4, c = bj * 128 + wc * 32 + n * 16 + fr;
; #pragma unroll
;         for (int j = 0; j < 4; ++j) stage[(r0 + j) * SP + c] = acc[AI][bj][m][n][j];
;       }
; }
; __device__ __forceinline__ void emit_rm(const float* stage, u16* dst, long ld, const float* rs) {
;   const int tid = ltid(), c4 = (tid & 31) * 4, rr = tid >> 5;
; #pragma unroll 1
;   for (int ps = 0; ps < 8; ++ps) {
;     const int r = ps * 16 + rr;
;     const float* s = stage + r * SP + c4;
;     const float4 a = *(const float4*)s, b = *(const float4*)(s + 128);
;     const float f = rs ? rs[r] : 1.f;
;     uint2 o0, o1;
;     o0.x = pack2(a.x * f, a.y * f); o0.y = pack2(a.z * f, a.w * f);
;     o1.x = pack2(b.x * f, b.y * f); o1.y = pack2(b.z * f, b.w * f);
;     *(uint2*)(dst + (long)r * ld + c4) = o0;
;     *(uint2*)(dst + (long)r * ld + 128 + c4) = o1;
;   }
; }
; template <int KIND>
; __device__ __forceinline__ void tile_emit(const Ctx& p, int t, int hd, int s, int half, const float* stage) {
;     ...
;   } else {
;     int tb, tc, tr, tv; num_decode(t, tb, tc, tr, tv);
;     emit_rm(stage, (u16*)(ws + OFF_KH) + ((long)tb * SEQ + tc * 2048 + tr * 256 + hr) * LDQ + tv * 256, LDQ,
;             (const float*)(ws + OFF_RDEN) + tb * SEQ + tc * 2048 + tr * 256 + hr);
;   }
.LBB0_466:
	v_lshl_add_u64 v[70:71], s[66:67], 0, v[68:69]
	global_load_dword v74, v[70:71], off
	v_add_u32_e32 v75, s4, v0
	ds_read_b128 v[70:73], v75
	s_addk_i32 s4, 0x4100
	v_lshl_add_u64 v[68:69], v[68:69], 0, 64
	s_cmp_lg_u32 s4, 0x20800
	s_waitcnt vmcnt(0) lgkmcnt(0)
	v_pk_mul_f32 v[70:71], v[70:71], v[74:75] op_sel_hi:[1,0]
	s_nop 0
	v_cvt_pk_bf16_f32 v76, v70, v71
	v_pk_mul_f32 v[70:71], v[72:73], v[74:75] op_sel_hi:[1,0]
	s_nop 0
	v_cvt_pk_bf16_f32 v77, v70, v71
	ds_read_b128 v[70:73], v75 offset:512
	s_waitcnt lgkmcnt(0)
	v_pk_mul_f32 v[70:71], v[70:71], v[74:75] op_sel_hi:[1,0]
	v_pk_mul_f32 v[72:73], v[72:73], v[74:75] op_sel_hi:[1,0]
	v_cvt_pk_bf16_f32 v70, v70, v71
	v_cvt_pk_bf16_f32 v71, v72, v73
	v_lshl_add_u64 v[72:73], s[66:67], 0, v[2:3]
	v_add_co_u32_e32 v72, vcc, 0x4200000, v72
	v_lshl_add_u64 v[2:3], v[2:3], 0, s[8:9]
	s_nop 0
	v_addc_co_u32_e32 v73, vcc, 0, v73, vcc
	global_store_dwordx2 v[72:73], v[76:77], off
	global_store_dwordx2 v[72:73], v[70:71], off offset:256
	s_cbranch_scc1 .LBB0_466
	v_mov_b32_e32 v0, v139
	v_mov_b32_e32 v2, v139
	s_waitcnt lgkmcnt(0)
	s_barrier
	s_mov_b64 s[4:5], -1
	v_lshrrev_b32_e32 v68, 2, v0
	v_and_b32_e32 v3, 15, v2
	v_and_b32_e32 v68, 0xfffffc0, v68
	v_lshrrev_b32_e32 v2, 2, v2
	v_lshlrev_b32_e32 v0, 1, v0
	v_and_or_b32 v2, v2, 12, v68
	v_and_b32_e32 v0, 0x180, v0
	v_add_u32_e32 v0, 16, v0
	v_lshlrev_b32_e32 v3, 2, v3
	v_mul_lo_u32 v2, v2, s81
	v_add3_u32 v0, v0, v3, v2
	v_add_u32_e32 v2, 0x400, v0
	ds_write2_b32 v2, v65, v61 offset0:4 offset1:20
	v_add_u32_e32 v61, 0x4000, v0
	ds_write2_b32 v61, v56, v52 offset0:64 offset1:80
	v_add_u32_e32 v52, 0x4400, v0
	ds_write2_b32 v52, v57, v53 offset0:68 offset1:84
	v_add_u32_e32 v53, 0x4800, v0
	ds_write2_b32 v53, v58, v54 offset0:72 offset1:88
	v_add_u32_e32 v54, 0x4c00, v0
	ds_write2_b32 v54, v59, v55 offset0:76 offset1:92
	v_add_u32_e32 v55, 0x8000, v0
	ds_write2_b32 v55, v48, v44 offset0:128 offset1:144
	v_add_u32_e32 v44, 0x8400, v0
	ds_write2_b32 v44, v49, v45 offset0:132 offset1:148
	v_add_u32_e32 v45, 0x8800, v0
	ds_write2_b32 v45, v50, v46 offset0:136 offset1:152
	v_add_u32_e32 v46, 0x8c00, v0
	ds_write2_b32 v46, v51, v47 offset0:140 offset1:156
	v_add_u32_e32 v47, 0xc000, v0
	ds_write2_b32 v47, v40, v36 offset0:192 offset1:208
	v_add_u32_e32 v36, 0xc400, v0
	ds_write2_b32 v36, v41, v37 offset0:196 offset1:212
	v_add_u32_e32 v37, 0xc800, v0
	ds_write2_b32 v0, v64, v60 offset1:16
	v_add_u32_e32 v3, 0x800, v0
	v_add_u32_e32 v60, 0xc00, v0
	ds_write2_b32 v37, v42, v38 offset0:200 offset1:216
	v_add_u32_e32 v38, 0xcc00, v0
	ds_write2_b32 v3, v66, v62 offset0:8 offset1:24
	ds_write2_b32 v60, v67, v63 offset0:12 offset1:28
	ds_write2_b32 v38, v43, v39 offset0:204 offset1:220
	ds_write2_b32 v0, v32, v28 offset0:128 offset1:144
	ds_write2_b32 v2, v33, v29 offset0:132 offset1:148
	ds_write2_b32 v3, v34, v30 offset0:136 offset1:152
	ds_write2_b32 v60, v35, v31 offset0:140 offset1:156
	ds_write2_b32 v61, v24, v20 offset0:192 offset1:208
	ds_write2_b32 v52, v25, v21 offset0:196 offset1:212
	ds_write2_b32 v53, v26, v22 offset0:200 offset1:216
	ds_write2_b32 v54, v27, v23 offset0:204 offset1:220
	ds_write2_b32 v44, v16, v12 offset1:16
	ds_write2_b32 v45, v17, v13 offset0:4 offset1:20
	ds_write2_b32 v46, v18, v14 offset0:8 offset1:24
	v_add_u32_e32 v2, 0x9000, v0
	v_add_u32_e32 v0, 0xd000, v0
	s_and_b64 vcc, exec, s[0:1]
	ds_write2_b32 v2, v19, v15 offset0:12 offset1:28
	ds_write2_b32 v36, v8, v4 offset0:64 offset1:80
	ds_write2_b32 v37, v9, v5 offset0:68 offset1:84
	ds_write2_b32 v38, v10, v6 offset0:72 offset1:88
	ds_write2_b32 v0, v11, v7 offset0:76 offset1:92
	s_waitcnt lgkmcnt(0)
	s_barrier
	s_cbranch_vccz .LBB0_469
	s_add_i32 s0, s28, 0xfffffe80
	s_lshr_b32 s0, s0, 4
	s_sub_i32 s8, 7, s0
	s_lshr_b32 s9, s28, 3
	s_mov_b64 s[4:5], 0

; __device__ __forceinline__ int ltid() { int t = threadIdx.x; asm volatile("" : "+v"(t)); return t; }
; __device__ __forceinline__ void emit_rm(const float* stage, u16* dst, long ld, const float* rs) {
;   const int tid = ltid(), c4 = (tid & 31) * 4, rr = tid >> 5;
; #pragma unroll 1
;   for (int ps = 0; ps < 8; ++ps) {
;     const int r = ps * 16 + rr;
;     const float* s = stage + r * SP + c4;
;     const float4 a = *(const float4*)s, b = *(const float4*)(s + 128);
;     const float f = rs ? rs[r] : 1.f;
;     uint2 o0, o1;
;     o0.x = pack2(a.x * f, a.y * f); o0.y = pack2(a.z * f, a.w * f);
;     o1.x = pack2(b.x * f, b.y * f); o1.y = pack2(b.z * f, b.w * f);
;     *(uint2*)(dst + (long)r * ld + c4) = o0;
;     *(uint2*)(dst + (long)r * ld + 128 + c4) = o1;
;   }
; }
.LBB0_472:
	v_lshl_add_u64 v[6:7], s[66:67], 0, v[4:5]
	global_load_dword v10, v[6:7], off
	v_add_u32_e32 v11, s0, v0
	ds_read_b128 v[6:9], v11
	s_addk_i32 s0, 0x4100
	v_lshl_add_u64 v[4:5], v[4:5], 0, 64
	s_cmp_lg_u32 s0, 0x20800
	s_waitcnt vmcnt(0) lgkmcnt(0)
	v_pk_mul_f32 v[6:7], v[6:7], v[10:11] op_sel_hi:[1,0]
	s_nop 0
	v_cvt_pk_bf16_f32 v12, v6, v7
	v_pk_mul_f32 v[6:7], v[8:9], v[10:11] op_sel_hi:[1,0]
	s_nop 0
	v_cvt_pk_bf16_f32 v13, v6, v7
	ds_read_b128 v[6:9], v11 offset:512
	s_waitcnt lgkmcnt(0)
	v_pk_mul_f32 v[6:7], v[6:7], v[10:11] op_sel_hi:[1,0]
	v_pk_mul_f32 v[8:9], v[8:9], v[10:11] op_sel_hi:[1,0]
	v_cvt_pk_bf16_f32 v6, v6, v7
	v_cvt_pk_bf16_f32 v7, v8, v9
	v_lshl_add_u64 v[8:9], s[66:67], 0, v[2:3]
	v_add_co_u32_e32 v8, vcc, 0x4284000, v8
	v_lshl_add_u64 v[2:3], v[2:3], 0, s[4:5]
	s_nop 0
	v_addc_co_u32_e32 v9, vcc, 0, v9, vcc
	global_store_dwordx2 v[8:9], v[12:13], off
	global_store_dwordx2 v[8:9], v[6:7], off offset:256
	s_cbranch_scc1 .LBB0_472
	s_add_i32 s27, s27, 1
	s_mov_b64 s[4:5], 0
	s_waitcnt lgkmcnt(0)
	s_barrier
	s_branch .LBB0_426

; __device__ void den_phase(const Ctx& p, const int hd) {
;     ...
;     if (lane == 0) {
;       float den = s;
;       if (c > 0) den += __expf(gA[bh * SEQ + c * 2048 - 1] - gA[bh * SEQ + t]) * qn;
;       rden[row] = 1.f / fmaxf(fabsf(den), gE[bh * SEQ + t]);
;     }
.LBB0_478:
	s_andn2_saveexec_b64 s[12:13], s[12:13]
	s_or_b64 exec, exec, s[12:13]
	v_lshl_add_u64 v[2:3], v[2:3], 2, s[8:9]
	global_load_dword v2, v[2:3], off
	v_max_f32_e64 v3, |v4|, |v4|
	s_waitcnt vmcnt(0) lgkmcnt(0)
	v_max_f32_e32 v2, v2, v2
	v_max_f32_e32 v2, v3, v2
	v_div_scale_f32 v3, s[12:13], v2, v2, 1.0
	v_rcp_f32_e32 v4, v3
	v_div_scale_f32 v5, vcc, 1.0, v2, 1.0
	v_fma_f32 v6, -v3, v4, 1.0
	v_fmac_f32_e32 v4, v6, v4
	v_mul_f32_e32 v6, v5, v4
	v_fma_f32 v7, -v3, v6, v5
	v_fmac_f32_e32 v6, v7, v4
	v_fma_f32 v3, -v3, v6, v5
	v_div_fmas_f32 v3, v3, v4, v6
	v_div_fixup_f32 v4, v3, v2, 1.0
	v_lshl_add_u64 v[2:3], v[52:53], 2, s[10:11]
	global_store_dword v[2:3], v4, off

; __device__ void den_phase(const Ctx& p, const int hd) {
;     ...
;   for (int item = blockIdx.x; item < NTOK / 8; item += gridDim.x) {
;     const int row = item * 8 + w;
;     const int b = row >> 13, t = row & 8191, c = t >> 11, i = t & 2047;
;     const int bh = b * 4 + hd;
;     const int ncol = ((i >> 8) + 1) * 256;
;     const u16* pr = Ph + (((long)b * 4 + c) * 2048 + i) * 2048;
;     uint4 pv[4], qv[4];
; #pragma unroll
;     for (int k = 0; k < 4; ++k) pv[k] = *(const uint4*)(pr + k * 512 + lane * 8);
;     const u16* qr = Qh + (long)row * LDQ;
;     const float* n = nv + (b * 3 + (c > 0 ? c - 1 : 0)) * 2048;
;     float4 n0[4], n1[4];
; #pragma unroll
;     for (int k = 0; k < 4; ++k) {
;       qv[k] = *(const uint4*)(qr + k * 512 + lane * 8);
;       n0[k] = *(const float4*)(n + k * 512 + lane * 8); n1[k] = *(const float4*)(n + k * 512 + lane * 8 + 4);
;     }
.LBB0_480:
	v_ashrrev_i32_e32 v54, 13, v52
	v_ashrrev_i32_e32 v55, 31, v54
	s_waitcnt lgkmcnt(0)
	v_and_b32_e32 v6, 0x7ff, v52
	v_lshlrev_b64 v[4:5], 13, v[54:55]
	v_and_b32_e32 v55, 0x1800, v52
	v_or3_b32 v4, v4, v55, v6
	v_mad_i64_i32 v[2:3], s[0:1], v52, s0, v[46:47]
	v_lshlrev_b64 v[4:5], 12, v[4:5]
	v_and_b32_e32 v65, 0x1fff, v52
	v_lshl_add_u64 v[6:7], v[48:49], 0, v[4:5]
	v_bfe_u32 v4, v52, 11, 2
	s_movk_i32 s0, 0x800
	v_add_u32_e32 v4, -1, v4
	v_cmp_gt_u32_e32 vcc, s0, v65
	v_mul_i32_i24_e32 v5, 3, v54
	global_load_dwordx4 v[66:69], v[2:3], off
	v_cndmask_b32_e64 v4, v4, 0, vcc
	v_add_lshl_u32 v4, v4, v5, 11
	global_load_dwordx4 v[26:29], v[2:3], off offset:1024
	global_load_dwordx4 v[70:73], v[6:7], off
	v_ashrrev_i32_e32 v5, 31, v4
	v_lshl_add_u64 v[8:9], v[4:5], 2, v[50:51]
	global_load_dwordx4 v[74:77], v[8:9], off
	global_load_dwordx4 v[78:81], v[6:7], off offset:1024
	global_load_dwordx4 v[42:45], v[8:9], off offset:2048
	global_load_dwordx4 v[82:85], v[8:9], off offset:16
	global_load_dwordx4 v[38:41], v[8:9], off offset:2064
	global_load_dwordx4 v[18:21], v[2:3], off offset:2048
	s_nop 0
	global_load_dwordx4 v[2:5], v[2:3], off offset:3072
	s_nop 0
	global_load_dwordx4 v[34:37], v[6:7], off offset:2048
	global_load_dwordx4 v[14:17], v[6:7], off offset:3072
	v_add_co_u32_e64 v6, s[0:1], s86, v8
	v_and_b32_e32 v10, 0x700, v52
	s_nop 0
	v_addc_co_u32_e64 v7, s[0:1], 0, v9, s[0:1]
	v_add_u32_e32 v53, 0x100, v10
	global_load_dwordx4 v[30:33], v[6:7], off
	global_load_dwordx4 v[22:25], v[6:7], off offset:16
	global_load_dwordx4 v[10:13], v[6:7], off offset:2048
	s_nop 0
	global_load_dwordx4 v[6:9], v[6:7], off offset:2064
	v_cmp_lt_u32_e64 s[0:1], v62, v53
	s_waitcnt vmcnt(0) lgkmcnt(0)
; __device__ __forceinline__ float bf2f(u16 h) { return __uint_as_float(((unsigned)h) << 16); }
; __device__ void den_phase(const Ctx& p, const int hd) {
;     ...
;     float s = 0.f, qn = 0.f;
; #pragma unroll
;     for (int k = 0; k < 4; ++k) {
;       const uint4 r = pv[k];
;       const float ps = bf2f(r.x & 0xffff) + bf2f(r.x >> 16) + bf2f(r.y & 0xffff) + bf2f(r.y >> 16) +
;                        bf2f(r.z & 0xffff) + bf2f(r.z >> 16) + bf2f(r.w & 0xffff) + bf2f(r.w >> 16);
;       s += (k * 512 + lane * 8 < ncol) ? ps : 0.f;
;       const uint4 q = qv[k];
;       qn += bf2f(q.x & 0xffff) * n0[k].x + bf2f(q.x >> 16) * n0[k].y + bf2f(q.y & 0xffff) * n0[k].z + bf2f(q.y >> 16) * n0[k].w +
;             bf2f(q.z & 0xffff) * n1[k].x + bf2f(q.z >> 16) * n1[k].y + bf2f(q.w & 0xffff) * n1[k].z + bf2f(q.w >> 16) * n1[k].w;
;     }
;     if (c == 0) qn = 0.f;
;     s = wave_sum(s); qn = wave_sum(qn);
;     if (lane == 0) {
;       float den = s;
;       if (c > 0) den += __expf(gA[bh * SEQ + c * 2048 - 1] - gA[bh * SEQ + t]) * qn;
;       rden[row] = 1.f / fmaxf(fabsf(den), gE[bh * SEQ + t]);
	v_lshlrev_b32_e32 v86, 16, v66
	v_and_b32_e32 v66, 0xffff0000, v66
	v_lshlrev_b32_e32 v90, 16, v26
	v_and_b32_e32 v26, 0xffff0000, v26
	v_mul_f32_e32 v26, v43, v26
	v_fmac_f32_e32 v26, v42, v90
	v_lshlrev_b32_e32 v42, 16, v27
	v_fmac_f32_e32 v26, v44, v42
	v_and_b32_e32 v27, 0xffff0000, v27
	v_fmac_f32_e32 v26, v45, v27
	v_lshlrev_b32_e32 v27, 16, v28
	v_fmac_f32_e32 v26, v38, v27
	v_and_b32_e32 v27, 0xffff0000, v28
	v_fmac_f32_e32 v26, v39, v27
	v_lshlrev_b32_e32 v27, 16, v29
	v_fmac_f32_e32 v26, v40, v27
	v_and_b32_e32 v27, 0xffff0000, v29
	v_fmac_f32_e32 v26, v41, v27
	v_lshlrev_b32_e32 v27, 16, v34
	v_and_b32_e32 v28, 0xffff0000, v34
	v_add_f32_e32 v27, v27, v28
	v_lshlrev_b32_e32 v28, 16, v35
	v_add_f32_e32 v27, v27, v28
	v_and_b32_e32 v28, 0xffff0000, v35
	v_add_f32_e32 v27, v27, v28
	v_lshlrev_b32_e32 v28, 16, v36
	v_add_f32_e32 v27, v27, v28
	v_and_b32_e32 v28, 0xffff0000, v36
	v_add_f32_e32 v27, v27, v28
	v_lshlrev_b32_e32 v28, 16, v37
	v_add_f32_e32 v27, v27, v28
	v_and_b32_e32 v28, 0xffff0000, v37
	v_add_f32_e32 v27, v27, v28
	v_lshlrev_b32_e32 v28, 16, v18
	v_and_b32_e32 v18, 0xffff0000, v18
	v_mul_f32_e32 v18, v31, v18
	v_fmac_f32_e32 v18, v30, v28
	v_lshlrev_b32_e32 v28, 16, v19
	v_fmac_f32_e32 v18, v32, v28
	v_and_b32_e32 v19, 0xffff0000, v19
	v_fmac_f32_e32 v18, v33, v19
	v_lshlrev_b32_e32 v19, 16, v20
	v_fmac_f32_e32 v18, v22, v19
	v_and_b32_e32 v19, 0xffff0000, v20
	v_fmac_f32_e32 v18, v23, v19
	v_lshlrev_b32_e32 v19, 16, v21
	v_fmac_f32_e32 v18, v24, v19
	v_and_b32_e32 v19, 0xffff0000, v21
	v_fmac_f32_e32 v18, v25, v19
	v_lshlrev_b32_e32 v19, 16, v14
	v_and_b32_e32 v14, 0xffff0000, v14
	v_add_f32_e32 v14, v19, v14
	v_lshlrev_b32_e32 v19, 16, v15
	v_add_f32_e32 v14, v14, v19
	v_and_b32_e32 v15, 0xffff0000, v15
	v_add_f32_e32 v14, v14, v15
	v_lshlrev_b32_e32 v15, 16, v16
	v_add_f32_e32 v14, v14, v15
	v_and_b32_e32 v15, 0xffff0000, v16
	v_lshlrev_b32_e32 v91, 16, v70
	v_and_b32_e32 v70, 0xffff0000, v70
	v_mul_f32_e32 v66, v75, v66
	v_lshlrev_b32_e32 v75, 16, v78
	v_and_b32_e32 v78, 0xffff0000, v78
	v_add_f32_e32 v14, v14, v15
	v_lshlrev_b32_e32 v15, 16, v17
	v_lshlrev_b32_e32 v87, 16, v67
	v_lshlrev_b32_e32 v92, 16, v71
	v_lshlrev_b32_e32 v95, 16, v79
	v_add_f32_e32 v43, v91, v70
	v_fmac_f32_e32 v66, v74, v86
	v_add_f32_e32 v70, v75, v78
	v_add_f32_e32 v14, v14, v15
	v_and_b32_e32 v15, 0xffff0000, v17
	v_and_b32_e32 v67, 0xffff0000, v67
	v_and_b32_e32 v71, 0xffff0000, v71
	v_and_b32_e32 v79, 0xffff0000, v79
	v_add_f32_e32 v43, v43, v92
	v_fmac_f32_e32 v66, v76, v87
	v_add_f32_e32 v70, v70, v95
	v_add_f32_e32 v14, v14, v15
	v_lshlrev_b32_e32 v15, 16, v2
	v_and_b32_e32 v2, 0xffff0000, v2
	v_lshlrev_b32_e32 v88, 16, v68
	v_lshlrev_b32_e32 v93, 16, v72
	v_lshlrev_b32_e32 v96, 16, v80
	v_add_f32_e32 v43, v43, v71
	v_fmac_f32_e32 v66, v77, v67
	v_add_f32_e32 v67, v70, v79
	v_mul_f32_e32 v2, v11, v2
	v_and_b32_e32 v68, 0xffff0000, v68
	v_and_b32_e32 v72, 0xffff0000, v72
	v_and_b32_e32 v80, 0xffff0000, v80
	v_add_f32_e32 v43, v43, v93
	v_fmac_f32_e32 v66, v82, v88
	v_add_f32_e32 v67, v67, v96
	v_fmac_f32_e32 v2, v10, v15
	v_lshlrev_b32_e32 v10, 16, v3
	v_lshlrev_b32_e32 v89, 16, v69
	v_lshlrev_b32_e32 v94, 16, v73
	v_lshlrev_b32_e32 v97, 16, v81
	v_add_f32_e32 v43, v43, v72
	v_fmac_f32_e32 v66, v83, v68
	v_add_f32_e32 v67, v67, v80
	v_fmac_f32_e32 v2, v12, v10
	v_and_b32_e32 v3, 0xffff0000, v3
	v_and_b32_e32 v69, 0xffff0000, v69
	v_and_b32_e32 v73, 0xffff0000, v73
	v_and_b32_e32 v81, 0xffff0000, v81
	v_add_f32_e32 v43, v43, v94
	v_fmac_f32_e32 v66, v84, v89
	v_add_f32_e32 v67, v67, v97
	v_fmac_f32_e32 v2, v13, v3
	v_lshlrev_b32_e32 v3, 16, v4
	v_add_f32_e32 v43, v43, v73
	v_fmac_f32_e32 v66, v85, v69
	v_add_f32_e32 v67, v67, v81
	v_fmac_f32_e32 v2, v6, v3
	v_and_b32_e32 v3, 0xffff0000, v4
	v_add_f32_e32 v43, 0, v43
	v_add_f32_e32 v66, 0, v66
	v_cndmask_b32_e64 v67, 0, v67, s[0:1]
	v_cmp_lt_u32_e64 s[0:1], v56, v53
	v_fmac_f32_e32 v2, v7, v3
	v_lshlrev_b32_e32 v3, 16, v5
	v_cndmask_b32_e64 v43, 0, v43, s[0:1]
	v_add_f32_e32 v26, v66, v26
	v_cmp_lt_u32_e64 s[0:1], v63, v53
	v_fmac_f32_e32 v2, v8, v3
	v_and_b32_e32 v3, 0xffff0000, v5
	v_add_f32_e32 v43, v43, v67
	v_cndmask_b32_e64 v27, 0, v27, s[0:1]
	v_add_f32_e32 v18, v26, v18
	v_cmp_lt_u32_e64 s[0:1], v64, v53
	v_fmac_f32_e32 v2, v9, v3
	v_add_f32_e32 v27, v43, v27
	v_cndmask_b32_e64 v14, 0, v14, s[0:1]
	v_add_f32_e32 v2, v18, v2
	v_add_f32_e32 v14, v27, v14
	v_cndmask_b32_e64 v2, v2, 0, vcc
	ds_bpermute_b32 v3, v0, v14
	ds_bpermute_b32 v4, v0, v2
	s_movk_i32 s0, 0x7ff
	v_ashrrev_i32_e32 v53, 31, v52
	v_cmp_lt_u32_e32 vcc, s0, v65
	s_waitcnt lgkmcnt(1)
	v_add_f32_e32 v3, v14, v3
	s_waitcnt lgkmcnt(0)
	v_add_f32_e32 v2, v2, v4
	ds_bpermute_b32 v5, v57, v3
	ds_bpermute_b32 v4, v57, v2
	s_waitcnt lgkmcnt(1)
	v_add_f32_e32 v3, v3, v5
	s_waitcnt lgkmcnt(0)
	v_add_f32_e32 v2, v2, v4
	ds_bpermute_b32 v5, v58, v3
	ds_bpermute_b32 v4, v58, v2
	s_waitcnt lgkmcnt(1)
	v_add_f32_e32 v3, v3, v5
	s_waitcnt lgkmcnt(0)
	v_add_f32_e32 v2, v2, v4
	ds_bpermute_b32 v5, v59, v3
	ds_bpermute_b32 v4, v59, v2
	s_waitcnt lgkmcnt(1)
	v_add_f32_e32 v3, v3, v5
	s_waitcnt lgkmcnt(0)
	v_add_f32_e32 v4, v2, v4
	ds_bpermute_b32 v5, v60, v3
	ds_bpermute_b32 v6, v60, v4
	s_waitcnt lgkmcnt(1)
	v_add_f32_e32 v2, v3, v5
	s_waitcnt lgkmcnt(0)
	v_add_f32_e32 v5, v4, v6
	ds_bpermute_b32 v3, v61, v2
	ds_bpermute_b32 v6, v61, v5
	s_and_saveexec_b64 s[0:1], s[4:5]
	s_cbranch_execz .LBB0_479
	v_lshl_add_u32 v7, v54, 15, s20
	s_waitcnt lgkmcnt(1)
	v_add_f32_e32 v4, v2, v3
	v_or_b32_e32 v2, v7, v65
	v_ashrrev_i32_e32 v3, 31, v2
	s_and_saveexec_b64 s[12:13], vcc
	s_xor_b64 s[12:13], exec, s[12:13]
	s_cbranch_execz .LBB0_478
	s_waitcnt lgkmcnt(0)
	v_add_f32_e32 v5, v5, v6
	v_or_b32_e32 v6, v7, v55
	v_ashrrev_i32_e32 v7, 31, v6
	v_lshl_add_u64 v[6:7], v[6:7], 2, s[6:7]
	v_add_co_u32_e32 v6, vcc, -4, v6
	s_nop 1
	v_addc_co_u32_e32 v7, vcc, -1, v7, vcc
	global_load_dword v8, v[6:7], off
	v_lshl_add_u64 v[6:7], v[2:3], 2, s[6:7]
	global_load_dword v6, v[6:7], off
	s_waitcnt vmcnt(0) lgkmcnt(0)
	v_sub_f32_e32 v6, v8, v6
	v_mul_f32_e32 v6, 0x3fb8aa3b, v6
	v_exp_f32_e32 v6, v6
	s_nop 0
	v_fmac_f32_e32 v4, v5, v6
	s_branch .LBB0_478

; #define FOR_ACC                                                                                       \
;   _Pragma("unroll") for (int ai = 0; ai < 2; ++ai) _Pragma("unroll") for (int bj = 0; bj < 2; ++bj)   \
;   _Pragma("unroll") for (int m = 0; m < 4; ++m) _Pragma("unroll") for (int n = 0; n < 2; ++n)
; template <int KIND>
; __device__ void gemm_phase(const Ctx& p, int hd, const int ntiles, const int blk0, const int nblk) {
;     ...
;         if (s > 0) {
;           const int bh = (t >> 6) * 4 + hd;
;           float f = __expf(gA[bh * SEQ + s * 2048 - 1] - gA[bh * SEQ + s * 2048 + 2047]);
;           FOR_ACC acc[ai][bj][m][n] *= f;
;         }
.LBB0_496:
	s_cmp_lt_i32 s0, 1
	s_cbranch_scc1 .LBB0_498
	s_lshr_b32 s1, s28, 4
	s_and_b32 s1, s1, 0x7fffc
	s_add_i32 s1, s1, s16
	s_lshl_b32 s1, s1, 13
	s_lshl_b32 s4, s0, 11
	s_add_i32 s4, s1, s4
	s_ashr_i32 s5, s4, 31
	s_lshl_b64 s[4:5], s[4:5], 2
	s_add_u32 s1, s19, s4
	s_addc_u32 s4, s22, s5
	v_add_co_u32_e64 v2, vcc, -4, s1
	v_mov_b32_e32 v132, s4
	v_mov_b32_e32 v0, s1
	v_addc_co_u32_e32 v3, vcc, -1, v132, vcc
	global_load_dword v133, v[2:3], off
	v_add_co_u32_e32 v2, vcc, s86, v0
	s_nop 1
	v_addc_co_u32_e32 v3, vcc, 0, v132, vcc
	global_load_dword v0, v[2:3], off offset:4092
	s_waitcnt vmcnt(0) lgkmcnt(0)
	v_sub_f32_e32 v0, v133, v0
	v_mul_f32_e32 v0, 0x3fb8aa3b, v0
	v_exp_f32_e32 v0, v0
	s_nop 0
	v_pk_mul_f32 v[130:131], v[130:131], v[0:1] op_sel_hi:[1,0]
	v_pk_mul_f32 v[128:129], v[128:129], v[0:1] op_sel_hi:[1,0]
	v_pk_mul_f32 v[126:127], v[126:127], v[0:1] op_sel_hi:[1,0]
	v_pk_mul_f32 v[124:125], v[124:125], v[0:1] op_sel_hi:[1,0]
	v_pk_mul_f32 v[122:123], v[122:123], v[0:1] op_sel_hi:[1,0]
	v_pk_mul_f32 v[120:121], v[120:121], v[0:1] op_sel_hi:[1,0]
	v_pk_mul_f32 v[118:119], v[118:119], v[0:1] op_sel_hi:[1,0]
	v_pk_mul_f32 v[116:117], v[116:117], v[0:1] op_sel_hi:[1,0]
	v_pk_mul_f32 v[114:115], v[114:115], v[0:1] op_sel_hi:[1,0]
	v_pk_mul_f32 v[112:113], v[112:113], v[0:1] op_sel_hi:[1,0]
	v_pk_mul_f32 v[110:111], v[110:111], v[0:1] op_sel_hi:[1,0]
	v_pk_mul_f32 v[108:109], v[108:109], v[0:1] op_sel_hi:[1,0]
	v_pk_mul_f32 v[106:107], v[106:107], v[0:1] op_sel_hi:[1,0]
	v_pk_mul_f32 v[104:105], v[104:105], v[0:1] op_sel_hi:[1,0]
	v_pk_mul_f32 v[102:103], v[102:103], v[0:1] op_sel_hi:[1,0]
	v_pk_mul_f32 v[100:101], v[100:101], v[0:1] op_sel_hi:[1,0]
	v_pk_mul_f32 v[98:99], v[98:99], v[0:1] op_sel_hi:[1,0]
	v_pk_mul_f32 v[96:97], v[96:97], v[0:1] op_sel_hi:[1,0]
	v_pk_mul_f32 v[94:95], v[94:95], v[0:1] op_sel_hi:[1,0]
	v_pk_mul_f32 v[92:93], v[92:93], v[0:1] op_sel_hi:[1,0]
	v_pk_mul_f32 v[90:91], v[90:91], v[0:1] op_sel_hi:[1,0]
	v_pk_mul_f32 v[88:89], v[88:89], v[0:1] op_sel_hi:[1,0]
	v_pk_mul_f32 v[86:87], v[86:87], v[0:1] op_sel_hi:[1,0]
	v_pk_mul_f32 v[84:85], v[84:85], v[0:1] op_sel_hi:[1,0]
	v_pk_mul_f32 v[82:83], v[82:83], v[0:1] op_sel_hi:[1,0]
	v_pk_mul_f32 v[80:81], v[80:81], v[0:1] op_sel_hi:[1,0]
	v_pk_mul_f32 v[78:79], v[78:79], v[0:1] op_sel_hi:[1,0]
	v_pk_mul_f32 v[76:77], v[76:77], v[0:1] op_sel_hi:[1,0]
	v_pk_mul_f32 v[74:75], v[74:75], v[0:1] op_sel_hi:[1,0]
	v_pk_mul_f32 v[72:73], v[72:73], v[0:1] op_sel_hi:[1,0]
	v_pk_mul_f32 v[70:71], v[70:71], v[0:1] op_sel_hi:[1,0]
	v_pk_mul_f32 v[68:69], v[68:69], v[0:1] op_sel_hi:[1,0]
	v_pk_mul_f32 v[66:67], v[66:67], v[0:1] op_sel_hi:[1,0]
	v_pk_mul_f32 v[64:65], v[64:65], v[0:1] op_sel_hi:[1,0]
	v_pk_mul_f32 v[62:63], v[62:63], v[0:1] op_sel_hi:[1,0]
	v_pk_mul_f32 v[60:61], v[60:61], v[0:1] op_sel_hi:[1,0]
	v_pk_mul_f32 v[58:59], v[58:59], v[0:1] op_sel_hi:[1,0]
	v_pk_mul_f32 v[56:57], v[56:57], v[0:1] op_sel_hi:[1,0]
	v_pk_mul_f32 v[54:55], v[54:55], v[0:1] op_sel_hi:[1,0]
	v_pk_mul_f32 v[52:53], v[52:53], v[0:1] op_sel_hi:[1,0]
	v_pk_mul_f32 v[50:51], v[50:51], v[0:1] op_sel_hi:[1,0]
	v_pk_mul_f32 v[48:49], v[48:49], v[0:1] op_sel_hi:[1,0]
	v_pk_mul_f32 v[46:47], v[46:47], v[0:1] op_sel_hi:[1,0]
	v_pk_mul_f32 v[44:45], v[44:45], v[0:1] op_sel_hi:[1,0]
	v_pk_mul_f32 v[42:43], v[42:43], v[0:1] op_sel_hi:[1,0]
	v_pk_mul_f32 v[40:41], v[40:41], v[0:1] op_sel_hi:[1,0]
	v_pk_mul_f32 v[38:39], v[38:39], v[0:1] op_sel_hi:[1,0]
	v_pk_mul_f32 v[36:37], v[36:37], v[0:1] op_sel_hi:[1,0]
	v_pk_mul_f32 v[34:35], v[34:35], v[0:1] op_sel_hi:[1,0]
	v_pk_mul_f32 v[32:33], v[32:33], v[0:1] op_sel_hi:[1,0]
	v_pk_mul_f32 v[30:31], v[30:31], v[0:1] op_sel_hi:[1,0]
	v_pk_mul_f32 v[28:29], v[28:29], v[0:1] op_sel_hi:[1,0]
	v_pk_mul_f32 v[26:27], v[26:27], v[0:1] op_sel_hi:[1,0]
	v_pk_mul_f32 v[24:25], v[24:25], v[0:1] op_sel_hi:[1,0]
	v_pk_mul_f32 v[22:23], v[22:23], v[0:1] op_sel_hi:[1,0]
	v_pk_mul_f32 v[20:21], v[20:21], v[0:1] op_sel_hi:[1,0]
	v_pk_mul_f32 v[18:19], v[18:19], v[0:1] op_sel_hi:[1,0]
	v_pk_mul_f32 v[16:17], v[16:17], v[0:1] op_sel_hi:[1,0]
	v_pk_mul_f32 v[14:15], v[14:15], v[0:1] op_sel_hi:[1,0]
	v_pk_mul_f32 v[12:13], v[12:13], v[0:1] op_sel_hi:[1,0]
	v_pk_mul_f32 v[10:11], v[10:11], v[0:1] op_sel_hi:[1,0]
	v_pk_mul_f32 v[8:9], v[8:9], v[0:1] op_sel_hi:[1,0]
	v_pk_mul_f32 v[6:7], v[6:7], v[0:1] op_sel_hi:[1,0]
	v_pk_mul_f32 v[4:5], v[4:5], v[0:1] op_sel_hi:[1,0]

; __device__ __forceinline__ int ltid() { int t = threadIdx.x; asm volatile("" : "+v"(t)); return t; }
; template <int AI>
; __device__ __forceinline__ void dump_half(const f32x4 (&acc)[2][2][4][2], float* stage) {
;   const int wid = ltid() >> 6, lane = ltid() & 63, wr = wid >> 2, wc = wid & 3, fr = lane & 15, fq = lane >> 4;
; #pragma unroll
;   for (int bj = 0; bj < 2; ++bj)
; #pragma unroll
;     for (int m = 0; m < 4; ++m)
; #pragma unroll
;       for (int n = 0; n < 2; ++n) {
;         const int r0 = wr * 64 + m * 16 + fq * 4, c = bj * 128 + wc * 32 + n * 16 + fr;
; #pragma unroll
;         for (int j = 0; j < 4; ++j) stage[(r0 + j) * SP + c] = acc[AI][bj][m][n][j];
;       }
; }
; __device__ __forceinline__ void emit_rm(const float* stage, u16* dst, long ld, const float* rs) {
;   const int tid = ltid(), c4 = (tid & 31) * 4, rr = tid >> 5;
; #pragma unroll 1
;   for (int ps = 0; ps < 8; ++ps) {
;     const int r = ps * 16 + rr;
;     const float* s = stage + r * SP + c4;
;     const float4 a = *(const float4*)s, b = *(const float4*)(s + 128);
;     const float f = rs ? rs[r] : 1.f;
;     uint2 o0, o1;
;     o0.x = pack2(a.x * f, a.y * f); o0.y = pack2(a.z * f, a.w * f);
;     o1.x = pack2(b.x * f, b.y * f); o1.y = pack2(b.z * f, b.w * f);
;     *(uint2*)(dst + (long)r * ld + c4) = o0;
;     *(uint2*)(dst + (long)r * ld + 128 + c4) = o1;
;   }
; }
; template <int KIND>
; __device__ void gemm_phase(const Ctx& p, int hd, const int ntiles, const int blk0, const int nblk) {
;     ...
;         dump_half<0>(acc, stage); __syncthreads();
;         tile_emit<KIND>(p, t, hd, s, 0, stage); __syncthreads();
;         dump_half<1>(acc, stage); __syncthreads();
;         tile_emit<KIND>(p, t, hd, s, 1, stage); __syncthreads();
;       }
.LBB0_505:
	ds_read_b128 v[132:135], v0
	ds_read_b128 v[142:145], v0 offset:512
	v_add_u32_e32 v0, 0x4100, v0
	s_waitcnt lgkmcnt(0)
	v_cvt_pk_bf16_f32 v132, v132, v133
	v_cvt_pk_bf16_f32 v133, v134, v135
	s_waitcnt lgkmcnt(0)
	v_cvt_pk_bf16_f32 v134, v142, v143
	v_lshl_add_u64 v[142:143], v[2:3], 0, s[6:7]
	s_add_u32 s6, s6, 0x10000
	v_add_co_u32_e32 v142, vcc, s80, v142
	s_addc_u32 s7, s7, 0
	s_nop 0
	v_addc_co_u32_e32 v143, vcc, 0, v143, vcc
	s_cmp_lg_u32 s6, 0x80000
	v_cvt_pk_bf16_f32 v135, v144, v145
	global_store_dwordx2 v[142:143], v[132:133], off
	global_store_dwordx2 v[142:143], v[134:135], off offset:256
	s_cbranch_scc1 .LBB0_505
	v_mov_b32_e32 v0, v139
	v_mov_b32_e32 v2, v139
	s_waitcnt lgkmcnt(0)
	s_barrier
	s_add_u32 s4, s1, s4
	v_lshrrev_b32_e32 v132, 2, v0
	v_and_b32_e32 v3, 15, v2
	v_and_b32_e32 v132, 0xfffffc0, v132
	v_lshrrev_b32_e32 v2, 2, v2
	v_lshlrev_b32_e32 v0, 1, v0
	v_and_or_b32 v2, v2, 12, v132
	v_and_b32_e32 v0, 0x180, v0
	v_add_u32_e32 v0, 16, v0
	v_lshlrev_b32_e32 v3, 2, v3
	v_mul_lo_u32 v2, v2, s81
	v_add3_u32 v0, v0, v3, v2
	v_add_u32_e32 v141, 0x8000, v0
	v_add_u32_e32 v144, 0xc000, v0
	v_add_u32_e32 v2, 0x400, v0
	v_add_u32_e32 v3, 0x800, v0
	v_add_u32_e32 v132, 0xc00, v0
	v_add_u32_e32 v133, 0x4000, v0
	v_add_u32_e32 v134, 0x4400, v0
	v_add_u32_e32 v135, 0x4800, v0
	v_add_u32_e32 v136, 0x4c00, v0
	ds_write2_b32 v141, v48, v44 offset0:128 offset1:144
	v_add_u32_e32 v141, 0x8400, v0
	v_add_u32_e32 v142, 0x8800, v0
	v_add_u32_e32 v143, 0x8c00, v0
	ds_write2_b32 v144, v40, v36 offset0:192 offset1:208
	v_add_u32_e32 v144, 0xc400, v0
	v_add_u32_e32 v145, 0xc800, v0
	v_add_u32_e32 v146, 0xcc00, v0
	ds_write2_b32 v0, v64, v60 offset1:16
	ds_write2_b32 v2, v65, v61 offset0:4 offset1:20
	ds_write2_b32 v3, v66, v62 offset0:8 offset1:24
	ds_write2_b32 v132, v67, v63 offset0:12 offset1:28
	ds_write2_b32 v133, v56, v52 offset0:64 offset1:80
	ds_write2_b32 v134, v57, v53 offset0:68 offset1:84
	ds_write2_b32 v135, v58, v54 offset0:72 offset1:88
	ds_write2_b32 v136, v59, v55 offset0:76 offset1:92
	ds_write2_b32 v141, v49, v45 offset0:132 offset1:148
	ds_write2_b32 v142, v50, v46 offset0:136 offset1:152
	ds_write2_b32 v143, v51, v47 offset0:140 offset1:156
	ds_write2_b32 v144, v41, v37 offset0:196 offset1:212
	ds_write2_b32 v145, v42, v38 offset0:200 offset1:216
	ds_write2_b32 v146, v43, v39 offset0:204 offset1:220
	ds_write2_b32 v0, v32, v28 offset0:128 offset1:144
	ds_write2_b32 v2, v33, v29 offset0:132 offset1:148
	ds_write2_b32 v3, v34, v30 offset0:136 offset1:152
	ds_write2_b32 v132, v35, v31 offset0:140 offset1:156
	ds_write2_b32 v133, v24, v20 offset0:192 offset1:208
	ds_write2_b32 v134, v25, v21 offset0:196 offset1:212
	ds_write2_b32 v135, v26, v22 offset0:200 offset1:216
	ds_write2_b32 v136, v27, v23 offset0:204 offset1:220
	ds_write2_b32 v141, v16, v12 offset1:16
	ds_write2_b32 v142, v17, v13 offset0:4 offset1:20
	ds_write2_b32 v143, v18, v14 offset0:8 offset1:24
	v_add_u32_e32 v2, 0x9000, v0
	v_add_u32_e32 v0, 0xd000, v0
	ds_write2_b32 v2, v19, v15 offset0:12 offset1:28
	ds_write2_b32 v144, v8, v4 offset0:64 offset1:80
	ds_write2_b32 v145, v9, v5 offset0:68 offset1:84
	ds_write2_b32 v146, v10, v6 offset0:72 offset1:88
	ds_write2_b32 v0, v11, v7 offset0:76 offset1:92
	v_mov_b32_e32 v0, v139
	s_waitcnt lgkmcnt(0)
	s_barrier
	s_addc_u32 s5, 0, s5
	v_ashrrev_i32_e32 v132, 5, v0
	v_ashrrev_i32_e32 v133, 31, v132
	v_lshlrev_b64 v[2:3], 12, v[132:133]
	v_and_b32_e32 v133, 31, v0
	v_lshl_add_u64 v[2:3], s[4:5], 0, v[2:3]
	v_lshlrev_b32_e32 v0, 3, v133
	v_lshl_add_u64 v[2:3], v[2:3], 0, v[0:1]
	v_mul_lo_u32 v0, v132, s81
	v_lshlrev_b32_e32 v132, 4, v133
	v_lshl_add_u64 v[2:3], s[66:67], 0, v[2:3]
	v_add3_u32 v0, v0, v132, 16
	s_mov_b64 s[4:5], 0
.LBB0_507:
	ds_read_b128 v[132:135], v0
	ds_read_b128 v[142:145], v0 offset:512
	v_add_u32_e32 v0, 0x4100, v0
	s_waitcnt lgkmcnt(0)
	v_cvt_pk_bf16_f32 v132, v132, v133
	v_cvt_pk_bf16_f32 v133, v134, v135
	v_cvt_pk_bf16_f32 v134, v142, v143
	v_lshl_add_u64 v[142:143], v[2:3], 0, s[4:5]
	s_add_u32 s4, s4, 0x10000
	v_add_co_u32_e32 v142, vcc, s2, v142
	s_addc_u32 s5, s5, 0
	s_nop 0
	v_addc_co_u32_e32 v143, vcc, 0, v143, vcc
	s_cmp_lg_u32 s4, 0x80000
	v_cvt_pk_bf16_f32 v135, v144, v145
	global_store_dwordx2 v[142:143], v[132:133], off
	global_store_dwordx2 v[142:143], v[134:135], off offset:256
	s_cbranch_scc1 .LBB0_507
	s_add_i32 s1, s0, 1
	s_cmp_gt_i32 s0, 1
	s_mov_b32 s0, s1
	s_waitcnt lgkmcnt(0)
	s_barrier
	s_cbranch_scc0 .LBB0_496
	s_add_i32 s27, s27, 1
	s_mov_b64 s[0:1], 0
	s_branch .LBB0_489

; __device__ __forceinline__ int ltid() { int t = threadIdx.x; asm volatile("" : "+v"(t)); return t; }
; __device__ __forceinline__ void emit_p(const float* stage, u16* dst, const float* aj, const float* Ai, int doff) {
;   const int tid = ltid(), c4 = (tid & 31) * 4, rr = tid >> 5;
;   const float4 a0 = *(const float4*)(aj + c4), a1 = *(const float4*)(aj + 128 + c4);
;   const float av[8] = {a0.x, a0.y, a0.z, a0.w, a1.x, a1.y, a1.z, a1.w};
; #pragma unroll 1
;   for (int ps = 0; ps < 8; ++ps) {
;     const int r = ps * 16 + rr;
;     const float* s = stage + r * SP + c4;
;     const float4 a = *(const float4*)s, b = *(const float4*)(s + 128);
;     float v[8] = {a.x, a.y, a.z, a.w, b.x, b.y, b.z, b.w};
;     const float A = Ai[r];
; #pragma unroll
;     for (int e = 0; e < 8; ++e) {
;       const int c = (e < 4) ? (c4 + e) : (128 + c4 + e - 4);
;       v[e] = (c <= r + doff) ? v[e] * __expf(av[e] - A) : 0.f;
;     }
;     uint2 o0, o1;
;     o0.x = pack2(v[0], v[1]); o0.y = pack2(v[2], v[3]); o1.x = pack2(v[4], v[5]); o1.y = pack2(v[6], v[7]);
;     *(uint2*)(dst + (long)r * 2048 + c4) = o0;
;     *(uint2*)(dst + (long)r * 2048 + 128 + c4) = o1;
;   }
; }
; __device__ __forceinline__ void s_decode(int t, int& tb, int& tc, int& ti, int& tj) {
;   tb = t / 144; int rem = t % 144; tc = rem / 36; int tri = rem % 36;
;   ti = 0; while ((ti + 1) * (ti + 2) / 2 <= tri) ++ti;
;   tj = tri - ti * (ti + 1) / 2;
; }
.LBB0_529:
	s_mov_b32 s8, s6
	s_mov_b32 s52, s7
	s_add_i32 s6, s5, 2
	s_add_i32 s7, s5, 3
	s_mul_i32 s6, s6, s7
	s_mov_b32 s9, s10
	s_lshr_b32 s11, s6, 1
	s_add_i32 s5, s5, 1
	s_add_i32 s6, s8, 1
	s_add_i32 s24, s1, 2
	s_add_i32 s10, s10, s1
	s_add_i32 s7, s52, 0x100
	s_cmp_le_i32 s11, s22
	s_mov_b32 s1, s24
	s_cbranch_scc1 .LBB0_529
	s_add_i32 s1, s5, 1
	s_mul_i32 s1, s1, s5
	s_lshr_b32 s1, s1, 1
	s_sext_i32_i16 s6, s4
	s_sub_i32 s4, s22, s1
	s_lshl_b32 s27, s0, 15
	s_lshl_b32 s30, s4, 8
	s_add_i32 s4, s27, s20
	s_ashr_i32 s1, s0, 31
	s_ashr_i32 s7, s6, 31
	s_ashr_i32 s5, s4, 31
	s_lshl_b64 s[10:11], s[0:1], 13
	s_lshl_b64 s[28:29], s[6:7], 11
	s_ashr_i32 s31, s30, 31
	s_lshl_b64 s[4:5], s[4:5], 2
	s_add_u32 s24, s14, s4
	s_addc_u32 s26, s15, s5
	s_lshl_b32 s4, s6, 11
	s_ashr_i32 s5, s4, 31
	s_lshl_b64 s[4:5], s[4:5], 2
	s_add_u32 s25, s24, s4
	v_mov_b32_e32 v84, v139
	s_addc_u32 s26, s26, s5
	s_lshl_b64 s[30:31], s[30:31], 2
	s_add_u32 s30, s25, s30
	v_lshlrev_b32_e32 v0, 2, v84
	v_and_b32_e32 v82, 0x7c, v0
	s_addc_u32 s31, s26, s31
	v_lshlrev_b32_e32 v0, 2, v82
	v_lshl_add_u64 v[2:3], s[30:31], 0, v[0:1]
	global_load_dwordx4 v[68:71], v[2:3], off
	global_load_dwordx4 v[72:75], v[2:3], off offset:512
	s_lshr_b32 s30, s9, 1
	v_ashrrev_i32_e32 v76, 5, v84
	s_add_i32 s8, s8, s30
	v_lshl_add_u32 v90, s8, 8, v76
	s_add_u32 s8, s10, s28
	s_addc_u32 s9, s11, s29
	s_add_u32 s8, s8, s52
	s_addc_u32 s9, s9, 0
	s_lshl_b32 s24, s22, 8
	s_lshl_b32 s10, s30, 8
	s_sub_i32 s10, s24, s10
	s_ashr_i32 s11, s10, 31
	v_ashrrev_i32_e32 v77, 31, v76
	s_lshl_b64 s[8:9], s[8:9], 12
	s_lshl_b64 s[10:11], s[10:11], 1
	v_lshlrev_b64 v[78:79], 12, v[76:77]
	v_and_b32_e32 v86, 31, v84
	s_add_u32 s8, s10, s8
	v_lshl_or_b32 v78, v86, 3, v78
	s_addc_u32 s9, s11, s9
	v_lshl_add_u64 v[84:85], s[8:9], 0, v[78:79]
	s_add_i32 s8, s17, s27
	s_ashr_i32 s9, s8, 31
	s_lshl_b64 s[8:9], s[8:9], 2
	s_lshl_b64 s[10:11], s[52:53], 2
	s_add_u32 s10, s10, s8
	s_addc_u32 s11, s11, s9
	s_add_u32 s10, s10, s4
	s_addc_u32 s11, s11, s5
	v_mul_lo_u32 v78, v76, s81
	v_lshlrev_b32_e32 v79, 4, v86
	v_lshl_add_u64 v[76:77], v[76:77], 2, s[10:11]
	s_mov_b64 s[10:11], 0x436c0000
	v_or_b32_e32 v3, 3, v82
	v_or_b32_e32 v0, 2, v82
	v_or_b32_e32 v81, 0x81, v82
	v_or_b32_e32 v2, 0x80, v82
	v_or_b32_e32 v83, 0x83, v82
	v_or_b32_e32 v80, 0x82, v82
	v_add3_u32 v91, v78, v79, 16
	v_lshl_add_u64 v[86:87], v[76:77], 0, s[10:11]
	s_mov_b32 s27, 0
	s_mov_b32 s30, 0xc400000
	s_branch .LBB0_532
.LBB0_531:
	s_or_b64 exec, exec, s[10:11]
	s_waitcnt vmcnt(0) lgkmcnt(0)
	v_sub_f32_e32 v95, v69, v93
	v_mul_f32_e32 v95, 0x3fb8aa3b, v95
	v_exp_f32_e32 v95, v95
	v_cmp_lt_i32_e32 vcc, v82, v90
	s_addk_i32 s27, 0x4100
	s_mov_b64 s[10:11], 0x10000
	v_mul_f32_e32 v94, v94, v95
	v_cndmask_b32_e32 v96, 0, v94, vcc
	v_sub_f32_e32 v94, v70, v93
	v_sub_f32_e32 v95, v71, v93
	v_mul_f32_e32 v94, 0x3fb8aa3b, v94
	v_mul_f32_e32 v95, 0x3fb8aa3b, v95
	v_exp_f32_e32 v94, v94
	v_exp_f32_e32 v95, v95
	v_cmp_le_i32_e32 vcc, v0, v90
	v_cvt_pk_bf16_f32 v92, v92, v96
	v_lshl_add_u64 v[86:87], v[86:87], 0, 64
	v_pk_mul_f32 v[88:89], v[88:89], v[94:95]
	v_sub_f32_e32 v94, v72, v93
	v_sub_f32_e32 v95, v73, v93
	v_mul_f32_e32 v94, 0x3fb8aa3b, v94
	v_mul_f32_e32 v95, 0x3fb8aa3b, v95
	v_exp_f32_e32 v94, v94
	v_exp_f32_e32 v95, v95
	v_cvt_pk_bf16_f32 v88, v88, v89
	v_cndmask_b32_e32 v89, 0, v88, vcc
	v_lshrrev_b32_e32 v88, 16, v88
	v_pk_mul_f32 v[76:77], v[76:77], v[94:95]
	v_sub_f32_e32 v94, v74, v93
	v_sub_f32_e32 v93, v75, v93
	v_mul_f32_e32 v94, 0x3fb8aa3b, v94
	v_mul_f32_e32 v93, 0x3fb8aa3b, v93
	v_exp_f32_e32 v94, v94
	v_exp_f32_e32 v95, v93
	v_cmp_le_i32_e32 vcc, v3, v90
	v_cvt_pk_bf16_f32 v76, v76, v77
	s_cmp_lg_u32 s27, 0x20800
	v_cndmask_b32_e32 v88, 0, v88, vcc
	v_cmp_le_i32_e32 vcc, v2, v90
	v_pk_mul_f32 v[78:79], v[78:79], v[94:95]
	v_perm_b32 v93, v88, v89, s59
	v_cndmask_b32_e32 v88, 0, v76, vcc
	v_lshrrev_b32_e32 v76, 16, v76
	v_cmp_le_i32_e32 vcc, v81, v90
	s_nop 1
	v_cndmask_b32_e32 v89, 0, v76, vcc
	v_cvt_pk_bf16_f32 v76, v78, v79
	v_cmp_le_i32_e32 vcc, v80, v90
	s_nop 1
	v_cndmask_b32_e32 v78, 0, v76, vcc
	v_lshrrev_b32_e32 v76, 16, v76
	v_cmp_le_i32_e32 vcc, v83, v90
	v_add_u32_e32 v90, 16, v90
	s_nop 0
	v_cndmask_b32_e32 v79, 0, v76, vcc
	v_lshl_add_u64 v[76:77], s[66:67], 0, v[84:85]
	v_add_co_u32_e32 v76, vcc, s30, v76
	v_perm_b32 v79, v79, v78, s59
	s_nop 0
	v_addc_co_u32_e32 v77, vcc, 0, v77, vcc
	v_perm_b32 v78, v89, v88, s59
	v_lshl_add_u64 v[84:85], v[84:85], 0, s[10:11]
	global_store_dwordx2 v[76:77], v[92:93], off
	global_store_dwordx2 v[76:77], v[78:79], off offset:256
	s_cbranch_scc0 .LBB0_534
.LBB0_532:
	v_lshl_add_u64 v[76:77], s[66:67], 0, v[86:87]
	global_load_dword v93, v[76:77], off
	v_add_u32_e32 v95, s27, v91
	ds_read_b32 v94, v95 offset:4
	ds_read_b64 v[88:89], v95 offset:8
	ds_read_b128 v[76:79], v95 offset:512
	v_cmp_le_i32_e32 vcc, v82, v90
	v_mov_b32_e32 v92, 0
	s_and_saveexec_b64 s[10:11], vcc
	s_cbranch_execz .LBB0_531
	s_waitcnt vmcnt(0) lgkmcnt(0)
	v_sub_f32_e32 v92, v68, v93
	v_mul_f32_e32 v92, 0x3fb8aa3b, v92
	ds_read_b32 v95, v95
	v_exp_f32_e32 v92, v92
	s_waitcnt lgkmcnt(0)
	v_mul_f32_e32 v92, v92, v95
	s_branch .LBB0_531

; __device__ __forceinline__ int ltid() { int t = threadIdx.x; asm volatile("" : "+v"(t)); return t; }
; __device__ __forceinline__ void emit_p(const float* stage, u16* dst, const float* aj, const float* Ai, int doff) {
;   const int tid = ltid(), c4 = (tid & 31) * 4, rr = tid >> 5;
;   const float4 a0 = *(const float4*)(aj + c4), a1 = *(const float4*)(aj + 128 + c4);
;   const float av[8] = {a0.x, a0.y, a0.z, a0.w, a1.x, a1.y, a1.z, a1.w};
; #pragma unroll 1
;   for (int ps = 0; ps < 8; ++ps) {
;     const int r = ps * 16 + rr;
;     const float* s = stage + r * SP + c4;
;     const float4 a = *(const float4*)s, b = *(const float4*)(s + 128);
;     float v[8] = {a.x, a.y, a.z, a.w, b.x, b.y, b.z, b.w};
;     const float A = Ai[r];
; #pragma unroll
;     for (int e = 0; e < 8; ++e) {
;       const int c = (e < 4) ? (c4 + e) : (128 + c4 + e - 4);
;       v[e] = (c <= r + doff) ? v[e] * __expf(av[e] - A) : 0.f;
;     }
;     uint2 o0, o1;
;     o0.x = pack2(v[0], v[1]); o0.y = pack2(v[2], v[3]); o1.x = pack2(v[4], v[5]); o1.y = pack2(v[6], v[7]);
;     *(uint2*)(dst + (long)r * 2048 + c4) = o0;
;     *(uint2*)(dst + (long)r * 2048 + 128 + c4) = o1;
;   }
; }
; __device__ __forceinline__ void s_decode(int t, int& tb, int& tc, int& ti, int& tj) {
;   tb = t / 144; int rem = t % 144; tc = rem / 36; int tri = rem % 36;
;   ti = 0; while ((ti + 1) * (ti + 2) / 2 <= tri) ++ti;
;   tj = tri - ti * (ti + 1) / 2;
; }
.LBB0_535:
	s_mov_b32 s11, s23
	s_mov_b32 s52, s29
	s_add_i32 s23, s28, 2
	s_add_i32 s29, s28, 3
	s_mul_i32 s23, s23, s29
	s_mov_b32 s27, s30
	s_lshr_b32 s31, s23, 1
	s_add_i32 s28, s28, 1
	s_add_i32 s23, s11, 1
	s_add_i32 s34, s10, 2
	s_add_i32 s30, s30, s10
	s_add_i32 s29, s52, 0x100
	s_cmp_le_i32 s31, s22
	s_mov_b32 s10, s34
	s_cbranch_scc1 .LBB0_535
	s_add_i32 s10, s28, 1
	s_mul_i32 s10, s10, s28
	s_lshr_b32 s10, s10, 1
	s_sub_i32 s10, s22, s10
	s_lshl_b32 s22, s10, 8
	s_ashr_i32 s23, s22, 31
	v_mov_b32_e32 v20, v139
	s_lshl_b64 s[22:23], s[22:23], 2
	s_add_u32 s22, s25, s22
	v_lshlrev_b32_e32 v0, 2, v20
	v_and_b32_e32 v18, 0x7c, v0
	s_addc_u32 s23, s26, s23
	v_lshlrev_b32_e32 v0, 2, v18
	v_lshl_add_u64 v[6:7], s[22:23], 0, v[0:1]
	global_load_dwordx4 v[2:5], v[6:7], off
	s_nop 0
	global_load_dwordx4 v[6:9], v[6:7], off offset:512
	s_lshr_b32 s10, s27, 1
	s_add_i32 s11, s11, s10
	s_lshl_b64 s[0:1], s[0:1], 25
	s_lshl_b64 s[6:7], s[6:7], 23
	v_ashrrev_i32_e32 v10, 5, v20
	s_add_u32 s0, s0, s6
	v_lshl_add_u32 v11, s11, 8, v10
	s_addc_u32 s1, s1, s7
	s_lshl_b32 s6, s10, 8
	v_add_u32_e32 v26, 0x80, v11
	v_ashrrev_i32_e32 v11, 31, v10
	s_sub_i32 s6, s24, s6
	v_lshlrev_b64 v[12:13], 12, v[10:11]
	s_ashr_i32 s7, s6, 31
	v_lshl_add_u64 v[12:13], s[0:1], 0, v[12:13]
	s_lshl_b64 s[0:1], s[52:53], 12
	s_lshl_b64 s[6:7], s[6:7], 1
	v_and_b32_e32 v22, 31, v20
	s_add_u32 s0, s6, s0
	v_lshl_or_b32 v12, v22, 3, v12
	s_addc_u32 s1, s7, s1
	v_lshl_add_u64 v[20:21], s[0:1], 0, v[12:13]
	s_lshl_b64 s[0:1], s[52:53], 2
	s_add_u32 s0, s0, s8
	s_addc_u32 s1, s1, s9
	s_add_u32 s0, s0, s4
	s_addc_u32 s1, s1, s5
	v_mul_lo_u32 v12, v10, s81
	v_lshlrev_b32_e32 v13, 4, v22
	v_lshl_add_u64 v[10:11], v[10:11], 2, s[0:1]
	s_mov_b64 s[0:1], 0x436c0200
	v_or_b32_e32 v15, 3, v18
	v_or_b32_e32 v0, 2, v18
	v_or_b32_e32 v17, 0x81, v18
	v_or_b32_e32 v14, 0x80, v18
	v_or_b32_e32 v19, 0x83, v18
	v_or_b32_e32 v16, 0x82, v18
	v_add3_u32 v27, v12, v13, 16
	v_lshl_add_u64 v[22:23], v[10:11], 0, s[0:1]
	s_mov_b32 s4, 0
	s_movk_i32 s52, 0x840
	s_branch .LBB0_538
.LBB0_537:
	s_or_b64 exec, exec, s[0:1]
	s_waitcnt vmcnt(0) lgkmcnt(0)
	v_sub_f32_e32 v31, v3, v29
	v_mul_f32_e32 v31, 0x3fb8aa3b, v31
	v_exp_f32_e32 v31, v31
	v_cmp_lt_i32_e32 vcc, v18, v26
	s_mov_b32 s0, 0xc480000
	s_addk_i32 s4, 0x4100
	v_mul_f32_e32 v30, v30, v31
	v_cndmask_b32_e32 v32, 0, v30, vcc
	v_sub_f32_e32 v30, v4, v29
	v_sub_f32_e32 v31, v5, v29
	v_mul_f32_e32 v30, 0x3fb8aa3b, v30
	v_mul_f32_e32 v31, 0x3fb8aa3b, v31
	v_exp_f32_e32 v30, v30
	v_exp_f32_e32 v31, v31
	v_cmp_le_i32_e32 vcc, v0, v26
	v_cvt_pk_bf16_f32 v28, v28, v32
	v_lshl_add_u64 v[22:23], v[22:23], 0, 64
	v_pk_mul_f32 v[24:25], v[24:25], v[30:31]
	v_sub_f32_e32 v30, v6, v29
	v_sub_f32_e32 v31, v7, v29
	v_mul_f32_e32 v30, 0x3fb8aa3b, v30
	v_mul_f32_e32 v31, 0x3fb8aa3b, v31
	v_exp_f32_e32 v30, v30
	v_exp_f32_e32 v31, v31
	v_cvt_pk_bf16_f32 v24, v24, v25
	v_cndmask_b32_e32 v25, 0, v24, vcc
	v_lshrrev_b32_e32 v24, 16, v24
	v_pk_mul_f32 v[10:11], v[10:11], v[30:31]
	v_sub_f32_e32 v30, v8, v29
	v_sub_f32_e32 v29, v9, v29
	v_mul_f32_e32 v30, 0x3fb8aa3b, v30
	v_mul_f32_e32 v29, 0x3fb8aa3b, v29
	v_exp_f32_e32 v30, v30
	v_exp_f32_e32 v31, v29
	v_cmp_le_i32_e32 vcc, v15, v26
	v_cvt_pk_bf16_f32 v10, v10, v11
	s_cmp_lg_u32 s4, 0x20800
	v_cndmask_b32_e32 v24, 0, v24, vcc
	v_cmp_le_i32_e32 vcc, v14, v26
	v_pk_mul_f32 v[12:13], v[12:13], v[30:31]
	v_perm_b32 v29, v24, v25, s59
	v_cndmask_b32_e32 v24, 0, v10, vcc
	v_lshrrev_b32_e32 v10, 16, v10
	v_cmp_le_i32_e32 vcc, v17, v26
	s_nop 1
	v_cndmask_b32_e32 v25, 0, v10, vcc
	v_cvt_pk_bf16_f32 v10, v12, v13
	v_cmp_le_i32_e32 vcc, v16, v26
	s_nop 1
	v_cndmask_b32_e32 v12, 0, v10, vcc
	v_lshrrev_b32_e32 v10, 16, v10
	v_cmp_le_i32_e32 vcc, v19, v26
	v_add_u32_e32 v26, 16, v26
	s_nop 0
	v_cndmask_b32_e32 v13, 0, v10, vcc
	v_lshl_add_u64 v[10:11], s[66:67], 0, v[20:21]
	v_add_co_u32_e32 v10, vcc, s0, v10
	s_mov_b64 s[0:1], 0x10000
	s_nop 0
	v_addc_co_u32_e32 v11, vcc, 0, v11, vcc
	v_perm_b32 v13, v13, v12, s59
	v_perm_b32 v12, v25, v24, s59
	v_lshl_add_u64 v[20:21], v[20:21], 0, s[0:1]
	global_store_dwordx2 v[10:11], v[28:29], off
	global_store_dwordx2 v[10:11], v[12:13], off offset:256
	s_cbranch_scc0 .LBB0_511
.LBB0_538:
	v_lshl_add_u64 v[10:11], s[66:67], 0, v[22:23]
	global_load_dword v29, v[10:11], off
	v_add_u32_e32 v31, s4, v27
	ds_read_b32 v30, v31 offset:4
	ds_read_b64 v[24:25], v31 offset:8
	ds_read_b128 v[10:13], v31 offset:512
	v_cmp_le_i32_e32 vcc, v18, v26
	v_mov_b32_e32 v28, 0
	s_and_saveexec_b64 s[0:1], vcc
	s_cbranch_execz .LBB0_537
	s_waitcnt vmcnt(0) lgkmcnt(0)
	v_sub_f32_e32 v28, v2, v29
	v_mul_f32_e32 v28, 0x3fb8aa3b, v28
	ds_read_b32 v31, v31
	v_exp_f32_e32 v28, v28
	s_waitcnt lgkmcnt(0)
	v_mul_f32_e32 v28, v28, v31
	s_branch .LBB0_537

; #define FOR_ACC                                                                                       \
;   _Pragma("unroll") for (int ai = 0; ai < 2; ++ai) _Pragma("unroll") for (int bj = 0; bj < 2; ++bj)   \
;   _Pragma("unroll") for (int m = 0; m < 4; ++m) _Pragma("unroll") for (int n = 0; n < 2; ++n)
; template <int KIND>
; __device__ void gemm_phase(const Ctx& p, int hd, const int ntiles, const int blk0, const int nblk) {
;     ...
;         if (s > 0) {
;           const int bh = (t >> 6) * 4 + hd;
;           float f = __expf(gA[bh * SEQ + s * 2048 - 1] - gA[bh * SEQ + s * 2048 + 2047]);
;           FOR_ACC acc[ai][bj][m][n] *= f;
;         }
.LBB0_544:
	s_cmp_lt_i32 s0, 1
	s_cbranch_scc1 .LBB0_546
	s_lshr_b32 s1, s27, 4
	s_and_b32 s1, s1, 0x7fffc
	s_add_i32 s1, s1, s16
	s_lshl_b32 s1, s1, 13
	s_lshl_b32 s4, s0, 11
	s_add_i32 s4, s1, s4
	s_ashr_i32 s5, s4, 31
	s_lshl_b64 s[4:5], s[4:5], 2
	s_add_u32 s1, s19, s4
	s_addc_u32 s4, s22, s5
	v_add_co_u32_e64 v2, vcc, -4, s1
	v_mov_b32_e32 v132, s4
	v_mov_b32_e32 v0, s1
	v_addc_co_u32_e32 v3, vcc, -1, v132, vcc
	global_load_dword v133, v[2:3], off
	v_add_co_u32_e32 v2, vcc, s86, v0
	s_nop 1
	v_addc_co_u32_e32 v3, vcc, 0, v132, vcc
	global_load_dword v0, v[2:3], off offset:4092
	s_waitcnt vmcnt(0) lgkmcnt(0)
	v_sub_f32_e32 v0, v133, v0
	v_mul_f32_e32 v0, 0x3fb8aa3b, v0
	v_exp_f32_e32 v0, v0
	s_nop 0
	v_pk_mul_f32 v[130:131], v[130:131], v[0:1] op_sel_hi:[1,0]
	v_pk_mul_f32 v[128:129], v[128:129], v[0:1] op_sel_hi:[1,0]
	v_pk_mul_f32 v[126:127], v[126:127], v[0:1] op_sel_hi:[1,0]
	v_pk_mul_f32 v[124:125], v[124:125], v[0:1] op_sel_hi:[1,0]
	v_pk_mul_f32 v[122:123], v[122:123], v[0:1] op_sel_hi:[1,0]
	v_pk_mul_f32 v[120:121], v[120:121], v[0:1] op_sel_hi:[1,0]
	v_pk_mul_f32 v[118:119], v[118:119], v[0:1] op_sel_hi:[1,0]
	v_pk_mul_f32 v[116:117], v[116:117], v[0:1] op_sel_hi:[1,0]
	v_pk_mul_f32 v[114:115], v[114:115], v[0:1] op_sel_hi:[1,0]
	v_pk_mul_f32 v[112:113], v[112:113], v[0:1] op_sel_hi:[1,0]
	v_pk_mul_f32 v[110:111], v[110:111], v[0:1] op_sel_hi:[1,0]
	v_pk_mul_f32 v[108:109], v[108:109], v[0:1] op_sel_hi:[1,0]
	v_pk_mul_f32 v[106:107], v[106:107], v[0:1] op_sel_hi:[1,0]
	v_pk_mul_f32 v[104:105], v[104:105], v[0:1] op_sel_hi:[1,0]
	v_pk_mul_f32 v[102:103], v[102:103], v[0:1] op_sel_hi:[1,0]
	v_pk_mul_f32 v[100:101], v[100:101], v[0:1] op_sel_hi:[1,0]
	v_pk_mul_f32 v[98:99], v[98:99], v[0:1] op_sel_hi:[1,0]
	v_pk_mul_f32 v[96:97], v[96:97], v[0:1] op_sel_hi:[1,0]
	v_pk_mul_f32 v[94:95], v[94:95], v[0:1] op_sel_hi:[1,0]
	v_pk_mul_f32 v[92:93], v[92:93], v[0:1] op_sel_hi:[1,0]
	v_pk_mul_f32 v[90:91], v[90:91], v[0:1] op_sel_hi:[1,0]
	v_pk_mul_f32 v[88:89], v[88:89], v[0:1] op_sel_hi:[1,0]
	v_pk_mul_f32 v[86:87], v[86:87], v[0:1] op_sel_hi:[1,0]
	v_pk_mul_f32 v[84:85], v[84:85], v[0:1] op_sel_hi:[1,0]
	v_pk_mul_f32 v[82:83], v[82:83], v[0:1] op_sel_hi:[1,0]
	v_pk_mul_f32 v[80:81], v[80:81], v[0:1] op_sel_hi:[1,0]
	v_pk_mul_f32 v[78:79], v[78:79], v[0:1] op_sel_hi:[1,0]
	v_pk_mul_f32 v[76:77], v[76:77], v[0:1] op_sel_hi:[1,0]
	v_pk_mul_f32 v[74:75], v[74:75], v[0:1] op_sel_hi:[1,0]
	v_pk_mul_f32 v[72:73], v[72:73], v[0:1] op_sel_hi:[1,0]
	v_pk_mul_f32 v[70:71], v[70:71], v[0:1] op_sel_hi:[1,0]
	v_pk_mul_f32 v[68:69], v[68:69], v[0:1] op_sel_hi:[1,0]
	v_pk_mul_f32 v[66:67], v[66:67], v[0:1] op_sel_hi:[1,0]
	v_pk_mul_f32 v[64:65], v[64:65], v[0:1] op_sel_hi:[1,0]
	v_pk_mul_f32 v[62:63], v[62:63], v[0:1] op_sel_hi:[1,0]
	v_pk_mul_f32 v[60:61], v[60:61], v[0:1] op_sel_hi:[1,0]
	v_pk_mul_f32 v[58:59], v[58:59], v[0:1] op_sel_hi:[1,0]
	v_pk_mul_f32 v[56:57], v[56:57], v[0:1] op_sel_hi:[1,0]
	v_pk_mul_f32 v[54:55], v[54:55], v[0:1] op_sel_hi:[1,0]
	v_pk_mul_f32 v[52:53], v[52:53], v[0:1] op_sel_hi:[1,0]
	v_pk_mul_f32 v[50:51], v[50:51], v[0:1] op_sel_hi:[1,0]
	v_pk_mul_f32 v[48:49], v[48:49], v[0:1] op_sel_hi:[1,0]
	v_pk_mul_f32 v[46:47], v[46:47], v[0:1] op_sel_hi:[1,0]
	v_pk_mul_f32 v[44:45], v[44:45], v[0:1] op_sel_hi:[1,0]
	v_pk_mul_f32 v[42:43], v[42:43], v[0:1] op_sel_hi:[1,0]
	v_pk_mul_f32 v[40:41], v[40:41], v[0:1] op_sel_hi:[1,0]
	v_pk_mul_f32 v[38:39], v[38:39], v[0:1] op_sel_hi:[1,0]
	v_pk_mul_f32 v[36:37], v[36:37], v[0:1] op_sel_hi:[1,0]
	v_pk_mul_f32 v[34:35], v[34:35], v[0:1] op_sel_hi:[1,0]
	v_pk_mul_f32 v[32:33], v[32:33], v[0:1] op_sel_hi:[1,0]
	v_pk_mul_f32 v[30:31], v[30:31], v[0:1] op_sel_hi:[1,0]
	v_pk_mul_f32 v[28:29], v[28:29], v[0:1] op_sel_hi:[1,0]
	v_pk_mul_f32 v[26:27], v[26:27], v[0:1] op_sel_hi:[1,0]
	v_pk_mul_f32 v[24:25], v[24:25], v[0:1] op_sel_hi:[1,0]
	v_pk_mul_f32 v[22:23], v[22:23], v[0:1] op_sel_hi:[1,0]
	v_pk_mul_f32 v[20:21], v[20:21], v[0:1] op_sel_hi:[1,0]
	v_pk_mul_f32 v[18:19], v[18:19], v[0:1] op_sel_hi:[1,0]
	v_pk_mul_f32 v[16:17], v[16:17], v[0:1] op_sel_hi:[1,0]
	v_pk_mul_f32 v[14:15], v[14:15], v[0:1] op_sel_hi:[1,0]
	v_pk_mul_f32 v[12:13], v[12:13], v[0:1] op_sel_hi:[1,0]
	v_pk_mul_f32 v[10:11], v[10:11], v[0:1] op_sel_hi:[1,0]
	v_pk_mul_f32 v[8:9], v[8:9], v[0:1] op_sel_hi:[1,0]
	v_pk_mul_f32 v[6:7], v[6:7], v[0:1] op_sel_hi:[1,0]
	v_pk_mul_f32 v[4:5], v[4:5], v[0:1] op_sel_hi:[1,0]

; __device__ __forceinline__ int ltid() { int t = threadIdx.x; asm volatile("" : "+v"(t)); return t; }
; __device__ __forceinline__ void emit_rm(const float* stage, u16* dst, long ld, const float* rs) {
;   const int tid = ltid(), c4 = (tid & 31) * 4, rr = tid >> 5;
; #pragma unroll 1
;   for (int ps = 0; ps < 8; ++ps) {
;     const int r = ps * 16 + rr;
;     const float* s = stage + r * SP + c4;
;     const float4 a = *(const float4*)s, b = *(const float4*)(s + 128);
;     const float f = rs ? rs[r] : 1.f;
;     uint2 o0, o1;
;     o0.x = pack2(a.x * f, a.y * f); o0.y = pack2(a.z * f, a.w * f);
;     o1.x = pack2(b.x * f, b.y * f); o1.y = pack2(b.z * f, b.w * f);
;     *(uint2*)(dst + (long)r * ld + c4) = o0;
;     *(uint2*)(dst + (long)r * ld + 128 + c4) = o1;
;   }
; }
; template <int KIND>
; __device__ void gemm_phase(const Ctx& p, int hd, const int ntiles, const int blk0, const int nblk) {
;     ...
;         dump_half<1>(acc, stage); __syncthreads();
;         tile_emit<KIND>(p, t, hd, s, 1, stage); __syncthreads();
;       }
.LBB0_555:
	ds_read_b128 v[132:135], v0
	ds_read_b128 v[142:145], v0 offset:512
	v_add_u32_e32 v0, 0x4100, v0
	s_waitcnt lgkmcnt(0)
	v_cvt_pk_bf16_f32 v132, v132, v133
	v_cvt_pk_bf16_f32 v133, v134, v135
	v_cvt_pk_bf16_f32 v134, v142, v143
	v_lshl_add_u64 v[142:143], v[2:3], 0, s[4:5]
	s_add_u32 s4, s4, 0x10000
	v_add_co_u32_e32 v142, vcc, s2, v142
	s_addc_u32 s5, s5, 0
	s_nop 0
	v_addc_co_u32_e32 v143, vcc, 0, v143, vcc
	s_cmp_lg_u32 s4, 0x80000
	v_cvt_pk_bf16_f32 v135, v144, v145
	global_store_dwordx2 v[142:143], v[132:133], off
	global_store_dwordx2 v[142:143], v[134:135], off offset:256
	s_cbranch_scc1 .LBB0_555
	s_add_i32 s1, s0, 1
	s_cmp_lt_i32 s0, 2
	s_mov_b32 s0, s1
	s_waitcnt lgkmcnt(0)
	s_barrier
	s_cbranch_scc1 .LBB0_544

; __device__ __forceinline__ int ltid() { int t = threadIdx.x; asm volatile("" : "+v"(t)); return t; }
; __device__ __forceinline__ void emit_p(const float* stage, u16* dst, const float* aj, const float* Ai, int doff) {
;   const int tid = ltid(), c4 = (tid & 31) * 4, rr = tid >> 5;
;   const float4 a0 = *(const float4*)(aj + c4), a1 = *(const float4*)(aj + 128 + c4);
;   const float av[8] = {a0.x, a0.y, a0.z, a0.w, a1.x, a1.y, a1.z, a1.w};
; #pragma unroll 1
;   for (int ps = 0; ps < 8; ++ps) {
;     const int r = ps * 16 + rr;
;     const float* s = stage + r * SP + c4;
;     const float4 a = *(const float4*)s, b = *(const float4*)(s + 128);
;     float v[8] = {a.x, a.y, a.z, a.w, b.x, b.y, b.z, b.w};
;     const float A = Ai[r];
; #pragma unroll
;     for (int e = 0; e < 8; ++e) {
;       const int c = (e < 4) ? (c4 + e) : (128 + c4 + e - 4);
;       v[e] = (c <= r + doff) ? v[e] * __expf(av[e] - A) : 0.f;
;     }
;     uint2 o0, o1;
;     o0.x = pack2(v[0], v[1]); o0.y = pack2(v[2], v[3]); o1.x = pack2(v[4], v[5]); o1.y = pack2(v[6], v[7]);
;     *(uint2*)(dst + (long)r * 2048 + c4) = o0;
;     *(uint2*)(dst + (long)r * 2048 + 128 + c4) = o1;
;   }
; }
; __device__ __forceinline__ void s_decode(int t, int& tb, int& tc, int& ti, int& tj) {
;   tb = t / 144; int rem = t % 144; tc = rem / 36; int tri = rem % 36;
;   ti = 0; while ((ti + 1) * (ti + 2) / 2 <= tri) ++ti;
;   tj = tri - ti * (ti + 1) / 2;
; }
.LBB0_577:
	s_mov_b32 s8, s6
	s_mov_b32 s52, s7
	s_add_i32 s6, s5, 2
	s_add_i32 s7, s5, 3
	s_mul_i32 s6, s6, s7
	s_mov_b32 s9, s10
	s_lshr_b32 s11, s6, 1
	s_add_i32 s5, s5, 1
	s_add_i32 s6, s8, 1
	s_add_i32 s22, s1, 2
	s_add_i32 s10, s10, s1
	s_add_i32 s7, s52, 0x100
	s_cmp_le_i32 s11, s18
	s_mov_b32 s1, s22
	s_cbranch_scc1 .LBB0_577
	s_add_i32 s1, s5, 1
	s_mul_i32 s1, s1, s5
	s_lshr_b32 s1, s1, 1
	s_sext_i32_i16 s6, s4
	s_sub_i32 s4, s18, s1
	s_lshl_b32 s25, s0, 15
	s_lshl_b32 s28, s4, 8
	s_add_i32 s4, s25, s20
	s_ashr_i32 s1, s0, 31
	s_ashr_i32 s7, s6, 31
	s_ashr_i32 s5, s4, 31
	s_lshl_b64 s[10:11], s[0:1], 13
	s_lshl_b64 s[26:27], s[6:7], 11
	s_ashr_i32 s29, s28, 31
	s_lshl_b64 s[4:5], s[4:5], 2
	s_add_u32 s22, s14, s4
	s_addc_u32 s24, s15, s5
	s_lshl_b32 s4, s6, 11
	s_ashr_i32 s5, s4, 31
	s_lshl_b64 s[4:5], s[4:5], 2
	s_add_u32 s23, s22, s4
	v_mov_b32_e32 v84, v139
	s_addc_u32 s24, s24, s5
	s_lshl_b64 s[28:29], s[28:29], 2
	s_add_u32 s28, s23, s28
	v_lshlrev_b32_e32 v0, 2, v84
	v_and_b32_e32 v82, 0x7c, v0
	s_addc_u32 s29, s24, s29
	v_lshlrev_b32_e32 v0, 2, v82
	v_lshl_add_u64 v[2:3], s[28:29], 0, v[0:1]
	global_load_dwordx4 v[68:71], v[2:3], off
	global_load_dwordx4 v[72:75], v[2:3], off offset:512
	s_lshr_b32 s28, s9, 1
	v_ashrrev_i32_e32 v76, 5, v84
	s_add_i32 s8, s8, s28
	v_lshl_add_u32 v90, s8, 8, v76
	s_add_u32 s8, s10, s26
	s_addc_u32 s9, s11, s27
	s_add_u32 s8, s8, s52
	s_addc_u32 s9, s9, 0
	s_lshl_b32 s22, s18, 8
	s_lshl_b32 s10, s28, 8
	s_sub_i32 s10, s22, s10
	s_ashr_i32 s11, s10, 31
	v_ashrrev_i32_e32 v77, 31, v76
	s_lshl_b64 s[8:9], s[8:9], 12
	s_lshl_b64 s[10:11], s[10:11], 1
	v_lshlrev_b64 v[78:79], 12, v[76:77]
	v_and_b32_e32 v86, 31, v84
	s_add_u32 s8, s10, s8
	v_lshl_or_b32 v78, v86, 3, v78
	s_addc_u32 s9, s11, s9
	v_lshl_add_u64 v[84:85], s[8:9], 0, v[78:79]
	s_add_i32 s8, s17, s25
	s_ashr_i32 s9, s8, 31
	s_lshl_b64 s[8:9], s[8:9], 2
	s_lshl_b64 s[10:11], s[52:53], 2
	s_add_u32 s10, s10, s8
	s_addc_u32 s11, s11, s9
	s_add_u32 s10, s10, s4
	s_addc_u32 s11, s11, s5
	v_mul_lo_u32 v78, v76, s81
	v_lshlrev_b32_e32 v79, 4, v86
	v_lshl_add_u64 v[76:77], v[76:77], 2, s[10:11]
	s_mov_b64 s[10:11], 0x436c0000
	v_or_b32_e32 v3, 3, v82
	v_or_b32_e32 v0, 2, v82
	v_or_b32_e32 v81, 0x81, v82
	v_or_b32_e32 v2, 0x80, v82
	v_or_b32_e32 v83, 0x83, v82
	v_or_b32_e32 v80, 0x82, v82
	v_add3_u32 v91, v78, v79, 16
	v_lshl_add_u64 v[86:87], v[76:77], 0, s[10:11]
	s_mov_b32 s25, 0
	s_mov_b32 s28, 0xc400000
	s_branch .LBB0_580
.LBB0_579:
	s_or_b64 exec, exec, s[10:11]
	s_waitcnt vmcnt(0) lgkmcnt(0)
	v_sub_f32_e32 v95, v69, v93
	v_mul_f32_e32 v95, 0x3fb8aa3b, v95
	v_exp_f32_e32 v95, v95
	v_cmp_lt_i32_e32 vcc, v82, v90
	s_addk_i32 s25, 0x4100
	s_mov_b64 s[10:11], 0x10000
	v_mul_f32_e32 v94, v94, v95
	v_cndmask_b32_e32 v96, 0, v94, vcc
	v_sub_f32_e32 v94, v70, v93
	v_sub_f32_e32 v95, v71, v93
	v_mul_f32_e32 v94, 0x3fb8aa3b, v94
	v_mul_f32_e32 v95, 0x3fb8aa3b, v95
	v_exp_f32_e32 v94, v94
	v_exp_f32_e32 v95, v95
	v_cmp_le_i32_e32 vcc, v0, v90
	v_cvt_pk_bf16_f32 v92, v92, v96
	v_lshl_add_u64 v[86:87], v[86:87], 0, 64
	v_pk_mul_f32 v[88:89], v[88:89], v[94:95]
	v_sub_f32_e32 v94, v72, v93
	v_sub_f32_e32 v95, v73, v93
	v_mul_f32_e32 v94, 0x3fb8aa3b, v94
	v_mul_f32_e32 v95, 0x3fb8aa3b, v95
	v_exp_f32_e32 v94, v94
	v_exp_f32_e32 v95, v95
	v_cvt_pk_bf16_f32 v88, v88, v89
	v_cndmask_b32_e32 v89, 0, v88, vcc
	v_lshrrev_b32_e32 v88, 16, v88
	v_pk_mul_f32 v[76:77], v[76:77], v[94:95]
	v_sub_f32_e32 v94, v74, v93
	v_sub_f32_e32 v93, v75, v93
	v_mul_f32_e32 v94, 0x3fb8aa3b, v94
	v_mul_f32_e32 v93, 0x3fb8aa3b, v93
	v_exp_f32_e32 v94, v94
	v_exp_f32_e32 v95, v93
	v_cmp_le_i32_e32 vcc, v3, v90
	v_cvt_pk_bf16_f32 v76, v76, v77
	s_cmp_lg_u32 s25, 0x20800
	v_cndmask_b32_e32 v88, 0, v88, vcc
	v_cmp_le_i32_e32 vcc, v2, v90
	v_pk_mul_f32 v[78:79], v[78:79], v[94:95]
	v_perm_b32 v93, v88, v89, s59
	v_cndmask_b32_e32 v88, 0, v76, vcc
	v_lshrrev_b32_e32 v76, 16, v76
	v_cmp_le_i32_e32 vcc, v81, v90
	s_nop 1
	v_cndmask_b32_e32 v89, 0, v76, vcc
	v_cvt_pk_bf16_f32 v76, v78, v79
	v_cmp_le_i32_e32 vcc, v80, v90
	s_nop 1
	v_cndmask_b32_e32 v78, 0, v76, vcc
	v_lshrrev_b32_e32 v76, 16, v76
	v_cmp_le_i32_e32 vcc, v83, v90
	v_add_u32_e32 v90, 16, v90
	s_nop 0
	v_cndmask_b32_e32 v79, 0, v76, vcc
	v_lshl_add_u64 v[76:77], s[66:67], 0, v[84:85]
	v_add_co_u32_e32 v76, vcc, s28, v76
	v_perm_b32 v79, v79, v78, s59
	s_nop 0
	v_addc_co_u32_e32 v77, vcc, 0, v77, vcc
	v_perm_b32 v78, v89, v88, s59
	v_lshl_add_u64 v[84:85], v[84:85], 0, s[10:11]
	global_store_dwordx2 v[76:77], v[92:93], off
	global_store_dwordx2 v[76:77], v[78:79], off offset:256
	s_cbranch_scc0 .LBB0_582
.LBB0_580:
	v_lshl_add_u64 v[76:77], s[66:67], 0, v[86:87]
	global_load_dword v93, v[76:77], off
	v_add_u32_e32 v95, s25, v91
	ds_read_b32 v94, v95 offset:4
	ds_read_b64 v[88:89], v95 offset:8
	ds_read_b128 v[76:79], v95 offset:512
	v_cmp_le_i32_e32 vcc, v82, v90
	v_mov_b32_e32 v92, 0
	s_and_saveexec_b64 s[10:11], vcc
	s_cbranch_execz .LBB0_579
	s_waitcnt vmcnt(0) lgkmcnt(0)
	v_sub_f32_e32 v92, v68, v93
	v_mul_f32_e32 v92, 0x3fb8aa3b, v92
	ds_read_b32 v95, v95
	v_exp_f32_e32 v92, v92
	s_waitcnt lgkmcnt(0)
	v_mul_f32_e32 v92, v92, v95
	s_branch .LBB0_579

; __device__ __forceinline__ int ltid() { int t = threadIdx.x; asm volatile("" : "+v"(t)); return t; }
; __device__ __forceinline__ void emit_p(const float* stage, u16* dst, const float* aj, const float* Ai, int doff) {
;   const int tid = ltid(), c4 = (tid & 31) * 4, rr = tid >> 5;
;   const float4 a0 = *(const float4*)(aj + c4), a1 = *(const float4*)(aj + 128 + c4);
;   const float av[8] = {a0.x, a0.y, a0.z, a0.w, a1.x, a1.y, a1.z, a1.w};
; #pragma unroll 1
;   for (int ps = 0; ps < 8; ++ps) {
;     const int r = ps * 16 + rr;
;     const float* s = stage + r * SP + c4;
;     const float4 a = *(const float4*)s, b = *(const float4*)(s + 128);
; __device__ __forceinline__ void s_decode(int t, int& tb, int& tc, int& ti, int& tj) {
;   tb = t / 144; int rem = t % 144; tc = rem / 36; int tri = rem % 36;
;   ti = 0; while ((ti + 1) * (ti + 2) / 2 <= tri) ++ti;
;   tj = tri - ti * (ti + 1) / 2;
; }
.LBB0_583:
	s_mov_b32 s11, s19
	s_mov_b32 s52, s27
	s_add_i32 s19, s26, 2
	s_add_i32 s27, s26, 3
	s_mul_i32 s19, s19, s27
	s_mov_b32 s25, s28
	s_lshr_b32 s29, s19, 1
	s_add_i32 s26, s26, 1
	s_add_i32 s19, s11, 1
	s_add_i32 s30, s10, 2
	s_add_i32 s28, s28, s10
	s_add_i32 s27, s52, 0x100
	s_cmp_le_i32 s29, s18
	s_mov_b32 s10, s30
	s_cbranch_scc1 .LBB0_583
	s_add_i32 s10, s26, 1
	s_mul_i32 s10, s10, s26
	s_lshr_b32 s10, s10, 1
	s_sub_i32 s10, s18, s10
	s_lshl_b32 s18, s10, 8
	s_ashr_i32 s19, s18, 31
	v_mov_b32_e32 v20, v139
	s_lshl_b64 s[18:19], s[18:19], 2
	s_add_u32 s18, s23, s18
	v_lshlrev_b32_e32 v0, 2, v20
	v_and_b32_e32 v18, 0x7c, v0
	s_addc_u32 s19, s24, s19
	v_lshlrev_b32_e32 v0, 2, v18
	v_lshl_add_u64 v[6:7], s[18:19], 0, v[0:1]
	global_load_dwordx4 v[2:5], v[6:7], off
	s_nop 0
	global_load_dwordx4 v[6:9], v[6:7], off offset:512
	s_lshr_b32 s10, s25, 1
	s_add_i32 s11, s11, s10
	s_lshl_b64 s[0:1], s[0:1], 25
	s_lshl_b64 s[6:7], s[6:7], 23
	v_ashrrev_i32_e32 v10, 5, v20
	s_add_u32 s0, s0, s6
	v_lshl_add_u32 v11, s11, 8, v10
	s_addc_u32 s1, s1, s7
	s_lshl_b32 s6, s10, 8
	v_add_u32_e32 v26, 0x80, v11
	v_ashrrev_i32_e32 v11, 31, v10
	s_sub_i32 s6, s22, s6
	v_lshlrev_b64 v[12:13], 12, v[10:11]
	s_ashr_i32 s7, s6, 31
	v_lshl_add_u64 v[12:13], s[0:1], 0, v[12:13]
	s_lshl_b64 s[0:1], s[52:53], 12
	s_lshl_b64 s[6:7], s[6:7], 1
	v_and_b32_e32 v22, 31, v20
	s_add_u32 s0, s6, s0
	v_lshl_or_b32 v12, v22, 3, v12
	s_addc_u32 s1, s7, s1
	v_lshl_add_u64 v[20:21], s[0:1], 0, v[12:13]
	s_lshl_b64 s[0:1], s[52:53], 2
	s_add_u32 s0, s0, s8
	s_addc_u32 s1, s1, s9
	s_add_u32 s0, s0, s4
	s_addc_u32 s1, s1, s5
	v_mul_lo_u32 v12, v10, s81
	v_lshlrev_b32_e32 v13, 4, v22
	v_lshl_add_u64 v[10:11], v[10:11], 2, s[0:1]
	s_mov_b64 s[0:1], 0x436c0200
	v_or_b32_e32 v15, 3, v18
	v_or_b32_e32 v0, 2, v18
	v_or_b32_e32 v17, 0x81, v18
	v_or_b32_e32 v14, 0x80, v18
	v_or_b32_e32 v19, 0x83, v18
	v_or_b32_e32 v16, 0x82, v18
	v_add3_u32 v27, v12, v13, 16
	v_lshl_add_u64 v[22:23], v[10:11], 0, s[0:1]
	s_mov_b32 s4, 0
	s_movk_i32 s52, 0x840
	s_branch .LBB0_586

; __device__ __forceinline__ float bf2f(u16 h) { return __uint_as_float(((unsigned)h) << 16); }
; __device__ void nvec_items(const Ctx& p, const int hd) {
;     ...
;   for (int item = blockIdx.x; item < 2 * 256; item += gridDim.x) {
;     const int b = item >> 8, d = (item & 255) * 8 + w;
;     const int bh = b * 4 + hd;
;     float st = 0.f;
;     for (int c = 0; c < 3; ++c) {
;       float s = 0.f;
;       for (int k = 0; k < 4; ++k) {
;         uint4 r = *(const uint4*)(KTh + ((long)b * 2048 + d) * SEQ + c * 2048 + k * 512 + lane * 8);
;         s += bf2f(r.x & 0xffff) + bf2f(r.x >> 16) + bf2f(r.y & 0xffff) + bf2f(r.y >> 16) +
;              bf2f(r.z & 0xffff) + bf2f(r.z >> 16) + bf2f(r.w & 0xffff) + bf2f(r.w >> 16);
;       }
;       s = wave_sum(s);
;       if (c > 0) st *= __expf(gA[bh * SEQ + c * 2048 - 1] - gA[bh * SEQ + c * 2048 + 2047]);
;       st += s;
;       if (lane == 0) nv[(b * 3 + c) * 2048 + d] = st;
;     }
.LBB0_591:
	s_ashr_i32 s6, s15, 8
	s_and_b32 s7, s14, 0x7f8
	v_add_u32_e32 v2, s7, v6
	s_ashr_i32 s7, s6, 31
	s_lshl_b64 s[8:9], s[6:7], 25
	v_ashrrev_i32_e32 v3, 31, v2
	s_add_u32 s8, s10, s8
	s_addc_u32 s9, s11, s9
	s_waitcnt lgkmcnt(0)
	v_lshlrev_b64 v[4:5], 14, v[2:3]
	v_lshl_add_u64 v[4:5], s[8:9], 0, v[4:5]
	v_lshl_add_u64 v[4:5], v[4:5], 0, v[0:1]
	global_load_dwordx4 v[14:17], v[4:5], off
	s_mul_i32 s16, s6, 0x1800
	s_waitcnt vmcnt(0) lgkmcnt(0)
	v_lshlrev_b32_e32 v3, 16, v14
	v_and_b32_e32 v13, 0xffff0000, v14
	v_add_f32_e32 v3, v3, v13
	v_lshlrev_b32_e32 v13, 16, v15
	v_add_f32_e32 v3, v3, v13
	v_and_b32_e32 v13, 0xffff0000, v15
	v_add_f32_e32 v3, v3, v13
	v_lshlrev_b32_e32 v13, 16, v16
	v_add_f32_e32 v3, v3, v13
	v_and_b32_e32 v13, 0xffff0000, v16
	v_add_f32_e32 v3, v3, v13
	v_lshlrev_b32_e32 v13, 16, v17
	v_add_f32_e32 v3, v3, v13
	v_and_b32_e32 v13, 0xffff0000, v17
	global_load_dwordx4 v[14:17], v[4:5], off offset:1024
	v_add_f32_e32 v3, v3, v13
	v_add_f32_e32 v3, 0, v3
	s_waitcnt vmcnt(0) lgkmcnt(0)
	v_lshlrev_b32_e32 v13, 16, v14
	v_and_b32_e32 v14, 0xffff0000, v14
	v_add_f32_e32 v13, v13, v14
	v_lshlrev_b32_e32 v14, 16, v15
	v_add_f32_e32 v13, v13, v14
	v_and_b32_e32 v14, 0xffff0000, v15
	v_add_f32_e32 v13, v13, v14
	v_lshlrev_b32_e32 v14, 16, v16
	v_add_f32_e32 v13, v13, v14
	v_and_b32_e32 v14, 0xffff0000, v16
	v_add_f32_e32 v13, v13, v14
	v_lshlrev_b32_e32 v14, 16, v17
	v_add_f32_e32 v13, v13, v14
	v_and_b32_e32 v14, 0xffff0000, v17
	v_add_f32_e32 v13, v13, v14
	global_load_dwordx4 v[14:17], v[4:5], off offset:2048
	v_add_f32_e32 v3, v3, v13
	s_waitcnt vmcnt(0) lgkmcnt(0)
	v_lshlrev_b32_e32 v13, 16, v14
	v_and_b32_e32 v14, 0xffff0000, v14
	v_add_f32_e32 v13, v13, v14
	v_lshlrev_b32_e32 v14, 16, v15
	v_add_f32_e32 v13, v13, v14
	v_and_b32_e32 v14, 0xffff0000, v15
	v_add_f32_e32 v13, v13, v14
	v_lshlrev_b32_e32 v14, 16, v16
	v_add_f32_e32 v13, v13, v14
	v_and_b32_e32 v14, 0xffff0000, v16
	v_add_f32_e32 v13, v13, v14
	v_lshlrev_b32_e32 v14, 16, v17
	v_add_f32_e32 v13, v13, v14
	v_and_b32_e32 v14, 0xffff0000, v17
	v_add_f32_e32 v13, v13, v14
	global_load_dwordx4 v[14:17], v[4:5], off offset:3072
	v_add_f32_e32 v3, v3, v13
	s_waitcnt vmcnt(0) lgkmcnt(0)
	v_lshlrev_b32_e32 v13, 16, v14
	v_and_b32_e32 v14, 0xffff0000, v14
	v_add_f32_e32 v13, v13, v14
	v_lshlrev_b32_e32 v14, 16, v15
	v_add_f32_e32 v13, v13, v14
	v_and_b32_e32 v14, 0xffff0000, v15
	v_add_f32_e32 v13, v13, v14
	v_lshlrev_b32_e32 v14, 16, v16
	v_add_f32_e32 v13, v13, v14
	v_and_b32_e32 v14, 0xffff0000, v16
	v_add_f32_e32 v13, v13, v14
	v_lshlrev_b32_e32 v14, 16, v17
	v_add_f32_e32 v13, v13, v14
	v_and_b32_e32 v14, 0xffff0000, v17
	v_add_f32_e32 v13, v13, v14
	v_add_f32_e32 v3, v3, v13
	ds_bpermute_b32 v13, v7, v3
	s_waitcnt lgkmcnt(0)
	v_add_f32_e32 v3, v3, v13
	ds_bpermute_b32 v13, v8, v3
	s_waitcnt lgkmcnt(0)
	v_add_f32_e32 v3, v3, v13
	ds_bpermute_b32 v13, v9, v3
	s_waitcnt lgkmcnt(0)
	v_add_f32_e32 v3, v3, v13
	ds_bpermute_b32 v13, v10, v3
	s_waitcnt lgkmcnt(0)
	v_add_f32_e32 v3, v3, v13
	ds_bpermute_b32 v13, v11, v3
	s_waitcnt lgkmcnt(0)
	v_add_f32_e32 v3, v3, v13
	ds_bpermute_b32 v13, v12, v3
	s_waitcnt lgkmcnt(0)
	v_add_f32_e32 v3, v3, v13
	v_add_f32_e32 v13, 0, v3
	s_and_saveexec_b64 s[8:9], s[4:5]
	s_cbranch_execz .LBB0_593
	v_add_u32_e32 v14, s16, v2
	v_ashrrev_i32_e32 v15, 31, v14
	v_lshl_add_u64 v[14:15], v[14:15], 2, s[0:1]
	global_store_dword v[14:15], v13, off
.LBB0_593:
	s_or_b64 exec, exec, s[8:9]
	v_add_co_u32_e32 v18, vcc, 0x1000, v4
	s_lshl_b32 s6, s6, 15
	s_nop 0
	v_addc_co_u32_e32 v19, vcc, 0, v5, vcc
	global_load_dwordx4 v[14:17], v[18:19], off
	s_add_i32 s6, s6, s20
	s_ashr_i32 s7, s6, 31
	s_lshl_b64 s[6:7], s[6:7], 2
	s_add_u32 s18, s12, s6
	s_addc_u32 s17, s13, s7
	s_add_u32 s6, s18, 0x3ffc
	s_addc_u32 s7, s17, 0
	s_waitcnt vmcnt(0) lgkmcnt(0)
	v_lshlrev_b32_e32 v3, 16, v14
	v_and_b32_e32 v14, 0xffff0000, v14
	v_add_f32_e32 v3, v3, v14
	v_lshlrev_b32_e32 v14, 16, v15
	v_add_f32_e32 v3, v3, v14
	v_and_b32_e32 v14, 0xffff0000, v15
	v_add_f32_e32 v3, v3, v14
	v_lshlrev_b32_e32 v14, 16, v16
	v_add_f32_e32 v3, v3, v14
	v_and_b32_e32 v14, 0xffff0000, v16
	v_add_f32_e32 v3, v3, v14
	v_lshlrev_b32_e32 v14, 16, v17
	v_add_f32_e32 v3, v3, v14
	v_and_b32_e32 v14, 0xffff0000, v17
	v_add_f32_e32 v3, v3, v14
	global_load_dwordx4 v[14:17], v[18:19], off offset:1024
	v_add_f32_e32 v3, 0, v3
	s_waitcnt vmcnt(0) lgkmcnt(0)
	v_lshlrev_b32_e32 v20, 16, v14
	v_and_b32_e32 v14, 0xffff0000, v14
	v_add_f32_e32 v14, v20, v14
	v_lshlrev_b32_e32 v20, 16, v15
	v_add_f32_e32 v14, v14, v20
	v_and_b32_e32 v15, 0xffff0000, v15
	v_add_f32_e32 v14, v14, v15
	v_lshlrev_b32_e32 v15, 16, v16
	v_add_f32_e32 v14, v14, v15
	v_and_b32_e32 v15, 0xffff0000, v16
	v_add_f32_e32 v14, v14, v15
	v_lshlrev_b32_e32 v15, 16, v17
	v_add_f32_e32 v14, v14, v15
	v_and_b32_e32 v15, 0xffff0000, v17
	v_add_f32_e32 v14, v14, v15
	v_add_f32_e32 v3, v3, v14
	global_load_dwordx4 v[14:17], v[18:19], off offset:2048
	s_waitcnt vmcnt(0) lgkmcnt(0)
	v_lshlrev_b32_e32 v20, 16, v14
	v_and_b32_e32 v14, 0xffff0000, v14
	v_add_f32_e32 v14, v20, v14
	v_lshlrev_b32_e32 v20, 16, v15
	v_add_f32_e32 v14, v14, v20
	v_and_b32_e32 v15, 0xffff0000, v15
	v_add_f32_e32 v14, v14, v15
	v_lshlrev_b32_e32 v15, 16, v16
	v_add_f32_e32 v14, v14, v15
	v_and_b32_e32 v15, 0xffff0000, v16
	v_add_f32_e32 v14, v14, v15
	v_lshlrev_b32_e32 v15, 16, v17
	v_add_f32_e32 v14, v14, v15
	v_and_b32_e32 v15, 0xffff0000, v17
	v_add_f32_e32 v14, v14, v15
	v_add_f32_e32 v3, v3, v14
	global_load_dwordx4 v[14:17], v[18:19], off offset:3072
	s_waitcnt vmcnt(0) lgkmcnt(0)
; __device__ __forceinline__ float bf2f(u16 h) { return __uint_as_float(((unsigned)h) << 16); }
; __device__ void nvec_items(const Ctx& p, const int hd) {
;     ...
;     for (int c = 0; c < 3; ++c) {
;       float s = 0.f;
;       for (int k = 0; k < 4; ++k) {
;         uint4 r = *(const uint4*)(KTh + ((long)b * 2048 + d) * SEQ + c * 2048 + k * 512 + lane * 8);
;         s += bf2f(r.x & 0xffff) + bf2f(r.x >> 16) + bf2f(r.y & 0xffff) + bf2f(r.y >> 16) +
;              bf2f(r.z & 0xffff) + bf2f(r.z >> 16) + bf2f(r.w & 0xffff) + bf2f(r.w >> 16);
;       }
;       s = wave_sum(s);
;       if (c > 0) st *= __expf(gA[bh * SEQ + c * 2048 - 1] - gA[bh * SEQ + c * 2048 + 2047]);
;       st += s;
;       if (lane == 0) nv[(b * 3 + c) * 2048 + d] = st;
;     }
	v_lshlrev_b32_e32 v18, 16, v14
	v_and_b32_e32 v14, 0xffff0000, v14
	v_add_f32_e32 v14, v18, v14
	v_lshlrev_b32_e32 v18, 16, v15
	v_add_f32_e32 v14, v14, v18
	v_and_b32_e32 v15, 0xffff0000, v15
	v_add_f32_e32 v14, v14, v15
	v_lshlrev_b32_e32 v15, 16, v16
	v_add_f32_e32 v14, v14, v15
	v_and_b32_e32 v15, 0xffff0000, v16
	v_add_f32_e32 v14, v14, v15
	v_lshlrev_b32_e32 v15, 16, v17
	v_add_f32_e32 v14, v14, v15
	v_and_b32_e32 v15, 0xffff0000, v17
	v_add_f32_e32 v14, v14, v15
	v_add_f32_e32 v3, v3, v14
	ds_bpermute_b32 v14, v7, v3
	v_mov_b32_e32 v16, s18
	v_mov_b32_e32 v17, s17
	s_waitcnt lgkmcnt(0)
	v_add_f32_e32 v3, v3, v14
	ds_bpermute_b32 v14, v8, v3
	s_waitcnt lgkmcnt(0)
	v_add_f32_e32 v3, v3, v14
	ds_bpermute_b32 v14, v9, v3
	s_waitcnt lgkmcnt(0)
	v_add_f32_e32 v3, v3, v14
	ds_bpermute_b32 v14, v10, v3
	s_waitcnt lgkmcnt(0)
	v_add_f32_e32 v3, v3, v14
	ds_bpermute_b32 v14, v11, v3
	s_waitcnt lgkmcnt(0)
	v_add_f32_e32 v3, v3, v14
	ds_bpermute_b32 v14, v12, v3
	s_waitcnt lgkmcnt(0)
	v_add_f32_e32 v3, v3, v14
	v_add_co_u32_e32 v14, vcc, 0x1000, v16
	s_nop 1
	v_addc_co_u32_e32 v15, vcc, 0, v17, vcc
	global_load_dword v18, v[14:15], off offset:4092
	v_add_co_u32_e32 v14, vcc, 0x3000, v16
	s_nop 1
	v_addc_co_u32_e32 v15, vcc, 0, v17, vcc
	global_load_dword v14, v[14:15], off offset:4092
	s_waitcnt vmcnt(0) lgkmcnt(0)
	v_sub_f32_e32 v14, v18, v14
	v_mul_f32_e32 v14, 0x3fb8aa3b, v14
	v_exp_f32_e32 v14, v14
	s_nop 0
	v_fmac_f32_e32 v3, v13, v14
	s_and_saveexec_b64 s[8:9], s[4:5]
	s_cbranch_execz .LBB0_595
	s_add_i32 s19, s16, 0x800
	v_add_u32_e32 v14, s19, v2
	v_ashrrev_i32_e32 v15, 31, v14
	v_lshl_add_u64 v[14:15], v[14:15], 2, s[0:1]
	global_store_dword v[14:15], v3, off
.LBB0_595:
	s_or_b64 exec, exec, s[8:9]
	v_add_co_u32_e32 v4, vcc, 0x2000, v4
	s_nop 1
	v_addc_co_u32_e32 v5, vcc, 0, v5, vcc
	global_load_dwordx4 v[14:17], v[4:5], off
	s_waitcnt vmcnt(0) lgkmcnt(0)
	v_lshlrev_b32_e32 v13, 16, v14
	v_and_b32_e32 v14, 0xffff0000, v14
	v_add_f32_e32 v13, v13, v14
	v_lshlrev_b32_e32 v14, 16, v15
	v_add_f32_e32 v13, v13, v14
	v_and_b32_e32 v14, 0xffff0000, v15
	v_add_f32_e32 v13, v13, v14
	v_lshlrev_b32_e32 v14, 16, v16
	v_add_f32_e32 v13, v13, v14
	v_and_b32_e32 v14, 0xffff0000, v16
	v_add_f32_e32 v13, v13, v14
	v_lshlrev_b32_e32 v14, 16, v17
	v_add_f32_e32 v13, v13, v14
	v_and_b32_e32 v14, 0xffff0000, v17
	v_add_f32_e32 v13, v13, v14
	global_load_dwordx4 v[14:17], v[4:5], off offset:1024
	v_add_f32_e32 v13, 0, v13
	s_waitcnt vmcnt(0) lgkmcnt(0)
	v_lshlrev_b32_e32 v18, 16, v14
	v_and_b32_e32 v14, 0xffff0000, v14
	v_add_f32_e32 v14, v18, v14
	v_lshlrev_b32_e32 v18, 16, v15
	v_add_f32_e32 v14, v14, v18
	v_and_b32_e32 v15, 0xffff0000, v15
	v_add_f32_e32 v14, v14, v15
	v_lshlrev_b32_e32 v15, 16, v16
	v_add_f32_e32 v14, v14, v15
	v_and_b32_e32 v15, 0xffff0000, v16
	v_add_f32_e32 v14, v14, v15
	v_lshlrev_b32_e32 v15, 16, v17
	v_add_f32_e32 v14, v14, v15
	v_and_b32_e32 v15, 0xffff0000, v17
	v_add_f32_e32 v14, v14, v15
	v_add_f32_e32 v13, v13, v14
	global_load_dwordx4 v[14:17], v[4:5], off offset:2048
	s_waitcnt vmcnt(0) lgkmcnt(0)
	v_lshlrev_b32_e32 v18, 16, v14
	v_and_b32_e32 v14, 0xffff0000, v14
	v_add_f32_e32 v14, v18, v14
	v_lshlrev_b32_e32 v18, 16, v15
	v_add_f32_e32 v14, v14, v18
	v_and_b32_e32 v15, 0xffff0000, v15
	v_add_f32_e32 v14, v14, v15
	v_lshlrev_b32_e32 v15, 16, v16
	v_add_f32_e32 v14, v14, v15
	v_and_b32_e32 v15, 0xffff0000, v16
	v_add_f32_e32 v14, v14, v15
	v_lshlrev_b32_e32 v15, 16, v17
	v_add_f32_e32 v14, v14, v15
	v_and_b32_e32 v15, 0xffff0000, v17
	v_add_f32_e32 v14, v14, v15
	v_add_f32_e32 v13, v13, v14
	global_load_dwordx4 v[14:17], v[4:5], off offset:3072
	s_waitcnt vmcnt(0) lgkmcnt(0)
	v_lshlrev_b32_e32 v4, 16, v14
	v_and_b32_e32 v5, 0xffff0000, v14
	v_add_f32_e32 v4, v4, v5
	v_lshlrev_b32_e32 v5, 16, v15
	v_add_f32_e32 v4, v4, v5
	v_and_b32_e32 v5, 0xffff0000, v15
	v_add_f32_e32 v4, v4, v5
	v_lshlrev_b32_e32 v5, 16, v16
	v_add_f32_e32 v4, v4, v5
	v_and_b32_e32 v5, 0xffff0000, v16
	v_add_f32_e32 v4, v4, v5
	v_lshlrev_b32_e32 v5, 16, v17
	v_add_f32_e32 v4, v4, v5
	v_and_b32_e32 v5, 0xffff0000, v17
	v_add_f32_e32 v4, v4, v5
	v_add_f32_e32 v4, v13, v4
	ds_bpermute_b32 v5, v7, v4
	s_waitcnt lgkmcnt(0)
	v_add_f32_e32 v4, v4, v5
	ds_bpermute_b32 v5, v8, v4
	s_waitcnt lgkmcnt(0)
	v_add_f32_e32 v4, v4, v5
	ds_bpermute_b32 v5, v9, v4
	s_waitcnt lgkmcnt(0)
	v_add_f32_e32 v4, v4, v5
	ds_bpermute_b32 v5, v10, v4
	s_waitcnt lgkmcnt(0)
	v_add_f32_e32 v4, v4, v5
	ds_bpermute_b32 v5, v11, v4
	s_waitcnt lgkmcnt(0)
	v_add_f32_e32 v4, v4, v5
	ds_bpermute_b32 v5, v12, v4
	s_and_saveexec_b64 s[8:9], s[4:5]
	s_cbranch_execz .LBB0_590
	s_waitcnt lgkmcnt(0)
	v_add_f32_e32 v13, v4, v5
	v_mov_b64_e32 v[4:5], s[6:7]
	global_load_dword v14, v[4:5], off
	v_mov_b32_e32 v4, s18
	v_add_co_u32_e32 v4, vcc, 0x5000, v4
	v_mov_b32_e32 v5, s17
	s_nop 0
	v_addc_co_u32_e32 v5, vcc, 0, v5, vcc
	global_load_dword v4, v[4:5], off offset:4092
	s_addk_i32 s16, 0x1000
	v_add_u32_e32 v2, s16, v2
	s_waitcnt vmcnt(0) lgkmcnt(0)
	v_sub_f32_e32 v4, v14, v4
	v_mul_f32_e32 v4, 0x3fb8aa3b, v4
	v_exp_f32_e32 v4, v4
	s_nop 0
	v_fmac_f32_e32 v13, v3, v4
	v_ashrrev_i32_e32 v3, 31, v2
	v_lshl_add_u64 v[2:3], v[2:3], 2, s[0:1]
	global_store_dword v[2:3], v13, off
	s_branch .LBB0_590

;   __device__ __forceinline__ const float* in(int i) const { return ((const float* const*)(ws + OFF_TBL))[i]; }
; __device__ void hq_phase(const Ctx& p, const int hd) {
;     ...
;   const int gw = blockIdx.x * 8 + (tid >> 6), nw = gridDim.x * 8;
;   const float* cw = p.in(14); const float* cb = p.in(15);
;   const float* wq = p.in(16); const float* wk = p.in(17);
; #pragma unroll 1
;   for (int it = gw; it < 2 * 128 * 128; it += nw) {
;     const int cgp = it & 127, tt = (it >> 7) & 127, b = it >> 14;
;     const int t = tt * 64 + lane, c0 = cgp * 16;
;     const int cg0 = hd * 2048 + c0;
;     const int bh = b * 4 + hd;
;     const float rwq = wq[(cg0 >> 2) * 16 + lane];
;     const float rwk = wk[(cg0 >> 2) * 16 + lane];
;     const float rcw = cw[(lane >> 4) * 8192 + cg0 + (lane & 15)];
;     const float rcb = cb[cg0 + (lane & 15)];
;     const float wt = __expf(ga[bh * SEQ + t] - gA[bh * SEQ + ((t >> 11) << 11) + 2047]);
;     const int tm1 = max(t - 1, 0), tm2 = max(t - 2, 0), tm3 = max(t - 3, 0);
;     u16 r0[16], r1[16], r2[16], r3[16];
; #pragma unroll
;     for (int x = 0; x < 16; ++x) {
;       const u16* xr = xmt + ((long)b * 8192 + cg0 + x) * SEQ;
;       r3[x] = xr[t]; r2[x] = xr[tm1]; r1[x] = xr[tm2]; r0[x] = xr[tm3];
.LBB0_598:
	s_and_b64 vcc, exec, s[0:1]
	s_cbranch_vccz .LBB0_605
	v_mov_b32_e32 v10, v139
	v_readlane_b32 s0, v253, 17
	v_ashrrev_i32_e32 v0, 6, v10
	s_nop 0
	v_add_u32_e32 v46, s0, v0
	v_cmp_gt_i32_e32 vcc, s84, v46
	s_and_saveexec_b64 s[6:7], vcc
	s_cbranch_execz .LBB0_604
	s_waitcnt vmcnt(0) lgkmcnt(0)
	v_mov_b32_e32 v2, s66
	s_mov_b32 s0, 0x4375c000
	s_waitcnt lgkmcnt(0)
	v_add_co_u32_e32 v6, vcc, s0, v2
	v_mov_b32_e32 v2, s67
	s_nop 0
	v_addc_co_u32_e32 v7, vcc, 0, v2, vcc
	global_load_dwordx4 v[2:5], v[6:7], off offset:112
	s_nop 0
	global_load_dwordx4 v[6:9], v[6:7], off offset:128
	s_add_u32 s8, s66, 0x10800000
	s_addc_u32 s9, s67, 0
	s_add_u32 s10, s66, 0x4200000
	s_addc_u32 s11, s67, 0
	s_add_u32 s12, s66, 0x8400000
	s_addc_u32 s13, s67, 0
	s_add_u32 s14, s66, 0x3b000000
	s_addc_u32 s15, s67, 0
	v_lshlrev_b32_e32 v11, 9, v10
	v_and_b32_e32 v48, 15, v10
	s_movk_i32 s0, 0x6000
	s_add_u32 s16, s66, 0x43680000
	v_and_or_b32 v49, v11, s0, v48
	v_readlane_b32 s0, v252, 33
	s_addc_u32 s17, s67, 0
	v_and_b32_e32 v47, 63, v10
	v_lshl_add_u32 v50, v0, 4, s0
	s_mov_b64 s[18:19], 0
	s_waitcnt vmcnt(0) lgkmcnt(0)
	v_lshrrev_b32_e32 v111, 3, v47
	v_and_b32_e32 v112, 7, v47
	v_lshlrev_b32_e32 v105, 14, v111
	v_lshl_add_u32 v105, v112, 4, v105
	v_mul_u32_u24_e32 v110, 0x900, v0
	v_add_u32_e32 v110, 0x400, v110
	v_mul_u32_u24_e32 v106, 0x90, v111
	v_lshl_add_u32 v106, v112, 4, v106
	v_add3_u32 v106, v106, v110, 16
	v_and_b32_e32 v109, 15, v47
	v_mul_u32_u24_e32 v107, 0x90, v109
	v_add_u32_e32 v107, v107, v110
	v_lshl_add_u32 v108, v47, 1, v110
	v_lshlrev_b32_e32 v109, 14, v109
	v_mov_b32_e32 v113, 0
	v_lshrrev_b32_e32 v145, 4, v47
	v_lshl_add_u32 v141, v0, 3, v145
	v_and_b32_e32 v146, 15, v47
	v_lshlrev_b32_e32 v142, 4, v146
	v_mul_u32_u24_e32 v143, 0x110, v141
	v_add_u32_e32 v143, v143, v142
	v_mul_u32_u24_e32 v144, 0x110, v47
	v_lshl_add_u32 v144, v0, 5, v144
	v_mov_b32_e32 v153, 0
	v_mov_b32_e32 v155, 0
	s_mov_b32 s99, 0x8000
	v_mov_b32_e32 v237, 0
	v_mov_b32_e32 v251, 0
	v_mov_b32_e32 v157, 0
	v_and_b32_e32 v224, 0x7f0, v50
	v_or_b32_e32 v225, s21, v224
	v_lshlrev_b32_e32 v235, 14, v225
	v_lshlrev_b32_e32 v110, 2, v47
	v_lshl_or_b32 v236, v225, 4, v110
	v_lshl_add_u64 v[238:239], v[6:7], 0, v[236:237]
	global_load_dword v220, v[238:239], off
	v_lshl_add_u64 v[240:241], v[8:9], 0, v[236:237]
	global_load_dword v221, v[240:241], off
	v_or_b32_e32 v250, v49, v225
	v_lshlrev_b32_e32 v250, 2, v250
	v_lshl_add_u64 v[242:243], v[2:3], 0, v[250:251]
	global_load_dword v222, v[242:243], off
	v_or_b32_e32 v156, v225, v48
	v_lshlrev_b32_e32 v156, 2, v156
	v_lshl_add_u64 v[244:245], v[4:5], 0, v[156:157]
	global_load_dword v223, v[244:245], off
	v_mov_b32_e32 v230, s66
	v_mov_b32_e32 v231, s67
	v_add_co_u32_e32 v230, vcc, 0x436c1000, v230
	s_nop 1
	v_addc_co_u32_e32 v231, vcc, 0, v231, vcc
	v_ashrrev_i32_e32 v226, 14, v46
	v_lshrrev_b32_e32 v227, 1, v46
	v_and_b32_e32 v104, 0x1fc0, v227
	v_or_b32_e32 v228, v104, v47
	v_lshlrev_b32_e32 v104, 1, v104
	v_lshl_add_u32 v229, v226, 27, v235
	v_add_u32_e32 v229, v229, v104
	v_add_u32_e32 v112, v229, v105
	v_lshl_add_u64 v[114:115], s[8:9], 0, v[112:113]
	global_load_dwordx4 v[120:123], v[114:115], off
	v_lshl_add_u64 v[118:119], v[114:115], 0, s[88:89]
	global_load_dwordx4 v[124:127], v[118:119], off
	v_add_u32_e32 v236, v229, v109
	v_lshl_add_u64 v[116:117], s[8:9], 0, v[236:237]
	s_mov_b64 exec, 0xffff
	global_load_dwordx4 v[128:131], v[116:117], off offset:-16
	s_mov_b64 exec, -1
	v_lshl_add_u32 v229, v226, 15, s20
	v_or_b32_e32 v250, v229, v228
	v_lshl_add_u64 v[246:247], v[250:251], 2, s[16:17]
	global_load_dword v232, v[246:247], off
	v_and_b32_e32 v156, 0x1800, v227
	v_or_b32_e32 v156, v156, v229
	v_lshl_add_u64 v[248:249], v[156:157], 2, v[230:231]
	global_load_dword v233, v[248:249], off offset:4092
	s_waitcnt vmcnt(0)
	s_branch .LBB0_602

;   __device__ __forceinline__ const float* in(int i) const { return ((const float* const*)(ws + OFF_TBL))[i]; }
; __device__ __forceinline__ int ltid() { int t = threadIdx.x; asm volatile("" : "+v"(t)); return t; }
; __device__ void cvt_bf16(const float* __restrict__ src, u16* __restrict__ dst, long n8) {
;   long gt = (long)blockIdx.x * blockDim.x + ltid(), gs = (long)gridDim.x * blockDim.x;
;   long i = gt;
;   for (; i + 3 * gs < n8; i += gs * 4) {
;     float4 a[4], b[4];
; #pragma unroll
;     for (int u = 0; u < 4; ++u) { long j = i + u * gs; a[u] = *(const float4*)(src + j * 8); b[u] = *(const float4*)(src + j * 8 + 4); }
; #pragma unroll
;     for (int u = 0; u < 4; ++u) {
;       long j = i + u * gs;
;       uint4 o; o.x = pack2(a[u].x, a[u].y); o.y = pack2(a[u].z, a[u].w); o.z = pack2(b[u].x, b[u].y); o.w = pack2(b[u].z, b[u].w);
;       *(uint4*)(dst + j * 8) = o;
;     }
;   }
; __device__ void phase_prep0(const Ctx& p) {
;     ...
;   cvt_bf16(p.in(0), (u16*)(ws + OFF_XB), (long)NTOK * DM / 8);
.LBB0_606:
	s_andn2_b64 vcc, exec, s[34:35]
	v_readlane_b32 s24, v252, 42
	v_readlane_b32 s26, v252, 44
	v_readlane_b32 s22, v252, 46
	v_readlane_b32 s30, v252, 49
	v_readlane_b32 s34, v252, 51
	v_readlane_b32 s25, v252, 43
	v_readlane_b32 s27, v252, 45
	v_readlane_b32 s23, v252, 47
	v_readlane_b32 s21, v252, 48
	s_mov_b32 s10, 0x42000000
	v_readlane_b32 s31, v252, 50
	v_readlane_b32 s35, v252, 52
	s_cbranch_vccnz .LBB0_747
	v_mov_b32_e32 v0, s66
	s_waitcnt vmcnt(0) lgkmcnt(0)
	v_add_co_u32_e32 v2, vcc, 0x4375c000, v0
	v_mov_b32_e32 v0, s67
	s_waitcnt lgkmcnt(0)
	v_addc_co_u32_e32 v3, vcc, 0, v0, vcc
	global_load_dwordx2 v[4:5], v[2:3], off
	v_mov_b32_e32 v18, v139
	v_readlane_b32 s0, v252, 15
	v_readlane_b32 s1, v252, 16
	v_ashrrev_i32_e32 v19, 31, v18
	s_nop 0
	v_lshl_add_u64 v[2:3], s[0:1], 0, v[18:19]
	v_cmp_gt_i64_e32 vcc, s[24:25], v[2:3]
	s_and_saveexec_b64 s[0:1], vcc
	s_cbranch_execz .LBB0_611
	v_readlane_b32 s4, v252, 17
	v_readlane_b32 s5, v252, 18
	v_lshlrev_b64 v[22:23], 4, v[18:19]
	v_lshlrev_b64 v[8:9], 5, v[18:19]
	s_waitcnt vmcnt(0) lgkmcnt(0)
	v_lshl_add_u64 v[6:7], v[4:5], 0, s[4:5]
	v_readlane_b32 s4, v252, 21
	v_readlane_b32 s5, v252, 22
	v_lshlrev_b64 v[14:15], 4, v[2:3]
	s_mov_b64 s[6:7], s[66:67]
	v_lshl_add_u64 v[10:11], v[4:5], 0, s[4:5]
	v_readlane_b32 s4, v252, 19
	v_readlane_b32 s5, v252, 20
	s_nop 1
	v_lshl_add_u64 v[12:13], s[4:5], 0, v[18:19]
	v_readlane_b32 s4, v252, 23
	v_readlane_b32 s5, v252, 24
	v_lshlrev_b64 v[12:13], 4, v[12:13]
	s_nop 0
	v_lshl_add_u64 v[16:17], v[4:5], 0, s[4:5]
	v_readlane_b32 s4, v252, 25
	v_readlane_b32 s5, v252, 26
	s_nop 1
	v_lshl_add_u64 v[18:19], s[4:5], 0, v[22:23]
	v_readlane_b32 s4, v252, 27
	v_readlane_b32 s5, v252, 28
	s_nop 1
	v_lshl_add_u64 v[20:21], v[4:5], 0, s[4:5]
	v_readlane_b32 s4, v252, 29
	v_readlane_b32 s5, v252, 30
	s_nop 1
	v_lshl_add_u64 v[22:23], s[4:5], 0, v[22:23]
	s_mov_b64 s[4:5], 0
.LBB0_609:
	v_lshl_add_u64 v[28:29], v[6:7], 0, v[8:9]
	v_lshl_add_u64 v[36:37], v[10:11], 0, v[8:9]
	v_lshl_add_u64 v[44:45], v[16:17], 0, v[8:9]
	v_lshl_add_u64 v[52:53], v[20:21], 0, v[8:9]
	global_load_dwordx4 v[24:27], v[28:29], off
	s_nop 0
	global_load_dwordx4 v[28:31], v[28:29], off offset:16
	s_nop 0
	global_load_dwordx4 v[32:35], v[36:37], off
	s_nop 0
	global_load_dwordx4 v[36:39], v[36:37], off offset:16
	s_nop 0
	global_load_dwordx4 v[40:43], v[44:45], off
	s_nop 0
	global_load_dwordx4 v[44:47], v[44:45], off offset:16
	s_nop 0
	global_load_dwordx4 v[48:51], v[52:53], off
	s_nop 0
	global_load_dwordx4 v[52:55], v[52:53], off offset:16
	s_add_u32 s8, s78, s78
	s_addc_u32 s9, s79, s79
	s_add_u32 s8, s8, s8
	s_addc_u32 s9, s9, s9
	v_lshl_add_u64 v[56:57], s[6:7], 0, v[14:15]
	v_lshl_add_u64 v[58:59], s[6:7], 0, v[12:13]
	v_lshl_add_u64 v[60:61], s[6:7], 0, v[22:23]
	v_lshl_add_u64 v[62:63], s[6:7], 0, v[18:19]
	v_lshl_add_u64 v[2:3], s[8:9], 0, v[2:3]
	s_add_u32 s6, s6, s76
	s_addc_u32 s7, s7, s77
	v_cmp_le_i64_e32 vcc, s[24:25], v[2:3]
	v_lshl_add_u64 v[8:9], v[8:9], 0, s[22:23]
	s_or_b64 s[4:5], vcc, s[4:5]
	s_waitcnt vmcnt(0) lgkmcnt(0)
	v_cvt_pk_bf16_f32 v24, v24, v25
	v_cvt_pk_bf16_f32 v25, v26, v27
	v_cvt_pk_bf16_f32 v26, v28, v29
	v_cvt_pk_bf16_f32 v27, v30, v31
	v_cvt_pk_bf16_f32 v28, v32, v33
	v_cvt_pk_bf16_f32 v29, v34, v35
	v_cvt_pk_bf16_f32 v30, v36, v37
	v_cvt_pk_bf16_f32 v31, v38, v39
	v_cvt_pk_bf16_f32 v32, v40, v41
	v_cvt_pk_bf16_f32 v33, v42, v43
	v_cvt_pk_bf16_f32 v34, v44, v45
	v_cvt_pk_bf16_f32 v35, v46, v47
	v_cvt_pk_bf16_f32 v36, v48, v49
	v_cvt_pk_bf16_f32 v37, v50, v51
	v_cvt_pk_bf16_f32 v38, v52, v53
	v_cvt_pk_bf16_f32 v39, v54, v55
	global_store_dwordx4 v[56:57], v[24:27], off
	global_store_dwordx4 v[58:59], v[28:31], off
	global_store_dwordx4 v[60:61], v[32:35], off
	global_store_dwordx4 v[62:63], v[36:39], off
	s_andn2_b64 exec, exec, s[4:5]
	s_cbranch_execnz .LBB0_609
	s_or_b64 exec, exec, s[4:5]

;   __device__ __forceinline__ const float* in(int i) const { return ((const float* const*)(ws + OFF_TBL))[i]; }
; __device__ __forceinline__ int ltid() { int t = threadIdx.x; asm volatile("" : "+v"(t)); return t; }
; __device__ void cvt_bf16(const float* __restrict__ src, u16* __restrict__ dst, long n8) {
;   long gt = (long)blockIdx.x * blockDim.x + ltid(), gs = (long)gridDim.x * blockDim.x;
;   long i = gt;
;   for (; i + 3 * gs < n8; i += gs * 4) {
;     float4 a[4], b[4];
; #pragma unroll
;     for (int u = 0; u < 4; ++u) { long j = i + u * gs; a[u] = *(const float4*)(src + j * 8); b[u] = *(const float4*)(src + j * 8 + 4); }
; #pragma unroll
;     for (int u = 0; u < 4; ++u) {
;       long j = i + u * gs;
;       uint4 o; o.x = pack2(a[u].x, a[u].y); o.y = pack2(a[u].z, a[u].w); o.z = pack2(b[u].x, b[u].y); o.w = pack2(b[u].z, b[u].w);
;       *(uint4*)(dst + j * 8) = o;
;     }
;   }
;   for (; i < n8; i += gs) {
;     float4 a = *(const float4*)(src + i * 8), b = *(const float4*)(src + i * 8 + 4);
;     uint4 o; o.x = pack2(a.x, a.y); o.y = pack2(a.z, a.w); o.z = pack2(b.x, b.y); o.w = pack2(b.z, b.w);
;     *(uint4*)(dst + i * 8) = o;
;   }
; }
; __device__ void phase_prep0(const Ctx& p) {
;     ...
;   cvt_bf16(p.in(1), (u16*)(ws + OFF_MEMB), (long)512 * DM / 8);
.LBB0_613:
	global_load_dwordx4 v[8:11], v[4:5], off
	global_load_dwordx4 v[12:15], v[4:5], off offset:16
	v_lshl_add_u64 v[2:3], v[2:3], 0, s[78:79]
	s_mov_b64 s[6:7], 0x7fffff
	v_cmp_lt_i64_e32 vcc, s[6:7], v[2:3]
	v_lshl_add_u64 v[4:5], v[4:5], 0, s[34:35]
	s_or_b64 s[4:5], vcc, s[4:5]
	s_waitcnt vmcnt(0) lgkmcnt(0)
	v_cvt_pk_bf16_f32 v8, v8, v9
	v_cvt_pk_bf16_f32 v9, v10, v11
	v_cvt_pk_bf16_f32 v10, v12, v13
	v_cvt_pk_bf16_f32 v11, v14, v15
	global_store_dwordx4 v[6:7], v[8:11], off
	v_lshl_add_u64 v[6:7], v[6:7], 0, s[30:31]
	s_andn2_b64 exec, exec, s[4:5]
	s_cbranch_execnz .LBB0_613
.LBB0_614:
	s_or_b64 exec, exec, s[0:1]
	v_mov_b32_e32 v0, s66
	v_add_co_u32_e32 v2, vcc, 0x4375c000, v0
	v_mov_b32_e32 v0, s67
	s_nop 0
	v_addc_co_u32_e32 v3, vcc, 0, v0, vcc
	s_waitcnt vmcnt(0) lgkmcnt(0)
	global_load_dwordx2 v[4:5], v[2:3], off offset:8
	v_mov_b32_e32 v18, v139
	v_readlane_b32 s0, v252, 15
	v_readlane_b32 s1, v252, 16
	v_ashrrev_i32_e32 v19, 31, v18
	s_nop 0
	v_lshl_add_u64 v[2:3], s[0:1], 0, v[18:19]
	v_cmp_gt_i64_e32 vcc, s[26:27], v[2:3]
	s_and_saveexec_b64 s[0:1], vcc
	s_cbranch_execz .LBB0_618
	v_readlane_b32 s4, v252, 23
	v_readlane_b32 s5, v252, 24
	v_lshlrev_b64 v[22:23], 4, v[18:19]
	v_lshlrev_b64 v[10:11], 5, v[18:19]
	s_waitcnt vmcnt(0) lgkmcnt(0)
	v_lshl_add_u64 v[8:9], v[4:5], 0, s[4:5]
	v_readlane_b32 s4, v252, 17
	v_readlane_b32 s5, v252, 18
	v_lshlrev_b64 v[6:7], 4, v[2:3]
	s_mov_b64 s[6:7], s[66:67]
	v_lshl_add_u64 v[12:13], v[4:5], 0, s[4:5]
	v_readlane_b32 s4, v252, 21
	v_readlane_b32 s5, v252, 22
	s_nop 1
	v_lshl_add_u64 v[14:15], v[4:5], 0, s[4:5]
	v_readlane_b32 s4, v252, 19
	v_readlane_b32 s5, v252, 20
	s_nop 1
	v_lshl_add_u64 v[16:17], s[4:5], 0, v[18:19]
	v_readlane_b32 s4, v252, 29
	v_readlane_b32 s5, v252, 30
	v_lshlrev_b64 v[16:17], 4, v[16:17]
	s_nop 0
	v_lshl_add_u64 v[18:19], s[4:5], 0, v[22:23]
	v_readlane_b32 s4, v252, 27
	v_readlane_b32 s5, v252, 28
	s_nop 1
	v_lshl_add_u64 v[20:21], v[4:5], 0, s[4:5]
	v_readlane_b32 s4, v252, 25
	v_readlane_b32 s5, v252, 26
	s_nop 1
	v_lshl_add_u64 v[22:23], s[4:5], 0, v[22:23]
	s_mov_b64 s[4:5], 0
.LBB0_616:
	v_lshl_add_u64 v[28:29], v[12:13], 0, v[10:11]
	v_lshl_add_u64 v[36:37], v[14:15], 0, v[10:11]
	v_lshl_add_u64 v[44:45], v[8:9], 0, v[10:11]
	v_lshl_add_u64 v[52:53], v[20:21], 0, v[10:11]
	global_load_dwordx4 v[24:27], v[28:29], off
	s_nop 0
	global_load_dwordx4 v[28:31], v[28:29], off offset:16
	s_nop 0
	global_load_dwordx4 v[32:35], v[36:37], off
	s_nop 0
	global_load_dwordx4 v[36:39], v[36:37], off offset:16
	s_nop 0
	global_load_dwordx4 v[40:43], v[44:45], off
	s_nop 0
	global_load_dwordx4 v[44:47], v[44:45], off offset:16
	s_nop 0
	global_load_dwordx4 v[48:51], v[52:53], off
	s_nop 0
	global_load_dwordx4 v[52:55], v[52:53], off offset:16
	v_lshl_add_u64 v[56:57], s[6:7], 0, v[6:7]
	v_add_co_u32_e32 v56, vcc, s10, v56
	v_lshl_add_u64 v[58:59], s[6:7], 0, v[16:17]
	s_nop 0
	v_addc_co_u32_e32 v57, vcc, 0, v57, vcc
	v_add_co_u32_e32 v58, vcc, s10, v58
	v_lshl_add_u64 v[60:61], s[6:7], 0, v[18:19]
	s_add_u32 s8, s78, s78
	v_addc_co_u32_e32 v59, vcc, 0, v59, vcc
	v_add_co_u32_e32 v60, vcc, s10, v60
	s_addc_u32 s9, s79, s79
	v_lshl_add_u64 v[62:63], s[6:7], 0, v[22:23]
	v_addc_co_u32_e32 v61, vcc, 0, v61, vcc
	s_add_u32 s8, s8, s8
	v_add_co_u32_e32 v62, vcc, s10, v62
	s_addc_u32 s9, s9, s9
	s_nop 0
	v_addc_co_u32_e32 v63, vcc, 0, v63, vcc
	v_lshl_add_u64 v[2:3], s[8:9], 0, v[2:3]
	s_add_u32 s6, s6, s76
	s_addc_u32 s7, s7, s77
	v_cmp_le_i64_e32 vcc, s[26:27], v[2:3]
	v_lshl_add_u64 v[10:11], v[10:11], 0, s[22:23]
	s_or_b64 s[4:5], vcc, s[4:5]
	s_waitcnt vmcnt(0) lgkmcnt(0)
	v_cvt_pk_bf16_f32 v24, v24, v25
	v_cvt_pk_bf16_f32 v25, v26, v27
	v_cvt_pk_bf16_f32 v26, v28, v29
	v_cvt_pk_bf16_f32 v27, v30, v31
	v_cvt_pk_bf16_f32 v28, v32, v33
	v_cvt_pk_bf16_f32 v29, v34, v35
	v_cvt_pk_bf16_f32 v30, v36, v37
	v_cvt_pk_bf16_f32 v31, v38, v39
	v_cvt_pk_bf16_f32 v32, v40, v41
	v_cvt_pk_bf16_f32 v33, v42, v43
	v_cvt_pk_bf16_f32 v34, v44, v45
	v_cvt_pk_bf16_f32 v35, v46, v47
	v_cvt_pk_bf16_f32 v36, v48, v49
	v_cvt_pk_bf16_f32 v37, v50, v51
	v_cvt_pk_bf16_f32 v38, v52, v53
	v_cvt_pk_bf16_f32 v39, v54, v55
	global_store_dwordx4 v[56:57], v[24:27], off
	global_store_dwordx4 v[58:59], v[28:31], off
	global_store_dwordx4 v[60:61], v[32:35], off
	global_store_dwordx4 v[62:63], v[36:39], off
	s_andn2_b64 exec, exec, s[4:5]
	s_cbranch_execnz .LBB0_616
	s_or_b64 exec, exec, s[4:5]

;   __device__ __forceinline__ const float* in(int i) const { return ((const float* const*)(ws + OFF_TBL))[i]; }
; __device__ __forceinline__ int ltid() { int t = threadIdx.x; asm volatile("" : "+v"(t)); return t; }
;   const int tid = ltid();
;   const int kg = tid & 7, ng = tid >> 3;
;   const int tn = Nd / 256, tk = R / 64;
;   if (nblk == 0) nblk = gridDim.x;
;   if ((int)blockIdx.x < blk0 || (int)blockIdx.x >= blk0 + nblk) return;
;   for (int t = (int)blockIdx.x - blk0; t < tn * tk; t += nblk) {
;     const int n0 = (t / tk) * 256 + ng * 4, k0 = (t % tk) * 64 + kg * 8;
;     int c = n0;
;     if (mode == 1) c = (n0 < 6144) ? n0 : (n0 < 15360 ? n0 + 16 : (n0 < 15376 ? 6144 + (n0 - 15360) : -1));
;     float4 v[8];
; #pragma unroll
;     for (int r = 0; r < 8; ++r) v[r] = (c >= 0) ? *(const float4*)(src + (long)(k0 + r) * C + c) : make_float4(0.f, 0.f, 0.f, 0.f);
;     uint4 o;
;     o.x = pack2(v[0].x, v[1].x); o.y = pack2(v[2].x, v[3].x); o.z = pack2(v[4].x, v[5].x); o.w = pack2(v[6].x, v[7].x);
;     *(uint4*)(dst + (long)(n0 + 0) * R + k0) = o;
;     o.x = pack2(v[0].y, v[1].y); o.y = pack2(v[2].y, v[3].y); o.z = pack2(v[4].y, v[5].y); o.w = pack2(v[6].y, v[7].y);
;     *(uint4*)(dst + (long)(n0 + 1) * R + k0) = o;
;     o.x = pack2(v[0].z, v[1].z); o.y = pack2(v[2].z, v[3].z); o.z = pack2(v[4].z, v[5].z); o.w = pack2(v[6].z, v[7].z);
;     *(uint4*)(dst + (long)(n0 + 2) * R + k0) = o;
;     o.x = pack2(v[0].w, v[1].w); o.y = pack2(v[2].w, v[3].w); o.z = pack2(v[4].w, v[5].w); o.w = pack2(v[6].w, v[7].w);
;     *(uint4*)(dst + (long)(n0 + 3) * R + k0) = o;
;   }
; __device__ void phase_prep0(const Ctx& p) {
;     ...
;   cvt_bf16(p.in(1), (u16*)(ws + OFF_MEMB), (long)512 * DM / 8);
;   transpose_cvt(p.in(3), DM, 15376, (u16*)(ws + OFF_W0T), H0LD, 1);
.LBB0_620:
	global_load_dwordx4 v[8:11], v[4:5], off
	global_load_dwordx4 v[12:15], v[4:5], off offset:16
	v_lshl_add_u64 v[2:3], v[2:3], 0, s[78:79]
	s_mov_b64 s[6:7], 0x3ffff
	v_cmp_lt_i64_e32 vcc, s[6:7], v[2:3]
	v_lshl_add_u64 v[4:5], v[4:5], 0, s[34:35]
	s_or_b64 s[4:5], vcc, s[4:5]
	s_waitcnt vmcnt(0) lgkmcnt(0)
	v_cvt_pk_bf16_f32 v8, v8, v9
	v_cvt_pk_bf16_f32 v9, v10, v11
	v_cvt_pk_bf16_f32 v10, v12, v13
	v_cvt_pk_bf16_f32 v11, v14, v15
	global_store_dwordx4 v[6:7], v[8:11], off
	v_lshl_add_u64 v[6:7], v[6:7], 0, s[30:31]
	s_andn2_b64 exec, exec, s[4:5]
	s_cbranch_execnz .LBB0_620
.LBB0_621:
	s_or_b64 exec, exec, s[0:1]
	v_mov_b32_e32 v0, s66
	v_add_co_u32_e32 v2, vcc, 0x4375c000, v0
	v_mov_b32_e32 v0, s67
	s_nop 0
	v_addc_co_u32_e32 v3, vcc, 0, v0, vcc
	global_load_dwordx2 v[34:35], v[2:3], off offset:24
	v_readlane_b32 s0, v253, 38
	v_readlane_b32 s1, v253, 39
	v_mov_b32_e32 v0, v139
	s_andn2_b64 vcc, exec, s[0:1]
	s_cbranch_vccnz .LBB0_646
	v_ashrrev_i32_e32 v2, 1, v0
	s_mul_i32 s0, s63, 0xf0400
	v_and_b32_e32 v42, -4, v2
	v_lshlrev_b32_e32 v2, 3, v0
	v_and_b32_e32 v0, 7, v0
	v_mov_b32_e32 v3, s0
	s_mov_b32 s0, 0x1e080
	s_add_u32 s4, s66, 0x8000000
	v_and_b32_e32 v2, 56, v2
	v_mad_u32_u24 v43, v0, s0, v3
	v_readlane_b32 s0, v252, 14
	s_addc_u32 s5, s67, 0
	s_mov_b32 s8, s63
	v_add_u32_e32 v44, s0, v2
	s_branch .LBB0_624
.LBB0_623:
	s_or_b64 exec, exec, s[6:7]
	s_lshl_b32 s0, s9, 12
	v_subrev_u32_e32 v46, s0, v44
	v_ashrrev_i32_e32 v37, 31, v36
	v_lshlrev_b64 v[48:49], 13, v[36:37]
	v_ashrrev_i32_e32 v47, 31, v46
	v_lshl_add_u64 v[48:49], s[4:5], 0, v[48:49]
	v_lshlrev_b64 v[46:47], 1, v[46:47]
	s_waitcnt vmcnt(0) lgkmcnt(0)
	v_cvt_pk_bf16_f32 v38, v2, v6
	v_cvt_pk_bf16_f32 v39, v14, v10
	v_cvt_pk_bf16_f32 v40, v22, v18
	v_cvt_pk_bf16_f32 v41, v30, v26
	v_lshl_add_u64 v[48:49], v[48:49], 0, v[46:47]
	v_or_b32_e32 v2, 1, v36
	global_store_dwordx4 v[48:49], v[38:41], off
	v_or_b32_e32 v6, 3, v36
	s_add_i32 s8, s8, s96
	v_cvt_pk_bf16_f32 v38, v3, v7
	v_ashrrev_i32_e32 v3, 31, v2
	v_lshlrev_b64 v[2:3], 13, v[2:3]
	v_lshl_add_u64 v[2:3], s[4:5], 0, v[2:3]
	v_cvt_pk_bf16_f32 v39, v15, v11
	v_cvt_pk_bf16_f32 v40, v23, v19
	v_cvt_pk_bf16_f32 v41, v31, v27
	v_lshl_add_u64 v[2:3], v[2:3], 0, v[46:47]
	global_store_dwordx4 v[2:3], v[38:41], off
	v_or_b32_e32 v2, 2, v36
	v_ashrrev_i32_e32 v3, 31, v2
	v_lshlrev_b64 v[2:3], 13, v[2:3]
	v_ashrrev_i32_e32 v7, 31, v6
	v_lshl_add_u64 v[2:3], s[4:5], 0, v[2:3]
	v_lshlrev_b64 v[6:7], 13, v[6:7]
	v_cvt_pk_bf16_f32 v38, v4, v8
	v_cvt_pk_bf16_f32 v39, v16, v12
	v_cvt_pk_bf16_f32 v40, v24, v20
	v_cvt_pk_bf16_f32 v41, v32, v28
	v_lshl_add_u64 v[2:3], v[2:3], 0, v[46:47]
	v_lshl_add_u64 v[6:7], s[4:5], 0, v[6:7]
	s_mul_i32 s0, s96, 0xf0400
	global_store_dwordx4 v[2:3], v[38:41], off
	v_cvt_pk_bf16_f32 v2, v5, v9
	v_cvt_pk_bf16_f32 v3, v17, v13
	v_cvt_pk_bf16_f32 v4, v25, v21
	v_cvt_pk_bf16_f32 v5, v33, v29
	v_lshl_add_u64 v[6:7], v[6:7], 0, v[46:47]
	v_add_u32_e32 v43, s0, v43
	s_cmpk_lt_i32 s8, 0xf40
	v_add_u32_e32 v44, s33, v44
	global_store_dwordx4 v[6:7], v[2:5], off
	s_cbranch_scc0 .LBB0_646

;   __device__ __forceinline__ const float* in(int i) const { return ((const float* const*)(ws + OFF_TBL))[i]; }
;     ...
;   for (int t = (int)blockIdx.x - blk0; t < tn * tk; t += nblk) {
;     const int n0 = (t / tk) * 256 + ng * 4, k0 = (t % tk) * 64 + kg * 8;
;     int c = n0;
;     if (mode == 1) c = (n0 < 6144) ? n0 : (n0 < 15360 ? n0 + 16 : (n0 < 15376 ? 6144 + (n0 - 15360) : -1));
;     float4 v[8];
; #pragma unroll
;     for (int r = 0; r < 8; ++r) v[r] = (c >= 0) ? *(const float4*)(src + (long)(k0 + r) * C + c) : make_float4(0.f, 0.f, 0.f, 0.f);
;     uint4 o;
;     o.x = pack2(v[0].x, v[1].x); o.y = pack2(v[2].x, v[3].x); o.z = pack2(v[4].x, v[5].x); o.w = pack2(v[6].x, v[7].x);
;     *(uint4*)(dst + (long)(n0 + 0) * R + k0) = o;
;     o.x = pack2(v[0].y, v[1].y); o.y = pack2(v[2].y, v[3].y); o.z = pack2(v[4].y, v[5].y); o.w = pack2(v[6].y, v[7].y);
;     *(uint4*)(dst + (long)(n0 + 1) * R + k0) = o;
;     o.x = pack2(v[0].z, v[1].z); o.y = pack2(v[2].z, v[3].z); o.z = pack2(v[4].z, v[5].z); o.w = pack2(v[6].z, v[7].z);
;     *(uint4*)(dst + (long)(n0 + 2) * R + k0) = o;
;     o.x = pack2(v[0].w, v[1].w); o.y = pack2(v[2].w, v[3].w); o.z = pack2(v[4].w, v[5].w); o.w = pack2(v[6].w, v[7].w);
;     *(uint4*)(dst + (long)(n0 + 3) * R + k0) = o;
;   }
; __device__ void phase_prep0(const Ctx& p) {
;     ...
;   transpose_cvt(p.in(3), DM, 15376, (u16*)(ws + OFF_W0T), H0LD, 1);
;   transpose_cvt(p.in(10), 4608, DM, (u16*)(ws + OFF_WO0T), DM, 0);
.LBB0_630:
	s_or_b64 exec, exec, s[0:1]
	s_mul_i32 s6, s9, 0xfc3f0000
	v_cmp_lt_i32_e64 s[0:1], -1, v0
	s_waitcnt vmcnt(0) lgkmcnt(0)
	v_lshl_add_u64 v[38:39], v[0:1], 2, v[34:35]
	v_mov_b32_e32 v8, 0
	v_add_u32_e32 v40, s6, v43
	v_mov_b32_e32 v4, 0
	v_mov_b32_e32 v5, 0
	v_mov_b32_e32 v2, 0
	v_mov_b32_e32 v3, 0
	s_and_saveexec_b64 s[6:7], s[0:1]
	s_cbranch_execz .LBB0_632
	v_ashrrev_i32_e32 v41, 31, v40
	v_lshl_add_u64 v[2:3], v[40:41], 2, v[38:39]
	global_load_dwordx4 v[2:5], v[2:3], off
.LBB0_632:
	s_or_b64 exec, exec, s[6:7]
	v_mov_b32_e32 v9, 0
	v_mov_b32_e32 v6, 0
	v_mov_b32_e32 v7, 0
	s_and_saveexec_b64 s[6:7], s[0:1]
	s_cbranch_execz .LBB0_634
	v_ashrrev_i32_e32 v41, 31, v40
	v_lshl_add_u64 v[6:7], v[40:41], 2, v[38:39]
	v_add_co_u32_e32 v6, vcc, 0xf000, v6
	s_nop 1
	v_addc_co_u32_e32 v7, vcc, 0, v7, vcc
	global_load_dwordx4 v[6:9], v[6:7], off offset:64
.LBB0_634:
	s_or_b64 exec, exec, s[6:7]
	v_mov_b32_e32 v12, 0
	v_mov_b32_e32 v16, 0
	v_mov_b32_e32 v17, 0
	v_mov_b32_e32 v14, 0
	v_mov_b32_e32 v15, 0
	s_and_saveexec_b64 s[6:7], s[0:1]
	s_cbranch_execz .LBB0_636
	v_ashrrev_i32_e32 v41, 31, v40
	v_lshl_add_u64 v[10:11], v[40:41], 2, v[38:39]
	v_add_co_u32_e32 v10, vcc, 0x1e000, v10
	s_nop 1
	v_addc_co_u32_e32 v11, vcc, 0, v11, vcc
	global_load_dwordx4 v[14:17], v[10:11], off offset:128
.LBB0_636:
	s_or_b64 exec, exec, s[6:7]
	v_mov_b32_e32 v13, 0
	v_mov_b32_e32 v10, 0
	v_mov_b32_e32 v11, 0
	s_and_saveexec_b64 s[6:7], s[0:1]
	s_cbranch_execz .LBB0_638
	v_ashrrev_i32_e32 v41, 31, v40
	v_lshl_add_u64 v[10:11], v[40:41], 2, v[38:39]
	v_add_co_u32_e32 v10, vcc, 0x2d000, v10
	s_nop 1
	v_addc_co_u32_e32 v11, vcc, 0, v11, vcc
	global_load_dwordx4 v[10:13], v[10:11], off offset:192
.LBB0_638:
	s_or_b64 exec, exec, s[6:7]
	v_mov_b32_e32 v20, 0
	v_mov_b32_e32 v24, 0
	v_mov_b32_e32 v25, 0
	v_mov_b32_e32 v22, 0
	v_mov_b32_e32 v23, 0
	s_and_saveexec_b64 s[6:7], s[0:1]
	s_cbranch_execz .LBB0_640
	v_ashrrev_i32_e32 v41, 31, v40
	v_lshl_add_u64 v[18:19], v[40:41], 2, v[38:39]
	v_add_co_u32_e32 v18, vcc, 0x3c000, v18
	s_nop 1
	v_addc_co_u32_e32 v19, vcc, 0, v19, vcc
	global_load_dwordx4 v[22:25], v[18:19], off offset:256
.LBB0_640:
	s_or_b64 exec, exec, s[6:7]
	v_mov_b32_e32 v21, 0
	v_mov_b32_e32 v18, 0
	v_mov_b32_e32 v19, 0
	s_and_saveexec_b64 s[6:7], s[0:1]
	s_cbranch_execz .LBB0_642
	v_ashrrev_i32_e32 v41, 31, v40
	v_lshl_add_u64 v[18:19], v[40:41], 2, v[38:39]
	v_add_co_u32_e32 v18, vcc, 0x4b000, v18
	s_nop 1
	v_addc_co_u32_e32 v19, vcc, 0, v19, vcc
	global_load_dwordx4 v[18:21], v[18:19], off offset:320
.LBB0_642:
	s_or_b64 exec, exec, s[6:7]
	v_mov_b32_e32 v28, 0
	v_mov_b32_e32 v32, 0
	v_mov_b32_e32 v33, 0
	v_mov_b32_e32 v30, 0
	v_mov_b32_e32 v31, 0
	s_and_saveexec_b64 s[6:7], s[0:1]
	s_cbranch_execz .LBB0_644
	v_ashrrev_i32_e32 v41, 31, v40
	v_lshl_add_u64 v[26:27], v[40:41], 2, v[38:39]
	v_add_co_u32_e32 v26, vcc, 0x5a000, v26
	s_nop 1
	v_addc_co_u32_e32 v27, vcc, 0, v27, vcc
	global_load_dwordx4 v[30:33], v[26:27], off offset:384
.LBB0_644:
	s_or_b64 exec, exec, s[6:7]
	v_mov_b32_e32 v29, 0
	v_mov_b32_e32 v26, 0
	v_mov_b32_e32 v27, 0
	s_and_saveexec_b64 s[6:7], s[0:1]
	s_cbranch_execz .LBB0_623
	v_ashrrev_i32_e32 v41, 31, v40
	v_lshl_add_u64 v[26:27], v[40:41], 2, v[38:39]
	v_add_co_u32_e32 v26, vcc, 0x69000, v26
	s_nop 1
	v_addc_co_u32_e32 v27, vcc, 0, v27, vcc
	global_load_dwordx4 v[26:29], v[26:27], off offset:448
	s_branch .LBB0_623
.LBB0_646:
	v_mov_b32_e32 v0, s66
	v_add_co_u32_e32 v2, vcc, 0x4375c000, v0
	v_mov_b32_e32 v0, s67
	s_nop 0
	v_addc_co_u32_e32 v3, vcc, 0, v0, vcc
	s_waitcnt vmcnt(0) lgkmcnt(0)
	global_load_dwordx2 v[34:35], v[2:3], off offset:80
	v_readlane_b32 s0, v253, 42
	v_readlane_b32 s1, v253, 43
	v_mov_b32_e32 v0, v139
	s_andn2_b64 vcc, exec, s[0:1]
	s_cbranch_vccnz .LBB0_665
	v_ashrrev_i32_e32 v2, 1, v0
	v_lshlrev_b32_e32 v0, 3, v0
	s_add_u32 s0, s66, 0x37200000
	v_and_b32_e32 v0, 56, v0
	v_readlane_b32 s4, v252, 14
	s_addc_u32 s1, s67, 0
	v_and_b32_e32 v40, -4, v2
	v_add_u32_e32 v41, s4, v0
	s_mov_b32 s6, s63
	s_branch .LBB0_649
.LBB0_648:
	s_or_b64 exec, exec, s[4:5]
	v_mov_b64_e32 v[46:47], s[0:1]
	s_movk_i32 s7, 0x2400
	v_mad_i64_i32 v[38:39], s[4:5], v0, s7, v[46:47]
	v_lshlrev_b64 v[48:49], 1, v[36:37]
	s_waitcnt vmcnt(0) lgkmcnt(0)
	v_cvt_pk_bf16_f32 v42, v2, v6
	v_cvt_pk_bf16_f32 v43, v14, v10
	v_cvt_pk_bf16_f32 v44, v22, v18
	v_cvt_pk_bf16_f32 v45, v30, v26
	v_lshl_add_u64 v[36:37], v[38:39], 0, v[48:49]
	v_or_b32_e32 v2, 1, v0
	global_store_dwordx4 v[36:37], v[42:45], off
	v_cvt_pk_bf16_f32 v36, v3, v7
	v_mad_i64_i32 v[2:3], s[4:5], v2, s7, v[46:47]
	v_cvt_pk_bf16_f32 v37, v15, v11
	v_cvt_pk_bf16_f32 v38, v23, v19
	v_cvt_pk_bf16_f32 v39, v31, v27
	v_lshl_add_u64 v[2:3], v[2:3], 0, v[48:49]
	global_store_dwordx4 v[2:3], v[36:39], off
	v_or_b32_e32 v2, 2, v0
	v_mad_i64_i32 v[2:3], s[4:5], v2, s7, v[46:47]
	v_or_b32_e32 v0, 3, v0
	v_cvt_pk_bf16_f32 v36, v4, v8
	v_cvt_pk_bf16_f32 v37, v16, v12
	v_cvt_pk_bf16_f32 v38, v24, v20
	v_cvt_pk_bf16_f32 v39, v32, v28
	v_lshl_add_u64 v[2:3], v[2:3], 0, v[48:49]
	v_mad_i64_i32 v[6:7], s[4:5], v0, s7, v[46:47]
	s_add_i32 s6, s6, s96
	global_store_dwordx4 v[2:3], v[36:39], off
	v_cvt_pk_bf16_f32 v2, v5, v9
	v_cvt_pk_bf16_f32 v3, v17, v13
	v_cvt_pk_bf16_f32 v4, v25, v21
	v_cvt_pk_bf16_f32 v5, v33, v29
	v_lshl_add_u64 v[6:7], v[6:7], 0, v[48:49]
	s_cmpk_lt_i32 s6, 0x480
	v_add_u32_e32 v41, s33, v41
	global_store_dwordx4 v[6:7], v[2:5], off
	s_cbranch_scc0 .LBB0_665
;   __device__ __forceinline__ const float* in(int i) const { return ((const float* const*)(ws + OFF_TBL))[i]; }
;     ...
;   for (int t = (int)blockIdx.x - blk0; t < tn * tk; t += nblk) {
;     const int n0 = (t / tk) * 256 + ng * 4, k0 = (t % tk) * 64 + kg * 8;
;     int c = n0;
;     if (mode == 1) c = (n0 < 6144) ? n0 : (n0 < 15360 ? n0 + 16 : (n0 < 15376 ? 6144 + (n0 - 15360) : -1));
;     float4 v[8];
; #pragma unroll
;     for (int r = 0; r < 8; ++r) v[r] = (c >= 0) ? *(const float4*)(src + (long)(k0 + r) * C + c) : make_float4(0.f, 0.f, 0.f, 0.f);
;     uint4 o;
;     o.x = pack2(v[0].x, v[1].x); o.y = pack2(v[2].x, v[3].x); o.z = pack2(v[4].x, v[5].x); o.w = pack2(v[6].x, v[7].x);
;     *(uint4*)(dst + (long)(n0 + 0) * R + k0) = o;
;     o.x = pack2(v[0].y, v[1].y); o.y = pack2(v[2].y, v[3].y); o.z = pack2(v[4].y, v[5].y); o.w = pack2(v[6].y, v[7].y);
;     *(uint4*)(dst + (long)(n0 + 1) * R + k0) = o;
;     o.x = pack2(v[0].z, v[1].z); o.y = pack2(v[2].z, v[3].z); o.z = pack2(v[4].z, v[5].z); o.w = pack2(v[6].z, v[7].z);
;     *(uint4*)(dst + (long)(n0 + 2) * R + k0) = o;
;     o.x = pack2(v[0].w, v[1].w); o.y = pack2(v[2].w, v[3].w); o.z = pack2(v[4].w, v[5].w); o.w = pack2(v[6].w, v[7].w);
;     *(uint4*)(dst + (long)(n0 + 3) * R + k0) = o;
;   }
; __device__ void phase_prep0(const Ctx& p) {
;     ...
;   transpose_cvt(p.in(10), 4608, DM, (u16*)(ws + OFF_WO0T), DM, 0);
;   transpose_cvt(p.in(8), DM, 512, (u16*)(ws + OFF_WKVT + 0 * 4 * MIB), 512, 0);
.LBB0_649:
	s_mul_hi_i32 s4, s6, 0x38e38e39
	s_lshr_b32 s5, s4, 31
	s_ashr_i32 s4, s4, 4
	s_add_i32 s4, s4, s5
	v_lshl_add_u32 v0, s4, 8, v40
	s_mulk_i32 s4, 0xee00
	v_add_u32_e32 v36, s4, v41
	v_cmp_lt_i32_e32 vcc, -1, v0
	s_waitcnt vmcnt(0) lgkmcnt(0)
	v_lshl_add_u64 v[38:39], v[0:1], 2, v[34:35]
	v_mov_b32_e32 v8, 0
	v_ashrrev_i32_e32 v37, 31, v36
	v_mov_b32_e32 v4, 0
	v_mov_b32_e32 v5, 0
	v_mov_b32_e32 v2, 0
	v_mov_b32_e32 v3, 0
	s_and_saveexec_b64 s[4:5], vcc
	s_cbranch_execz .LBB0_651
	v_lshlrev_b64 v[2:3], 14, v[36:37]
	v_lshl_add_u64 v[2:3], v[38:39], 0, v[2:3]
	global_load_dwordx4 v[2:5], v[2:3], off
.LBB0_651:
	s_or_b64 exec, exec, s[4:5]
	v_mov_b32_e32 v9, 0
	v_mov_b32_e32 v6, 0
	v_mov_b32_e32 v7, 0
	s_and_saveexec_b64 s[4:5], vcc
	s_cbranch_execz .LBB0_653
	v_add_u32_e32 v6, 1, v36
	v_ashrrev_i32_e32 v7, 31, v6
	v_lshlrev_b64 v[6:7], 14, v[6:7]
	v_lshl_add_u64 v[6:7], v[38:39], 0, v[6:7]
	global_load_dwordx4 v[6:9], v[6:7], off
.LBB0_653:
	s_or_b64 exec, exec, s[4:5]
	v_mov_b32_e32 v12, 0
	v_mov_b32_e32 v16, 0
	v_mov_b32_e32 v17, 0
	v_mov_b32_e32 v14, 0
	v_mov_b32_e32 v15, 0
	s_and_saveexec_b64 s[4:5], vcc
	s_cbranch_execz .LBB0_655
	v_add_u32_e32 v10, 2, v36
	v_ashrrev_i32_e32 v11, 31, v10
	v_lshlrev_b64 v[10:11], 14, v[10:11]
	v_lshl_add_u64 v[10:11], v[38:39], 0, v[10:11]
	global_load_dwordx4 v[14:17], v[10:11], off
.LBB0_655:
	s_or_b64 exec, exec, s[4:5]
	v_mov_b32_e32 v13, 0
	v_mov_b32_e32 v10, 0
	v_mov_b32_e32 v11, 0
	s_and_saveexec_b64 s[4:5], vcc
	s_cbranch_execz .LBB0_657
	v_add_u32_e32 v10, 3, v36
	v_ashrrev_i32_e32 v11, 31, v10
	v_lshlrev_b64 v[10:11], 14, v[10:11]
	v_lshl_add_u64 v[10:11], v[38:39], 0, v[10:11]
	global_load_dwordx4 v[10:13], v[10:11], off
.LBB0_657:
	s_or_b64 exec, exec, s[4:5]
	v_mov_b32_e32 v20, 0
	v_mov_b32_e32 v24, 0
	v_mov_b32_e32 v25, 0
	v_mov_b32_e32 v22, 0
	v_mov_b32_e32 v23, 0
	s_and_saveexec_b64 s[4:5], vcc
	s_cbranch_execz .LBB0_659
	v_add_u32_e32 v18, 4, v36
	v_ashrrev_i32_e32 v19, 31, v18
	v_lshlrev_b64 v[18:19], 14, v[18:19]
	v_lshl_add_u64 v[18:19], v[38:39], 0, v[18:19]
	global_load_dwordx4 v[22:25], v[18:19], off
.LBB0_659:
	s_or_b64 exec, exec, s[4:5]
	v_mov_b32_e32 v21, 0
	v_mov_b32_e32 v18, 0
	v_mov_b32_e32 v19, 0
	s_and_saveexec_b64 s[4:5], vcc
	s_cbranch_execz .LBB0_661
	v_add_u32_e32 v18, 5, v36
	v_ashrrev_i32_e32 v19, 31, v18
	v_lshlrev_b64 v[18:19], 14, v[18:19]
	v_lshl_add_u64 v[18:19], v[38:39], 0, v[18:19]
	global_load_dwordx4 v[18:21], v[18:19], off
.LBB0_661:
	s_or_b64 exec, exec, s[4:5]
	v_mov_b32_e32 v28, 0
	v_mov_b32_e32 v32, 0
	v_mov_b32_e32 v33, 0
	v_mov_b32_e32 v30, 0
	v_mov_b32_e32 v31, 0
	s_and_saveexec_b64 s[4:5], vcc
	s_cbranch_execz .LBB0_663
	v_add_u32_e32 v26, 6, v36
	v_ashrrev_i32_e32 v27, 31, v26
	v_lshlrev_b64 v[26:27], 14, v[26:27]
	v_lshl_add_u64 v[26:27], v[38:39], 0, v[26:27]
	global_load_dwordx4 v[30:33], v[26:27], off
.LBB0_663:
	s_or_b64 exec, exec, s[4:5]
	v_mov_b32_e32 v29, 0
	v_mov_b32_e32 v26, 0
	v_mov_b32_e32 v27, 0
	s_and_saveexec_b64 s[4:5], vcc
	s_cbranch_execz .LBB0_648
	v_add_u32_e32 v26, 7, v36
	v_ashrrev_i32_e32 v27, 31, v26
	v_lshlrev_b64 v[26:27], 14, v[26:27]
	v_lshl_add_u64 v[26:27], v[38:39], 0, v[26:27]
	global_load_dwordx4 v[26:29], v[26:27], off
	s_branch .LBB0_648
.LBB0_665:
	v_mov_b32_e32 v0, s66
	v_add_co_u32_e32 v2, vcc, 0x4375c000, v0
	v_mov_b32_e32 v0, s67
	s_nop 0
	v_addc_co_u32_e32 v3, vcc, 0, v0, vcc
	s_waitcnt vmcnt(0) lgkmcnt(0)
	global_load_dwordx2 v[34:35], v[2:3], off offset:64
	v_readlane_b32 s0, v253, 46
	v_readlane_b32 s1, v253, 47
	v_mov_b32_e32 v0, v139
	s_andn2_b64 vcc, exec, s[0:1]
	v_cndmask_b32_e64 v2, 0, 1, s[0:1]
	v_cmp_ne_u32_e64 s[4:5], 1, v2
	s_cbranch_vccnz .LBB0_684
	v_ashrrev_i32_e32 v2, 1, v0
	v_lshlrev_b32_e32 v0, 3, v0
	s_add_u32 s0, s66, 0x42400000
	v_and_b32_e32 v0, 56, v0
	v_readlane_b32 s6, v252, 14
	s_addc_u32 s1, s67, 0
	v_and_b32_e32 v40, -4, v2
	v_add_u32_e32 v41, s6, v0
	s_mov_b32 s8, s63
	s_branch .LBB0_668
;   __device__ __forceinline__ const float* in(int i) const { return ((const float* const*)(ws + OFF_TBL))[i]; }
;     ...
;   for (int t = (int)blockIdx.x - blk0; t < tn * tk; t += nblk) {
;     const int n0 = (t / tk) * 256 + ng * 4, k0 = (t % tk) * 64 + kg * 8;
;     int c = n0;
;     if (mode == 1) c = (n0 < 6144) ? n0 : (n0 < 15360 ? n0 + 16 : (n0 < 15376 ? 6144 + (n0 - 15360) : -1));
;     float4 v[8];
; #pragma unroll
;     for (int r = 0; r < 8; ++r) v[r] = (c >= 0) ? *(const float4*)(src + (long)(k0 + r) * C + c) : make_float4(0.f, 0.f, 0.f, 0.f);
;     uint4 o;
;     o.x = pack2(v[0].x, v[1].x); o.y = pack2(v[2].x, v[3].x); o.z = pack2(v[4].x, v[5].x); o.w = pack2(v[6].x, v[7].x);
;     *(uint4*)(dst + (long)(n0 + 0) * R + k0) = o;
;     o.x = pack2(v[0].y, v[1].y); o.y = pack2(v[2].y, v[3].y); o.z = pack2(v[4].y, v[5].y); o.w = pack2(v[6].y, v[7].y);
;     *(uint4*)(dst + (long)(n0 + 1) * R + k0) = o;
;     o.x = pack2(v[0].z, v[1].z); o.y = pack2(v[2].z, v[3].z); o.z = pack2(v[4].z, v[5].z); o.w = pack2(v[6].z, v[7].z);
;     *(uint4*)(dst + (long)(n0 + 2) * R + k0) = o;
;     o.x = pack2(v[0].w, v[1].w); o.y = pack2(v[2].w, v[3].w); o.z = pack2(v[4].w, v[5].w); o.w = pack2(v[6].w, v[7].w);
;     *(uint4*)(dst + (long)(n0 + 3) * R + k0) = o;
;   }
; __device__ void phase_prep0(const Ctx& p) {
;     ...
;   transpose_cvt(p.in(8), DM, 512, (u16*)(ws + OFF_WKVT + 0 * 4 * MIB), 512, 0);
;   transpose_cvt(p.in(9), DM, 512, (u16*)(ws + OFF_WKVT + 1 * 4 * MIB), 512, 0);
.LBB0_667:
	s_or_b64 exec, exec, s[6:7]
	v_ashrrev_i32_e32 v39, 31, v0
	v_mov_b32_e32 v38, v0
	v_lshlrev_b64 v[38:39], 13, v[38:39]
	v_lshl_add_u64 v[38:39], s[0:1], 0, v[38:39]
	v_lshlrev_b64 v[46:47], 1, v[36:37]
	s_waitcnt vmcnt(0) lgkmcnt(0)
	v_cvt_pk_bf16_f32 v42, v2, v6
	v_cvt_pk_bf16_f32 v43, v14, v10
	v_cvt_pk_bf16_f32 v44, v22, v18
	v_cvt_pk_bf16_f32 v45, v30, v26
	v_lshl_add_u64 v[36:37], v[38:39], 0, v[46:47]
	v_or_b32_e32 v2, 1, v0
	global_store_dwordx4 v[36:37], v[42:45], off
	v_cvt_pk_bf16_f32 v36, v3, v7
	v_ashrrev_i32_e32 v3, 31, v2
	v_lshlrev_b64 v[2:3], 13, v[2:3]
	v_lshl_add_u64 v[2:3], s[0:1], 0, v[2:3]
	v_cvt_pk_bf16_f32 v37, v15, v11
	v_cvt_pk_bf16_f32 v38, v23, v19
	v_cvt_pk_bf16_f32 v39, v31, v27
	v_lshl_add_u64 v[2:3], v[2:3], 0, v[46:47]
	global_store_dwordx4 v[2:3], v[36:39], off
	v_or_b32_e32 v2, 2, v0
	v_ashrrev_i32_e32 v3, 31, v2
	v_or_b32_e32 v6, 3, v0
	v_lshlrev_b64 v[2:3], 13, v[2:3]
	v_ashrrev_i32_e32 v7, 31, v6
	v_lshl_add_u64 v[2:3], s[0:1], 0, v[2:3]
	v_lshlrev_b64 v[6:7], 13, v[6:7]
	v_cvt_pk_bf16_f32 v36, v4, v8
	v_cvt_pk_bf16_f32 v37, v16, v12
	v_cvt_pk_bf16_f32 v38, v24, v20
	v_cvt_pk_bf16_f32 v39, v32, v28
	v_lshl_add_u64 v[2:3], v[2:3], 0, v[46:47]
	v_lshl_add_u64 v[6:7], s[0:1], 0, v[6:7]
	s_add_i32 s8, s8, s96
	global_store_dwordx4 v[2:3], v[36:39], off
	v_cvt_pk_bf16_f32 v2, v5, v9
	v_cvt_pk_bf16_f32 v3, v17, v13
	v_cvt_pk_bf16_f32 v4, v25, v21
	v_cvt_pk_bf16_f32 v5, v33, v29
	v_lshl_add_u64 v[6:7], v[6:7], 0, v[46:47]
	s_cmpk_lt_i32 s8, 0x80
	v_add_u32_e32 v41, s33, v41
	global_store_dwordx4 v[6:7], v[2:5], off
	s_cbranch_scc0 .LBB0_684
.LBB0_668:
	s_ashr_i32 s6, s8, 31
	s_lshr_b32 s6, s6, 26
	s_add_i32 s6, s8, s6
	s_ashr_i32 s6, s6, 6
	v_lshl_add_u32 v0, s6, 8, v40
	s_lshl_b32 s6, s6, 12
	v_subrev_u32_e32 v36, s6, v41
	v_cmp_lt_i32_e32 vcc, -1, v0
	s_waitcnt vmcnt(0) lgkmcnt(0)
	v_lshl_add_u64 v[38:39], v[0:1], 2, v[34:35]
	v_mov_b32_e32 v8, 0
	v_ashrrev_i32_e32 v37, 31, v36
	v_mov_b32_e32 v4, 0
	v_mov_b32_e32 v5, 0
	v_mov_b32_e32 v2, 0
	v_mov_b32_e32 v3, 0
	s_and_saveexec_b64 s[6:7], vcc
	s_cbranch_execz .LBB0_670
	v_lshlrev_b64 v[2:3], 11, v[36:37]
	v_lshl_add_u64 v[2:3], v[38:39], 0, v[2:3]
	global_load_dwordx4 v[2:5], v[2:3], off
.LBB0_670:
	s_or_b64 exec, exec, s[6:7]
	v_mov_b32_e32 v9, 0
	v_mov_b32_e32 v6, 0
	v_mov_b32_e32 v7, 0
	s_and_saveexec_b64 s[6:7], vcc
	s_cbranch_execz .LBB0_672
	v_add_u32_e32 v6, 1, v36
	v_ashrrev_i32_e32 v7, 31, v6
	v_lshlrev_b64 v[6:7], 11, v[6:7]
	v_lshl_add_u64 v[6:7], v[38:39], 0, v[6:7]
	global_load_dwordx4 v[6:9], v[6:7], off
.LBB0_672:
	s_or_b64 exec, exec, s[6:7]
	v_mov_b32_e32 v12, 0
	v_mov_b32_e32 v16, 0
	v_mov_b32_e32 v17, 0
	v_mov_b32_e32 v14, 0
	v_mov_b32_e32 v15, 0
	s_and_saveexec_b64 s[6:7], vcc
	s_cbranch_execz .LBB0_674
	v_add_u32_e32 v10, 2, v36
	v_ashrrev_i32_e32 v11, 31, v10
	v_lshlrev_b64 v[10:11], 11, v[10:11]
	v_lshl_add_u64 v[10:11], v[38:39], 0, v[10:11]
	global_load_dwordx4 v[14:17], v[10:11], off
.LBB0_674:
	s_or_b64 exec, exec, s[6:7]
	v_mov_b32_e32 v13, 0
	v_mov_b32_e32 v10, 0
	v_mov_b32_e32 v11, 0
	s_and_saveexec_b64 s[6:7], vcc
	s_cbranch_execz .LBB0_676
	v_add_u32_e32 v10, 3, v36
	v_ashrrev_i32_e32 v11, 31, v10
	v_lshlrev_b64 v[10:11], 11, v[10:11]
	v_lshl_add_u64 v[10:11], v[38:39], 0, v[10:11]
	global_load_dwordx4 v[10:13], v[10:11], off
.LBB0_676:
	s_or_b64 exec, exec, s[6:7]
	v_mov_b32_e32 v20, 0
	v_mov_b32_e32 v24, 0
	v_mov_b32_e32 v25, 0
	v_mov_b32_e32 v22, 0
	v_mov_b32_e32 v23, 0
	s_and_saveexec_b64 s[6:7], vcc
	s_cbranch_execz .LBB0_678
	v_add_u32_e32 v18, 4, v36
	v_ashrrev_i32_e32 v19, 31, v18
	v_lshlrev_b64 v[18:19], 11, v[18:19]
	v_lshl_add_u64 v[18:19], v[38:39], 0, v[18:19]
	global_load_dwordx4 v[22:25], v[18:19], off
.LBB0_678:
	s_or_b64 exec, exec, s[6:7]
	v_mov_b32_e32 v21, 0
	v_mov_b32_e32 v18, 0
	v_mov_b32_e32 v19, 0
	s_and_saveexec_b64 s[6:7], vcc
	s_cbranch_execz .LBB0_680
	v_add_u32_e32 v18, 5, v36
	v_ashrrev_i32_e32 v19, 31, v18
	v_lshlrev_b64 v[18:19], 11, v[18:19]
	v_lshl_add_u64 v[18:19], v[38:39], 0, v[18:19]
	global_load_dwordx4 v[18:21], v[18:19], off
.LBB0_680:
	s_or_b64 exec, exec, s[6:7]
	v_mov_b32_e32 v28, 0
	v_mov_b32_e32 v32, 0
	v_mov_b32_e32 v33, 0
	v_mov_b32_e32 v30, 0
	v_mov_b32_e32 v31, 0
	s_and_saveexec_b64 s[6:7], vcc
	s_cbranch_execz .LBB0_682
	v_add_u32_e32 v26, 6, v36
	v_ashrrev_i32_e32 v27, 31, v26
	v_lshlrev_b64 v[26:27], 11, v[26:27]
	v_lshl_add_u64 v[26:27], v[38:39], 0, v[26:27]
	global_load_dwordx4 v[30:33], v[26:27], off
.LBB0_682:
	s_or_b64 exec, exec, s[6:7]
	v_mov_b32_e32 v29, 0
	v_mov_b32_e32 v26, 0
	v_mov_b32_e32 v27, 0
	s_and_saveexec_b64 s[6:7], vcc
	s_cbranch_execz .LBB0_667
	v_add_u32_e32 v26, 7, v36
	v_ashrrev_i32_e32 v27, 31, v26
	v_lshlrev_b64 v[26:27], 11, v[26:27]
	v_lshl_add_u64 v[26:27], v[38:39], 0, v[26:27]
	global_load_dwordx4 v[26:29], v[26:27], off
	s_branch .LBB0_667
.LBB0_684:
	v_mov_b32_e32 v0, s66
	v_add_co_u32_e32 v2, vcc, 0x4375c000, v0
	v_mov_b32_e32 v0, s67
	s_nop 0
	v_addc_co_u32_e32 v3, vcc, 0, v0, vcc
	s_waitcnt vmcnt(0) lgkmcnt(0)
	global_load_dwordx2 v[34:35], v[2:3], off offset:72
	v_mov_b32_e32 v0, v139
	s_and_b64 vcc, exec, s[4:5]
	s_cbranch_vccnz .LBB0_703
	v_ashrrev_i32_e32 v2, 1, v0
	v_lshlrev_b32_e32 v0, 3, v0
	s_add_u32 s0, s66, 0x42800000
	v_and_b32_e32 v0, 56, v0
	v_readlane_b32 s6, v252, 14
	s_addc_u32 s1, s67, 0
	v_and_b32_e32 v40, -4, v2
	v_add_u32_e32 v41, s6, v0
	s_mov_b32 s8, s63
	s_branch .LBB0_687

;   __device__ __forceinline__ const float* in(int i) const { return ((const float* const*)(ws + OFF_TBL))[i]; }
; __device__ __forceinline__ int ltid() { int t = threadIdx.x; asm volatile("" : "+v"(t)); return t; }
;   const int tid = ltid();
;   const int kg = tid & 7, ng = tid >> 3;
;   const int tn = Nd / 256, tk = R / 64;
;   if (nblk == 0) nblk = gridDim.x;
;   if ((int)blockIdx.x < blk0 || (int)blockIdx.x >= blk0 + nblk) return;
;   for (int t = (int)blockIdx.x - blk0; t < tn * tk; t += nblk) {
; __device__ void phase_prep0(const Ctx& p) {
;     ...
;   transpose_cvt(p.in(23), DM, 512, (u16*)(ws + OFF_WKVT + 2 * 4 * MIB), 512, 0);
.LBB0_703:
	v_mov_b32_e32 v0, s66
	v_add_co_u32_e32 v2, vcc, 0x4375c000, v0
	v_mov_b32_e32 v0, s67
	s_nop 0
	v_addc_co_u32_e32 v3, vcc, 0, v0, vcc
	s_waitcnt vmcnt(0) lgkmcnt(0)
	global_load_dwordx2 v[34:35], v[2:3], off offset:184
	v_mov_b32_e32 v0, v139
	s_and_b64 vcc, exec, s[4:5]
	s_cbranch_vccnz .LBB0_722
	v_ashrrev_i32_e32 v2, 1, v0
	v_lshlrev_b32_e32 v0, 3, v0
	s_add_u32 s0, s66, 0x42c00000
	v_and_b32_e32 v0, 56, v0
	v_readlane_b32 s6, v252, 14
	s_addc_u32 s1, s67, 0
	v_and_b32_e32 v40, -4, v2
	v_add_u32_e32 v41, s6, v0
	s_mov_b32 s8, s63
	s_branch .LBB0_706

;   __device__ __forceinline__ const float* in(int i) const { return ((const float* const*)(ws + OFF_TBL))[i]; }
; __device__ __forceinline__ int ltid() { int t = threadIdx.x; asm volatile("" : "+v"(t)); return t; }
;     ...
;   for (int t = (int)blockIdx.x - blk0; t < tn * tk; t += nblk) {
;     const int n0 = (t / tk) * 256 + ng * 4, k0 = (t % tk) * 64 + kg * 8;
;     int c = n0;
;     if (mode == 1) c = (n0 < 6144) ? n0 : (n0 < 15360 ? n0 + 16 : (n0 < 15376 ? 6144 + (n0 - 15360) : -1));
;     float4 v[8];
; #pragma unroll
;     for (int r = 0; r < 8; ++r) v[r] = (c >= 0) ? *(const float4*)(src + (long)(k0 + r) * C + c) : make_float4(0.f, 0.f, 0.f, 0.f);
;     uint4 o;
;     o.x = pack2(v[0].x, v[1].x); o.y = pack2(v[2].x, v[3].x); o.z = pack2(v[4].x, v[5].x); o.w = pack2(v[6].x, v[7].x);
;     *(uint4*)(dst + (long)(n0 + 0) * R + k0) = o;
;     o.x = pack2(v[0].y, v[1].y); o.y = pack2(v[2].y, v[3].y); o.z = pack2(v[4].y, v[5].y); o.w = pack2(v[6].y, v[7].y);
;     *(uint4*)(dst + (long)(n0 + 1) * R + k0) = o;
;     o.x = pack2(v[0].z, v[1].z); o.y = pack2(v[2].z, v[3].z); o.z = pack2(v[4].z, v[5].z); o.w = pack2(v[6].z, v[7].z);
;     *(uint4*)(dst + (long)(n0 + 2) * R + k0) = o;
;     o.x = pack2(v[0].w, v[1].w); o.y = pack2(v[2].w, v[3].w); o.z = pack2(v[4].w, v[5].w); o.w = pack2(v[6].w, v[7].w);
;     *(uint4*)(dst + (long)(n0 + 3) * R + k0) = o;
;   }
; __device__ void phase_prep0(const Ctx& p) {
;     ...
;   transpose_cvt(p.in(24), DM, 512, (u16*)(ws + OFF_WKVT + 3 * 4 * MIB), 512, 0);
;   const float* wq = p.in(16); const float* wk = p.in(17); const float* wv = p.in(18); const float* wif = p.in(19);
;   float* Wqk = (float*)(ws + OFF_WEFF); float* Wv = Wqk + 8192 * 8;
;   for (int c = blockIdx.x * blockDim.x + ltid(); c < 8192; c += gridDim.x * blockDim.x) {
.LBB0_722:
	v_mov_b32_e32 v0, s66
	v_add_co_u32_e32 v2, vcc, 0x4375c000, v0
	v_mov_b32_e32 v0, s67
	s_nop 0
	v_addc_co_u32_e32 v3, vcc, 0, v0, vcc
	s_waitcnt vmcnt(0) lgkmcnt(0)
	global_load_dwordx2 v[34:35], v[2:3], off offset:192
	v_mov_b32_e32 v0, v139
	s_and_b64 vcc, exec, s[4:5]
	s_cbranch_vccnz .LBB0_741
	v_ashrrev_i32_e32 v2, 1, v0
	v_lshlrev_b32_e32 v0, 3, v0
	s_add_u32 s0, s66, 0x43000000
	v_and_b32_e32 v0, 56, v0
	v_readlane_b32 s4, v252, 14
	s_addc_u32 s1, s67, 0
	v_and_b32_e32 v40, -4, v2
	v_add_u32_e32 v41, s4, v0
	s_mov_b32 s6, s63
	s_branch .LBB0_725
.LBB0_724:
	s_or_b64 exec, exec, s[4:5]
	v_ashrrev_i32_e32 v39, 31, v0
	v_mov_b32_e32 v38, v0
	v_lshlrev_b64 v[38:39], 13, v[38:39]
	v_lshl_add_u64 v[38:39], s[0:1], 0, v[38:39]
	v_lshlrev_b64 v[46:47], 1, v[36:37]
	s_waitcnt vmcnt(0) lgkmcnt(0)
	v_cvt_pk_bf16_f32 v42, v2, v6
	v_cvt_pk_bf16_f32 v43, v14, v10
	v_cvt_pk_bf16_f32 v44, v22, v18
	v_cvt_pk_bf16_f32 v45, v30, v26
	v_lshl_add_u64 v[36:37], v[38:39], 0, v[46:47]
	v_or_b32_e32 v2, 1, v0
	global_store_dwordx4 v[36:37], v[42:45], off
	v_cvt_pk_bf16_f32 v36, v3, v7
	v_ashrrev_i32_e32 v3, 31, v2
	v_lshlrev_b64 v[2:3], 13, v[2:3]
	v_lshl_add_u64 v[2:3], s[0:1], 0, v[2:3]
	v_cvt_pk_bf16_f32 v37, v15, v11
	v_cvt_pk_bf16_f32 v38, v23, v19
	v_cvt_pk_bf16_f32 v39, v31, v27
	v_lshl_add_u64 v[2:3], v[2:3], 0, v[46:47]
	global_store_dwordx4 v[2:3], v[36:39], off
	v_or_b32_e32 v2, 2, v0
	v_ashrrev_i32_e32 v3, 31, v2
	v_or_b32_e32 v6, 3, v0
	v_lshlrev_b64 v[2:3], 13, v[2:3]
	v_ashrrev_i32_e32 v7, 31, v6
	v_lshl_add_u64 v[2:3], s[0:1], 0, v[2:3]
	v_lshlrev_b64 v[6:7], 13, v[6:7]
	v_cvt_pk_bf16_f32 v36, v4, v8
	v_cvt_pk_bf16_f32 v37, v16, v12
	v_cvt_pk_bf16_f32 v38, v24, v20
	v_cvt_pk_bf16_f32 v39, v32, v28
	v_lshl_add_u64 v[2:3], v[2:3], 0, v[46:47]
	v_lshl_add_u64 v[6:7], s[0:1], 0, v[6:7]
	s_add_i32 s6, s6, s96
	global_store_dwordx4 v[2:3], v[36:39], off
	v_cvt_pk_bf16_f32 v2, v5, v9
	v_cvt_pk_bf16_f32 v3, v17, v13
	v_cvt_pk_bf16_f32 v4, v25, v21
	v_cvt_pk_bf16_f32 v5, v33, v29
	v_lshl_add_u64 v[6:7], v[6:7], 0, v[46:47]
	s_cmpk_lt_i32 s6, 0x80
	v_add_u32_e32 v41, s33, v41
	global_store_dwordx4 v[6:7], v[2:5], off
	s_cbranch_scc0 .LBB0_741
.LBB0_725:
	s_ashr_i32 s4, s6, 31
	s_lshr_b32 s4, s4, 26
	s_add_i32 s4, s6, s4
	s_ashr_i32 s4, s4, 6
	v_lshl_add_u32 v0, s4, 8, v40
	s_lshl_b32 s4, s4, 12
	v_subrev_u32_e32 v36, s4, v41
	v_cmp_lt_i32_e32 vcc, -1, v0
	s_waitcnt vmcnt(0) lgkmcnt(0)
	v_lshl_add_u64 v[38:39], v[0:1], 2, v[34:35]
	v_mov_b32_e32 v8, 0
	v_ashrrev_i32_e32 v37, 31, v36
	v_mov_b32_e32 v4, 0
	v_mov_b32_e32 v5, 0
	v_mov_b32_e32 v2, 0
	v_mov_b32_e32 v3, 0
	s_and_saveexec_b64 s[4:5], vcc
	s_cbranch_execz .LBB0_727
	v_lshlrev_b64 v[2:3], 11, v[36:37]
	v_lshl_add_u64 v[2:3], v[38:39], 0, v[2:3]
	global_load_dwordx4 v[2:5], v[2:3], off
.LBB0_727:
	s_or_b64 exec, exec, s[4:5]
	v_mov_b32_e32 v9, 0
	v_mov_b32_e32 v6, 0
	v_mov_b32_e32 v7, 0
	s_and_saveexec_b64 s[4:5], vcc
	s_cbranch_execz .LBB0_729
	v_add_u32_e32 v6, 1, v36
	v_ashrrev_i32_e32 v7, 31, v6
	v_lshlrev_b64 v[6:7], 11, v[6:7]
	v_lshl_add_u64 v[6:7], v[38:39], 0, v[6:7]
	global_load_dwordx4 v[6:9], v[6:7], off
.LBB0_729:
	s_or_b64 exec, exec, s[4:5]
	v_mov_b32_e32 v12, 0
	v_mov_b32_e32 v16, 0
	v_mov_b32_e32 v17, 0
	v_mov_b32_e32 v14, 0
	v_mov_b32_e32 v15, 0
	s_and_saveexec_b64 s[4:5], vcc
	s_cbranch_execz .LBB0_731
	v_add_u32_e32 v10, 2, v36
	v_ashrrev_i32_e32 v11, 31, v10
	v_lshlrev_b64 v[10:11], 11, v[10:11]
	v_lshl_add_u64 v[10:11], v[38:39], 0, v[10:11]
	global_load_dwordx4 v[14:17], v[10:11], off
.LBB0_731:
	s_or_b64 exec, exec, s[4:5]
	v_mov_b32_e32 v13, 0
	v_mov_b32_e32 v10, 0
	v_mov_b32_e32 v11, 0
	s_and_saveexec_b64 s[4:5], vcc
	s_cbranch_execz .LBB0_733
	v_add_u32_e32 v10, 3, v36
	v_ashrrev_i32_e32 v11, 31, v10
	v_lshlrev_b64 v[10:11], 11, v[10:11]
	v_lshl_add_u64 v[10:11], v[38:39], 0, v[10:11]
	global_load_dwordx4 v[10:13], v[10:11], off
.LBB0_733:
	s_or_b64 exec, exec, s[4:5]
	v_mov_b32_e32 v20, 0
	v_mov_b32_e32 v24, 0
	v_mov_b32_e32 v25, 0
	v_mov_b32_e32 v22, 0
	v_mov_b32_e32 v23, 0
	s_and_saveexec_b64 s[4:5], vcc
	s_cbranch_execz .LBB0_735
	v_add_u32_e32 v18, 4, v36
	v_ashrrev_i32_e32 v19, 31, v18
	v_lshlrev_b64 v[18:19], 11, v[18:19]
	v_lshl_add_u64 v[18:19], v[38:39], 0, v[18:19]
	global_load_dwordx4 v[22:25], v[18:19], off
.LBB0_735:
	s_or_b64 exec, exec, s[4:5]
	v_mov_b32_e32 v21, 0
	v_mov_b32_e32 v18, 0
	v_mov_b32_e32 v19, 0
	s_and_saveexec_b64 s[4:5], vcc
	s_cbranch_execz .LBB0_737
	v_add_u32_e32 v18, 5, v36
	v_ashrrev_i32_e32 v19, 31, v18
	v_lshlrev_b64 v[18:19], 11, v[18:19]
	v_lshl_add_u64 v[18:19], v[38:39], 0, v[18:19]
	global_load_dwordx4 v[18:21], v[18:19], off
.LBB0_737:
	s_or_b64 exec, exec, s[4:5]
	v_mov_b32_e32 v28, 0
	v_mov_b32_e32 v32, 0
	v_mov_b32_e32 v33, 0
	v_mov_b32_e32 v30, 0
	v_mov_b32_e32 v31, 0
	s_and_saveexec_b64 s[4:5], vcc
	s_cbranch_execz .LBB0_739
	v_add_u32_e32 v26, 6, v36
	v_ashrrev_i32_e32 v27, 31, v26
	v_lshlrev_b64 v[26:27], 11, v[26:27]
	v_lshl_add_u64 v[26:27], v[38:39], 0, v[26:27]
	global_load_dwordx4 v[30:33], v[26:27], off
.LBB0_739:
	s_or_b64 exec, exec, s[4:5]
	v_mov_b32_e32 v29, 0
	v_mov_b32_e32 v26, 0
	v_mov_b32_e32 v27, 0
	s_and_saveexec_b64 s[4:5], vcc
	s_cbranch_execz .LBB0_724
	v_add_u32_e32 v26, 7, v36
	v_ashrrev_i32_e32 v27, 31, v26
	v_lshlrev_b64 v[26:27], 11, v[26:27]
	v_lshl_add_u64 v[26:27], v[38:39], 0, v[26:27]
	global_load_dwordx4 v[26:29], v[26:27], off
	s_branch .LBB0_724
.LBB0_741:
	v_mov_b32_e32 v0, s66
	v_add_co_u32_e32 v6, vcc, 0x4375c000, v0
	v_mov_b32_e32 v0, s67
	s_nop 0
	v_addc_co_u32_e32 v7, vcc, 0, v0, vcc
	global_load_dwordx4 v[2:5], v[6:7], off offset:128
	s_nop 0
	global_load_dwordx4 v[6:9], v[6:7], off offset:144
	v_mov_b32_e32 v0, v139
	v_readlane_b32 s0, v252, 15
	v_readlane_b32 s1, v252, 16
	s_nop 0
	v_add_u32_e32 v0, s0, v0
	s_movk_i32 s0, 0x2000
	v_cmp_gt_i32_e32 vcc, s0, v0
	s_and_saveexec_b64 s[0:1], vcc
	s_cbranch_execz .LBB0_746
	s_add_u32 s4, s66, 0x43600000
	s_addc_u32 s5, s67, 0
	s_add_u32 s6, s66, 0x43640000
	s_addc_u32 s7, s67, 0
	v_lshlrev_b32_e32 v26, 3, v0
	s_mov_b64 s[8:9], 0

; __device__ __forceinline__ int ltid() { int t = threadIdx.x; asm volatile("" : "+v"(t)); return t; }
; __device__ void phase_prep0(const Ctx& p) {
;     ...
;   for (int c = blockIdx.x * blockDim.x + ltid(); c < 8192; c += gridDim.x * blockDim.x) {
;     int nb = c >> 2, i = c & 3;
;     for (int g = 0; g < 8; ++g) {
;       float sqk = 0.f, sv = 0.f;
;       for (int o = 0; o < 4; ++o) {
;         sqk += wq[nb * 16 + i * 4 + o] * wif[(long)(4 * nb + o) * 8 + g] + wk[nb * 16 + i * 4 + o] * wif[(long)(8192 + 4 * nb + o) * 8 + g];
;         sv += wv[nb * 16 + i * 4 + o] * wif[(long)(16384 + 4 * nb + o) * 8 + g];
;       }
;       Wqk[c * 8 + g] = sqk; Wv[c * 8 + g] = sv;
;     }
.LBB0_744:
	global_load_dwordx4 v[32:35], v[18:19], off
	global_load_dwordx4 v[28:31], v[16:17], off
	global_load_dwordx4 v[36:39], v[20:21], off
	v_lshl_add_u64 v[42:43], v[12:13], 0, s[10:11]
	v_lshl_add_u64 v[40:41], v[14:15], 0, s[10:11]
	v_lshl_add_u64 v[44:45], v[10:11], 0, s[10:11]
	v_lshl_add_u64 v[46:47], v[22:23], 0, s[10:11]
	global_load_dword v27, v[42:43], off
	global_load_dword v52, v[44:45], off
	global_load_dword v53, v[42:43], off offset:32
	global_load_dword v54, v[42:43], off offset:64
	global_load_dword v55, v[42:43], off offset:96
	global_load_dword v56, v[40:41], off
	global_load_dword v57, v[40:41], off offset:32
	global_load_dword v58, v[44:45], off offset:32
	global_load_dword v59, v[40:41], off offset:64
	global_load_dword v60, v[46:47], off
	global_load_dword v61, v[44:45], off offset:64
	global_load_dword v62, v[44:45], off offset:96
	v_ashrrev_i32_e32 v25, 31, v24
	v_lshlrev_b64 v[48:49], 2, v[24:25]
	v_lshl_add_u64 v[50:51], s[4:5], 0, v[48:49]
	v_lshl_add_u64 v[48:49], s[6:7], 0, v[48:49]
	s_add_u32 s10, s10, 8
	s_addc_u32 s11, s11, 0
	s_cmp_lg_u32 s10, 32
	s_waitcnt vmcnt(0) lgkmcnt(0)
	v_mul_f32_e32 v25, v32, v27
	v_mul_f32_e32 v32, v33, v53
	v_fmac_f32_e32 v25, v28, v56
	v_fma_f32 v27, v36, v52, 0
	v_mul_f32_e32 v33, v34, v54
	v_fmac_f32_e32 v32, v29, v57
	v_add_f32_e32 v25, 0, v25
	v_mul_f32_e32 v34, v35, v55
	v_fmac_f32_e32 v27, v37, v58
	v_fmac_f32_e32 v33, v30, v59
	v_add_f32_e32 v25, v25, v32
	v_fmac_f32_e32 v34, v31, v60
	v_fmac_f32_e32 v27, v38, v61
	v_add_f32_e32 v25, v25, v33
	v_fmac_f32_e32 v27, v39, v62
	v_add_f32_e32 v25, v25, v34
	global_store_dword v[48:49], v27, off
	global_store_dword v[50:51], v25, off
	global_load_dwordx4 v[28:31], v[16:17], off
	global_load_dwordx4 v[32:35], v[18:19], off
	global_load_dwordx4 v[36:39], v[20:21], off
	s_nop 0
	global_load_dword v25, v[42:43], off offset:4
	global_load_dword v27, v[44:45], off offset:4
	global_load_dword v48, v[42:43], off offset:36
	global_load_dword v49, v[42:43], off offset:68
	global_load_dword v50, v[42:43], off offset:100
	global_load_dword v51, v[40:41], off offset:4
	global_load_dword v52, v[40:41], off offset:36
	global_load_dword v53, v[44:45], off offset:36
	global_load_dword v54, v[40:41], off offset:68
	s_nop 0
	global_load_dword v46, v[46:47], off offset:4
	s_nop 0
	global_load_dword v47, v[44:45], off offset:68
	s_nop 0
	global_load_dword v44, v[44:45], off offset:100
	v_add_u32_e32 v40, 1, v24
	v_ashrrev_i32_e32 v41, 31, v40
	v_lshlrev_b64 v[40:41], 2, v[40:41]
	v_add_u32_e32 v24, 2, v24
	v_lshl_add_u64 v[42:43], s[4:5], 0, v[40:41]
	v_lshl_add_u64 v[40:41], s[6:7], 0, v[40:41]
	s_waitcnt vmcnt(0) lgkmcnt(0)
	v_mul_f32_e32 v25, v32, v25
	v_fma_f32 v27, v36, v27, 0
	v_mul_f32_e32 v32, v33, v48
	v_mul_f32_e32 v33, v34, v49
	v_mul_f32_e32 v34, v35, v50
	v_fmac_f32_e32 v25, v28, v51
	v_fmac_f32_e32 v32, v29, v52
	v_add_f32_e32 v25, 0, v25
	v_fmac_f32_e32 v27, v37, v53
	v_fmac_f32_e32 v33, v30, v54
	v_add_f32_e32 v25, v25, v32
	v_fmac_f32_e32 v34, v31, v46
	v_fmac_f32_e32 v27, v38, v47
	v_add_f32_e32 v25, v25, v33
	v_fmac_f32_e32 v27, v39, v44
	v_add_f32_e32 v25, v25, v34
	global_store_dword v[40:41], v27, off
	global_store_dword v[42:43], v25, off
	s_cbranch_scc1 .LBB0_744
	v_add_u32_e32 v0, s78, v0
	s_movk_i32 s10, 0x1fff
	v_cmp_lt_i32_e32 vcc, s10, v0
	s_or_b64 s[8:9], vcc, s[8:9]
	v_add_u32_e32 v26, s21, v26
	s_andn2_b64 exec, exec, s[8:9]
	s_cbranch_execnz .LBB0_743
